# speedup vs baseline: 1.0488x; 1.0073x over previous
.LBB0_423:
	s_add_i32 s15, s14, 0x80
	s_min_u32 s4, s15, 0x3c0
	s_lshl_b32 s4, s4, 1
	v_lshl_add_u64 v[144:145], v[104:105], 0, s[4:5]
	v_add_co_u32_e32 v128, vcc, s8, v144
	v_lshl_add_u64 v[148:149], v[108:109], 0, s[4:5]
	s_nop 0
	v_addc_co_u32_e32 v129, vcc, 0, v145, vcc
	v_add_co_u32_e32 v132, vcc, s8, v148
	global_load_dwordx4 v[120:123], v[144:145], off
	global_load_dwordx4 v[124:127], v[148:149], off
	v_addc_co_u32_e32 v133, vcc, 0, v149, vcc
	v_add_co_u32_e32 v136, vcc, s9, v144
	global_load_dwordx4 v[128:131], v[128:129], off
	s_nop 0
	v_addc_co_u32_e32 v137, vcc, 0, v145, vcc
	v_add_co_u32_e32 v140, vcc, s9, v148
	global_load_dwordx4 v[132:135], v[132:133], off
	s_nop 0
	v_addc_co_u32_e32 v141, vcc, 0, v149, vcc
	v_add_co_u32_e32 v144, vcc, s10, v144
	global_load_dwordx4 v[136:139], v[136:137], off
	s_nop 0
	v_addc_co_u32_e32 v145, vcc, 0, v145, vcc
	v_add_co_u32_e32 v148, vcc, s10, v148
	global_load_dwordx4 v[140:143], v[140:141], off
	s_nop 0
	v_addc_co_u32_e32 v149, vcc, 0, v149, vcc
	global_load_dwordx4 v[144:147], v[144:145], off
	s_nop 0
	global_load_dwordx4 v[148:151], v[148:149], off
	s_setprio 1
	ds_read_b128 v[152:155], v112 offset:16384
	ds_read_b128 v[156:159], v112 offset:18432
	ds_read_b128 v[160:163], v110
	ds_read_b128 v[164:167], v110 offset:2048
	ds_read_b128 v[168:171], v112 offset:20480
	ds_read_b128 v[172:175], v113 offset:16384
	s_waitcnt lgkmcnt(3)
	v_mfma_f32_16x16x32_bf16 v[94:97], v[152:155], v[160:163], v[94:97]
	v_mfma_f32_16x16x32_bf16 v[90:93], v[156:159], v[160:163], v[90:93]
	s_waitcnt lgkmcnt(1)
	v_mfma_f32_16x16x32_bf16 v[86:89], v[168:171], v[160:163], v[86:89]
	s_waitcnt lgkmcnt(0)
	v_mfma_f32_16x16x32_bf16 v[82:85], v[172:175], v[160:163], v[82:85]
	v_mfma_f32_16x16x32_bf16 v[78:81], v[152:155], v[164:167], v[78:81]
	v_mfma_f32_16x16x32_bf16 v[74:77], v[156:159], v[164:167], v[74:77]
	v_mfma_f32_16x16x32_bf16 v[62:65], v[168:171], v[164:167], v[62:65]
	v_mfma_f32_16x16x32_bf16 v[30:33], v[172:175], v[164:167], v[30:33]
	ds_read_b128 v[160:163], v110 offset:4096
	ds_read_b128 v[164:167], v111
	s_waitcnt lgkmcnt(1)
	v_mfma_f32_16x16x32_bf16 v[66:69], v[152:155], v[160:163], v[66:69]
	v_mfma_f32_16x16x32_bf16 v[38:41], v[156:159], v[160:163], v[38:41]
	v_mfma_f32_16x16x32_bf16 v[34:37], v[168:171], v[160:163], v[34:37]
	v_mfma_f32_16x16x32_bf16 v[18:21], v[172:175], v[160:163], v[18:21]
	s_waitcnt lgkmcnt(0)
	v_mfma_f32_16x16x32_bf16 v[14:17], v[152:155], v[164:167], v[14:17]
	ds_read_b128 v[152:155], v116 offset:16384
	v_mfma_f32_16x16x32_bf16 v[10:13], v[156:159], v[164:167], v[10:13]
	v_mfma_f32_16x16x32_bf16 v[6:9], v[168:171], v[164:167], v[6:9]
	v_mfma_f32_16x16x32_bf16 v[2:5], v[172:175], v[164:167], v[2:5]
	ds_read_b128 v[156:159], v116 offset:18432
	ds_read_b128 v[160:163], v114
	ds_read_b128 v[164:167], v114 offset:2048
	ds_read_b128 v[168:171], v116 offset:20480
	ds_read_b128 v[172:175], v117 offset:16384
	s_waitcnt lgkmcnt(3)
	v_mfma_f32_16x16x32_bf16 v[94:97], v[152:155], v[160:163], v[94:97]
	v_mfma_f32_16x16x32_bf16 v[90:93], v[156:159], v[160:163], v[90:93]
	s_waitcnt lgkmcnt(1)
	v_mfma_f32_16x16x32_bf16 v[86:89], v[168:171], v[160:163], v[86:89]
	s_waitcnt lgkmcnt(0)
	v_mfma_f32_16x16x32_bf16 v[82:85], v[172:175], v[160:163], v[82:85]
	v_mfma_f32_16x16x32_bf16 v[78:81], v[152:155], v[164:167], v[78:81]
	v_mfma_f32_16x16x32_bf16 v[74:77], v[156:159], v[164:167], v[74:77]
	v_mfma_f32_16x16x32_bf16 v[62:65], v[168:171], v[164:167], v[62:65]
	v_mfma_f32_16x16x32_bf16 v[30:33], v[172:175], v[164:167], v[30:33]
	ds_read_b128 v[160:163], v114 offset:4096
	ds_read_b128 v[164:167], v115
	s_waitcnt lgkmcnt(1)
	v_mfma_f32_16x16x32_bf16 v[66:69], v[152:155], v[160:163], v[66:69]
	v_mfma_f32_16x16x32_bf16 v[38:41], v[156:159], v[160:163], v[38:41]
	v_mfma_f32_16x16x32_bf16 v[34:37], v[168:171], v[160:163], v[34:37]
	v_mfma_f32_16x16x32_bf16 v[18:21], v[172:175], v[160:163], v[18:21]
	s_waitcnt lgkmcnt(0)
	v_mfma_f32_16x16x32_bf16 v[14:17], v[152:155], v[164:167], v[14:17]
	v_mfma_f32_16x16x32_bf16 v[10:13], v[156:159], v[164:167], v[10:13]
	v_mfma_f32_16x16x32_bf16 v[6:9], v[168:171], v[164:167], v[6:9]
	v_mfma_f32_16x16x32_bf16 v[2:5], v[172:175], v[164:167], v[2:5]
	s_setprio 0
	s_min_u32 s4, s14, 0x300
	s_lshl_b32 s4, s4, 1
	s_waitcnt vmcnt(15)
	ds_write_b128 v107, v[22:25] offset:32768
	s_waitcnt vmcnt(14)
	ds_write_b128 v107, v[26:29] offset:49152
	s_waitcnt vmcnt(13)
	ds_write_b128 v107, v[42:45] offset:36864
	s_waitcnt vmcnt(12)
	ds_write_b128 v107, v[46:49] offset:53248
	s_waitcnt vmcnt(11)
	ds_write_b128 v107, v[50:53] offset:40960
	s_waitcnt vmcnt(10)
	ds_write_b128 v107, v[54:57] offset:57344
	s_waitcnt vmcnt(9)
	ds_write_b128 v107, v[58:61] offset:45056
	s_waitcnt vmcnt(8)
	ds_write_b128 v107, v[70:73] offset:61440
	v_lshl_add_u64 v[42:43], v[104:105], 0, s[4:5]
	v_add_co_u32_e32 v46, vcc, s8, v42
	v_lshl_add_u64 v[44:45], v[108:109], 0, s[4:5]
	s_nop 0
	v_addc_co_u32_e32 v47, vcc, 0, v43, vcc
	v_add_co_u32_e32 v48, vcc, s8, v44
	s_waitcnt lgkmcnt(0)
	s_nop 0
	v_addc_co_u32_e32 v49, vcc, 0, v45, vcc
	v_add_co_u32_e32 v50, vcc, s9, v42
	s_barrier
	s_nop 0
	v_addc_co_u32_e32 v51, vcc, 0, v43, vcc
	v_add_co_u32_e32 v54, vcc, s9, v44
	s_nop 1
	v_addc_co_u32_e32 v55, vcc, 0, v45, vcc
	v_add_co_u32_e32 v58, vcc, s10, v42
	global_load_dwordx4 v[22:25], v[42:43], off offset:384
	global_load_dwordx4 v[26:29], v[44:45], off offset:384
	v_addc_co_u32_e32 v59, vcc, 0, v43, vcc
	v_add_co_u32_e32 v70, vcc, s10, v44
	s_nop 1
	v_addc_co_u32_e32 v71, vcc, 0, v45, vcc
	global_load_dwordx4 v[42:45], v[46:47], off offset:384
	s_nop 0
	global_load_dwordx4 v[46:49], v[48:49], off offset:384
	s_nop 0
	global_load_dwordx4 v[50:53], v[50:51], off offset:384
	s_nop 0
	global_load_dwordx4 v[54:57], v[54:55], off offset:384
	s_nop 0
	global_load_dwordx4 v[58:61], v[58:59], off offset:384
	s_nop 0
	global_load_dwordx4 v[70:73], v[70:71], off offset:384
	s_setprio 1
	ds_read_b128 v[152:155], v112 offset:49152
	ds_read_b128 v[156:159], v112 offset:51200
	ds_read_b128 v[160:163], v110 offset:32768
	ds_read_b128 v[164:167], v110 offset:34816
	ds_read_b128 v[168:171], v112 offset:53248
	ds_read_b128 v[172:175], v113 offset:49152
	s_waitcnt lgkmcnt(3)
	v_mfma_f32_16x16x32_bf16 v[94:97], v[152:155], v[160:163], v[94:97]
	v_mfma_f32_16x16x32_bf16 v[90:93], v[156:159], v[160:163], v[90:93]
	s_waitcnt lgkmcnt(1)
	v_mfma_f32_16x16x32_bf16 v[86:89], v[168:171], v[160:163], v[86:89]
	s_waitcnt lgkmcnt(0)
	v_mfma_f32_16x16x32_bf16 v[82:85], v[172:175], v[160:163], v[82:85]
	v_mfma_f32_16x16x32_bf16 v[78:81], v[152:155], v[164:167], v[78:81]
	v_mfma_f32_16x16x32_bf16 v[74:77], v[156:159], v[164:167], v[74:77]
	v_mfma_f32_16x16x32_bf16 v[62:65], v[168:171], v[164:167], v[62:65]
	v_mfma_f32_16x16x32_bf16 v[30:33], v[172:175], v[164:167], v[30:33]
	ds_read_b128 v[160:163], v110 offset:36864
	ds_read_b128 v[164:167], v111 offset:32768
	s_waitcnt lgkmcnt(1)
	v_mfma_f32_16x16x32_bf16 v[66:69], v[152:155], v[160:163], v[66:69]
	v_mfma_f32_16x16x32_bf16 v[38:41], v[156:159], v[160:163], v[38:41]
	v_mfma_f32_16x16x32_bf16 v[34:37], v[168:171], v[160:163], v[34:37]
	v_mfma_f32_16x16x32_bf16 v[18:21], v[172:175], v[160:163], v[18:21]
	s_waitcnt lgkmcnt(0)
	v_mfma_f32_16x16x32_bf16 v[14:17], v[152:155], v[164:167], v[14:17]
	ds_read_b128 v[152:155], v116 offset:49152
	v_mfma_f32_16x16x32_bf16 v[10:13], v[156:159], v[164:167], v[10:13]
	v_mfma_f32_16x16x32_bf16 v[6:9], v[168:171], v[164:167], v[6:9]
	v_mfma_f32_16x16x32_bf16 v[2:5], v[172:175], v[164:167], v[2:5]
	ds_read_b128 v[156:159], v116 offset:51200
	ds_read_b128 v[160:163], v114 offset:32768
	ds_read_b128 v[164:167], v114 offset:34816
	ds_read_b128 v[168:171], v116 offset:53248
	ds_read_b128 v[172:175], v117 offset:49152
	s_waitcnt lgkmcnt(3)
	v_mfma_f32_16x16x32_bf16 v[94:97], v[152:155], v[160:163], v[94:97]
	v_mfma_f32_16x16x32_bf16 v[90:93], v[156:159], v[160:163], v[90:93]
	s_waitcnt lgkmcnt(1)
	v_mfma_f32_16x16x32_bf16 v[86:89], v[168:171], v[160:163], v[86:89]
	s_waitcnt lgkmcnt(0)
	v_mfma_f32_16x16x32_bf16 v[82:85], v[172:175], v[160:163], v[82:85]
	v_mfma_f32_16x16x32_bf16 v[78:81], v[152:155], v[164:167], v[78:81]
	v_mfma_f32_16x16x32_bf16 v[74:77], v[156:159], v[164:167], v[74:77]
	v_mfma_f32_16x16x32_bf16 v[62:65], v[168:171], v[164:167], v[62:65]
	v_mfma_f32_16x16x32_bf16 v[30:33], v[172:175], v[164:167], v[30:33]
	ds_read_b128 v[160:163], v114 offset:36864
	ds_read_b128 v[164:167], v115 offset:32768
	s_waitcnt lgkmcnt(1)
	v_mfma_f32_16x16x32_bf16 v[66:69], v[152:155], v[160:163], v[66:69]
	v_mfma_f32_16x16x32_bf16 v[38:41], v[156:159], v[160:163], v[38:41]
	v_mfma_f32_16x16x32_bf16 v[34:37], v[168:171], v[160:163], v[34:37]
	v_mfma_f32_16x16x32_bf16 v[18:21], v[172:175], v[160:163], v[18:21]
	s_waitcnt lgkmcnt(0)
	v_mfma_f32_16x16x32_bf16 v[14:17], v[152:155], v[164:167], v[14:17]
	v_mfma_f32_16x16x32_bf16 v[10:13], v[156:159], v[164:167], v[10:13]
	v_mfma_f32_16x16x32_bf16 v[6:9], v[168:171], v[164:167], v[6:9]
	v_mfma_f32_16x16x32_bf16 v[2:5], v[172:175], v[164:167], v[2:5]
	s_setprio 0
	s_add_i32 s13, s13, 2
	s_cmp_lt_u32 s13, 14
	s_mov_b32 s14, s15
	s_waitcnt vmcnt(15)
	ds_write_b128 v107, v[120:123]
	s_waitcnt vmcnt(14)
	ds_write_b128 v107, v[124:127] offset:16384
	s_waitcnt vmcnt(13)
	ds_write_b128 v107, v[128:131] offset:4096
	s_waitcnt vmcnt(12)
	ds_write_b128 v107, v[132:135] offset:20480
	s_waitcnt vmcnt(11)
	ds_write_b128 v107, v[136:139] offset:8192
	s_waitcnt vmcnt(10)
	ds_write_b128 v107, v[140:143] offset:24576
	s_waitcnt vmcnt(9)
	ds_write_b128 v107, v[144:147] offset:12288
	s_waitcnt vmcnt(8)
	ds_write_b128 v107, v[148:151] offset:28672
	s_waitcnt lgkmcnt(0)
	s_barrier
	s_cbranch_scc1 .LBB0_423
	s_waitcnt vmcnt(0)
	v_or_b32_e32 v170, s12, v119
	v_add_lshl_u32 v98, v118, s11, 10
	v_readlane_b32 s12, v254, 8
	v_readlane_b32 s13, v254, 9
	v_readlane_b32 s14, v254, 10
	v_readlane_b32 s15, v254, 11
	v_readlane_b32 s16, v254, 12
	v_readlane_b32 s17, v254, 13
	v_readlane_b32 s18, v254, 14
	v_readlane_b32 s19, v254, 15
	v_readlane_b32 s20, v254, 16
	v_readlane_b32 s21, v254, 17
	v_readlane_b32 s22, v254, 18
	v_readlane_b32 s23, v254, 19
	v_readlane_b32 s24, v254, 20
	v_readlane_b32 s25, v254, 21
	v_readlane_b32 s26, v254, 22
	v_readlane_b32 s27, v254, 23
	v_lshlrev_b32_e32 v168, 2, v170
	v_mov_b32_e32 v169, v99
	v_lshlrev_b64 v[174:175], 2, v[98:99]
	v_lshl_add_u64 v[152:153], s[12:13], 0, v[174:175]
	v_lshl_add_u64 v[160:161], s[82:83], 0, v[174:175]
	v_lshl_add_u64 v[152:153], v[152:153], 0, v[168:169]
	v_lshl_add_u64 v[160:161], v[160:161], 0, v[168:169]
	global_load_dwordx4 v[120:123], v[152:153], off
	global_load_dwordx4 v[124:127], v[152:153], off offset:64
	global_load_dwordx4 v[128:131], v[152:153], off offset:128
	global_load_dwordx4 v[132:135], v[152:153], off offset:192
	v_or_b32_e32 v172, 0x4000, v98
	v_mov_b32_e32 v173, v99
	v_lshlrev_b64 v[174:175], 2, v[172:173]
	v_lshl_add_u64 v[154:155], s[12:13], 0, v[174:175]
	v_lshl_add_u64 v[162:163], s[82:83], 0, v[174:175]
	v_lshl_add_u64 v[154:155], v[154:155], 0, v[168:169]
	v_lshl_add_u64 v[162:163], v[162:163], 0, v[168:169]
	global_load_dwordx4 v[136:139], v[154:155], off
	global_load_dwordx4 v[140:143], v[154:155], off offset:64
	global_load_dwordx4 v[144:147], v[154:155], off offset:128
	global_load_dwordx4 v[148:151], v[154:155], off offset:192
	v_or_b32_e32 v172, 0x8000, v98
	v_mov_b32_e32 v173, v99
	v_lshlrev_b64 v[174:175], 2, v[172:173]
	v_lshl_add_u64 v[156:157], s[12:13], 0, v[174:175]
	v_lshl_add_u64 v[164:165], s[82:83], 0, v[174:175]
	v_lshl_add_u64 v[156:157], v[156:157], 0, v[168:169]
	v_lshl_add_u64 v[164:165], v[164:165], 0, v[168:169]
	global_load_dwordx4 v[22:25], v[156:157], off
	global_load_dwordx4 v[26:29], v[156:157], off offset:64
	global_load_dwordx4 v[42:45], v[156:157], off offset:128
	global_load_dwordx4 v[46:49], v[156:157], off offset:192
	v_or_b32_e32 v172, 0xc000, v98
	v_mov_b32_e32 v173, v99
	v_lshlrev_b64 v[174:175], 2, v[172:173]
	v_lshl_add_u64 v[158:159], s[12:13], 0, v[174:175]
	v_lshl_add_u64 v[166:167], s[82:83], 0, v[174:175]
	v_lshl_add_u64 v[158:159], v[158:159], 0, v[168:169]
	v_lshl_add_u64 v[166:167], v[166:167], 0, v[168:169]
	global_load_dwordx4 v[50:53], v[158:159], off
	global_load_dwordx4 v[54:57], v[158:159], off offset:64
	global_load_dwordx4 v[58:61], v[158:159], off offset:128
	global_load_dwordx4 v[70:73], v[158:159], off offset:192
	s_waitcnt vmcnt(15)
	v_pk_fma_f32 v[120:121], v[120:121], s[6:7], v[94:95] op_sel_hi:[1,0,1]
	v_pk_fma_f32 v[122:123], v[122:123], s[6:7], v[96:97] op_sel_hi:[1,0,1]
	s_waitcnt vmcnt(14)
	v_pk_fma_f32 v[124:125], v[124:125], s[6:7], v[90:91] op_sel_hi:[1,0,1]
	v_pk_fma_f32 v[126:127], v[126:127], s[6:7], v[92:93] op_sel_hi:[1,0,1]
	s_waitcnt vmcnt(13)
	v_pk_fma_f32 v[128:129], v[128:129], s[6:7], v[86:87] op_sel_hi:[1,0,1]
	v_pk_fma_f32 v[130:131], v[130:131], s[6:7], v[88:89] op_sel_hi:[1,0,1]
	s_waitcnt vmcnt(12)
	v_pk_fma_f32 v[132:133], v[132:133], s[6:7], v[82:83] op_sel_hi:[1,0,1]
	v_pk_fma_f32 v[134:135], v[134:135], s[6:7], v[84:85] op_sel_hi:[1,0,1]
	s_waitcnt vmcnt(11)
	v_pk_fma_f32 v[136:137], v[136:137], s[6:7], v[78:79] op_sel_hi:[1,0,1]
	v_pk_fma_f32 v[138:139], v[138:139], s[6:7], v[80:81] op_sel_hi:[1,0,1]
	s_waitcnt vmcnt(10)
	v_pk_fma_f32 v[140:141], v[140:141], s[6:7], v[74:75] op_sel_hi:[1,0,1]
	v_pk_fma_f32 v[142:143], v[142:143], s[6:7], v[76:77] op_sel_hi:[1,0,1]
	s_waitcnt vmcnt(9)
	v_pk_fma_f32 v[144:145], v[144:145], s[6:7], v[62:63] op_sel_hi:[1,0,1]
	v_pk_fma_f32 v[146:147], v[146:147], s[6:7], v[64:65] op_sel_hi:[1,0,1]
	s_waitcnt vmcnt(8)
	v_pk_fma_f32 v[148:149], v[148:149], s[6:7], v[30:31] op_sel_hi:[1,0,1]
	v_pk_fma_f32 v[150:151], v[150:151], s[6:7], v[32:33] op_sel_hi:[1,0,1]
	s_waitcnt vmcnt(7)
	v_pk_fma_f32 v[22:23], v[22:23], s[6:7], v[66:67] op_sel_hi:[1,0,1]
	v_pk_fma_f32 v[24:25], v[24:25], s[6:7], v[68:69] op_sel_hi:[1,0,1]
	s_waitcnt vmcnt(6)
	v_pk_fma_f32 v[26:27], v[26:27], s[6:7], v[38:39] op_sel_hi:[1,0,1]
	v_pk_fma_f32 v[28:29], v[28:29], s[6:7], v[40:41] op_sel_hi:[1,0,1]
	s_waitcnt vmcnt(5)
	v_pk_fma_f32 v[42:43], v[42:43], s[6:7], v[34:35] op_sel_hi:[1,0,1]
	v_pk_fma_f32 v[44:45], v[44:45], s[6:7], v[36:37] op_sel_hi:[1,0,1]
	s_waitcnt vmcnt(4)
	v_pk_fma_f32 v[46:47], v[46:47], s[6:7], v[18:19] op_sel_hi:[1,0,1]
	v_pk_fma_f32 v[48:49], v[48:49], s[6:7], v[20:21] op_sel_hi:[1,0,1]
	s_waitcnt vmcnt(3)
	v_pk_fma_f32 v[50:51], v[50:51], s[6:7], v[14:15] op_sel_hi:[1,0,1]
	v_pk_fma_f32 v[52:53], v[52:53], s[6:7], v[16:17] op_sel_hi:[1,0,1]
	s_waitcnt vmcnt(2)
	v_pk_fma_f32 v[54:55], v[54:55], s[6:7], v[10:11] op_sel_hi:[1,0,1]
	v_pk_fma_f32 v[56:57], v[56:57], s[6:7], v[12:13] op_sel_hi:[1,0,1]
	s_waitcnt vmcnt(1)
	v_pk_fma_f32 v[58:59], v[58:59], s[6:7], v[6:7] op_sel_hi:[1,0,1]
	v_pk_fma_f32 v[60:61], v[60:61], s[6:7], v[8:9] op_sel_hi:[1,0,1]
	s_waitcnt vmcnt(0)
	v_pk_fma_f32 v[70:71], v[70:71], s[6:7], v[2:3] op_sel_hi:[1,0,1]
	v_pk_fma_f32 v[72:73], v[72:73], s[6:7], v[4:5] op_sel_hi:[1,0,1]
	global_store_dwordx4 v[160:161], v[120:123], off
	global_store_dwordx4 v[160:161], v[124:127], off offset:64
	global_store_dwordx4 v[160:161], v[128:131], off offset:128
	global_store_dwordx4 v[160:161], v[132:135], off offset:192
	global_store_dwordx4 v[162:163], v[136:139], off
	global_store_dwordx4 v[162:163], v[140:143], off offset:64
	global_store_dwordx4 v[162:163], v[144:147], off offset:128
	global_store_dwordx4 v[162:163], v[148:151], off offset:192
	global_store_dwordx4 v[164:165], v[22:25], off
	global_store_dwordx4 v[164:165], v[26:29], off offset:64
	global_store_dwordx4 v[164:165], v[42:45], off offset:128
	global_store_dwordx4 v[164:165], v[46:49], off offset:192
	global_store_dwordx4 v[166:167], v[50:53], off
	global_store_dwordx4 v[166:167], v[54:57], off offset:64
	global_store_dwordx4 v[166:167], v[58:61], off offset:128
	global_store_dwordx4 v[166:167], v[70:73], off offset:192
	s_add_i32 s7, s7, s3
	s_cmpk_lt_u32 s7, 0x100
	s_cbranch_scc1 .LBB0_422

.LBB0_519:
	s_add_i32 s14, s13, 0x80
	s_min_u32 s4, s14, 0x1c0
	s_lshl_b32 s4, s4, 1
	v_lshl_add_u64 v[144:145], v[104:105], 0, s[4:5]
	v_add_co_u32_e32 v128, vcc, s7, v144
	v_lshl_add_u64 v[148:149], v[108:109], 0, s[4:5]
	s_nop 0
	v_addc_co_u32_e32 v129, vcc, 0, v145, vcc
	v_add_co_u32_e32 v132, vcc, s7, v148
	global_load_dwordx4 v[120:123], v[144:145], off
	global_load_dwordx4 v[124:127], v[148:149], off
	v_addc_co_u32_e32 v133, vcc, 0, v149, vcc
	v_add_co_u32_e32 v136, vcc, s8, v144
	global_load_dwordx4 v[128:131], v[128:129], off
	s_nop 0
	v_addc_co_u32_e32 v137, vcc, 0, v145, vcc
	v_add_co_u32_e32 v140, vcc, s8, v148
	global_load_dwordx4 v[132:135], v[132:133], off
	s_nop 0
	v_addc_co_u32_e32 v141, vcc, 0, v149, vcc
	v_add_co_u32_e32 v144, vcc, s9, v144
	global_load_dwordx4 v[136:139], v[136:137], off
	s_nop 0
	v_addc_co_u32_e32 v145, vcc, 0, v145, vcc
	v_add_co_u32_e32 v148, vcc, s9, v148
	global_load_dwordx4 v[140:143], v[140:141], off
	s_nop 0
	v_addc_co_u32_e32 v149, vcc, 0, v149, vcc
	global_load_dwordx4 v[144:147], v[144:145], off
	s_nop 0
	global_load_dwordx4 v[148:151], v[148:149], off
	s_setprio 1
	ds_read_b128 v[152:155], v112 offset:16384
	ds_read_b128 v[156:159], v112 offset:18432
	ds_read_b128 v[160:163], v110
	ds_read_b128 v[164:167], v110 offset:2048
	ds_read_b128 v[168:171], v112 offset:20480
	ds_read_b128 v[172:175], v113 offset:16384
	s_waitcnt lgkmcnt(3)
	v_mfma_i32_16x16x64_i8 v[94:97], v[152:155], v[160:163], v[94:97]
	v_mfma_i32_16x16x64_i8 v[90:93], v[156:159], v[160:163], v[90:93]
	s_waitcnt lgkmcnt(1)
	v_mfma_i32_16x16x64_i8 v[86:89], v[168:171], v[160:163], v[86:89]
	s_waitcnt lgkmcnt(0)
	v_mfma_i32_16x16x64_i8 v[82:85], v[172:175], v[160:163], v[82:85]
	v_mfma_i32_16x16x64_i8 v[74:77], v[152:155], v[164:167], v[74:77]
	v_mfma_i32_16x16x64_i8 v[50:53], v[156:159], v[164:167], v[50:53]
	v_mfma_i32_16x16x64_i8 v[38:41], v[168:171], v[164:167], v[38:41]
	v_mfma_i32_16x16x64_i8 v[30:33], v[172:175], v[164:167], v[30:33]
	ds_read_b128 v[160:163], v110 offset:4096
	ds_read_b128 v[164:167], v111
	s_waitcnt lgkmcnt(1)
	v_mfma_i32_16x16x64_i8 v[34:37], v[152:155], v[160:163], v[34:37]
	v_mfma_i32_16x16x64_i8 v[26:29], v[156:159], v[160:163], v[26:29]
	v_mfma_i32_16x16x64_i8 v[22:25], v[168:171], v[160:163], v[22:25]
	v_mfma_i32_16x16x64_i8 v[18:21], v[172:175], v[160:163], v[18:21]
	s_waitcnt lgkmcnt(0)
	v_mfma_i32_16x16x64_i8 v[14:17], v[152:155], v[164:167], v[14:17]
	ds_read_b128 v[152:155], v116 offset:16384
	v_mfma_i32_16x16x64_i8 v[10:13], v[156:159], v[164:167], v[10:13]
	v_mfma_i32_16x16x64_i8 v[6:9], v[168:171], v[164:167], v[6:9]
	v_mfma_i32_16x16x64_i8 v[2:5], v[172:175], v[164:167], v[2:5]
	ds_read_b128 v[156:159], v116 offset:18432
	ds_read_b128 v[160:163], v114
	ds_read_b128 v[164:167], v114 offset:2048
	ds_read_b128 v[168:171], v116 offset:20480
	ds_read_b128 v[172:175], v117 offset:16384
	s_waitcnt lgkmcnt(3)
	v_mfma_i32_16x16x64_i8 v[94:97], v[152:155], v[160:163], v[94:97]
	v_mfma_i32_16x16x64_i8 v[90:93], v[156:159], v[160:163], v[90:93]
	s_waitcnt lgkmcnt(1)
	v_mfma_i32_16x16x64_i8 v[86:89], v[168:171], v[160:163], v[86:89]
	s_waitcnt lgkmcnt(0)
	v_mfma_i32_16x16x64_i8 v[82:85], v[172:175], v[160:163], v[82:85]
	v_mfma_i32_16x16x64_i8 v[74:77], v[152:155], v[164:167], v[74:77]
	v_mfma_i32_16x16x64_i8 v[50:53], v[156:159], v[164:167], v[50:53]
	v_mfma_i32_16x16x64_i8 v[38:41], v[168:171], v[164:167], v[38:41]
	v_mfma_i32_16x16x64_i8 v[30:33], v[172:175], v[164:167], v[30:33]
	ds_read_b128 v[160:163], v114 offset:4096
	ds_read_b128 v[164:167], v115
	s_waitcnt lgkmcnt(1)
	v_mfma_i32_16x16x64_i8 v[34:37], v[152:155], v[160:163], v[34:37]
	v_mfma_i32_16x16x64_i8 v[26:29], v[156:159], v[160:163], v[26:29]
	v_mfma_i32_16x16x64_i8 v[22:25], v[168:171], v[160:163], v[22:25]
	v_mfma_i32_16x16x64_i8 v[18:21], v[172:175], v[160:163], v[18:21]
	s_waitcnt lgkmcnt(0)
	v_mfma_i32_16x16x64_i8 v[14:17], v[152:155], v[164:167], v[14:17]
	v_mfma_i32_16x16x64_i8 v[10:13], v[156:159], v[164:167], v[10:13]
	v_mfma_i32_16x16x64_i8 v[6:9], v[168:171], v[164:167], v[6:9]
	v_mfma_i32_16x16x64_i8 v[2:5], v[172:175], v[164:167], v[2:5]
	s_setprio 0
	s_min_u32 s4, s13, 0x100
	s_lshl_b32 s4, s4, 1
	s_waitcnt vmcnt(15)
	ds_write_b128 v107, v[42:45] offset:32768
	s_waitcnt vmcnt(14)
	ds_write_b128 v107, v[46:49] offset:49152
	s_waitcnt vmcnt(13)
	ds_write_b128 v107, v[54:57] offset:36864
	s_waitcnt vmcnt(10)
	ds_write_b128 v107, v[66:69] offset:53248
	ds_write_b128 v107, v[58:61] offset:40960
	s_waitcnt vmcnt(9)
	ds_write_b128 v107, v[70:73] offset:57344
	ds_write_b128 v107, v[62:65] offset:45056
	s_waitcnt vmcnt(8)
	ds_write_b128 v107, v[78:81] offset:61440
	v_lshl_add_u64 v[54:55], v[104:105], 0, s[4:5]
	v_add_co_u32_e32 v58, vcc, s7, v54
	v_lshl_add_u64 v[56:57], v[108:109], 0, s[4:5]
	s_nop 0
	v_addc_co_u32_e32 v59, vcc, 0, v55, vcc
	v_add_co_u32_e32 v60, vcc, s7, v56
	s_waitcnt lgkmcnt(0)
	s_nop 0
	v_addc_co_u32_e32 v61, vcc, 0, v57, vcc
	v_add_co_u32_e32 v62, vcc, s8, v54
	s_barrier
	s_nop 0
	v_addc_co_u32_e32 v63, vcc, 0, v55, vcc
	v_add_co_u32_e32 v64, vcc, s8, v56
	s_nop 1
	v_addc_co_u32_e32 v65, vcc, 0, v57, vcc
	v_add_co_u32_e32 v78, vcc, s9, v54
	global_load_dwordx4 v[42:45], v[54:55], off offset:384
	global_load_dwordx4 v[46:49], v[56:57], off offset:384
	v_addc_co_u32_e32 v79, vcc, 0, v55, vcc
	v_add_co_u32_e32 v80, vcc, s9, v56
	s_nop 1
	v_addc_co_u32_e32 v81, vcc, 0, v57, vcc
	global_load_dwordx4 v[54:57], v[58:59], off offset:384
	global_load_dwordx4 v[66:69], v[60:61], off offset:384
	s_nop 0
	global_load_dwordx4 v[58:61], v[62:63], off offset:384
	global_load_dwordx4 v[70:73], v[64:65], off offset:384
	s_nop 0
	global_load_dwordx4 v[62:65], v[78:79], off offset:384
	s_nop 0
	global_load_dwordx4 v[78:81], v[80:81], off offset:384
	s_setprio 1
	ds_read_b128 v[152:155], v112 offset:49152
	ds_read_b128 v[156:159], v112 offset:51200
	ds_read_b128 v[160:163], v110 offset:32768
	ds_read_b128 v[164:167], v110 offset:34816
	ds_read_b128 v[168:171], v112 offset:53248
	ds_read_b128 v[172:175], v113 offset:49152
	s_waitcnt lgkmcnt(3)
	v_mfma_i32_16x16x64_i8 v[94:97], v[152:155], v[160:163], v[94:97]
	v_mfma_i32_16x16x64_i8 v[90:93], v[156:159], v[160:163], v[90:93]
	s_waitcnt lgkmcnt(1)
	v_mfma_i32_16x16x64_i8 v[86:89], v[168:171], v[160:163], v[86:89]
	s_waitcnt lgkmcnt(0)
	v_mfma_i32_16x16x64_i8 v[82:85], v[172:175], v[160:163], v[82:85]
	v_mfma_i32_16x16x64_i8 v[74:77], v[152:155], v[164:167], v[74:77]
	v_mfma_i32_16x16x64_i8 v[50:53], v[156:159], v[164:167], v[50:53]
	v_mfma_i32_16x16x64_i8 v[38:41], v[168:171], v[164:167], v[38:41]
	v_mfma_i32_16x16x64_i8 v[30:33], v[172:175], v[164:167], v[30:33]
	ds_read_b128 v[160:163], v110 offset:36864
	ds_read_b128 v[164:167], v111 offset:32768
	s_waitcnt lgkmcnt(1)
	v_mfma_i32_16x16x64_i8 v[34:37], v[152:155], v[160:163], v[34:37]
	v_mfma_i32_16x16x64_i8 v[26:29], v[156:159], v[160:163], v[26:29]
	v_mfma_i32_16x16x64_i8 v[22:25], v[168:171], v[160:163], v[22:25]
	v_mfma_i32_16x16x64_i8 v[18:21], v[172:175], v[160:163], v[18:21]
	s_waitcnt lgkmcnt(0)
	v_mfma_i32_16x16x64_i8 v[14:17], v[152:155], v[164:167], v[14:17]
	ds_read_b128 v[152:155], v116 offset:49152
	v_mfma_i32_16x16x64_i8 v[10:13], v[156:159], v[164:167], v[10:13]
	v_mfma_i32_16x16x64_i8 v[6:9], v[168:171], v[164:167], v[6:9]
	v_mfma_i32_16x16x64_i8 v[2:5], v[172:175], v[164:167], v[2:5]
	ds_read_b128 v[156:159], v116 offset:51200
	ds_read_b128 v[160:163], v114 offset:32768
	ds_read_b128 v[164:167], v114 offset:34816
	ds_read_b128 v[168:171], v116 offset:53248
	ds_read_b128 v[172:175], v117 offset:49152
	s_waitcnt lgkmcnt(3)
	v_mfma_i32_16x16x64_i8 v[94:97], v[152:155], v[160:163], v[94:97]
	v_mfma_i32_16x16x64_i8 v[90:93], v[156:159], v[160:163], v[90:93]
	s_waitcnt lgkmcnt(1)
	v_mfma_i32_16x16x64_i8 v[86:89], v[168:171], v[160:163], v[86:89]
	s_waitcnt lgkmcnt(0)
	v_mfma_i32_16x16x64_i8 v[82:85], v[172:175], v[160:163], v[82:85]
	v_mfma_i32_16x16x64_i8 v[74:77], v[152:155], v[164:167], v[74:77]
	v_mfma_i32_16x16x64_i8 v[50:53], v[156:159], v[164:167], v[50:53]
	v_mfma_i32_16x16x64_i8 v[38:41], v[168:171], v[164:167], v[38:41]
	v_mfma_i32_16x16x64_i8 v[30:33], v[172:175], v[164:167], v[30:33]
	ds_read_b128 v[160:163], v114 offset:36864
	ds_read_b128 v[164:167], v115 offset:32768
	s_waitcnt lgkmcnt(1)
	v_mfma_i32_16x16x64_i8 v[34:37], v[152:155], v[160:163], v[34:37]
	v_mfma_i32_16x16x64_i8 v[26:29], v[156:159], v[160:163], v[26:29]
	v_mfma_i32_16x16x64_i8 v[22:25], v[168:171], v[160:163], v[22:25]
	v_mfma_i32_16x16x64_i8 v[18:21], v[172:175], v[160:163], v[18:21]
	s_waitcnt lgkmcnt(0)
	v_mfma_i32_16x16x64_i8 v[14:17], v[152:155], v[164:167], v[14:17]
	v_mfma_i32_16x16x64_i8 v[10:13], v[156:159], v[164:167], v[10:13]
	v_mfma_i32_16x16x64_i8 v[6:9], v[168:171], v[164:167], v[6:9]
	v_mfma_i32_16x16x64_i8 v[2:5], v[172:175], v[164:167], v[2:5]
	s_setprio 0
	s_add_i32 s12, s12, 2
	s_cmp_lt_u32 s12, 6
	s_mov_b32 s13, s14
	s_waitcnt vmcnt(15)
	ds_write_b128 v107, v[120:123]
	s_waitcnt vmcnt(14)
	ds_write_b128 v107, v[124:127] offset:16384
	s_waitcnt vmcnt(13)
	ds_write_b128 v107, v[128:131] offset:4096
	s_waitcnt vmcnt(12)
	ds_write_b128 v107, v[132:135] offset:20480
	s_waitcnt vmcnt(11)
	ds_write_b128 v107, v[136:139] offset:8192
	s_waitcnt vmcnt(10)
	ds_write_b128 v107, v[140:143] offset:24576
	s_waitcnt vmcnt(9)
	ds_write_b128 v107, v[144:147] offset:12288
	s_waitcnt vmcnt(8)
	ds_write_b128 v107, v[148:151] offset:28672
	s_waitcnt lgkmcnt(0)
	s_barrier
	s_cbranch_scc1 .LBB0_519
	v_cvt_f32_i32_e32 v94, v94
	v_cvt_f32_i32_e32 v95, v95
	v_cvt_f32_i32_e32 v96, v96
	v_cvt_f32_i32_e32 v97, v97
	v_cvt_f32_i32_e32 v90, v90
	v_cvt_f32_i32_e32 v91, v91
	v_cvt_f32_i32_e32 v92, v92
	v_cvt_f32_i32_e32 v93, v93
	v_cvt_f32_i32_e32 v86, v86
	v_cvt_f32_i32_e32 v87, v87
	v_cvt_f32_i32_e32 v88, v88
	v_cvt_f32_i32_e32 v89, v89
	v_cvt_f32_i32_e32 v82, v82
	v_cvt_f32_i32_e32 v83, v83
	v_cvt_f32_i32_e32 v84, v84
	v_cvt_f32_i32_e32 v85, v85
	v_cvt_f32_i32_e32 v74, v74
	v_cvt_f32_i32_e32 v75, v75
	v_cvt_f32_i32_e32 v76, v76
	v_cvt_f32_i32_e32 v77, v77
	v_cvt_f32_i32_e32 v50, v50
	v_cvt_f32_i32_e32 v51, v51
	v_cvt_f32_i32_e32 v52, v52
	v_cvt_f32_i32_e32 v53, v53
	v_cvt_f32_i32_e32 v38, v38
	v_cvt_f32_i32_e32 v39, v39
	v_cvt_f32_i32_e32 v40, v40
	v_cvt_f32_i32_e32 v41, v41
	v_cvt_f32_i32_e32 v30, v30
	v_cvt_f32_i32_e32 v31, v31
	v_cvt_f32_i32_e32 v32, v32
	v_cvt_f32_i32_e32 v33, v33
	v_cvt_f32_i32_e32 v34, v34
	v_cvt_f32_i32_e32 v35, v35
	v_cvt_f32_i32_e32 v36, v36
	v_cvt_f32_i32_e32 v37, v37
	v_cvt_f32_i32_e32 v26, v26
	v_cvt_f32_i32_e32 v27, v27
	v_cvt_f32_i32_e32 v28, v28
	v_cvt_f32_i32_e32 v29, v29
	v_cvt_f32_i32_e32 v22, v22
	v_cvt_f32_i32_e32 v23, v23
	v_cvt_f32_i32_e32 v24, v24
	v_cvt_f32_i32_e32 v25, v25
	v_cvt_f32_i32_e32 v18, v18
	v_cvt_f32_i32_e32 v19, v19
	v_cvt_f32_i32_e32 v20, v20
	v_cvt_f32_i32_e32 v21, v21
	v_cvt_f32_i32_e32 v14, v14
	v_cvt_f32_i32_e32 v15, v15
	v_cvt_f32_i32_e32 v16, v16
	v_cvt_f32_i32_e32 v17, v17
	v_cvt_f32_i32_e32 v10, v10
	v_cvt_f32_i32_e32 v11, v11
	v_cvt_f32_i32_e32 v12, v12
	v_cvt_f32_i32_e32 v13, v13
	v_cvt_f32_i32_e32 v6, v6
	v_cvt_f32_i32_e32 v7, v7
	v_cvt_f32_i32_e32 v8, v8
	v_cvt_f32_i32_e32 v9, v9
	v_cvt_f32_i32_e32 v2, v2
	v_cvt_f32_i32_e32 v3, v3
	v_cvt_f32_i32_e32 v4, v4
	v_cvt_f32_i32_e32 v5, v5
	s_waitcnt vmcnt(0)
	v_add_u32_e32 v98, s10, v118
	v_or_b32_e32 v146, s11, v119
	v_lshl_add_u64 v[144:145], v[98:99], 2, s[68:69]
	v_lshlrev_b32_e32 v148, 2, v146
	global_load_dword v136, v[144:145], off
	global_load_dword v138, v[144:145], off offset:64
	global_load_dword v140, v[144:145], off offset:128
	global_load_dword v142, v[144:145], off offset:192
	global_load_dwordx4 v[120:123], v148, s[74:75]
	global_load_dwordx4 v[124:127], v148, s[74:75] offset:64
	global_load_dwordx4 v[128:131], v148, s[74:75] offset:128
	global_load_dwordx4 v[132:135], v148, s[74:75] offset:192
	v_lshlrev_b32_e32 v146, 1, v146
	v_mov_b32_e32 v147, v99
	v_lshlrev_b64 v[42:43], 12, v[98:99]
	v_lshl_add_u64 v[42:43], s[64:65], 0, v[42:43]
	v_lshl_add_u64 v[42:43], v[42:43], 0, v[146:147]
	v_or_b32_e32 v54, 16, v98
	v_mov_b32_e32 v55, v99
	v_lshlrev_b64 v[44:45], 12, v[54:55]
	v_lshl_add_u64 v[44:45], s[64:65], 0, v[44:45]
	v_lshl_add_u64 v[44:45], v[44:45], 0, v[146:147]
	v_or_b32_e32 v54, 32, v98
	v_mov_b32_e32 v55, v99
	v_lshlrev_b64 v[46:47], 12, v[54:55]
	v_lshl_add_u64 v[46:47], s[64:65], 0, v[46:47]
	v_lshl_add_u64 v[46:47], v[46:47], 0, v[146:147]
	v_or_b32_e32 v54, 48, v98
	v_mov_b32_e32 v55, v99
	v_lshlrev_b64 v[48:49], 12, v[54:55]
	v_lshl_add_u64 v[48:49], s[64:65], 0, v[48:49]
	v_lshl_add_u64 v[48:49], v[48:49], 0, v[146:147]
	s_waitcnt vmcnt(0)
	v_pk_mul_f32 v[94:95], v[136:137], v[94:95] op_sel_hi:[0,1]
	v_pk_mul_f32 v[96:97], v[136:137], v[96:97] op_sel_hi:[0,1]
	v_pk_mul_f32 v[94:95], v[120:121], v[94:95]
	v_pk_mul_f32 v[96:97], v[96:97], v[122:123]
	v_cvt_pk_bf16_f32 v94, v94, v95
	v_cvt_pk_bf16_f32 v95, v96, v97
	global_store_dwordx2 v[42:43], v[94:95], off
	v_pk_mul_f32 v[90:91], v[136:137], v[90:91] op_sel_hi:[0,1]
	v_pk_mul_f32 v[92:93], v[136:137], v[92:93] op_sel_hi:[0,1]
	v_pk_mul_f32 v[90:91], v[124:125], v[90:91]
	v_pk_mul_f32 v[92:93], v[92:93], v[126:127]
	v_cvt_pk_bf16_f32 v90, v90, v91
	v_cvt_pk_bf16_f32 v91, v92, v93
	global_store_dwordx2 v[42:43], v[90:91], off offset:32
	v_pk_mul_f32 v[86:87], v[136:137], v[86:87] op_sel_hi:[0,1]
	v_pk_mul_f32 v[88:89], v[136:137], v[88:89] op_sel_hi:[0,1]
	v_pk_mul_f32 v[86:87], v[128:129], v[86:87]
	v_pk_mul_f32 v[88:89], v[88:89], v[130:131]
	v_cvt_pk_bf16_f32 v86, v86, v87
	v_cvt_pk_bf16_f32 v87, v88, v89
	global_store_dwordx2 v[42:43], v[86:87], off offset:64
	v_pk_mul_f32 v[82:83], v[136:137], v[82:83] op_sel_hi:[0,1]
	v_pk_mul_f32 v[84:85], v[136:137], v[84:85] op_sel_hi:[0,1]
	v_pk_mul_f32 v[82:83], v[132:133], v[82:83]
	v_pk_mul_f32 v[84:85], v[84:85], v[134:135]
	v_cvt_pk_bf16_f32 v82, v82, v83
	v_cvt_pk_bf16_f32 v83, v84, v85
	global_store_dwordx2 v[42:43], v[82:83], off offset:96
	v_pk_mul_f32 v[74:75], v[138:139], v[74:75] op_sel_hi:[0,1]
	v_pk_mul_f32 v[76:77], v[138:139], v[76:77] op_sel_hi:[0,1]
	v_pk_mul_f32 v[74:75], v[120:121], v[74:75]
	v_pk_mul_f32 v[76:77], v[76:77], v[122:123]
	v_cvt_pk_bf16_f32 v74, v74, v75
	v_cvt_pk_bf16_f32 v75, v76, v77
	global_store_dwordx2 v[44:45], v[74:75], off
	v_pk_mul_f32 v[50:51], v[138:139], v[50:51] op_sel_hi:[0,1]
	v_pk_mul_f32 v[52:53], v[138:139], v[52:53] op_sel_hi:[0,1]
	v_pk_mul_f32 v[50:51], v[124:125], v[50:51]
	v_pk_mul_f32 v[52:53], v[52:53], v[126:127]
	v_cvt_pk_bf16_f32 v50, v50, v51
	v_cvt_pk_bf16_f32 v51, v52, v53
	global_store_dwordx2 v[44:45], v[50:51], off offset:32
	v_pk_mul_f32 v[38:39], v[138:139], v[38:39] op_sel_hi:[0,1]
	v_pk_mul_f32 v[40:41], v[138:139], v[40:41] op_sel_hi:[0,1]
	v_pk_mul_f32 v[38:39], v[128:129], v[38:39]
	v_pk_mul_f32 v[40:41], v[40:41], v[130:131]
	v_cvt_pk_bf16_f32 v38, v38, v39
	v_cvt_pk_bf16_f32 v39, v40, v41
	global_store_dwordx2 v[44:45], v[38:39], off offset:64
	v_pk_mul_f32 v[30:31], v[138:139], v[30:31] op_sel_hi:[0,1]
	v_pk_mul_f32 v[32:33], v[138:139], v[32:33] op_sel_hi:[0,1]
	v_pk_mul_f32 v[30:31], v[132:133], v[30:31]
	v_pk_mul_f32 v[32:33], v[32:33], v[134:135]
	v_cvt_pk_bf16_f32 v30, v30, v31
	v_cvt_pk_bf16_f32 v31, v32, v33
	global_store_dwordx2 v[44:45], v[30:31], off offset:96
	v_pk_mul_f32 v[34:35], v[140:141], v[34:35] op_sel_hi:[0,1]
	v_pk_mul_f32 v[36:37], v[140:141], v[36:37] op_sel_hi:[0,1]
	v_pk_mul_f32 v[34:35], v[120:121], v[34:35]
	v_pk_mul_f32 v[36:37], v[36:37], v[122:123]
	v_cvt_pk_bf16_f32 v34, v34, v35
	v_cvt_pk_bf16_f32 v35, v36, v37
	global_store_dwordx2 v[46:47], v[34:35], off
	v_pk_mul_f32 v[26:27], v[140:141], v[26:27] op_sel_hi:[0,1]
	v_pk_mul_f32 v[28:29], v[140:141], v[28:29] op_sel_hi:[0,1]
	v_pk_mul_f32 v[26:27], v[124:125], v[26:27]
	v_pk_mul_f32 v[28:29], v[28:29], v[126:127]
	v_cvt_pk_bf16_f32 v26, v26, v27
	v_cvt_pk_bf16_f32 v27, v28, v29
	global_store_dwordx2 v[46:47], v[26:27], off offset:32
	v_pk_mul_f32 v[22:23], v[140:141], v[22:23] op_sel_hi:[0,1]
	v_pk_mul_f32 v[24:25], v[140:141], v[24:25] op_sel_hi:[0,1]
	v_pk_mul_f32 v[22:23], v[128:129], v[22:23]
	v_pk_mul_f32 v[24:25], v[24:25], v[130:131]
	v_cvt_pk_bf16_f32 v22, v22, v23
	v_cvt_pk_bf16_f32 v23, v24, v25
	global_store_dwordx2 v[46:47], v[22:23], off offset:64
	v_pk_mul_f32 v[18:19], v[140:141], v[18:19] op_sel_hi:[0,1]
	v_pk_mul_f32 v[20:21], v[140:141], v[20:21] op_sel_hi:[0,1]
	v_pk_mul_f32 v[18:19], v[132:133], v[18:19]
	v_pk_mul_f32 v[20:21], v[20:21], v[134:135]
	v_cvt_pk_bf16_f32 v18, v18, v19
	v_cvt_pk_bf16_f32 v19, v20, v21
	global_store_dwordx2 v[46:47], v[18:19], off offset:96
	v_pk_mul_f32 v[14:15], v[142:143], v[14:15] op_sel_hi:[0,1]
	v_pk_mul_f32 v[16:17], v[142:143], v[16:17] op_sel_hi:[0,1]
	v_pk_mul_f32 v[14:15], v[120:121], v[14:15]
	v_pk_mul_f32 v[16:17], v[16:17], v[122:123]
	v_cvt_pk_bf16_f32 v14, v14, v15
	v_cvt_pk_bf16_f32 v15, v16, v17
	global_store_dwordx2 v[48:49], v[14:15], off
	v_pk_mul_f32 v[10:11], v[142:143], v[10:11] op_sel_hi:[0,1]
	v_pk_mul_f32 v[12:13], v[142:143], v[12:13] op_sel_hi:[0,1]
	v_pk_mul_f32 v[10:11], v[124:125], v[10:11]
	v_pk_mul_f32 v[12:13], v[12:13], v[126:127]
	v_cvt_pk_bf16_f32 v10, v10, v11
	v_cvt_pk_bf16_f32 v11, v12, v13
	global_store_dwordx2 v[48:49], v[10:11], off offset:32
	v_pk_mul_f32 v[6:7], v[142:143], v[6:7] op_sel_hi:[0,1]
	v_pk_mul_f32 v[8:9], v[142:143], v[8:9] op_sel_hi:[0,1]
	v_pk_mul_f32 v[6:7], v[128:129], v[6:7]
	v_pk_mul_f32 v[8:9], v[8:9], v[130:131]
	v_cvt_pk_bf16_f32 v6, v6, v7
	v_cvt_pk_bf16_f32 v7, v8, v9
	global_store_dwordx2 v[48:49], v[6:7], off offset:64
	v_pk_mul_f32 v[2:3], v[142:143], v[2:3] op_sel_hi:[0,1]
	v_pk_mul_f32 v[4:5], v[142:143], v[4:5] op_sel_hi:[0,1]
	v_pk_mul_f32 v[2:3], v[132:133], v[2:3]
	v_pk_mul_f32 v[4:5], v[4:5], v[134:135]
	v_cvt_pk_bf16_f32 v2, v2, v3
	v_cvt_pk_bf16_f32 v3, v4, v5
	global_store_dwordx2 v[48:49], v[2:3], off offset:96
	s_add_i32 s6, s6, s3
	s_cmpk_lt_u32 s6, 0x200
	s_cbranch_scc1 .LBB0_518

.LBB0_606:
	v_lshrrev_b32_e32 v1, 6, v106
	v_lshl_add_u32 v108, s96, 2, v1
	s_mov_b32 s0, 0x8000
	v_cmp_gt_i32_e32 vcc, s0, v108
	s_and_saveexec_b64 s[42:43], vcc
	s_cbranch_execz .LBB0_621
	v_readlane_b32 s4, v254, 40
	v_mov_b32_e32 v111, 0
	v_and_b32_e32 v6, 1, v106
	v_and_b32_e32 v4, 48, v106
	v_readlane_b32 s5, v254, 41
	v_readlane_b32 s6, v254, 42
	v_readlane_b32 s7, v254, 43
	v_readlane_b32 s8, v254, 44
	v_readlane_b32 s9, v254, 45
	v_readlane_b32 s10, v254, 46
	v_readlane_b32 s11, v254, 47
	v_readlane_b32 s12, v254, 48
	v_readlane_b32 s13, v254, 49
	v_readlane_b32 s14, v254, 50
	v_readlane_b32 s15, v254, 51
	v_and_b32_e32 v10, 15, v106
	v_lshl_or_b32 v4, v6, 6, v4
	v_mov_b32_e32 v5, v111
	v_readlane_b32 s16, v254, 52
	v_readlane_b32 s17, v254, 53
	v_readlane_b32 s18, v254, 54
	v_readlane_b32 s19, v254, 55
	s_mov_b64 s[4:5], s[8:9]
	v_bfe_u32 v3, v106, 4, 2
	v_lshl_add_u64 v[112:113], s[4:5], 0, v[4:5]
	v_lshlrev_b32_e32 v4, 5, v10
	v_mov_b32_e32 v2, 0x110
	v_lshlrev_b32_e32 v12, 5, v3
	v_lshlrev_b32_e32 v7, 1, v106
	v_lshl_or_b32 v4, v3, 3, v4
	v_mbcnt_lo_u32_b32 v3, -1, 0
	v_lshl_add_u32 v1, v1, 11, v2
	v_and_b32_e32 v11, 63, v106
	v_and_b32_e32 v7, 28, v7
	v_mbcnt_hi_u32_b32 v3, -1, v3
	v_lshl_add_u32 v13, v6, 7, v1
	v_add_u32_e32 v148, v1, v7
	s_mov_b64 s[6:7], s[10:11]
	v_cmp_eq_u32_e32 vcc, 0, v6
	v_and_b32_e32 v5, 64, v3
	v_lshlrev_b32_e32 v6, 3, v11
	v_mov_b32_e32 v7, v111
	v_add_u32_e32 v5, 64, v5
	v_lshl_add_u64 v[114:115], s[6:7], 0, v[6:7]
	v_xor_b32_e32 v6, 32, v3
	v_cmp_lt_i32_e64 s[36:37], v6, v5
	v_readlane_b32 s44, v254, 24
	v_readlane_b32 s46, v254, 26
	v_cndmask_b32_e64 v6, v3, v6, s[36:37]
	v_lshlrev_b32_e32 v150, 2, v6
	v_xor_b32_e32 v6, 16, v3
	v_cmp_lt_i32_e64 s[36:37], v6, v5
	v_readlane_b32 s47, v254, 27
	s_add_u32 s0, s46, 0x1000
	v_cndmask_b32_e64 v6, v3, v6, s[36:37]
	v_lshlrev_b32_e32 v151, 2, v6
	v_xor_b32_e32 v6, 8, v3
	v_cmp_lt_i32_e64 s[36:37], v6, v5
	s_addc_u32 s1, s47, 0
	v_readlane_b32 s45, v254, 25
	v_cndmask_b32_e64 v6, v3, v6, s[36:37]
	v_lshlrev_b32_e32 v152, 2, v6
	v_xor_b32_e32 v6, 4, v3
	v_cmp_lt_i32_e64 s[36:37], v6, v5
	s_add_u32 s38, s44, 0x1000
	s_addc_u32 s39, s45, 0
	v_cndmask_b32_e64 v6, v3, v6, s[36:37]
	v_lshlrev_b32_e32 v153, 2, v6
	v_xor_b32_e32 v6, 2, v3
	v_cmp_lt_i32_e64 s[36:37], v6, v5
	v_mov_b32_e32 v9, v111
	v_lshlrev_b32_e32 v2, 2, v11
	v_cndmask_b32_e64 v6, v3, v6, s[36:37]
	v_lshlrev_b32_e32 v154, 2, v6
	v_xor_b32_e32 v6, 1, v3
	v_cmp_lt_i32_e64 s[36:37], v6, v5
	v_readlane_b32 s2, v254, 0
	v_readlane_b32 s48, v254, 28
	v_cndmask_b32_e64 v3, v3, v6, s[36:37]
	v_lshlrev_b32_e32 v6, 6, v11
	v_or_b32_e32 v8, 16, v6
	v_lshlrev_b32_e32 v155, 2, v3
	v_lshl_add_u64 v[120:121], s[38:39], 0, v[8:9]
	v_lshl_add_u64 v[122:123], s[0:1], 0, v[8:9]
	v_or_b32_e32 v8, 32, v6
	v_mov_b32_e32 v3, v111
	v_readlane_b32 s49, v254, 29
	v_add_u32_e32 v107, v1, v2
	v_lshlrev_b32_e32 v110, 4, v11
	s_mov_b64 s[8:9], s[12:13]
	s_mov_b64 s[10:11], s[14:15]
	s_mov_b64 s[12:13], s[16:17]
	s_mov_b64 s[14:15], s[18:19]
	v_readlane_b32 s3, v254, 1
	v_lshl_add_u64 v[124:125], s[38:39], 0, v[8:9]
	v_lshl_add_u64 v[126:127], s[0:1], 0, v[8:9]
	v_or_b32_e32 v8, 48, v6
	v_lshl_add_u64 v[132:133], s[90:91], 0, v[2:3]
	v_mov_b32_e32 v5, v111
	v_lshlrev_b32_e32 v2, 5, v11
	v_add_u32_e32 v149, v1, v4
	s_lshl_b32 s2, s2, 2
	v_cmp_eq_u32_e64 s[4:5], 0, v10
	v_cmp_eq_u32_e64 s[6:7], 1, v10
	v_cmp_eq_u32_e64 s[8:9], 2, v10
	v_cmp_eq_u32_e64 s[10:11], 3, v10
	v_cmp_eq_u32_e64 s[12:13], 4, v10
	v_cmp_eq_u32_e64 s[14:15], 5, v10
	v_cmp_eq_u32_e64 s[16:17], 6, v10
	v_cmp_eq_u32_e64 s[18:19], 7, v10
	v_cmp_eq_u32_e64 s[20:21], 11, v10
	v_cmp_eq_u32_e64 s[22:23], 10, v10
	v_cmp_eq_u32_e64 s[24:25], 9, v10
	v_cmp_eq_u32_e64 s[26:27], 8, v10
	v_cmp_eq_u32_e64 s[28:29], 12, v10
	v_cmp_eq_u32_e64 s[30:31], 13, v10
	v_cmp_eq_u32_e64 s[34:35], 14, v10
	v_lshl_add_u64 v[116:117], s[38:39], 0, v[6:7]
	v_lshl_add_u64 v[118:119], s[0:1], 0, v[6:7]
	v_lshl_add_u64 v[128:129], s[38:39], 0, v[8:9]
	v_lshl_add_u64 v[130:131], s[0:1], 0, v[8:9]
	v_lshl_add_u64 v[134:135], s[94:95], 0, v[110:111]
	v_lshl_add_u64 v[136:137], s[82:83], 0, v[6:7]
	v_lshl_add_u64 v[138:139], s[92:93], 0, v[4:5]
	v_lshl_add_u64 v[140:141], s[48:49], 0, v[6:7]
	v_lshl_add_u64 v[142:143], s[82:83], 0, v[2:3]
	v_add_u32_e32 v111, 64, v1
	v_add_u32_e32 v156, v13, v12
	s_mov_b32 s3, 0x378e98ab
	s_mov_b32 s33, 0x3b7cd369
	s_mov_b32 s47, 0xbcc618b2
	s_mov_b32 s64, 0x3dda74e4
	s_mov_b32 s65, 0x3f228afd
	s_mov_b32 s66, 0x3e03c728
	s_mov_b32 s67, 0xbfb8aa3b
	s_mov_b32 s76, 0x42ce8ed0
	s_mov_b32 s77, 0xc2b17218
	v_mov_b32_e32 v157, 0x3ba10414
	s_brev_b32 s78, -2
	v_mov_b32_e32 v158, 0x3727c5ac
	v_mov_b32_e32 v159, 0xb9c68948
	v_mov_b32_e32 v160, 0x7f800000
	v_mov_b32_e32 v161, 15
	v_cmp_eq_u32_e64 s[36:37], 15, v10
	s_mov_b64 s[44:45], 0
	s_mov_b32 s46, 0x3fb504f3
	v_readlane_b32 s50, v254, 30
	v_readlane_b32 s51, v254, 31
	v_readlane_b32 s52, v254, 32
	v_readlane_b32 s53, v254, 33
	v_readlane_b32 s54, v254, 34
	v_readlane_b32 s55, v254, 35
	v_readlane_b32 s56, v254, 36
	v_readlane_b32 s57, v254, 37
	v_readlane_b32 s58, v254, 38
	v_readlane_b32 s59, v254, 39
	v_mov_b32_e32 v228, v108
	v_mov_b32_e32 v229, 0
	v_lshlrev_b64 v[230:231], 9, v[228:229]
	v_lshlrev_b64 v[232:233], 10, v[228:229]
	v_lshlrev_b64 v[234:235], 2, v[228:229]
	v_lshl_add_u64 v[230:231], v[132:133], 0, v[230:231]
	v_lshl_add_u64 v[232:233], v[134:135], 0, v[232:233]
	v_lshl_add_u64 v[236:237], s[68:69], 0, v[234:235]
	v_lshl_add_u64 v[234:235], s[70:71], 0, v[234:235]
	global_load_dword v246, v[230:231], off
	global_load_dword v247, v[230:231], off offset:256
	global_load_dwordx4 v[248:251], v[232:233], off
	global_load_dword v252, v[236:237], off
	global_load_dword v253, v[234:235], off
	s_waitcnt vmcnt(0)
	s_branch .LBB0_609
.LBB0_608:
	v_lshlrev_b64 v[22:23], 2, v[144:145]
	v_add_f32_e32 v18, v101, v162
	v_mul_f32_e32 v18, 0x40f00000, v18
	s_mov_b32 s0, 0x800000
	v_lshl_add_u64 v[22:23], v[140:141], 0, v[22:23]
	v_pk_fma_f32 v[2:3], v[228:229], s[46:47], v[18:19] op_sel_hi:[1,0,0] neg_lo:[0,0,1] neg_hi:[0,0,1]
	v_pk_fma_f32 v[4:5], v[230:231], s[46:47], v[18:19] op_sel_hi:[1,0,0] neg_lo:[0,0,1] neg_hi:[0,0,1]
	v_pk_fma_f32 v[6:7], v[232:233], s[46:47], v[18:19] op_sel_hi:[1,0,0] neg_lo:[0,0,1] neg_hi:[0,0,1]
	v_pk_fma_f32 v[8:9], v[234:235], s[46:47], v[18:19] op_sel_hi:[1,0,0] neg_lo:[0,0,1] neg_hi:[0,0,1]
	v_pk_fma_f32 v[10:11], v[236:237], s[46:47], v[18:19] op_sel_hi:[1,0,0] neg_lo:[0,0,1] neg_hi:[0,0,1]
	v_pk_fma_f32 v[12:13], v[238:239], s[46:47], v[18:19] op_sel_hi:[1,0,0] neg_lo:[0,0,1] neg_hi:[0,0,1]
	v_pk_fma_f32 v[14:15], v[240:241], s[46:47], v[18:19] op_sel_hi:[1,0,0] neg_lo:[0,0,1] neg_hi:[0,0,1]
	v_pk_fma_f32 v[16:17], v[242:243], s[46:47], v[18:19] op_sel_hi:[1,0,0] neg_lo:[0,0,1] neg_hi:[0,0,1]
	v_pk_add_f32 v[18:19], v[92:93], v[2:3]
	v_pk_add_f32 v[20:21], v[90:91], v[4:5]
	v_add_f32_e32 v2, 0, v18
	v_add_f32_e32 v2, v2, v19
	v_add_f32_e32 v2, v2, v20
	v_pk_add_f32 v[24:25], v[86:87], v[6:7]
	v_add_f32_e32 v2, v2, v21
	v_add_f32_e32 v2, v2, v24
	v_pk_add_f32 v[26:27], v[84:85], v[8:9]
	v_add_f32_e32 v2, v2, v25
	v_add_f32_e32 v2, v2, v26
	v_pk_add_f32 v[10:11], v[80:81], v[10:11]
	v_add_f32_e32 v2, v2, v27
	v_add_f32_e32 v2, v2, v10
	v_pk_add_f32 v[12:13], v[78:79], v[12:13]
	v_add_f32_e32 v2, v2, v11
	v_add_f32_e32 v2, v2, v12
	v_pk_add_f32 v[14:15], v[70:71], v[14:15]
	v_add_f32_e32 v2, v2, v13
	v_add_f32_e32 v2, v2, v14
	v_pk_add_f32 v[16:17], v[62:63], v[16:17]
	v_add_f32_e32 v2, v2, v15
	v_add_f32_e32 v2, v2, v16
	v_add_f32_e32 v2, v2, v17
	ds_bpermute_b32 v3, v150, v2
	s_waitcnt lgkmcnt(0)
	v_add_f32_e32 v2, v2, v3
	ds_bpermute_b32 v3, v151, v2
	s_waitcnt lgkmcnt(0)
	v_add_f32_e32 v2, v2, v3
	ds_bpermute_b32 v3, v152, v2
	s_waitcnt lgkmcnt(0)
	v_add_f32_e32 v2, v2, v3
	ds_bpermute_b32 v3, v153, v2
	s_waitcnt lgkmcnt(0)
	v_add_f32_e32 v2, v2, v3
	ds_bpermute_b32 v3, v154, v2
	s_waitcnt lgkmcnt(0)
	v_add_f32_e32 v28, v2, v3
	global_load_dwordx4 v[2:5], v[116:117], off
	global_load_dwordx4 v[6:9], v[118:119], off
	ds_bpermute_b32 v29, v155, v28
	s_waitcnt lgkmcnt(0)
	v_add_f32_e32 v28, v28, v29
	v_mul_f32_e32 v28, 0x3a800000, v28
	v_pk_add_f32 v[18:19], v[18:19], v[28:29] op_sel_hi:[1,0] neg_lo:[0,1] neg_hi:[0,1]
	v_pk_add_f32 v[20:21], v[20:21], v[28:29] op_sel_hi:[1,0] neg_lo:[0,1] neg_hi:[0,1]
	v_pk_add_f32 v[30:31], v[10:11], v[28:29] op_sel_hi:[1,0] neg_lo:[0,1] neg_hi:[0,1]
	v_pk_mul_f32 v[10:11], v[18:19], v[18:19]
	v_pk_add_f32 v[32:33], v[12:13], v[28:29] op_sel_hi:[1,0] neg_lo:[0,1] neg_hi:[0,1]
	v_pk_mul_f32 v[12:13], v[20:21], v[20:21]
	v_add_f32_e32 v10, v10, v11
	v_pk_add_f32 v[24:25], v[24:25], v[28:29] op_sel_hi:[1,0] neg_lo:[0,1] neg_hi:[0,1]
	v_add_f32_e32 v10, v12, v10
	v_pk_add_f32 v[34:35], v[14:15], v[28:29] op_sel_hi:[1,0] neg_lo:[0,1] neg_hi:[0,1]
	v_pk_mul_f32 v[14:15], v[24:25], v[24:25]
	v_add_f32_e32 v10, v13, v10
	v_pk_add_f32 v[26:27], v[26:27], v[28:29] op_sel_hi:[1,0] neg_lo:[0,1] neg_hi:[0,1]
	v_add_f32_e32 v10, v14, v10
	v_pk_add_f32 v[28:29], v[16:17], v[28:29] op_sel_hi:[1,0] neg_lo:[0,1] neg_hi:[0,1]
	v_pk_mul_f32 v[16:17], v[26:27], v[26:27]
	v_add_f32_e32 v10, v15, v10
	v_add_f32_e32 v10, v16, v10
	v_pk_mul_f32 v[36:37], v[30:31], v[30:31]
	v_add_f32_e32 v10, v17, v10
	v_add_f32_e32 v10, v36, v10
	v_pk_mul_f32 v[38:39], v[32:33], v[32:33]
	v_add_f32_e32 v10, v37, v10
	v_add_f32_e32 v10, v38, v10
	v_pk_mul_f32 v[40:41], v[34:35], v[34:35]
	v_add_f32_e32 v10, v39, v10
	v_add_f32_e32 v10, v40, v10
	v_pk_mul_f32 v[42:43], v[28:29], v[28:29]
	v_add_f32_e32 v10, v41, v10
	v_add_f32_e32 v10, v42, v10
	v_add_f32_e32 v10, v43, v10
	ds_bpermute_b32 v11, v150, v10
	s_waitcnt lgkmcnt(0)
	v_add_f32_e32 v10, v10, v11
	ds_bpermute_b32 v11, v151, v10
	s_waitcnt lgkmcnt(0)
	v_add_f32_e32 v10, v10, v11
	ds_bpermute_b32 v11, v152, v10
	s_waitcnt lgkmcnt(0)
	v_add_f32_e32 v10, v10, v11
	ds_bpermute_b32 v11, v153, v10
	s_waitcnt lgkmcnt(0)
	v_add_f32_e32 v10, v10, v11
	ds_bpermute_b32 v11, v154, v10
	s_waitcnt lgkmcnt(0)
	v_add_f32_e32 v10, v10, v11
	ds_bpermute_b32 v11, v155, v10
	s_waitcnt lgkmcnt(0)
	v_add_f32_e32 v10, v10, v11
	v_fmamk_f32 v10, v10, 0x3a800000, v158
	v_mul_f32_e32 v11, 0x4b800000, v10
	v_cmp_gt_f32_e64 s[38:39], s0, v10
	s_movk_i32 s0, 0x7fff
	s_nop 0
	v_cndmask_b32_e64 v10, v10, v11, s[38:39]
	v_rsq_f32_e32 v12, v10
	v_lshlrev_b64 v[10:11], 12, v[108:109]
	v_lshl_add_u64 v[36:37], v[142:143], 0, v[10:11]
	v_add_u32_e32 v108, s2, v108
	v_mul_f32_e32 v10, 0x45800000, v12
	v_cndmask_b32_e64 v38, v12, v10, s[38:39]
	v_pk_mul_f32 v[10:11], v[18:19], v[38:39] op_sel_hi:[1,0]
	v_pk_mul_f32 v[12:13], v[20:21], v[38:39] op_sel_hi:[1,0]
	s_waitcnt vmcnt(0)
	v_pk_fma_f32 v[2:3], v[2:3], v[10:11], v[6:7]
	v_pk_fma_f32 v[4:5], v[4:5], v[12:13], v[8:9]
	v_cvt_pk_bf16_f32 v6, v2, v3
	v_cvt_pk_bf16_f32 v7, v4, v5
	global_store_dwordx2 v[36:37], v[6:7], off
	global_load_dwordx4 v[6:9], v[120:121], off
	s_nop 0
	global_load_dwordx4 v[10:13], v[122:123], off
	v_pk_mul_f32 v[14:15], v[24:25], v[38:39] op_sel_hi:[1,0]
	v_pk_mul_f32 v[16:17], v[26:27], v[38:39] op_sel_hi:[1,0]
	v_pk_mul_f32 v[18:19], v[30:31], v[38:39] op_sel_hi:[1,0]
	v_pk_mul_f32 v[20:21], v[32:33], v[38:39] op_sel_hi:[1,0]
	v_pk_mul_f32 v[24:25], v[34:35], v[38:39] op_sel_hi:[1,0]
	v_pk_mul_f32 v[26:27], v[28:29], v[38:39] op_sel_hi:[1,0]
	v_cmp_lt_i32_e64 s[38:39], s0, v108
	s_or_b64 s[44:45], s[38:39], s[44:45]
	s_waitcnt vmcnt(0)
	v_pk_fma_f32 v[6:7], v[6:7], v[14:15], v[10:11]
	v_pk_fma_f32 v[8:9], v[8:9], v[16:17], v[12:13]
	v_cvt_pk_bf16_f32 v10, v6, v7
	v_cvt_pk_bf16_f32 v11, v8, v9
	global_store_dwordx2 v[36:37], v[10:11], off offset:8
	global_load_dwordx4 v[10:13], v[124:125], off
	s_nop 0
	global_load_dwordx4 v[14:17], v[126:127], off
	s_waitcnt vmcnt(0)
	v_pk_fma_f32 v[10:11], v[10:11], v[18:19], v[14:15]
	v_pk_fma_f32 v[12:13], v[20:21], v[12:13], v[16:17]
	v_cvt_pk_bf16_f32 v14, v10, v11
	v_cvt_pk_bf16_f32 v15, v12, v13
	global_store_dwordx2 v[36:37], v[14:15], off offset:16
	global_load_dwordx4 v[14:17], v[128:129], off
	s_nop 0
	global_load_dwordx4 v[18:21], v[130:131], off
	s_nop 0
	global_store_dwordx4 v[22:23], v[2:5], off
	global_store_dwordx4 v[22:23], v[6:9], off offset:16
	global_store_dwordx4 v[22:23], v[10:13], off offset:32
	s_waitcnt vmcnt(3)
	v_pk_fma_f32 v[2:3], v[24:25], v[14:15], v[18:19]
	v_pk_fma_f32 v[4:5], v[26:27], v[16:17], v[20:21]
	global_store_dwordx4 v[22:23], v[2:5], off offset:48
	s_nop 1
	v_cvt_pk_bf16_f32 v2, v2, v3
	v_cvt_pk_bf16_f32 v3, v4, v5
	global_store_dwordx2 v[36:37], v[2:3], off offset:24
	s_andn2_b64 exec, exec, s[44:45]
	s_cbranch_execz .LBB0_621
.LBB0_609:
	v_ashrrev_i32_e32 v109, 31, v108
	v_lshlrev_b64 v[144:145], 10, v[108:109]
	v_add_u32_e32 v12, v1, v110
	v_mov_b32_e32 v146, v252
	v_mov_b32_e32 v147, v253
	v_readlane_b32 s48, v254, 40
	v_readlane_b32 s56, v254, 48
	v_readlane_b32 s57, v254, 49
	v_readlane_b32 s49, v254, 41
	v_readlane_b32 s50, v254, 42
	v_readlane_b32 s51, v254, 43
	v_readlane_b32 s52, v254, 44
	v_readlane_b32 s53, v254, 45
	v_readlane_b32 s54, v254, 46
	v_readlane_b32 s55, v254, 47
	v_readlane_b32 s58, v254, 50
	v_readlane_b32 s59, v254, 51
	v_readlane_b32 s60, v254, 52
	v_readlane_b32 s61, v254, 53
	v_readlane_b32 s62, v254, 54
	v_readlane_b32 s63, v254, 55
	ds_write2st64_b32 v107, v246, v247 offset1:1
	ds_write_b128 v12, v[248:251] offset:1024
	ds_read2_b32 v[2:3], v148 offset1:8
	s_waitcnt lgkmcnt(0)
	v_ashrrev_i32_e32 v5, 31, v2
	v_mov_b32_e32 v4, v2
	v_lshlrev_b64 v[4:5], 9, v[4:5]
	v_lshl_add_u64 v[4:5], v[112:113], 0, v[4:5]
	global_load_dwordx4 v[86:89], v[4:5], off
	global_load_dwordx4 v[90:93], v[4:5], off offset:128
	global_load_dwordx4 v[94:97], v[4:5], off offset:256
	global_load_dwordx4 v[98:101], v[4:5], off offset:384
	v_ashrrev_i32_e32 v5, 31, v3
	v_mov_b32_e32 v4, v3
	v_lshlrev_b64 v[2:3], 9, v[4:5]
	v_lshl_add_u64 v[26:27], v[112:113], 0, v[2:3]
	global_load_dwordx4 v[78:81], v[26:27], off
	global_load_dwordx4 v[70:73], v[26:27], off offset:128
	ds_read2_b32 v[34:35], v148 offset0:16 offset1:24
	ds_read2_b32 v[82:83], v148 offset0:32 offset1:40
	ds_read_b128 v[6:9], v156 offset:1024
	ds_read_b128 v[2:5], v156 offset:1040
	global_load_dwordx4 v[102:105], v[26:27], off offset:256
	s_waitcnt lgkmcnt(3)
	v_ashrrev_i32_e32 v29, 31, v34
	v_mov_b32_e32 v28, v34
	v_lshlrev_b64 v[28:29], 9, v[28:29]
	ds_read_b128 v[14:17], v156 offset:1280
	ds_read_b128 v[10:13], v156 offset:1296
	ds_read_b128 v[22:25], v156 offset:1536
	ds_read_b128 v[18:21], v156 offset:1552
	v_lshl_add_u64 v[36:37], v[112:113], 0, v[28:29]
	global_load_dwordx4 v[162:165], v[26:27], off offset:384
	global_load_dwordx4 v[166:169], v[36:37], off
	v_ashrrev_i32_e32 v39, 31, v35
	v_mov_b32_e32 v38, v35
	s_waitcnt lgkmcnt(6)
	v_ashrrev_i32_e32 v35, 31, v82
	v_mov_b32_e32 v34, v82
	v_lshlrev_b64 v[38:39], 9, v[38:39]
	v_lshlrev_b64 v[34:35], 9, v[34:35]
	v_lshl_add_u64 v[38:39], v[112:113], 0, v[38:39]
	v_lshl_add_u64 v[34:35], v[112:113], 0, v[34:35]
	ds_read_b128 v[26:29], v156 offset:1792
	ds_read_b128 v[30:33], v156 offset:1808
	global_load_dwordx4 v[170:173], v[36:37], off offset:128
	global_load_dwordx4 v[74:77], v[36:37], off offset:256
	global_load_dwordx4 v[66:69], v[36:37], off offset:384
	global_load_dwordx4 v[62:65], v[38:39], off
	global_load_dwordx4 v[54:57], v[38:39], off offset:128
	global_load_dwordx4 v[58:61], v[38:39], off offset:256
	global_load_dwordx4 v[50:53], v[38:39], off offset:384
	global_load_dwordx4 v[46:49], v[34:35], off
	global_load_dwordx4 v[42:45], v[34:35], off offset:128
	s_nop 0
	global_load_dwordx4 v[38:41], v[34:35], off offset:256
	s_nop 0
	global_load_dwordx4 v[34:37], v[34:35], off offset:384
	v_ashrrev_i32_e32 v85, 31, v83
	s_waitcnt vmcnt(19)
	v_lshrrev_b32_e32 v82, 4, v86
	v_lshrrev_b32_e32 v84, 4, v87
	v_and_b32_e32 v174, 0xf0f0f0f, v86
	v_and_b32_e32 v176, 0xf0f0f0f, v87
	v_and_b32_e32 v175, 0xf0f0f0f, v82
	v_and_b32_e32 v177, 0xf0f0f0f, v84
	v_and_b32_e32 v86, 0xf0f0f0f, v88
	s_waitcnt vmcnt(15)
	v_lshrrev_b32_e32 v181, 4, v78
	v_and_b32_e32 v192, 0xf0f0f0f, v79
	v_lshrrev_b32_e32 v79, 4, v79
	v_and_b32_e32 v190, 0xf0f0f0f, v78
	v_and_b32_e32 v191, 0xf0f0f0f, v181
	v_and_b32_e32 v193, 0xf0f0f0f, v79
	v_and_b32_e32 v78, 0xf0f0f0f, v80
	v_lshrrev_b32_e32 v195, 4, v80
	v_and_b32_e32 v80, 0xf0f0f0f, v81
	v_lshrrev_b32_e32 v81, 4, v81
	v_and_b32_e32 v79, 0xf0f0f0f, v195
	v_and_b32_e32 v81, 0xf0f0f0f, v81
	v_lshrrev_b32_e32 v87, 4, v88
	v_and_b32_e32 v88, 0xf0f0f0f, v89
	v_lshrrev_b32_e32 v89, 4, v89
	s_waitcnt lgkmcnt(7)
	v_mfma_i32_16x16x64_i8 v[190:193], v[190:193], v[6:9], 0
	v_and_b32_e32 v87, 0xf0f0f0f, v87
	v_and_b32_e32 v89, 0xf0f0f0f, v89
	s_waitcnt vmcnt(14)
	v_lshrrev_b32_e32 v197, 4, v70
	v_and_b32_e32 v196, 0xf0f0f0f, v71
	v_lshrrev_b32_e32 v71, 4, v71
	v_mfma_i32_16x16x64_i8 v[174:177], v[174:177], v[6:9], 0
	v_and_b32_e32 v194, 0xf0f0f0f, v70
	v_and_b32_e32 v195, 0xf0f0f0f, v197
	v_and_b32_e32 v197, 0xf0f0f0f, v71
	v_lshrrev_b32_e32 v179, 4, v90
	v_and_b32_e32 v180, 0xf0f0f0f, v91
	v_lshrrev_b32_e32 v91, 4, v91
	s_waitcnt lgkmcnt(6)
	v_mfma_i32_16x16x64_i8 v[78:81], v[78:81], v[2:5], v[190:193]
	v_and_b32_e32 v178, 0xf0f0f0f, v90
	v_and_b32_e32 v179, 0xf0f0f0f, v179
	v_and_b32_e32 v181, 0xf0f0f0f, v91
	v_and_b32_e32 v70, 0xf0f0f0f, v72
	v_lshrrev_b32_e32 v199, 4, v72
	v_and_b32_e32 v72, 0xf0f0f0f, v73
	v_lshrrev_b32_e32 v73, 4, v73
	v_mfma_i32_16x16x64_i8 v[86:89], v[86:89], v[2:5], v[174:177]
	v_and_b32_e32 v71, 0xf0f0f0f, v199
	v_and_b32_e32 v73, 0xf0f0f0f, v73
	v_and_b32_e32 v90, 0xf0f0f0f, v92
	v_lshrrev_b32_e32 v183, 4, v92
	v_and_b32_e32 v92, 0xf0f0f0f, v93
	v_lshrrev_b32_e32 v93, 4, v93
	s_waitcnt lgkmcnt(5)
	v_mfma_i32_16x16x64_i8 v[78:81], v[194:197], v[14:17], v[78:81]
	v_and_b32_e32 v91, 0xf0f0f0f, v183
	v_and_b32_e32 v93, 0xf0f0f0f, v93
	s_waitcnt vmcnt(13)
	v_lshrrev_b32_e32 v201, 4, v102
	v_and_b32_e32 v200, 0xf0f0f0f, v103
	v_lshrrev_b32_e32 v103, 4, v103
	v_mfma_i32_16x16x64_i8 v[86:89], v[178:181], v[14:17], v[86:89]
	v_and_b32_e32 v198, 0xf0f0f0f, v102
	v_and_b32_e32 v199, 0xf0f0f0f, v201
	v_and_b32_e32 v201, 0xf0f0f0f, v103
	v_lshrrev_b32_e32 v185, 4, v94
	v_and_b32_e32 v184, 0xf0f0f0f, v95
	v_lshrrev_b32_e32 v95, 4, v95
	s_waitcnt lgkmcnt(4)
	v_mfma_i32_16x16x64_i8 v[70:73], v[70:73], v[10:13], v[78:81]
	v_and_b32_e32 v182, 0xf0f0f0f, v94
	s_waitcnt vmcnt(12)
	v_and_b32_e32 v202, 0xf0f0f0f, v162
	v_lshrrev_b32_e32 v211, 4, v162
	s_waitcnt vmcnt(11)
	v_lshrrev_b32_e32 v162, 4, v166
	v_lshrrev_b32_e32 v82, 4, v167
	v_and_b32_e32 v183, 0xf0f0f0f, v185
	v_and_b32_e32 v185, 0xf0f0f0f, v95
	v_and_b32_e32 v102, 0xf0f0f0f, v104
	v_lshrrev_b32_e32 v203, 4, v104
	v_and_b32_e32 v104, 0xf0f0f0f, v105
	v_lshrrev_b32_e32 v105, 4, v105
	v_and_b32_e32 v204, 0xf0f0f0f, v166
	v_and_b32_e32 v206, 0xf0f0f0f, v167
	v_and_b32_e32 v205, 0xf0f0f0f, v162
	v_and_b32_e32 v207, 0xf0f0f0f, v82
	v_mfma_i32_16x16x64_i8 v[86:89], v[90:93], v[10:13], v[86:89]
	v_and_b32_e32 v103, 0xf0f0f0f, v203
	v_and_b32_e32 v105, 0xf0f0f0f, v105
	v_and_b32_e32 v94, 0xf0f0f0f, v96
	v_lshrrev_b32_e32 v187, 4, v96
	v_and_b32_e32 v96, 0xf0f0f0f, v97
	v_lshrrev_b32_e32 v97, 4, v97
	s_waitcnt lgkmcnt(3)
	v_mfma_i32_16x16x64_i8 v[70:73], v[198:201], v[22:25], v[70:73]
	v_lshrrev_b32_e32 v82, 4, v168
	v_and_b32_e32 v95, 0xf0f0f0f, v187
	v_and_b32_e32 v97, 0xf0f0f0f, v97
	v_and_b32_e32 v167, 0xf0f0f0f, v82
	v_lshrrev_b32_e32 v82, 4, v163
	v_mfma_i32_16x16x64_i8 v[78:81], v[182:185], v[22:25], v[86:89]
	v_and_b32_e32 v203, 0xf0f0f0f, v211
	v_lshrrev_b32_e32 v189, 4, v98
	v_and_b32_e32 v188, 0xf0f0f0f, v99
	v_mfma_i32_16x16x64_i8 v[206:209], v[204:207], v[6:9], 0
	v_and_b32_e32 v204, 0xf0f0f0f, v163
	v_and_b32_e32 v205, 0xf0f0f0f, v82
	v_lshrrev_b32_e32 v99, 4, v99
	v_lshrrev_b32_e32 v84, 4, v169
	s_waitcnt lgkmcnt(2)
	v_mfma_i32_16x16x64_i8 v[70:73], v[102:105], v[18:21], v[70:73]
	v_and_b32_e32 v186, 0xf0f0f0f, v98
	v_and_b32_e32 v166, 0xf0f0f0f, v168
	v_and_b32_e32 v168, 0xf0f0f0f, v169
	v_and_b32_e32 v169, 0xf0f0f0f, v84
	v_and_b32_e32 v187, 0xf0f0f0f, v189
	v_and_b32_e32 v189, 0xf0f0f0f, v99
	v_lshrrev_b32_e32 v84, 4, v164
	v_lshrrev_b32_e32 v91, 4, v165
	v_mfma_i32_16x16x64_i8 v[78:81], v[94:97], v[18:21], v[78:81]
	v_and_b32_e32 v162, 0xf0f0f0f, v164
	v_and_b32_e32 v164, 0xf0f0f0f, v165
	v_and_b32_e32 v163, 0xf0f0f0f, v84
	v_and_b32_e32 v165, 0xf0f0f0f, v91
	v_and_b32_e32 v98, 0xf0f0f0f, v100
	v_lshrrev_b32_e32 v210, 4, v100
	v_and_b32_e32 v100, 0xf0f0f0f, v101
	v_lshrrev_b32_e32 v101, 4, v101
	s_waitcnt vmcnt(10)
	v_lshrrev_b32_e32 v87, 4, v170
	v_lshrrev_b32_e32 v89, 4, v171
	s_waitcnt lgkmcnt(1)
	v_mfma_i32_16x16x64_i8 v[70:73], v[202:205], v[26:29], v[70:73]
	v_and_b32_e32 v86, 0xf0f0f0f, v170
	v_and_b32_e32 v88, 0xf0f0f0f, v171
	v_and_b32_e32 v99, 0xf0f0f0f, v210
	v_and_b32_e32 v101, 0xf0f0f0f, v101
	v_and_b32_e32 v87, 0xf0f0f0f, v87
	v_and_b32_e32 v89, 0xf0f0f0f, v89
	v_mfma_i32_16x16x64_i8 v[166:169], v[166:169], v[2:5], v[206:209]
	v_lshrrev_b32_e32 v82, 4, v172
	v_and_b32_e32 v90, 0xf0f0f0f, v172
	v_and_b32_e32 v92, 0xf0f0f0f, v173
	v_mfma_i32_16x16x64_i8 v[78:81], v[186:189], v[26:29], v[78:81]
	v_and_b32_e32 v91, 0xf0f0f0f, v82
	v_mov_b32_e32 v84, v83
	s_waitcnt vmcnt(3)
	v_and_b32_e32 v170, 0xf0f0f0f, v49
	s_waitcnt lgkmcnt(0)
	v_mfma_i32_16x16x64_i8 v[94:97], v[162:165], v[30:33], v[70:73]
	v_and_b32_e32 v162, 0xf0f0f0f, v56
	v_and_b32_e32 v164, 0xf0f0f0f, v57
	s_nop 0
	v_lshrrev_b32_e32 v70, 4, v173
	v_and_b32_e32 v93, 0xf0f0f0f, v70
	v_mfma_i32_16x16x64_i8 v[102:105], v[98:101], v[30:33], v[78:81]
	s_nop 1
	v_cndmask_b32_e32 v94, v95, v94, vcc
	v_mfma_i32_16x16x64_i8 v[70:73], v[86:89], v[14:17], v[166:169]
	v_lshlrev_b64 v[78:79], 9, v[84:85]
	v_lshl_add_u64 v[82:83], v[112:113], 0, v[78:79]
	v_and_b32_e32 v78, 0xf0f0f0f, v74
	v_lshrrev_b32_e32 v74, 4, v74
	v_and_b32_e32 v79, 0xf0f0f0f, v74
	v_lshrrev_b32_e32 v74, 4, v75
	v_and_b32_e32 v80, 0xf0f0f0f, v75
	v_and_b32_e32 v81, 0xf0f0f0f, v74
	v_mfma_i32_16x16x64_i8 v[70:73], v[90:93], v[10:13], v[70:73]
	v_and_b32_e32 v74, 0xf0f0f0f, v76
	v_lshrrev_b32_e32 v75, 4, v76
	v_and_b32_e32 v76, 0xf0f0f0f, v77
	v_lshrrev_b32_e32 v77, 4, v77
	v_and_b32_e32 v75, 0xf0f0f0f, v75
	v_and_b32_e32 v77, 0xf0f0f0f, v77
	v_mfma_i32_16x16x64_i8 v[70:73], v[78:81], v[22:25], v[70:73]
	global_load_dwordx4 v[90:93], v[82:83], off
	global_load_dwordx4 v[86:89], v[82:83], off offset:128
	ds_read2_b32 v[166:167], v148 offset0:48 offset1:56
	v_mfma_i32_16x16x64_i8 v[70:73], v[74:77], v[18:21], v[70:73]
	v_and_b32_e32 v74, 0xf0f0f0f, v66
	v_lshrrev_b32_e32 v66, 4, v66
	v_and_b32_e32 v75, 0xf0f0f0f, v66
	v_lshrrev_b32_e32 v66, 4, v67
	v_and_b32_e32 v76, 0xf0f0f0f, v67
	v_and_b32_e32 v77, 0xf0f0f0f, v66
	v_and_b32_e32 v66, 0xf0f0f0f, v68
	v_lshrrev_b32_e32 v67, 4, v68
	v_and_b32_e32 v68, 0xf0f0f0f, v69
	v_lshrrev_b32_e32 v69, 4, v69
	v_and_b32_e32 v67, 0xf0f0f0f, v67
	v_and_b32_e32 v69, 0xf0f0f0f, v69
	v_mfma_i32_16x16x64_i8 v[74:77], v[74:77], v[26:29], v[70:73]
	global_load_dwordx4 v[78:81], v[82:83], off offset:256
	s_nop 1
	global_load_dwordx4 v[70:73], v[82:83], off offset:384
	s_waitcnt lgkmcnt(0)
	v_ashrrev_i32_e32 v83, 31, v166
	v_mov_b32_e32 v82, v166
	v_mfma_i32_16x16x64_i8 v[98:101], v[66:69], v[30:33], v[74:77]
	v_and_b32_e32 v66, 0xf0f0f0f, v62
	v_lshrrev_b32_e32 v62, 4, v62
	v_and_b32_e32 v67, 0xf0f0f0f, v62
	v_lshrrev_b32_e32 v62, 4, v63
	v_and_b32_e32 v68, 0xf0f0f0f, v63
	v_and_b32_e32 v69, 0xf0f0f0f, v62
	v_and_b32_e32 v62, 0xf0f0f0f, v64
	v_lshrrev_b32_e32 v63, 4, v64
	v_and_b32_e32 v64, 0xf0f0f0f, v65
	v_lshrrev_b32_e32 v65, 4, v65
	v_and_b32_e32 v63, 0xf0f0f0f, v63
	v_and_b32_e32 v65, 0xf0f0f0f, v65
	v_mfma_i32_16x16x64_i8 v[66:69], v[66:69], v[6:9], 0
	v_lshlrev_b64 v[74:75], 9, v[82:83]
	v_lshl_add_u64 v[168:169], v[112:113], 0, v[74:75]
	v_mfma_i32_16x16x64_i8 v[62:65], v[62:65], v[2:5], v[66:69]
	s_nop 4
	v_and_b32_e32 v66, 0xf0f0f0f, v54
	v_lshrrev_b32_e32 v54, 4, v54
	v_and_b32_e32 v67, 0xf0f0f0f, v54
	v_lshrrev_b32_e32 v54, 4, v55
	v_and_b32_e32 v68, 0xf0f0f0f, v55
	v_and_b32_e32 v69, 0xf0f0f0f, v54
	v_lshrrev_b32_e32 v54, 4, v56
	v_and_b32_e32 v163, 0xf0f0f0f, v54
	v_lshrrev_b32_e32 v54, 4, v57
	v_and_b32_e32 v165, 0xf0f0f0f, v54
	v_mfma_i32_16x16x64_i8 v[66:69], v[66:69], v[14:17], v[62:65]
	global_load_dwordx4 v[82:85], v[168:169], off
	global_load_dwordx4 v[74:77], v[168:169], off offset:128
	s_nop 0
	global_load_dwordx4 v[62:65], v[168:169], off offset:256
	global_load_dwordx4 v[54:57], v[168:169], off offset:384
	v_and_b32_e32 v168, 0xf0f0f0f, v48
	v_mfma_i32_16x16x64_i8 v[66:69], v[162:165], v[10:13], v[66:69]
	v_and_b32_e32 v162, 0xf0f0f0f, v58
	v_lshrrev_b32_e32 v58, 4, v58
	v_and_b32_e32 v163, 0xf0f0f0f, v58
	v_lshrrev_b32_e32 v58, 4, v59
	v_and_b32_e32 v164, 0xf0f0f0f, v59
	v_and_b32_e32 v165, 0xf0f0f0f, v58
	v_and_b32_e32 v58, 0xf0f0f0f, v60
	v_lshrrev_b32_e32 v59, 4, v60
	v_and_b32_e32 v60, 0xf0f0f0f, v61
	v_lshrrev_b32_e32 v61, 4, v61
	v_and_b32_e32 v59, 0xf0f0f0f, v59
	v_and_b32_e32 v61, 0xf0f0f0f, v61
	v_mfma_i32_16x16x64_i8 v[66:69], v[162:165], v[22:25], v[66:69]
	v_ashrrev_i32_e32 v163, 31, v167
	v_mov_b32_e32 v162, v167
	v_lshlrev_b64 v[166:167], 9, v[162:163]
	v_mfma_i32_16x16x64_i8 v[58:61], v[58:61], v[18:21], v[66:69]
	v_and_b32_e32 v162, 0xf0f0f0f, v52
	v_and_b32_e32 v164, 0xf0f0f0f, v53
	v_lshl_add_u64 v[176:177], v[112:113], 0, v[166:167]
	s_nop 0
	v_and_b32_e32 v66, 0xf0f0f0f, v50
	v_lshrrev_b32_e32 v50, 4, v50
	v_and_b32_e32 v67, 0xf0f0f0f, v50
	v_lshrrev_b32_e32 v50, 4, v51
	v_and_b32_e32 v68, 0xf0f0f0f, v51
	v_and_b32_e32 v69, 0xf0f0f0f, v50
	v_lshrrev_b32_e32 v50, 4, v52
	v_and_b32_e32 v163, 0xf0f0f0f, v50
	v_lshrrev_b32_e32 v50, 4, v53
	v_and_b32_e32 v165, 0xf0f0f0f, v50
	v_mfma_i32_16x16x64_i8 v[66:69], v[66:69], v[26:29], v[58:61]
	s_nop 2
	global_load_dwordx4 v[58:61], v[176:177], off
	global_load_dwordx4 v[50:53], v[176:177], off offset:128
	v_mfma_i32_16x16x64_i8 v[164:167], v[162:165], v[30:33], v[66:69]
	v_cndmask_b32_e32 v162, v103, v102, vcc
	v_cndmask_b32_e32 v102, v105, v104, vcc
	s_nop 0
	v_and_b32_e32 v66, 0xf0f0f0f, v46
	v_lshrrev_b32_e32 v46, 4, v46
	v_and_b32_e32 v67, 0xf0f0f0f, v46
	v_lshrrev_b32_e32 v46, 4, v47
	v_and_b32_e32 v68, 0xf0f0f0f, v47
	v_and_b32_e32 v69, 0xf0f0f0f, v46
	v_lshrrev_b32_e32 v46, 4, v48
	v_and_b32_e32 v169, 0xf0f0f0f, v46
	v_lshrrev_b32_e32 v46, 4, v49
	v_and_b32_e32 v171, 0xf0f0f0f, v46
	v_mfma_i32_16x16x64_i8 v[172:175], v[66:69], v[6:9], 0
	v_add_u32_dpp v104, v162, v162 quad_perm:[1,0,3,2] row_mask:0xf bank_mask:0xf bound_ctrl:1
	v_cndmask_b32_e64 v162, 0, v104, s[4:5]
	global_load_dwordx4 v[66:69], v[176:177], off offset:256
	global_load_dwordx4 v[46:49], v[176:177], off offset:384
	v_mfma_i32_16x16x64_i8 v[168:171], v[168:171], v[2:5], v[172:175]
	v_cndmask_b32_e32 v104, v97, v96, vcc
	v_mov_b32_dpp v103, v102 quad_perm:[1,0,3,2] row_mask:0xf bank_mask:0xf bound_ctrl:1
	s_waitcnt vmcnt(14)
	v_and_b32_e32 v172, 0xf0f0f0f, v42
	v_lshrrev_b32_e32 v42, 4, v42
	v_and_b32_e32 v173, 0xf0f0f0f, v42
	v_lshrrev_b32_e32 v42, 4, v43
	v_and_b32_e32 v174, 0xf0f0f0f, v43
	v_and_b32_e32 v175, 0xf0f0f0f, v42
	v_and_b32_e32 v42, 0xf0f0f0f, v44
	v_lshrrev_b32_e32 v43, 4, v44
	v_and_b32_e32 v44, 0xf0f0f0f, v45
	v_lshrrev_b32_e32 v45, 4, v45
	v_and_b32_e32 v43, 0xf0f0f0f, v43
	v_and_b32_e32 v45, 0xf0f0f0f, v45
	v_mfma_i32_16x16x64_i8 v[168:171], v[172:175], v[14:17], v[168:171]
	v_mov_b32_dpp v105, v104 quad_perm:[1,0,3,2] row_mask:0xf bank_mask:0xf bound_ctrl:1
	v_mfma_i32_16x16x64_i8 v[42:45], v[42:45], v[10:13], v[168:171]
	s_waitcnt vmcnt(13)
	s_nop 4
	v_and_b32_e32 v168, 0xf0f0f0f, v38
	v_lshrrev_b32_e32 v38, 4, v38
	v_and_b32_e32 v169, 0xf0f0f0f, v38
	v_lshrrev_b32_e32 v38, 4, v39
	v_and_b32_e32 v170, 0xf0f0f0f, v39
	v_and_b32_e32 v171, 0xf0f0f0f, v38
	v_and_b32_e32 v38, 0xf0f0f0f, v40
	v_lshrrev_b32_e32 v39, 4, v40
	v_and_b32_e32 v40, 0xf0f0f0f, v41
	v_lshrrev_b32_e32 v41, 4, v41
	v_and_b32_e32 v39, 0xf0f0f0f, v39
	v_and_b32_e32 v41, 0xf0f0f0f, v41
	v_mfma_i32_16x16x64_i8 v[42:45], v[168:171], v[22:25], v[42:45]
	s_nop 0
	v_mfma_i32_16x16x64_i8 v[38:41], v[38:41], v[18:21], v[42:45]
	s_waitcnt vmcnt(12)
	s_nop 4
	v_and_b32_e32 v42, 0xf0f0f0f, v34
	v_lshrrev_b32_e32 v34, 4, v34
	v_and_b32_e32 v43, 0xf0f0f0f, v34
	v_lshrrev_b32_e32 v34, 4, v35
	v_and_b32_e32 v44, 0xf0f0f0f, v35
	v_and_b32_e32 v45, 0xf0f0f0f, v34
	v_and_b32_e32 v34, 0xf0f0f0f, v36
	v_lshrrev_b32_e32 v35, 4, v36
	v_and_b32_e32 v36, 0xf0f0f0f, v37
	v_lshrrev_b32_e32 v37, 4, v37
	v_and_b32_e32 v35, 0xf0f0f0f, v35
	v_and_b32_e32 v37, 0xf0f0f0f, v37
	v_mfma_i32_16x16x64_i8 v[38:41], v[42:45], v[26:29], v[38:41]
	v_add_u32_dpp v42, v94, v94 quad_perm:[1,0,3,2] row_mask:0xf bank_mask:0xf bound_ctrl:1
	s_waitcnt vmcnt(11)
	v_lshrrev_b32_e32 v43, 4, v92
	v_lshrrev_b32_e32 v45, 4, v93
	v_mfma_i32_16x16x64_i8 v[34:37], v[34:37], v[30:33], v[38:41]
	v_cndmask_b32_e64 v94, v162, v42, s[6:7]
	v_and_b32_e32 v42, 0xf0f0f0f, v92
	v_and_b32_e32 v43, 0xf0f0f0f, v43
	v_lshrrev_b32_e32 v39, 4, v90
	v_lshrrev_b32_e32 v41, 4, v91
	v_and_b32_e32 v38, 0xf0f0f0f, v90
	v_and_b32_e32 v39, 0xf0f0f0f, v39
	v_and_b32_e32 v40, 0xf0f0f0f, v91
	v_and_b32_e32 v41, 0xf0f0f0f, v41
	v_and_b32_e32 v44, 0xf0f0f0f, v93
	v_and_b32_e32 v45, 0xf0f0f0f, v45
	v_mfma_i32_16x16x64_i8 v[38:41], v[38:41], v[6:9], 0
	v_cndmask_b32_e32 v90, v99, v98, vcc
	v_cndmask_b32_e32 v91, v165, v164, vcc
	v_cndmask_b32_e32 v162, v101, v100, vcc
	v_mfma_i32_16x16x64_i8 v[38:41], v[42:45], v[2:5], v[38:41]
	s_waitcnt vmcnt(10)
	v_lshrrev_b32_e32 v43, 4, v86
	v_lshrrev_b32_e32 v45, 4, v87
	v_and_b32_e32 v42, 0xf0f0f0f, v86
	v_and_b32_e32 v43, 0xf0f0f0f, v43
	v_and_b32_e32 v44, 0xf0f0f0f, v87
	v_and_b32_e32 v45, 0xf0f0f0f, v45
	v_and_b32_e32 v86, 0xf0f0f0f, v88
	v_lshrrev_b32_e32 v87, 4, v88
	v_and_b32_e32 v88, 0xf0f0f0f, v89
	v_lshrrev_b32_e32 v89, 4, v89
	v_and_b32_e32 v87, 0xf0f0f0f, v87
	v_and_b32_e32 v89, 0xf0f0f0f, v89
	v_mfma_i32_16x16x64_i8 v[38:41], v[42:45], v[14:17], v[38:41]
	v_add_u32_dpp v42, v90, v90 quad_perm:[1,0,3,2] row_mask:0xf bank_mask:0xf bound_ctrl:1
	s_waitcnt vmcnt(9)
	v_lshrrev_b32_e32 v43, 4, v78
	v_lshrrev_b32_e32 v45, 4, v79
	v_cndmask_b32_e64 v90, v94, v42, s[8:9]
	v_and_b32_e32 v42, 0xf0f0f0f, v78
	v_and_b32_e32 v43, 0xf0f0f0f, v43
	v_and_b32_e32 v44, 0xf0f0f0f, v79
	v_and_b32_e32 v45, 0xf0f0f0f, v45
	v_mfma_i32_16x16x64_i8 v[38:41], v[86:89], v[10:13], v[38:41]
	v_and_b32_e32 v78, 0xf0f0f0f, v80
	v_lshrrev_b32_e32 v79, 4, v80
	v_and_b32_e32 v80, 0xf0f0f0f, v81
	v_lshrrev_b32_e32 v81, 4, v81
	v_and_b32_e32 v79, 0xf0f0f0f, v79
	v_and_b32_e32 v81, 0xf0f0f0f, v81
	v_mfma_i32_16x16x64_i8 v[38:41], v[42:45], v[22:25], v[38:41]
	ds_read2_b32 v[94:95], v148 offset0:64 offset1:72
	s_waitcnt vmcnt(8)
	v_lshrrev_b32_e32 v43, 4, v70
	v_lshrrev_b32_e32 v45, 4, v71
	v_and_b32_e32 v42, 0xf0f0f0f, v70
	v_and_b32_e32 v43, 0xf0f0f0f, v43
	v_and_b32_e32 v44, 0xf0f0f0f, v71
	v_and_b32_e32 v45, 0xf0f0f0f, v45
	v_mfma_i32_16x16x64_i8 v[38:41], v[78:81], v[18:21], v[38:41]
	v_and_b32_e32 v70, 0xf0f0f0f, v72
	v_lshrrev_b32_e32 v71, 4, v72
	v_and_b32_e32 v72, 0xf0f0f0f, v73
	v_lshrrev_b32_e32 v73, 4, v73
	s_waitcnt lgkmcnt(0)
	v_ashrrev_i32_e32 v79, 31, v94
	v_mov_b32_e32 v78, v94
	v_and_b32_e32 v71, 0xf0f0f0f, v71
	v_and_b32_e32 v73, 0xf0f0f0f, v73
	v_lshlrev_b64 v[78:79], 9, v[78:79]
	v_mfma_i32_16x16x64_i8 v[38:41], v[42:45], v[26:29], v[38:41]
	v_add_u32_dpp v42, v91, v91 quad_perm:[1,0,3,2] row_mask:0xf bank_mask:0xf bound_ctrl:1
	s_waitcnt vmcnt(7)
	v_lshrrev_b32_e32 v43, 4, v82
	v_lshrrev_b32_e32 v45, 4, v83
	v_lshl_add_u64 v[78:79], v[112:113], 0, v[78:79]
	v_cndmask_b32_e32 v164, v167, v166, vcc
	v_cndmask_b32_e64 v182, v90, v42, s[10:11]
	v_and_b32_e32 v42, 0xf0f0f0f, v82
	v_and_b32_e32 v43, 0xf0f0f0f, v43
	v_and_b32_e32 v44, 0xf0f0f0f, v83
	v_and_b32_e32 v45, 0xf0f0f0f, v45
	global_load_dwordx4 v[90:93], v[78:79], off
	global_load_dwordx4 v[166:169], v[78:79], off offset:128
	global_load_dwordx4 v[98:101], v[78:79], off offset:256
	global_load_dwordx4 v[86:89], v[78:79], off offset:384
	v_mfma_i32_16x16x64_i8 v[38:41], v[70:73], v[30:33], v[38:41]
	v_lshrrev_b32_e32 v71, 4, v84
	v_lshrrev_b32_e32 v73, 4, v85
	v_and_b32_e32 v70, 0xf0f0f0f, v84
	v_and_b32_e32 v71, 0xf0f0f0f, v71
	v_and_b32_e32 v72, 0xf0f0f0f, v85
	v_and_b32_e32 v73, 0xf0f0f0f, v73
	v_mfma_i32_16x16x64_i8 v[42:45], v[42:45], v[6:9], 0
	s_nop 0
	v_cndmask_b32_e32 v38, v39, v38, vcc
	v_mov_b32_dpp v163, v162 quad_perm:[1,0,3,2] row_mask:0xf bank_mask:0xf bound_ctrl:1
	v_mov_b32_dpp v165, v164 quad_perm:[1,0,3,2] row_mask:0xf bank_mask:0xf bound_ctrl:1
	v_mfma_i32_16x16x64_i8 v[42:45], v[70:73], v[2:5], v[42:45]
	s_waitcnt vmcnt(10)
	v_lshrrev_b32_e32 v71, 4, v74
	v_lshrrev_b32_e32 v73, 4, v75
	v_and_b32_e32 v70, 0xf0f0f0f, v74
	v_and_b32_e32 v71, 0xf0f0f0f, v71
	v_and_b32_e32 v72, 0xf0f0f0f, v75
	v_and_b32_e32 v73, 0xf0f0f0f, v73
	v_and_b32_e32 v74, 0xf0f0f0f, v76
	v_lshrrev_b32_e32 v75, 4, v76
	v_and_b32_e32 v76, 0xf0f0f0f, v77
	v_lshrrev_b32_e32 v77, 4, v77
	v_and_b32_e32 v75, 0xf0f0f0f, v75
	v_and_b32_e32 v77, 0xf0f0f0f, v77
	v_mfma_i32_16x16x64_i8 v[42:45], v[70:73], v[14:17], v[42:45]
	s_waitcnt vmcnt(9)
	v_and_b32_e32 v70, 0xf0f0f0f, v62
	v_lshrrev_b32_e32 v62, 4, v62
	v_and_b32_e32 v71, 0xf0f0f0f, v62
	v_lshrrev_b32_e32 v62, 4, v63
	v_and_b32_e32 v72, 0xf0f0f0f, v63
	v_and_b32_e32 v73, 0xf0f0f0f, v62
	v_mfma_i32_16x16x64_i8 v[42:45], v[74:77], v[10:13], v[42:45]
	v_and_b32_e32 v62, 0xf0f0f0f, v64
	v_lshrrev_b32_e32 v63, 4, v64
	v_and_b32_e32 v64, 0xf0f0f0f, v65
	v_lshrrev_b32_e32 v65, 4, v65
	v_and_b32_e32 v63, 0xf0f0f0f, v63
	v_and_b32_e32 v65, 0xf0f0f0f, v65
	v_mfma_i32_16x16x64_i8 v[42:45], v[70:73], v[22:25], v[42:45]
	v_ashrrev_i32_e32 v71, 31, v95
	v_mov_b32_e32 v70, v95
	v_lshlrev_b64 v[70:71], 9, v[70:71]
	v_mfma_i32_16x16x64_i8 v[42:45], v[62:65], v[18:21], v[42:45]
	s_waitcnt vmcnt(8)
	v_and_b32_e32 v62, 0xf0f0f0f, v54
	v_lshrrev_b32_e32 v54, 4, v54
	v_and_b32_e32 v63, 0xf0f0f0f, v54
	v_lshrrev_b32_e32 v54, 4, v55
	v_and_b32_e32 v64, 0xf0f0f0f, v55
	v_and_b32_e32 v65, 0xf0f0f0f, v54
	v_and_b32_e32 v54, 0xf0f0f0f, v56
	v_lshrrev_b32_e32 v55, 4, v56
	v_and_b32_e32 v56, 0xf0f0f0f, v57
	v_lshrrev_b32_e32 v57, 4, v57
	v_and_b32_e32 v55, 0xf0f0f0f, v55
	v_and_b32_e32 v57, 0xf0f0f0f, v57
	v_mfma_i32_16x16x64_i8 v[42:45], v[62:65], v[26:29], v[42:45]
	v_lshl_add_u64 v[62:63], v[112:113], 0, v[70:71]
	global_load_dwordx4 v[94:97], v[62:63], off
	global_load_dwordx4 v[74:77], v[62:63], off offset:128
	s_waitcnt vmcnt(3)
	v_and_b32_e32 v180, 0xf0f0f0f, v101
	v_mfma_i32_16x16x64_i8 v[70:73], v[54:57], v[30:33], v[42:45]
	v_lshrrev_b32_e32 v54, 4, v60
	s_waitcnt vmcnt(1)
	v_lshrrev_b32_e32 v39, 4, v94
	v_lshrrev_b32_e32 v43, 4, v58
	v_lshrrev_b32_e32 v45, 4, v59
	v_and_b32_e32 v42, 0xf0f0f0f, v58
	v_and_b32_e32 v43, 0xf0f0f0f, v43
	v_and_b32_e32 v44, 0xf0f0f0f, v59
	v_and_b32_e32 v45, 0xf0f0f0f, v45
	v_and_b32_e32 v59, 0xf0f0f0f, v54
	v_lshrrev_b32_e32 v54, 4, v61
	v_and_b32_e32 v58, 0xf0f0f0f, v60
	v_and_b32_e32 v60, 0xf0f0f0f, v61
	v_and_b32_e32 v61, 0xf0f0f0f, v54
	v_mfma_i32_16x16x64_i8 v[42:45], v[42:45], v[6:9], 0
	global_load_dwordx4 v[82:85], v[62:63], off offset:256
	global_load_dwordx4 v[54:57], v[62:63], off offset:384
	ds_read2_b32 v[174:175], v148 offset0:80 offset1:88
	s_waitcnt lgkmcnt(0)
	v_ashrrev_i32_e32 v177, 31, v175
	v_mfma_i32_16x16x64_i8 v[42:45], v[58:61], v[2:5], v[42:45]
	v_and_b32_e32 v58, 0xf0f0f0f, v50
	v_lshrrev_b32_e32 v50, 4, v50
	v_and_b32_e32 v59, 0xf0f0f0f, v50
	v_lshrrev_b32_e32 v50, 4, v51
	v_and_b32_e32 v60, 0xf0f0f0f, v51
	v_and_b32_e32 v61, 0xf0f0f0f, v50
	v_and_b32_e32 v50, 0xf0f0f0f, v52
	v_lshrrev_b32_e32 v51, 4, v52
	v_and_b32_e32 v52, 0xf0f0f0f, v53
	v_lshrrev_b32_e32 v53, 4, v53
	v_and_b32_e32 v51, 0xf0f0f0f, v51
	v_and_b32_e32 v53, 0xf0f0f0f, v53
	v_mfma_i32_16x16x64_i8 v[42:45], v[58:61], v[14:17], v[42:45]
	v_ashrrev_i32_e32 v59, 31, v174
	v_mov_b32_e32 v58, v174
	v_lshlrev_b64 v[62:63], 9, v[58:59]
	v_mfma_i32_16x16x64_i8 v[42:45], v[50:53], v[10:13], v[42:45]
	v_lshrrev_b32_e32 v51, 4, v66
	v_lshrrev_b32_e32 v53, 4, v67
	v_and_b32_e32 v50, 0xf0f0f0f, v66
	v_and_b32_e32 v51, 0xf0f0f0f, v51
	v_and_b32_e32 v52, 0xf0f0f0f, v67
	v_and_b32_e32 v53, 0xf0f0f0f, v53
	v_lshrrev_b32_e32 v59, 4, v68
	v_lshrrev_b32_e32 v61, 4, v69
	v_and_b32_e32 v58, 0xf0f0f0f, v68
	v_and_b32_e32 v59, 0xf0f0f0f, v59
	v_and_b32_e32 v60, 0xf0f0f0f, v69
	v_and_b32_e32 v61, 0xf0f0f0f, v61
	v_mfma_i32_16x16x64_i8 v[42:45], v[50:53], v[22:25], v[42:45]
	v_and_b32_e32 v50, 0xf0f0f0f, v46
	v_lshrrev_b32_e32 v46, 4, v46
	v_and_b32_e32 v51, 0xf0f0f0f, v46
	v_lshrrev_b32_e32 v46, 4, v47
	v_and_b32_e32 v52, 0xf0f0f0f, v47
	v_and_b32_e32 v53, 0xf0f0f0f, v46
	v_mfma_i32_16x16x64_i8 v[42:45], v[58:61], v[18:21], v[42:45]
	v_lshrrev_b32_e32 v46, 4, v48
	v_and_b32_e32 v67, 0xf0f0f0f, v46
	v_lshrrev_b32_e32 v46, 4, v49
	v_and_b32_e32 v66, 0xf0f0f0f, v48
	v_and_b32_e32 v68, 0xf0f0f0f, v49
	v_and_b32_e32 v69, 0xf0f0f0f, v46
	v_mfma_i32_16x16x64_i8 v[42:45], v[50:53], v[26:29], v[42:45]
	v_lshl_add_u64 v[170:171], v[112:113], 0, v[62:63]
	global_load_dwordx4 v[78:81], v[170:171], off
	global_load_dwordx4 v[62:65], v[170:171], off offset:128
	global_load_dwordx4 v[58:61], v[170:171], off offset:256
	global_load_dwordx4 v[46:49], v[170:171], off offset:384
	v_mfma_i32_16x16x64_i8 v[170:173], v[66:69], v[30:33], v[42:45]
	v_lshrrev_b32_e32 v51, 4, v92
	v_lshrrev_b32_e32 v53, 4, v93
	v_and_b32_e32 v50, 0xf0f0f0f, v92
	v_lshrrev_b32_e32 v43, 4, v90
	v_lshrrev_b32_e32 v45, 4, v91
	v_and_b32_e32 v42, 0xf0f0f0f, v90
	v_and_b32_e32 v43, 0xf0f0f0f, v43
	v_and_b32_e32 v44, 0xf0f0f0f, v91
	v_and_b32_e32 v45, 0xf0f0f0f, v45
	v_and_b32_e32 v51, 0xf0f0f0f, v51
	v_and_b32_e32 v52, 0xf0f0f0f, v93
	v_and_b32_e32 v53, 0xf0f0f0f, v53
	v_mfma_i32_16x16x64_i8 v[42:45], v[42:45], v[6:9], 0
	v_mov_b32_e32 v176, v175
	v_lshlrev_b64 v[66:67], 9, v[176:177]
	v_lshl_add_u64 v[178:179], v[112:113], 0, v[66:67]
	v_mfma_i32_16x16x64_i8 v[42:45], v[50:53], v[2:5], v[42:45]
	v_lshrrev_b32_e32 v51, 4, v166
	v_lshrrev_b32_e32 v53, 4, v167
	v_and_b32_e32 v50, 0xf0f0f0f, v166
	v_and_b32_e32 v51, 0xf0f0f0f, v51
	v_and_b32_e32 v52, 0xf0f0f0f, v167
	v_and_b32_e32 v53, 0xf0f0f0f, v53
	v_lshrrev_b32_e32 v66, 4, v168
	v_and_b32_e32 v167, 0xf0f0f0f, v66
	v_lshrrev_b32_e32 v66, 4, v169
	v_and_b32_e32 v166, 0xf0f0f0f, v168
	v_and_b32_e32 v168, 0xf0f0f0f, v169
	v_and_b32_e32 v169, 0xf0f0f0f, v66
	v_mfma_i32_16x16x64_i8 v[174:177], v[50:53], v[14:17], v[42:45]
	global_load_dwordx4 v[90:93], v[178:179], off
	global_load_dwordx4 v[66:69], v[178:179], off offset:128
	global_load_dwordx4 v[50:53], v[178:179], off offset:256
	global_load_dwordx4 v[42:45], v[178:179], off offset:384
	v_and_b32_e32 v178, 0xf0f0f0f, v100
	v_mfma_i32_16x16x64_i8 v[166:169], v[166:169], v[10:13], v[174:177]
	s_nop 2
	v_and_b32_e32 v174, 0xf0f0f0f, v98
	v_lshrrev_b32_e32 v98, 4, v98
	v_and_b32_e32 v175, 0xf0f0f0f, v98
	v_lshrrev_b32_e32 v98, 4, v99
	v_and_b32_e32 v176, 0xf0f0f0f, v99
	v_and_b32_e32 v177, 0xf0f0f0f, v98
	v_lshrrev_b32_e32 v98, 4, v100
	v_and_b32_e32 v179, 0xf0f0f0f, v98
	v_lshrrev_b32_e32 v98, 4, v101
	v_and_b32_e32 v181, 0xf0f0f0f, v98
	v_mfma_i32_16x16x64_i8 v[166:169], v[174:177], v[22:25], v[166:169]
	v_cndmask_b32_e32 v100, v35, v34, vcc
	v_cndmask_b32_e32 v98, v37, v36, vcc
	v_mfma_i32_16x16x64_i8 v[34:37], v[178:181], v[18:21], v[166:169]
	v_add_u32_dpp v100, v100, v100 quad_perm:[1,0,3,2] row_mask:0xf bank_mask:0xf bound_ctrl:1
	v_cndmask_b32_e64 v100, v182, v100, s[12:13]
	v_mov_b32_dpp v99, v98 quad_perm:[1,0,3,2] row_mask:0xf bank_mask:0xf bound_ctrl:1
	s_nop 1
	v_and_b32_e32 v166, 0xf0f0f0f, v86
	v_lshrrev_b32_e32 v86, 4, v86
	v_and_b32_e32 v167, 0xf0f0f0f, v86
	v_lshrrev_b32_e32 v86, 4, v87
	v_and_b32_e32 v168, 0xf0f0f0f, v87
	v_and_b32_e32 v169, 0xf0f0f0f, v86
	v_and_b32_e32 v86, 0xf0f0f0f, v88
	v_lshrrev_b32_e32 v87, 4, v88
	v_and_b32_e32 v88, 0xf0f0f0f, v89
	v_lshrrev_b32_e32 v89, 4, v89
	v_and_b32_e32 v87, 0xf0f0f0f, v87
	v_and_b32_e32 v89, 0xf0f0f0f, v89
	v_mfma_i32_16x16x64_i8 v[34:37], v[166:169], v[26:29], v[34:37]
	s_nop 0
	v_mfma_i32_16x16x64_i8 v[34:37], v[86:89], v[30:33], v[34:37]
	v_and_b32_e32 v87, 0xf0f0f0f, v39
	v_lshrrev_b32_e32 v39, 4, v95
	v_and_b32_e32 v86, 0xf0f0f0f, v94
	v_and_b32_e32 v88, 0xf0f0f0f, v95
	v_and_b32_e32 v89, 0xf0f0f0f, v39
	v_lshrrev_b32_e32 v39, 4, v96
	v_and_b32_e32 v95, 0xf0f0f0f, v39
	v_lshrrev_b32_e32 v39, 4, v97
	v_and_b32_e32 v94, 0xf0f0f0f, v96
	v_and_b32_e32 v96, 0xf0f0f0f, v97
	v_and_b32_e32 v97, 0xf0f0f0f, v39
	v_mfma_i32_16x16x64_i8 v[166:169], v[86:89], v[6:9], 0
	v_cndmask_b32_e32 v86, v41, v40, vcc
	v_add_u32_dpp v88, v38, v38 quad_perm:[1,0,3,2] row_mask:0xf bank_mask:0xf bound_ctrl:1
	v_cndmask_b32_e32 v89, v71, v70, vcc
	v_mfma_i32_16x16x64_i8 v[38:41], v[94:97], v[2:5], v[166:169]
	s_waitcnt vmcnt(10)
	v_and_b32_e32 v94, 0xf0f0f0f, v74
	v_lshrrev_b32_e32 v74, 4, v74
	v_and_b32_e32 v95, 0xf0f0f0f, v74
	v_lshrrev_b32_e32 v74, 4, v75
	v_and_b32_e32 v96, 0xf0f0f0f, v75
	v_and_b32_e32 v97, 0xf0f0f0f, v74
	v_and_b32_e32 v74, 0xf0f0f0f, v76
	v_lshrrev_b32_e32 v75, 4, v76
	v_and_b32_e32 v76, 0xf0f0f0f, v77
	v_lshrrev_b32_e32 v77, 4, v77
	v_and_b32_e32 v75, 0xf0f0f0f, v75
	v_and_b32_e32 v77, 0xf0f0f0f, v77
	v_mfma_i32_16x16x64_i8 v[38:41], v[94:97], v[14:17], v[38:41]
	s_waitcnt vmcnt(9)
	v_lshrrev_b32_e32 v71, 4, v82
	v_cndmask_b32_e32 v70, v73, v72, vcc
	v_and_b32_e32 v73, 0xf0f0f0f, v71
	v_lshrrev_b32_e32 v71, 4, v83
	v_mfma_i32_16x16x64_i8 v[38:41], v[74:77], v[10:13], v[38:41]
	v_and_b32_e32 v72, 0xf0f0f0f, v82
	v_and_b32_e32 v74, 0xf0f0f0f, v83
	v_and_b32_e32 v75, 0xf0f0f0f, v71
	v_lshrrev_b32_e32 v71, 4, v84
	v_and_b32_e32 v83, 0xf0f0f0f, v71
	v_lshrrev_b32_e32 v71, 4, v85
	v_and_b32_e32 v82, 0xf0f0f0f, v84
	v_and_b32_e32 v84, 0xf0f0f0f, v85
	v_and_b32_e32 v85, 0xf0f0f0f, v71
	v_cndmask_b32_e64 v88, v100, v88, s[14:15]
	v_mfma_i32_16x16x64_i8 v[38:41], v[72:75], v[22:25], v[38:41]
	v_add_u32_dpp v72, v89, v89 quad_perm:[1,0,3,2] row_mask:0xf bank_mask:0xf bound_ctrl:1
	v_cndmask_b32_e64 v88, v88, v72, s[16:17]
	s_waitcnt vmcnt(8)
	v_and_b32_e32 v72, 0xf0f0f0f, v54
	v_lshrrev_b32_e32 v54, 4, v54
	v_and_b32_e32 v73, 0xf0f0f0f, v54
	v_lshrrev_b32_e32 v54, 4, v55
	v_and_b32_e32 v74, 0xf0f0f0f, v55
	v_and_b32_e32 v75, 0xf0f0f0f, v54
	v_mfma_i32_16x16x64_i8 v[38:41], v[82:85], v[18:21], v[38:41]
	v_and_b32_e32 v54, 0xf0f0f0f, v56
	v_lshrrev_b32_e32 v55, 4, v56
	v_and_b32_e32 v56, 0xf0f0f0f, v57
	v_lshrrev_b32_e32 v57, 4, v57
	v_and_b32_e32 v55, 0xf0f0f0f, v55
	v_and_b32_e32 v57, 0xf0f0f0f, v57
	v_mfma_i32_16x16x64_i8 v[38:41], v[72:75], v[26:29], v[38:41]
	s_waitcnt vmcnt(7)
	v_lshrrev_b32_e32 v75, 4, v80
	v_lshrrev_b32_e32 v77, 4, v81
	v_and_b32_e32 v74, 0xf0f0f0f, v80
	v_mfma_i32_16x16x64_i8 v[54:57], v[54:57], v[30:33], v[38:41]
	v_and_b32_e32 v75, 0xf0f0f0f, v75
	v_and_b32_e32 v76, 0xf0f0f0f, v81
	v_and_b32_e32 v77, 0xf0f0f0f, v77
	v_lshrrev_b32_e32 v39, 4, v78
	v_lshrrev_b32_e32 v41, 4, v79
	v_and_b32_e32 v38, 0xf0f0f0f, v78
	v_and_b32_e32 v39, 0xf0f0f0f, v39
	v_and_b32_e32 v40, 0xf0f0f0f, v79
	v_and_b32_e32 v41, 0xf0f0f0f, v41
	v_cndmask_b32_e32 v82, v171, v170, vcc
	v_cndmask_b32_e32 v72, v173, v172, vcc
	v_mfma_i32_16x16x64_i8 v[38:41], v[38:41], v[6:9], 0
	v_add_u32_dpp v78, v82, v82 quad_perm:[1,0,3,2] row_mask:0xf bank_mask:0xf bound_ctrl:1
	v_cndmask_b32_e64 v190, v88, v78, s[18:19]
	ds_read2_b32 v[88:89], v148 offset0:96 offset1:104
	v_mfma_i32_16x16x64_i8 v[38:41], v[74:77], v[2:5], v[38:41]
	s_waitcnt vmcnt(6)
	v_and_b32_e32 v74, 0xf0f0f0f, v62
	v_lshrrev_b32_e32 v62, 4, v62
	v_and_b32_e32 v75, 0xf0f0f0f, v62
	v_lshrrev_b32_e32 v62, 4, v63
	v_and_b32_e32 v76, 0xf0f0f0f, v63
	v_and_b32_e32 v77, 0xf0f0f0f, v62
	v_and_b32_e32 v62, 0xf0f0f0f, v64
	v_lshrrev_b32_e32 v63, 4, v64
	v_and_b32_e32 v64, 0xf0f0f0f, v65
	v_lshrrev_b32_e32 v65, 4, v65
	v_and_b32_e32 v63, 0xf0f0f0f, v63
	v_and_b32_e32 v65, 0xf0f0f0f, v65
	v_mfma_i32_16x16x64_i8 v[38:41], v[74:77], v[14:17], v[38:41]
	s_waitcnt lgkmcnt(0)
	v_ashrrev_i32_e32 v75, 31, v88
	v_mov_b32_e32 v74, v88
	v_lshlrev_b64 v[74:75], 9, v[74:75]
	v_mfma_i32_16x16x64_i8 v[38:41], v[62:65], v[10:13], v[38:41]
	s_waitcnt vmcnt(5)
	v_and_b32_e32 v62, 0xf0f0f0f, v58
	v_lshrrev_b32_e32 v58, 4, v58
	v_and_b32_e32 v63, 0xf0f0f0f, v58
	v_lshrrev_b32_e32 v58, 4, v59
	v_and_b32_e32 v64, 0xf0f0f0f, v59
	v_and_b32_e32 v65, 0xf0f0f0f, v58
	v_lshl_add_u64 v[82:83], v[112:113], 0, v[74:75]
	v_and_b32_e32 v58, 0xf0f0f0f, v60
	v_mfma_i32_16x16x64_i8 v[38:41], v[62:65], v[22:25], v[38:41]
	global_load_dwordx4 v[62:65], v[82:83], off
	global_load_dwordx4 v[74:77], v[82:83], off offset:128
	global_load_dwordx4 v[78:81], v[82:83], off offset:256
	s_nop 0
	global_load_dwordx4 v[82:85], v[82:83], off offset:384
	v_lshrrev_b32_e32 v59, 4, v60
	v_and_b32_e32 v60, 0xf0f0f0f, v61
	v_lshrrev_b32_e32 v61, 4, v61
	v_and_b32_e32 v59, 0xf0f0f0f, v59
	v_and_b32_e32 v61, 0xf0f0f0f, v61
	v_ashrrev_i32_e32 v95, 31, v89
	v_mov_b32_e32 v94, v89
	v_mfma_i32_16x16x64_i8 v[38:41], v[58:61], v[18:21], v[38:41]
	s_waitcnt vmcnt(8)
	v_and_b32_e32 v58, 0xf0f0f0f, v46
	v_lshrrev_b32_e32 v46, 4, v46
	v_and_b32_e32 v59, 0xf0f0f0f, v46
	v_lshrrev_b32_e32 v46, 4, v47
	v_and_b32_e32 v60, 0xf0f0f0f, v47
	v_and_b32_e32 v61, 0xf0f0f0f, v46
	v_and_b32_e32 v46, 0xf0f0f0f, v48
	v_lshrrev_b32_e32 v47, 4, v48
	v_and_b32_e32 v48, 0xf0f0f0f, v49
	v_lshrrev_b32_e32 v49, 4, v49
	v_and_b32_e32 v47, 0xf0f0f0f, v47
	v_and_b32_e32 v49, 0xf0f0f0f, v49
	v_mfma_i32_16x16x64_i8 v[38:41], v[58:61], v[26:29], v[38:41]
	v_lshlrev_b64 v[88:89], 9, v[94:95]
	v_lshl_add_u64 v[96:97], v[112:113], 0, v[88:89]
	v_mov_b32_dpp v87, v86 quad_perm:[1,0,3,2] row_mask:0xf bank_mask:0xf bound_ctrl:1
	v_mfma_i32_16x16x64_i8 v[58:61], v[46:49], v[30:33], v[38:41]
	s_waitcnt vmcnt(7)
	v_and_b32_e32 v46, 0xf0f0f0f, v92
	v_lshrrev_b32_e32 v47, 4, v92
	v_and_b32_e32 v48, 0xf0f0f0f, v93
	v_lshrrev_b32_e32 v39, 4, v90
	v_lshrrev_b32_e32 v41, 4, v91
	v_and_b32_e32 v38, 0xf0f0f0f, v90
	v_and_b32_e32 v39, 0xf0f0f0f, v39
	v_and_b32_e32 v40, 0xf0f0f0f, v91
	v_and_b32_e32 v41, 0xf0f0f0f, v41
	v_lshrrev_b32_e32 v49, 4, v93
	global_load_dwordx4 v[88:91], v[96:97], off
	global_load_dwordx4 v[92:95], v[96:97], off offset:128
	v_and_b32_e32 v47, 0xf0f0f0f, v47
	v_and_b32_e32 v49, 0xf0f0f0f, v49
	v_mfma_i32_16x16x64_i8 v[38:41], v[38:41], v[6:9], 0
	ds_read2_b32 v[100:101], v148 offset0:112 offset1:120
	global_load_dwordx4 v[166:169], v[96:97], off offset:256
	global_load_dwordx4 v[170:173], v[96:97], off offset:384
	v_cndmask_b32_e32 v96, v35, v34, vcc
	v_mfma_i32_16x16x64_i8 v[38:41], v[46:49], v[2:5], v[38:41]
	s_waitcnt vmcnt(10)
	v_lshrrev_b32_e32 v47, 4, v66
	v_lshrrev_b32_e32 v49, 4, v67
	v_and_b32_e32 v46, 0xf0f0f0f, v66
	v_and_b32_e32 v47, 0xf0f0f0f, v47
	v_and_b32_e32 v48, 0xf0f0f0f, v67
	v_and_b32_e32 v49, 0xf0f0f0f, v49
	v_and_b32_e32 v66, 0xf0f0f0f, v68
	v_lshrrev_b32_e32 v67, 4, v68
	v_and_b32_e32 v68, 0xf0f0f0f, v69
	v_lshrrev_b32_e32 v69, 4, v69
	v_and_b32_e32 v67, 0xf0f0f0f, v67
	v_and_b32_e32 v69, 0xf0f0f0f, v69
	v_mfma_i32_16x16x64_i8 v[38:41], v[46:49], v[14:17], v[38:41]
	s_waitcnt vmcnt(9)
	v_lshrrev_b32_e32 v47, 4, v50
	v_lshrrev_b32_e32 v49, 4, v51
	v_and_b32_e32 v46, 0xf0f0f0f, v50
	v_and_b32_e32 v47, 0xf0f0f0f, v47
	v_and_b32_e32 v48, 0xf0f0f0f, v51
	v_and_b32_e32 v49, 0xf0f0f0f, v49
	v_mfma_i32_16x16x64_i8 v[38:41], v[66:69], v[10:13], v[38:41]
	v_and_b32_e32 v50, 0xf0f0f0f, v52
	v_lshrrev_b32_e32 v51, 4, v52
	v_and_b32_e32 v52, 0xf0f0f0f, v53
	v_lshrrev_b32_e32 v53, 4, v53
	v_and_b32_e32 v51, 0xf0f0f0f, v51
	v_and_b32_e32 v53, 0xf0f0f0f, v53
	v_mfma_i32_16x16x64_i8 v[38:41], v[46:49], v[22:25], v[38:41]
	s_waitcnt vmcnt(8)
	v_and_b32_e32 v46, 0xf0f0f0f, v42
	v_lshrrev_b32_e32 v42, 4, v42
	v_and_b32_e32 v47, 0xf0f0f0f, v42
	v_lshrrev_b32_e32 v42, 4, v43
	v_and_b32_e32 v48, 0xf0f0f0f, v43
	v_and_b32_e32 v49, 0xf0f0f0f, v42
	v_mfma_i32_16x16x64_i8 v[38:41], v[50:53], v[18:21], v[38:41]
	v_and_b32_e32 v42, 0xf0f0f0f, v44
	v_lshrrev_b32_e32 v43, 4, v44
	v_and_b32_e32 v44, 0xf0f0f0f, v45
	v_lshrrev_b32_e32 v45, 4, v45
	v_and_b32_e32 v43, 0xf0f0f0f, v43
	v_and_b32_e32 v45, 0xf0f0f0f, v45
	v_mfma_i32_16x16x64_i8 v[38:41], v[46:49], v[26:29], v[38:41]
	s_waitcnt lgkmcnt(0)
	v_ashrrev_i32_e32 v67, 31, v100
	v_mov_b32_e32 v66, v100
	v_lshlrev_b64 v[46:47], 9, v[66:67]
	v_lshl_add_u64 v[46:47], v[112:113], 0, v[46:47]
	v_mfma_i32_16x16x64_i8 v[174:177], v[42:45], v[30:33], v[38:41]
	s_waitcnt vmcnt(7)
	v_and_b32_e32 v42, 0xf0f0f0f, v64
	v_lshrrev_b32_e32 v43, 4, v64
	v_and_b32_e32 v44, 0xf0f0f0f, v65
	v_and_b32_e32 v38, 0xf0f0f0f, v62
	v_lshrrev_b32_e32 v39, 4, v62
	v_and_b32_e32 v40, 0xf0f0f0f, v63
	v_lshrrev_b32_e32 v41, 4, v63
	v_lshrrev_b32_e32 v45, 4, v65
	global_load_dwordx4 v[178:181], v[46:47], off
	global_load_dwordx4 v[182:185], v[46:47], off offset:128
	global_load_dwordx4 v[186:189], v[46:47], off offset:256
	global_load_dwordx4 v[62:65], v[46:47], off offset:384
	v_and_b32_e32 v39, 0xf0f0f0f, v39
	v_and_b32_e32 v41, 0xf0f0f0f, v41
	v_and_b32_e32 v43, 0xf0f0f0f, v43
	v_and_b32_e32 v45, 0xf0f0f0f, v45
	v_mfma_i32_16x16x64_i8 v[38:41], v[38:41], v[6:9], 0
	s_waitcnt vmcnt(10)
	v_lshrrev_b32_e32 v47, 4, v76
	v_lshrrev_b32_e32 v49, 4, v77
	v_and_b32_e32 v46, 0xf0f0f0f, v76
	v_mfma_i32_16x16x64_i8 v[38:41], v[42:45], v[2:5], v[38:41]
	v_lshrrev_b32_e32 v43, 4, v74
	v_lshrrev_b32_e32 v45, 4, v75
	v_and_b32_e32 v42, 0xf0f0f0f, v74
	v_and_b32_e32 v43, 0xf0f0f0f, v43
	v_and_b32_e32 v44, 0xf0f0f0f, v75
	v_and_b32_e32 v45, 0xf0f0f0f, v45
	v_and_b32_e32 v47, 0xf0f0f0f, v47
	v_and_b32_e32 v48, 0xf0f0f0f, v77
	v_and_b32_e32 v49, 0xf0f0f0f, v49
	v_mfma_i32_16x16x64_i8 v[38:41], v[42:45], v[14:17], v[38:41]
	v_ashrrev_i32_e32 v43, 31, v101
	v_mov_b32_e32 v42, v101
	v_lshlrev_b64 v[50:51], 9, v[42:43]
	s_waitcnt vmcnt(9)
	v_lshrrev_b32_e32 v43, 4, v78
	v_lshrrev_b32_e32 v45, 4, v79
	v_and_b32_e32 v42, 0xf0f0f0f, v78
	v_and_b32_e32 v43, 0xf0f0f0f, v43
	v_and_b32_e32 v44, 0xf0f0f0f, v79
	v_and_b32_e32 v45, 0xf0f0f0f, v45
	v_mfma_i32_16x16x64_i8 v[38:41], v[46:49], v[10:13], v[38:41]
	v_lshrrev_b32_e32 v47, 4, v80
	v_lshrrev_b32_e32 v49, 4, v81
	v_and_b32_e32 v46, 0xf0f0f0f, v80
	v_and_b32_e32 v47, 0xf0f0f0f, v47
	v_and_b32_e32 v48, 0xf0f0f0f, v81
	v_and_b32_e32 v49, 0xf0f0f0f, v49
	v_mfma_i32_16x16x64_i8 v[38:41], v[42:45], v[22:25], v[38:41]
	v_lshl_add_u64 v[78:79], v[112:113], 0, v[50:51]
	s_waitcnt vmcnt(8)
	v_lshrrev_b32_e32 v67, 4, v84
	v_lshrrev_b32_e32 v69, 4, v85
	v_mfma_i32_16x16x64_i8 v[38:41], v[46:49], v[18:21], v[38:41]
	v_lshrrev_b32_e32 v47, 4, v82
	v_lshrrev_b32_e32 v49, 4, v83
	v_and_b32_e32 v46, 0xf0f0f0f, v82
	v_and_b32_e32 v47, 0xf0f0f0f, v47
	v_and_b32_e32 v48, 0xf0f0f0f, v83
	v_and_b32_e32 v49, 0xf0f0f0f, v49
	global_load_dwordx4 v[50:53], v[78:79], off
	global_load_dwordx4 v[42:45], v[78:79], off offset:128
	v_and_b32_e32 v66, 0xf0f0f0f, v84
	v_and_b32_e32 v67, 0xf0f0f0f, v67
	v_and_b32_e32 v68, 0xf0f0f0f, v85
	v_and_b32_e32 v69, 0xf0f0f0f, v69
	v_mfma_i32_16x16x64_i8 v[74:77], v[46:49], v[26:29], v[38:41]
	s_waitcnt vmcnt(9)
	v_lshrrev_b32_e32 v34, 4, v88
	global_load_dwordx4 v[46:49], v[78:79], off offset:256
	global_load_dwordx4 v[38:41], v[78:79], off offset:384
	v_and_b32_e32 v78, 0xf0f0f0f, v90
	v_mfma_i32_16x16x64_i8 v[74:77], v[66:69], v[30:33], v[74:77]
	v_and_b32_e32 v67, 0xf0f0f0f, v34
	v_lshrrev_b32_e32 v34, 4, v89
	v_and_b32_e32 v66, 0xf0f0f0f, v88
	v_and_b32_e32 v68, 0xf0f0f0f, v89
	v_and_b32_e32 v69, 0xf0f0f0f, v34
	v_lshrrev_b32_e32 v34, 4, v90
	v_and_b32_e32 v79, 0xf0f0f0f, v34
	v_lshrrev_b32_e32 v34, 4, v91
	v_and_b32_e32 v80, 0xf0f0f0f, v91
	v_and_b32_e32 v81, 0xf0f0f0f, v34
	v_mfma_i32_16x16x64_i8 v[82:85], v[66:69], v[6:9], 0
	s_waitcnt vmcnt(10)
	v_lshrrev_b32_e32 v68, 4, v92
	v_cndmask_b32_e32 v66, v37, v36, vcc
	v_cndmask_b32_e32 v89, v55, v54, vcc
	v_mfma_i32_16x16x64_i8 v[34:37], v[78:81], v[2:5], v[82:85]
	v_and_b32_e32 v79, 0xf0f0f0f, v68
	v_lshrrev_b32_e32 v68, 4, v93
	v_and_b32_e32 v78, 0xf0f0f0f, v92
	v_and_b32_e32 v80, 0xf0f0f0f, v93
	v_and_b32_e32 v81, 0xf0f0f0f, v68
	v_lshrrev_b32_e32 v68, 4, v94
	v_and_b32_e32 v83, 0xf0f0f0f, v68
	v_lshrrev_b32_e32 v68, 4, v95
	v_and_b32_e32 v82, 0xf0f0f0f, v94
	v_and_b32_e32 v84, 0xf0f0f0f, v95
	v_and_b32_e32 v85, 0xf0f0f0f, v68
	v_mfma_i32_16x16x64_i8 v[34:37], v[78:81], v[14:17], v[34:37]
	v_cndmask_b32_e32 v68, v57, v56, vcc
	s_waitcnt vmcnt(9)
	v_lshrrev_b32_e32 v55, 4, v166
	v_lshrrev_b32_e32 v57, 4, v167
	v_and_b32_e32 v54, 0xf0f0f0f, v166
	v_and_b32_e32 v55, 0xf0f0f0f, v55
	v_and_b32_e32 v56, 0xf0f0f0f, v167
	v_and_b32_e32 v57, 0xf0f0f0f, v57
	v_mfma_i32_16x16x64_i8 v[34:37], v[82:85], v[10:13], v[34:37]
	v_lshrrev_b32_e32 v69, 4, v168
	v_and_b32_e32 v79, 0xf0f0f0f, v69
	v_lshrrev_b32_e32 v69, 4, v169
	v_and_b32_e32 v78, 0xf0f0f0f, v168
	v_and_b32_e32 v80, 0xf0f0f0f, v169
	v_and_b32_e32 v81, 0xf0f0f0f, v69
	v_mfma_i32_16x16x64_i8 v[34:37], v[54:57], v[22:25], v[34:37]
	s_waitcnt vmcnt(8)
	v_lshrrev_b32_e32 v55, 4, v170
	v_lshrrev_b32_e32 v57, 4, v171
	v_and_b32_e32 v54, 0xf0f0f0f, v170
	v_and_b32_e32 v55, 0xf0f0f0f, v55
	v_and_b32_e32 v56, 0xf0f0f0f, v171
	v_and_b32_e32 v57, 0xf0f0f0f, v57
	v_mfma_i32_16x16x64_i8 v[34:37], v[78:81], v[18:21], v[34:37]
	v_cndmask_b32_e32 v91, v59, v58, vcc
	v_lshrrev_b32_e32 v59, 4, v172
	v_and_b32_e32 v79, 0xf0f0f0f, v59
	v_lshrrev_b32_e32 v59, 4, v173
	v_and_b32_e32 v78, 0xf0f0f0f, v172
	v_and_b32_e32 v80, 0xf0f0f0f, v173
	v_and_b32_e32 v81, 0xf0f0f0f, v59
	v_mfma_i32_16x16x64_i8 v[34:37], v[54:57], v[26:29], v[34:37]
	s_waitcnt vmcnt(7)
	v_lshrrev_b32_e32 v55, 4, v178
	v_lshrrev_b32_e32 v57, 4, v179
	v_and_b32_e32 v54, 0xf0f0f0f, v178
	v_and_b32_e32 v55, 0xf0f0f0f, v55
	v_and_b32_e32 v56, 0xf0f0f0f, v179
	v_and_b32_e32 v57, 0xf0f0f0f, v57
	v_cndmask_b32_e32 v58, v61, v60, vcc
	v_lshrrev_b32_e32 v60, 4, v180
	v_mfma_i32_16x16x64_i8 v[34:37], v[78:81], v[30:33], v[34:37]
	v_and_b32_e32 v79, 0xf0f0f0f, v60
	v_lshrrev_b32_e32 v60, 4, v181
	v_and_b32_e32 v78, 0xf0f0f0f, v180
	v_and_b32_e32 v80, 0xf0f0f0f, v181
	v_and_b32_e32 v81, 0xf0f0f0f, v60
	v_mfma_i32_16x16x64_i8 v[54:57], v[54:57], v[6:9], 0
	v_cndmask_b32_e32 v82, v175, v174, vcc
	s_waitcnt vmcnt(6)
	v_lshrrev_b32_e32 v83, 4, v184
	v_lshrrev_b32_e32 v85, 4, v185
	v_mfma_i32_16x16x64_i8 v[54:57], v[78:81], v[2:5], v[54:57]
	v_lshrrev_b32_e32 v79, 4, v182
	v_lshrrev_b32_e32 v81, 4, v183
	v_and_b32_e32 v78, 0xf0f0f0f, v182
	v_and_b32_e32 v79, 0xf0f0f0f, v79
	v_and_b32_e32 v80, 0xf0f0f0f, v183
	v_and_b32_e32 v81, 0xf0f0f0f, v81
	v_add_u32_dpp v93, v82, v82 quad_perm:[1,0,3,2] row_mask:0xf bank_mask:0xf bound_ctrl:1
	v_and_b32_e32 v82, 0xf0f0f0f, v184
	v_and_b32_e32 v83, 0xf0f0f0f, v83
	v_and_b32_e32 v84, 0xf0f0f0f, v185
	v_and_b32_e32 v85, 0xf0f0f0f, v85
	v_mfma_i32_16x16x64_i8 v[54:57], v[78:81], v[14:17], v[54:57]
	s_waitcnt vmcnt(5)
	v_lshrrev_b32_e32 v79, 4, v186
	v_lshrrev_b32_e32 v81, 4, v187
	v_and_b32_e32 v78, 0xf0f0f0f, v186
	v_and_b32_e32 v79, 0xf0f0f0f, v79
	v_and_b32_e32 v80, 0xf0f0f0f, v187
	v_and_b32_e32 v81, 0xf0f0f0f, v81
	v_mfma_i32_16x16x64_i8 v[54:57], v[82:85], v[10:13], v[54:57]
	v_mov_b32_dpp v88, v96 quad_perm:[1,0,3,2] row_mask:0xf bank_mask:0xf bound_ctrl:1
	v_mov_b32_dpp v90, v89 quad_perm:[1,0,3,2] row_mask:0xf bank_mask:0xf bound_ctrl:1
	v_add_u32_e32 v88, v96, v88
	v_lshrrev_b32_e32 v83, 4, v188
	v_lshrrev_b32_e32 v85, 4, v189
	v_mov_b32_dpp v92, v91 quad_perm:[1,0,3,2] row_mask:0xf bank_mask:0xf bound_ctrl:1
	v_add_u32_e32 v89, v89, v90
	v_and_b32_e32 v82, 0xf0f0f0f, v188
	v_and_b32_e32 v83, 0xf0f0f0f, v83
	v_and_b32_e32 v84, 0xf0f0f0f, v189
	v_and_b32_e32 v85, 0xf0f0f0f, v85
	v_mfma_i32_16x16x64_i8 v[54:57], v[78:81], v[22:25], v[54:57]
	v_cndmask_b32_e64 v78, v190, v88, s[26:27]
	v_add_u32_e32 v91, v91, v92
	v_cndmask_b32_e64 v78, v78, v89, s[24:25]
	v_cndmask_b32_e64 v88, v78, v91, s[22:23]
	s_waitcnt vmcnt(4)
	v_and_b32_e32 v78, 0xf0f0f0f, v62
	v_lshrrev_b32_e32 v62, 4, v62
	v_and_b32_e32 v79, 0xf0f0f0f, v62
	v_lshrrev_b32_e32 v62, 4, v63
	v_and_b32_e32 v80, 0xf0f0f0f, v63
	v_and_b32_e32 v81, 0xf0f0f0f, v62
	v_mfma_i32_16x16x64_i8 v[54:57], v[82:85], v[18:21], v[54:57]
	v_lshrrev_b32_e32 v62, 4, v64
	v_and_b32_e32 v83, 0xf0f0f0f, v62
	v_lshrrev_b32_e32 v62, 4, v65
	v_and_b32_e32 v82, 0xf0f0f0f, v64
	v_and_b32_e32 v84, 0xf0f0f0f, v65
	v_and_b32_e32 v85, 0xf0f0f0f, v62
	ds_read_b64 v[64:65], v149
	v_mfma_i32_16x16x64_i8 v[54:57], v[78:81], v[26:29], v[54:57]
	v_cndmask_b32_e64 v63, v88, v93, s[20:21]
	v_cndmask_b32_e32 v88, v75, v74, vcc
	v_cndmask_b32_e32 v62, v77, v76, vcc
	v_mfma_i32_16x16x64_i8 v[74:77], v[82:85], v[30:33], v[54:57]
	s_waitcnt vmcnt(3)
	v_and_b32_e32 v78, 0xf0f0f0f, v50
	v_lshrrev_b32_e32 v50, 4, v50
	v_and_b32_e32 v79, 0xf0f0f0f, v50
	s_waitcnt lgkmcnt(0)
	v_ashrrev_i32_e32 v55, 31, v64
	v_mov_b32_e32 v54, v64
	v_lshl_add_u64 v[56:57], v[54:55], 2, s[56:57]
	global_load_dword v89, v[56:57], off
	v_ashrrev_i32_e32 v57, 31, v65
	v_mov_b32_e32 v56, v65
	v_lshl_add_u64 v[64:65], v[56:57], 2, s[56:57]
	global_load_dword v50, v[64:65], off
	v_and_b32_e32 v80, 0xf0f0f0f, v51
	v_lshrrev_b32_e32 v51, 4, v51
	v_and_b32_e32 v81, 0xf0f0f0f, v51
	v_lshrrev_b32_e32 v51, 4, v52
	v_and_b32_e32 v83, 0xf0f0f0f, v51
	v_lshrrev_b32_e32 v51, 4, v53
	v_and_b32_e32 v82, 0xf0f0f0f, v52
	v_and_b32_e32 v84, 0xf0f0f0f, v53
	v_and_b32_e32 v85, 0xf0f0f0f, v51
	v_mfma_i32_16x16x64_i8 v[78:81], v[78:81], v[6:9], 0
	v_add_u32_dpp v7, v88, v88 quad_perm:[1,0,3,2] row_mask:0xf bank_mask:0xf bound_ctrl:1
	v_cndmask_b32_e64 v51, v63, v7, s[28:29]
	s_waitcnt vmcnt(4)
	v_lshrrev_b32_e32 v7, 4, v42
	v_mfma_i32_16x16x64_i8 v[2:5], v[82:85], v[2:5], v[78:81]
	v_cndmask_b32_e32 v60, v177, v176, vcc
	v_mov_b32_dpp v71, v70 quad_perm:[1,0,3,2] row_mask:0xf bank_mask:0xf bound_ctrl:1
	v_mov_b32_dpp v73, v72 quad_perm:[1,0,3,2] row_mask:0xf bank_mask:0xf bound_ctrl:1
	v_and_b32_e32 v79, 0xf0f0f0f, v7
	v_lshrrev_b32_e32 v7, 4, v43
	v_and_b32_e32 v78, 0xf0f0f0f, v42
	v_and_b32_e32 v80, 0xf0f0f0f, v43
	v_and_b32_e32 v81, 0xf0f0f0f, v7
	v_lshrrev_b32_e32 v7, 4, v44
	v_and_b32_e32 v43, 0xf0f0f0f, v7
	v_lshrrev_b32_e32 v7, 4, v45
	v_and_b32_e32 v42, 0xf0f0f0f, v44
	v_and_b32_e32 v44, 0xf0f0f0f, v45
	v_and_b32_e32 v45, 0xf0f0f0f, v7
	v_mfma_i32_16x16x64_i8 v[14:17], v[78:81], v[14:17], v[2:5]
	v_mov_b32_dpp v67, v66 quad_perm:[1,0,3,2] row_mask:0xf bank_mask:0xf bound_ctrl:1
	v_mov_b32_dpp v69, v68 quad_perm:[1,0,3,2] row_mask:0xf bank_mask:0xf bound_ctrl:1
	v_mov_b32_dpp v59, v58 quad_perm:[1,0,3,2] row_mask:0xf bank_mask:0xf bound_ctrl:1
	s_waitcnt vmcnt(3)
	v_lshrrev_b32_e32 v3, 4, v46
	v_mfma_i32_16x16x64_i8 v[8:11], v[42:45], v[10:13], v[14:17]
	v_and_b32_e32 v13, 0xf0f0f0f, v3
	v_lshrrev_b32_e32 v3, 4, v47
	v_and_b32_e32 v12, 0xf0f0f0f, v46
	v_and_b32_e32 v14, 0xf0f0f0f, v47
	v_and_b32_e32 v15, 0xf0f0f0f, v3
	v_lshrrev_b32_e32 v3, 4, v48
	v_cndmask_b32_e32 v2, v35, v34, vcc
	v_and_b32_e32 v35, 0xf0f0f0f, v3
	v_lshrrev_b32_e32 v3, 4, v49
	v_cndmask_b32_e32 v5, v37, v36, vcc
	v_and_b32_e32 v34, 0xf0f0f0f, v48
	v_and_b32_e32 v36, 0xf0f0f0f, v49
	v_and_b32_e32 v37, 0xf0f0f0f, v3
	v_mfma_i32_16x16x64_i8 v[8:11], v[12:15], v[22:25], v[8:11]
	s_waitcnt vmcnt(2)
	v_lshrrev_b32_e32 v4, 4, v38
	v_and_b32_e32 v13, 0xf0f0f0f, v4
	v_lshrrev_b32_e32 v4, 4, v39
	v_and_b32_e32 v12, 0xf0f0f0f, v38
	v_and_b32_e32 v14, 0xf0f0f0f, v39
	v_and_b32_e32 v15, 0xf0f0f0f, v4
	v_mfma_i32_16x16x64_i8 v[8:11], v[34:37], v[18:21], v[8:11]
	v_lshrrev_b32_e32 v4, 4, v40
	v_and_b32_e32 v17, 0xf0f0f0f, v4
	v_lshrrev_b32_e32 v4, 4, v41
	v_and_b32_e32 v16, 0xf0f0f0f, v40
	v_and_b32_e32 v18, 0xf0f0f0f, v41
	v_and_b32_e32 v19, 0xf0f0f0f, v4
	v_mfma_i32_16x16x64_i8 v[10:13], v[12:15], v[26:29], v[8:11]
	v_add_u32_dpp v2, v2, v2 quad_perm:[1,0,3,2] row_mask:0xf bank_mask:0xf bound_ctrl:1
	v_cndmask_b32_e32 v3, v75, v74, vcc
	v_cndmask_b32_e64 v2, v51, v2, s[30:31]
	v_mfma_i32_16x16x64_i8 v[10:13], v[16:19], v[30:33], v[10:13]
	v_add_u32_dpp v3, v3, v3 quad_perm:[1,0,3,2] row_mask:0xf bank_mask:0xf bound_ctrl:1
	v_cndmask_b32_e64 v2, v2, v3, s[34:35]
	v_cndmask_b32_e32 v8, v77, v76, vcc
	v_mov_b32_dpp v61, v60 quad_perm:[1,0,3,2] row_mask:0xf bank_mask:0xf bound_ctrl:1
	v_mov_b32_dpp v6, v62 quad_perm:[1,0,3,2] row_mask:0xf bank_mask:0xf bound_ctrl:1
	s_nop 2
	v_cndmask_b32_e32 v3, v11, v10, vcc
	v_cndmask_b32_e32 v9, v13, v12, vcc
	v_mov_b32_dpp v7, v5 quad_perm:[1,0,3,2] row_mask:0xf bank_mask:0xf bound_ctrl:1
	v_add_u32_dpp v3, v3, v3 quad_perm:[1,0,3,2] row_mask:0xf bank_mask:0xf bound_ctrl:1
	v_cndmask_b32_e64 v2, v2, v3, s[36:37]
	v_cvt_f32_i32_e32 v2, v2
	v_mov_b32_dpp v10, v8 quad_perm:[1,0,3,2] row_mask:0xf bank_mask:0xf bound_ctrl:1
	v_mov_b32_dpp v11, v9 quad_perm:[1,0,3,2] row_mask:0xf bank_mask:0xf bound_ctrl:1
	v_fmac_f32_e32 v2, 0xc0f00000, v147
	s_waitcnt vmcnt(1)
	v_mul_f32_e32 v2, v89, v2
	v_mul_f32_e32 v2, v146, v2
	v_mul_f32_e32 v3, 0x3f3504f3, v2
	v_cmp_nlt_f32_e64 s[0:1], |v3|, 1.0
	s_and_saveexec_b64 s[38:39], s[0:1]
	s_xor_b64 s[0:1], exec, s[38:39]
	s_cbranch_execz .LBB0_611
	v_fma_f32 v4, |v3|, s3, v159
	v_fma_f32 v4, |v3|, v4, s33
	v_fma_f32 v4, |v3|, v4, s47
	v_fma_f32 v4, |v3|, v4, s64
	v_fma_f32 v4, |v3|, v4, s65
	v_fma_f32 v4, |v3|, v4, s66
	v_fma_f32 v4, |v3|, v4, |v3|
	v_mul_f32_e32 v12, 0xbfb8aa3b, v4
	v_fma_f32 v13, v4, s67, -v12
	v_rndne_f32_e32 v14, v12
	v_fmac_f32_e32 v13, 0xb2a5705f, v4
	v_sub_f32_e32 v12, v12, v14
	v_add_f32_e32 v12, v12, v13
	v_cvt_i32_f32_e32 v13, v14
	v_exp_f32_e32 v12, v12
	v_cmp_nlt_f32_e64 s[38:39], s76, v4
	v_ldexp_f32 v12, v12, v13
	s_nop 0
	v_cndmask_b32_e64 v12, 0, v12, s[38:39]
	v_cmp_ngt_f32_e64 s[38:39], s77, v4
	s_nop 1
	v_cndmask_b32_e64 v4, v160, v12, s[38:39]
	v_sub_f32_e32 v4, 1.0, v4

.LBB0_615:
	s_andn2_saveexec_b64 s[0:1], s[0:1]
	v_mul_f32_e32 v7, v6, v6
	v_fmamk_f32 v8, v7, 0xba1345e1, v157
	v_fmaak_f32 v8, v7, v8, 0xbcdac9b8
	v_fmaak_f32 v8, v7, v8, 0x3de703be
	v_fmaak_f32 v8, v7, v8, 0xbec09330
	v_fmaak_f32 v7, v7, v8, 0x3e0375d0
	v_fma_f32 v7, |v6|, v7, |v6|
	s_or_b64 exec, exec, s[0:1]
	v_readlane_b32 s48, v254, 40
	v_lshlrev_b64 v[8:9], 7, v[108:109]
	v_readlane_b32 s58, v254, 50
	v_readlane_b32 s59, v254, 51
	v_lshl_add_u64 v[8:9], v[8:9], 2, v[138:139]
	v_bfi_b32 v3, s78, v4, v3
	v_lshl_add_u64 v[10:11], v[54:55], 2, s[58:59]
	v_lshl_add_u64 v[12:13], v[56:57], 2, s[58:59]
	global_load_dwordx2 v[8:9], v[8:9], off
	s_nop 0
	global_load_dword v10, v[10:11], off
	s_nop 0
	global_load_dword v11, v[12:13], off
	v_mul_f32_e32 v4, 0.5, v5
	v_bfi_b32 v5, s78, v7, v6
	v_mul_f32_e32 v2, 0.5, v2
	v_add_f32_e32 v3, 1.0, v3
	v_add_f32_e32 v5, 1.0, v5
	v_mul_f32_e32 v2, v2, v3
	v_mul_f32_e32 v3, v4, v5
	v_mov_b32_e32 v92, 0
	s_mov_b32 s0, 0
	v_mov_b32_e32 v93, v92
	v_mov_b32_e32 v90, v92
	v_mov_b32_e32 v91, v92
	v_mov_b32_e32 v86, v92
	v_mov_b32_e32 v87, v92
	v_mov_b32_e32 v84, v92
	v_mov_b32_e32 v85, v92
	v_mov_b32_e32 v80, v92
	v_mov_b32_e32 v81, v92
	v_mov_b32_e32 v78, v92
	v_mov_b32_e32 v79, v92
	v_mov_b32_e32 v70, v92
	v_mov_b32_e32 v71, v92
	v_mov_b32_e32 v62, v92
	v_mov_b32_e32 v63, v92
	v_readlane_b32 s49, v254, 41
	v_readlane_b32 s50, v254, 42
	v_readlane_b32 s51, v254, 43
	v_readlane_b32 s52, v254, 44
	v_readlane_b32 s53, v254, 45
	v_readlane_b32 s54, v254, 46
	v_readlane_b32 s55, v254, 47
	v_readlane_b32 s56, v254, 48
	v_readlane_b32 s57, v254, 49
	v_readlane_b32 s60, v254, 52
	v_readlane_b32 s61, v254, 53
	v_readlane_b32 s62, v254, 54
	v_readlane_b32 s63, v254, 55
	s_waitcnt vmcnt(2)
	v_pk_mul_f32 v[2:3], v[2:3], v[8:9]
	s_waitcnt vmcnt(0)
	v_pk_mul_f32 v[24:25], v[2:3], v[10:11]
	ds_write_b64 v149, v[24:25] offset:512
	v_lshl_add_u64 v[244:245], v[144:145], 2, v[136:137]
	global_load_dwordx4 v[228:231], v[244:245], off
	global_load_dwordx4 v[232:235], v[244:245], off offset:16
	global_load_dwordx4 v[236:239], v[244:245], off offset:32
	global_load_dwordx4 v[240:243], v[244:245], off offset:48
	v_add_u32_e32 v34, s2, v108
	v_min_u32_e32 v34, 0x7fff, v34
	v_mov_b32_e32 v35, 0
	v_lshlrev_b64 v[36:37], 9, v[34:35]
	v_lshlrev_b64 v[38:39], 10, v[34:35]
	v_lshlrev_b64 v[40:41], 2, v[34:35]
	v_lshl_add_u64 v[36:37], v[132:133], 0, v[36:37]
	v_lshl_add_u64 v[38:39], v[134:135], 0, v[38:39]
	v_lshl_add_u64 v[42:43], s[68:69], 0, v[40:41]
	v_lshl_add_u64 v[40:41], s[70:71], 0, v[40:41]
	global_load_dword v246, v[36:37], off
	global_load_dword v247, v[36:37], off offset:256
	global_load_dwordx4 v[248:251], v[38:39], off
	global_load_dword v252, v[42:43], off
	global_load_dword v253, v[40:41], off
	s_mov_b32 s0, 0x0f0f0f0f
	s_mov_b32 s1, 0xf0f0f0f0
	v_readfirstlane_b32 s38, v114
	v_readfirstlane_b32 s39, v115
	v_mul_f32_e32 v146, 0x3d800000, v24
	v_mul_f32_e32 v147, 0x3d800000, v25
	v_subrev_u32_e32 v100, s38, v114
	ds_write_b64 v149, v[146:147] offset:1536
	ds_read_b128 v[72:75], v1 offset:0
	ds_read_b128 v[94:97], v1 offset:16
	ds_read_b128 v[50:53], v1 offset:32
	ds_read_b128 v[54:57], v1 offset:48
	s_waitcnt lgkmcnt(2)
	v_lshl_add_u32 v72, v72, 9, v100
	v_lshl_add_u32 v73, v73, 9, v100
	v_lshl_add_u32 v74, v74, 9, v100
	v_lshl_add_u32 v75, v75, 9, v100
	v_lshl_add_u32 v94, v94, 9, v100
	v_lshl_add_u32 v95, v95, 9, v100
	v_lshl_add_u32 v96, v96, 9, v100
	v_lshl_add_u32 v97, v97, 9, v100
	global_load_dwordx2 v[164:165], v72, s[38:39]
	global_load_dwordx2 v[166:167], v73, s[38:39]
	global_load_dwordx2 v[168:169], v74, s[38:39]
	global_load_dwordx2 v[170:171], v75, s[38:39]
	global_load_dwordx2 v[172:173], v94, s[38:39]
	global_load_dwordx2 v[174:175], v95, s[38:39]
	global_load_dwordx2 v[176:177], v96, s[38:39]
	global_load_dwordx2 v[178:179], v97, s[38:39]
	ds_read_b128 v[72:75], v1 offset:64
	ds_read_b128 v[94:97], v1 offset:80
	s_waitcnt lgkmcnt(2)
	v_lshl_add_u32 v50, v50, 9, v100
	v_lshl_add_u32 v51, v51, 9, v100
	v_lshl_add_u32 v52, v52, 9, v100
	v_lshl_add_u32 v53, v53, 9, v100
	v_lshl_add_u32 v54, v54, 9, v100
	v_lshl_add_u32 v55, v55, 9, v100
	v_lshl_add_u32 v56, v56, 9, v100
	v_lshl_add_u32 v57, v57, 9, v100
	global_load_dwordx2 v[180:181], v50, s[38:39]
	global_load_dwordx2 v[182:183], v51, s[38:39]
	global_load_dwordx2 v[184:185], v52, s[38:39]
	global_load_dwordx2 v[186:187], v53, s[38:39]
	global_load_dwordx2 v[188:189], v54, s[38:39]
	global_load_dwordx2 v[190:191], v55, s[38:39]
	global_load_dwordx2 v[192:193], v56, s[38:39]
	global_load_dwordx2 v[194:195], v57, s[38:39]
	ds_read_b128 v[50:53], v1 offset:96
	ds_read_b128 v[54:57], v1 offset:112
	s_waitcnt lgkmcnt(2)
	v_lshl_add_u32 v72, v72, 9, v100
	v_lshl_add_u32 v73, v73, 9, v100
	v_lshl_add_u32 v74, v74, 9, v100
	v_lshl_add_u32 v75, v75, 9, v100
	v_lshl_add_u32 v94, v94, 9, v100
	v_lshl_add_u32 v95, v95, 9, v100
	v_lshl_add_u32 v96, v96, 9, v100
	v_lshl_add_u32 v97, v97, 9, v100
	global_load_dwordx2 v[196:197], v72, s[38:39]
	global_load_dwordx2 v[198:199], v73, s[38:39]
	global_load_dwordx2 v[200:201], v74, s[38:39]
	global_load_dwordx2 v[202:203], v75, s[38:39]
	global_load_dwordx2 v[204:205], v94, s[38:39]
	global_load_dwordx2 v[206:207], v95, s[38:39]
	global_load_dwordx2 v[208:209], v96, s[38:39]
	global_load_dwordx2 v[210:211], v97, s[38:39]
	ds_read_b128 v[72:75], v1 offset:128
	ds_read_b128 v[94:97], v1 offset:144
	s_waitcnt lgkmcnt(2)
	v_lshl_add_u32 v50, v50, 9, v100
	v_lshl_add_u32 v51, v51, 9, v100
	v_lshl_add_u32 v52, v52, 9, v100
	v_lshl_add_u32 v53, v53, 9, v100
	v_lshl_add_u32 v54, v54, 9, v100
	v_lshl_add_u32 v55, v55, 9, v100
	v_lshl_add_u32 v56, v56, 9, v100
	v_lshl_add_u32 v57, v57, 9, v100
	global_load_dwordx2 v[212:213], v50, s[38:39]
	global_load_dwordx2 v[214:215], v51, s[38:39]
	global_load_dwordx2 v[216:217], v52, s[38:39]
	global_load_dwordx2 v[218:219], v53, s[38:39]
	global_load_dwordx2 v[220:221], v54, s[38:39]
	global_load_dwordx2 v[222:223], v55, s[38:39]
	global_load_dwordx2 v[224:225], v56, s[38:39]
	global_load_dwordx2 v[226:227], v57, s[38:39]
	s_waitcnt lgkmcnt(0)
	v_lshl_add_u32 v72, v72, 9, v100
	v_lshl_add_u32 v73, v73, 9, v100
	v_lshl_add_u32 v74, v74, 9, v100
	v_lshl_add_u32 v75, v75, 9, v100
	v_lshl_add_u32 v94, v94, 9, v100
	v_lshl_add_u32 v95, v95, 9, v100
	v_lshl_add_u32 v96, v96, 9, v100
	v_lshl_add_u32 v97, v97, 9, v100
	global_load_dwordx2 v[2:3], v72, s[38:39]
	global_load_dwordx2 v[4:5], v73, s[38:39]
	global_load_dwordx2 v[6:7], v74, s[38:39]
	global_load_dwordx2 v[8:9], v75, s[38:39]
	global_load_dwordx2 v[10:11], v94, s[38:39]
	global_load_dwordx2 v[12:13], v95, s[38:39]
	global_load_dwordx2 v[14:15], v96, s[38:39]
	global_load_dwordx2 v[16:17], v97, s[38:39]
	v_add_f32_e32 v146, v24, v25
	ds_bpermute_b32 v147, v150, v146
	s_waitcnt lgkmcnt(0)
	v_add_f32_e32 v146, v146, v147
	ds_bpermute_b32 v147, v151, v146
	s_waitcnt lgkmcnt(0)
	v_add_f32_e32 v146, v146, v147
	ds_bpermute_b32 v147, v152, v146
	s_waitcnt lgkmcnt(0)
	v_add_f32_e32 v146, v146, v147
	ds_bpermute_b32 v147, v153, v146
	s_waitcnt lgkmcnt(0)
	v_add_f32_e32 v146, v146, v147
	ds_bpermute_b32 v147, v154, v146
	s_waitcnt lgkmcnt(0)
	v_add_f32_e32 v101, v146, v147
	ds_bpermute_b32 v162, v155, v101
	ds_read_b128 v[72:75], v1 offset:160
	ds_read_b128 v[94:97], v1 offset:176
	ds_read_b128 v[34:37], v1 offset:512
	ds_read_b128 v[38:41], v1 offset:528
	ds_read_b128 v[42:45], v1 offset:1536
	ds_read_b128 v[46:49], v1 offset:1552
	s_waitcnt lgkmcnt(0)
	v_lshl_add_u32 v72, v72, 9, v100
	v_lshl_add_u32 v73, v73, 9, v100
	v_lshl_add_u32 v74, v74, 9, v100
	v_lshl_add_u32 v75, v75, 9, v100
	v_lshl_add_u32 v94, v94, 9, v100
	v_lshl_add_u32 v95, v95, 9, v100
	v_lshl_add_u32 v96, v96, 9, v100
	v_lshl_add_u32 v97, v97, 9, v100
	global_load_dwordx2 v[18:19], v72, s[38:39]
	global_load_dwordx2 v[20:21], v73, s[38:39]
	global_load_dwordx2 v[22:23], v74, s[38:39]
	global_load_dwordx2 v[24:25], v75, s[38:39]
	global_load_dwordx2 v[26:27], v94, s[38:39]
	global_load_dwordx2 v[28:29], v95, s[38:39]
	global_load_dwordx2 v[30:31], v96, s[38:39]
	global_load_dwordx2 v[32:33], v97, s[38:39]
	ds_read_b128 v[72:75], v1 offset:192
	ds_read_b128 v[94:97], v1 offset:208
	ds_read_b128 v[50:53], v1 offset:544
	ds_read_b128 v[54:57], v1 offset:560
	ds_read_b128 v[58:61], v1 offset:1568
	ds_read_b128 v[64:67], v1 offset:1584
	s_waitcnt vmcnt(40)
	v_and_b32_e32 v68, s0, v164
	v_and_b32_e32 v69, s1, v164
	v_and_b32_e32 v76, s0, v165
	v_and_b32_e32 v77, s1, v165
	v_cvt_f32_ubyte0_e32 v98, v68
	v_cvt_f32_ubyte1_e32 v99, v68
	v_cvt_f32_ubyte2_e32 v102, v68
	v_cvt_f32_ubyte3_e32 v103, v68
	v_pk_fma_f32 v[92:93], v[34:35], v[98:99], v[92:93] op_sel_hi:[0,1,1]
	v_cvt_f32_ubyte0_e32 v104, v69
	v_cvt_f32_ubyte1_e32 v105, v69
	v_pk_fma_f32 v[90:91], v[34:35], v[102:103], v[90:91] op_sel_hi:[0,1,1]
	v_cvt_f32_ubyte2_e32 v146, v69
	v_cvt_f32_ubyte3_e32 v147, v69
	v_pk_fma_f32 v[86:87], v[42:43], v[104:105], v[86:87] op_sel_hi:[0,1,1]
	v_cvt_f32_ubyte0_e32 v98, v76
	v_cvt_f32_ubyte1_e32 v99, v76
	v_pk_fma_f32 v[84:85], v[42:43], v[146:147], v[84:85] op_sel_hi:[0,1,1]
	v_and_b32_e32 v82, s0, v166
	v_and_b32_e32 v83, s1, v166
	v_and_b32_e32 v88, s0, v167
	v_and_b32_e32 v89, s1, v167
	v_cvt_f32_ubyte2_e32 v102, v76
	v_cvt_f32_ubyte3_e32 v103, v76
	v_pk_fma_f32 v[80:81], v[34:35], v[98:99], v[80:81] op_sel_hi:[0,1,1]
	v_cvt_f32_ubyte0_e32 v104, v77
	v_cvt_f32_ubyte1_e32 v105, v77
	v_pk_fma_f32 v[78:79], v[34:35], v[102:103], v[78:79] op_sel_hi:[0,1,1]
	v_cvt_f32_ubyte2_e32 v146, v77
	v_cvt_f32_ubyte3_e32 v147, v77
	v_pk_fma_f32 v[70:71], v[42:43], v[104:105], v[70:71] op_sel_hi:[0,1,1]
	v_cvt_f32_ubyte0_e32 v98, v82
	v_cvt_f32_ubyte1_e32 v99, v82
	v_pk_fma_f32 v[62:63], v[42:43], v[146:147], v[62:63] op_sel_hi:[0,1,1]
	v_cvt_f32_ubyte2_e32 v102, v82
	v_cvt_f32_ubyte3_e32 v103, v82
	v_pk_fma_f32 v[92:93], v[34:35], v[98:99], v[92:93] op_sel:[1,0,0]
	v_cvt_f32_ubyte0_e32 v104, v83
	v_cvt_f32_ubyte1_e32 v105, v83
	v_pk_fma_f32 v[90:91], v[34:35], v[102:103], v[90:91] op_sel:[1,0,0]
	v_cvt_f32_ubyte2_e32 v146, v83
	v_cvt_f32_ubyte3_e32 v147, v83
	v_pk_fma_f32 v[86:87], v[42:43], v[104:105], v[86:87] op_sel:[1,0,0]
	v_cvt_f32_ubyte0_e32 v98, v88
	v_cvt_f32_ubyte1_e32 v99, v88
	v_pk_fma_f32 v[84:85], v[42:43], v[146:147], v[84:85] op_sel:[1,0,0]
	v_and_b32_e32 v68, s0, v168
	v_and_b32_e32 v69, s1, v168
	v_and_b32_e32 v76, s0, v169
	v_and_b32_e32 v77, s1, v169
	v_cvt_f32_ubyte2_e32 v102, v88
	v_cvt_f32_ubyte3_e32 v103, v88
	v_pk_fma_f32 v[80:81], v[34:35], v[98:99], v[80:81] op_sel:[1,0,0]
	v_cvt_f32_ubyte0_e32 v104, v89
	v_cvt_f32_ubyte1_e32 v105, v89
	v_pk_fma_f32 v[78:79], v[34:35], v[102:103], v[78:79] op_sel:[1,0,0]
	v_cvt_f32_ubyte2_e32 v146, v89
	v_cvt_f32_ubyte3_e32 v147, v89
	v_pk_fma_f32 v[70:71], v[42:43], v[104:105], v[70:71] op_sel:[1,0,0]
	v_cvt_f32_ubyte0_e32 v98, v68
	v_cvt_f32_ubyte1_e32 v99, v68
	v_pk_fma_f32 v[62:63], v[42:43], v[146:147], v[62:63] op_sel:[1,0,0]
	v_cvt_f32_ubyte2_e32 v102, v68
	v_cvt_f32_ubyte3_e32 v103, v68
	v_pk_fma_f32 v[92:93], v[36:37], v[98:99], v[92:93] op_sel_hi:[0,1,1]
	v_cvt_f32_ubyte0_e32 v104, v69
	v_cvt_f32_ubyte1_e32 v105, v69
	v_pk_fma_f32 v[90:91], v[36:37], v[102:103], v[90:91] op_sel_hi:[0,1,1]
	v_cvt_f32_ubyte2_e32 v146, v69
	v_cvt_f32_ubyte3_e32 v147, v69
	v_pk_fma_f32 v[86:87], v[44:45], v[104:105], v[86:87] op_sel_hi:[0,1,1]
	v_cvt_f32_ubyte0_e32 v98, v76
	v_cvt_f32_ubyte1_e32 v99, v76
	v_pk_fma_f32 v[84:85], v[44:45], v[146:147], v[84:85] op_sel_hi:[0,1,1]
	v_and_b32_e32 v82, s0, v170
	v_and_b32_e32 v83, s1, v170
	v_and_b32_e32 v88, s0, v171
	v_and_b32_e32 v89, s1, v171
	v_cvt_f32_ubyte2_e32 v102, v76
	v_cvt_f32_ubyte3_e32 v103, v76
	v_pk_fma_f32 v[80:81], v[36:37], v[98:99], v[80:81] op_sel_hi:[0,1,1]
	v_cvt_f32_ubyte0_e32 v104, v77
	v_cvt_f32_ubyte1_e32 v105, v77
	v_pk_fma_f32 v[78:79], v[36:37], v[102:103], v[78:79] op_sel_hi:[0,1,1]
	v_cvt_f32_ubyte2_e32 v146, v77
	v_cvt_f32_ubyte3_e32 v147, v77
	v_pk_fma_f32 v[70:71], v[44:45], v[104:105], v[70:71] op_sel_hi:[0,1,1]
	v_cvt_f32_ubyte0_e32 v98, v82
	v_cvt_f32_ubyte1_e32 v99, v82
	v_pk_fma_f32 v[62:63], v[44:45], v[146:147], v[62:63] op_sel_hi:[0,1,1]
	v_cvt_f32_ubyte2_e32 v102, v82
	v_cvt_f32_ubyte3_e32 v103, v82
	v_pk_fma_f32 v[92:93], v[36:37], v[98:99], v[92:93] op_sel:[1,0,0]
	v_cvt_f32_ubyte0_e32 v104, v83
	v_cvt_f32_ubyte1_e32 v105, v83
	v_pk_fma_f32 v[90:91], v[36:37], v[102:103], v[90:91] op_sel:[1,0,0]
	v_cvt_f32_ubyte2_e32 v146, v83
	v_cvt_f32_ubyte3_e32 v147, v83
	v_pk_fma_f32 v[86:87], v[44:45], v[104:105], v[86:87] op_sel:[1,0,0]
	v_cvt_f32_ubyte0_e32 v98, v88
	v_cvt_f32_ubyte1_e32 v99, v88
	v_pk_fma_f32 v[84:85], v[44:45], v[146:147], v[84:85] op_sel:[1,0,0]
	v_and_b32_e32 v68, s0, v172
	v_and_b32_e32 v69, s1, v172
	v_and_b32_e32 v76, s0, v173
	v_and_b32_e32 v77, s1, v173
	v_cvt_f32_ubyte2_e32 v102, v88
	v_cvt_f32_ubyte3_e32 v103, v88
	v_pk_fma_f32 v[80:81], v[36:37], v[98:99], v[80:81] op_sel:[1,0,0]
	v_cvt_f32_ubyte0_e32 v104, v89
	v_cvt_f32_ubyte1_e32 v105, v89
	v_pk_fma_f32 v[78:79], v[36:37], v[102:103], v[78:79] op_sel:[1,0,0]
	v_cvt_f32_ubyte2_e32 v146, v89
	v_cvt_f32_ubyte3_e32 v147, v89
	v_pk_fma_f32 v[70:71], v[44:45], v[104:105], v[70:71] op_sel:[1,0,0]
	v_cvt_f32_ubyte0_e32 v98, v68
	v_cvt_f32_ubyte1_e32 v99, v68
	v_pk_fma_f32 v[62:63], v[44:45], v[146:147], v[62:63] op_sel:[1,0,0]
	v_cvt_f32_ubyte2_e32 v102, v68
	v_cvt_f32_ubyte3_e32 v103, v68
	v_pk_fma_f32 v[92:93], v[38:39], v[98:99], v[92:93] op_sel_hi:[0,1,1]
	v_cvt_f32_ubyte0_e32 v104, v69
	v_cvt_f32_ubyte1_e32 v105, v69
	v_pk_fma_f32 v[90:91], v[38:39], v[102:103], v[90:91] op_sel_hi:[0,1,1]
	v_cvt_f32_ubyte2_e32 v146, v69
	v_cvt_f32_ubyte3_e32 v147, v69
	v_pk_fma_f32 v[86:87], v[46:47], v[104:105], v[86:87] op_sel_hi:[0,1,1]
	v_cvt_f32_ubyte0_e32 v98, v76
	v_cvt_f32_ubyte1_e32 v99, v76
	v_pk_fma_f32 v[84:85], v[46:47], v[146:147], v[84:85] op_sel_hi:[0,1,1]
	v_and_b32_e32 v82, s0, v174
	v_and_b32_e32 v83, s1, v174
	v_and_b32_e32 v88, s0, v175
	v_and_b32_e32 v89, s1, v175
	v_cvt_f32_ubyte2_e32 v102, v76
	v_cvt_f32_ubyte3_e32 v103, v76
	v_pk_fma_f32 v[80:81], v[38:39], v[98:99], v[80:81] op_sel_hi:[0,1,1]
	v_cvt_f32_ubyte0_e32 v104, v77
	v_cvt_f32_ubyte1_e32 v105, v77
	v_pk_fma_f32 v[78:79], v[38:39], v[102:103], v[78:79] op_sel_hi:[0,1,1]
	v_cvt_f32_ubyte2_e32 v146, v77
	v_cvt_f32_ubyte3_e32 v147, v77
	v_pk_fma_f32 v[70:71], v[46:47], v[104:105], v[70:71] op_sel_hi:[0,1,1]
	v_cvt_f32_ubyte0_e32 v98, v82
	v_cvt_f32_ubyte1_e32 v99, v82
	v_pk_fma_f32 v[62:63], v[46:47], v[146:147], v[62:63] op_sel_hi:[0,1,1]
	v_cvt_f32_ubyte2_e32 v102, v82
	v_cvt_f32_ubyte3_e32 v103, v82
	v_pk_fma_f32 v[92:93], v[38:39], v[98:99], v[92:93] op_sel:[1,0,0]
	v_cvt_f32_ubyte0_e32 v104, v83
	v_cvt_f32_ubyte1_e32 v105, v83
	v_pk_fma_f32 v[90:91], v[38:39], v[102:103], v[90:91] op_sel:[1,0,0]
	v_cvt_f32_ubyte2_e32 v146, v83
	v_cvt_f32_ubyte3_e32 v147, v83
	v_pk_fma_f32 v[86:87], v[46:47], v[104:105], v[86:87] op_sel:[1,0,0]
	v_cvt_f32_ubyte0_e32 v98, v88
	v_cvt_f32_ubyte1_e32 v99, v88
	v_pk_fma_f32 v[84:85], v[46:47], v[146:147], v[84:85] op_sel:[1,0,0]
	v_and_b32_e32 v68, s0, v176
	v_and_b32_e32 v69, s1, v176
	v_and_b32_e32 v76, s0, v177
	v_and_b32_e32 v77, s1, v177
	v_cvt_f32_ubyte2_e32 v102, v88
	v_cvt_f32_ubyte3_e32 v103, v88
	v_pk_fma_f32 v[80:81], v[38:39], v[98:99], v[80:81] op_sel:[1,0,0]
	v_cvt_f32_ubyte0_e32 v104, v89
	v_cvt_f32_ubyte1_e32 v105, v89
	v_pk_fma_f32 v[78:79], v[38:39], v[102:103], v[78:79] op_sel:[1,0,0]
	v_cvt_f32_ubyte2_e32 v146, v89
	v_cvt_f32_ubyte3_e32 v147, v89
	v_pk_fma_f32 v[70:71], v[46:47], v[104:105], v[70:71] op_sel:[1,0,0]
	v_cvt_f32_ubyte0_e32 v98, v68
	v_cvt_f32_ubyte1_e32 v99, v68
	v_pk_fma_f32 v[62:63], v[46:47], v[146:147], v[62:63] op_sel:[1,0,0]
	v_cvt_f32_ubyte2_e32 v102, v68
	v_cvt_f32_ubyte3_e32 v103, v68
	v_pk_fma_f32 v[92:93], v[40:41], v[98:99], v[92:93] op_sel_hi:[0,1,1]
	v_cvt_f32_ubyte0_e32 v104, v69
	v_cvt_f32_ubyte1_e32 v105, v69
	v_pk_fma_f32 v[90:91], v[40:41], v[102:103], v[90:91] op_sel_hi:[0,1,1]
	v_cvt_f32_ubyte2_e32 v146, v69
	v_cvt_f32_ubyte3_e32 v147, v69
	v_pk_fma_f32 v[86:87], v[48:49], v[104:105], v[86:87] op_sel_hi:[0,1,1]
	v_cvt_f32_ubyte0_e32 v98, v76
	v_cvt_f32_ubyte1_e32 v99, v76
	v_pk_fma_f32 v[84:85], v[48:49], v[146:147], v[84:85] op_sel_hi:[0,1,1]
	v_and_b32_e32 v82, s0, v178
	v_and_b32_e32 v83, s1, v178
	v_and_b32_e32 v88, s0, v179
	v_and_b32_e32 v89, s1, v179
	v_cvt_f32_ubyte2_e32 v102, v76
	v_cvt_f32_ubyte3_e32 v103, v76
	v_pk_fma_f32 v[80:81], v[40:41], v[98:99], v[80:81] op_sel_hi:[0,1,1]
	v_cvt_f32_ubyte0_e32 v104, v77
	v_cvt_f32_ubyte1_e32 v105, v77
	v_pk_fma_f32 v[78:79], v[40:41], v[102:103], v[78:79] op_sel_hi:[0,1,1]
	v_cvt_f32_ubyte2_e32 v146, v77
	v_cvt_f32_ubyte3_e32 v147, v77
	v_pk_fma_f32 v[70:71], v[48:49], v[104:105], v[70:71] op_sel_hi:[0,1,1]
	v_cvt_f32_ubyte0_e32 v98, v82
	v_cvt_f32_ubyte1_e32 v99, v82
	v_pk_fma_f32 v[62:63], v[48:49], v[146:147], v[62:63] op_sel_hi:[0,1,1]
	v_cvt_f32_ubyte2_e32 v102, v82
	v_cvt_f32_ubyte3_e32 v103, v82
	v_pk_fma_f32 v[92:93], v[40:41], v[98:99], v[92:93] op_sel:[1,0,0]
	v_cvt_f32_ubyte0_e32 v104, v83
	v_cvt_f32_ubyte1_e32 v105, v83
	v_pk_fma_f32 v[90:91], v[40:41], v[102:103], v[90:91] op_sel:[1,0,0]
	v_cvt_f32_ubyte2_e32 v146, v83
	v_cvt_f32_ubyte3_e32 v147, v83
	v_pk_fma_f32 v[86:87], v[48:49], v[104:105], v[86:87] op_sel:[1,0,0]
	v_cvt_f32_ubyte0_e32 v98, v88
	v_cvt_f32_ubyte1_e32 v99, v88
	v_pk_fma_f32 v[84:85], v[48:49], v[146:147], v[84:85] op_sel:[1,0,0]
	v_cvt_f32_ubyte2_e32 v102, v88
	v_cvt_f32_ubyte3_e32 v103, v88
	v_pk_fma_f32 v[80:81], v[40:41], v[98:99], v[80:81] op_sel:[1,0,0]
	v_cvt_f32_ubyte0_e32 v104, v89
	v_cvt_f32_ubyte1_e32 v105, v89
	v_pk_fma_f32 v[78:79], v[40:41], v[102:103], v[78:79] op_sel:[1,0,0]
	v_cvt_f32_ubyte2_e32 v146, v89
	v_cvt_f32_ubyte3_e32 v147, v89
	v_pk_fma_f32 v[70:71], v[48:49], v[104:105], v[70:71] op_sel:[1,0,0]
	v_pk_fma_f32 v[62:63], v[48:49], v[146:147], v[62:63] op_sel:[1,0,0]
	s_waitcnt lgkmcnt(0)
	v_lshl_add_u32 v72, v72, 9, v100
	v_lshl_add_u32 v73, v73, 9, v100
	v_lshl_add_u32 v74, v74, 9, v100
	v_lshl_add_u32 v75, v75, 9, v100
	v_lshl_add_u32 v94, v94, 9, v100
	v_lshl_add_u32 v95, v95, 9, v100
	v_lshl_add_u32 v96, v96, 9, v100
	v_lshl_add_u32 v97, v97, 9, v100
	global_load_dwordx2 v[164:165], v72, s[38:39]
	global_load_dwordx2 v[166:167], v73, s[38:39]
	global_load_dwordx2 v[168:169], v74, s[38:39]
	global_load_dwordx2 v[170:171], v75, s[38:39]
	global_load_dwordx2 v[172:173], v94, s[38:39]
	global_load_dwordx2 v[174:175], v95, s[38:39]
	global_load_dwordx2 v[176:177], v96, s[38:39]
	global_load_dwordx2 v[178:179], v97, s[38:39]
	ds_read_b128 v[72:75], v1 offset:224
	ds_read_b128 v[94:97], v1 offset:240
	ds_read_b128 v[34:37], v1 offset:576
	ds_read_b128 v[38:41], v1 offset:592
	ds_read_b128 v[42:45], v1 offset:1600
	ds_read_b128 v[46:49], v1 offset:1616
	s_waitcnt vmcnt(40)
	v_and_b32_e32 v68, s0, v180
	v_and_b32_e32 v69, s1, v180
	v_and_b32_e32 v76, s0, v181
	v_and_b32_e32 v77, s1, v181
	v_cvt_f32_ubyte0_e32 v98, v68
	v_cvt_f32_ubyte1_e32 v99, v68
	v_cvt_f32_ubyte2_e32 v102, v68
	v_cvt_f32_ubyte3_e32 v103, v68
	v_pk_fma_f32 v[92:93], v[50:51], v[98:99], v[92:93] op_sel_hi:[0,1,1]
	v_cvt_f32_ubyte0_e32 v104, v69
	v_cvt_f32_ubyte1_e32 v105, v69
	v_pk_fma_f32 v[90:91], v[50:51], v[102:103], v[90:91] op_sel_hi:[0,1,1]
	v_cvt_f32_ubyte2_e32 v146, v69
	v_cvt_f32_ubyte3_e32 v147, v69
	v_pk_fma_f32 v[86:87], v[58:59], v[104:105], v[86:87] op_sel_hi:[0,1,1]
	v_cvt_f32_ubyte0_e32 v98, v76
	v_cvt_f32_ubyte1_e32 v99, v76
	v_pk_fma_f32 v[84:85], v[58:59], v[146:147], v[84:85] op_sel_hi:[0,1,1]
	v_and_b32_e32 v82, s0, v182
	v_and_b32_e32 v83, s1, v182
	v_and_b32_e32 v88, s0, v183
	v_and_b32_e32 v89, s1, v183
	v_cvt_f32_ubyte2_e32 v102, v76
	v_cvt_f32_ubyte3_e32 v103, v76
	v_pk_fma_f32 v[80:81], v[50:51], v[98:99], v[80:81] op_sel_hi:[0,1,1]
	v_cvt_f32_ubyte0_e32 v104, v77
	v_cvt_f32_ubyte1_e32 v105, v77
	v_pk_fma_f32 v[78:79], v[50:51], v[102:103], v[78:79] op_sel_hi:[0,1,1]
	v_cvt_f32_ubyte2_e32 v146, v77
	v_cvt_f32_ubyte3_e32 v147, v77
	v_pk_fma_f32 v[70:71], v[58:59], v[104:105], v[70:71] op_sel_hi:[0,1,1]
	v_cvt_f32_ubyte0_e32 v98, v82
	v_cvt_f32_ubyte1_e32 v99, v82
	v_pk_fma_f32 v[62:63], v[58:59], v[146:147], v[62:63] op_sel_hi:[0,1,1]
	v_cvt_f32_ubyte2_e32 v102, v82
	v_cvt_f32_ubyte3_e32 v103, v82
	v_pk_fma_f32 v[92:93], v[50:51], v[98:99], v[92:93] op_sel:[1,0,0]
	v_cvt_f32_ubyte0_e32 v104, v83
	v_cvt_f32_ubyte1_e32 v105, v83
	v_pk_fma_f32 v[90:91], v[50:51], v[102:103], v[90:91] op_sel:[1,0,0]
	v_cvt_f32_ubyte2_e32 v146, v83
	v_cvt_f32_ubyte3_e32 v147, v83
	v_pk_fma_f32 v[86:87], v[58:59], v[104:105], v[86:87] op_sel:[1,0,0]
	v_cvt_f32_ubyte0_e32 v98, v88
	v_cvt_f32_ubyte1_e32 v99, v88
	v_pk_fma_f32 v[84:85], v[58:59], v[146:147], v[84:85] op_sel:[1,0,0]
	v_and_b32_e32 v68, s0, v184
	v_and_b32_e32 v69, s1, v184
	v_and_b32_e32 v76, s0, v185
	v_and_b32_e32 v77, s1, v185
	v_cvt_f32_ubyte2_e32 v102, v88
	v_cvt_f32_ubyte3_e32 v103, v88
	v_pk_fma_f32 v[80:81], v[50:51], v[98:99], v[80:81] op_sel:[1,0,0]
	v_cvt_f32_ubyte0_e32 v104, v89
	v_cvt_f32_ubyte1_e32 v105, v89
	v_pk_fma_f32 v[78:79], v[50:51], v[102:103], v[78:79] op_sel:[1,0,0]
	v_cvt_f32_ubyte2_e32 v146, v89
	v_cvt_f32_ubyte3_e32 v147, v89
	v_pk_fma_f32 v[70:71], v[58:59], v[104:105], v[70:71] op_sel:[1,0,0]
	v_cvt_f32_ubyte0_e32 v98, v68
	v_cvt_f32_ubyte1_e32 v99, v68
	v_pk_fma_f32 v[62:63], v[58:59], v[146:147], v[62:63] op_sel:[1,0,0]
	v_cvt_f32_ubyte2_e32 v102, v68
	v_cvt_f32_ubyte3_e32 v103, v68
	v_pk_fma_f32 v[92:93], v[52:53], v[98:99], v[92:93] op_sel_hi:[0,1,1]
	v_cvt_f32_ubyte0_e32 v104, v69
	v_cvt_f32_ubyte1_e32 v105, v69
	v_pk_fma_f32 v[90:91], v[52:53], v[102:103], v[90:91] op_sel_hi:[0,1,1]
	v_cvt_f32_ubyte2_e32 v146, v69
	v_cvt_f32_ubyte3_e32 v147, v69
	v_pk_fma_f32 v[86:87], v[60:61], v[104:105], v[86:87] op_sel_hi:[0,1,1]
	v_cvt_f32_ubyte0_e32 v98, v76
	v_cvt_f32_ubyte1_e32 v99, v76
	v_pk_fma_f32 v[84:85], v[60:61], v[146:147], v[84:85] op_sel_hi:[0,1,1]
	v_and_b32_e32 v82, s0, v186
	v_and_b32_e32 v83, s1, v186
	v_and_b32_e32 v88, s0, v187
	v_and_b32_e32 v89, s1, v187
	v_cvt_f32_ubyte2_e32 v102, v76
	v_cvt_f32_ubyte3_e32 v103, v76
	v_pk_fma_f32 v[80:81], v[52:53], v[98:99], v[80:81] op_sel_hi:[0,1,1]
	v_cvt_f32_ubyte0_e32 v104, v77
	v_cvt_f32_ubyte1_e32 v105, v77
	v_pk_fma_f32 v[78:79], v[52:53], v[102:103], v[78:79] op_sel_hi:[0,1,1]
	v_cvt_f32_ubyte2_e32 v146, v77
	v_cvt_f32_ubyte3_e32 v147, v77
	v_pk_fma_f32 v[70:71], v[60:61], v[104:105], v[70:71] op_sel_hi:[0,1,1]
	v_cvt_f32_ubyte0_e32 v98, v82
	v_cvt_f32_ubyte1_e32 v99, v82
	v_pk_fma_f32 v[62:63], v[60:61], v[146:147], v[62:63] op_sel_hi:[0,1,1]
	v_cvt_f32_ubyte2_e32 v102, v82
	v_cvt_f32_ubyte3_e32 v103, v82
	v_pk_fma_f32 v[92:93], v[52:53], v[98:99], v[92:93] op_sel:[1,0,0]
	v_cvt_f32_ubyte0_e32 v104, v83
	v_cvt_f32_ubyte1_e32 v105, v83
	v_pk_fma_f32 v[90:91], v[52:53], v[102:103], v[90:91] op_sel:[1,0,0]
	v_cvt_f32_ubyte2_e32 v146, v83
	v_cvt_f32_ubyte3_e32 v147, v83
	v_pk_fma_f32 v[86:87], v[60:61], v[104:105], v[86:87] op_sel:[1,0,0]
	v_cvt_f32_ubyte0_e32 v98, v88
	v_cvt_f32_ubyte1_e32 v99, v88
	v_pk_fma_f32 v[84:85], v[60:61], v[146:147], v[84:85] op_sel:[1,0,0]
	v_and_b32_e32 v68, s0, v188
	v_and_b32_e32 v69, s1, v188
	v_and_b32_e32 v76, s0, v189
	v_and_b32_e32 v77, s1, v189
	v_cvt_f32_ubyte2_e32 v102, v88
	v_cvt_f32_ubyte3_e32 v103, v88
	v_pk_fma_f32 v[80:81], v[52:53], v[98:99], v[80:81] op_sel:[1,0,0]
	v_cvt_f32_ubyte0_e32 v104, v89
	v_cvt_f32_ubyte1_e32 v105, v89
	v_pk_fma_f32 v[78:79], v[52:53], v[102:103], v[78:79] op_sel:[1,0,0]
	v_cvt_f32_ubyte2_e32 v146, v89
	v_cvt_f32_ubyte3_e32 v147, v89
	v_pk_fma_f32 v[70:71], v[60:61], v[104:105], v[70:71] op_sel:[1,0,0]
	v_cvt_f32_ubyte0_e32 v98, v68
	v_cvt_f32_ubyte1_e32 v99, v68
	v_pk_fma_f32 v[62:63], v[60:61], v[146:147], v[62:63] op_sel:[1,0,0]
	v_cvt_f32_ubyte2_e32 v102, v68
	v_cvt_f32_ubyte3_e32 v103, v68
	v_pk_fma_f32 v[92:93], v[54:55], v[98:99], v[92:93] op_sel_hi:[0,1,1]
	v_cvt_f32_ubyte0_e32 v104, v69
	v_cvt_f32_ubyte1_e32 v105, v69
	v_pk_fma_f32 v[90:91], v[54:55], v[102:103], v[90:91] op_sel_hi:[0,1,1]
	v_cvt_f32_ubyte2_e32 v146, v69
	v_cvt_f32_ubyte3_e32 v147, v69
	v_pk_fma_f32 v[86:87], v[64:65], v[104:105], v[86:87] op_sel_hi:[0,1,1]
	v_cvt_f32_ubyte0_e32 v98, v76
	v_cvt_f32_ubyte1_e32 v99, v76
	v_pk_fma_f32 v[84:85], v[64:65], v[146:147], v[84:85] op_sel_hi:[0,1,1]
	v_and_b32_e32 v82, s0, v190
	v_and_b32_e32 v83, s1, v190
	v_and_b32_e32 v88, s0, v191
	v_and_b32_e32 v89, s1, v191
	v_cvt_f32_ubyte2_e32 v102, v76
	v_cvt_f32_ubyte3_e32 v103, v76
	v_pk_fma_f32 v[80:81], v[54:55], v[98:99], v[80:81] op_sel_hi:[0,1,1]
	v_cvt_f32_ubyte0_e32 v104, v77
	v_cvt_f32_ubyte1_e32 v105, v77
	v_pk_fma_f32 v[78:79], v[54:55], v[102:103], v[78:79] op_sel_hi:[0,1,1]
	v_cvt_f32_ubyte2_e32 v146, v77
	v_cvt_f32_ubyte3_e32 v147, v77
	v_pk_fma_f32 v[70:71], v[64:65], v[104:105], v[70:71] op_sel_hi:[0,1,1]
	v_cvt_f32_ubyte0_e32 v98, v82
	v_cvt_f32_ubyte1_e32 v99, v82
	v_pk_fma_f32 v[62:63], v[64:65], v[146:147], v[62:63] op_sel_hi:[0,1,1]
	v_cvt_f32_ubyte2_e32 v102, v82
	v_cvt_f32_ubyte3_e32 v103, v82
	v_pk_fma_f32 v[92:93], v[54:55], v[98:99], v[92:93] op_sel:[1,0,0]
	v_cvt_f32_ubyte0_e32 v104, v83
	v_cvt_f32_ubyte1_e32 v105, v83
	v_pk_fma_f32 v[90:91], v[54:55], v[102:103], v[90:91] op_sel:[1,0,0]
	v_cvt_f32_ubyte2_e32 v146, v83
	v_cvt_f32_ubyte3_e32 v147, v83
	v_pk_fma_f32 v[86:87], v[64:65], v[104:105], v[86:87] op_sel:[1,0,0]
	v_cvt_f32_ubyte0_e32 v98, v88
	v_cvt_f32_ubyte1_e32 v99, v88
	v_pk_fma_f32 v[84:85], v[64:65], v[146:147], v[84:85] op_sel:[1,0,0]
	v_and_b32_e32 v68, s0, v192
	v_and_b32_e32 v69, s1, v192
	v_and_b32_e32 v76, s0, v193
	v_and_b32_e32 v77, s1, v193
	v_cvt_f32_ubyte2_e32 v102, v88
	v_cvt_f32_ubyte3_e32 v103, v88
	v_pk_fma_f32 v[80:81], v[54:55], v[98:99], v[80:81] op_sel:[1,0,0]
	v_cvt_f32_ubyte0_e32 v104, v89
	v_cvt_f32_ubyte1_e32 v105, v89
	v_pk_fma_f32 v[78:79], v[54:55], v[102:103], v[78:79] op_sel:[1,0,0]
	v_cvt_f32_ubyte2_e32 v146, v89
	v_cvt_f32_ubyte3_e32 v147, v89
	v_pk_fma_f32 v[70:71], v[64:65], v[104:105], v[70:71] op_sel:[1,0,0]
	v_cvt_f32_ubyte0_e32 v98, v68
	v_cvt_f32_ubyte1_e32 v99, v68
	v_pk_fma_f32 v[62:63], v[64:65], v[146:147], v[62:63] op_sel:[1,0,0]
	v_cvt_f32_ubyte2_e32 v102, v68
	v_cvt_f32_ubyte3_e32 v103, v68
	v_pk_fma_f32 v[92:93], v[56:57], v[98:99], v[92:93] op_sel_hi:[0,1,1]
	v_cvt_f32_ubyte0_e32 v104, v69
	v_cvt_f32_ubyte1_e32 v105, v69
	v_pk_fma_f32 v[90:91], v[56:57], v[102:103], v[90:91] op_sel_hi:[0,1,1]
	v_cvt_f32_ubyte2_e32 v146, v69
	v_cvt_f32_ubyte3_e32 v147, v69
	v_pk_fma_f32 v[86:87], v[66:67], v[104:105], v[86:87] op_sel_hi:[0,1,1]
	v_cvt_f32_ubyte0_e32 v98, v76
	v_cvt_f32_ubyte1_e32 v99, v76
	v_pk_fma_f32 v[84:85], v[66:67], v[146:147], v[84:85] op_sel_hi:[0,1,1]
	v_and_b32_e32 v82, s0, v194
	v_and_b32_e32 v83, s1, v194
	v_and_b32_e32 v88, s0, v195
	v_and_b32_e32 v89, s1, v195
	v_cvt_f32_ubyte2_e32 v102, v76
	v_cvt_f32_ubyte3_e32 v103, v76
	v_pk_fma_f32 v[80:81], v[56:57], v[98:99], v[80:81] op_sel_hi:[0,1,1]
	v_cvt_f32_ubyte0_e32 v104, v77
	v_cvt_f32_ubyte1_e32 v105, v77
	v_pk_fma_f32 v[78:79], v[56:57], v[102:103], v[78:79] op_sel_hi:[0,1,1]
	v_cvt_f32_ubyte2_e32 v146, v77
	v_cvt_f32_ubyte3_e32 v147, v77
	v_pk_fma_f32 v[70:71], v[66:67], v[104:105], v[70:71] op_sel_hi:[0,1,1]
	v_cvt_f32_ubyte0_e32 v98, v82
	v_cvt_f32_ubyte1_e32 v99, v82
	v_pk_fma_f32 v[62:63], v[66:67], v[146:147], v[62:63] op_sel_hi:[0,1,1]
	v_cvt_f32_ubyte2_e32 v102, v82
	v_cvt_f32_ubyte3_e32 v103, v82
	v_pk_fma_f32 v[92:93], v[56:57], v[98:99], v[92:93] op_sel:[1,0,0]
	v_cvt_f32_ubyte0_e32 v104, v83
	v_cvt_f32_ubyte1_e32 v105, v83
	v_pk_fma_f32 v[90:91], v[56:57], v[102:103], v[90:91] op_sel:[1,0,0]
	v_cvt_f32_ubyte2_e32 v146, v83
	v_cvt_f32_ubyte3_e32 v147, v83
	v_pk_fma_f32 v[86:87], v[66:67], v[104:105], v[86:87] op_sel:[1,0,0]
	v_cvt_f32_ubyte0_e32 v98, v88
	v_cvt_f32_ubyte1_e32 v99, v88
	v_pk_fma_f32 v[84:85], v[66:67], v[146:147], v[84:85] op_sel:[1,0,0]
	v_cvt_f32_ubyte2_e32 v102, v88
	v_cvt_f32_ubyte3_e32 v103, v88
	v_pk_fma_f32 v[80:81], v[56:57], v[98:99], v[80:81] op_sel:[1,0,0]
	v_cvt_f32_ubyte0_e32 v104, v89
	v_cvt_f32_ubyte1_e32 v105, v89
	v_pk_fma_f32 v[78:79], v[56:57], v[102:103], v[78:79] op_sel:[1,0,0]
	v_cvt_f32_ubyte2_e32 v146, v89
	v_cvt_f32_ubyte3_e32 v147, v89
	v_pk_fma_f32 v[70:71], v[66:67], v[104:105], v[70:71] op_sel:[1,0,0]
	v_pk_fma_f32 v[62:63], v[66:67], v[146:147], v[62:63] op_sel:[1,0,0]
	s_waitcnt lgkmcnt(0)
	v_lshl_add_u32 v72, v72, 9, v100
	v_lshl_add_u32 v73, v73, 9, v100
	v_lshl_add_u32 v74, v74, 9, v100
	v_lshl_add_u32 v75, v75, 9, v100
	v_lshl_add_u32 v94, v94, 9, v100
	v_lshl_add_u32 v95, v95, 9, v100
	v_lshl_add_u32 v96, v96, 9, v100
	v_lshl_add_u32 v97, v97, 9, v100
	global_load_dwordx2 v[180:181], v72, s[38:39]
	global_load_dwordx2 v[182:183], v73, s[38:39]
	global_load_dwordx2 v[184:185], v74, s[38:39]
	global_load_dwordx2 v[186:187], v75, s[38:39]
	global_load_dwordx2 v[188:189], v94, s[38:39]
	global_load_dwordx2 v[190:191], v95, s[38:39]
	global_load_dwordx2 v[192:193], v96, s[38:39]
	global_load_dwordx2 v[194:195], v97, s[38:39]
	ds_read_b128 v[72:75], v1 offset:256
	ds_read_b128 v[94:97], v1 offset:272
	ds_read_b128 v[50:53], v1 offset:608
	ds_read_b128 v[54:57], v1 offset:624
	ds_read_b128 v[58:61], v1 offset:1632
	ds_read_b128 v[64:67], v1 offset:1648
	s_waitcnt vmcnt(40)
	v_and_b32_e32 v68, s0, v196
	v_and_b32_e32 v69, s1, v196
	v_and_b32_e32 v76, s0, v197
	v_and_b32_e32 v77, s1, v197
	v_cvt_f32_ubyte0_e32 v98, v68
	v_cvt_f32_ubyte1_e32 v99, v68
	v_cvt_f32_ubyte2_e32 v102, v68
	v_cvt_f32_ubyte3_e32 v103, v68
	v_pk_fma_f32 v[92:93], v[34:35], v[98:99], v[92:93] op_sel_hi:[0,1,1]
	v_cvt_f32_ubyte0_e32 v104, v69
	v_cvt_f32_ubyte1_e32 v105, v69
	v_pk_fma_f32 v[90:91], v[34:35], v[102:103], v[90:91] op_sel_hi:[0,1,1]
	v_cvt_f32_ubyte2_e32 v146, v69
	v_cvt_f32_ubyte3_e32 v147, v69
	v_pk_fma_f32 v[86:87], v[42:43], v[104:105], v[86:87] op_sel_hi:[0,1,1]
	v_cvt_f32_ubyte0_e32 v98, v76
	v_cvt_f32_ubyte1_e32 v99, v76
	v_pk_fma_f32 v[84:85], v[42:43], v[146:147], v[84:85] op_sel_hi:[0,1,1]
	v_and_b32_e32 v82, s0, v198
	v_and_b32_e32 v83, s1, v198
	v_and_b32_e32 v88, s0, v199
	v_and_b32_e32 v89, s1, v199
	v_cvt_f32_ubyte2_e32 v102, v76
	v_cvt_f32_ubyte3_e32 v103, v76
	v_pk_fma_f32 v[80:81], v[34:35], v[98:99], v[80:81] op_sel_hi:[0,1,1]
	v_cvt_f32_ubyte0_e32 v104, v77
	v_cvt_f32_ubyte1_e32 v105, v77
	v_pk_fma_f32 v[78:79], v[34:35], v[102:103], v[78:79] op_sel_hi:[0,1,1]
	v_cvt_f32_ubyte2_e32 v146, v77
	v_cvt_f32_ubyte3_e32 v147, v77
	v_pk_fma_f32 v[70:71], v[42:43], v[104:105], v[70:71] op_sel_hi:[0,1,1]
	v_cvt_f32_ubyte0_e32 v98, v82
	v_cvt_f32_ubyte1_e32 v99, v82
	v_pk_fma_f32 v[62:63], v[42:43], v[146:147], v[62:63] op_sel_hi:[0,1,1]
	v_cvt_f32_ubyte2_e32 v102, v82
	v_cvt_f32_ubyte3_e32 v103, v82
	v_pk_fma_f32 v[92:93], v[34:35], v[98:99], v[92:93] op_sel:[1,0,0]
	v_cvt_f32_ubyte0_e32 v104, v83
	v_cvt_f32_ubyte1_e32 v105, v83
	v_pk_fma_f32 v[90:91], v[34:35], v[102:103], v[90:91] op_sel:[1,0,0]
	v_cvt_f32_ubyte2_e32 v146, v83
	v_cvt_f32_ubyte3_e32 v147, v83
	v_pk_fma_f32 v[86:87], v[42:43], v[104:105], v[86:87] op_sel:[1,0,0]
	v_cvt_f32_ubyte0_e32 v98, v88
	v_cvt_f32_ubyte1_e32 v99, v88
	v_pk_fma_f32 v[84:85], v[42:43], v[146:147], v[84:85] op_sel:[1,0,0]
	v_and_b32_e32 v68, s0, v200
	v_and_b32_e32 v69, s1, v200
	v_and_b32_e32 v76, s0, v201
	v_and_b32_e32 v77, s1, v201
	v_cvt_f32_ubyte2_e32 v102, v88
	v_cvt_f32_ubyte3_e32 v103, v88
	v_pk_fma_f32 v[80:81], v[34:35], v[98:99], v[80:81] op_sel:[1,0,0]
	v_cvt_f32_ubyte0_e32 v104, v89
	v_cvt_f32_ubyte1_e32 v105, v89
	v_pk_fma_f32 v[78:79], v[34:35], v[102:103], v[78:79] op_sel:[1,0,0]
	v_cvt_f32_ubyte2_e32 v146, v89
	v_cvt_f32_ubyte3_e32 v147, v89
	v_pk_fma_f32 v[70:71], v[42:43], v[104:105], v[70:71] op_sel:[1,0,0]
	v_cvt_f32_ubyte0_e32 v98, v68
	v_cvt_f32_ubyte1_e32 v99, v68
	v_pk_fma_f32 v[62:63], v[42:43], v[146:147], v[62:63] op_sel:[1,0,0]
	v_cvt_f32_ubyte2_e32 v102, v68
	v_cvt_f32_ubyte3_e32 v103, v68
	v_pk_fma_f32 v[92:93], v[36:37], v[98:99], v[92:93] op_sel_hi:[0,1,1]
	v_cvt_f32_ubyte0_e32 v104, v69
	v_cvt_f32_ubyte1_e32 v105, v69
	v_pk_fma_f32 v[90:91], v[36:37], v[102:103], v[90:91] op_sel_hi:[0,1,1]
	v_cvt_f32_ubyte2_e32 v146, v69
	v_cvt_f32_ubyte3_e32 v147, v69
	v_pk_fma_f32 v[86:87], v[44:45], v[104:105], v[86:87] op_sel_hi:[0,1,1]
	v_cvt_f32_ubyte0_e32 v98, v76
	v_cvt_f32_ubyte1_e32 v99, v76
	v_pk_fma_f32 v[84:85], v[44:45], v[146:147], v[84:85] op_sel_hi:[0,1,1]
	v_and_b32_e32 v82, s0, v202
	v_and_b32_e32 v83, s1, v202
	v_and_b32_e32 v88, s0, v203
	v_and_b32_e32 v89, s1, v203
	v_cvt_f32_ubyte2_e32 v102, v76
	v_cvt_f32_ubyte3_e32 v103, v76
	v_pk_fma_f32 v[80:81], v[36:37], v[98:99], v[80:81] op_sel_hi:[0,1,1]
	v_cvt_f32_ubyte0_e32 v104, v77
	v_cvt_f32_ubyte1_e32 v105, v77
	v_pk_fma_f32 v[78:79], v[36:37], v[102:103], v[78:79] op_sel_hi:[0,1,1]
	v_cvt_f32_ubyte2_e32 v146, v77
	v_cvt_f32_ubyte3_e32 v147, v77
	v_pk_fma_f32 v[70:71], v[44:45], v[104:105], v[70:71] op_sel_hi:[0,1,1]
	v_cvt_f32_ubyte0_e32 v98, v82
	v_cvt_f32_ubyte1_e32 v99, v82
	v_pk_fma_f32 v[62:63], v[44:45], v[146:147], v[62:63] op_sel_hi:[0,1,1]
	v_cvt_f32_ubyte2_e32 v102, v82
	v_cvt_f32_ubyte3_e32 v103, v82
	v_pk_fma_f32 v[92:93], v[36:37], v[98:99], v[92:93] op_sel:[1,0,0]
	v_cvt_f32_ubyte0_e32 v104, v83
	v_cvt_f32_ubyte1_e32 v105, v83
	v_pk_fma_f32 v[90:91], v[36:37], v[102:103], v[90:91] op_sel:[1,0,0]
	v_cvt_f32_ubyte2_e32 v146, v83
	v_cvt_f32_ubyte3_e32 v147, v83
	v_pk_fma_f32 v[86:87], v[44:45], v[104:105], v[86:87] op_sel:[1,0,0]
	v_cvt_f32_ubyte0_e32 v98, v88
	v_cvt_f32_ubyte1_e32 v99, v88
	v_pk_fma_f32 v[84:85], v[44:45], v[146:147], v[84:85] op_sel:[1,0,0]
	v_and_b32_e32 v68, s0, v204
	v_and_b32_e32 v69, s1, v204
	v_and_b32_e32 v76, s0, v205
	v_and_b32_e32 v77, s1, v205
	v_cvt_f32_ubyte2_e32 v102, v88
	v_cvt_f32_ubyte3_e32 v103, v88
	v_pk_fma_f32 v[80:81], v[36:37], v[98:99], v[80:81] op_sel:[1,0,0]
	v_cvt_f32_ubyte0_e32 v104, v89
	v_cvt_f32_ubyte1_e32 v105, v89
	v_pk_fma_f32 v[78:79], v[36:37], v[102:103], v[78:79] op_sel:[1,0,0]
	v_cvt_f32_ubyte2_e32 v146, v89
	v_cvt_f32_ubyte3_e32 v147, v89
	v_pk_fma_f32 v[70:71], v[44:45], v[104:105], v[70:71] op_sel:[1,0,0]
	v_cvt_f32_ubyte0_e32 v98, v68
	v_cvt_f32_ubyte1_e32 v99, v68
	v_pk_fma_f32 v[62:63], v[44:45], v[146:147], v[62:63] op_sel:[1,0,0]
	v_cvt_f32_ubyte2_e32 v102, v68
	v_cvt_f32_ubyte3_e32 v103, v68
	v_pk_fma_f32 v[92:93], v[38:39], v[98:99], v[92:93] op_sel_hi:[0,1,1]
	v_cvt_f32_ubyte0_e32 v104, v69
	v_cvt_f32_ubyte1_e32 v105, v69
	v_pk_fma_f32 v[90:91], v[38:39], v[102:103], v[90:91] op_sel_hi:[0,1,1]
	v_cvt_f32_ubyte2_e32 v146, v69
	v_cvt_f32_ubyte3_e32 v147, v69
	v_pk_fma_f32 v[86:87], v[46:47], v[104:105], v[86:87] op_sel_hi:[0,1,1]
	v_cvt_f32_ubyte0_e32 v98, v76
	v_cvt_f32_ubyte1_e32 v99, v76
	v_pk_fma_f32 v[84:85], v[46:47], v[146:147], v[84:85] op_sel_hi:[0,1,1]
	v_and_b32_e32 v82, s0, v206
	v_and_b32_e32 v83, s1, v206
	v_and_b32_e32 v88, s0, v207
	v_and_b32_e32 v89, s1, v207
	v_cvt_f32_ubyte2_e32 v102, v76
	v_cvt_f32_ubyte3_e32 v103, v76
	v_pk_fma_f32 v[80:81], v[38:39], v[98:99], v[80:81] op_sel_hi:[0,1,1]
	v_cvt_f32_ubyte0_e32 v104, v77
	v_cvt_f32_ubyte1_e32 v105, v77
	v_pk_fma_f32 v[78:79], v[38:39], v[102:103], v[78:79] op_sel_hi:[0,1,1]
	v_cvt_f32_ubyte2_e32 v146, v77
	v_cvt_f32_ubyte3_e32 v147, v77
	v_pk_fma_f32 v[70:71], v[46:47], v[104:105], v[70:71] op_sel_hi:[0,1,1]
	v_cvt_f32_ubyte0_e32 v98, v82
	v_cvt_f32_ubyte1_e32 v99, v82
	v_pk_fma_f32 v[62:63], v[46:47], v[146:147], v[62:63] op_sel_hi:[0,1,1]
	v_cvt_f32_ubyte2_e32 v102, v82
	v_cvt_f32_ubyte3_e32 v103, v82
	v_pk_fma_f32 v[92:93], v[38:39], v[98:99], v[92:93] op_sel:[1,0,0]
	v_cvt_f32_ubyte0_e32 v104, v83
	v_cvt_f32_ubyte1_e32 v105, v83
	v_pk_fma_f32 v[90:91], v[38:39], v[102:103], v[90:91] op_sel:[1,0,0]
	v_cvt_f32_ubyte2_e32 v146, v83
	v_cvt_f32_ubyte3_e32 v147, v83
	v_pk_fma_f32 v[86:87], v[46:47], v[104:105], v[86:87] op_sel:[1,0,0]
	v_cvt_f32_ubyte0_e32 v98, v88
	v_cvt_f32_ubyte1_e32 v99, v88
	v_pk_fma_f32 v[84:85], v[46:47], v[146:147], v[84:85] op_sel:[1,0,0]
	v_and_b32_e32 v68, s0, v208
	v_and_b32_e32 v69, s1, v208
	v_and_b32_e32 v76, s0, v209
	v_and_b32_e32 v77, s1, v209
	v_cvt_f32_ubyte2_e32 v102, v88
	v_cvt_f32_ubyte3_e32 v103, v88
	v_pk_fma_f32 v[80:81], v[38:39], v[98:99], v[80:81] op_sel:[1,0,0]
	v_cvt_f32_ubyte0_e32 v104, v89
	v_cvt_f32_ubyte1_e32 v105, v89
	v_pk_fma_f32 v[78:79], v[38:39], v[102:103], v[78:79] op_sel:[1,0,0]
	v_cvt_f32_ubyte2_e32 v146, v89
	v_cvt_f32_ubyte3_e32 v147, v89
	v_pk_fma_f32 v[70:71], v[46:47], v[104:105], v[70:71] op_sel:[1,0,0]
	v_cvt_f32_ubyte0_e32 v98, v68
	v_cvt_f32_ubyte1_e32 v99, v68
	v_pk_fma_f32 v[62:63], v[46:47], v[146:147], v[62:63] op_sel:[1,0,0]
	v_cvt_f32_ubyte2_e32 v102, v68
	v_cvt_f32_ubyte3_e32 v103, v68
	v_pk_fma_f32 v[92:93], v[40:41], v[98:99], v[92:93] op_sel_hi:[0,1,1]
	v_cvt_f32_ubyte0_e32 v104, v69
	v_cvt_f32_ubyte1_e32 v105, v69
	v_pk_fma_f32 v[90:91], v[40:41], v[102:103], v[90:91] op_sel_hi:[0,1,1]
	v_cvt_f32_ubyte2_e32 v146, v69
	v_cvt_f32_ubyte3_e32 v147, v69
	v_pk_fma_f32 v[86:87], v[48:49], v[104:105], v[86:87] op_sel_hi:[0,1,1]
	v_cvt_f32_ubyte0_e32 v98, v76
	v_cvt_f32_ubyte1_e32 v99, v76
	v_pk_fma_f32 v[84:85], v[48:49], v[146:147], v[84:85] op_sel_hi:[0,1,1]
	v_and_b32_e32 v82, s0, v210
	v_and_b32_e32 v83, s1, v210
	v_and_b32_e32 v88, s0, v211
	v_and_b32_e32 v89, s1, v211
	v_cvt_f32_ubyte2_e32 v102, v76
	v_cvt_f32_ubyte3_e32 v103, v76
	v_pk_fma_f32 v[80:81], v[40:41], v[98:99], v[80:81] op_sel_hi:[0,1,1]
	v_cvt_f32_ubyte0_e32 v104, v77
	v_cvt_f32_ubyte1_e32 v105, v77
	v_pk_fma_f32 v[78:79], v[40:41], v[102:103], v[78:79] op_sel_hi:[0,1,1]
	v_cvt_f32_ubyte2_e32 v146, v77
	v_cvt_f32_ubyte3_e32 v147, v77
	v_pk_fma_f32 v[70:71], v[48:49], v[104:105], v[70:71] op_sel_hi:[0,1,1]
	v_cvt_f32_ubyte0_e32 v98, v82
	v_cvt_f32_ubyte1_e32 v99, v82
	v_pk_fma_f32 v[62:63], v[48:49], v[146:147], v[62:63] op_sel_hi:[0,1,1]
	v_cvt_f32_ubyte2_e32 v102, v82
	v_cvt_f32_ubyte3_e32 v103, v82
	v_pk_fma_f32 v[92:93], v[40:41], v[98:99], v[92:93] op_sel:[1,0,0]
	v_cvt_f32_ubyte0_e32 v104, v83
	v_cvt_f32_ubyte1_e32 v105, v83
	v_pk_fma_f32 v[90:91], v[40:41], v[102:103], v[90:91] op_sel:[1,0,0]
	v_cvt_f32_ubyte2_e32 v146, v83
	v_cvt_f32_ubyte3_e32 v147, v83
	v_pk_fma_f32 v[86:87], v[48:49], v[104:105], v[86:87] op_sel:[1,0,0]
	v_cvt_f32_ubyte0_e32 v98, v88
	v_cvt_f32_ubyte1_e32 v99, v88
	v_pk_fma_f32 v[84:85], v[48:49], v[146:147], v[84:85] op_sel:[1,0,0]
	v_cvt_f32_ubyte2_e32 v102, v88
	v_cvt_f32_ubyte3_e32 v103, v88
	v_pk_fma_f32 v[80:81], v[40:41], v[98:99], v[80:81] op_sel:[1,0,0]
	v_cvt_f32_ubyte0_e32 v104, v89
	v_cvt_f32_ubyte1_e32 v105, v89
	v_pk_fma_f32 v[78:79], v[40:41], v[102:103], v[78:79] op_sel:[1,0,0]
	v_cvt_f32_ubyte2_e32 v146, v89
	v_cvt_f32_ubyte3_e32 v147, v89
	v_pk_fma_f32 v[70:71], v[48:49], v[104:105], v[70:71] op_sel:[1,0,0]
	v_pk_fma_f32 v[62:63], v[48:49], v[146:147], v[62:63] op_sel:[1,0,0]
	s_waitcnt lgkmcnt(0)
	v_lshl_add_u32 v72, v72, 9, v100
	v_lshl_add_u32 v73, v73, 9, v100
	v_lshl_add_u32 v74, v74, 9, v100
	v_lshl_add_u32 v75, v75, 9, v100
	v_lshl_add_u32 v94, v94, 9, v100
	v_lshl_add_u32 v95, v95, 9, v100
	v_lshl_add_u32 v96, v96, 9, v100
	v_lshl_add_u32 v97, v97, 9, v100
	global_load_dwordx2 v[196:197], v72, s[38:39]
	global_load_dwordx2 v[198:199], v73, s[38:39]
	global_load_dwordx2 v[200:201], v74, s[38:39]
	global_load_dwordx2 v[202:203], v75, s[38:39]
	global_load_dwordx2 v[204:205], v94, s[38:39]
	global_load_dwordx2 v[206:207], v95, s[38:39]
	global_load_dwordx2 v[208:209], v96, s[38:39]
	global_load_dwordx2 v[210:211], v97, s[38:39]
	ds_read_b128 v[72:75], v1 offset:288
	ds_read_b128 v[94:97], v1 offset:304
	ds_read_b128 v[34:37], v1 offset:640
	ds_read_b128 v[38:41], v1 offset:656
	ds_read_b128 v[42:45], v1 offset:1664
	ds_read_b128 v[46:49], v1 offset:1680
	s_waitcnt vmcnt(40)
	v_and_b32_e32 v68, s0, v212
	v_and_b32_e32 v69, s1, v212
	v_and_b32_e32 v76, s0, v213
	v_and_b32_e32 v77, s1, v213
	v_cvt_f32_ubyte0_e32 v98, v68
	v_cvt_f32_ubyte1_e32 v99, v68
	v_cvt_f32_ubyte2_e32 v102, v68
	v_cvt_f32_ubyte3_e32 v103, v68
	v_pk_fma_f32 v[92:93], v[50:51], v[98:99], v[92:93] op_sel_hi:[0,1,1]
	v_cvt_f32_ubyte0_e32 v104, v69
	v_cvt_f32_ubyte1_e32 v105, v69
	v_pk_fma_f32 v[90:91], v[50:51], v[102:103], v[90:91] op_sel_hi:[0,1,1]
	v_cvt_f32_ubyte2_e32 v146, v69
	v_cvt_f32_ubyte3_e32 v147, v69
	v_pk_fma_f32 v[86:87], v[58:59], v[104:105], v[86:87] op_sel_hi:[0,1,1]
	v_cvt_f32_ubyte0_e32 v98, v76
	v_cvt_f32_ubyte1_e32 v99, v76
	v_pk_fma_f32 v[84:85], v[58:59], v[146:147], v[84:85] op_sel_hi:[0,1,1]
	v_and_b32_e32 v82, s0, v214
	v_and_b32_e32 v83, s1, v214
	v_and_b32_e32 v88, s0, v215
	v_and_b32_e32 v89, s1, v215
	v_cvt_f32_ubyte2_e32 v102, v76
	v_cvt_f32_ubyte3_e32 v103, v76
	v_pk_fma_f32 v[80:81], v[50:51], v[98:99], v[80:81] op_sel_hi:[0,1,1]
	v_cvt_f32_ubyte0_e32 v104, v77
	v_cvt_f32_ubyte1_e32 v105, v77
	v_pk_fma_f32 v[78:79], v[50:51], v[102:103], v[78:79] op_sel_hi:[0,1,1]
	v_cvt_f32_ubyte2_e32 v146, v77
	v_cvt_f32_ubyte3_e32 v147, v77
	v_pk_fma_f32 v[70:71], v[58:59], v[104:105], v[70:71] op_sel_hi:[0,1,1]
	v_cvt_f32_ubyte0_e32 v98, v82
	v_cvt_f32_ubyte1_e32 v99, v82
	v_pk_fma_f32 v[62:63], v[58:59], v[146:147], v[62:63] op_sel_hi:[0,1,1]
	v_cvt_f32_ubyte2_e32 v102, v82
	v_cvt_f32_ubyte3_e32 v103, v82
	v_pk_fma_f32 v[92:93], v[50:51], v[98:99], v[92:93] op_sel:[1,0,0]
	v_cvt_f32_ubyte0_e32 v104, v83
	v_cvt_f32_ubyte1_e32 v105, v83
	v_pk_fma_f32 v[90:91], v[50:51], v[102:103], v[90:91] op_sel:[1,0,0]
	v_cvt_f32_ubyte2_e32 v146, v83
	v_cvt_f32_ubyte3_e32 v147, v83
	v_pk_fma_f32 v[86:87], v[58:59], v[104:105], v[86:87] op_sel:[1,0,0]
	v_cvt_f32_ubyte0_e32 v98, v88
	v_cvt_f32_ubyte1_e32 v99, v88
	v_pk_fma_f32 v[84:85], v[58:59], v[146:147], v[84:85] op_sel:[1,0,0]
	v_and_b32_e32 v68, s0, v216
	v_and_b32_e32 v69, s1, v216
	v_and_b32_e32 v76, s0, v217
	v_and_b32_e32 v77, s1, v217
	v_cvt_f32_ubyte2_e32 v102, v88
	v_cvt_f32_ubyte3_e32 v103, v88
	v_pk_fma_f32 v[80:81], v[50:51], v[98:99], v[80:81] op_sel:[1,0,0]
	v_cvt_f32_ubyte0_e32 v104, v89
	v_cvt_f32_ubyte1_e32 v105, v89
	v_pk_fma_f32 v[78:79], v[50:51], v[102:103], v[78:79] op_sel:[1,0,0]
	v_cvt_f32_ubyte2_e32 v146, v89
	v_cvt_f32_ubyte3_e32 v147, v89
	v_pk_fma_f32 v[70:71], v[58:59], v[104:105], v[70:71] op_sel:[1,0,0]
	v_cvt_f32_ubyte0_e32 v98, v68
	v_cvt_f32_ubyte1_e32 v99, v68
	v_pk_fma_f32 v[62:63], v[58:59], v[146:147], v[62:63] op_sel:[1,0,0]
	v_cvt_f32_ubyte2_e32 v102, v68
	v_cvt_f32_ubyte3_e32 v103, v68
	v_pk_fma_f32 v[92:93], v[52:53], v[98:99], v[92:93] op_sel_hi:[0,1,1]
	v_cvt_f32_ubyte0_e32 v104, v69
	v_cvt_f32_ubyte1_e32 v105, v69
	v_pk_fma_f32 v[90:91], v[52:53], v[102:103], v[90:91] op_sel_hi:[0,1,1]
	v_cvt_f32_ubyte2_e32 v146, v69
	v_cvt_f32_ubyte3_e32 v147, v69
	v_pk_fma_f32 v[86:87], v[60:61], v[104:105], v[86:87] op_sel_hi:[0,1,1]
	v_cvt_f32_ubyte0_e32 v98, v76
	v_cvt_f32_ubyte1_e32 v99, v76
	v_pk_fma_f32 v[84:85], v[60:61], v[146:147], v[84:85] op_sel_hi:[0,1,1]
	v_and_b32_e32 v82, s0, v218
	v_and_b32_e32 v83, s1, v218
	v_and_b32_e32 v88, s0, v219
	v_and_b32_e32 v89, s1, v219
	v_cvt_f32_ubyte2_e32 v102, v76
	v_cvt_f32_ubyte3_e32 v103, v76
	v_pk_fma_f32 v[80:81], v[52:53], v[98:99], v[80:81] op_sel_hi:[0,1,1]
	v_cvt_f32_ubyte0_e32 v104, v77
	v_cvt_f32_ubyte1_e32 v105, v77
	v_pk_fma_f32 v[78:79], v[52:53], v[102:103], v[78:79] op_sel_hi:[0,1,1]
	v_cvt_f32_ubyte2_e32 v146, v77
	v_cvt_f32_ubyte3_e32 v147, v77
	v_pk_fma_f32 v[70:71], v[60:61], v[104:105], v[70:71] op_sel_hi:[0,1,1]
	v_cvt_f32_ubyte0_e32 v98, v82
	v_cvt_f32_ubyte1_e32 v99, v82
	v_pk_fma_f32 v[62:63], v[60:61], v[146:147], v[62:63] op_sel_hi:[0,1,1]
	v_cvt_f32_ubyte2_e32 v102, v82
	v_cvt_f32_ubyte3_e32 v103, v82
	v_pk_fma_f32 v[92:93], v[52:53], v[98:99], v[92:93] op_sel:[1,0,0]
	v_cvt_f32_ubyte0_e32 v104, v83
	v_cvt_f32_ubyte1_e32 v105, v83
	v_pk_fma_f32 v[90:91], v[52:53], v[102:103], v[90:91] op_sel:[1,0,0]
	v_cvt_f32_ubyte2_e32 v146, v83
	v_cvt_f32_ubyte3_e32 v147, v83
	v_pk_fma_f32 v[86:87], v[60:61], v[104:105], v[86:87] op_sel:[1,0,0]
	v_cvt_f32_ubyte0_e32 v98, v88
	v_cvt_f32_ubyte1_e32 v99, v88
	v_pk_fma_f32 v[84:85], v[60:61], v[146:147], v[84:85] op_sel:[1,0,0]
	v_and_b32_e32 v68, s0, v220
	v_and_b32_e32 v69, s1, v220
	v_and_b32_e32 v76, s0, v221
	v_and_b32_e32 v77, s1, v221
	v_cvt_f32_ubyte2_e32 v102, v88
	v_cvt_f32_ubyte3_e32 v103, v88
	v_pk_fma_f32 v[80:81], v[52:53], v[98:99], v[80:81] op_sel:[1,0,0]
	v_cvt_f32_ubyte0_e32 v104, v89
	v_cvt_f32_ubyte1_e32 v105, v89
	v_pk_fma_f32 v[78:79], v[52:53], v[102:103], v[78:79] op_sel:[1,0,0]
	v_cvt_f32_ubyte2_e32 v146, v89
	v_cvt_f32_ubyte3_e32 v147, v89
	v_pk_fma_f32 v[70:71], v[60:61], v[104:105], v[70:71] op_sel:[1,0,0]
	v_cvt_f32_ubyte0_e32 v98, v68
	v_cvt_f32_ubyte1_e32 v99, v68
	v_pk_fma_f32 v[62:63], v[60:61], v[146:147], v[62:63] op_sel:[1,0,0]
	v_cvt_f32_ubyte2_e32 v102, v68
	v_cvt_f32_ubyte3_e32 v103, v68
	v_pk_fma_f32 v[92:93], v[54:55], v[98:99], v[92:93] op_sel_hi:[0,1,1]
	v_cvt_f32_ubyte0_e32 v104, v69
	v_cvt_f32_ubyte1_e32 v105, v69
	v_pk_fma_f32 v[90:91], v[54:55], v[102:103], v[90:91] op_sel_hi:[0,1,1]
	v_cvt_f32_ubyte2_e32 v146, v69
	v_cvt_f32_ubyte3_e32 v147, v69
	v_pk_fma_f32 v[86:87], v[64:65], v[104:105], v[86:87] op_sel_hi:[0,1,1]
	v_cvt_f32_ubyte0_e32 v98, v76
	v_cvt_f32_ubyte1_e32 v99, v76
	v_pk_fma_f32 v[84:85], v[64:65], v[146:147], v[84:85] op_sel_hi:[0,1,1]
	v_and_b32_e32 v82, s0, v222
	v_and_b32_e32 v83, s1, v222
	v_and_b32_e32 v88, s0, v223
	v_and_b32_e32 v89, s1, v223
	v_cvt_f32_ubyte2_e32 v102, v76
	v_cvt_f32_ubyte3_e32 v103, v76
	v_pk_fma_f32 v[80:81], v[54:55], v[98:99], v[80:81] op_sel_hi:[0,1,1]
	v_cvt_f32_ubyte0_e32 v104, v77
	v_cvt_f32_ubyte1_e32 v105, v77
	v_pk_fma_f32 v[78:79], v[54:55], v[102:103], v[78:79] op_sel_hi:[0,1,1]
	v_cvt_f32_ubyte2_e32 v146, v77
	v_cvt_f32_ubyte3_e32 v147, v77
	v_pk_fma_f32 v[70:71], v[64:65], v[104:105], v[70:71] op_sel_hi:[0,1,1]
	v_cvt_f32_ubyte0_e32 v98, v82
	v_cvt_f32_ubyte1_e32 v99, v82
	v_pk_fma_f32 v[62:63], v[64:65], v[146:147], v[62:63] op_sel_hi:[0,1,1]
	v_cvt_f32_ubyte2_e32 v102, v82
	v_cvt_f32_ubyte3_e32 v103, v82
	v_pk_fma_f32 v[92:93], v[54:55], v[98:99], v[92:93] op_sel:[1,0,0]
	v_cvt_f32_ubyte0_e32 v104, v83
	v_cvt_f32_ubyte1_e32 v105, v83
	v_pk_fma_f32 v[90:91], v[54:55], v[102:103], v[90:91] op_sel:[1,0,0]
	v_cvt_f32_ubyte2_e32 v146, v83
	v_cvt_f32_ubyte3_e32 v147, v83
	v_pk_fma_f32 v[86:87], v[64:65], v[104:105], v[86:87] op_sel:[1,0,0]
	v_cvt_f32_ubyte0_e32 v98, v88
	v_cvt_f32_ubyte1_e32 v99, v88
	v_pk_fma_f32 v[84:85], v[64:65], v[146:147], v[84:85] op_sel:[1,0,0]
	v_and_b32_e32 v68, s0, v224
	v_and_b32_e32 v69, s1, v224
	v_and_b32_e32 v76, s0, v225
	v_and_b32_e32 v77, s1, v225
	v_cvt_f32_ubyte2_e32 v102, v88
	v_cvt_f32_ubyte3_e32 v103, v88
	v_pk_fma_f32 v[80:81], v[54:55], v[98:99], v[80:81] op_sel:[1,0,0]
	v_cvt_f32_ubyte0_e32 v104, v89
	v_cvt_f32_ubyte1_e32 v105, v89
	v_pk_fma_f32 v[78:79], v[54:55], v[102:103], v[78:79] op_sel:[1,0,0]
	v_cvt_f32_ubyte2_e32 v146, v89
	v_cvt_f32_ubyte3_e32 v147, v89
	v_pk_fma_f32 v[70:71], v[64:65], v[104:105], v[70:71] op_sel:[1,0,0]
	v_cvt_f32_ubyte0_e32 v98, v68
	v_cvt_f32_ubyte1_e32 v99, v68
	v_pk_fma_f32 v[62:63], v[64:65], v[146:147], v[62:63] op_sel:[1,0,0]
	v_cvt_f32_ubyte2_e32 v102, v68
	v_cvt_f32_ubyte3_e32 v103, v68
	v_pk_fma_f32 v[92:93], v[56:57], v[98:99], v[92:93] op_sel_hi:[0,1,1]
	v_cvt_f32_ubyte0_e32 v104, v69
	v_cvt_f32_ubyte1_e32 v105, v69
	v_pk_fma_f32 v[90:91], v[56:57], v[102:103], v[90:91] op_sel_hi:[0,1,1]
	v_cvt_f32_ubyte2_e32 v146, v69
	v_cvt_f32_ubyte3_e32 v147, v69
	v_pk_fma_f32 v[86:87], v[66:67], v[104:105], v[86:87] op_sel_hi:[0,1,1]
	v_cvt_f32_ubyte0_e32 v98, v76
	v_cvt_f32_ubyte1_e32 v99, v76
	v_pk_fma_f32 v[84:85], v[66:67], v[146:147], v[84:85] op_sel_hi:[0,1,1]
	v_and_b32_e32 v82, s0, v226
	v_and_b32_e32 v83, s1, v226
	v_and_b32_e32 v88, s0, v227
	v_and_b32_e32 v89, s1, v227
	v_cvt_f32_ubyte2_e32 v102, v76
	v_cvt_f32_ubyte3_e32 v103, v76
	v_pk_fma_f32 v[80:81], v[56:57], v[98:99], v[80:81] op_sel_hi:[0,1,1]
	v_cvt_f32_ubyte0_e32 v104, v77
	v_cvt_f32_ubyte1_e32 v105, v77
	v_pk_fma_f32 v[78:79], v[56:57], v[102:103], v[78:79] op_sel_hi:[0,1,1]
	v_cvt_f32_ubyte2_e32 v146, v77
	v_cvt_f32_ubyte3_e32 v147, v77
	v_pk_fma_f32 v[70:71], v[66:67], v[104:105], v[70:71] op_sel_hi:[0,1,1]
	v_cvt_f32_ubyte0_e32 v98, v82
	v_cvt_f32_ubyte1_e32 v99, v82
	v_pk_fma_f32 v[62:63], v[66:67], v[146:147], v[62:63] op_sel_hi:[0,1,1]
	v_cvt_f32_ubyte2_e32 v102, v82
	v_cvt_f32_ubyte3_e32 v103, v82
	v_pk_fma_f32 v[92:93], v[56:57], v[98:99], v[92:93] op_sel:[1,0,0]
	v_cvt_f32_ubyte0_e32 v104, v83
	v_cvt_f32_ubyte1_e32 v105, v83
	v_pk_fma_f32 v[90:91], v[56:57], v[102:103], v[90:91] op_sel:[1,0,0]
	v_cvt_f32_ubyte2_e32 v146, v83
	v_cvt_f32_ubyte3_e32 v147, v83
	v_pk_fma_f32 v[86:87], v[66:67], v[104:105], v[86:87] op_sel:[1,0,0]
	v_cvt_f32_ubyte0_e32 v98, v88
	v_cvt_f32_ubyte1_e32 v99, v88
	v_pk_fma_f32 v[84:85], v[66:67], v[146:147], v[84:85] op_sel:[1,0,0]
	v_cvt_f32_ubyte2_e32 v102, v88
	v_cvt_f32_ubyte3_e32 v103, v88
	v_pk_fma_f32 v[80:81], v[56:57], v[98:99], v[80:81] op_sel:[1,0,0]
	v_cvt_f32_ubyte0_e32 v104, v89
	v_cvt_f32_ubyte1_e32 v105, v89
	v_pk_fma_f32 v[78:79], v[56:57], v[102:103], v[78:79] op_sel:[1,0,0]
	v_cvt_f32_ubyte2_e32 v146, v89
	v_cvt_f32_ubyte3_e32 v147, v89
	v_pk_fma_f32 v[70:71], v[66:67], v[104:105], v[70:71] op_sel:[1,0,0]
	v_pk_fma_f32 v[62:63], v[66:67], v[146:147], v[62:63] op_sel:[1,0,0]
	s_waitcnt lgkmcnt(0)
	v_lshl_add_u32 v72, v72, 9, v100
	v_lshl_add_u32 v73, v73, 9, v100
	v_lshl_add_u32 v74, v74, 9, v100
	v_lshl_add_u32 v75, v75, 9, v100
	v_lshl_add_u32 v94, v94, 9, v100
	v_lshl_add_u32 v95, v95, 9, v100
	v_lshl_add_u32 v96, v96, 9, v100
	v_lshl_add_u32 v97, v97, 9, v100
	global_load_dwordx2 v[212:213], v72, s[38:39]
	global_load_dwordx2 v[214:215], v73, s[38:39]
	global_load_dwordx2 v[216:217], v74, s[38:39]
	global_load_dwordx2 v[218:219], v75, s[38:39]
	global_load_dwordx2 v[220:221], v94, s[38:39]
	global_load_dwordx2 v[222:223], v95, s[38:39]
	global_load_dwordx2 v[224:225], v96, s[38:39]
	global_load_dwordx2 v[226:227], v97, s[38:39]
	ds_read_b128 v[72:75], v1 offset:320
	ds_read_b128 v[94:97], v1 offset:336
	ds_read_b128 v[50:53], v1 offset:672
	ds_read_b128 v[54:57], v1 offset:688
	ds_read_b128 v[58:61], v1 offset:1696
	ds_read_b128 v[64:67], v1 offset:1712
	s_waitcnt vmcnt(40)
	v_and_b32_e32 v68, s0, v2
	v_and_b32_e32 v69, s1, v2
	v_and_b32_e32 v76, s0, v3
	v_and_b32_e32 v77, s1, v3
	v_cvt_f32_ubyte0_e32 v98, v68
	v_cvt_f32_ubyte1_e32 v99, v68
	v_cvt_f32_ubyte2_e32 v102, v68
	v_cvt_f32_ubyte3_e32 v103, v68
	v_pk_fma_f32 v[92:93], v[34:35], v[98:99], v[92:93] op_sel_hi:[0,1,1]
	v_cvt_f32_ubyte0_e32 v104, v69
	v_cvt_f32_ubyte1_e32 v105, v69
	v_pk_fma_f32 v[90:91], v[34:35], v[102:103], v[90:91] op_sel_hi:[0,1,1]
	v_cvt_f32_ubyte2_e32 v146, v69
	v_cvt_f32_ubyte3_e32 v147, v69
	v_pk_fma_f32 v[86:87], v[42:43], v[104:105], v[86:87] op_sel_hi:[0,1,1]
	v_cvt_f32_ubyte0_e32 v98, v76
	v_cvt_f32_ubyte1_e32 v99, v76
	v_pk_fma_f32 v[84:85], v[42:43], v[146:147], v[84:85] op_sel_hi:[0,1,1]
	v_and_b32_e32 v82, s0, v4
	v_and_b32_e32 v83, s1, v4
	v_and_b32_e32 v88, s0, v5
	v_and_b32_e32 v89, s1, v5
	v_cvt_f32_ubyte2_e32 v102, v76
	v_cvt_f32_ubyte3_e32 v103, v76
	v_pk_fma_f32 v[80:81], v[34:35], v[98:99], v[80:81] op_sel_hi:[0,1,1]
	v_cvt_f32_ubyte0_e32 v104, v77
	v_cvt_f32_ubyte1_e32 v105, v77
	v_pk_fma_f32 v[78:79], v[34:35], v[102:103], v[78:79] op_sel_hi:[0,1,1]
	v_cvt_f32_ubyte2_e32 v146, v77
	v_cvt_f32_ubyte3_e32 v147, v77
	v_pk_fma_f32 v[70:71], v[42:43], v[104:105], v[70:71] op_sel_hi:[0,1,1]
	v_cvt_f32_ubyte0_e32 v98, v82
	v_cvt_f32_ubyte1_e32 v99, v82
	v_pk_fma_f32 v[62:63], v[42:43], v[146:147], v[62:63] op_sel_hi:[0,1,1]
	v_cvt_f32_ubyte2_e32 v102, v82
	v_cvt_f32_ubyte3_e32 v103, v82
	v_pk_fma_f32 v[92:93], v[34:35], v[98:99], v[92:93] op_sel:[1,0,0]
	v_cvt_f32_ubyte0_e32 v104, v83
	v_cvt_f32_ubyte1_e32 v105, v83
	v_pk_fma_f32 v[90:91], v[34:35], v[102:103], v[90:91] op_sel:[1,0,0]
	v_cvt_f32_ubyte2_e32 v146, v83
	v_cvt_f32_ubyte3_e32 v147, v83
	v_pk_fma_f32 v[86:87], v[42:43], v[104:105], v[86:87] op_sel:[1,0,0]
	v_cvt_f32_ubyte0_e32 v98, v88
	v_cvt_f32_ubyte1_e32 v99, v88
	v_pk_fma_f32 v[84:85], v[42:43], v[146:147], v[84:85] op_sel:[1,0,0]
	v_and_b32_e32 v68, s0, v6
	v_and_b32_e32 v69, s1, v6
	v_and_b32_e32 v76, s0, v7
	v_and_b32_e32 v77, s1, v7
	v_cvt_f32_ubyte2_e32 v102, v88
	v_cvt_f32_ubyte3_e32 v103, v88
	v_pk_fma_f32 v[80:81], v[34:35], v[98:99], v[80:81] op_sel:[1,0,0]
	v_cvt_f32_ubyte0_e32 v104, v89
	v_cvt_f32_ubyte1_e32 v105, v89
	v_pk_fma_f32 v[78:79], v[34:35], v[102:103], v[78:79] op_sel:[1,0,0]
	v_cvt_f32_ubyte2_e32 v146, v89
	v_cvt_f32_ubyte3_e32 v147, v89
	v_pk_fma_f32 v[70:71], v[42:43], v[104:105], v[70:71] op_sel:[1,0,0]
	v_cvt_f32_ubyte0_e32 v98, v68
	v_cvt_f32_ubyte1_e32 v99, v68
	v_pk_fma_f32 v[62:63], v[42:43], v[146:147], v[62:63] op_sel:[1,0,0]
	v_cvt_f32_ubyte2_e32 v102, v68
	v_cvt_f32_ubyte3_e32 v103, v68
	v_pk_fma_f32 v[92:93], v[36:37], v[98:99], v[92:93] op_sel_hi:[0,1,1]
	v_cvt_f32_ubyte0_e32 v104, v69
	v_cvt_f32_ubyte1_e32 v105, v69
	v_pk_fma_f32 v[90:91], v[36:37], v[102:103], v[90:91] op_sel_hi:[0,1,1]
	v_cvt_f32_ubyte2_e32 v146, v69
	v_cvt_f32_ubyte3_e32 v147, v69
	v_pk_fma_f32 v[86:87], v[44:45], v[104:105], v[86:87] op_sel_hi:[0,1,1]
	v_cvt_f32_ubyte0_e32 v98, v76
	v_cvt_f32_ubyte1_e32 v99, v76
	v_pk_fma_f32 v[84:85], v[44:45], v[146:147], v[84:85] op_sel_hi:[0,1,1]
	v_and_b32_e32 v82, s0, v8
	v_and_b32_e32 v83, s1, v8
	v_and_b32_e32 v88, s0, v9
	v_and_b32_e32 v89, s1, v9
	v_cvt_f32_ubyte2_e32 v102, v76
	v_cvt_f32_ubyte3_e32 v103, v76
	v_pk_fma_f32 v[80:81], v[36:37], v[98:99], v[80:81] op_sel_hi:[0,1,1]
	v_cvt_f32_ubyte0_e32 v104, v77
	v_cvt_f32_ubyte1_e32 v105, v77
	v_pk_fma_f32 v[78:79], v[36:37], v[102:103], v[78:79] op_sel_hi:[0,1,1]
	v_cvt_f32_ubyte2_e32 v146, v77
	v_cvt_f32_ubyte3_e32 v147, v77
	v_pk_fma_f32 v[70:71], v[44:45], v[104:105], v[70:71] op_sel_hi:[0,1,1]
	v_cvt_f32_ubyte0_e32 v98, v82
	v_cvt_f32_ubyte1_e32 v99, v82
	v_pk_fma_f32 v[62:63], v[44:45], v[146:147], v[62:63] op_sel_hi:[0,1,1]
	v_cvt_f32_ubyte2_e32 v102, v82
	v_cvt_f32_ubyte3_e32 v103, v82
	v_pk_fma_f32 v[92:93], v[36:37], v[98:99], v[92:93] op_sel:[1,0,0]
	v_cvt_f32_ubyte0_e32 v104, v83
	v_cvt_f32_ubyte1_e32 v105, v83
	v_pk_fma_f32 v[90:91], v[36:37], v[102:103], v[90:91] op_sel:[1,0,0]
	v_cvt_f32_ubyte2_e32 v146, v83
	v_cvt_f32_ubyte3_e32 v147, v83
	v_pk_fma_f32 v[86:87], v[44:45], v[104:105], v[86:87] op_sel:[1,0,0]
	v_cvt_f32_ubyte0_e32 v98, v88
	v_cvt_f32_ubyte1_e32 v99, v88
	v_pk_fma_f32 v[84:85], v[44:45], v[146:147], v[84:85] op_sel:[1,0,0]
	v_and_b32_e32 v68, s0, v10
	v_and_b32_e32 v69, s1, v10
	v_and_b32_e32 v76, s0, v11
	v_and_b32_e32 v77, s1, v11
	v_cvt_f32_ubyte2_e32 v102, v88
	v_cvt_f32_ubyte3_e32 v103, v88
	v_pk_fma_f32 v[80:81], v[36:37], v[98:99], v[80:81] op_sel:[1,0,0]
	v_cvt_f32_ubyte0_e32 v104, v89
	v_cvt_f32_ubyte1_e32 v105, v89
	v_pk_fma_f32 v[78:79], v[36:37], v[102:103], v[78:79] op_sel:[1,0,0]
	v_cvt_f32_ubyte2_e32 v146, v89
	v_cvt_f32_ubyte3_e32 v147, v89
	v_pk_fma_f32 v[70:71], v[44:45], v[104:105], v[70:71] op_sel:[1,0,0]
	v_cvt_f32_ubyte0_e32 v98, v68
	v_cvt_f32_ubyte1_e32 v99, v68
	v_pk_fma_f32 v[62:63], v[44:45], v[146:147], v[62:63] op_sel:[1,0,0]
	v_cvt_f32_ubyte2_e32 v102, v68
	v_cvt_f32_ubyte3_e32 v103, v68
	v_pk_fma_f32 v[92:93], v[38:39], v[98:99], v[92:93] op_sel_hi:[0,1,1]
	v_cvt_f32_ubyte0_e32 v104, v69
	v_cvt_f32_ubyte1_e32 v105, v69
	v_pk_fma_f32 v[90:91], v[38:39], v[102:103], v[90:91] op_sel_hi:[0,1,1]
	v_cvt_f32_ubyte2_e32 v146, v69
	v_cvt_f32_ubyte3_e32 v147, v69
	v_pk_fma_f32 v[86:87], v[46:47], v[104:105], v[86:87] op_sel_hi:[0,1,1]
	v_cvt_f32_ubyte0_e32 v98, v76
	v_cvt_f32_ubyte1_e32 v99, v76
	v_pk_fma_f32 v[84:85], v[46:47], v[146:147], v[84:85] op_sel_hi:[0,1,1]
	v_and_b32_e32 v82, s0, v12
	v_and_b32_e32 v83, s1, v12
	v_and_b32_e32 v88, s0, v13
	v_and_b32_e32 v89, s1, v13
	v_cvt_f32_ubyte2_e32 v102, v76
	v_cvt_f32_ubyte3_e32 v103, v76
	v_pk_fma_f32 v[80:81], v[38:39], v[98:99], v[80:81] op_sel_hi:[0,1,1]
	v_cvt_f32_ubyte0_e32 v104, v77
	v_cvt_f32_ubyte1_e32 v105, v77
	v_pk_fma_f32 v[78:79], v[38:39], v[102:103], v[78:79] op_sel_hi:[0,1,1]
	v_cvt_f32_ubyte2_e32 v146, v77
	v_cvt_f32_ubyte3_e32 v147, v77
	v_pk_fma_f32 v[70:71], v[46:47], v[104:105], v[70:71] op_sel_hi:[0,1,1]
	v_cvt_f32_ubyte0_e32 v98, v82
	v_cvt_f32_ubyte1_e32 v99, v82
	v_pk_fma_f32 v[62:63], v[46:47], v[146:147], v[62:63] op_sel_hi:[0,1,1]
	v_cvt_f32_ubyte2_e32 v102, v82
	v_cvt_f32_ubyte3_e32 v103, v82
	v_pk_fma_f32 v[92:93], v[38:39], v[98:99], v[92:93] op_sel:[1,0,0]
	v_cvt_f32_ubyte0_e32 v104, v83
	v_cvt_f32_ubyte1_e32 v105, v83
	v_pk_fma_f32 v[90:91], v[38:39], v[102:103], v[90:91] op_sel:[1,0,0]
	v_cvt_f32_ubyte2_e32 v146, v83
	v_cvt_f32_ubyte3_e32 v147, v83
	v_pk_fma_f32 v[86:87], v[46:47], v[104:105], v[86:87] op_sel:[1,0,0]
	v_cvt_f32_ubyte0_e32 v98, v88
	v_cvt_f32_ubyte1_e32 v99, v88
	v_pk_fma_f32 v[84:85], v[46:47], v[146:147], v[84:85] op_sel:[1,0,0]
	v_and_b32_e32 v68, s0, v14
	v_and_b32_e32 v69, s1, v14
	v_and_b32_e32 v76, s0, v15
	v_and_b32_e32 v77, s1, v15
	v_cvt_f32_ubyte2_e32 v102, v88
	v_cvt_f32_ubyte3_e32 v103, v88
	v_pk_fma_f32 v[80:81], v[38:39], v[98:99], v[80:81] op_sel:[1,0,0]
	v_cvt_f32_ubyte0_e32 v104, v89
	v_cvt_f32_ubyte1_e32 v105, v89
	v_pk_fma_f32 v[78:79], v[38:39], v[102:103], v[78:79] op_sel:[1,0,0]
	v_cvt_f32_ubyte2_e32 v146, v89
	v_cvt_f32_ubyte3_e32 v147, v89
	v_pk_fma_f32 v[70:71], v[46:47], v[104:105], v[70:71] op_sel:[1,0,0]
	v_cvt_f32_ubyte0_e32 v98, v68
	v_cvt_f32_ubyte1_e32 v99, v68
	v_pk_fma_f32 v[62:63], v[46:47], v[146:147], v[62:63] op_sel:[1,0,0]
	v_cvt_f32_ubyte2_e32 v102, v68
	v_cvt_f32_ubyte3_e32 v103, v68
	v_pk_fma_f32 v[92:93], v[40:41], v[98:99], v[92:93] op_sel_hi:[0,1,1]
	v_cvt_f32_ubyte0_e32 v104, v69
	v_cvt_f32_ubyte1_e32 v105, v69
	v_pk_fma_f32 v[90:91], v[40:41], v[102:103], v[90:91] op_sel_hi:[0,1,1]
	v_cvt_f32_ubyte2_e32 v146, v69
	v_cvt_f32_ubyte3_e32 v147, v69
	v_pk_fma_f32 v[86:87], v[48:49], v[104:105], v[86:87] op_sel_hi:[0,1,1]
	v_cvt_f32_ubyte0_e32 v98, v76
	v_cvt_f32_ubyte1_e32 v99, v76
	v_pk_fma_f32 v[84:85], v[48:49], v[146:147], v[84:85] op_sel_hi:[0,1,1]
	v_and_b32_e32 v82, s0, v16
	v_and_b32_e32 v83, s1, v16
	v_and_b32_e32 v88, s0, v17
	v_and_b32_e32 v89, s1, v17
	v_cvt_f32_ubyte2_e32 v102, v76
	v_cvt_f32_ubyte3_e32 v103, v76
	v_pk_fma_f32 v[80:81], v[40:41], v[98:99], v[80:81] op_sel_hi:[0,1,1]
	v_cvt_f32_ubyte0_e32 v104, v77
	v_cvt_f32_ubyte1_e32 v105, v77
	v_pk_fma_f32 v[78:79], v[40:41], v[102:103], v[78:79] op_sel_hi:[0,1,1]
	v_cvt_f32_ubyte2_e32 v146, v77
	v_cvt_f32_ubyte3_e32 v147, v77
	v_pk_fma_f32 v[70:71], v[48:49], v[104:105], v[70:71] op_sel_hi:[0,1,1]
	v_cvt_f32_ubyte0_e32 v98, v82
	v_cvt_f32_ubyte1_e32 v99, v82
	v_pk_fma_f32 v[62:63], v[48:49], v[146:147], v[62:63] op_sel_hi:[0,1,1]
	v_cvt_f32_ubyte2_e32 v102, v82
	v_cvt_f32_ubyte3_e32 v103, v82
	v_pk_fma_f32 v[92:93], v[40:41], v[98:99], v[92:93] op_sel:[1,0,0]
	v_cvt_f32_ubyte0_e32 v104, v83
	v_cvt_f32_ubyte1_e32 v105, v83
	v_pk_fma_f32 v[90:91], v[40:41], v[102:103], v[90:91] op_sel:[1,0,0]
	v_cvt_f32_ubyte2_e32 v146, v83
	v_cvt_f32_ubyte3_e32 v147, v83
	v_pk_fma_f32 v[86:87], v[48:49], v[104:105], v[86:87] op_sel:[1,0,0]
	v_cvt_f32_ubyte0_e32 v98, v88
	v_cvt_f32_ubyte1_e32 v99, v88
	v_pk_fma_f32 v[84:85], v[48:49], v[146:147], v[84:85] op_sel:[1,0,0]
	v_cvt_f32_ubyte2_e32 v102, v88
	v_cvt_f32_ubyte3_e32 v103, v88
	v_pk_fma_f32 v[80:81], v[40:41], v[98:99], v[80:81] op_sel:[1,0,0]
	v_cvt_f32_ubyte0_e32 v104, v89
	v_cvt_f32_ubyte1_e32 v105, v89
	v_pk_fma_f32 v[78:79], v[40:41], v[102:103], v[78:79] op_sel:[1,0,0]
	v_cvt_f32_ubyte2_e32 v146, v89
	v_cvt_f32_ubyte3_e32 v147, v89
	v_pk_fma_f32 v[70:71], v[48:49], v[104:105], v[70:71] op_sel:[1,0,0]
	v_pk_fma_f32 v[62:63], v[48:49], v[146:147], v[62:63] op_sel:[1,0,0]
	s_waitcnt lgkmcnt(0)
	v_lshl_add_u32 v72, v72, 9, v100
	v_lshl_add_u32 v73, v73, 9, v100
	v_lshl_add_u32 v74, v74, 9, v100
	v_lshl_add_u32 v75, v75, 9, v100
	v_lshl_add_u32 v94, v94, 9, v100
	v_lshl_add_u32 v95, v95, 9, v100
	v_lshl_add_u32 v96, v96, 9, v100
	v_lshl_add_u32 v97, v97, 9, v100
	global_load_dwordx2 v[2:3], v72, s[38:39]
	global_load_dwordx2 v[4:5], v73, s[38:39]
	global_load_dwordx2 v[6:7], v74, s[38:39]
	global_load_dwordx2 v[8:9], v75, s[38:39]
	global_load_dwordx2 v[10:11], v94, s[38:39]
	global_load_dwordx2 v[12:13], v95, s[38:39]
	global_load_dwordx2 v[14:15], v96, s[38:39]
	global_load_dwordx2 v[16:17], v97, s[38:39]
	ds_read_b128 v[72:75], v1 offset:352
	ds_read_b128 v[94:97], v1 offset:368
	ds_read_b128 v[34:37], v1 offset:704
	ds_read_b128 v[38:41], v1 offset:720
	ds_read_b128 v[42:45], v1 offset:1728
	ds_read_b128 v[46:49], v1 offset:1744
	s_waitcnt vmcnt(40)
	v_and_b32_e32 v68, s0, v18
	v_and_b32_e32 v69, s1, v18
	v_and_b32_e32 v76, s0, v19
	v_and_b32_e32 v77, s1, v19
	v_cvt_f32_ubyte0_e32 v98, v68
	v_cvt_f32_ubyte1_e32 v99, v68
	v_cvt_f32_ubyte2_e32 v102, v68
	v_cvt_f32_ubyte3_e32 v103, v68
	v_pk_fma_f32 v[92:93], v[50:51], v[98:99], v[92:93] op_sel_hi:[0,1,1]
	v_cvt_f32_ubyte0_e32 v104, v69
	v_cvt_f32_ubyte1_e32 v105, v69
	v_pk_fma_f32 v[90:91], v[50:51], v[102:103], v[90:91] op_sel_hi:[0,1,1]
	v_cvt_f32_ubyte2_e32 v146, v69
	v_cvt_f32_ubyte3_e32 v147, v69
	v_pk_fma_f32 v[86:87], v[58:59], v[104:105], v[86:87] op_sel_hi:[0,1,1]
	v_cvt_f32_ubyte0_e32 v98, v76
	v_cvt_f32_ubyte1_e32 v99, v76
	v_pk_fma_f32 v[84:85], v[58:59], v[146:147], v[84:85] op_sel_hi:[0,1,1]
	v_and_b32_e32 v82, s0, v20
	v_and_b32_e32 v83, s1, v20
	v_and_b32_e32 v88, s0, v21
	v_and_b32_e32 v89, s1, v21
	v_cvt_f32_ubyte2_e32 v102, v76
	v_cvt_f32_ubyte3_e32 v103, v76
	v_pk_fma_f32 v[80:81], v[50:51], v[98:99], v[80:81] op_sel_hi:[0,1,1]
	v_cvt_f32_ubyte0_e32 v104, v77
	v_cvt_f32_ubyte1_e32 v105, v77
	v_pk_fma_f32 v[78:79], v[50:51], v[102:103], v[78:79] op_sel_hi:[0,1,1]
	v_cvt_f32_ubyte2_e32 v146, v77
	v_cvt_f32_ubyte3_e32 v147, v77
	v_pk_fma_f32 v[70:71], v[58:59], v[104:105], v[70:71] op_sel_hi:[0,1,1]
	v_cvt_f32_ubyte0_e32 v98, v82
	v_cvt_f32_ubyte1_e32 v99, v82
	v_pk_fma_f32 v[62:63], v[58:59], v[146:147], v[62:63] op_sel_hi:[0,1,1]
	v_cvt_f32_ubyte2_e32 v102, v82
	v_cvt_f32_ubyte3_e32 v103, v82
	v_pk_fma_f32 v[92:93], v[50:51], v[98:99], v[92:93] op_sel:[1,0,0]
	v_cvt_f32_ubyte0_e32 v104, v83
	v_cvt_f32_ubyte1_e32 v105, v83
	v_pk_fma_f32 v[90:91], v[50:51], v[102:103], v[90:91] op_sel:[1,0,0]
	v_cvt_f32_ubyte2_e32 v146, v83
	v_cvt_f32_ubyte3_e32 v147, v83
	v_pk_fma_f32 v[86:87], v[58:59], v[104:105], v[86:87] op_sel:[1,0,0]
	v_cvt_f32_ubyte0_e32 v98, v88
	v_cvt_f32_ubyte1_e32 v99, v88
	v_pk_fma_f32 v[84:85], v[58:59], v[146:147], v[84:85] op_sel:[1,0,0]
	v_and_b32_e32 v68, s0, v22
	v_and_b32_e32 v69, s1, v22
	v_and_b32_e32 v76, s0, v23
	v_and_b32_e32 v77, s1, v23
	v_cvt_f32_ubyte2_e32 v102, v88
	v_cvt_f32_ubyte3_e32 v103, v88
	v_pk_fma_f32 v[80:81], v[50:51], v[98:99], v[80:81] op_sel:[1,0,0]
	v_cvt_f32_ubyte0_e32 v104, v89
	v_cvt_f32_ubyte1_e32 v105, v89
	v_pk_fma_f32 v[78:79], v[50:51], v[102:103], v[78:79] op_sel:[1,0,0]
	v_cvt_f32_ubyte2_e32 v146, v89
	v_cvt_f32_ubyte3_e32 v147, v89
	v_pk_fma_f32 v[70:71], v[58:59], v[104:105], v[70:71] op_sel:[1,0,0]
	v_cvt_f32_ubyte0_e32 v98, v68
	v_cvt_f32_ubyte1_e32 v99, v68
	v_pk_fma_f32 v[62:63], v[58:59], v[146:147], v[62:63] op_sel:[1,0,0]
	v_cvt_f32_ubyte2_e32 v102, v68
	v_cvt_f32_ubyte3_e32 v103, v68
	v_pk_fma_f32 v[92:93], v[52:53], v[98:99], v[92:93] op_sel_hi:[0,1,1]
	v_cvt_f32_ubyte0_e32 v104, v69
	v_cvt_f32_ubyte1_e32 v105, v69
	v_pk_fma_f32 v[90:91], v[52:53], v[102:103], v[90:91] op_sel_hi:[0,1,1]
	v_cvt_f32_ubyte2_e32 v146, v69
	v_cvt_f32_ubyte3_e32 v147, v69
	v_pk_fma_f32 v[86:87], v[60:61], v[104:105], v[86:87] op_sel_hi:[0,1,1]
	v_cvt_f32_ubyte0_e32 v98, v76
	v_cvt_f32_ubyte1_e32 v99, v76
	v_pk_fma_f32 v[84:85], v[60:61], v[146:147], v[84:85] op_sel_hi:[0,1,1]
	v_and_b32_e32 v82, s0, v24
	v_and_b32_e32 v83, s1, v24
	v_and_b32_e32 v88, s0, v25
	v_and_b32_e32 v89, s1, v25
	v_cvt_f32_ubyte2_e32 v102, v76
	v_cvt_f32_ubyte3_e32 v103, v76
	v_pk_fma_f32 v[80:81], v[52:53], v[98:99], v[80:81] op_sel_hi:[0,1,1]
	v_cvt_f32_ubyte0_e32 v104, v77
	v_cvt_f32_ubyte1_e32 v105, v77
	v_pk_fma_f32 v[78:79], v[52:53], v[102:103], v[78:79] op_sel_hi:[0,1,1]
	v_cvt_f32_ubyte2_e32 v146, v77
	v_cvt_f32_ubyte3_e32 v147, v77
	v_pk_fma_f32 v[70:71], v[60:61], v[104:105], v[70:71] op_sel_hi:[0,1,1]
	v_cvt_f32_ubyte0_e32 v98, v82
	v_cvt_f32_ubyte1_e32 v99, v82
	v_pk_fma_f32 v[62:63], v[60:61], v[146:147], v[62:63] op_sel_hi:[0,1,1]
	v_cvt_f32_ubyte2_e32 v102, v82
	v_cvt_f32_ubyte3_e32 v103, v82
	v_pk_fma_f32 v[92:93], v[52:53], v[98:99], v[92:93] op_sel:[1,0,0]
	v_cvt_f32_ubyte0_e32 v104, v83
	v_cvt_f32_ubyte1_e32 v105, v83
	v_pk_fma_f32 v[90:91], v[52:53], v[102:103], v[90:91] op_sel:[1,0,0]
	v_cvt_f32_ubyte2_e32 v146, v83
	v_cvt_f32_ubyte3_e32 v147, v83
	v_pk_fma_f32 v[86:87], v[60:61], v[104:105], v[86:87] op_sel:[1,0,0]
	v_cvt_f32_ubyte0_e32 v98, v88
	v_cvt_f32_ubyte1_e32 v99, v88
	v_pk_fma_f32 v[84:85], v[60:61], v[146:147], v[84:85] op_sel:[1,0,0]
	v_and_b32_e32 v68, s0, v26
	v_and_b32_e32 v69, s1, v26
	v_and_b32_e32 v76, s0, v27
	v_and_b32_e32 v77, s1, v27
	v_cvt_f32_ubyte2_e32 v102, v88
	v_cvt_f32_ubyte3_e32 v103, v88
	v_pk_fma_f32 v[80:81], v[52:53], v[98:99], v[80:81] op_sel:[1,0,0]
	v_cvt_f32_ubyte0_e32 v104, v89
	v_cvt_f32_ubyte1_e32 v105, v89
	v_pk_fma_f32 v[78:79], v[52:53], v[102:103], v[78:79] op_sel:[1,0,0]
	v_cvt_f32_ubyte2_e32 v146, v89
	v_cvt_f32_ubyte3_e32 v147, v89
	v_pk_fma_f32 v[70:71], v[60:61], v[104:105], v[70:71] op_sel:[1,0,0]
	v_cvt_f32_ubyte0_e32 v98, v68
	v_cvt_f32_ubyte1_e32 v99, v68
	v_pk_fma_f32 v[62:63], v[60:61], v[146:147], v[62:63] op_sel:[1,0,0]
	v_cvt_f32_ubyte2_e32 v102, v68
	v_cvt_f32_ubyte3_e32 v103, v68
	v_pk_fma_f32 v[92:93], v[54:55], v[98:99], v[92:93] op_sel_hi:[0,1,1]
	v_cvt_f32_ubyte0_e32 v104, v69
	v_cvt_f32_ubyte1_e32 v105, v69
	v_pk_fma_f32 v[90:91], v[54:55], v[102:103], v[90:91] op_sel_hi:[0,1,1]
	v_cvt_f32_ubyte2_e32 v146, v69
	v_cvt_f32_ubyte3_e32 v147, v69
	v_pk_fma_f32 v[86:87], v[64:65], v[104:105], v[86:87] op_sel_hi:[0,1,1]
	v_cvt_f32_ubyte0_e32 v98, v76
	v_cvt_f32_ubyte1_e32 v99, v76
	v_pk_fma_f32 v[84:85], v[64:65], v[146:147], v[84:85] op_sel_hi:[0,1,1]
	v_and_b32_e32 v82, s0, v28
	v_and_b32_e32 v83, s1, v28
	v_and_b32_e32 v88, s0, v29
	v_and_b32_e32 v89, s1, v29
	v_cvt_f32_ubyte2_e32 v102, v76
	v_cvt_f32_ubyte3_e32 v103, v76
	v_pk_fma_f32 v[80:81], v[54:55], v[98:99], v[80:81] op_sel_hi:[0,1,1]
	v_cvt_f32_ubyte0_e32 v104, v77
	v_cvt_f32_ubyte1_e32 v105, v77
	v_pk_fma_f32 v[78:79], v[54:55], v[102:103], v[78:79] op_sel_hi:[0,1,1]
	v_cvt_f32_ubyte2_e32 v146, v77
	v_cvt_f32_ubyte3_e32 v147, v77
	v_pk_fma_f32 v[70:71], v[64:65], v[104:105], v[70:71] op_sel_hi:[0,1,1]
	v_cvt_f32_ubyte0_e32 v98, v82
	v_cvt_f32_ubyte1_e32 v99, v82
	v_pk_fma_f32 v[62:63], v[64:65], v[146:147], v[62:63] op_sel_hi:[0,1,1]
	v_cvt_f32_ubyte2_e32 v102, v82
	v_cvt_f32_ubyte3_e32 v103, v82
	v_pk_fma_f32 v[92:93], v[54:55], v[98:99], v[92:93] op_sel:[1,0,0]
	v_cvt_f32_ubyte0_e32 v104, v83
	v_cvt_f32_ubyte1_e32 v105, v83
	v_pk_fma_f32 v[90:91], v[54:55], v[102:103], v[90:91] op_sel:[1,0,0]
	v_cvt_f32_ubyte2_e32 v146, v83
	v_cvt_f32_ubyte3_e32 v147, v83
	v_pk_fma_f32 v[86:87], v[64:65], v[104:105], v[86:87] op_sel:[1,0,0]
	v_cvt_f32_ubyte0_e32 v98, v88
	v_cvt_f32_ubyte1_e32 v99, v88
	v_pk_fma_f32 v[84:85], v[64:65], v[146:147], v[84:85] op_sel:[1,0,0]
	v_and_b32_e32 v68, s0, v30
	v_and_b32_e32 v69, s1, v30
	v_and_b32_e32 v76, s0, v31
	v_and_b32_e32 v77, s1, v31
	v_cvt_f32_ubyte2_e32 v102, v88
	v_cvt_f32_ubyte3_e32 v103, v88
	v_pk_fma_f32 v[80:81], v[54:55], v[98:99], v[80:81] op_sel:[1,0,0]
	v_cvt_f32_ubyte0_e32 v104, v89
	v_cvt_f32_ubyte1_e32 v105, v89
	v_pk_fma_f32 v[78:79], v[54:55], v[102:103], v[78:79] op_sel:[1,0,0]
	v_cvt_f32_ubyte2_e32 v146, v89
	v_cvt_f32_ubyte3_e32 v147, v89
	v_pk_fma_f32 v[70:71], v[64:65], v[104:105], v[70:71] op_sel:[1,0,0]
	v_cvt_f32_ubyte0_e32 v98, v68
	v_cvt_f32_ubyte1_e32 v99, v68
	v_pk_fma_f32 v[62:63], v[64:65], v[146:147], v[62:63] op_sel:[1,0,0]
	v_cvt_f32_ubyte2_e32 v102, v68
	v_cvt_f32_ubyte3_e32 v103, v68
	v_pk_fma_f32 v[92:93], v[56:57], v[98:99], v[92:93] op_sel_hi:[0,1,1]
	v_cvt_f32_ubyte0_e32 v104, v69
	v_cvt_f32_ubyte1_e32 v105, v69
	v_pk_fma_f32 v[90:91], v[56:57], v[102:103], v[90:91] op_sel_hi:[0,1,1]
	v_cvt_f32_ubyte2_e32 v146, v69
	v_cvt_f32_ubyte3_e32 v147, v69
	v_pk_fma_f32 v[86:87], v[66:67], v[104:105], v[86:87] op_sel_hi:[0,1,1]
	v_cvt_f32_ubyte0_e32 v98, v76
	v_cvt_f32_ubyte1_e32 v99, v76
	v_pk_fma_f32 v[84:85], v[66:67], v[146:147], v[84:85] op_sel_hi:[0,1,1]
	v_and_b32_e32 v82, s0, v32
	v_and_b32_e32 v83, s1, v32
	v_and_b32_e32 v88, s0, v33
	v_and_b32_e32 v89, s1, v33
	v_cvt_f32_ubyte2_e32 v102, v76
	v_cvt_f32_ubyte3_e32 v103, v76
	v_pk_fma_f32 v[80:81], v[56:57], v[98:99], v[80:81] op_sel_hi:[0,1,1]
	v_cvt_f32_ubyte0_e32 v104, v77
	v_cvt_f32_ubyte1_e32 v105, v77
	v_pk_fma_f32 v[78:79], v[56:57], v[102:103], v[78:79] op_sel_hi:[0,1,1]
	v_cvt_f32_ubyte2_e32 v146, v77
	v_cvt_f32_ubyte3_e32 v147, v77
	v_pk_fma_f32 v[70:71], v[66:67], v[104:105], v[70:71] op_sel_hi:[0,1,1]
	v_cvt_f32_ubyte0_e32 v98, v82
	v_cvt_f32_ubyte1_e32 v99, v82
	v_pk_fma_f32 v[62:63], v[66:67], v[146:147], v[62:63] op_sel_hi:[0,1,1]
	v_cvt_f32_ubyte2_e32 v102, v82
	v_cvt_f32_ubyte3_e32 v103, v82
	v_pk_fma_f32 v[92:93], v[56:57], v[98:99], v[92:93] op_sel:[1,0,0]
	v_cvt_f32_ubyte0_e32 v104, v83
	v_cvt_f32_ubyte1_e32 v105, v83
	v_pk_fma_f32 v[90:91], v[56:57], v[102:103], v[90:91] op_sel:[1,0,0]
	v_cvt_f32_ubyte2_e32 v146, v83
	v_cvt_f32_ubyte3_e32 v147, v83
	v_pk_fma_f32 v[86:87], v[66:67], v[104:105], v[86:87] op_sel:[1,0,0]
	v_cvt_f32_ubyte0_e32 v98, v88
	v_cvt_f32_ubyte1_e32 v99, v88
	v_pk_fma_f32 v[84:85], v[66:67], v[146:147], v[84:85] op_sel:[1,0,0]
	v_cvt_f32_ubyte2_e32 v102, v88
	v_cvt_f32_ubyte3_e32 v103, v88
	v_pk_fma_f32 v[80:81], v[56:57], v[98:99], v[80:81] op_sel:[1,0,0]
	v_cvt_f32_ubyte0_e32 v104, v89
	v_cvt_f32_ubyte1_e32 v105, v89
	v_pk_fma_f32 v[78:79], v[56:57], v[102:103], v[78:79] op_sel:[1,0,0]
	v_cvt_f32_ubyte2_e32 v146, v89
	v_cvt_f32_ubyte3_e32 v147, v89
	v_pk_fma_f32 v[70:71], v[66:67], v[104:105], v[70:71] op_sel:[1,0,0]
	v_pk_fma_f32 v[62:63], v[66:67], v[146:147], v[62:63] op_sel:[1,0,0]
	s_waitcnt lgkmcnt(0)
	v_lshl_add_u32 v72, v72, 9, v100
	v_lshl_add_u32 v73, v73, 9, v100
	v_lshl_add_u32 v74, v74, 9, v100
	v_lshl_add_u32 v75, v75, 9, v100
	v_lshl_add_u32 v94, v94, 9, v100
	v_lshl_add_u32 v95, v95, 9, v100
	v_lshl_add_u32 v96, v96, 9, v100
	v_lshl_add_u32 v97, v97, 9, v100
	global_load_dwordx2 v[18:19], v72, s[38:39]
	global_load_dwordx2 v[20:21], v73, s[38:39]
	global_load_dwordx2 v[22:23], v74, s[38:39]
	global_load_dwordx2 v[24:25], v75, s[38:39]
	global_load_dwordx2 v[26:27], v94, s[38:39]
	global_load_dwordx2 v[28:29], v95, s[38:39]
	global_load_dwordx2 v[30:31], v96, s[38:39]
	global_load_dwordx2 v[32:33], v97, s[38:39]
	ds_read_b128 v[72:75], v1 offset:384
	ds_read_b128 v[94:97], v1 offset:400
	ds_read_b128 v[50:53], v1 offset:736
	ds_read_b128 v[54:57], v1 offset:752
	ds_read_b128 v[58:61], v1 offset:1760
	ds_read_b128 v[64:67], v1 offset:1776
	s_waitcnt vmcnt(40)
	v_and_b32_e32 v68, s0, v164
	v_and_b32_e32 v69, s1, v164
	v_and_b32_e32 v76, s0, v165
	v_and_b32_e32 v77, s1, v165
	v_cvt_f32_ubyte0_e32 v98, v68
	v_cvt_f32_ubyte1_e32 v99, v68
	v_cvt_f32_ubyte2_e32 v102, v68
	v_cvt_f32_ubyte3_e32 v103, v68
	v_pk_fma_f32 v[92:93], v[34:35], v[98:99], v[92:93] op_sel_hi:[0,1,1]
	v_cvt_f32_ubyte0_e32 v104, v69
	v_cvt_f32_ubyte1_e32 v105, v69
	v_pk_fma_f32 v[90:91], v[34:35], v[102:103], v[90:91] op_sel_hi:[0,1,1]
	v_cvt_f32_ubyte2_e32 v146, v69
	v_cvt_f32_ubyte3_e32 v147, v69
	v_pk_fma_f32 v[86:87], v[42:43], v[104:105], v[86:87] op_sel_hi:[0,1,1]
	v_cvt_f32_ubyte0_e32 v98, v76
	v_cvt_f32_ubyte1_e32 v99, v76
	v_pk_fma_f32 v[84:85], v[42:43], v[146:147], v[84:85] op_sel_hi:[0,1,1]
	v_and_b32_e32 v82, s0, v166
	v_and_b32_e32 v83, s1, v166
	v_and_b32_e32 v88, s0, v167
	v_and_b32_e32 v89, s1, v167
	v_cvt_f32_ubyte2_e32 v102, v76
	v_cvt_f32_ubyte3_e32 v103, v76
	v_pk_fma_f32 v[80:81], v[34:35], v[98:99], v[80:81] op_sel_hi:[0,1,1]
	v_cvt_f32_ubyte0_e32 v104, v77
	v_cvt_f32_ubyte1_e32 v105, v77
	v_pk_fma_f32 v[78:79], v[34:35], v[102:103], v[78:79] op_sel_hi:[0,1,1]
	v_cvt_f32_ubyte2_e32 v146, v77
	v_cvt_f32_ubyte3_e32 v147, v77
	v_pk_fma_f32 v[70:71], v[42:43], v[104:105], v[70:71] op_sel_hi:[0,1,1]
	v_cvt_f32_ubyte0_e32 v98, v82
	v_cvt_f32_ubyte1_e32 v99, v82
	v_pk_fma_f32 v[62:63], v[42:43], v[146:147], v[62:63] op_sel_hi:[0,1,1]
	v_cvt_f32_ubyte2_e32 v102, v82
	v_cvt_f32_ubyte3_e32 v103, v82
	v_pk_fma_f32 v[92:93], v[34:35], v[98:99], v[92:93] op_sel:[1,0,0]
	v_cvt_f32_ubyte0_e32 v104, v83
	v_cvt_f32_ubyte1_e32 v105, v83
	v_pk_fma_f32 v[90:91], v[34:35], v[102:103], v[90:91] op_sel:[1,0,0]
	v_cvt_f32_ubyte2_e32 v146, v83
	v_cvt_f32_ubyte3_e32 v147, v83
	v_pk_fma_f32 v[86:87], v[42:43], v[104:105], v[86:87] op_sel:[1,0,0]
	v_cvt_f32_ubyte0_e32 v98, v88
	v_cvt_f32_ubyte1_e32 v99, v88
	v_pk_fma_f32 v[84:85], v[42:43], v[146:147], v[84:85] op_sel:[1,0,0]
	v_and_b32_e32 v68, s0, v168
	v_and_b32_e32 v69, s1, v168
	v_and_b32_e32 v76, s0, v169
	v_and_b32_e32 v77, s1, v169
	v_cvt_f32_ubyte2_e32 v102, v88
	v_cvt_f32_ubyte3_e32 v103, v88
	v_pk_fma_f32 v[80:81], v[34:35], v[98:99], v[80:81] op_sel:[1,0,0]
	v_cvt_f32_ubyte0_e32 v104, v89
	v_cvt_f32_ubyte1_e32 v105, v89
	v_pk_fma_f32 v[78:79], v[34:35], v[102:103], v[78:79] op_sel:[1,0,0]
	v_cvt_f32_ubyte2_e32 v146, v89
	v_cvt_f32_ubyte3_e32 v147, v89
	v_pk_fma_f32 v[70:71], v[42:43], v[104:105], v[70:71] op_sel:[1,0,0]
	v_cvt_f32_ubyte0_e32 v98, v68
	v_cvt_f32_ubyte1_e32 v99, v68
	v_pk_fma_f32 v[62:63], v[42:43], v[146:147], v[62:63] op_sel:[1,0,0]
	v_cvt_f32_ubyte2_e32 v102, v68
	v_cvt_f32_ubyte3_e32 v103, v68
	v_pk_fma_f32 v[92:93], v[36:37], v[98:99], v[92:93] op_sel_hi:[0,1,1]
	v_cvt_f32_ubyte0_e32 v104, v69
	v_cvt_f32_ubyte1_e32 v105, v69
	v_pk_fma_f32 v[90:91], v[36:37], v[102:103], v[90:91] op_sel_hi:[0,1,1]
	v_cvt_f32_ubyte2_e32 v146, v69
	v_cvt_f32_ubyte3_e32 v147, v69
	v_pk_fma_f32 v[86:87], v[44:45], v[104:105], v[86:87] op_sel_hi:[0,1,1]
	v_cvt_f32_ubyte0_e32 v98, v76
	v_cvt_f32_ubyte1_e32 v99, v76
	v_pk_fma_f32 v[84:85], v[44:45], v[146:147], v[84:85] op_sel_hi:[0,1,1]
	v_and_b32_e32 v82, s0, v170
	v_and_b32_e32 v83, s1, v170
	v_and_b32_e32 v88, s0, v171
	v_and_b32_e32 v89, s1, v171
	v_cvt_f32_ubyte2_e32 v102, v76
	v_cvt_f32_ubyte3_e32 v103, v76
	v_pk_fma_f32 v[80:81], v[36:37], v[98:99], v[80:81] op_sel_hi:[0,1,1]
	v_cvt_f32_ubyte0_e32 v104, v77
	v_cvt_f32_ubyte1_e32 v105, v77
	v_pk_fma_f32 v[78:79], v[36:37], v[102:103], v[78:79] op_sel_hi:[0,1,1]
	v_cvt_f32_ubyte2_e32 v146, v77
	v_cvt_f32_ubyte3_e32 v147, v77
	v_pk_fma_f32 v[70:71], v[44:45], v[104:105], v[70:71] op_sel_hi:[0,1,1]
	v_cvt_f32_ubyte0_e32 v98, v82
	v_cvt_f32_ubyte1_e32 v99, v82
	v_pk_fma_f32 v[62:63], v[44:45], v[146:147], v[62:63] op_sel_hi:[0,1,1]
	v_cvt_f32_ubyte2_e32 v102, v82
	v_cvt_f32_ubyte3_e32 v103, v82
	v_pk_fma_f32 v[92:93], v[36:37], v[98:99], v[92:93] op_sel:[1,0,0]
	v_cvt_f32_ubyte0_e32 v104, v83
	v_cvt_f32_ubyte1_e32 v105, v83
	v_pk_fma_f32 v[90:91], v[36:37], v[102:103], v[90:91] op_sel:[1,0,0]
	v_cvt_f32_ubyte2_e32 v146, v83
	v_cvt_f32_ubyte3_e32 v147, v83
	v_pk_fma_f32 v[86:87], v[44:45], v[104:105], v[86:87] op_sel:[1,0,0]
	v_cvt_f32_ubyte0_e32 v98, v88
	v_cvt_f32_ubyte1_e32 v99, v88
	v_pk_fma_f32 v[84:85], v[44:45], v[146:147], v[84:85] op_sel:[1,0,0]
	v_and_b32_e32 v68, s0, v172
	v_and_b32_e32 v69, s1, v172
	v_and_b32_e32 v76, s0, v173
	v_and_b32_e32 v77, s1, v173
	v_cvt_f32_ubyte2_e32 v102, v88
	v_cvt_f32_ubyte3_e32 v103, v88
	v_pk_fma_f32 v[80:81], v[36:37], v[98:99], v[80:81] op_sel:[1,0,0]
	v_cvt_f32_ubyte0_e32 v104, v89
	v_cvt_f32_ubyte1_e32 v105, v89
	v_pk_fma_f32 v[78:79], v[36:37], v[102:103], v[78:79] op_sel:[1,0,0]
	v_cvt_f32_ubyte2_e32 v146, v89
	v_cvt_f32_ubyte3_e32 v147, v89
	v_pk_fma_f32 v[70:71], v[44:45], v[104:105], v[70:71] op_sel:[1,0,0]
	v_cvt_f32_ubyte0_e32 v98, v68
	v_cvt_f32_ubyte1_e32 v99, v68
	v_pk_fma_f32 v[62:63], v[44:45], v[146:147], v[62:63] op_sel:[1,0,0]
	v_cvt_f32_ubyte2_e32 v102, v68
	v_cvt_f32_ubyte3_e32 v103, v68
	v_pk_fma_f32 v[92:93], v[38:39], v[98:99], v[92:93] op_sel_hi:[0,1,1]
	v_cvt_f32_ubyte0_e32 v104, v69
	v_cvt_f32_ubyte1_e32 v105, v69
	v_pk_fma_f32 v[90:91], v[38:39], v[102:103], v[90:91] op_sel_hi:[0,1,1]
	v_cvt_f32_ubyte2_e32 v146, v69
	v_cvt_f32_ubyte3_e32 v147, v69
	v_pk_fma_f32 v[86:87], v[46:47], v[104:105], v[86:87] op_sel_hi:[0,1,1]
	v_cvt_f32_ubyte0_e32 v98, v76
	v_cvt_f32_ubyte1_e32 v99, v76
	v_pk_fma_f32 v[84:85], v[46:47], v[146:147], v[84:85] op_sel_hi:[0,1,1]
	v_and_b32_e32 v82, s0, v174
	v_and_b32_e32 v83, s1, v174
	v_and_b32_e32 v88, s0, v175
	v_and_b32_e32 v89, s1, v175
	v_cvt_f32_ubyte2_e32 v102, v76
	v_cvt_f32_ubyte3_e32 v103, v76
	v_pk_fma_f32 v[80:81], v[38:39], v[98:99], v[80:81] op_sel_hi:[0,1,1]
	v_cvt_f32_ubyte0_e32 v104, v77
	v_cvt_f32_ubyte1_e32 v105, v77
	v_pk_fma_f32 v[78:79], v[38:39], v[102:103], v[78:79] op_sel_hi:[0,1,1]
	v_cvt_f32_ubyte2_e32 v146, v77
	v_cvt_f32_ubyte3_e32 v147, v77
	v_pk_fma_f32 v[70:71], v[46:47], v[104:105], v[70:71] op_sel_hi:[0,1,1]
	v_cvt_f32_ubyte0_e32 v98, v82
	v_cvt_f32_ubyte1_e32 v99, v82
	v_pk_fma_f32 v[62:63], v[46:47], v[146:147], v[62:63] op_sel_hi:[0,1,1]
	v_cvt_f32_ubyte2_e32 v102, v82
	v_cvt_f32_ubyte3_e32 v103, v82
	v_pk_fma_f32 v[92:93], v[38:39], v[98:99], v[92:93] op_sel:[1,0,0]
	v_cvt_f32_ubyte0_e32 v104, v83
	v_cvt_f32_ubyte1_e32 v105, v83
	v_pk_fma_f32 v[90:91], v[38:39], v[102:103], v[90:91] op_sel:[1,0,0]
	v_cvt_f32_ubyte2_e32 v146, v83
	v_cvt_f32_ubyte3_e32 v147, v83
	v_pk_fma_f32 v[86:87], v[46:47], v[104:105], v[86:87] op_sel:[1,0,0]
	v_cvt_f32_ubyte0_e32 v98, v88
	v_cvt_f32_ubyte1_e32 v99, v88
	v_pk_fma_f32 v[84:85], v[46:47], v[146:147], v[84:85] op_sel:[1,0,0]
	v_and_b32_e32 v68, s0, v176
	v_and_b32_e32 v69, s1, v176
	v_and_b32_e32 v76, s0, v177
	v_and_b32_e32 v77, s1, v177
	v_cvt_f32_ubyte2_e32 v102, v88
	v_cvt_f32_ubyte3_e32 v103, v88
	v_pk_fma_f32 v[80:81], v[38:39], v[98:99], v[80:81] op_sel:[1,0,0]
	v_cvt_f32_ubyte0_e32 v104, v89
	v_cvt_f32_ubyte1_e32 v105, v89
	v_pk_fma_f32 v[78:79], v[38:39], v[102:103], v[78:79] op_sel:[1,0,0]
	v_cvt_f32_ubyte2_e32 v146, v89
	v_cvt_f32_ubyte3_e32 v147, v89
	v_pk_fma_f32 v[70:71], v[46:47], v[104:105], v[70:71] op_sel:[1,0,0]
	v_cvt_f32_ubyte0_e32 v98, v68
	v_cvt_f32_ubyte1_e32 v99, v68
	v_pk_fma_f32 v[62:63], v[46:47], v[146:147], v[62:63] op_sel:[1,0,0]
	v_cvt_f32_ubyte2_e32 v102, v68
	v_cvt_f32_ubyte3_e32 v103, v68
	v_pk_fma_f32 v[92:93], v[40:41], v[98:99], v[92:93] op_sel_hi:[0,1,1]
	v_cvt_f32_ubyte0_e32 v104, v69
	v_cvt_f32_ubyte1_e32 v105, v69
	v_pk_fma_f32 v[90:91], v[40:41], v[102:103], v[90:91] op_sel_hi:[0,1,1]
	v_cvt_f32_ubyte2_e32 v146, v69
	v_cvt_f32_ubyte3_e32 v147, v69
	v_pk_fma_f32 v[86:87], v[48:49], v[104:105], v[86:87] op_sel_hi:[0,1,1]
	v_cvt_f32_ubyte0_e32 v98, v76
	v_cvt_f32_ubyte1_e32 v99, v76
	v_pk_fma_f32 v[84:85], v[48:49], v[146:147], v[84:85] op_sel_hi:[0,1,1]
	v_and_b32_e32 v82, s0, v178
	v_and_b32_e32 v83, s1, v178
	v_and_b32_e32 v88, s0, v179
	v_and_b32_e32 v89, s1, v179
	v_cvt_f32_ubyte2_e32 v102, v76
	v_cvt_f32_ubyte3_e32 v103, v76
	v_pk_fma_f32 v[80:81], v[40:41], v[98:99], v[80:81] op_sel_hi:[0,1,1]
	v_cvt_f32_ubyte0_e32 v104, v77
	v_cvt_f32_ubyte1_e32 v105, v77
	v_pk_fma_f32 v[78:79], v[40:41], v[102:103], v[78:79] op_sel_hi:[0,1,1]
	v_cvt_f32_ubyte2_e32 v146, v77
	v_cvt_f32_ubyte3_e32 v147, v77
	v_pk_fma_f32 v[70:71], v[48:49], v[104:105], v[70:71] op_sel_hi:[0,1,1]
	v_cvt_f32_ubyte0_e32 v98, v82
	v_cvt_f32_ubyte1_e32 v99, v82
	v_pk_fma_f32 v[62:63], v[48:49], v[146:147], v[62:63] op_sel_hi:[0,1,1]
	v_cvt_f32_ubyte2_e32 v102, v82
	v_cvt_f32_ubyte3_e32 v103, v82
	v_pk_fma_f32 v[92:93], v[40:41], v[98:99], v[92:93] op_sel:[1,0,0]
	v_cvt_f32_ubyte0_e32 v104, v83
	v_cvt_f32_ubyte1_e32 v105, v83
	v_pk_fma_f32 v[90:91], v[40:41], v[102:103], v[90:91] op_sel:[1,0,0]
	v_cvt_f32_ubyte2_e32 v146, v83
	v_cvt_f32_ubyte3_e32 v147, v83
	v_pk_fma_f32 v[86:87], v[48:49], v[104:105], v[86:87] op_sel:[1,0,0]
	v_cvt_f32_ubyte0_e32 v98, v88
	v_cvt_f32_ubyte1_e32 v99, v88
	v_pk_fma_f32 v[84:85], v[48:49], v[146:147], v[84:85] op_sel:[1,0,0]
	v_cvt_f32_ubyte2_e32 v102, v88
	v_cvt_f32_ubyte3_e32 v103, v88
	v_pk_fma_f32 v[80:81], v[40:41], v[98:99], v[80:81] op_sel:[1,0,0]
	v_cvt_f32_ubyte0_e32 v104, v89
	v_cvt_f32_ubyte1_e32 v105, v89
	v_pk_fma_f32 v[78:79], v[40:41], v[102:103], v[78:79] op_sel:[1,0,0]
	v_cvt_f32_ubyte2_e32 v146, v89
	v_cvt_f32_ubyte3_e32 v147, v89
	v_pk_fma_f32 v[70:71], v[48:49], v[104:105], v[70:71] op_sel:[1,0,0]
	v_pk_fma_f32 v[62:63], v[48:49], v[146:147], v[62:63] op_sel:[1,0,0]
	s_waitcnt lgkmcnt(0)
	v_lshl_add_u32 v72, v72, 9, v100
	v_lshl_add_u32 v73, v73, 9, v100
	v_lshl_add_u32 v74, v74, 9, v100
	v_lshl_add_u32 v75, v75, 9, v100
	v_lshl_add_u32 v94, v94, 9, v100
	v_lshl_add_u32 v95, v95, 9, v100
	v_lshl_add_u32 v96, v96, 9, v100
	v_lshl_add_u32 v97, v97, 9, v100
	global_load_dwordx2 v[164:165], v72, s[38:39]
	global_load_dwordx2 v[166:167], v73, s[38:39]
	global_load_dwordx2 v[168:169], v74, s[38:39]
	global_load_dwordx2 v[170:171], v75, s[38:39]
	global_load_dwordx2 v[172:173], v94, s[38:39]
	global_load_dwordx2 v[174:175], v95, s[38:39]
	global_load_dwordx2 v[176:177], v96, s[38:39]
	global_load_dwordx2 v[178:179], v97, s[38:39]
	ds_read_b128 v[72:75], v1 offset:416
	ds_read_b128 v[94:97], v1 offset:432
	ds_read_b128 v[34:37], v1 offset:768
	ds_read_b128 v[38:41], v1 offset:784
	ds_read_b128 v[42:45], v1 offset:1792
	ds_read_b128 v[46:49], v1 offset:1808
	s_waitcnt vmcnt(40)
	v_and_b32_e32 v68, s0, v180
	v_and_b32_e32 v69, s1, v180
	v_and_b32_e32 v76, s0, v181
	v_and_b32_e32 v77, s1, v181
	v_cvt_f32_ubyte0_e32 v98, v68
	v_cvt_f32_ubyte1_e32 v99, v68
	v_cvt_f32_ubyte2_e32 v102, v68
	v_cvt_f32_ubyte3_e32 v103, v68
	v_pk_fma_f32 v[92:93], v[50:51], v[98:99], v[92:93] op_sel_hi:[0,1,1]
	v_cvt_f32_ubyte0_e32 v104, v69
	v_cvt_f32_ubyte1_e32 v105, v69
	v_pk_fma_f32 v[90:91], v[50:51], v[102:103], v[90:91] op_sel_hi:[0,1,1]
	v_cvt_f32_ubyte2_e32 v146, v69
	v_cvt_f32_ubyte3_e32 v147, v69
	v_pk_fma_f32 v[86:87], v[58:59], v[104:105], v[86:87] op_sel_hi:[0,1,1]
	v_cvt_f32_ubyte0_e32 v98, v76
	v_cvt_f32_ubyte1_e32 v99, v76
	v_pk_fma_f32 v[84:85], v[58:59], v[146:147], v[84:85] op_sel_hi:[0,1,1]
	v_and_b32_e32 v82, s0, v182
	v_and_b32_e32 v83, s1, v182
	v_and_b32_e32 v88, s0, v183
	v_and_b32_e32 v89, s1, v183
	v_cvt_f32_ubyte2_e32 v102, v76
	v_cvt_f32_ubyte3_e32 v103, v76
	v_pk_fma_f32 v[80:81], v[50:51], v[98:99], v[80:81] op_sel_hi:[0,1,1]
	v_cvt_f32_ubyte0_e32 v104, v77
	v_cvt_f32_ubyte1_e32 v105, v77
	v_pk_fma_f32 v[78:79], v[50:51], v[102:103], v[78:79] op_sel_hi:[0,1,1]
	v_cvt_f32_ubyte2_e32 v146, v77
	v_cvt_f32_ubyte3_e32 v147, v77
	v_pk_fma_f32 v[70:71], v[58:59], v[104:105], v[70:71] op_sel_hi:[0,1,1]
	v_cvt_f32_ubyte0_e32 v98, v82
	v_cvt_f32_ubyte1_e32 v99, v82
	v_pk_fma_f32 v[62:63], v[58:59], v[146:147], v[62:63] op_sel_hi:[0,1,1]
	v_cvt_f32_ubyte2_e32 v102, v82
	v_cvt_f32_ubyte3_e32 v103, v82
	v_pk_fma_f32 v[92:93], v[50:51], v[98:99], v[92:93] op_sel:[1,0,0]
	v_cvt_f32_ubyte0_e32 v104, v83
	v_cvt_f32_ubyte1_e32 v105, v83
	v_pk_fma_f32 v[90:91], v[50:51], v[102:103], v[90:91] op_sel:[1,0,0]
	v_cvt_f32_ubyte2_e32 v146, v83
	v_cvt_f32_ubyte3_e32 v147, v83
	v_pk_fma_f32 v[86:87], v[58:59], v[104:105], v[86:87] op_sel:[1,0,0]
	v_cvt_f32_ubyte0_e32 v98, v88
	v_cvt_f32_ubyte1_e32 v99, v88
	v_pk_fma_f32 v[84:85], v[58:59], v[146:147], v[84:85] op_sel:[1,0,0]
	v_and_b32_e32 v68, s0, v184
	v_and_b32_e32 v69, s1, v184
	v_and_b32_e32 v76, s0, v185
	v_and_b32_e32 v77, s1, v185
	v_cvt_f32_ubyte2_e32 v102, v88
	v_cvt_f32_ubyte3_e32 v103, v88
	v_pk_fma_f32 v[80:81], v[50:51], v[98:99], v[80:81] op_sel:[1,0,0]
	v_cvt_f32_ubyte0_e32 v104, v89
	v_cvt_f32_ubyte1_e32 v105, v89
	v_pk_fma_f32 v[78:79], v[50:51], v[102:103], v[78:79] op_sel:[1,0,0]
	v_cvt_f32_ubyte2_e32 v146, v89
	v_cvt_f32_ubyte3_e32 v147, v89
	v_pk_fma_f32 v[70:71], v[58:59], v[104:105], v[70:71] op_sel:[1,0,0]
	v_cvt_f32_ubyte0_e32 v98, v68
	v_cvt_f32_ubyte1_e32 v99, v68
	v_pk_fma_f32 v[62:63], v[58:59], v[146:147], v[62:63] op_sel:[1,0,0]
	v_cvt_f32_ubyte2_e32 v102, v68
	v_cvt_f32_ubyte3_e32 v103, v68
	v_pk_fma_f32 v[92:93], v[52:53], v[98:99], v[92:93] op_sel_hi:[0,1,1]
	v_cvt_f32_ubyte0_e32 v104, v69
	v_cvt_f32_ubyte1_e32 v105, v69
	v_pk_fma_f32 v[90:91], v[52:53], v[102:103], v[90:91] op_sel_hi:[0,1,1]
	v_cvt_f32_ubyte2_e32 v146, v69
	v_cvt_f32_ubyte3_e32 v147, v69
	v_pk_fma_f32 v[86:87], v[60:61], v[104:105], v[86:87] op_sel_hi:[0,1,1]
	v_cvt_f32_ubyte0_e32 v98, v76
	v_cvt_f32_ubyte1_e32 v99, v76
	v_pk_fma_f32 v[84:85], v[60:61], v[146:147], v[84:85] op_sel_hi:[0,1,1]
	v_and_b32_e32 v82, s0, v186
	v_and_b32_e32 v83, s1, v186
	v_and_b32_e32 v88, s0, v187
	v_and_b32_e32 v89, s1, v187
	v_cvt_f32_ubyte2_e32 v102, v76
	v_cvt_f32_ubyte3_e32 v103, v76
	v_pk_fma_f32 v[80:81], v[52:53], v[98:99], v[80:81] op_sel_hi:[0,1,1]
	v_cvt_f32_ubyte0_e32 v104, v77
	v_cvt_f32_ubyte1_e32 v105, v77
	v_pk_fma_f32 v[78:79], v[52:53], v[102:103], v[78:79] op_sel_hi:[0,1,1]
	v_cvt_f32_ubyte2_e32 v146, v77
	v_cvt_f32_ubyte3_e32 v147, v77
	v_pk_fma_f32 v[70:71], v[60:61], v[104:105], v[70:71] op_sel_hi:[0,1,1]
	v_cvt_f32_ubyte0_e32 v98, v82
	v_cvt_f32_ubyte1_e32 v99, v82
	v_pk_fma_f32 v[62:63], v[60:61], v[146:147], v[62:63] op_sel_hi:[0,1,1]
	v_cvt_f32_ubyte2_e32 v102, v82
	v_cvt_f32_ubyte3_e32 v103, v82
	v_pk_fma_f32 v[92:93], v[52:53], v[98:99], v[92:93] op_sel:[1,0,0]
	v_cvt_f32_ubyte0_e32 v104, v83
	v_cvt_f32_ubyte1_e32 v105, v83
	v_pk_fma_f32 v[90:91], v[52:53], v[102:103], v[90:91] op_sel:[1,0,0]
	v_cvt_f32_ubyte2_e32 v146, v83
	v_cvt_f32_ubyte3_e32 v147, v83
	v_pk_fma_f32 v[86:87], v[60:61], v[104:105], v[86:87] op_sel:[1,0,0]
	v_cvt_f32_ubyte0_e32 v98, v88
	v_cvt_f32_ubyte1_e32 v99, v88
	v_pk_fma_f32 v[84:85], v[60:61], v[146:147], v[84:85] op_sel:[1,0,0]
	v_and_b32_e32 v68, s0, v188
	v_and_b32_e32 v69, s1, v188
	v_and_b32_e32 v76, s0, v189
	v_and_b32_e32 v77, s1, v189
	v_cvt_f32_ubyte2_e32 v102, v88
	v_cvt_f32_ubyte3_e32 v103, v88
	v_pk_fma_f32 v[80:81], v[52:53], v[98:99], v[80:81] op_sel:[1,0,0]
	v_cvt_f32_ubyte0_e32 v104, v89
	v_cvt_f32_ubyte1_e32 v105, v89
	v_pk_fma_f32 v[78:79], v[52:53], v[102:103], v[78:79] op_sel:[1,0,0]
	v_cvt_f32_ubyte2_e32 v146, v89
	v_cvt_f32_ubyte3_e32 v147, v89
	v_pk_fma_f32 v[70:71], v[60:61], v[104:105], v[70:71] op_sel:[1,0,0]
	v_cvt_f32_ubyte0_e32 v98, v68
	v_cvt_f32_ubyte1_e32 v99, v68
	v_pk_fma_f32 v[62:63], v[60:61], v[146:147], v[62:63] op_sel:[1,0,0]
	v_cvt_f32_ubyte2_e32 v102, v68
	v_cvt_f32_ubyte3_e32 v103, v68
	v_pk_fma_f32 v[92:93], v[54:55], v[98:99], v[92:93] op_sel_hi:[0,1,1]
	v_cvt_f32_ubyte0_e32 v104, v69
	v_cvt_f32_ubyte1_e32 v105, v69
	v_pk_fma_f32 v[90:91], v[54:55], v[102:103], v[90:91] op_sel_hi:[0,1,1]
	v_cvt_f32_ubyte2_e32 v146, v69
	v_cvt_f32_ubyte3_e32 v147, v69
	v_pk_fma_f32 v[86:87], v[64:65], v[104:105], v[86:87] op_sel_hi:[0,1,1]
	v_cvt_f32_ubyte0_e32 v98, v76
	v_cvt_f32_ubyte1_e32 v99, v76
	v_pk_fma_f32 v[84:85], v[64:65], v[146:147], v[84:85] op_sel_hi:[0,1,1]
	v_and_b32_e32 v82, s0, v190
	v_and_b32_e32 v83, s1, v190
	v_and_b32_e32 v88, s0, v191
	v_and_b32_e32 v89, s1, v191
	v_cvt_f32_ubyte2_e32 v102, v76
	v_cvt_f32_ubyte3_e32 v103, v76
	v_pk_fma_f32 v[80:81], v[54:55], v[98:99], v[80:81] op_sel_hi:[0,1,1]
	v_cvt_f32_ubyte0_e32 v104, v77
	v_cvt_f32_ubyte1_e32 v105, v77
	v_pk_fma_f32 v[78:79], v[54:55], v[102:103], v[78:79] op_sel_hi:[0,1,1]
	v_cvt_f32_ubyte2_e32 v146, v77
	v_cvt_f32_ubyte3_e32 v147, v77
	v_pk_fma_f32 v[70:71], v[64:65], v[104:105], v[70:71] op_sel_hi:[0,1,1]
	v_cvt_f32_ubyte0_e32 v98, v82
	v_cvt_f32_ubyte1_e32 v99, v82
	v_pk_fma_f32 v[62:63], v[64:65], v[146:147], v[62:63] op_sel_hi:[0,1,1]
	v_cvt_f32_ubyte2_e32 v102, v82
	v_cvt_f32_ubyte3_e32 v103, v82
	v_pk_fma_f32 v[92:93], v[54:55], v[98:99], v[92:93] op_sel:[1,0,0]
	v_cvt_f32_ubyte0_e32 v104, v83
	v_cvt_f32_ubyte1_e32 v105, v83
	v_pk_fma_f32 v[90:91], v[54:55], v[102:103], v[90:91] op_sel:[1,0,0]
	v_cvt_f32_ubyte2_e32 v146, v83
	v_cvt_f32_ubyte3_e32 v147, v83
	v_pk_fma_f32 v[86:87], v[64:65], v[104:105], v[86:87] op_sel:[1,0,0]
	v_cvt_f32_ubyte0_e32 v98, v88
	v_cvt_f32_ubyte1_e32 v99, v88
	v_pk_fma_f32 v[84:85], v[64:65], v[146:147], v[84:85] op_sel:[1,0,0]
	v_and_b32_e32 v68, s0, v192
	v_and_b32_e32 v69, s1, v192
	v_and_b32_e32 v76, s0, v193
	v_and_b32_e32 v77, s1, v193
	v_cvt_f32_ubyte2_e32 v102, v88
	v_cvt_f32_ubyte3_e32 v103, v88
	v_pk_fma_f32 v[80:81], v[54:55], v[98:99], v[80:81] op_sel:[1,0,0]
	v_cvt_f32_ubyte0_e32 v104, v89
	v_cvt_f32_ubyte1_e32 v105, v89
	v_pk_fma_f32 v[78:79], v[54:55], v[102:103], v[78:79] op_sel:[1,0,0]
	v_cvt_f32_ubyte2_e32 v146, v89
	v_cvt_f32_ubyte3_e32 v147, v89
	v_pk_fma_f32 v[70:71], v[64:65], v[104:105], v[70:71] op_sel:[1,0,0]
	v_cvt_f32_ubyte0_e32 v98, v68
	v_cvt_f32_ubyte1_e32 v99, v68
	v_pk_fma_f32 v[62:63], v[64:65], v[146:147], v[62:63] op_sel:[1,0,0]
	v_cvt_f32_ubyte2_e32 v102, v68
	v_cvt_f32_ubyte3_e32 v103, v68
	v_pk_fma_f32 v[92:93], v[56:57], v[98:99], v[92:93] op_sel_hi:[0,1,1]
	v_cvt_f32_ubyte0_e32 v104, v69
	v_cvt_f32_ubyte1_e32 v105, v69
	v_pk_fma_f32 v[90:91], v[56:57], v[102:103], v[90:91] op_sel_hi:[0,1,1]
	v_cvt_f32_ubyte2_e32 v146, v69
	v_cvt_f32_ubyte3_e32 v147, v69
	v_pk_fma_f32 v[86:87], v[66:67], v[104:105], v[86:87] op_sel_hi:[0,1,1]
	v_cvt_f32_ubyte0_e32 v98, v76
	v_cvt_f32_ubyte1_e32 v99, v76
	v_pk_fma_f32 v[84:85], v[66:67], v[146:147], v[84:85] op_sel_hi:[0,1,1]
	v_and_b32_e32 v82, s0, v194
	v_and_b32_e32 v83, s1, v194
	v_and_b32_e32 v88, s0, v195
	v_and_b32_e32 v89, s1, v195
	v_cvt_f32_ubyte2_e32 v102, v76
	v_cvt_f32_ubyte3_e32 v103, v76
	v_pk_fma_f32 v[80:81], v[56:57], v[98:99], v[80:81] op_sel_hi:[0,1,1]
	v_cvt_f32_ubyte0_e32 v104, v77
	v_cvt_f32_ubyte1_e32 v105, v77
	v_pk_fma_f32 v[78:79], v[56:57], v[102:103], v[78:79] op_sel_hi:[0,1,1]
	v_cvt_f32_ubyte2_e32 v146, v77
	v_cvt_f32_ubyte3_e32 v147, v77
	v_pk_fma_f32 v[70:71], v[66:67], v[104:105], v[70:71] op_sel_hi:[0,1,1]
	v_cvt_f32_ubyte0_e32 v98, v82
	v_cvt_f32_ubyte1_e32 v99, v82
	v_pk_fma_f32 v[62:63], v[66:67], v[146:147], v[62:63] op_sel_hi:[0,1,1]
	v_cvt_f32_ubyte2_e32 v102, v82
	v_cvt_f32_ubyte3_e32 v103, v82
	v_pk_fma_f32 v[92:93], v[56:57], v[98:99], v[92:93] op_sel:[1,0,0]
	v_cvt_f32_ubyte0_e32 v104, v83
	v_cvt_f32_ubyte1_e32 v105, v83
	v_pk_fma_f32 v[90:91], v[56:57], v[102:103], v[90:91] op_sel:[1,0,0]
	v_cvt_f32_ubyte2_e32 v146, v83
	v_cvt_f32_ubyte3_e32 v147, v83
	v_pk_fma_f32 v[86:87], v[66:67], v[104:105], v[86:87] op_sel:[1,0,0]
	v_cvt_f32_ubyte0_e32 v98, v88
	v_cvt_f32_ubyte1_e32 v99, v88
	v_pk_fma_f32 v[84:85], v[66:67], v[146:147], v[84:85] op_sel:[1,0,0]
	v_cvt_f32_ubyte2_e32 v102, v88
	v_cvt_f32_ubyte3_e32 v103, v88
	v_pk_fma_f32 v[80:81], v[56:57], v[98:99], v[80:81] op_sel:[1,0,0]
	v_cvt_f32_ubyte0_e32 v104, v89
	v_cvt_f32_ubyte1_e32 v105, v89
	v_pk_fma_f32 v[78:79], v[56:57], v[102:103], v[78:79] op_sel:[1,0,0]
	v_cvt_f32_ubyte2_e32 v146, v89
	v_cvt_f32_ubyte3_e32 v147, v89
	v_pk_fma_f32 v[70:71], v[66:67], v[104:105], v[70:71] op_sel:[1,0,0]
	v_pk_fma_f32 v[62:63], v[66:67], v[146:147], v[62:63] op_sel:[1,0,0]
	s_waitcnt lgkmcnt(0)
	v_lshl_add_u32 v72, v72, 9, v100
	v_lshl_add_u32 v73, v73, 9, v100
	v_lshl_add_u32 v74, v74, 9, v100
	v_lshl_add_u32 v75, v75, 9, v100
	v_lshl_add_u32 v94, v94, 9, v100
	v_lshl_add_u32 v95, v95, 9, v100
	v_lshl_add_u32 v96, v96, 9, v100
	v_lshl_add_u32 v97, v97, 9, v100
	global_load_dwordx2 v[180:181], v72, s[38:39]
	global_load_dwordx2 v[182:183], v73, s[38:39]
	global_load_dwordx2 v[184:185], v74, s[38:39]
	global_load_dwordx2 v[186:187], v75, s[38:39]
	global_load_dwordx2 v[188:189], v94, s[38:39]
	global_load_dwordx2 v[190:191], v95, s[38:39]
	global_load_dwordx2 v[192:193], v96, s[38:39]
	global_load_dwordx2 v[194:195], v97, s[38:39]
	ds_read_b128 v[72:75], v1 offset:448
	ds_read_b128 v[94:97], v1 offset:464
	ds_read_b128 v[50:53], v1 offset:800
	ds_read_b128 v[54:57], v1 offset:816
	ds_read_b128 v[58:61], v1 offset:1824
	ds_read_b128 v[64:67], v1 offset:1840
	s_waitcnt vmcnt(40)
	v_and_b32_e32 v68, s0, v196
	v_and_b32_e32 v69, s1, v196
	v_and_b32_e32 v76, s0, v197
	v_and_b32_e32 v77, s1, v197
	v_cvt_f32_ubyte0_e32 v98, v68
	v_cvt_f32_ubyte1_e32 v99, v68
	v_cvt_f32_ubyte2_e32 v102, v68
	v_cvt_f32_ubyte3_e32 v103, v68
	v_pk_fma_f32 v[92:93], v[34:35], v[98:99], v[92:93] op_sel_hi:[0,1,1]
	v_cvt_f32_ubyte0_e32 v104, v69
	v_cvt_f32_ubyte1_e32 v105, v69
	v_pk_fma_f32 v[90:91], v[34:35], v[102:103], v[90:91] op_sel_hi:[0,1,1]
	v_cvt_f32_ubyte2_e32 v146, v69
	v_cvt_f32_ubyte3_e32 v147, v69
	v_pk_fma_f32 v[86:87], v[42:43], v[104:105], v[86:87] op_sel_hi:[0,1,1]
	v_cvt_f32_ubyte0_e32 v98, v76
	v_cvt_f32_ubyte1_e32 v99, v76
	v_pk_fma_f32 v[84:85], v[42:43], v[146:147], v[84:85] op_sel_hi:[0,1,1]
	v_and_b32_e32 v82, s0, v198
	v_and_b32_e32 v83, s1, v198
	v_and_b32_e32 v88, s0, v199
	v_and_b32_e32 v89, s1, v199
	v_cvt_f32_ubyte2_e32 v102, v76
	v_cvt_f32_ubyte3_e32 v103, v76
	v_pk_fma_f32 v[80:81], v[34:35], v[98:99], v[80:81] op_sel_hi:[0,1,1]
	v_cvt_f32_ubyte0_e32 v104, v77
	v_cvt_f32_ubyte1_e32 v105, v77
	v_pk_fma_f32 v[78:79], v[34:35], v[102:103], v[78:79] op_sel_hi:[0,1,1]
	v_cvt_f32_ubyte2_e32 v146, v77
	v_cvt_f32_ubyte3_e32 v147, v77
	v_pk_fma_f32 v[70:71], v[42:43], v[104:105], v[70:71] op_sel_hi:[0,1,1]
	v_cvt_f32_ubyte0_e32 v98, v82
	v_cvt_f32_ubyte1_e32 v99, v82
	v_pk_fma_f32 v[62:63], v[42:43], v[146:147], v[62:63] op_sel_hi:[0,1,1]
	v_cvt_f32_ubyte2_e32 v102, v82
	v_cvt_f32_ubyte3_e32 v103, v82
	v_pk_fma_f32 v[92:93], v[34:35], v[98:99], v[92:93] op_sel:[1,0,0]
	v_cvt_f32_ubyte0_e32 v104, v83
	v_cvt_f32_ubyte1_e32 v105, v83
	v_pk_fma_f32 v[90:91], v[34:35], v[102:103], v[90:91] op_sel:[1,0,0]
	v_cvt_f32_ubyte2_e32 v146, v83
	v_cvt_f32_ubyte3_e32 v147, v83
	v_pk_fma_f32 v[86:87], v[42:43], v[104:105], v[86:87] op_sel:[1,0,0]
	v_cvt_f32_ubyte0_e32 v98, v88
	v_cvt_f32_ubyte1_e32 v99, v88
	v_pk_fma_f32 v[84:85], v[42:43], v[146:147], v[84:85] op_sel:[1,0,0]
	v_and_b32_e32 v68, s0, v200
	v_and_b32_e32 v69, s1, v200
	v_and_b32_e32 v76, s0, v201
	v_and_b32_e32 v77, s1, v201
	v_cvt_f32_ubyte2_e32 v102, v88
	v_cvt_f32_ubyte3_e32 v103, v88
	v_pk_fma_f32 v[80:81], v[34:35], v[98:99], v[80:81] op_sel:[1,0,0]
	v_cvt_f32_ubyte0_e32 v104, v89
	v_cvt_f32_ubyte1_e32 v105, v89
	v_pk_fma_f32 v[78:79], v[34:35], v[102:103], v[78:79] op_sel:[1,0,0]
	v_cvt_f32_ubyte2_e32 v146, v89
	v_cvt_f32_ubyte3_e32 v147, v89
	v_pk_fma_f32 v[70:71], v[42:43], v[104:105], v[70:71] op_sel:[1,0,0]
	v_cvt_f32_ubyte0_e32 v98, v68
	v_cvt_f32_ubyte1_e32 v99, v68
	v_pk_fma_f32 v[62:63], v[42:43], v[146:147], v[62:63] op_sel:[1,0,0]
	v_cvt_f32_ubyte2_e32 v102, v68
	v_cvt_f32_ubyte3_e32 v103, v68
	v_pk_fma_f32 v[92:93], v[36:37], v[98:99], v[92:93] op_sel_hi:[0,1,1]
	v_cvt_f32_ubyte0_e32 v104, v69
	v_cvt_f32_ubyte1_e32 v105, v69
	v_pk_fma_f32 v[90:91], v[36:37], v[102:103], v[90:91] op_sel_hi:[0,1,1]
	v_cvt_f32_ubyte2_e32 v146, v69
	v_cvt_f32_ubyte3_e32 v147, v69
	v_pk_fma_f32 v[86:87], v[44:45], v[104:105], v[86:87] op_sel_hi:[0,1,1]
	v_cvt_f32_ubyte0_e32 v98, v76
	v_cvt_f32_ubyte1_e32 v99, v76
	v_pk_fma_f32 v[84:85], v[44:45], v[146:147], v[84:85] op_sel_hi:[0,1,1]
	v_and_b32_e32 v82, s0, v202
	v_and_b32_e32 v83, s1, v202
	v_and_b32_e32 v88, s0, v203
	v_and_b32_e32 v89, s1, v203
	v_cvt_f32_ubyte2_e32 v102, v76
	v_cvt_f32_ubyte3_e32 v103, v76
	v_pk_fma_f32 v[80:81], v[36:37], v[98:99], v[80:81] op_sel_hi:[0,1,1]
	v_cvt_f32_ubyte0_e32 v104, v77
	v_cvt_f32_ubyte1_e32 v105, v77
	v_pk_fma_f32 v[78:79], v[36:37], v[102:103], v[78:79] op_sel_hi:[0,1,1]
	v_cvt_f32_ubyte2_e32 v146, v77
	v_cvt_f32_ubyte3_e32 v147, v77
	v_pk_fma_f32 v[70:71], v[44:45], v[104:105], v[70:71] op_sel_hi:[0,1,1]
	v_cvt_f32_ubyte0_e32 v98, v82
	v_cvt_f32_ubyte1_e32 v99, v82
	v_pk_fma_f32 v[62:63], v[44:45], v[146:147], v[62:63] op_sel_hi:[0,1,1]
	v_cvt_f32_ubyte2_e32 v102, v82
	v_cvt_f32_ubyte3_e32 v103, v82
	v_pk_fma_f32 v[92:93], v[36:37], v[98:99], v[92:93] op_sel:[1,0,0]
	v_cvt_f32_ubyte0_e32 v104, v83
	v_cvt_f32_ubyte1_e32 v105, v83
	v_pk_fma_f32 v[90:91], v[36:37], v[102:103], v[90:91] op_sel:[1,0,0]
	v_cvt_f32_ubyte2_e32 v146, v83
	v_cvt_f32_ubyte3_e32 v147, v83
	v_pk_fma_f32 v[86:87], v[44:45], v[104:105], v[86:87] op_sel:[1,0,0]
	v_cvt_f32_ubyte0_e32 v98, v88
	v_cvt_f32_ubyte1_e32 v99, v88
	v_pk_fma_f32 v[84:85], v[44:45], v[146:147], v[84:85] op_sel:[1,0,0]
	v_and_b32_e32 v68, s0, v204
	v_and_b32_e32 v69, s1, v204
	v_and_b32_e32 v76, s0, v205
	v_and_b32_e32 v77, s1, v205
	v_cvt_f32_ubyte2_e32 v102, v88
	v_cvt_f32_ubyte3_e32 v103, v88
	v_pk_fma_f32 v[80:81], v[36:37], v[98:99], v[80:81] op_sel:[1,0,0]
	v_cvt_f32_ubyte0_e32 v104, v89
	v_cvt_f32_ubyte1_e32 v105, v89
	v_pk_fma_f32 v[78:79], v[36:37], v[102:103], v[78:79] op_sel:[1,0,0]
	v_cvt_f32_ubyte2_e32 v146, v89
	v_cvt_f32_ubyte3_e32 v147, v89
	v_pk_fma_f32 v[70:71], v[44:45], v[104:105], v[70:71] op_sel:[1,0,0]
	v_cvt_f32_ubyte0_e32 v98, v68
	v_cvt_f32_ubyte1_e32 v99, v68
	v_pk_fma_f32 v[62:63], v[44:45], v[146:147], v[62:63] op_sel:[1,0,0]
	v_cvt_f32_ubyte2_e32 v102, v68
	v_cvt_f32_ubyte3_e32 v103, v68
	v_pk_fma_f32 v[92:93], v[38:39], v[98:99], v[92:93] op_sel_hi:[0,1,1]
	v_cvt_f32_ubyte0_e32 v104, v69
	v_cvt_f32_ubyte1_e32 v105, v69
	v_pk_fma_f32 v[90:91], v[38:39], v[102:103], v[90:91] op_sel_hi:[0,1,1]
	v_cvt_f32_ubyte2_e32 v146, v69
	v_cvt_f32_ubyte3_e32 v147, v69
	v_pk_fma_f32 v[86:87], v[46:47], v[104:105], v[86:87] op_sel_hi:[0,1,1]
	v_cvt_f32_ubyte0_e32 v98, v76
	v_cvt_f32_ubyte1_e32 v99, v76
	v_pk_fma_f32 v[84:85], v[46:47], v[146:147], v[84:85] op_sel_hi:[0,1,1]
	v_and_b32_e32 v82, s0, v206
	v_and_b32_e32 v83, s1, v206
	v_and_b32_e32 v88, s0, v207
	v_and_b32_e32 v89, s1, v207
	v_cvt_f32_ubyte2_e32 v102, v76
	v_cvt_f32_ubyte3_e32 v103, v76
	v_pk_fma_f32 v[80:81], v[38:39], v[98:99], v[80:81] op_sel_hi:[0,1,1]
	v_cvt_f32_ubyte0_e32 v104, v77
	v_cvt_f32_ubyte1_e32 v105, v77
	v_pk_fma_f32 v[78:79], v[38:39], v[102:103], v[78:79] op_sel_hi:[0,1,1]
	v_cvt_f32_ubyte2_e32 v146, v77
	v_cvt_f32_ubyte3_e32 v147, v77
	v_pk_fma_f32 v[70:71], v[46:47], v[104:105], v[70:71] op_sel_hi:[0,1,1]
	v_cvt_f32_ubyte0_e32 v98, v82
	v_cvt_f32_ubyte1_e32 v99, v82
	v_pk_fma_f32 v[62:63], v[46:47], v[146:147], v[62:63] op_sel_hi:[0,1,1]
	v_cvt_f32_ubyte2_e32 v102, v82
	v_cvt_f32_ubyte3_e32 v103, v82
	v_pk_fma_f32 v[92:93], v[38:39], v[98:99], v[92:93] op_sel:[1,0,0]
	v_cvt_f32_ubyte0_e32 v104, v83
	v_cvt_f32_ubyte1_e32 v105, v83
	v_pk_fma_f32 v[90:91], v[38:39], v[102:103], v[90:91] op_sel:[1,0,0]
	v_cvt_f32_ubyte2_e32 v146, v83
	v_cvt_f32_ubyte3_e32 v147, v83
	v_pk_fma_f32 v[86:87], v[46:47], v[104:105], v[86:87] op_sel:[1,0,0]
	v_cvt_f32_ubyte0_e32 v98, v88
	v_cvt_f32_ubyte1_e32 v99, v88
	v_pk_fma_f32 v[84:85], v[46:47], v[146:147], v[84:85] op_sel:[1,0,0]
	v_and_b32_e32 v68, s0, v208
	v_and_b32_e32 v69, s1, v208
	v_and_b32_e32 v76, s0, v209
	v_and_b32_e32 v77, s1, v209
	v_cvt_f32_ubyte2_e32 v102, v88
	v_cvt_f32_ubyte3_e32 v103, v88
	v_pk_fma_f32 v[80:81], v[38:39], v[98:99], v[80:81] op_sel:[1,0,0]
	v_cvt_f32_ubyte0_e32 v104, v89
	v_cvt_f32_ubyte1_e32 v105, v89
	v_pk_fma_f32 v[78:79], v[38:39], v[102:103], v[78:79] op_sel:[1,0,0]
	v_cvt_f32_ubyte2_e32 v146, v89
	v_cvt_f32_ubyte3_e32 v147, v89
	v_pk_fma_f32 v[70:71], v[46:47], v[104:105], v[70:71] op_sel:[1,0,0]
	v_cvt_f32_ubyte0_e32 v98, v68
	v_cvt_f32_ubyte1_e32 v99, v68
	v_pk_fma_f32 v[62:63], v[46:47], v[146:147], v[62:63] op_sel:[1,0,0]
	v_cvt_f32_ubyte2_e32 v102, v68
	v_cvt_f32_ubyte3_e32 v103, v68
	v_pk_fma_f32 v[92:93], v[40:41], v[98:99], v[92:93] op_sel_hi:[0,1,1]
	v_cvt_f32_ubyte0_e32 v104, v69
	v_cvt_f32_ubyte1_e32 v105, v69
	v_pk_fma_f32 v[90:91], v[40:41], v[102:103], v[90:91] op_sel_hi:[0,1,1]
	v_cvt_f32_ubyte2_e32 v146, v69
	v_cvt_f32_ubyte3_e32 v147, v69
	v_pk_fma_f32 v[86:87], v[48:49], v[104:105], v[86:87] op_sel_hi:[0,1,1]
	v_cvt_f32_ubyte0_e32 v98, v76
	v_cvt_f32_ubyte1_e32 v99, v76
	v_pk_fma_f32 v[84:85], v[48:49], v[146:147], v[84:85] op_sel_hi:[0,1,1]
	v_and_b32_e32 v82, s0, v210
	v_and_b32_e32 v83, s1, v210
	v_and_b32_e32 v88, s0, v211
	v_and_b32_e32 v89, s1, v211
	v_cvt_f32_ubyte2_e32 v102, v76
	v_cvt_f32_ubyte3_e32 v103, v76
	v_pk_fma_f32 v[80:81], v[40:41], v[98:99], v[80:81] op_sel_hi:[0,1,1]
	v_cvt_f32_ubyte0_e32 v104, v77
	v_cvt_f32_ubyte1_e32 v105, v77
	v_pk_fma_f32 v[78:79], v[40:41], v[102:103], v[78:79] op_sel_hi:[0,1,1]
	v_cvt_f32_ubyte2_e32 v146, v77
	v_cvt_f32_ubyte3_e32 v147, v77
	v_pk_fma_f32 v[70:71], v[48:49], v[104:105], v[70:71] op_sel_hi:[0,1,1]
	v_cvt_f32_ubyte0_e32 v98, v82
	v_cvt_f32_ubyte1_e32 v99, v82
	v_pk_fma_f32 v[62:63], v[48:49], v[146:147], v[62:63] op_sel_hi:[0,1,1]
	v_cvt_f32_ubyte2_e32 v102, v82
	v_cvt_f32_ubyte3_e32 v103, v82
	v_pk_fma_f32 v[92:93], v[40:41], v[98:99], v[92:93] op_sel:[1,0,0]
	v_cvt_f32_ubyte0_e32 v104, v83
	v_cvt_f32_ubyte1_e32 v105, v83
	v_pk_fma_f32 v[90:91], v[40:41], v[102:103], v[90:91] op_sel:[1,0,0]
	v_cvt_f32_ubyte2_e32 v146, v83
	v_cvt_f32_ubyte3_e32 v147, v83
	v_pk_fma_f32 v[86:87], v[48:49], v[104:105], v[86:87] op_sel:[1,0,0]
	v_cvt_f32_ubyte0_e32 v98, v88
	v_cvt_f32_ubyte1_e32 v99, v88
	v_pk_fma_f32 v[84:85], v[48:49], v[146:147], v[84:85] op_sel:[1,0,0]
	v_cvt_f32_ubyte2_e32 v102, v88
	v_cvt_f32_ubyte3_e32 v103, v88
	v_pk_fma_f32 v[80:81], v[40:41], v[98:99], v[80:81] op_sel:[1,0,0]
	v_cvt_f32_ubyte0_e32 v104, v89
	v_cvt_f32_ubyte1_e32 v105, v89
	v_pk_fma_f32 v[78:79], v[40:41], v[102:103], v[78:79] op_sel:[1,0,0]
	v_cvt_f32_ubyte2_e32 v146, v89
	v_cvt_f32_ubyte3_e32 v147, v89
	v_pk_fma_f32 v[70:71], v[48:49], v[104:105], v[70:71] op_sel:[1,0,0]
	v_pk_fma_f32 v[62:63], v[48:49], v[146:147], v[62:63] op_sel:[1,0,0]
	s_waitcnt lgkmcnt(0)
	v_lshl_add_u32 v72, v72, 9, v100
	v_lshl_add_u32 v73, v73, 9, v100
	v_lshl_add_u32 v74, v74, 9, v100
	v_lshl_add_u32 v75, v75, 9, v100
	v_lshl_add_u32 v94, v94, 9, v100
	v_lshl_add_u32 v95, v95, 9, v100
	v_lshl_add_u32 v96, v96, 9, v100
	v_lshl_add_u32 v97, v97, 9, v100
	global_load_dwordx2 v[196:197], v72, s[38:39]
	global_load_dwordx2 v[198:199], v73, s[38:39]
	global_load_dwordx2 v[200:201], v74, s[38:39]
	global_load_dwordx2 v[202:203], v75, s[38:39]
	global_load_dwordx2 v[204:205], v94, s[38:39]
	global_load_dwordx2 v[206:207], v95, s[38:39]
	global_load_dwordx2 v[208:209], v96, s[38:39]
	global_load_dwordx2 v[210:211], v97, s[38:39]
	ds_read_b128 v[72:75], v1 offset:480
	ds_read_b128 v[94:97], v1 offset:496
	ds_read_b128 v[34:37], v1 offset:832
	ds_read_b128 v[38:41], v1 offset:848
	ds_read_b128 v[42:45], v1 offset:1856
	ds_read_b128 v[46:49], v1 offset:1872
	s_waitcnt vmcnt(40)
	v_and_b32_e32 v68, s0, v212
	v_and_b32_e32 v69, s1, v212
	v_and_b32_e32 v76, s0, v213
	v_and_b32_e32 v77, s1, v213
	v_cvt_f32_ubyte0_e32 v98, v68
	v_cvt_f32_ubyte1_e32 v99, v68
	v_cvt_f32_ubyte2_e32 v102, v68
	v_cvt_f32_ubyte3_e32 v103, v68
	v_pk_fma_f32 v[92:93], v[50:51], v[98:99], v[92:93] op_sel_hi:[0,1,1]
	v_cvt_f32_ubyte0_e32 v104, v69
	v_cvt_f32_ubyte1_e32 v105, v69
	v_pk_fma_f32 v[90:91], v[50:51], v[102:103], v[90:91] op_sel_hi:[0,1,1]
	v_cvt_f32_ubyte2_e32 v146, v69
	v_cvt_f32_ubyte3_e32 v147, v69
	v_pk_fma_f32 v[86:87], v[58:59], v[104:105], v[86:87] op_sel_hi:[0,1,1]
	v_cvt_f32_ubyte0_e32 v98, v76
	v_cvt_f32_ubyte1_e32 v99, v76
	v_pk_fma_f32 v[84:85], v[58:59], v[146:147], v[84:85] op_sel_hi:[0,1,1]
	v_and_b32_e32 v82, s0, v214
	v_and_b32_e32 v83, s1, v214
	v_and_b32_e32 v88, s0, v215
	v_and_b32_e32 v89, s1, v215
	v_cvt_f32_ubyte2_e32 v102, v76
	v_cvt_f32_ubyte3_e32 v103, v76
	v_pk_fma_f32 v[80:81], v[50:51], v[98:99], v[80:81] op_sel_hi:[0,1,1]
	v_cvt_f32_ubyte0_e32 v104, v77
	v_cvt_f32_ubyte1_e32 v105, v77
	v_pk_fma_f32 v[78:79], v[50:51], v[102:103], v[78:79] op_sel_hi:[0,1,1]
	v_cvt_f32_ubyte2_e32 v146, v77
	v_cvt_f32_ubyte3_e32 v147, v77
	v_pk_fma_f32 v[70:71], v[58:59], v[104:105], v[70:71] op_sel_hi:[0,1,1]
	v_cvt_f32_ubyte0_e32 v98, v82
	v_cvt_f32_ubyte1_e32 v99, v82
	v_pk_fma_f32 v[62:63], v[58:59], v[146:147], v[62:63] op_sel_hi:[0,1,1]
	v_cvt_f32_ubyte2_e32 v102, v82
	v_cvt_f32_ubyte3_e32 v103, v82
	v_pk_fma_f32 v[92:93], v[50:51], v[98:99], v[92:93] op_sel:[1,0,0]
	v_cvt_f32_ubyte0_e32 v104, v83
	v_cvt_f32_ubyte1_e32 v105, v83
	v_pk_fma_f32 v[90:91], v[50:51], v[102:103], v[90:91] op_sel:[1,0,0]
	v_cvt_f32_ubyte2_e32 v146, v83
	v_cvt_f32_ubyte3_e32 v147, v83
	v_pk_fma_f32 v[86:87], v[58:59], v[104:105], v[86:87] op_sel:[1,0,0]
	v_cvt_f32_ubyte0_e32 v98, v88
	v_cvt_f32_ubyte1_e32 v99, v88
	v_pk_fma_f32 v[84:85], v[58:59], v[146:147], v[84:85] op_sel:[1,0,0]
	v_and_b32_e32 v68, s0, v216
	v_and_b32_e32 v69, s1, v216
	v_and_b32_e32 v76, s0, v217
	v_and_b32_e32 v77, s1, v217
	v_cvt_f32_ubyte2_e32 v102, v88
	v_cvt_f32_ubyte3_e32 v103, v88
	v_pk_fma_f32 v[80:81], v[50:51], v[98:99], v[80:81] op_sel:[1,0,0]
	v_cvt_f32_ubyte0_e32 v104, v89
	v_cvt_f32_ubyte1_e32 v105, v89
	v_pk_fma_f32 v[78:79], v[50:51], v[102:103], v[78:79] op_sel:[1,0,0]
	v_cvt_f32_ubyte2_e32 v146, v89
	v_cvt_f32_ubyte3_e32 v147, v89
	v_pk_fma_f32 v[70:71], v[58:59], v[104:105], v[70:71] op_sel:[1,0,0]
	v_cvt_f32_ubyte0_e32 v98, v68
	v_cvt_f32_ubyte1_e32 v99, v68
	v_pk_fma_f32 v[62:63], v[58:59], v[146:147], v[62:63] op_sel:[1,0,0]
	v_cvt_f32_ubyte2_e32 v102, v68
	v_cvt_f32_ubyte3_e32 v103, v68
	v_pk_fma_f32 v[92:93], v[52:53], v[98:99], v[92:93] op_sel_hi:[0,1,1]
	v_cvt_f32_ubyte0_e32 v104, v69
	v_cvt_f32_ubyte1_e32 v105, v69
	v_pk_fma_f32 v[90:91], v[52:53], v[102:103], v[90:91] op_sel_hi:[0,1,1]
	v_cvt_f32_ubyte2_e32 v146, v69
	v_cvt_f32_ubyte3_e32 v147, v69
	v_pk_fma_f32 v[86:87], v[60:61], v[104:105], v[86:87] op_sel_hi:[0,1,1]
	v_cvt_f32_ubyte0_e32 v98, v76
	v_cvt_f32_ubyte1_e32 v99, v76
	v_pk_fma_f32 v[84:85], v[60:61], v[146:147], v[84:85] op_sel_hi:[0,1,1]
	v_and_b32_e32 v82, s0, v218
	v_and_b32_e32 v83, s1, v218
	v_and_b32_e32 v88, s0, v219
	v_and_b32_e32 v89, s1, v219
	v_cvt_f32_ubyte2_e32 v102, v76
	v_cvt_f32_ubyte3_e32 v103, v76
	v_pk_fma_f32 v[80:81], v[52:53], v[98:99], v[80:81] op_sel_hi:[0,1,1]
	v_cvt_f32_ubyte0_e32 v104, v77
	v_cvt_f32_ubyte1_e32 v105, v77
	v_pk_fma_f32 v[78:79], v[52:53], v[102:103], v[78:79] op_sel_hi:[0,1,1]
	v_cvt_f32_ubyte2_e32 v146, v77
	v_cvt_f32_ubyte3_e32 v147, v77
	v_pk_fma_f32 v[70:71], v[60:61], v[104:105], v[70:71] op_sel_hi:[0,1,1]
	v_cvt_f32_ubyte0_e32 v98, v82
	v_cvt_f32_ubyte1_e32 v99, v82
	v_pk_fma_f32 v[62:63], v[60:61], v[146:147], v[62:63] op_sel_hi:[0,1,1]
	v_cvt_f32_ubyte2_e32 v102, v82
	v_cvt_f32_ubyte3_e32 v103, v82
	v_pk_fma_f32 v[92:93], v[52:53], v[98:99], v[92:93] op_sel:[1,0,0]
	v_cvt_f32_ubyte0_e32 v104, v83
	v_cvt_f32_ubyte1_e32 v105, v83
	v_pk_fma_f32 v[90:91], v[52:53], v[102:103], v[90:91] op_sel:[1,0,0]
	v_cvt_f32_ubyte2_e32 v146, v83
	v_cvt_f32_ubyte3_e32 v147, v83
	v_pk_fma_f32 v[86:87], v[60:61], v[104:105], v[86:87] op_sel:[1,0,0]
	v_cvt_f32_ubyte0_e32 v98, v88
	v_cvt_f32_ubyte1_e32 v99, v88
	v_pk_fma_f32 v[84:85], v[60:61], v[146:147], v[84:85] op_sel:[1,0,0]
	v_and_b32_e32 v68, s0, v220
	v_and_b32_e32 v69, s1, v220
	v_and_b32_e32 v76, s0, v221
	v_and_b32_e32 v77, s1, v221
	v_cvt_f32_ubyte2_e32 v102, v88
	v_cvt_f32_ubyte3_e32 v103, v88
	v_pk_fma_f32 v[80:81], v[52:53], v[98:99], v[80:81] op_sel:[1,0,0]
	v_cvt_f32_ubyte0_e32 v104, v89
	v_cvt_f32_ubyte1_e32 v105, v89
	v_pk_fma_f32 v[78:79], v[52:53], v[102:103], v[78:79] op_sel:[1,0,0]
	v_cvt_f32_ubyte2_e32 v146, v89
	v_cvt_f32_ubyte3_e32 v147, v89
	v_pk_fma_f32 v[70:71], v[60:61], v[104:105], v[70:71] op_sel:[1,0,0]
	v_cvt_f32_ubyte0_e32 v98, v68
	v_cvt_f32_ubyte1_e32 v99, v68
	v_pk_fma_f32 v[62:63], v[60:61], v[146:147], v[62:63] op_sel:[1,0,0]
	v_cvt_f32_ubyte2_e32 v102, v68
	v_cvt_f32_ubyte3_e32 v103, v68
	v_pk_fma_f32 v[92:93], v[54:55], v[98:99], v[92:93] op_sel_hi:[0,1,1]
	v_cvt_f32_ubyte0_e32 v104, v69
	v_cvt_f32_ubyte1_e32 v105, v69
	v_pk_fma_f32 v[90:91], v[54:55], v[102:103], v[90:91] op_sel_hi:[0,1,1]
	v_cvt_f32_ubyte2_e32 v146, v69
	v_cvt_f32_ubyte3_e32 v147, v69
	v_pk_fma_f32 v[86:87], v[64:65], v[104:105], v[86:87] op_sel_hi:[0,1,1]
	v_cvt_f32_ubyte0_e32 v98, v76
	v_cvt_f32_ubyte1_e32 v99, v76
	v_pk_fma_f32 v[84:85], v[64:65], v[146:147], v[84:85] op_sel_hi:[0,1,1]
	v_and_b32_e32 v82, s0, v222
	v_and_b32_e32 v83, s1, v222
	v_and_b32_e32 v88, s0, v223
	v_and_b32_e32 v89, s1, v223
	v_cvt_f32_ubyte2_e32 v102, v76
	v_cvt_f32_ubyte3_e32 v103, v76
	v_pk_fma_f32 v[80:81], v[54:55], v[98:99], v[80:81] op_sel_hi:[0,1,1]
	v_cvt_f32_ubyte0_e32 v104, v77
	v_cvt_f32_ubyte1_e32 v105, v77
	v_pk_fma_f32 v[78:79], v[54:55], v[102:103], v[78:79] op_sel_hi:[0,1,1]
	v_cvt_f32_ubyte2_e32 v146, v77
	v_cvt_f32_ubyte3_e32 v147, v77
	v_pk_fma_f32 v[70:71], v[64:65], v[104:105], v[70:71] op_sel_hi:[0,1,1]
	v_cvt_f32_ubyte0_e32 v98, v82
	v_cvt_f32_ubyte1_e32 v99, v82
	v_pk_fma_f32 v[62:63], v[64:65], v[146:147], v[62:63] op_sel_hi:[0,1,1]
	v_cvt_f32_ubyte2_e32 v102, v82
	v_cvt_f32_ubyte3_e32 v103, v82
	v_pk_fma_f32 v[92:93], v[54:55], v[98:99], v[92:93] op_sel:[1,0,0]
	v_cvt_f32_ubyte0_e32 v104, v83
	v_cvt_f32_ubyte1_e32 v105, v83
	v_pk_fma_f32 v[90:91], v[54:55], v[102:103], v[90:91] op_sel:[1,0,0]
	v_cvt_f32_ubyte2_e32 v146, v83
	v_cvt_f32_ubyte3_e32 v147, v83
	v_pk_fma_f32 v[86:87], v[64:65], v[104:105], v[86:87] op_sel:[1,0,0]
	v_cvt_f32_ubyte0_e32 v98, v88
	v_cvt_f32_ubyte1_e32 v99, v88
	v_pk_fma_f32 v[84:85], v[64:65], v[146:147], v[84:85] op_sel:[1,0,0]
	v_and_b32_e32 v68, s0, v224
	v_and_b32_e32 v69, s1, v224
	v_and_b32_e32 v76, s0, v225
	v_and_b32_e32 v77, s1, v225
	v_cvt_f32_ubyte2_e32 v102, v88
	v_cvt_f32_ubyte3_e32 v103, v88
	v_pk_fma_f32 v[80:81], v[54:55], v[98:99], v[80:81] op_sel:[1,0,0]
	v_cvt_f32_ubyte0_e32 v104, v89
	v_cvt_f32_ubyte1_e32 v105, v89
	v_pk_fma_f32 v[78:79], v[54:55], v[102:103], v[78:79] op_sel:[1,0,0]
	v_cvt_f32_ubyte2_e32 v146, v89
	v_cvt_f32_ubyte3_e32 v147, v89
	v_pk_fma_f32 v[70:71], v[64:65], v[104:105], v[70:71] op_sel:[1,0,0]
	v_cvt_f32_ubyte0_e32 v98, v68
	v_cvt_f32_ubyte1_e32 v99, v68
	v_pk_fma_f32 v[62:63], v[64:65], v[146:147], v[62:63] op_sel:[1,0,0]
	v_cvt_f32_ubyte2_e32 v102, v68
	v_cvt_f32_ubyte3_e32 v103, v68
	v_pk_fma_f32 v[92:93], v[56:57], v[98:99], v[92:93] op_sel_hi:[0,1,1]
	v_cvt_f32_ubyte0_e32 v104, v69
	v_cvt_f32_ubyte1_e32 v105, v69
	v_pk_fma_f32 v[90:91], v[56:57], v[102:103], v[90:91] op_sel_hi:[0,1,1]
	v_cvt_f32_ubyte2_e32 v146, v69
	v_cvt_f32_ubyte3_e32 v147, v69
	v_pk_fma_f32 v[86:87], v[66:67], v[104:105], v[86:87] op_sel_hi:[0,1,1]
	v_cvt_f32_ubyte0_e32 v98, v76
	v_cvt_f32_ubyte1_e32 v99, v76
	v_pk_fma_f32 v[84:85], v[66:67], v[146:147], v[84:85] op_sel_hi:[0,1,1]
	v_and_b32_e32 v82, s0, v226
	v_and_b32_e32 v83, s1, v226
	v_and_b32_e32 v88, s0, v227
	v_and_b32_e32 v89, s1, v227
	v_cvt_f32_ubyte2_e32 v102, v76
	v_cvt_f32_ubyte3_e32 v103, v76
	v_pk_fma_f32 v[80:81], v[56:57], v[98:99], v[80:81] op_sel_hi:[0,1,1]
	v_cvt_f32_ubyte0_e32 v104, v77
	v_cvt_f32_ubyte1_e32 v105, v77
	v_pk_fma_f32 v[78:79], v[56:57], v[102:103], v[78:79] op_sel_hi:[0,1,1]
	v_cvt_f32_ubyte2_e32 v146, v77
	v_cvt_f32_ubyte3_e32 v147, v77
	v_pk_fma_f32 v[70:71], v[66:67], v[104:105], v[70:71] op_sel_hi:[0,1,1]
	v_cvt_f32_ubyte0_e32 v98, v82
	v_cvt_f32_ubyte1_e32 v99, v82
	v_pk_fma_f32 v[62:63], v[66:67], v[146:147], v[62:63] op_sel_hi:[0,1,1]
	v_cvt_f32_ubyte2_e32 v102, v82
	v_cvt_f32_ubyte3_e32 v103, v82
	v_pk_fma_f32 v[92:93], v[56:57], v[98:99], v[92:93] op_sel:[1,0,0]
	v_cvt_f32_ubyte0_e32 v104, v83
	v_cvt_f32_ubyte1_e32 v105, v83
	v_pk_fma_f32 v[90:91], v[56:57], v[102:103], v[90:91] op_sel:[1,0,0]
	v_cvt_f32_ubyte2_e32 v146, v83
	v_cvt_f32_ubyte3_e32 v147, v83
	v_pk_fma_f32 v[86:87], v[66:67], v[104:105], v[86:87] op_sel:[1,0,0]
	v_cvt_f32_ubyte0_e32 v98, v88
	v_cvt_f32_ubyte1_e32 v99, v88
	v_pk_fma_f32 v[84:85], v[66:67], v[146:147], v[84:85] op_sel:[1,0,0]
	v_cvt_f32_ubyte2_e32 v102, v88
	v_cvt_f32_ubyte3_e32 v103, v88
	v_pk_fma_f32 v[80:81], v[56:57], v[98:99], v[80:81] op_sel:[1,0,0]
	v_cvt_f32_ubyte0_e32 v104, v89
	v_cvt_f32_ubyte1_e32 v105, v89
	v_pk_fma_f32 v[78:79], v[56:57], v[102:103], v[78:79] op_sel:[1,0,0]
	v_cvt_f32_ubyte2_e32 v146, v89
	v_cvt_f32_ubyte3_e32 v147, v89
	v_pk_fma_f32 v[70:71], v[66:67], v[104:105], v[70:71] op_sel:[1,0,0]
	v_pk_fma_f32 v[62:63], v[66:67], v[146:147], v[62:63] op_sel:[1,0,0]
	s_waitcnt lgkmcnt(0)
	v_lshl_add_u32 v72, v72, 9, v100
	v_lshl_add_u32 v73, v73, 9, v100
	v_lshl_add_u32 v74, v74, 9, v100
	v_lshl_add_u32 v75, v75, 9, v100
	v_lshl_add_u32 v94, v94, 9, v100
	v_lshl_add_u32 v95, v95, 9, v100
	v_lshl_add_u32 v96, v96, 9, v100
	v_lshl_add_u32 v97, v97, 9, v100
	global_load_dwordx2 v[212:213], v72, s[38:39]
	global_load_dwordx2 v[214:215], v73, s[38:39]
	global_load_dwordx2 v[216:217], v74, s[38:39]
	global_load_dwordx2 v[218:219], v75, s[38:39]
	global_load_dwordx2 v[220:221], v94, s[38:39]
	global_load_dwordx2 v[222:223], v95, s[38:39]
	global_load_dwordx2 v[224:225], v96, s[38:39]
	global_load_dwordx2 v[226:227], v97, s[38:39]
	ds_read_b128 v[50:53], v1 offset:864
	ds_read_b128 v[54:57], v1 offset:880
	ds_read_b128 v[58:61], v1 offset:1888
	ds_read_b128 v[64:67], v1 offset:1904
	s_waitcnt vmcnt(40)
	v_and_b32_e32 v68, s0, v2
	v_and_b32_e32 v69, s1, v2
	v_and_b32_e32 v76, s0, v3
	v_and_b32_e32 v77, s1, v3
	v_cvt_f32_ubyte0_e32 v98, v68
	v_cvt_f32_ubyte1_e32 v99, v68
	v_cvt_f32_ubyte2_e32 v102, v68
	v_cvt_f32_ubyte3_e32 v103, v68
	v_pk_fma_f32 v[92:93], v[34:35], v[98:99], v[92:93] op_sel_hi:[0,1,1]
	v_cvt_f32_ubyte0_e32 v104, v69
	v_cvt_f32_ubyte1_e32 v105, v69
	v_pk_fma_f32 v[90:91], v[34:35], v[102:103], v[90:91] op_sel_hi:[0,1,1]
	v_cvt_f32_ubyte2_e32 v146, v69
	v_cvt_f32_ubyte3_e32 v147, v69
	v_pk_fma_f32 v[86:87], v[42:43], v[104:105], v[86:87] op_sel_hi:[0,1,1]
	v_cvt_f32_ubyte0_e32 v98, v76
	v_cvt_f32_ubyte1_e32 v99, v76
	v_pk_fma_f32 v[84:85], v[42:43], v[146:147], v[84:85] op_sel_hi:[0,1,1]
	v_and_b32_e32 v82, s0, v4
	v_and_b32_e32 v83, s1, v4
	v_and_b32_e32 v88, s0, v5
	v_and_b32_e32 v89, s1, v5
	v_cvt_f32_ubyte2_e32 v102, v76
	v_cvt_f32_ubyte3_e32 v103, v76
	v_pk_fma_f32 v[80:81], v[34:35], v[98:99], v[80:81] op_sel_hi:[0,1,1]
	v_cvt_f32_ubyte0_e32 v104, v77
	v_cvt_f32_ubyte1_e32 v105, v77
	v_pk_fma_f32 v[78:79], v[34:35], v[102:103], v[78:79] op_sel_hi:[0,1,1]
	v_cvt_f32_ubyte2_e32 v146, v77
	v_cvt_f32_ubyte3_e32 v147, v77
	v_pk_fma_f32 v[70:71], v[42:43], v[104:105], v[70:71] op_sel_hi:[0,1,1]
	v_cvt_f32_ubyte0_e32 v98, v82
	v_cvt_f32_ubyte1_e32 v99, v82
	v_pk_fma_f32 v[62:63], v[42:43], v[146:147], v[62:63] op_sel_hi:[0,1,1]
	v_cvt_f32_ubyte2_e32 v102, v82
	v_cvt_f32_ubyte3_e32 v103, v82
	v_pk_fma_f32 v[92:93], v[34:35], v[98:99], v[92:93] op_sel:[1,0,0]
	v_cvt_f32_ubyte0_e32 v104, v83
	v_cvt_f32_ubyte1_e32 v105, v83
	v_pk_fma_f32 v[90:91], v[34:35], v[102:103], v[90:91] op_sel:[1,0,0]
	v_cvt_f32_ubyte2_e32 v146, v83
	v_cvt_f32_ubyte3_e32 v147, v83
	v_pk_fma_f32 v[86:87], v[42:43], v[104:105], v[86:87] op_sel:[1,0,0]
	v_cvt_f32_ubyte0_e32 v98, v88
	v_cvt_f32_ubyte1_e32 v99, v88
	v_pk_fma_f32 v[84:85], v[42:43], v[146:147], v[84:85] op_sel:[1,0,0]
	v_and_b32_e32 v68, s0, v6
	v_and_b32_e32 v69, s1, v6
	v_and_b32_e32 v76, s0, v7
	v_and_b32_e32 v77, s1, v7
	v_cvt_f32_ubyte2_e32 v102, v88
	v_cvt_f32_ubyte3_e32 v103, v88
	v_pk_fma_f32 v[80:81], v[34:35], v[98:99], v[80:81] op_sel:[1,0,0]
	v_cvt_f32_ubyte0_e32 v104, v89
	v_cvt_f32_ubyte1_e32 v105, v89
	v_pk_fma_f32 v[78:79], v[34:35], v[102:103], v[78:79] op_sel:[1,0,0]
	v_cvt_f32_ubyte2_e32 v146, v89
	v_cvt_f32_ubyte3_e32 v147, v89
	v_pk_fma_f32 v[70:71], v[42:43], v[104:105], v[70:71] op_sel:[1,0,0]
	v_cvt_f32_ubyte0_e32 v98, v68
	v_cvt_f32_ubyte1_e32 v99, v68
	v_pk_fma_f32 v[62:63], v[42:43], v[146:147], v[62:63] op_sel:[1,0,0]
	v_cvt_f32_ubyte2_e32 v102, v68
	v_cvt_f32_ubyte3_e32 v103, v68
	v_pk_fma_f32 v[92:93], v[36:37], v[98:99], v[92:93] op_sel_hi:[0,1,1]
	v_cvt_f32_ubyte0_e32 v104, v69
	v_cvt_f32_ubyte1_e32 v105, v69
	v_pk_fma_f32 v[90:91], v[36:37], v[102:103], v[90:91] op_sel_hi:[0,1,1]
	v_cvt_f32_ubyte2_e32 v146, v69
	v_cvt_f32_ubyte3_e32 v147, v69
	v_pk_fma_f32 v[86:87], v[44:45], v[104:105], v[86:87] op_sel_hi:[0,1,1]
	v_cvt_f32_ubyte0_e32 v98, v76
	v_cvt_f32_ubyte1_e32 v99, v76
	v_pk_fma_f32 v[84:85], v[44:45], v[146:147], v[84:85] op_sel_hi:[0,1,1]
	v_and_b32_e32 v82, s0, v8
	v_and_b32_e32 v83, s1, v8
	v_and_b32_e32 v88, s0, v9
	v_and_b32_e32 v89, s1, v9
	v_cvt_f32_ubyte2_e32 v102, v76
	v_cvt_f32_ubyte3_e32 v103, v76
	v_pk_fma_f32 v[80:81], v[36:37], v[98:99], v[80:81] op_sel_hi:[0,1,1]
	v_cvt_f32_ubyte0_e32 v104, v77
	v_cvt_f32_ubyte1_e32 v105, v77
	v_pk_fma_f32 v[78:79], v[36:37], v[102:103], v[78:79] op_sel_hi:[0,1,1]
	v_cvt_f32_ubyte2_e32 v146, v77
	v_cvt_f32_ubyte3_e32 v147, v77
	v_pk_fma_f32 v[70:71], v[44:45], v[104:105], v[70:71] op_sel_hi:[0,1,1]
	v_cvt_f32_ubyte0_e32 v98, v82
	v_cvt_f32_ubyte1_e32 v99, v82
	v_pk_fma_f32 v[62:63], v[44:45], v[146:147], v[62:63] op_sel_hi:[0,1,1]
	v_cvt_f32_ubyte2_e32 v102, v82
	v_cvt_f32_ubyte3_e32 v103, v82
	v_pk_fma_f32 v[92:93], v[36:37], v[98:99], v[92:93] op_sel:[1,0,0]
	v_cvt_f32_ubyte0_e32 v104, v83
	v_cvt_f32_ubyte1_e32 v105, v83
	v_pk_fma_f32 v[90:91], v[36:37], v[102:103], v[90:91] op_sel:[1,0,0]
	v_cvt_f32_ubyte2_e32 v146, v83
	v_cvt_f32_ubyte3_e32 v147, v83
	v_pk_fma_f32 v[86:87], v[44:45], v[104:105], v[86:87] op_sel:[1,0,0]
	v_cvt_f32_ubyte0_e32 v98, v88
	v_cvt_f32_ubyte1_e32 v99, v88
	v_pk_fma_f32 v[84:85], v[44:45], v[146:147], v[84:85] op_sel:[1,0,0]
	v_and_b32_e32 v68, s0, v10
	v_and_b32_e32 v69, s1, v10
	v_and_b32_e32 v76, s0, v11
	v_and_b32_e32 v77, s1, v11
	v_cvt_f32_ubyte2_e32 v102, v88
	v_cvt_f32_ubyte3_e32 v103, v88
	v_pk_fma_f32 v[80:81], v[36:37], v[98:99], v[80:81] op_sel:[1,0,0]
	v_cvt_f32_ubyte0_e32 v104, v89
	v_cvt_f32_ubyte1_e32 v105, v89
	v_pk_fma_f32 v[78:79], v[36:37], v[102:103], v[78:79] op_sel:[1,0,0]
	v_cvt_f32_ubyte2_e32 v146, v89
	v_cvt_f32_ubyte3_e32 v147, v89
	v_pk_fma_f32 v[70:71], v[44:45], v[104:105], v[70:71] op_sel:[1,0,0]
	v_cvt_f32_ubyte0_e32 v98, v68
	v_cvt_f32_ubyte1_e32 v99, v68
	v_pk_fma_f32 v[62:63], v[44:45], v[146:147], v[62:63] op_sel:[1,0,0]
	v_cvt_f32_ubyte2_e32 v102, v68
	v_cvt_f32_ubyte3_e32 v103, v68
	v_pk_fma_f32 v[92:93], v[38:39], v[98:99], v[92:93] op_sel_hi:[0,1,1]
	v_cvt_f32_ubyte0_e32 v104, v69
	v_cvt_f32_ubyte1_e32 v105, v69
	v_pk_fma_f32 v[90:91], v[38:39], v[102:103], v[90:91] op_sel_hi:[0,1,1]
	v_cvt_f32_ubyte2_e32 v146, v69
	v_cvt_f32_ubyte3_e32 v147, v69
	v_pk_fma_f32 v[86:87], v[46:47], v[104:105], v[86:87] op_sel_hi:[0,1,1]
	v_cvt_f32_ubyte0_e32 v98, v76
	v_cvt_f32_ubyte1_e32 v99, v76
	v_pk_fma_f32 v[84:85], v[46:47], v[146:147], v[84:85] op_sel_hi:[0,1,1]
	v_and_b32_e32 v82, s0, v12
	v_and_b32_e32 v83, s1, v12
	v_and_b32_e32 v88, s0, v13
	v_and_b32_e32 v89, s1, v13
	v_cvt_f32_ubyte2_e32 v102, v76
	v_cvt_f32_ubyte3_e32 v103, v76
	v_pk_fma_f32 v[80:81], v[38:39], v[98:99], v[80:81] op_sel_hi:[0,1,1]
	v_cvt_f32_ubyte0_e32 v104, v77
	v_cvt_f32_ubyte1_e32 v105, v77
	v_pk_fma_f32 v[78:79], v[38:39], v[102:103], v[78:79] op_sel_hi:[0,1,1]
	v_cvt_f32_ubyte2_e32 v146, v77
	v_cvt_f32_ubyte3_e32 v147, v77
	v_pk_fma_f32 v[70:71], v[46:47], v[104:105], v[70:71] op_sel_hi:[0,1,1]
	v_cvt_f32_ubyte0_e32 v98, v82
	v_cvt_f32_ubyte1_e32 v99, v82
	v_pk_fma_f32 v[62:63], v[46:47], v[146:147], v[62:63] op_sel_hi:[0,1,1]
	v_cvt_f32_ubyte2_e32 v102, v82
	v_cvt_f32_ubyte3_e32 v103, v82
	v_pk_fma_f32 v[92:93], v[38:39], v[98:99], v[92:93] op_sel:[1,0,0]
	v_cvt_f32_ubyte0_e32 v104, v83
	v_cvt_f32_ubyte1_e32 v105, v83
	v_pk_fma_f32 v[90:91], v[38:39], v[102:103], v[90:91] op_sel:[1,0,0]
	v_cvt_f32_ubyte2_e32 v146, v83
	v_cvt_f32_ubyte3_e32 v147, v83
	v_pk_fma_f32 v[86:87], v[46:47], v[104:105], v[86:87] op_sel:[1,0,0]
	v_cvt_f32_ubyte0_e32 v98, v88
	v_cvt_f32_ubyte1_e32 v99, v88
	v_pk_fma_f32 v[84:85], v[46:47], v[146:147], v[84:85] op_sel:[1,0,0]
	v_and_b32_e32 v68, s0, v14
	v_and_b32_e32 v69, s1, v14
	v_and_b32_e32 v76, s0, v15
	v_and_b32_e32 v77, s1, v15
	v_cvt_f32_ubyte2_e32 v102, v88
	v_cvt_f32_ubyte3_e32 v103, v88
	v_pk_fma_f32 v[80:81], v[38:39], v[98:99], v[80:81] op_sel:[1,0,0]
	v_cvt_f32_ubyte0_e32 v104, v89
	v_cvt_f32_ubyte1_e32 v105, v89
	v_pk_fma_f32 v[78:79], v[38:39], v[102:103], v[78:79] op_sel:[1,0,0]
	v_cvt_f32_ubyte2_e32 v146, v89
	v_cvt_f32_ubyte3_e32 v147, v89
	v_pk_fma_f32 v[70:71], v[46:47], v[104:105], v[70:71] op_sel:[1,0,0]
	v_cvt_f32_ubyte0_e32 v98, v68
	v_cvt_f32_ubyte1_e32 v99, v68
	v_pk_fma_f32 v[62:63], v[46:47], v[146:147], v[62:63] op_sel:[1,0,0]
	v_cvt_f32_ubyte2_e32 v102, v68
	v_cvt_f32_ubyte3_e32 v103, v68
	v_pk_fma_f32 v[92:93], v[40:41], v[98:99], v[92:93] op_sel_hi:[0,1,1]
	v_cvt_f32_ubyte0_e32 v104, v69
	v_cvt_f32_ubyte1_e32 v105, v69
	v_pk_fma_f32 v[90:91], v[40:41], v[102:103], v[90:91] op_sel_hi:[0,1,1]
	v_cvt_f32_ubyte2_e32 v146, v69
	v_cvt_f32_ubyte3_e32 v147, v69
	v_pk_fma_f32 v[86:87], v[48:49], v[104:105], v[86:87] op_sel_hi:[0,1,1]
	v_cvt_f32_ubyte0_e32 v98, v76
	v_cvt_f32_ubyte1_e32 v99, v76
	v_pk_fma_f32 v[84:85], v[48:49], v[146:147], v[84:85] op_sel_hi:[0,1,1]
	v_and_b32_e32 v82, s0, v16
	v_and_b32_e32 v83, s1, v16
	v_and_b32_e32 v88, s0, v17
	v_and_b32_e32 v89, s1, v17
	v_cvt_f32_ubyte2_e32 v102, v76
	v_cvt_f32_ubyte3_e32 v103, v76
	v_pk_fma_f32 v[80:81], v[40:41], v[98:99], v[80:81] op_sel_hi:[0,1,1]
	v_cvt_f32_ubyte0_e32 v104, v77
	v_cvt_f32_ubyte1_e32 v105, v77
	v_pk_fma_f32 v[78:79], v[40:41], v[102:103], v[78:79] op_sel_hi:[0,1,1]
	v_cvt_f32_ubyte2_e32 v146, v77
	v_cvt_f32_ubyte3_e32 v147, v77
	v_pk_fma_f32 v[70:71], v[48:49], v[104:105], v[70:71] op_sel_hi:[0,1,1]
	v_cvt_f32_ubyte0_e32 v98, v82
	v_cvt_f32_ubyte1_e32 v99, v82
	v_pk_fma_f32 v[62:63], v[48:49], v[146:147], v[62:63] op_sel_hi:[0,1,1]
	v_cvt_f32_ubyte2_e32 v102, v82
	v_cvt_f32_ubyte3_e32 v103, v82
	v_pk_fma_f32 v[92:93], v[40:41], v[98:99], v[92:93] op_sel:[1,0,0]
	v_cvt_f32_ubyte0_e32 v104, v83
	v_cvt_f32_ubyte1_e32 v105, v83
	v_pk_fma_f32 v[90:91], v[40:41], v[102:103], v[90:91] op_sel:[1,0,0]
	v_cvt_f32_ubyte2_e32 v146, v83
	v_cvt_f32_ubyte3_e32 v147, v83
	v_pk_fma_f32 v[86:87], v[48:49], v[104:105], v[86:87] op_sel:[1,0,0]
	v_cvt_f32_ubyte0_e32 v98, v88
	v_cvt_f32_ubyte1_e32 v99, v88
	v_pk_fma_f32 v[84:85], v[48:49], v[146:147], v[84:85] op_sel:[1,0,0]
	v_cvt_f32_ubyte2_e32 v102, v88
	v_cvt_f32_ubyte3_e32 v103, v88
	v_pk_fma_f32 v[80:81], v[40:41], v[98:99], v[80:81] op_sel:[1,0,0]
	v_cvt_f32_ubyte0_e32 v104, v89
	v_cvt_f32_ubyte1_e32 v105, v89
	v_pk_fma_f32 v[78:79], v[40:41], v[102:103], v[78:79] op_sel:[1,0,0]
	v_cvt_f32_ubyte2_e32 v146, v89
	v_cvt_f32_ubyte3_e32 v147, v89
	v_pk_fma_f32 v[70:71], v[48:49], v[104:105], v[70:71] op_sel:[1,0,0]
	v_pk_fma_f32 v[62:63], v[48:49], v[146:147], v[62:63] op_sel:[1,0,0]
	s_waitcnt lgkmcnt(0)
	ds_read_b128 v[34:37], v1 offset:896
	ds_read_b128 v[38:41], v1 offset:912
	ds_read_b128 v[42:45], v1 offset:1920
	ds_read_b128 v[46:49], v1 offset:1936
	s_waitcnt vmcnt(32)
	v_and_b32_e32 v68, s0, v18
	v_and_b32_e32 v69, s1, v18
	v_and_b32_e32 v76, s0, v19
	v_and_b32_e32 v77, s1, v19
	v_cvt_f32_ubyte0_e32 v98, v68
	v_cvt_f32_ubyte1_e32 v99, v68
	v_cvt_f32_ubyte2_e32 v102, v68
	v_cvt_f32_ubyte3_e32 v103, v68
	v_pk_fma_f32 v[92:93], v[50:51], v[98:99], v[92:93] op_sel_hi:[0,1,1]
	v_cvt_f32_ubyte0_e32 v104, v69
	v_cvt_f32_ubyte1_e32 v105, v69
	v_pk_fma_f32 v[90:91], v[50:51], v[102:103], v[90:91] op_sel_hi:[0,1,1]
	v_cvt_f32_ubyte2_e32 v146, v69
	v_cvt_f32_ubyte3_e32 v147, v69
	v_pk_fma_f32 v[86:87], v[58:59], v[104:105], v[86:87] op_sel_hi:[0,1,1]
	v_cvt_f32_ubyte0_e32 v98, v76
	v_cvt_f32_ubyte1_e32 v99, v76
	v_pk_fma_f32 v[84:85], v[58:59], v[146:147], v[84:85] op_sel_hi:[0,1,1]
	v_and_b32_e32 v82, s0, v20
	v_and_b32_e32 v83, s1, v20
	v_and_b32_e32 v88, s0, v21
	v_and_b32_e32 v89, s1, v21
	v_cvt_f32_ubyte2_e32 v102, v76
	v_cvt_f32_ubyte3_e32 v103, v76
	v_pk_fma_f32 v[80:81], v[50:51], v[98:99], v[80:81] op_sel_hi:[0,1,1]
	v_cvt_f32_ubyte0_e32 v104, v77
	v_cvt_f32_ubyte1_e32 v105, v77
	v_pk_fma_f32 v[78:79], v[50:51], v[102:103], v[78:79] op_sel_hi:[0,1,1]
	v_cvt_f32_ubyte2_e32 v146, v77
	v_cvt_f32_ubyte3_e32 v147, v77
	v_pk_fma_f32 v[70:71], v[58:59], v[104:105], v[70:71] op_sel_hi:[0,1,1]
	v_cvt_f32_ubyte0_e32 v98, v82
	v_cvt_f32_ubyte1_e32 v99, v82
	v_pk_fma_f32 v[62:63], v[58:59], v[146:147], v[62:63] op_sel_hi:[0,1,1]
	v_cvt_f32_ubyte2_e32 v102, v82
	v_cvt_f32_ubyte3_e32 v103, v82
	v_pk_fma_f32 v[92:93], v[50:51], v[98:99], v[92:93] op_sel:[1,0,0]
	v_cvt_f32_ubyte0_e32 v104, v83
	v_cvt_f32_ubyte1_e32 v105, v83
	v_pk_fma_f32 v[90:91], v[50:51], v[102:103], v[90:91] op_sel:[1,0,0]
	v_cvt_f32_ubyte2_e32 v146, v83
	v_cvt_f32_ubyte3_e32 v147, v83
	v_pk_fma_f32 v[86:87], v[58:59], v[104:105], v[86:87] op_sel:[1,0,0]
	v_cvt_f32_ubyte0_e32 v98, v88
	v_cvt_f32_ubyte1_e32 v99, v88
	v_pk_fma_f32 v[84:85], v[58:59], v[146:147], v[84:85] op_sel:[1,0,0]
	v_and_b32_e32 v68, s0, v22
	v_and_b32_e32 v69, s1, v22
	v_and_b32_e32 v76, s0, v23
	v_and_b32_e32 v77, s1, v23
	v_cvt_f32_ubyte2_e32 v102, v88
	v_cvt_f32_ubyte3_e32 v103, v88
	v_pk_fma_f32 v[80:81], v[50:51], v[98:99], v[80:81] op_sel:[1,0,0]
	v_cvt_f32_ubyte0_e32 v104, v89
	v_cvt_f32_ubyte1_e32 v105, v89
	v_pk_fma_f32 v[78:79], v[50:51], v[102:103], v[78:79] op_sel:[1,0,0]
	v_cvt_f32_ubyte2_e32 v146, v89
	v_cvt_f32_ubyte3_e32 v147, v89
	v_pk_fma_f32 v[70:71], v[58:59], v[104:105], v[70:71] op_sel:[1,0,0]
	v_cvt_f32_ubyte0_e32 v98, v68
	v_cvt_f32_ubyte1_e32 v99, v68
	v_pk_fma_f32 v[62:63], v[58:59], v[146:147], v[62:63] op_sel:[1,0,0]
	v_cvt_f32_ubyte2_e32 v102, v68
	v_cvt_f32_ubyte3_e32 v103, v68
	v_pk_fma_f32 v[92:93], v[52:53], v[98:99], v[92:93] op_sel_hi:[0,1,1]
	v_cvt_f32_ubyte0_e32 v104, v69
	v_cvt_f32_ubyte1_e32 v105, v69
	v_pk_fma_f32 v[90:91], v[52:53], v[102:103], v[90:91] op_sel_hi:[0,1,1]
	v_cvt_f32_ubyte2_e32 v146, v69
	v_cvt_f32_ubyte3_e32 v147, v69
	v_pk_fma_f32 v[86:87], v[60:61], v[104:105], v[86:87] op_sel_hi:[0,1,1]
	v_cvt_f32_ubyte0_e32 v98, v76
	v_cvt_f32_ubyte1_e32 v99, v76
	v_pk_fma_f32 v[84:85], v[60:61], v[146:147], v[84:85] op_sel_hi:[0,1,1]
	v_and_b32_e32 v82, s0, v24
	v_and_b32_e32 v83, s1, v24
	v_and_b32_e32 v88, s0, v25
	v_and_b32_e32 v89, s1, v25
	v_cvt_f32_ubyte2_e32 v102, v76
	v_cvt_f32_ubyte3_e32 v103, v76
	v_pk_fma_f32 v[80:81], v[52:53], v[98:99], v[80:81] op_sel_hi:[0,1,1]
	v_cvt_f32_ubyte0_e32 v104, v77
	v_cvt_f32_ubyte1_e32 v105, v77
	v_pk_fma_f32 v[78:79], v[52:53], v[102:103], v[78:79] op_sel_hi:[0,1,1]
	v_cvt_f32_ubyte2_e32 v146, v77
	v_cvt_f32_ubyte3_e32 v147, v77
	v_pk_fma_f32 v[70:71], v[60:61], v[104:105], v[70:71] op_sel_hi:[0,1,1]
	v_cvt_f32_ubyte0_e32 v98, v82
	v_cvt_f32_ubyte1_e32 v99, v82
	v_pk_fma_f32 v[62:63], v[60:61], v[146:147], v[62:63] op_sel_hi:[0,1,1]
	v_cvt_f32_ubyte2_e32 v102, v82
	v_cvt_f32_ubyte3_e32 v103, v82
	v_pk_fma_f32 v[92:93], v[52:53], v[98:99], v[92:93] op_sel:[1,0,0]
	v_cvt_f32_ubyte0_e32 v104, v83
	v_cvt_f32_ubyte1_e32 v105, v83
	v_pk_fma_f32 v[90:91], v[52:53], v[102:103], v[90:91] op_sel:[1,0,0]
	v_cvt_f32_ubyte2_e32 v146, v83
	v_cvt_f32_ubyte3_e32 v147, v83
	v_pk_fma_f32 v[86:87], v[60:61], v[104:105], v[86:87] op_sel:[1,0,0]
	v_cvt_f32_ubyte0_e32 v98, v88
	v_cvt_f32_ubyte1_e32 v99, v88
	v_pk_fma_f32 v[84:85], v[60:61], v[146:147], v[84:85] op_sel:[1,0,0]
	v_and_b32_e32 v68, s0, v26
	v_and_b32_e32 v69, s1, v26
	v_and_b32_e32 v76, s0, v27
	v_and_b32_e32 v77, s1, v27
	v_cvt_f32_ubyte2_e32 v102, v88
	v_cvt_f32_ubyte3_e32 v103, v88
	v_pk_fma_f32 v[80:81], v[52:53], v[98:99], v[80:81] op_sel:[1,0,0]
	v_cvt_f32_ubyte0_e32 v104, v89
	v_cvt_f32_ubyte1_e32 v105, v89
	v_pk_fma_f32 v[78:79], v[52:53], v[102:103], v[78:79] op_sel:[1,0,0]
	v_cvt_f32_ubyte2_e32 v146, v89
	v_cvt_f32_ubyte3_e32 v147, v89
	v_pk_fma_f32 v[70:71], v[60:61], v[104:105], v[70:71] op_sel:[1,0,0]
	v_cvt_f32_ubyte0_e32 v98, v68
	v_cvt_f32_ubyte1_e32 v99, v68
	v_pk_fma_f32 v[62:63], v[60:61], v[146:147], v[62:63] op_sel:[1,0,0]
	v_cvt_f32_ubyte2_e32 v102, v68
	v_cvt_f32_ubyte3_e32 v103, v68
	v_pk_fma_f32 v[92:93], v[54:55], v[98:99], v[92:93] op_sel_hi:[0,1,1]
	v_cvt_f32_ubyte0_e32 v104, v69
	v_cvt_f32_ubyte1_e32 v105, v69
	v_pk_fma_f32 v[90:91], v[54:55], v[102:103], v[90:91] op_sel_hi:[0,1,1]
	v_cvt_f32_ubyte2_e32 v146, v69
	v_cvt_f32_ubyte3_e32 v147, v69
	v_pk_fma_f32 v[86:87], v[64:65], v[104:105], v[86:87] op_sel_hi:[0,1,1]
	v_cvt_f32_ubyte0_e32 v98, v76
	v_cvt_f32_ubyte1_e32 v99, v76
	v_pk_fma_f32 v[84:85], v[64:65], v[146:147], v[84:85] op_sel_hi:[0,1,1]
	v_and_b32_e32 v82, s0, v28
	v_and_b32_e32 v83, s1, v28
	v_and_b32_e32 v88, s0, v29
	v_and_b32_e32 v89, s1, v29
	v_cvt_f32_ubyte2_e32 v102, v76
	v_cvt_f32_ubyte3_e32 v103, v76
	v_pk_fma_f32 v[80:81], v[54:55], v[98:99], v[80:81] op_sel_hi:[0,1,1]
	v_cvt_f32_ubyte0_e32 v104, v77
	v_cvt_f32_ubyte1_e32 v105, v77
	v_pk_fma_f32 v[78:79], v[54:55], v[102:103], v[78:79] op_sel_hi:[0,1,1]
	v_cvt_f32_ubyte2_e32 v146, v77
	v_cvt_f32_ubyte3_e32 v147, v77
	v_pk_fma_f32 v[70:71], v[64:65], v[104:105], v[70:71] op_sel_hi:[0,1,1]
	v_cvt_f32_ubyte0_e32 v98, v82
	v_cvt_f32_ubyte1_e32 v99, v82
	v_pk_fma_f32 v[62:63], v[64:65], v[146:147], v[62:63] op_sel_hi:[0,1,1]
	v_cvt_f32_ubyte2_e32 v102, v82
	v_cvt_f32_ubyte3_e32 v103, v82
	v_pk_fma_f32 v[92:93], v[54:55], v[98:99], v[92:93] op_sel:[1,0,0]
	v_cvt_f32_ubyte0_e32 v104, v83
	v_cvt_f32_ubyte1_e32 v105, v83
	v_pk_fma_f32 v[90:91], v[54:55], v[102:103], v[90:91] op_sel:[1,0,0]
	v_cvt_f32_ubyte2_e32 v146, v83
	v_cvt_f32_ubyte3_e32 v147, v83
	v_pk_fma_f32 v[86:87], v[64:65], v[104:105], v[86:87] op_sel:[1,0,0]
	v_cvt_f32_ubyte0_e32 v98, v88
	v_cvt_f32_ubyte1_e32 v99, v88
	v_pk_fma_f32 v[84:85], v[64:65], v[146:147], v[84:85] op_sel:[1,0,0]
	v_and_b32_e32 v68, s0, v30
	v_and_b32_e32 v69, s1, v30
	v_and_b32_e32 v76, s0, v31
	v_and_b32_e32 v77, s1, v31
	v_cvt_f32_ubyte2_e32 v102, v88
	v_cvt_f32_ubyte3_e32 v103, v88
	v_pk_fma_f32 v[80:81], v[54:55], v[98:99], v[80:81] op_sel:[1,0,0]
	v_cvt_f32_ubyte0_e32 v104, v89
	v_cvt_f32_ubyte1_e32 v105, v89
	v_pk_fma_f32 v[78:79], v[54:55], v[102:103], v[78:79] op_sel:[1,0,0]
	v_cvt_f32_ubyte2_e32 v146, v89
	v_cvt_f32_ubyte3_e32 v147, v89
	v_pk_fma_f32 v[70:71], v[64:65], v[104:105], v[70:71] op_sel:[1,0,0]
	v_cvt_f32_ubyte0_e32 v98, v68
	v_cvt_f32_ubyte1_e32 v99, v68
	v_pk_fma_f32 v[62:63], v[64:65], v[146:147], v[62:63] op_sel:[1,0,0]
	v_cvt_f32_ubyte2_e32 v102, v68
	v_cvt_f32_ubyte3_e32 v103, v68
	v_pk_fma_f32 v[92:93], v[56:57], v[98:99], v[92:93] op_sel_hi:[0,1,1]
	v_cvt_f32_ubyte0_e32 v104, v69
	v_cvt_f32_ubyte1_e32 v105, v69
	v_pk_fma_f32 v[90:91], v[56:57], v[102:103], v[90:91] op_sel_hi:[0,1,1]
	v_cvt_f32_ubyte2_e32 v146, v69
	v_cvt_f32_ubyte3_e32 v147, v69
	v_pk_fma_f32 v[86:87], v[66:67], v[104:105], v[86:87] op_sel_hi:[0,1,1]
	v_cvt_f32_ubyte0_e32 v98, v76
	v_cvt_f32_ubyte1_e32 v99, v76
	v_pk_fma_f32 v[84:85], v[66:67], v[146:147], v[84:85] op_sel_hi:[0,1,1]
	v_and_b32_e32 v82, s0, v32
	v_and_b32_e32 v83, s1, v32
	v_and_b32_e32 v88, s0, v33
	v_and_b32_e32 v89, s1, v33
	v_cvt_f32_ubyte2_e32 v102, v76
	v_cvt_f32_ubyte3_e32 v103, v76
	v_pk_fma_f32 v[80:81], v[56:57], v[98:99], v[80:81] op_sel_hi:[0,1,1]
	v_cvt_f32_ubyte0_e32 v104, v77
	v_cvt_f32_ubyte1_e32 v105, v77
	v_pk_fma_f32 v[78:79], v[56:57], v[102:103], v[78:79] op_sel_hi:[0,1,1]
	v_cvt_f32_ubyte2_e32 v146, v77
	v_cvt_f32_ubyte3_e32 v147, v77
	v_pk_fma_f32 v[70:71], v[66:67], v[104:105], v[70:71] op_sel_hi:[0,1,1]
	v_cvt_f32_ubyte0_e32 v98, v82
	v_cvt_f32_ubyte1_e32 v99, v82
	v_pk_fma_f32 v[62:63], v[66:67], v[146:147], v[62:63] op_sel_hi:[0,1,1]
	v_cvt_f32_ubyte2_e32 v102, v82
	v_cvt_f32_ubyte3_e32 v103, v82
	v_pk_fma_f32 v[92:93], v[56:57], v[98:99], v[92:93] op_sel:[1,0,0]
	v_cvt_f32_ubyte0_e32 v104, v83
	v_cvt_f32_ubyte1_e32 v105, v83
	v_pk_fma_f32 v[90:91], v[56:57], v[102:103], v[90:91] op_sel:[1,0,0]
	v_cvt_f32_ubyte2_e32 v146, v83
	v_cvt_f32_ubyte3_e32 v147, v83
	v_pk_fma_f32 v[86:87], v[66:67], v[104:105], v[86:87] op_sel:[1,0,0]
	v_cvt_f32_ubyte0_e32 v98, v88
	v_cvt_f32_ubyte1_e32 v99, v88
	v_pk_fma_f32 v[84:85], v[66:67], v[146:147], v[84:85] op_sel:[1,0,0]
	v_cvt_f32_ubyte2_e32 v102, v88
	v_cvt_f32_ubyte3_e32 v103, v88
	v_pk_fma_f32 v[80:81], v[56:57], v[98:99], v[80:81] op_sel:[1,0,0]
	v_cvt_f32_ubyte0_e32 v104, v89
	v_cvt_f32_ubyte1_e32 v105, v89
	v_pk_fma_f32 v[78:79], v[56:57], v[102:103], v[78:79] op_sel:[1,0,0]
	v_cvt_f32_ubyte2_e32 v146, v89
	v_cvt_f32_ubyte3_e32 v147, v89
	v_pk_fma_f32 v[70:71], v[66:67], v[104:105], v[70:71] op_sel:[1,0,0]
	v_pk_fma_f32 v[62:63], v[66:67], v[146:147], v[62:63] op_sel:[1,0,0]
	s_waitcnt lgkmcnt(0)
	ds_read_b128 v[50:53], v1 offset:928
	ds_read_b128 v[54:57], v1 offset:944
	ds_read_b128 v[58:61], v1 offset:1952
	ds_read_b128 v[64:67], v1 offset:1968
	s_waitcnt vmcnt(24)
	v_and_b32_e32 v68, s0, v164
	v_and_b32_e32 v69, s1, v164
	v_and_b32_e32 v76, s0, v165
	v_and_b32_e32 v77, s1, v165
	v_cvt_f32_ubyte0_e32 v98, v68
	v_cvt_f32_ubyte1_e32 v99, v68
	v_cvt_f32_ubyte2_e32 v102, v68
	v_cvt_f32_ubyte3_e32 v103, v68
	v_pk_fma_f32 v[92:93], v[34:35], v[98:99], v[92:93] op_sel_hi:[0,1,1]
	v_cvt_f32_ubyte0_e32 v104, v69
	v_cvt_f32_ubyte1_e32 v105, v69
	v_pk_fma_f32 v[90:91], v[34:35], v[102:103], v[90:91] op_sel_hi:[0,1,1]
	v_cvt_f32_ubyte2_e32 v146, v69
	v_cvt_f32_ubyte3_e32 v147, v69
	v_pk_fma_f32 v[86:87], v[42:43], v[104:105], v[86:87] op_sel_hi:[0,1,1]
	v_cvt_f32_ubyte0_e32 v98, v76
	v_cvt_f32_ubyte1_e32 v99, v76
	v_pk_fma_f32 v[84:85], v[42:43], v[146:147], v[84:85] op_sel_hi:[0,1,1]
	v_and_b32_e32 v82, s0, v166
	v_and_b32_e32 v83, s1, v166
	v_and_b32_e32 v88, s0, v167
	v_and_b32_e32 v89, s1, v167
	v_cvt_f32_ubyte2_e32 v102, v76
	v_cvt_f32_ubyte3_e32 v103, v76
	v_pk_fma_f32 v[80:81], v[34:35], v[98:99], v[80:81] op_sel_hi:[0,1,1]
	v_cvt_f32_ubyte0_e32 v104, v77
	v_cvt_f32_ubyte1_e32 v105, v77
	v_pk_fma_f32 v[78:79], v[34:35], v[102:103], v[78:79] op_sel_hi:[0,1,1]
	v_cvt_f32_ubyte2_e32 v146, v77
	v_cvt_f32_ubyte3_e32 v147, v77
	v_pk_fma_f32 v[70:71], v[42:43], v[104:105], v[70:71] op_sel_hi:[0,1,1]
	v_cvt_f32_ubyte0_e32 v98, v82
	v_cvt_f32_ubyte1_e32 v99, v82
	v_pk_fma_f32 v[62:63], v[42:43], v[146:147], v[62:63] op_sel_hi:[0,1,1]
	v_cvt_f32_ubyte2_e32 v102, v82
	v_cvt_f32_ubyte3_e32 v103, v82
	v_pk_fma_f32 v[92:93], v[34:35], v[98:99], v[92:93] op_sel:[1,0,0]
	v_cvt_f32_ubyte0_e32 v104, v83
	v_cvt_f32_ubyte1_e32 v105, v83
	v_pk_fma_f32 v[90:91], v[34:35], v[102:103], v[90:91] op_sel:[1,0,0]
	v_cvt_f32_ubyte2_e32 v146, v83
	v_cvt_f32_ubyte3_e32 v147, v83
	v_pk_fma_f32 v[86:87], v[42:43], v[104:105], v[86:87] op_sel:[1,0,0]
	v_cvt_f32_ubyte0_e32 v98, v88
	v_cvt_f32_ubyte1_e32 v99, v88
	v_pk_fma_f32 v[84:85], v[42:43], v[146:147], v[84:85] op_sel:[1,0,0]
	v_and_b32_e32 v68, s0, v168
	v_and_b32_e32 v69, s1, v168
	v_and_b32_e32 v76, s0, v169
	v_and_b32_e32 v77, s1, v169
	v_cvt_f32_ubyte2_e32 v102, v88
	v_cvt_f32_ubyte3_e32 v103, v88
	v_pk_fma_f32 v[80:81], v[34:35], v[98:99], v[80:81] op_sel:[1,0,0]
	v_cvt_f32_ubyte0_e32 v104, v89
	v_cvt_f32_ubyte1_e32 v105, v89
	v_pk_fma_f32 v[78:79], v[34:35], v[102:103], v[78:79] op_sel:[1,0,0]
	v_cvt_f32_ubyte2_e32 v146, v89
	v_cvt_f32_ubyte3_e32 v147, v89
	v_pk_fma_f32 v[70:71], v[42:43], v[104:105], v[70:71] op_sel:[1,0,0]
	v_cvt_f32_ubyte0_e32 v98, v68
	v_cvt_f32_ubyte1_e32 v99, v68
	v_pk_fma_f32 v[62:63], v[42:43], v[146:147], v[62:63] op_sel:[1,0,0]
	v_cvt_f32_ubyte2_e32 v102, v68
	v_cvt_f32_ubyte3_e32 v103, v68
	v_pk_fma_f32 v[92:93], v[36:37], v[98:99], v[92:93] op_sel_hi:[0,1,1]
	v_cvt_f32_ubyte0_e32 v104, v69
	v_cvt_f32_ubyte1_e32 v105, v69
	v_pk_fma_f32 v[90:91], v[36:37], v[102:103], v[90:91] op_sel_hi:[0,1,1]
	v_cvt_f32_ubyte2_e32 v146, v69
	v_cvt_f32_ubyte3_e32 v147, v69
	v_pk_fma_f32 v[86:87], v[44:45], v[104:105], v[86:87] op_sel_hi:[0,1,1]
	v_cvt_f32_ubyte0_e32 v98, v76
	v_cvt_f32_ubyte1_e32 v99, v76
	v_pk_fma_f32 v[84:85], v[44:45], v[146:147], v[84:85] op_sel_hi:[0,1,1]
	v_and_b32_e32 v82, s0, v170
	v_and_b32_e32 v83, s1, v170
	v_and_b32_e32 v88, s0, v171
	v_and_b32_e32 v89, s1, v171
	v_cvt_f32_ubyte2_e32 v102, v76
	v_cvt_f32_ubyte3_e32 v103, v76
	v_pk_fma_f32 v[80:81], v[36:37], v[98:99], v[80:81] op_sel_hi:[0,1,1]
	v_cvt_f32_ubyte0_e32 v104, v77
	v_cvt_f32_ubyte1_e32 v105, v77
	v_pk_fma_f32 v[78:79], v[36:37], v[102:103], v[78:79] op_sel_hi:[0,1,1]
	v_cvt_f32_ubyte2_e32 v146, v77
	v_cvt_f32_ubyte3_e32 v147, v77
	v_pk_fma_f32 v[70:71], v[44:45], v[104:105], v[70:71] op_sel_hi:[0,1,1]
	v_cvt_f32_ubyte0_e32 v98, v82
	v_cvt_f32_ubyte1_e32 v99, v82
	v_pk_fma_f32 v[62:63], v[44:45], v[146:147], v[62:63] op_sel_hi:[0,1,1]
	v_cvt_f32_ubyte2_e32 v102, v82
	v_cvt_f32_ubyte3_e32 v103, v82
	v_pk_fma_f32 v[92:93], v[36:37], v[98:99], v[92:93] op_sel:[1,0,0]
	v_cvt_f32_ubyte0_e32 v104, v83
	v_cvt_f32_ubyte1_e32 v105, v83
	v_pk_fma_f32 v[90:91], v[36:37], v[102:103], v[90:91] op_sel:[1,0,0]
	v_cvt_f32_ubyte2_e32 v146, v83
	v_cvt_f32_ubyte3_e32 v147, v83
	v_pk_fma_f32 v[86:87], v[44:45], v[104:105], v[86:87] op_sel:[1,0,0]
	v_cvt_f32_ubyte0_e32 v98, v88
	v_cvt_f32_ubyte1_e32 v99, v88
	v_pk_fma_f32 v[84:85], v[44:45], v[146:147], v[84:85] op_sel:[1,0,0]
	v_and_b32_e32 v68, s0, v172
	v_and_b32_e32 v69, s1, v172
	v_and_b32_e32 v76, s0, v173
	v_and_b32_e32 v77, s1, v173
	v_cvt_f32_ubyte2_e32 v102, v88
	v_cvt_f32_ubyte3_e32 v103, v88
	v_pk_fma_f32 v[80:81], v[36:37], v[98:99], v[80:81] op_sel:[1,0,0]
	v_cvt_f32_ubyte0_e32 v104, v89
	v_cvt_f32_ubyte1_e32 v105, v89
	v_pk_fma_f32 v[78:79], v[36:37], v[102:103], v[78:79] op_sel:[1,0,0]
	v_cvt_f32_ubyte2_e32 v146, v89
	v_cvt_f32_ubyte3_e32 v147, v89
	v_pk_fma_f32 v[70:71], v[44:45], v[104:105], v[70:71] op_sel:[1,0,0]
	v_cvt_f32_ubyte0_e32 v98, v68
	v_cvt_f32_ubyte1_e32 v99, v68
	v_pk_fma_f32 v[62:63], v[44:45], v[146:147], v[62:63] op_sel:[1,0,0]
	v_cvt_f32_ubyte2_e32 v102, v68
	v_cvt_f32_ubyte3_e32 v103, v68
	v_pk_fma_f32 v[92:93], v[38:39], v[98:99], v[92:93] op_sel_hi:[0,1,1]
	v_cvt_f32_ubyte0_e32 v104, v69
	v_cvt_f32_ubyte1_e32 v105, v69
	v_pk_fma_f32 v[90:91], v[38:39], v[102:103], v[90:91] op_sel_hi:[0,1,1]
	v_cvt_f32_ubyte2_e32 v146, v69
	v_cvt_f32_ubyte3_e32 v147, v69
	v_pk_fma_f32 v[86:87], v[46:47], v[104:105], v[86:87] op_sel_hi:[0,1,1]
	v_cvt_f32_ubyte0_e32 v98, v76
	v_cvt_f32_ubyte1_e32 v99, v76
	v_pk_fma_f32 v[84:85], v[46:47], v[146:147], v[84:85] op_sel_hi:[0,1,1]
	v_and_b32_e32 v82, s0, v174
	v_and_b32_e32 v83, s1, v174
	v_and_b32_e32 v88, s0, v175
	v_and_b32_e32 v89, s1, v175
	v_cvt_f32_ubyte2_e32 v102, v76
	v_cvt_f32_ubyte3_e32 v103, v76
	v_pk_fma_f32 v[80:81], v[38:39], v[98:99], v[80:81] op_sel_hi:[0,1,1]
	v_cvt_f32_ubyte0_e32 v104, v77
	v_cvt_f32_ubyte1_e32 v105, v77
	v_pk_fma_f32 v[78:79], v[38:39], v[102:103], v[78:79] op_sel_hi:[0,1,1]
	v_cvt_f32_ubyte2_e32 v146, v77
	v_cvt_f32_ubyte3_e32 v147, v77
	v_pk_fma_f32 v[70:71], v[46:47], v[104:105], v[70:71] op_sel_hi:[0,1,1]
	v_cvt_f32_ubyte0_e32 v98, v82
	v_cvt_f32_ubyte1_e32 v99, v82
	v_pk_fma_f32 v[62:63], v[46:47], v[146:147], v[62:63] op_sel_hi:[0,1,1]
	v_cvt_f32_ubyte2_e32 v102, v82
	v_cvt_f32_ubyte3_e32 v103, v82
	v_pk_fma_f32 v[92:93], v[38:39], v[98:99], v[92:93] op_sel:[1,0,0]
	v_cvt_f32_ubyte0_e32 v104, v83
	v_cvt_f32_ubyte1_e32 v105, v83
	v_pk_fma_f32 v[90:91], v[38:39], v[102:103], v[90:91] op_sel:[1,0,0]
	v_cvt_f32_ubyte2_e32 v146, v83
	v_cvt_f32_ubyte3_e32 v147, v83
	v_pk_fma_f32 v[86:87], v[46:47], v[104:105], v[86:87] op_sel:[1,0,0]
	v_cvt_f32_ubyte0_e32 v98, v88
	v_cvt_f32_ubyte1_e32 v99, v88
	v_pk_fma_f32 v[84:85], v[46:47], v[146:147], v[84:85] op_sel:[1,0,0]
	v_and_b32_e32 v68, s0, v176
	v_and_b32_e32 v69, s1, v176
	v_and_b32_e32 v76, s0, v177
	v_and_b32_e32 v77, s1, v177
	v_cvt_f32_ubyte2_e32 v102, v88
	v_cvt_f32_ubyte3_e32 v103, v88
	v_pk_fma_f32 v[80:81], v[38:39], v[98:99], v[80:81] op_sel:[1,0,0]
	v_cvt_f32_ubyte0_e32 v104, v89
	v_cvt_f32_ubyte1_e32 v105, v89
	v_pk_fma_f32 v[78:79], v[38:39], v[102:103], v[78:79] op_sel:[1,0,0]
	v_cvt_f32_ubyte2_e32 v146, v89
	v_cvt_f32_ubyte3_e32 v147, v89
	v_pk_fma_f32 v[70:71], v[46:47], v[104:105], v[70:71] op_sel:[1,0,0]
	v_cvt_f32_ubyte0_e32 v98, v68
	v_cvt_f32_ubyte1_e32 v99, v68
	v_pk_fma_f32 v[62:63], v[46:47], v[146:147], v[62:63] op_sel:[1,0,0]
	v_cvt_f32_ubyte2_e32 v102, v68
	v_cvt_f32_ubyte3_e32 v103, v68
	v_pk_fma_f32 v[92:93], v[40:41], v[98:99], v[92:93] op_sel_hi:[0,1,1]
	v_cvt_f32_ubyte0_e32 v104, v69
	v_cvt_f32_ubyte1_e32 v105, v69
	v_pk_fma_f32 v[90:91], v[40:41], v[102:103], v[90:91] op_sel_hi:[0,1,1]
	v_cvt_f32_ubyte2_e32 v146, v69
	v_cvt_f32_ubyte3_e32 v147, v69
	v_pk_fma_f32 v[86:87], v[48:49], v[104:105], v[86:87] op_sel_hi:[0,1,1]
	v_cvt_f32_ubyte0_e32 v98, v76
	v_cvt_f32_ubyte1_e32 v99, v76
	v_pk_fma_f32 v[84:85], v[48:49], v[146:147], v[84:85] op_sel_hi:[0,1,1]
	v_and_b32_e32 v82, s0, v178
	v_and_b32_e32 v83, s1, v178
	v_and_b32_e32 v88, s0, v179
	v_and_b32_e32 v89, s1, v179
	v_cvt_f32_ubyte2_e32 v102, v76
	v_cvt_f32_ubyte3_e32 v103, v76
	v_pk_fma_f32 v[80:81], v[40:41], v[98:99], v[80:81] op_sel_hi:[0,1,1]
	v_cvt_f32_ubyte0_e32 v104, v77
	v_cvt_f32_ubyte1_e32 v105, v77
	v_pk_fma_f32 v[78:79], v[40:41], v[102:103], v[78:79] op_sel_hi:[0,1,1]
	v_cvt_f32_ubyte2_e32 v146, v77
	v_cvt_f32_ubyte3_e32 v147, v77
	v_pk_fma_f32 v[70:71], v[48:49], v[104:105], v[70:71] op_sel_hi:[0,1,1]
	v_cvt_f32_ubyte0_e32 v98, v82
	v_cvt_f32_ubyte1_e32 v99, v82
	v_pk_fma_f32 v[62:63], v[48:49], v[146:147], v[62:63] op_sel_hi:[0,1,1]
	v_cvt_f32_ubyte2_e32 v102, v82
	v_cvt_f32_ubyte3_e32 v103, v82
	v_pk_fma_f32 v[92:93], v[40:41], v[98:99], v[92:93] op_sel:[1,0,0]
	v_cvt_f32_ubyte0_e32 v104, v83
	v_cvt_f32_ubyte1_e32 v105, v83
	v_pk_fma_f32 v[90:91], v[40:41], v[102:103], v[90:91] op_sel:[1,0,0]
	v_cvt_f32_ubyte2_e32 v146, v83
	v_cvt_f32_ubyte3_e32 v147, v83
	v_pk_fma_f32 v[86:87], v[48:49], v[104:105], v[86:87] op_sel:[1,0,0]
	v_cvt_f32_ubyte0_e32 v98, v88
	v_cvt_f32_ubyte1_e32 v99, v88
	v_pk_fma_f32 v[84:85], v[48:49], v[146:147], v[84:85] op_sel:[1,0,0]
	v_cvt_f32_ubyte2_e32 v102, v88
	v_cvt_f32_ubyte3_e32 v103, v88
	v_pk_fma_f32 v[80:81], v[40:41], v[98:99], v[80:81] op_sel:[1,0,0]
	v_cvt_f32_ubyte0_e32 v104, v89
	v_cvt_f32_ubyte1_e32 v105, v89
	v_pk_fma_f32 v[78:79], v[40:41], v[102:103], v[78:79] op_sel:[1,0,0]
	v_cvt_f32_ubyte2_e32 v146, v89
	v_cvt_f32_ubyte3_e32 v147, v89
	v_pk_fma_f32 v[70:71], v[48:49], v[104:105], v[70:71] op_sel:[1,0,0]
	v_pk_fma_f32 v[62:63], v[48:49], v[146:147], v[62:63] op_sel:[1,0,0]
	s_waitcnt lgkmcnt(0)
	ds_read_b128 v[34:37], v1 offset:960
	ds_read_b128 v[38:41], v1 offset:976
	ds_read_b128 v[42:45], v1 offset:1984
	ds_read_b128 v[46:49], v1 offset:2000
	s_waitcnt vmcnt(16)
	v_and_b32_e32 v68, s0, v180
	v_and_b32_e32 v69, s1, v180
	v_and_b32_e32 v76, s0, v181
	v_and_b32_e32 v77, s1, v181
	v_cvt_f32_ubyte0_e32 v98, v68
	v_cvt_f32_ubyte1_e32 v99, v68
	v_cvt_f32_ubyte2_e32 v102, v68
	v_cvt_f32_ubyte3_e32 v103, v68
	v_pk_fma_f32 v[92:93], v[50:51], v[98:99], v[92:93] op_sel_hi:[0,1,1]
	v_cvt_f32_ubyte0_e32 v104, v69
	v_cvt_f32_ubyte1_e32 v105, v69
	v_pk_fma_f32 v[90:91], v[50:51], v[102:103], v[90:91] op_sel_hi:[0,1,1]
	v_cvt_f32_ubyte2_e32 v146, v69
	v_cvt_f32_ubyte3_e32 v147, v69
	v_pk_fma_f32 v[86:87], v[58:59], v[104:105], v[86:87] op_sel_hi:[0,1,1]
	v_cvt_f32_ubyte0_e32 v98, v76
	v_cvt_f32_ubyte1_e32 v99, v76
	v_pk_fma_f32 v[84:85], v[58:59], v[146:147], v[84:85] op_sel_hi:[0,1,1]
	v_and_b32_e32 v82, s0, v182
	v_and_b32_e32 v83, s1, v182
	v_and_b32_e32 v88, s0, v183
	v_and_b32_e32 v89, s1, v183
	v_cvt_f32_ubyte2_e32 v102, v76
	v_cvt_f32_ubyte3_e32 v103, v76
	v_pk_fma_f32 v[80:81], v[50:51], v[98:99], v[80:81] op_sel_hi:[0,1,1]
	v_cvt_f32_ubyte0_e32 v104, v77
	v_cvt_f32_ubyte1_e32 v105, v77
	v_pk_fma_f32 v[78:79], v[50:51], v[102:103], v[78:79] op_sel_hi:[0,1,1]
	v_cvt_f32_ubyte2_e32 v146, v77
	v_cvt_f32_ubyte3_e32 v147, v77
	v_pk_fma_f32 v[70:71], v[58:59], v[104:105], v[70:71] op_sel_hi:[0,1,1]
	v_cvt_f32_ubyte0_e32 v98, v82
	v_cvt_f32_ubyte1_e32 v99, v82
	v_pk_fma_f32 v[62:63], v[58:59], v[146:147], v[62:63] op_sel_hi:[0,1,1]
	v_cvt_f32_ubyte2_e32 v102, v82
	v_cvt_f32_ubyte3_e32 v103, v82
	v_pk_fma_f32 v[92:93], v[50:51], v[98:99], v[92:93] op_sel:[1,0,0]
	v_cvt_f32_ubyte0_e32 v104, v83
	v_cvt_f32_ubyte1_e32 v105, v83
	v_pk_fma_f32 v[90:91], v[50:51], v[102:103], v[90:91] op_sel:[1,0,0]
	v_cvt_f32_ubyte2_e32 v146, v83
	v_cvt_f32_ubyte3_e32 v147, v83
	v_pk_fma_f32 v[86:87], v[58:59], v[104:105], v[86:87] op_sel:[1,0,0]
	v_cvt_f32_ubyte0_e32 v98, v88
	v_cvt_f32_ubyte1_e32 v99, v88
	v_pk_fma_f32 v[84:85], v[58:59], v[146:147], v[84:85] op_sel:[1,0,0]
	v_and_b32_e32 v68, s0, v184
	v_and_b32_e32 v69, s1, v184
	v_and_b32_e32 v76, s0, v185
	v_and_b32_e32 v77, s1, v185
	v_cvt_f32_ubyte2_e32 v102, v88
	v_cvt_f32_ubyte3_e32 v103, v88
	v_pk_fma_f32 v[80:81], v[50:51], v[98:99], v[80:81] op_sel:[1,0,0]
	v_cvt_f32_ubyte0_e32 v104, v89
	v_cvt_f32_ubyte1_e32 v105, v89
	v_pk_fma_f32 v[78:79], v[50:51], v[102:103], v[78:79] op_sel:[1,0,0]
	v_cvt_f32_ubyte2_e32 v146, v89
	v_cvt_f32_ubyte3_e32 v147, v89
	v_pk_fma_f32 v[70:71], v[58:59], v[104:105], v[70:71] op_sel:[1,0,0]
	v_cvt_f32_ubyte0_e32 v98, v68
	v_cvt_f32_ubyte1_e32 v99, v68
	v_pk_fma_f32 v[62:63], v[58:59], v[146:147], v[62:63] op_sel:[1,0,0]
	v_cvt_f32_ubyte2_e32 v102, v68
	v_cvt_f32_ubyte3_e32 v103, v68
	v_pk_fma_f32 v[92:93], v[52:53], v[98:99], v[92:93] op_sel_hi:[0,1,1]
	v_cvt_f32_ubyte0_e32 v104, v69
	v_cvt_f32_ubyte1_e32 v105, v69
	v_pk_fma_f32 v[90:91], v[52:53], v[102:103], v[90:91] op_sel_hi:[0,1,1]
	v_cvt_f32_ubyte2_e32 v146, v69
	v_cvt_f32_ubyte3_e32 v147, v69
	v_pk_fma_f32 v[86:87], v[60:61], v[104:105], v[86:87] op_sel_hi:[0,1,1]
	v_cvt_f32_ubyte0_e32 v98, v76
	v_cvt_f32_ubyte1_e32 v99, v76
	v_pk_fma_f32 v[84:85], v[60:61], v[146:147], v[84:85] op_sel_hi:[0,1,1]
	v_and_b32_e32 v82, s0, v186
	v_and_b32_e32 v83, s1, v186
	v_and_b32_e32 v88, s0, v187
	v_and_b32_e32 v89, s1, v187
	v_cvt_f32_ubyte2_e32 v102, v76
	v_cvt_f32_ubyte3_e32 v103, v76
	v_pk_fma_f32 v[80:81], v[52:53], v[98:99], v[80:81] op_sel_hi:[0,1,1]
	v_cvt_f32_ubyte0_e32 v104, v77
	v_cvt_f32_ubyte1_e32 v105, v77
	v_pk_fma_f32 v[78:79], v[52:53], v[102:103], v[78:79] op_sel_hi:[0,1,1]
	v_cvt_f32_ubyte2_e32 v146, v77
	v_cvt_f32_ubyte3_e32 v147, v77
	v_pk_fma_f32 v[70:71], v[60:61], v[104:105], v[70:71] op_sel_hi:[0,1,1]
	v_cvt_f32_ubyte0_e32 v98, v82
	v_cvt_f32_ubyte1_e32 v99, v82
	v_pk_fma_f32 v[62:63], v[60:61], v[146:147], v[62:63] op_sel_hi:[0,1,1]
	v_cvt_f32_ubyte2_e32 v102, v82
	v_cvt_f32_ubyte3_e32 v103, v82
	v_pk_fma_f32 v[92:93], v[52:53], v[98:99], v[92:93] op_sel:[1,0,0]
	v_cvt_f32_ubyte0_e32 v104, v83
	v_cvt_f32_ubyte1_e32 v105, v83
	v_pk_fma_f32 v[90:91], v[52:53], v[102:103], v[90:91] op_sel:[1,0,0]
	v_cvt_f32_ubyte2_e32 v146, v83
	v_cvt_f32_ubyte3_e32 v147, v83
	v_pk_fma_f32 v[86:87], v[60:61], v[104:105], v[86:87] op_sel:[1,0,0]
	v_cvt_f32_ubyte0_e32 v98, v88
	v_cvt_f32_ubyte1_e32 v99, v88
	v_pk_fma_f32 v[84:85], v[60:61], v[146:147], v[84:85] op_sel:[1,0,0]
	v_and_b32_e32 v68, s0, v188
	v_and_b32_e32 v69, s1, v188
	v_and_b32_e32 v76, s0, v189
	v_and_b32_e32 v77, s1, v189
	v_cvt_f32_ubyte2_e32 v102, v88
	v_cvt_f32_ubyte3_e32 v103, v88
	v_pk_fma_f32 v[80:81], v[52:53], v[98:99], v[80:81] op_sel:[1,0,0]
	v_cvt_f32_ubyte0_e32 v104, v89
	v_cvt_f32_ubyte1_e32 v105, v89
	v_pk_fma_f32 v[78:79], v[52:53], v[102:103], v[78:79] op_sel:[1,0,0]
	v_cvt_f32_ubyte2_e32 v146, v89
	v_cvt_f32_ubyte3_e32 v147, v89
	v_pk_fma_f32 v[70:71], v[60:61], v[104:105], v[70:71] op_sel:[1,0,0]
	v_cvt_f32_ubyte0_e32 v98, v68
	v_cvt_f32_ubyte1_e32 v99, v68
	v_pk_fma_f32 v[62:63], v[60:61], v[146:147], v[62:63] op_sel:[1,0,0]
	v_cvt_f32_ubyte2_e32 v102, v68
	v_cvt_f32_ubyte3_e32 v103, v68
	v_pk_fma_f32 v[92:93], v[54:55], v[98:99], v[92:93] op_sel_hi:[0,1,1]
	v_cvt_f32_ubyte0_e32 v104, v69
	v_cvt_f32_ubyte1_e32 v105, v69
	v_pk_fma_f32 v[90:91], v[54:55], v[102:103], v[90:91] op_sel_hi:[0,1,1]
	v_cvt_f32_ubyte2_e32 v146, v69
	v_cvt_f32_ubyte3_e32 v147, v69
	v_pk_fma_f32 v[86:87], v[64:65], v[104:105], v[86:87] op_sel_hi:[0,1,1]
	v_cvt_f32_ubyte0_e32 v98, v76
	v_cvt_f32_ubyte1_e32 v99, v76
	v_pk_fma_f32 v[84:85], v[64:65], v[146:147], v[84:85] op_sel_hi:[0,1,1]
	v_and_b32_e32 v82, s0, v190
	v_and_b32_e32 v83, s1, v190
	v_and_b32_e32 v88, s0, v191
	v_and_b32_e32 v89, s1, v191
	v_cvt_f32_ubyte2_e32 v102, v76
	v_cvt_f32_ubyte3_e32 v103, v76
	v_pk_fma_f32 v[80:81], v[54:55], v[98:99], v[80:81] op_sel_hi:[0,1,1]
	v_cvt_f32_ubyte0_e32 v104, v77
	v_cvt_f32_ubyte1_e32 v105, v77
	v_pk_fma_f32 v[78:79], v[54:55], v[102:103], v[78:79] op_sel_hi:[0,1,1]
	v_cvt_f32_ubyte2_e32 v146, v77
	v_cvt_f32_ubyte3_e32 v147, v77
	v_pk_fma_f32 v[70:71], v[64:65], v[104:105], v[70:71] op_sel_hi:[0,1,1]
	v_cvt_f32_ubyte0_e32 v98, v82
	v_cvt_f32_ubyte1_e32 v99, v82
	v_pk_fma_f32 v[62:63], v[64:65], v[146:147], v[62:63] op_sel_hi:[0,1,1]
	v_cvt_f32_ubyte2_e32 v102, v82
	v_cvt_f32_ubyte3_e32 v103, v82
	v_pk_fma_f32 v[92:93], v[54:55], v[98:99], v[92:93] op_sel:[1,0,0]
	v_cvt_f32_ubyte0_e32 v104, v83
	v_cvt_f32_ubyte1_e32 v105, v83
	v_pk_fma_f32 v[90:91], v[54:55], v[102:103], v[90:91] op_sel:[1,0,0]
	v_cvt_f32_ubyte2_e32 v146, v83
	v_cvt_f32_ubyte3_e32 v147, v83
	v_pk_fma_f32 v[86:87], v[64:65], v[104:105], v[86:87] op_sel:[1,0,0]
	v_cvt_f32_ubyte0_e32 v98, v88
	v_cvt_f32_ubyte1_e32 v99, v88
	v_pk_fma_f32 v[84:85], v[64:65], v[146:147], v[84:85] op_sel:[1,0,0]
	v_and_b32_e32 v68, s0, v192
	v_and_b32_e32 v69, s1, v192
	v_and_b32_e32 v76, s0, v193
	v_and_b32_e32 v77, s1, v193
	v_cvt_f32_ubyte2_e32 v102, v88
	v_cvt_f32_ubyte3_e32 v103, v88
	v_pk_fma_f32 v[80:81], v[54:55], v[98:99], v[80:81] op_sel:[1,0,0]
	v_cvt_f32_ubyte0_e32 v104, v89
	v_cvt_f32_ubyte1_e32 v105, v89
	v_pk_fma_f32 v[78:79], v[54:55], v[102:103], v[78:79] op_sel:[1,0,0]
	v_cvt_f32_ubyte2_e32 v146, v89
	v_cvt_f32_ubyte3_e32 v147, v89
	v_pk_fma_f32 v[70:71], v[64:65], v[104:105], v[70:71] op_sel:[1,0,0]
	v_cvt_f32_ubyte0_e32 v98, v68
	v_cvt_f32_ubyte1_e32 v99, v68
	v_pk_fma_f32 v[62:63], v[64:65], v[146:147], v[62:63] op_sel:[1,0,0]
	v_cvt_f32_ubyte2_e32 v102, v68
	v_cvt_f32_ubyte3_e32 v103, v68
	v_pk_fma_f32 v[92:93], v[56:57], v[98:99], v[92:93] op_sel_hi:[0,1,1]
	v_cvt_f32_ubyte0_e32 v104, v69
	v_cvt_f32_ubyte1_e32 v105, v69
	v_pk_fma_f32 v[90:91], v[56:57], v[102:103], v[90:91] op_sel_hi:[0,1,1]
	v_cvt_f32_ubyte2_e32 v146, v69
	v_cvt_f32_ubyte3_e32 v147, v69
	v_pk_fma_f32 v[86:87], v[66:67], v[104:105], v[86:87] op_sel_hi:[0,1,1]
	v_cvt_f32_ubyte0_e32 v98, v76
	v_cvt_f32_ubyte1_e32 v99, v76
	v_pk_fma_f32 v[84:85], v[66:67], v[146:147], v[84:85] op_sel_hi:[0,1,1]
	v_and_b32_e32 v82, s0, v194
	v_and_b32_e32 v83, s1, v194
	v_and_b32_e32 v88, s0, v195
	v_and_b32_e32 v89, s1, v195
	v_cvt_f32_ubyte2_e32 v102, v76
	v_cvt_f32_ubyte3_e32 v103, v76
	v_pk_fma_f32 v[80:81], v[56:57], v[98:99], v[80:81] op_sel_hi:[0,1,1]
	v_cvt_f32_ubyte0_e32 v104, v77
	v_cvt_f32_ubyte1_e32 v105, v77
	v_pk_fma_f32 v[78:79], v[56:57], v[102:103], v[78:79] op_sel_hi:[0,1,1]
	v_cvt_f32_ubyte2_e32 v146, v77
	v_cvt_f32_ubyte3_e32 v147, v77
	v_pk_fma_f32 v[70:71], v[66:67], v[104:105], v[70:71] op_sel_hi:[0,1,1]
	v_cvt_f32_ubyte0_e32 v98, v82
	v_cvt_f32_ubyte1_e32 v99, v82
	v_pk_fma_f32 v[62:63], v[66:67], v[146:147], v[62:63] op_sel_hi:[0,1,1]
	v_cvt_f32_ubyte2_e32 v102, v82
	v_cvt_f32_ubyte3_e32 v103, v82
	v_pk_fma_f32 v[92:93], v[56:57], v[98:99], v[92:93] op_sel:[1,0,0]
	v_cvt_f32_ubyte0_e32 v104, v83
	v_cvt_f32_ubyte1_e32 v105, v83
	v_pk_fma_f32 v[90:91], v[56:57], v[102:103], v[90:91] op_sel:[1,0,0]
	v_cvt_f32_ubyte2_e32 v146, v83
	v_cvt_f32_ubyte3_e32 v147, v83
	v_pk_fma_f32 v[86:87], v[66:67], v[104:105], v[86:87] op_sel:[1,0,0]
	v_cvt_f32_ubyte0_e32 v98, v88
	v_cvt_f32_ubyte1_e32 v99, v88
	v_pk_fma_f32 v[84:85], v[66:67], v[146:147], v[84:85] op_sel:[1,0,0]
	v_cvt_f32_ubyte2_e32 v102, v88
	v_cvt_f32_ubyte3_e32 v103, v88
	v_pk_fma_f32 v[80:81], v[56:57], v[98:99], v[80:81] op_sel:[1,0,0]
	v_cvt_f32_ubyte0_e32 v104, v89
	v_cvt_f32_ubyte1_e32 v105, v89
	v_pk_fma_f32 v[78:79], v[56:57], v[102:103], v[78:79] op_sel:[1,0,0]
	v_cvt_f32_ubyte2_e32 v146, v89
	v_cvt_f32_ubyte3_e32 v147, v89
	v_pk_fma_f32 v[70:71], v[66:67], v[104:105], v[70:71] op_sel:[1,0,0]
	v_pk_fma_f32 v[62:63], v[66:67], v[146:147], v[62:63] op_sel:[1,0,0]
	s_waitcnt lgkmcnt(0)
	ds_read_b128 v[50:53], v1 offset:992
	ds_read_b128 v[54:57], v1 offset:1008
	ds_read_b128 v[58:61], v1 offset:2016
	ds_read_b128 v[64:67], v1 offset:2032
	s_waitcnt vmcnt(8)
	v_and_b32_e32 v68, s0, v196
	v_and_b32_e32 v69, s1, v196
	v_and_b32_e32 v76, s0, v197
	v_and_b32_e32 v77, s1, v197
	v_cvt_f32_ubyte0_e32 v98, v68
	v_cvt_f32_ubyte1_e32 v99, v68
	v_cvt_f32_ubyte2_e32 v102, v68
	v_cvt_f32_ubyte3_e32 v103, v68
	v_pk_fma_f32 v[92:93], v[34:35], v[98:99], v[92:93] op_sel_hi:[0,1,1]
	v_cvt_f32_ubyte0_e32 v104, v69
	v_cvt_f32_ubyte1_e32 v105, v69
	v_pk_fma_f32 v[90:91], v[34:35], v[102:103], v[90:91] op_sel_hi:[0,1,1]
	v_cvt_f32_ubyte2_e32 v146, v69
	v_cvt_f32_ubyte3_e32 v147, v69
	v_pk_fma_f32 v[86:87], v[42:43], v[104:105], v[86:87] op_sel_hi:[0,1,1]
	v_cvt_f32_ubyte0_e32 v98, v76
	v_cvt_f32_ubyte1_e32 v99, v76
	v_pk_fma_f32 v[84:85], v[42:43], v[146:147], v[84:85] op_sel_hi:[0,1,1]
	v_and_b32_e32 v82, s0, v198
	v_and_b32_e32 v83, s1, v198
	v_and_b32_e32 v88, s0, v199
	v_and_b32_e32 v89, s1, v199
	v_cvt_f32_ubyte2_e32 v102, v76
	v_cvt_f32_ubyte3_e32 v103, v76
	v_pk_fma_f32 v[80:81], v[34:35], v[98:99], v[80:81] op_sel_hi:[0,1,1]
	v_cvt_f32_ubyte0_e32 v104, v77
	v_cvt_f32_ubyte1_e32 v105, v77
	v_pk_fma_f32 v[78:79], v[34:35], v[102:103], v[78:79] op_sel_hi:[0,1,1]
	v_cvt_f32_ubyte2_e32 v146, v77
	v_cvt_f32_ubyte3_e32 v147, v77
	v_pk_fma_f32 v[70:71], v[42:43], v[104:105], v[70:71] op_sel_hi:[0,1,1]
	v_cvt_f32_ubyte0_e32 v98, v82
	v_cvt_f32_ubyte1_e32 v99, v82
	v_pk_fma_f32 v[62:63], v[42:43], v[146:147], v[62:63] op_sel_hi:[0,1,1]
	v_cvt_f32_ubyte2_e32 v102, v82
	v_cvt_f32_ubyte3_e32 v103, v82
	v_pk_fma_f32 v[92:93], v[34:35], v[98:99], v[92:93] op_sel:[1,0,0]
	v_cvt_f32_ubyte0_e32 v104, v83
	v_cvt_f32_ubyte1_e32 v105, v83
	v_pk_fma_f32 v[90:91], v[34:35], v[102:103], v[90:91] op_sel:[1,0,0]
	v_cvt_f32_ubyte2_e32 v146, v83
	v_cvt_f32_ubyte3_e32 v147, v83
	v_pk_fma_f32 v[86:87], v[42:43], v[104:105], v[86:87] op_sel:[1,0,0]
	v_cvt_f32_ubyte0_e32 v98, v88
	v_cvt_f32_ubyte1_e32 v99, v88
	v_pk_fma_f32 v[84:85], v[42:43], v[146:147], v[84:85] op_sel:[1,0,0]
	v_and_b32_e32 v68, s0, v200
	v_and_b32_e32 v69, s1, v200
	v_and_b32_e32 v76, s0, v201
	v_and_b32_e32 v77, s1, v201
	v_cvt_f32_ubyte2_e32 v102, v88
	v_cvt_f32_ubyte3_e32 v103, v88
	v_pk_fma_f32 v[80:81], v[34:35], v[98:99], v[80:81] op_sel:[1,0,0]
	v_cvt_f32_ubyte0_e32 v104, v89
	v_cvt_f32_ubyte1_e32 v105, v89
	v_pk_fma_f32 v[78:79], v[34:35], v[102:103], v[78:79] op_sel:[1,0,0]
	v_cvt_f32_ubyte2_e32 v146, v89
	v_cvt_f32_ubyte3_e32 v147, v89
	v_pk_fma_f32 v[70:71], v[42:43], v[104:105], v[70:71] op_sel:[1,0,0]
	v_cvt_f32_ubyte0_e32 v98, v68
	v_cvt_f32_ubyte1_e32 v99, v68
	v_pk_fma_f32 v[62:63], v[42:43], v[146:147], v[62:63] op_sel:[1,0,0]
	v_cvt_f32_ubyte2_e32 v102, v68
	v_cvt_f32_ubyte3_e32 v103, v68
	v_pk_fma_f32 v[92:93], v[36:37], v[98:99], v[92:93] op_sel_hi:[0,1,1]
	v_cvt_f32_ubyte0_e32 v104, v69
	v_cvt_f32_ubyte1_e32 v105, v69
	v_pk_fma_f32 v[90:91], v[36:37], v[102:103], v[90:91] op_sel_hi:[0,1,1]
	v_cvt_f32_ubyte2_e32 v146, v69
	v_cvt_f32_ubyte3_e32 v147, v69
	v_pk_fma_f32 v[86:87], v[44:45], v[104:105], v[86:87] op_sel_hi:[0,1,1]
	v_cvt_f32_ubyte0_e32 v98, v76
	v_cvt_f32_ubyte1_e32 v99, v76
	v_pk_fma_f32 v[84:85], v[44:45], v[146:147], v[84:85] op_sel_hi:[0,1,1]
	v_and_b32_e32 v82, s0, v202
	v_and_b32_e32 v83, s1, v202
	v_and_b32_e32 v88, s0, v203
	v_and_b32_e32 v89, s1, v203
	v_cvt_f32_ubyte2_e32 v102, v76
	v_cvt_f32_ubyte3_e32 v103, v76
	v_pk_fma_f32 v[80:81], v[36:37], v[98:99], v[80:81] op_sel_hi:[0,1,1]
	v_cvt_f32_ubyte0_e32 v104, v77
	v_cvt_f32_ubyte1_e32 v105, v77
	v_pk_fma_f32 v[78:79], v[36:37], v[102:103], v[78:79] op_sel_hi:[0,1,1]
	v_cvt_f32_ubyte2_e32 v146, v77
	v_cvt_f32_ubyte3_e32 v147, v77
	v_pk_fma_f32 v[70:71], v[44:45], v[104:105], v[70:71] op_sel_hi:[0,1,1]
	v_cvt_f32_ubyte0_e32 v98, v82
	v_cvt_f32_ubyte1_e32 v99, v82
	v_pk_fma_f32 v[62:63], v[44:45], v[146:147], v[62:63] op_sel_hi:[0,1,1]
	v_cvt_f32_ubyte2_e32 v102, v82
	v_cvt_f32_ubyte3_e32 v103, v82
	v_pk_fma_f32 v[92:93], v[36:37], v[98:99], v[92:93] op_sel:[1,0,0]
	v_cvt_f32_ubyte0_e32 v104, v83
	v_cvt_f32_ubyte1_e32 v105, v83
	v_pk_fma_f32 v[90:91], v[36:37], v[102:103], v[90:91] op_sel:[1,0,0]
	v_cvt_f32_ubyte2_e32 v146, v83
	v_cvt_f32_ubyte3_e32 v147, v83
	v_pk_fma_f32 v[86:87], v[44:45], v[104:105], v[86:87] op_sel:[1,0,0]
	v_cvt_f32_ubyte0_e32 v98, v88
	v_cvt_f32_ubyte1_e32 v99, v88
	v_pk_fma_f32 v[84:85], v[44:45], v[146:147], v[84:85] op_sel:[1,0,0]
	v_and_b32_e32 v68, s0, v204
	v_and_b32_e32 v69, s1, v204
	v_and_b32_e32 v76, s0, v205
	v_and_b32_e32 v77, s1, v205
	v_cvt_f32_ubyte2_e32 v102, v88
	v_cvt_f32_ubyte3_e32 v103, v88
	v_pk_fma_f32 v[80:81], v[36:37], v[98:99], v[80:81] op_sel:[1,0,0]
	v_cvt_f32_ubyte0_e32 v104, v89
	v_cvt_f32_ubyte1_e32 v105, v89
	v_pk_fma_f32 v[78:79], v[36:37], v[102:103], v[78:79] op_sel:[1,0,0]
	v_cvt_f32_ubyte2_e32 v146, v89
	v_cvt_f32_ubyte3_e32 v147, v89
	v_pk_fma_f32 v[70:71], v[44:45], v[104:105], v[70:71] op_sel:[1,0,0]
	v_cvt_f32_ubyte0_e32 v98, v68
	v_cvt_f32_ubyte1_e32 v99, v68
	v_pk_fma_f32 v[62:63], v[44:45], v[146:147], v[62:63] op_sel:[1,0,0]
	v_cvt_f32_ubyte2_e32 v102, v68
	v_cvt_f32_ubyte3_e32 v103, v68
	v_pk_fma_f32 v[92:93], v[38:39], v[98:99], v[92:93] op_sel_hi:[0,1,1]
	v_cvt_f32_ubyte0_e32 v104, v69
	v_cvt_f32_ubyte1_e32 v105, v69
	v_pk_fma_f32 v[90:91], v[38:39], v[102:103], v[90:91] op_sel_hi:[0,1,1]
	v_cvt_f32_ubyte2_e32 v146, v69
	v_cvt_f32_ubyte3_e32 v147, v69
	v_pk_fma_f32 v[86:87], v[46:47], v[104:105], v[86:87] op_sel_hi:[0,1,1]
	v_cvt_f32_ubyte0_e32 v98, v76
	v_cvt_f32_ubyte1_e32 v99, v76
	v_pk_fma_f32 v[84:85], v[46:47], v[146:147], v[84:85] op_sel_hi:[0,1,1]
	v_and_b32_e32 v82, s0, v206
	v_and_b32_e32 v83, s1, v206
	v_and_b32_e32 v88, s0, v207
	v_and_b32_e32 v89, s1, v207
	v_cvt_f32_ubyte2_e32 v102, v76
	v_cvt_f32_ubyte3_e32 v103, v76
	v_pk_fma_f32 v[80:81], v[38:39], v[98:99], v[80:81] op_sel_hi:[0,1,1]
	v_cvt_f32_ubyte0_e32 v104, v77
	v_cvt_f32_ubyte1_e32 v105, v77
	v_pk_fma_f32 v[78:79], v[38:39], v[102:103], v[78:79] op_sel_hi:[0,1,1]
	v_cvt_f32_ubyte2_e32 v146, v77
	v_cvt_f32_ubyte3_e32 v147, v77
	v_pk_fma_f32 v[70:71], v[46:47], v[104:105], v[70:71] op_sel_hi:[0,1,1]
	v_cvt_f32_ubyte0_e32 v98, v82
	v_cvt_f32_ubyte1_e32 v99, v82
	v_pk_fma_f32 v[62:63], v[46:47], v[146:147], v[62:63] op_sel_hi:[0,1,1]
	v_cvt_f32_ubyte2_e32 v102, v82
	v_cvt_f32_ubyte3_e32 v103, v82
	v_pk_fma_f32 v[92:93], v[38:39], v[98:99], v[92:93] op_sel:[1,0,0]
	v_cvt_f32_ubyte0_e32 v104, v83
	v_cvt_f32_ubyte1_e32 v105, v83
	v_pk_fma_f32 v[90:91], v[38:39], v[102:103], v[90:91] op_sel:[1,0,0]
	v_cvt_f32_ubyte2_e32 v146, v83
	v_cvt_f32_ubyte3_e32 v147, v83
	v_pk_fma_f32 v[86:87], v[46:47], v[104:105], v[86:87] op_sel:[1,0,0]
	v_cvt_f32_ubyte0_e32 v98, v88
	v_cvt_f32_ubyte1_e32 v99, v88
	v_pk_fma_f32 v[84:85], v[46:47], v[146:147], v[84:85] op_sel:[1,0,0]
	v_and_b32_e32 v68, s0, v208
	v_and_b32_e32 v69, s1, v208
	v_and_b32_e32 v76, s0, v209
	v_and_b32_e32 v77, s1, v209
	v_cvt_f32_ubyte2_e32 v102, v88
	v_cvt_f32_ubyte3_e32 v103, v88
	v_pk_fma_f32 v[80:81], v[38:39], v[98:99], v[80:81] op_sel:[1,0,0]
	v_cvt_f32_ubyte0_e32 v104, v89
	v_cvt_f32_ubyte1_e32 v105, v89
	v_pk_fma_f32 v[78:79], v[38:39], v[102:103], v[78:79] op_sel:[1,0,0]
	v_cvt_f32_ubyte2_e32 v146, v89
	v_cvt_f32_ubyte3_e32 v147, v89
	v_pk_fma_f32 v[70:71], v[46:47], v[104:105], v[70:71] op_sel:[1,0,0]
	v_cvt_f32_ubyte0_e32 v98, v68
	v_cvt_f32_ubyte1_e32 v99, v68
	v_pk_fma_f32 v[62:63], v[46:47], v[146:147], v[62:63] op_sel:[1,0,0]
	v_cvt_f32_ubyte2_e32 v102, v68
	v_cvt_f32_ubyte3_e32 v103, v68
	v_pk_fma_f32 v[92:93], v[40:41], v[98:99], v[92:93] op_sel_hi:[0,1,1]
	v_cvt_f32_ubyte0_e32 v104, v69
	v_cvt_f32_ubyte1_e32 v105, v69
	v_pk_fma_f32 v[90:91], v[40:41], v[102:103], v[90:91] op_sel_hi:[0,1,1]
	v_cvt_f32_ubyte2_e32 v146, v69
	v_cvt_f32_ubyte3_e32 v147, v69
	v_pk_fma_f32 v[86:87], v[48:49], v[104:105], v[86:87] op_sel_hi:[0,1,1]
	v_cvt_f32_ubyte0_e32 v98, v76
	v_cvt_f32_ubyte1_e32 v99, v76
	v_pk_fma_f32 v[84:85], v[48:49], v[146:147], v[84:85] op_sel_hi:[0,1,1]
	v_and_b32_e32 v82, s0, v210
	v_and_b32_e32 v83, s1, v210
	v_and_b32_e32 v88, s0, v211
	v_and_b32_e32 v89, s1, v211
	v_cvt_f32_ubyte2_e32 v102, v76
	v_cvt_f32_ubyte3_e32 v103, v76
	v_pk_fma_f32 v[80:81], v[40:41], v[98:99], v[80:81] op_sel_hi:[0,1,1]
	v_cvt_f32_ubyte0_e32 v104, v77
	v_cvt_f32_ubyte1_e32 v105, v77
	v_pk_fma_f32 v[78:79], v[40:41], v[102:103], v[78:79] op_sel_hi:[0,1,1]
	v_cvt_f32_ubyte2_e32 v146, v77
	v_cvt_f32_ubyte3_e32 v147, v77
	v_pk_fma_f32 v[70:71], v[48:49], v[104:105], v[70:71] op_sel_hi:[0,1,1]
	v_cvt_f32_ubyte0_e32 v98, v82
	v_cvt_f32_ubyte1_e32 v99, v82
	v_pk_fma_f32 v[62:63], v[48:49], v[146:147], v[62:63] op_sel_hi:[0,1,1]
	v_cvt_f32_ubyte2_e32 v102, v82
	v_cvt_f32_ubyte3_e32 v103, v82
	v_pk_fma_f32 v[92:93], v[40:41], v[98:99], v[92:93] op_sel:[1,0,0]
	v_cvt_f32_ubyte0_e32 v104, v83
	v_cvt_f32_ubyte1_e32 v105, v83
	v_pk_fma_f32 v[90:91], v[40:41], v[102:103], v[90:91] op_sel:[1,0,0]
	v_cvt_f32_ubyte2_e32 v146, v83
	v_cvt_f32_ubyte3_e32 v147, v83
	v_pk_fma_f32 v[86:87], v[48:49], v[104:105], v[86:87] op_sel:[1,0,0]
	v_cvt_f32_ubyte0_e32 v98, v88
	v_cvt_f32_ubyte1_e32 v99, v88
	v_pk_fma_f32 v[84:85], v[48:49], v[146:147], v[84:85] op_sel:[1,0,0]
	v_cvt_f32_ubyte2_e32 v102, v88
	v_cvt_f32_ubyte3_e32 v103, v88
	v_pk_fma_f32 v[80:81], v[40:41], v[98:99], v[80:81] op_sel:[1,0,0]
	v_cvt_f32_ubyte0_e32 v104, v89
	v_cvt_f32_ubyte1_e32 v105, v89
	v_pk_fma_f32 v[78:79], v[40:41], v[102:103], v[78:79] op_sel:[1,0,0]
	v_cvt_f32_ubyte2_e32 v146, v89
	v_cvt_f32_ubyte3_e32 v147, v89
	v_pk_fma_f32 v[70:71], v[48:49], v[104:105], v[70:71] op_sel:[1,0,0]
	v_pk_fma_f32 v[62:63], v[48:49], v[146:147], v[62:63] op_sel:[1,0,0]
	s_waitcnt lgkmcnt(0)
	s_waitcnt vmcnt(0)
	v_and_b32_e32 v68, s0, v212
	v_and_b32_e32 v69, s1, v212
	v_and_b32_e32 v76, s0, v213
	v_and_b32_e32 v77, s1, v213
	v_cvt_f32_ubyte0_e32 v98, v68
	v_cvt_f32_ubyte1_e32 v99, v68
	v_cvt_f32_ubyte2_e32 v102, v68
	v_cvt_f32_ubyte3_e32 v103, v68
	v_pk_fma_f32 v[92:93], v[50:51], v[98:99], v[92:93] op_sel_hi:[0,1,1]
	v_cvt_f32_ubyte0_e32 v104, v69
	v_cvt_f32_ubyte1_e32 v105, v69
	v_pk_fma_f32 v[90:91], v[50:51], v[102:103], v[90:91] op_sel_hi:[0,1,1]
	v_cvt_f32_ubyte2_e32 v146, v69
	v_cvt_f32_ubyte3_e32 v147, v69
	v_pk_fma_f32 v[86:87], v[58:59], v[104:105], v[86:87] op_sel_hi:[0,1,1]
	v_cvt_f32_ubyte0_e32 v98, v76
	v_cvt_f32_ubyte1_e32 v99, v76
	v_pk_fma_f32 v[84:85], v[58:59], v[146:147], v[84:85] op_sel_hi:[0,1,1]
	v_and_b32_e32 v82, s0, v214
	v_and_b32_e32 v83, s1, v214
	v_and_b32_e32 v88, s0, v215
	v_and_b32_e32 v89, s1, v215
	v_cvt_f32_ubyte2_e32 v102, v76
	v_cvt_f32_ubyte3_e32 v103, v76
	v_pk_fma_f32 v[80:81], v[50:51], v[98:99], v[80:81] op_sel_hi:[0,1,1]
	v_cvt_f32_ubyte0_e32 v104, v77
	v_cvt_f32_ubyte1_e32 v105, v77
	v_pk_fma_f32 v[78:79], v[50:51], v[102:103], v[78:79] op_sel_hi:[0,1,1]
	v_cvt_f32_ubyte2_e32 v146, v77
	v_cvt_f32_ubyte3_e32 v147, v77
	v_pk_fma_f32 v[70:71], v[58:59], v[104:105], v[70:71] op_sel_hi:[0,1,1]
	v_cvt_f32_ubyte0_e32 v98, v82
	v_cvt_f32_ubyte1_e32 v99, v82
	v_pk_fma_f32 v[62:63], v[58:59], v[146:147], v[62:63] op_sel_hi:[0,1,1]
	v_cvt_f32_ubyte2_e32 v102, v82
	v_cvt_f32_ubyte3_e32 v103, v82
	v_pk_fma_f32 v[92:93], v[50:51], v[98:99], v[92:93] op_sel:[1,0,0]
	v_cvt_f32_ubyte0_e32 v104, v83
	v_cvt_f32_ubyte1_e32 v105, v83
	v_pk_fma_f32 v[90:91], v[50:51], v[102:103], v[90:91] op_sel:[1,0,0]
	v_cvt_f32_ubyte2_e32 v146, v83
	v_cvt_f32_ubyte3_e32 v147, v83
	v_pk_fma_f32 v[86:87], v[58:59], v[104:105], v[86:87] op_sel:[1,0,0]
	v_cvt_f32_ubyte0_e32 v98, v88
	v_cvt_f32_ubyte1_e32 v99, v88
	v_pk_fma_f32 v[84:85], v[58:59], v[146:147], v[84:85] op_sel:[1,0,0]
	v_and_b32_e32 v68, s0, v216
	v_and_b32_e32 v69, s1, v216
	v_and_b32_e32 v76, s0, v217
	v_and_b32_e32 v77, s1, v217
	v_cvt_f32_ubyte2_e32 v102, v88
	v_cvt_f32_ubyte3_e32 v103, v88
	v_pk_fma_f32 v[80:81], v[50:51], v[98:99], v[80:81] op_sel:[1,0,0]
	v_cvt_f32_ubyte0_e32 v104, v89
	v_cvt_f32_ubyte1_e32 v105, v89
	v_pk_fma_f32 v[78:79], v[50:51], v[102:103], v[78:79] op_sel:[1,0,0]
	v_cvt_f32_ubyte2_e32 v146, v89
	v_cvt_f32_ubyte3_e32 v147, v89
	v_pk_fma_f32 v[70:71], v[58:59], v[104:105], v[70:71] op_sel:[1,0,0]
	v_cvt_f32_ubyte0_e32 v98, v68
	v_cvt_f32_ubyte1_e32 v99, v68
	v_pk_fma_f32 v[62:63], v[58:59], v[146:147], v[62:63] op_sel:[1,0,0]
	v_cvt_f32_ubyte2_e32 v102, v68
	v_cvt_f32_ubyte3_e32 v103, v68
	v_pk_fma_f32 v[92:93], v[52:53], v[98:99], v[92:93] op_sel_hi:[0,1,1]
	v_cvt_f32_ubyte0_e32 v104, v69
	v_cvt_f32_ubyte1_e32 v105, v69
	v_pk_fma_f32 v[90:91], v[52:53], v[102:103], v[90:91] op_sel_hi:[0,1,1]
	v_cvt_f32_ubyte2_e32 v146, v69
	v_cvt_f32_ubyte3_e32 v147, v69
	v_pk_fma_f32 v[86:87], v[60:61], v[104:105], v[86:87] op_sel_hi:[0,1,1]
	v_cvt_f32_ubyte0_e32 v98, v76
	v_cvt_f32_ubyte1_e32 v99, v76
	v_pk_fma_f32 v[84:85], v[60:61], v[146:147], v[84:85] op_sel_hi:[0,1,1]
	v_and_b32_e32 v82, s0, v218
	v_and_b32_e32 v83, s1, v218
	v_and_b32_e32 v88, s0, v219
	v_and_b32_e32 v89, s1, v219
	v_cvt_f32_ubyte2_e32 v102, v76
	v_cvt_f32_ubyte3_e32 v103, v76
	v_pk_fma_f32 v[80:81], v[52:53], v[98:99], v[80:81] op_sel_hi:[0,1,1]
	v_cvt_f32_ubyte0_e32 v104, v77
	v_cvt_f32_ubyte1_e32 v105, v77
	v_pk_fma_f32 v[78:79], v[52:53], v[102:103], v[78:79] op_sel_hi:[0,1,1]
	v_cvt_f32_ubyte2_e32 v146, v77
	v_cvt_f32_ubyte3_e32 v147, v77
	v_pk_fma_f32 v[70:71], v[60:61], v[104:105], v[70:71] op_sel_hi:[0,1,1]
	v_cvt_f32_ubyte0_e32 v98, v82
	v_cvt_f32_ubyte1_e32 v99, v82
	v_pk_fma_f32 v[62:63], v[60:61], v[146:147], v[62:63] op_sel_hi:[0,1,1]
	v_cvt_f32_ubyte2_e32 v102, v82
	v_cvt_f32_ubyte3_e32 v103, v82
	v_pk_fma_f32 v[92:93], v[52:53], v[98:99], v[92:93] op_sel:[1,0,0]
	v_cvt_f32_ubyte0_e32 v104, v83
	v_cvt_f32_ubyte1_e32 v105, v83
	v_pk_fma_f32 v[90:91], v[52:53], v[102:103], v[90:91] op_sel:[1,0,0]
	v_cvt_f32_ubyte2_e32 v146, v83
	v_cvt_f32_ubyte3_e32 v147, v83
	v_pk_fma_f32 v[86:87], v[60:61], v[104:105], v[86:87] op_sel:[1,0,0]
	v_cvt_f32_ubyte0_e32 v98, v88
	v_cvt_f32_ubyte1_e32 v99, v88
	v_pk_fma_f32 v[84:85], v[60:61], v[146:147], v[84:85] op_sel:[1,0,0]
	v_and_b32_e32 v68, s0, v220
	v_and_b32_e32 v69, s1, v220
	v_and_b32_e32 v76, s0, v221
	v_and_b32_e32 v77, s1, v221
	v_cvt_f32_ubyte2_e32 v102, v88
	v_cvt_f32_ubyte3_e32 v103, v88
	v_pk_fma_f32 v[80:81], v[52:53], v[98:99], v[80:81] op_sel:[1,0,0]
	v_cvt_f32_ubyte0_e32 v104, v89
	v_cvt_f32_ubyte1_e32 v105, v89
	v_pk_fma_f32 v[78:79], v[52:53], v[102:103], v[78:79] op_sel:[1,0,0]
	v_cvt_f32_ubyte2_e32 v146, v89
	v_cvt_f32_ubyte3_e32 v147, v89
	v_pk_fma_f32 v[70:71], v[60:61], v[104:105], v[70:71] op_sel:[1,0,0]
	v_cvt_f32_ubyte0_e32 v98, v68
	v_cvt_f32_ubyte1_e32 v99, v68
	v_pk_fma_f32 v[62:63], v[60:61], v[146:147], v[62:63] op_sel:[1,0,0]
	v_cvt_f32_ubyte2_e32 v102, v68
	v_cvt_f32_ubyte3_e32 v103, v68
	v_pk_fma_f32 v[92:93], v[54:55], v[98:99], v[92:93] op_sel_hi:[0,1,1]
	v_cvt_f32_ubyte0_e32 v104, v69
	v_cvt_f32_ubyte1_e32 v105, v69
	v_pk_fma_f32 v[90:91], v[54:55], v[102:103], v[90:91] op_sel_hi:[0,1,1]
	v_cvt_f32_ubyte2_e32 v146, v69
	v_cvt_f32_ubyte3_e32 v147, v69
	v_pk_fma_f32 v[86:87], v[64:65], v[104:105], v[86:87] op_sel_hi:[0,1,1]
	v_cvt_f32_ubyte0_e32 v98, v76
	v_cvt_f32_ubyte1_e32 v99, v76
	v_pk_fma_f32 v[84:85], v[64:65], v[146:147], v[84:85] op_sel_hi:[0,1,1]
	v_and_b32_e32 v82, s0, v222
	v_and_b32_e32 v83, s1, v222
	v_and_b32_e32 v88, s0, v223
	v_and_b32_e32 v89, s1, v223
	v_cvt_f32_ubyte2_e32 v102, v76
	v_cvt_f32_ubyte3_e32 v103, v76
	v_pk_fma_f32 v[80:81], v[54:55], v[98:99], v[80:81] op_sel_hi:[0,1,1]
	v_cvt_f32_ubyte0_e32 v104, v77
	v_cvt_f32_ubyte1_e32 v105, v77
	v_pk_fma_f32 v[78:79], v[54:55], v[102:103], v[78:79] op_sel_hi:[0,1,1]
	v_cvt_f32_ubyte2_e32 v146, v77
	v_cvt_f32_ubyte3_e32 v147, v77
	v_pk_fma_f32 v[70:71], v[64:65], v[104:105], v[70:71] op_sel_hi:[0,1,1]
	v_cvt_f32_ubyte0_e32 v98, v82
	v_cvt_f32_ubyte1_e32 v99, v82
	v_pk_fma_f32 v[62:63], v[64:65], v[146:147], v[62:63] op_sel_hi:[0,1,1]
	v_cvt_f32_ubyte2_e32 v102, v82
	v_cvt_f32_ubyte3_e32 v103, v82
	v_pk_fma_f32 v[92:93], v[54:55], v[98:99], v[92:93] op_sel:[1,0,0]
	v_cvt_f32_ubyte0_e32 v104, v83
	v_cvt_f32_ubyte1_e32 v105, v83
	v_pk_fma_f32 v[90:91], v[54:55], v[102:103], v[90:91] op_sel:[1,0,0]
	v_cvt_f32_ubyte2_e32 v146, v83
	v_cvt_f32_ubyte3_e32 v147, v83
	v_pk_fma_f32 v[86:87], v[64:65], v[104:105], v[86:87] op_sel:[1,0,0]
	v_cvt_f32_ubyte0_e32 v98, v88
	v_cvt_f32_ubyte1_e32 v99, v88
	v_pk_fma_f32 v[84:85], v[64:65], v[146:147], v[84:85] op_sel:[1,0,0]
	v_and_b32_e32 v68, s0, v224
	v_and_b32_e32 v69, s1, v224
	v_and_b32_e32 v76, s0, v225
	v_and_b32_e32 v77, s1, v225
	v_cvt_f32_ubyte2_e32 v102, v88
	v_cvt_f32_ubyte3_e32 v103, v88
	v_pk_fma_f32 v[80:81], v[54:55], v[98:99], v[80:81] op_sel:[1,0,0]
	v_cvt_f32_ubyte0_e32 v104, v89
	v_cvt_f32_ubyte1_e32 v105, v89
	v_pk_fma_f32 v[78:79], v[54:55], v[102:103], v[78:79] op_sel:[1,0,0]
	v_cvt_f32_ubyte2_e32 v146, v89
	v_cvt_f32_ubyte3_e32 v147, v89
	v_pk_fma_f32 v[70:71], v[64:65], v[104:105], v[70:71] op_sel:[1,0,0]
	v_cvt_f32_ubyte0_e32 v98, v68
	v_cvt_f32_ubyte1_e32 v99, v68
	v_pk_fma_f32 v[62:63], v[64:65], v[146:147], v[62:63] op_sel:[1,0,0]
	v_cvt_f32_ubyte2_e32 v102, v68
	v_cvt_f32_ubyte3_e32 v103, v68
	v_pk_fma_f32 v[92:93], v[56:57], v[98:99], v[92:93] op_sel_hi:[0,1,1]
	v_cvt_f32_ubyte0_e32 v104, v69
	v_cvt_f32_ubyte1_e32 v105, v69
	v_pk_fma_f32 v[90:91], v[56:57], v[102:103], v[90:91] op_sel_hi:[0,1,1]
	v_cvt_f32_ubyte2_e32 v146, v69
	v_cvt_f32_ubyte3_e32 v147, v69
	v_pk_fma_f32 v[86:87], v[66:67], v[104:105], v[86:87] op_sel_hi:[0,1,1]
	v_cvt_f32_ubyte0_e32 v98, v76
	v_cvt_f32_ubyte1_e32 v99, v76
	v_pk_fma_f32 v[84:85], v[66:67], v[146:147], v[84:85] op_sel_hi:[0,1,1]
	v_and_b32_e32 v82, s0, v226
	v_and_b32_e32 v83, s1, v226
	v_and_b32_e32 v88, s0, v227
	v_and_b32_e32 v89, s1, v227
	v_cvt_f32_ubyte2_e32 v102, v76
	v_cvt_f32_ubyte3_e32 v103, v76
	v_pk_fma_f32 v[80:81], v[56:57], v[98:99], v[80:81] op_sel_hi:[0,1,1]
	v_cvt_f32_ubyte0_e32 v104, v77
	v_cvt_f32_ubyte1_e32 v105, v77
	v_pk_fma_f32 v[78:79], v[56:57], v[102:103], v[78:79] op_sel_hi:[0,1,1]
	v_cvt_f32_ubyte2_e32 v146, v77
	v_cvt_f32_ubyte3_e32 v147, v77
	v_pk_fma_f32 v[70:71], v[66:67], v[104:105], v[70:71] op_sel_hi:[0,1,1]
	v_cvt_f32_ubyte0_e32 v98, v82
	v_cvt_f32_ubyte1_e32 v99, v82
	v_pk_fma_f32 v[62:63], v[66:67], v[146:147], v[62:63] op_sel_hi:[0,1,1]
	v_cvt_f32_ubyte2_e32 v102, v82
	v_cvt_f32_ubyte3_e32 v103, v82
	v_pk_fma_f32 v[92:93], v[56:57], v[98:99], v[92:93] op_sel:[1,0,0]
	v_cvt_f32_ubyte0_e32 v104, v83
	v_cvt_f32_ubyte1_e32 v105, v83
	v_pk_fma_f32 v[90:91], v[56:57], v[102:103], v[90:91] op_sel:[1,0,0]
	v_cvt_f32_ubyte2_e32 v146, v83
	v_cvt_f32_ubyte3_e32 v147, v83
	v_pk_fma_f32 v[86:87], v[66:67], v[104:105], v[86:87] op_sel:[1,0,0]
	v_cvt_f32_ubyte0_e32 v98, v88
	v_cvt_f32_ubyte1_e32 v99, v88
	v_pk_fma_f32 v[84:85], v[66:67], v[146:147], v[84:85] op_sel:[1,0,0]
	v_cvt_f32_ubyte2_e32 v102, v88
	v_cvt_f32_ubyte3_e32 v103, v88
	v_pk_fma_f32 v[80:81], v[56:57], v[98:99], v[80:81] op_sel:[1,0,0]
	v_cvt_f32_ubyte0_e32 v104, v89
	v_cvt_f32_ubyte1_e32 v105, v89
	v_pk_fma_f32 v[78:79], v[56:57], v[102:103], v[78:79] op_sel:[1,0,0]
	v_cvt_f32_ubyte2_e32 v146, v89
	v_cvt_f32_ubyte3_e32 v147, v89
	v_pk_fma_f32 v[70:71], v[66:67], v[104:105], v[70:71] op_sel:[1,0,0]
	v_pk_fma_f32 v[62:63], v[66:67], v[146:147], v[62:63] op_sel:[1,0,0]
	s_waitcnt lgkmcnt(0)
	s_branch .LBB0_608

.LBB0_799:
	s_add_i32 s15, s14, 0x80
	s_min_u32 s4, s15, 0x3c0
	s_lshl_b32 s4, s4, 1
	v_lshl_add_u64 v[144:145], v[102:103], 0, s[4:5]
	v_add_co_u32_e32 v128, vcc, s8, v144
	v_lshl_add_u64 v[148:149], v[104:105], 0, s[4:5]
	s_nop 0
	v_addc_co_u32_e32 v129, vcc, 0, v145, vcc
	v_add_co_u32_e32 v132, vcc, s8, v148
	global_load_dwordx4 v[120:123], v[144:145], off
	global_load_dwordx4 v[124:127], v[148:149], off
	v_addc_co_u32_e32 v133, vcc, 0, v149, vcc
	v_add_co_u32_e32 v136, vcc, s9, v144
	global_load_dwordx4 v[128:131], v[128:129], off
	s_nop 0
	v_addc_co_u32_e32 v137, vcc, 0, v145, vcc
	v_add_co_u32_e32 v140, vcc, s9, v148
	global_load_dwordx4 v[132:135], v[132:133], off
	s_nop 0
	v_addc_co_u32_e32 v141, vcc, 0, v149, vcc
	v_add_co_u32_e32 v144, vcc, s10, v144
	global_load_dwordx4 v[136:139], v[136:137], off
	s_nop 0
	v_addc_co_u32_e32 v145, vcc, 0, v145, vcc
	v_add_co_u32_e32 v148, vcc, s10, v148
	global_load_dwordx4 v[140:143], v[140:141], off
	s_nop 0
	v_addc_co_u32_e32 v149, vcc, 0, v149, vcc
	global_load_dwordx4 v[144:147], v[144:145], off
	s_nop 0
	global_load_dwordx4 v[148:151], v[148:149], off
	s_setprio 1
	ds_read_b128 v[152:155], v111 offset:16384
	ds_read_b128 v[156:159], v111 offset:18432
	ds_read_b128 v[160:163], v109
	ds_read_b128 v[164:167], v109 offset:2048
	ds_read_b128 v[168:171], v111 offset:20480
	ds_read_b128 v[172:175], v112 offset:16384
	s_waitcnt lgkmcnt(3)
	v_mfma_f32_16x16x32_bf16 v[92:95], v[152:155], v[160:163], v[92:95]
	v_mfma_f32_16x16x32_bf16 v[88:91], v[156:159], v[160:163], v[88:91]
	s_waitcnt lgkmcnt(1)
	v_mfma_f32_16x16x32_bf16 v[84:87], v[168:171], v[160:163], v[84:87]
	s_waitcnt lgkmcnt(0)
	v_mfma_f32_16x16x32_bf16 v[80:83], v[172:175], v[160:163], v[80:83]
	v_mfma_f32_16x16x32_bf16 v[76:79], v[152:155], v[164:167], v[76:79]
	v_mfma_f32_16x16x32_bf16 v[72:75], v[156:159], v[164:167], v[72:75]
	v_mfma_f32_16x16x32_bf16 v[60:63], v[168:171], v[164:167], v[60:63]
	v_mfma_f32_16x16x32_bf16 v[28:31], v[172:175], v[164:167], v[28:31]
	ds_read_b128 v[160:163], v109 offset:4096
	ds_read_b128 v[164:167], v110
	s_waitcnt lgkmcnt(1)
	v_mfma_f32_16x16x32_bf16 v[64:67], v[152:155], v[160:163], v[64:67]
	v_mfma_f32_16x16x32_bf16 v[36:39], v[156:159], v[160:163], v[36:39]
	v_mfma_f32_16x16x32_bf16 v[32:35], v[168:171], v[160:163], v[32:35]
	v_mfma_f32_16x16x32_bf16 v[16:19], v[172:175], v[160:163], v[16:19]
	s_waitcnt lgkmcnt(0)
	v_mfma_f32_16x16x32_bf16 v[12:15], v[152:155], v[164:167], v[12:15]
	ds_read_b128 v[152:155], v115 offset:16384
	v_mfma_f32_16x16x32_bf16 v[8:11], v[156:159], v[164:167], v[8:11]
	v_mfma_f32_16x16x32_bf16 v[4:7], v[168:171], v[164:167], v[4:7]
	v_mfma_f32_16x16x32_bf16 v[0:3], v[172:175], v[164:167], v[0:3]
	ds_read_b128 v[156:159], v115 offset:18432
	ds_read_b128 v[160:163], v113
	ds_read_b128 v[164:167], v113 offset:2048
	ds_read_b128 v[168:171], v115 offset:20480
	ds_read_b128 v[172:175], v116 offset:16384
	s_waitcnt lgkmcnt(3)
	v_mfma_f32_16x16x32_bf16 v[92:95], v[152:155], v[160:163], v[92:95]
	v_mfma_f32_16x16x32_bf16 v[88:91], v[156:159], v[160:163], v[88:91]
	s_waitcnt lgkmcnt(1)
	v_mfma_f32_16x16x32_bf16 v[84:87], v[168:171], v[160:163], v[84:87]
	s_waitcnt lgkmcnt(0)
	v_mfma_f32_16x16x32_bf16 v[80:83], v[172:175], v[160:163], v[80:83]
	v_mfma_f32_16x16x32_bf16 v[76:79], v[152:155], v[164:167], v[76:79]
	v_mfma_f32_16x16x32_bf16 v[72:75], v[156:159], v[164:167], v[72:75]
	v_mfma_f32_16x16x32_bf16 v[60:63], v[168:171], v[164:167], v[60:63]
	v_mfma_f32_16x16x32_bf16 v[28:31], v[172:175], v[164:167], v[28:31]
	ds_read_b128 v[160:163], v113 offset:4096
	ds_read_b128 v[164:167], v114
	s_waitcnt lgkmcnt(1)
	v_mfma_f32_16x16x32_bf16 v[64:67], v[152:155], v[160:163], v[64:67]
	v_mfma_f32_16x16x32_bf16 v[36:39], v[156:159], v[160:163], v[36:39]
	v_mfma_f32_16x16x32_bf16 v[32:35], v[168:171], v[160:163], v[32:35]
	v_mfma_f32_16x16x32_bf16 v[16:19], v[172:175], v[160:163], v[16:19]
	s_waitcnt lgkmcnt(0)
	v_mfma_f32_16x16x32_bf16 v[12:15], v[152:155], v[164:167], v[12:15]
	v_mfma_f32_16x16x32_bf16 v[8:11], v[156:159], v[164:167], v[8:11]
	v_mfma_f32_16x16x32_bf16 v[4:7], v[168:171], v[164:167], v[4:7]
	v_mfma_f32_16x16x32_bf16 v[0:3], v[172:175], v[164:167], v[0:3]
	s_setprio 0
	s_min_u32 s4, s14, 0x300
	s_lshl_b32 s4, s4, 1
	s_waitcnt vmcnt(15)
	ds_write_b128 v108, v[20:23] offset:32768
	s_waitcnt vmcnt(14)
	ds_write_b128 v108, v[24:27] offset:49152
	s_waitcnt vmcnt(13)
	ds_write_b128 v108, v[40:43] offset:36864
	s_waitcnt vmcnt(12)
	ds_write_b128 v108, v[44:47] offset:53248
	s_waitcnt vmcnt(11)
	ds_write_b128 v108, v[48:51] offset:40960
	s_waitcnt vmcnt(10)
	ds_write_b128 v108, v[52:55] offset:57344
	s_waitcnt vmcnt(9)
	ds_write_b128 v108, v[56:59] offset:45056
	s_waitcnt vmcnt(8)
	ds_write_b128 v108, v[68:71] offset:61440
	v_lshl_add_u64 v[40:41], v[102:103], 0, s[4:5]
	v_add_co_u32_e32 v44, vcc, s8, v40
	v_lshl_add_u64 v[42:43], v[104:105], 0, s[4:5]
	s_nop 0
	v_addc_co_u32_e32 v45, vcc, 0, v41, vcc
	v_add_co_u32_e32 v46, vcc, s8, v42
	s_waitcnt lgkmcnt(0)
	s_nop 0
	v_addc_co_u32_e32 v47, vcc, 0, v43, vcc
	v_add_co_u32_e32 v48, vcc, s9, v40
	s_barrier
	s_nop 0
	v_addc_co_u32_e32 v49, vcc, 0, v41, vcc
	v_add_co_u32_e32 v52, vcc, s9, v42
	s_nop 1
	v_addc_co_u32_e32 v53, vcc, 0, v43, vcc
	v_add_co_u32_e32 v56, vcc, s10, v40
	global_load_dwordx4 v[20:23], v[40:41], off offset:384
	global_load_dwordx4 v[24:27], v[42:43], off offset:384
	v_addc_co_u32_e32 v57, vcc, 0, v41, vcc
	v_add_co_u32_e32 v68, vcc, s10, v42
	s_nop 1
	v_addc_co_u32_e32 v69, vcc, 0, v43, vcc
	global_load_dwordx4 v[40:43], v[44:45], off offset:384
	s_nop 0
	global_load_dwordx4 v[44:47], v[46:47], off offset:384
	s_nop 0
	global_load_dwordx4 v[48:51], v[48:49], off offset:384
	s_nop 0
	global_load_dwordx4 v[52:55], v[52:53], off offset:384
	s_nop 0
	global_load_dwordx4 v[56:59], v[56:57], off offset:384
	s_nop 0
	global_load_dwordx4 v[68:71], v[68:69], off offset:384
	s_setprio 1
	ds_read_b128 v[152:155], v111 offset:49152
	ds_read_b128 v[156:159], v111 offset:51200
	ds_read_b128 v[160:163], v109 offset:32768
	ds_read_b128 v[164:167], v109 offset:34816
	ds_read_b128 v[168:171], v111 offset:53248
	ds_read_b128 v[172:175], v112 offset:49152
	s_waitcnt lgkmcnt(3)
	v_mfma_f32_16x16x32_bf16 v[92:95], v[152:155], v[160:163], v[92:95]
	v_mfma_f32_16x16x32_bf16 v[88:91], v[156:159], v[160:163], v[88:91]
	s_waitcnt lgkmcnt(1)
	v_mfma_f32_16x16x32_bf16 v[84:87], v[168:171], v[160:163], v[84:87]
	s_waitcnt lgkmcnt(0)
	v_mfma_f32_16x16x32_bf16 v[80:83], v[172:175], v[160:163], v[80:83]
	v_mfma_f32_16x16x32_bf16 v[76:79], v[152:155], v[164:167], v[76:79]
	v_mfma_f32_16x16x32_bf16 v[72:75], v[156:159], v[164:167], v[72:75]
	v_mfma_f32_16x16x32_bf16 v[60:63], v[168:171], v[164:167], v[60:63]
	v_mfma_f32_16x16x32_bf16 v[28:31], v[172:175], v[164:167], v[28:31]
	ds_read_b128 v[160:163], v109 offset:36864
	ds_read_b128 v[164:167], v110 offset:32768
	s_waitcnt lgkmcnt(1)
	v_mfma_f32_16x16x32_bf16 v[64:67], v[152:155], v[160:163], v[64:67]
	v_mfma_f32_16x16x32_bf16 v[36:39], v[156:159], v[160:163], v[36:39]
	v_mfma_f32_16x16x32_bf16 v[32:35], v[168:171], v[160:163], v[32:35]
	v_mfma_f32_16x16x32_bf16 v[16:19], v[172:175], v[160:163], v[16:19]
	s_waitcnt lgkmcnt(0)
	v_mfma_f32_16x16x32_bf16 v[12:15], v[152:155], v[164:167], v[12:15]
	ds_read_b128 v[152:155], v115 offset:49152
	v_mfma_f32_16x16x32_bf16 v[8:11], v[156:159], v[164:167], v[8:11]
	v_mfma_f32_16x16x32_bf16 v[4:7], v[168:171], v[164:167], v[4:7]
	v_mfma_f32_16x16x32_bf16 v[0:3], v[172:175], v[164:167], v[0:3]
	ds_read_b128 v[156:159], v115 offset:51200
	ds_read_b128 v[160:163], v113 offset:32768
	ds_read_b128 v[164:167], v113 offset:34816
	ds_read_b128 v[168:171], v115 offset:53248
	ds_read_b128 v[172:175], v116 offset:49152
	s_waitcnt lgkmcnt(3)
	v_mfma_f32_16x16x32_bf16 v[92:95], v[152:155], v[160:163], v[92:95]
	v_mfma_f32_16x16x32_bf16 v[88:91], v[156:159], v[160:163], v[88:91]
	s_waitcnt lgkmcnt(1)
	v_mfma_f32_16x16x32_bf16 v[84:87], v[168:171], v[160:163], v[84:87]
	s_waitcnt lgkmcnt(0)
	v_mfma_f32_16x16x32_bf16 v[80:83], v[172:175], v[160:163], v[80:83]
	v_mfma_f32_16x16x32_bf16 v[76:79], v[152:155], v[164:167], v[76:79]
	v_mfma_f32_16x16x32_bf16 v[72:75], v[156:159], v[164:167], v[72:75]
	v_mfma_f32_16x16x32_bf16 v[60:63], v[168:171], v[164:167], v[60:63]
	v_mfma_f32_16x16x32_bf16 v[28:31], v[172:175], v[164:167], v[28:31]
	ds_read_b128 v[160:163], v113 offset:36864
	ds_read_b128 v[164:167], v114 offset:32768
	s_waitcnt lgkmcnt(1)
	v_mfma_f32_16x16x32_bf16 v[64:67], v[152:155], v[160:163], v[64:67]
	v_mfma_f32_16x16x32_bf16 v[36:39], v[156:159], v[160:163], v[36:39]
	v_mfma_f32_16x16x32_bf16 v[32:35], v[168:171], v[160:163], v[32:35]
	v_mfma_f32_16x16x32_bf16 v[16:19], v[172:175], v[160:163], v[16:19]
	s_waitcnt lgkmcnt(0)
	v_mfma_f32_16x16x32_bf16 v[12:15], v[152:155], v[164:167], v[12:15]
	v_mfma_f32_16x16x32_bf16 v[8:11], v[156:159], v[164:167], v[8:11]
	v_mfma_f32_16x16x32_bf16 v[4:7], v[168:171], v[164:167], v[4:7]
	v_mfma_f32_16x16x32_bf16 v[0:3], v[172:175], v[164:167], v[0:3]
	s_setprio 0
	s_add_i32 s13, s13, 2
	s_cmp_lt_u32 s13, 14
	s_mov_b32 s14, s15
	s_waitcnt vmcnt(15)
	ds_write_b128 v108, v[120:123]
	s_waitcnt vmcnt(14)
	ds_write_b128 v108, v[124:127] offset:16384
	s_waitcnt vmcnt(13)
	ds_write_b128 v108, v[128:131] offset:4096
	s_waitcnt vmcnt(12)
	ds_write_b128 v108, v[132:135] offset:20480
	s_waitcnt vmcnt(11)
	ds_write_b128 v108, v[136:139] offset:8192
	s_waitcnt vmcnt(10)
	ds_write_b128 v108, v[140:143] offset:24576
	s_waitcnt vmcnt(9)
	ds_write_b128 v108, v[144:147] offset:12288
	s_waitcnt vmcnt(8)
	ds_write_b128 v108, v[148:151] offset:28672
	s_waitcnt lgkmcnt(0)
	s_barrier
	s_cbranch_scc1 .LBB0_799
	s_waitcnt vmcnt(0)
	v_or_b32_e32 v170, s12, v118
	v_add_lshl_u32 v96, v117, s11, 10
	v_readlane_b32 s12, v254, 24
	v_readlane_b32 s16, v254, 28
	v_readlane_b32 s17, v254, 29
	v_readlane_b32 s13, v254, 25
	v_readlane_b32 s14, v254, 26
	v_readlane_b32 s15, v254, 27
	v_readlane_b32 s18, v254, 30
	v_readlane_b32 s19, v254, 31
	v_readlane_b32 s20, v254, 32
	v_readlane_b32 s21, v254, 33
	v_readlane_b32 s22, v254, 34
	v_readlane_b32 s23, v254, 35
	v_readlane_b32 s24, v254, 36
	v_readlane_b32 s25, v254, 37
	v_readlane_b32 s26, v254, 38
	v_readlane_b32 s27, v254, 39
	v_lshlrev_b32_e32 v168, 2, v170
	v_mov_b32_e32 v169, v97
	v_lshlrev_b64 v[174:175], 2, v[96:97]
	v_lshl_add_u64 v[152:153], s[16:17], 0, v[174:175]
	v_lshl_add_u64 v[160:161], s[82:83], 0, v[174:175]
	v_lshl_add_u64 v[152:153], v[152:153], 0, v[168:169]
	v_lshl_add_u64 v[160:161], v[160:161], 0, v[168:169]
	global_load_dwordx4 v[120:123], v[152:153], off
	global_load_dwordx4 v[124:127], v[152:153], off offset:64
	global_load_dwordx4 v[128:131], v[152:153], off offset:128
	global_load_dwordx4 v[132:135], v[152:153], off offset:192
	v_or_b32_e32 v172, 0x4000, v96
	v_mov_b32_e32 v173, v97
	v_lshlrev_b64 v[174:175], 2, v[172:173]
	v_lshl_add_u64 v[154:155], s[16:17], 0, v[174:175]
	v_lshl_add_u64 v[162:163], s[82:83], 0, v[174:175]
	v_lshl_add_u64 v[154:155], v[154:155], 0, v[168:169]
	v_lshl_add_u64 v[162:163], v[162:163], 0, v[168:169]
	global_load_dwordx4 v[136:139], v[154:155], off
	global_load_dwordx4 v[140:143], v[154:155], off offset:64
	global_load_dwordx4 v[144:147], v[154:155], off offset:128
	global_load_dwordx4 v[148:151], v[154:155], off offset:192
	v_or_b32_e32 v172, 0x8000, v96
	v_mov_b32_e32 v173, v97
	v_lshlrev_b64 v[174:175], 2, v[172:173]
	v_lshl_add_u64 v[156:157], s[16:17], 0, v[174:175]
	v_lshl_add_u64 v[164:165], s[82:83], 0, v[174:175]
	v_lshl_add_u64 v[156:157], v[156:157], 0, v[168:169]
	v_lshl_add_u64 v[164:165], v[164:165], 0, v[168:169]
	global_load_dwordx4 v[20:23], v[156:157], off
	global_load_dwordx4 v[24:27], v[156:157], off offset:64
	global_load_dwordx4 v[40:43], v[156:157], off offset:128
	global_load_dwordx4 v[44:47], v[156:157], off offset:192
	v_or_b32_e32 v172, 0xc000, v96
	v_mov_b32_e32 v173, v97
	v_lshlrev_b64 v[174:175], 2, v[172:173]
	v_lshl_add_u64 v[158:159], s[16:17], 0, v[174:175]
	v_lshl_add_u64 v[166:167], s[82:83], 0, v[174:175]
	v_lshl_add_u64 v[158:159], v[158:159], 0, v[168:169]
	v_lshl_add_u64 v[166:167], v[166:167], 0, v[168:169]
	global_load_dwordx4 v[48:51], v[158:159], off
	global_load_dwordx4 v[52:55], v[158:159], off offset:64
	global_load_dwordx4 v[56:59], v[158:159], off offset:128
	global_load_dwordx4 v[68:71], v[158:159], off offset:192
	s_waitcnt vmcnt(15)
	v_pk_fma_f32 v[120:121], v[120:121], s[6:7], v[92:93] op_sel_hi:[1,0,1]
	v_pk_fma_f32 v[122:123], v[122:123], s[6:7], v[94:95] op_sel_hi:[1,0,1]
	s_waitcnt vmcnt(14)
	v_pk_fma_f32 v[124:125], v[124:125], s[6:7], v[88:89] op_sel_hi:[1,0,1]
	v_pk_fma_f32 v[126:127], v[126:127], s[6:7], v[90:91] op_sel_hi:[1,0,1]
	s_waitcnt vmcnt(13)
	v_pk_fma_f32 v[128:129], v[128:129], s[6:7], v[84:85] op_sel_hi:[1,0,1]
	v_pk_fma_f32 v[130:131], v[130:131], s[6:7], v[86:87] op_sel_hi:[1,0,1]
	s_waitcnt vmcnt(12)
	v_pk_fma_f32 v[132:133], v[132:133], s[6:7], v[80:81] op_sel_hi:[1,0,1]
	v_pk_fma_f32 v[134:135], v[134:135], s[6:7], v[82:83] op_sel_hi:[1,0,1]
	s_waitcnt vmcnt(11)
	v_pk_fma_f32 v[136:137], v[136:137], s[6:7], v[76:77] op_sel_hi:[1,0,1]
	v_pk_fma_f32 v[138:139], v[138:139], s[6:7], v[78:79] op_sel_hi:[1,0,1]
	s_waitcnt vmcnt(10)
	v_pk_fma_f32 v[140:141], v[140:141], s[6:7], v[72:73] op_sel_hi:[1,0,1]
	v_pk_fma_f32 v[142:143], v[142:143], s[6:7], v[74:75] op_sel_hi:[1,0,1]
	s_waitcnt vmcnt(9)
	v_pk_fma_f32 v[144:145], v[144:145], s[6:7], v[60:61] op_sel_hi:[1,0,1]
	v_pk_fma_f32 v[146:147], v[146:147], s[6:7], v[62:63] op_sel_hi:[1,0,1]
	s_waitcnt vmcnt(8)
	v_pk_fma_f32 v[148:149], v[148:149], s[6:7], v[28:29] op_sel_hi:[1,0,1]
	v_pk_fma_f32 v[150:151], v[150:151], s[6:7], v[30:31] op_sel_hi:[1,0,1]
	s_waitcnt vmcnt(7)
	v_pk_fma_f32 v[20:21], v[20:21], s[6:7], v[64:65] op_sel_hi:[1,0,1]
	v_pk_fma_f32 v[22:23], v[22:23], s[6:7], v[66:67] op_sel_hi:[1,0,1]
	s_waitcnt vmcnt(6)
	v_pk_fma_f32 v[24:25], v[24:25], s[6:7], v[36:37] op_sel_hi:[1,0,1]
	v_pk_fma_f32 v[26:27], v[26:27], s[6:7], v[38:39] op_sel_hi:[1,0,1]
	s_waitcnt vmcnt(5)
	v_pk_fma_f32 v[40:41], v[40:41], s[6:7], v[32:33] op_sel_hi:[1,0,1]
	v_pk_fma_f32 v[42:43], v[42:43], s[6:7], v[34:35] op_sel_hi:[1,0,1]
	s_waitcnt vmcnt(4)
	v_pk_fma_f32 v[44:45], v[44:45], s[6:7], v[16:17] op_sel_hi:[1,0,1]
	v_pk_fma_f32 v[46:47], v[46:47], s[6:7], v[18:19] op_sel_hi:[1,0,1]
	s_waitcnt vmcnt(3)
	v_pk_fma_f32 v[48:49], v[48:49], s[6:7], v[12:13] op_sel_hi:[1,0,1]
	v_pk_fma_f32 v[50:51], v[50:51], s[6:7], v[14:15] op_sel_hi:[1,0,1]
	s_waitcnt vmcnt(2)
	v_pk_fma_f32 v[52:53], v[52:53], s[6:7], v[8:9] op_sel_hi:[1,0,1]
	v_pk_fma_f32 v[54:55], v[54:55], s[6:7], v[10:11] op_sel_hi:[1,0,1]
	s_waitcnt vmcnt(1)
	v_pk_fma_f32 v[56:57], v[56:57], s[6:7], v[4:5] op_sel_hi:[1,0,1]
	v_pk_fma_f32 v[58:59], v[58:59], s[6:7], v[6:7] op_sel_hi:[1,0,1]
	s_waitcnt vmcnt(0)
	v_pk_fma_f32 v[68:69], v[68:69], s[6:7], v[0:1] op_sel_hi:[1,0,1]
	v_pk_fma_f32 v[70:71], v[70:71], s[6:7], v[2:3] op_sel_hi:[1,0,1]
	global_store_dwordx4 v[160:161], v[120:123], off
	global_store_dwordx4 v[160:161], v[124:127], off offset:64
	global_store_dwordx4 v[160:161], v[128:131], off offset:128
	global_store_dwordx4 v[160:161], v[132:135], off offset:192
	global_store_dwordx4 v[162:163], v[136:139], off
	global_store_dwordx4 v[162:163], v[140:143], off offset:64
	global_store_dwordx4 v[162:163], v[144:147], off offset:128
	global_store_dwordx4 v[162:163], v[148:151], off offset:192
	global_store_dwordx4 v[164:165], v[20:23], off
	global_store_dwordx4 v[164:165], v[24:27], off offset:64
	global_store_dwordx4 v[164:165], v[40:43], off offset:128
	global_store_dwordx4 v[164:165], v[44:47], off offset:192
	global_store_dwordx4 v[166:167], v[48:51], off
	global_store_dwordx4 v[166:167], v[52:55], off offset:64
	global_store_dwordx4 v[166:167], v[56:59], off offset:128
	global_store_dwordx4 v[166:167], v[68:71], off offset:192
	s_add_i32 s7, s7, s3
	s_cmpk_lt_u32 s7, 0x100
	s_cbranch_scc1 .LBB0_798

.LBB0_890:
	s_add_i32 s16, s15, 0x80
	s_min_u32 s6, s16, 0x1c0
	s_lshl_b32 s6, s6, 1
	v_lshl_add_u64 v[144:145], v[102:103], 0, s[6:7]
	v_add_co_u32_e32 v128, vcc, s9, v144
	v_lshl_add_u64 v[148:149], v[104:105], 0, s[6:7]
	s_nop 0
	v_addc_co_u32_e32 v129, vcc, 0, v145, vcc
	v_add_co_u32_e32 v132, vcc, s9, v148
	global_load_dwordx4 v[120:123], v[144:145], off
	global_load_dwordx4 v[124:127], v[148:149], off
	v_addc_co_u32_e32 v133, vcc, 0, v149, vcc
	v_add_co_u32_e32 v136, vcc, s10, v144
	global_load_dwordx4 v[128:131], v[128:129], off
	s_nop 0
	v_addc_co_u32_e32 v137, vcc, 0, v145, vcc
	v_add_co_u32_e32 v140, vcc, s10, v148
	global_load_dwordx4 v[132:135], v[132:133], off
	s_nop 0
	v_addc_co_u32_e32 v141, vcc, 0, v149, vcc
	v_add_co_u32_e32 v144, vcc, s11, v144
	global_load_dwordx4 v[136:139], v[136:137], off
	s_nop 0
	v_addc_co_u32_e32 v145, vcc, 0, v145, vcc
	v_add_co_u32_e32 v148, vcc, s11, v148
	global_load_dwordx4 v[140:143], v[140:141], off
	s_nop 0
	v_addc_co_u32_e32 v149, vcc, 0, v149, vcc
	global_load_dwordx4 v[144:147], v[144:145], off
	s_nop 0
	global_load_dwordx4 v[148:151], v[148:149], off
	s_setprio 1
	ds_read_b128 v[152:155], v111 offset:16384
	ds_read_b128 v[156:159], v111 offset:18432
	ds_read_b128 v[160:163], v109
	ds_read_b128 v[164:167], v109 offset:2048
	ds_read_b128 v[168:171], v111 offset:20480
	ds_read_b128 v[172:175], v112 offset:16384
	s_waitcnt lgkmcnt(3)
	v_mfma_i32_16x16x64_i8 v[92:95], v[152:155], v[160:163], v[92:95]
	v_mfma_i32_16x16x64_i8 v[88:91], v[156:159], v[160:163], v[88:91]
	s_waitcnt lgkmcnt(1)
	v_mfma_i32_16x16x64_i8 v[84:87], v[168:171], v[160:163], v[84:87]
	s_waitcnt lgkmcnt(0)
	v_mfma_i32_16x16x64_i8 v[80:83], v[172:175], v[160:163], v[80:83]
	v_mfma_i32_16x16x64_i8 v[60:63], v[152:155], v[164:167], v[60:63]
	v_mfma_i32_16x16x64_i8 v[40:43], v[156:159], v[164:167], v[40:43]
	v_mfma_i32_16x16x64_i8 v[36:39], v[168:171], v[164:167], v[36:39]
	v_mfma_i32_16x16x64_i8 v[28:31], v[172:175], v[164:167], v[28:31]
	ds_read_b128 v[160:163], v109 offset:4096
	ds_read_b128 v[164:167], v110
	s_waitcnt lgkmcnt(1)
	v_mfma_i32_16x16x64_i8 v[32:35], v[152:155], v[160:163], v[32:35]
	v_mfma_i32_16x16x64_i8 v[24:27], v[156:159], v[160:163], v[24:27]
	v_mfma_i32_16x16x64_i8 v[20:23], v[168:171], v[160:163], v[20:23]
	v_mfma_i32_16x16x64_i8 v[16:19], v[172:175], v[160:163], v[16:19]
	s_waitcnt lgkmcnt(0)
	v_mfma_i32_16x16x64_i8 v[12:15], v[152:155], v[164:167], v[12:15]
	ds_read_b128 v[152:155], v115 offset:16384
	v_mfma_i32_16x16x64_i8 v[8:11], v[156:159], v[164:167], v[8:11]
	v_mfma_i32_16x16x64_i8 v[4:7], v[168:171], v[164:167], v[4:7]
	v_mfma_i32_16x16x64_i8 v[0:3], v[172:175], v[164:167], v[0:3]
	ds_read_b128 v[156:159], v115 offset:18432
	ds_read_b128 v[160:163], v113
	ds_read_b128 v[164:167], v113 offset:2048
	ds_read_b128 v[168:171], v115 offset:20480
	ds_read_b128 v[172:175], v116 offset:16384
	s_waitcnt lgkmcnt(3)
	v_mfma_i32_16x16x64_i8 v[92:95], v[152:155], v[160:163], v[92:95]
	v_mfma_i32_16x16x64_i8 v[88:91], v[156:159], v[160:163], v[88:91]
	s_waitcnt lgkmcnt(1)
	v_mfma_i32_16x16x64_i8 v[84:87], v[168:171], v[160:163], v[84:87]
	s_waitcnt lgkmcnt(0)
	v_mfma_i32_16x16x64_i8 v[80:83], v[172:175], v[160:163], v[80:83]
	v_mfma_i32_16x16x64_i8 v[60:63], v[152:155], v[164:167], v[60:63]
	v_mfma_i32_16x16x64_i8 v[40:43], v[156:159], v[164:167], v[40:43]
	v_mfma_i32_16x16x64_i8 v[36:39], v[168:171], v[164:167], v[36:39]
	v_mfma_i32_16x16x64_i8 v[28:31], v[172:175], v[164:167], v[28:31]
	ds_read_b128 v[160:163], v113 offset:4096
	ds_read_b128 v[164:167], v114
	s_waitcnt lgkmcnt(1)
	v_mfma_i32_16x16x64_i8 v[32:35], v[152:155], v[160:163], v[32:35]
	v_mfma_i32_16x16x64_i8 v[24:27], v[156:159], v[160:163], v[24:27]
	v_mfma_i32_16x16x64_i8 v[20:23], v[168:171], v[160:163], v[20:23]
	v_mfma_i32_16x16x64_i8 v[16:19], v[172:175], v[160:163], v[16:19]
	s_waitcnt lgkmcnt(0)
	v_mfma_i32_16x16x64_i8 v[12:15], v[152:155], v[164:167], v[12:15]
	v_mfma_i32_16x16x64_i8 v[8:11], v[156:159], v[164:167], v[8:11]
	v_mfma_i32_16x16x64_i8 v[4:7], v[168:171], v[164:167], v[4:7]
	v_mfma_i32_16x16x64_i8 v[0:3], v[172:175], v[164:167], v[0:3]
	s_setprio 0
	s_min_u32 s6, s15, 0x100
	s_lshl_b32 s6, s6, 1
	s_waitcnt vmcnt(15)
	ds_write_b128 v108, v[44:47] offset:32768
	s_waitcnt vmcnt(14)
	ds_write_b128 v108, v[48:51] offset:49152
	s_waitcnt vmcnt(13)
	ds_write_b128 v108, v[52:55] offset:36864
	s_waitcnt vmcnt(10)
	ds_write_b128 v108, v[68:71] offset:53248
	ds_write_b128 v108, v[56:59] offset:40960
	s_waitcnt vmcnt(9)
	ds_write_b128 v108, v[72:75] offset:57344
	ds_write_b128 v108, v[64:67] offset:45056
	s_waitcnt vmcnt(8)
	ds_write_b128 v108, v[76:79] offset:61440
	v_lshl_add_u64 v[52:53], v[102:103], 0, s[6:7]
	v_add_co_u32_e32 v56, vcc, s9, v52
	v_lshl_add_u64 v[54:55], v[104:105], 0, s[6:7]
	s_nop 0
	v_addc_co_u32_e32 v57, vcc, 0, v53, vcc
	v_add_co_u32_e32 v58, vcc, s9, v54
	s_waitcnt lgkmcnt(0)
	s_nop 0
	v_addc_co_u32_e32 v59, vcc, 0, v55, vcc
	v_add_co_u32_e32 v64, vcc, s10, v52
	s_barrier
	s_nop 0
	v_addc_co_u32_e32 v65, vcc, 0, v53, vcc
	v_add_co_u32_e32 v66, vcc, s10, v54
	s_nop 1
	v_addc_co_u32_e32 v67, vcc, 0, v55, vcc
	v_add_co_u32_e32 v76, vcc, s11, v52
	global_load_dwordx4 v[44:47], v[52:53], off offset:384
	global_load_dwordx4 v[48:51], v[54:55], off offset:384
	v_addc_co_u32_e32 v77, vcc, 0, v53, vcc
	v_add_co_u32_e32 v78, vcc, s11, v54
	s_nop 1
	v_addc_co_u32_e32 v79, vcc, 0, v55, vcc
	global_load_dwordx4 v[52:55], v[56:57], off offset:384
	global_load_dwordx4 v[68:71], v[58:59], off offset:384
	s_nop 0
	global_load_dwordx4 v[56:59], v[64:65], off offset:384
	global_load_dwordx4 v[72:75], v[66:67], off offset:384
	s_nop 0
	global_load_dwordx4 v[64:67], v[76:77], off offset:384
	s_nop 0
	global_load_dwordx4 v[76:79], v[78:79], off offset:384
	s_setprio 1
	ds_read_b128 v[152:155], v111 offset:49152
	ds_read_b128 v[156:159], v111 offset:51200
	ds_read_b128 v[160:163], v109 offset:32768
	ds_read_b128 v[164:167], v109 offset:34816
	ds_read_b128 v[168:171], v111 offset:53248
	ds_read_b128 v[172:175], v112 offset:49152
	s_waitcnt lgkmcnt(3)
	v_mfma_i32_16x16x64_i8 v[92:95], v[152:155], v[160:163], v[92:95]
	v_mfma_i32_16x16x64_i8 v[88:91], v[156:159], v[160:163], v[88:91]
	s_waitcnt lgkmcnt(1)
	v_mfma_i32_16x16x64_i8 v[84:87], v[168:171], v[160:163], v[84:87]
	s_waitcnt lgkmcnt(0)
	v_mfma_i32_16x16x64_i8 v[80:83], v[172:175], v[160:163], v[80:83]
	v_mfma_i32_16x16x64_i8 v[60:63], v[152:155], v[164:167], v[60:63]
	v_mfma_i32_16x16x64_i8 v[40:43], v[156:159], v[164:167], v[40:43]
	v_mfma_i32_16x16x64_i8 v[36:39], v[168:171], v[164:167], v[36:39]
	v_mfma_i32_16x16x64_i8 v[28:31], v[172:175], v[164:167], v[28:31]
	ds_read_b128 v[160:163], v109 offset:36864
	ds_read_b128 v[164:167], v110 offset:32768
	s_waitcnt lgkmcnt(1)
	v_mfma_i32_16x16x64_i8 v[32:35], v[152:155], v[160:163], v[32:35]
	v_mfma_i32_16x16x64_i8 v[24:27], v[156:159], v[160:163], v[24:27]
	v_mfma_i32_16x16x64_i8 v[20:23], v[168:171], v[160:163], v[20:23]
	v_mfma_i32_16x16x64_i8 v[16:19], v[172:175], v[160:163], v[16:19]
	s_waitcnt lgkmcnt(0)
	v_mfma_i32_16x16x64_i8 v[12:15], v[152:155], v[164:167], v[12:15]
	ds_read_b128 v[152:155], v115 offset:49152
	v_mfma_i32_16x16x64_i8 v[8:11], v[156:159], v[164:167], v[8:11]
	v_mfma_i32_16x16x64_i8 v[4:7], v[168:171], v[164:167], v[4:7]
	v_mfma_i32_16x16x64_i8 v[0:3], v[172:175], v[164:167], v[0:3]
	ds_read_b128 v[156:159], v115 offset:51200
	ds_read_b128 v[160:163], v113 offset:32768
	ds_read_b128 v[164:167], v113 offset:34816
	ds_read_b128 v[168:171], v115 offset:53248
	ds_read_b128 v[172:175], v116 offset:49152
	s_waitcnt lgkmcnt(3)
	v_mfma_i32_16x16x64_i8 v[92:95], v[152:155], v[160:163], v[92:95]
	v_mfma_i32_16x16x64_i8 v[88:91], v[156:159], v[160:163], v[88:91]
	s_waitcnt lgkmcnt(1)
	v_mfma_i32_16x16x64_i8 v[84:87], v[168:171], v[160:163], v[84:87]
	s_waitcnt lgkmcnt(0)
	v_mfma_i32_16x16x64_i8 v[80:83], v[172:175], v[160:163], v[80:83]
	v_mfma_i32_16x16x64_i8 v[60:63], v[152:155], v[164:167], v[60:63]
	v_mfma_i32_16x16x64_i8 v[40:43], v[156:159], v[164:167], v[40:43]
	v_mfma_i32_16x16x64_i8 v[36:39], v[168:171], v[164:167], v[36:39]
	v_mfma_i32_16x16x64_i8 v[28:31], v[172:175], v[164:167], v[28:31]
	ds_read_b128 v[160:163], v113 offset:36864
	ds_read_b128 v[164:167], v114 offset:32768
	s_waitcnt lgkmcnt(1)
	v_mfma_i32_16x16x64_i8 v[32:35], v[152:155], v[160:163], v[32:35]
	v_mfma_i32_16x16x64_i8 v[24:27], v[156:159], v[160:163], v[24:27]
	v_mfma_i32_16x16x64_i8 v[20:23], v[168:171], v[160:163], v[20:23]
	v_mfma_i32_16x16x64_i8 v[16:19], v[172:175], v[160:163], v[16:19]
	s_waitcnt lgkmcnt(0)
	v_mfma_i32_16x16x64_i8 v[12:15], v[152:155], v[164:167], v[12:15]
	v_mfma_i32_16x16x64_i8 v[8:11], v[156:159], v[164:167], v[8:11]
	v_mfma_i32_16x16x64_i8 v[4:7], v[168:171], v[164:167], v[4:7]
	v_mfma_i32_16x16x64_i8 v[0:3], v[172:175], v[164:167], v[0:3]
	s_setprio 0
	s_add_i32 s14, s14, 2
	s_cmp_lt_u32 s14, 6
	s_mov_b32 s15, s16
	s_waitcnt vmcnt(15)
	ds_write_b128 v108, v[120:123]
	s_waitcnt vmcnt(14)
	ds_write_b128 v108, v[124:127] offset:16384
	s_waitcnt vmcnt(13)
	ds_write_b128 v108, v[128:131] offset:4096
	s_waitcnt vmcnt(12)
	ds_write_b128 v108, v[132:135] offset:20480
	s_waitcnt vmcnt(11)
	ds_write_b128 v108, v[136:139] offset:8192
	s_waitcnt vmcnt(10)
	ds_write_b128 v108, v[140:143] offset:24576
	s_waitcnt vmcnt(9)
	ds_write_b128 v108, v[144:147] offset:12288
	s_waitcnt vmcnt(8)
	ds_write_b128 v108, v[148:151] offset:28672
	s_waitcnt lgkmcnt(0)
	s_barrier
	s_cbranch_scc1 .LBB0_890
	v_cvt_f32_i32_e32 v92, v92
	v_cvt_f32_i32_e32 v93, v93
	v_cvt_f32_i32_e32 v94, v94
	v_cvt_f32_i32_e32 v95, v95
	v_cvt_f32_i32_e32 v88, v88
	v_cvt_f32_i32_e32 v89, v89
	v_cvt_f32_i32_e32 v90, v90
	v_cvt_f32_i32_e32 v91, v91
	v_cvt_f32_i32_e32 v84, v84
	v_cvt_f32_i32_e32 v85, v85
	v_cvt_f32_i32_e32 v86, v86
	v_cvt_f32_i32_e32 v87, v87
	v_cvt_f32_i32_e32 v80, v80
	v_cvt_f32_i32_e32 v81, v81
	v_cvt_f32_i32_e32 v82, v82
	v_cvt_f32_i32_e32 v83, v83
	v_cvt_f32_i32_e32 v60, v60
	v_cvt_f32_i32_e32 v61, v61
	v_cvt_f32_i32_e32 v62, v62
	v_cvt_f32_i32_e32 v63, v63
	v_cvt_f32_i32_e32 v40, v40
	v_cvt_f32_i32_e32 v41, v41
	v_cvt_f32_i32_e32 v42, v42
	v_cvt_f32_i32_e32 v43, v43
	v_cvt_f32_i32_e32 v36, v36
	v_cvt_f32_i32_e32 v37, v37
	v_cvt_f32_i32_e32 v38, v38
	v_cvt_f32_i32_e32 v39, v39
	v_cvt_f32_i32_e32 v28, v28
	v_cvt_f32_i32_e32 v29, v29
	v_cvt_f32_i32_e32 v30, v30
	v_cvt_f32_i32_e32 v31, v31
	v_cvt_f32_i32_e32 v32, v32
	v_cvt_f32_i32_e32 v33, v33
	v_cvt_f32_i32_e32 v34, v34
	v_cvt_f32_i32_e32 v35, v35
	v_cvt_f32_i32_e32 v24, v24
	v_cvt_f32_i32_e32 v25, v25
	v_cvt_f32_i32_e32 v26, v26
	v_cvt_f32_i32_e32 v27, v27
	v_cvt_f32_i32_e32 v20, v20
	v_cvt_f32_i32_e32 v21, v21
	v_cvt_f32_i32_e32 v22, v22
	v_cvt_f32_i32_e32 v23, v23
	v_cvt_f32_i32_e32 v16, v16
	v_cvt_f32_i32_e32 v17, v17
	v_cvt_f32_i32_e32 v18, v18
	v_cvt_f32_i32_e32 v19, v19
	v_cvt_f32_i32_e32 v12, v12
	v_cvt_f32_i32_e32 v13, v13
	v_cvt_f32_i32_e32 v14, v14
	v_cvt_f32_i32_e32 v15, v15
	v_cvt_f32_i32_e32 v8, v8
	v_cvt_f32_i32_e32 v9, v9
	v_cvt_f32_i32_e32 v10, v10
	v_cvt_f32_i32_e32 v11, v11
	v_cvt_f32_i32_e32 v4, v4
	v_cvt_f32_i32_e32 v5, v5
	v_cvt_f32_i32_e32 v6, v6
	v_cvt_f32_i32_e32 v7, v7
	v_cvt_f32_i32_e32 v0, v0
	v_cvt_f32_i32_e32 v1, v1
	v_cvt_f32_i32_e32 v2, v2
	v_cvt_f32_i32_e32 v3, v3
	s_waitcnt vmcnt(0)
	v_add_u32_e32 v96, s12, v117
	v_or_b32_e32 v146, s13, v118
	v_lshl_add_u64 v[144:145], v[96:97], 2, s[68:69]
	v_lshlrev_b32_e32 v148, 2, v146
	global_load_dword v136, v[144:145], off
	global_load_dword v138, v[144:145], off offset:64
	global_load_dword v140, v[144:145], off offset:128
	global_load_dword v142, v[144:145], off offset:192
	global_load_dwordx4 v[120:123], v148, s[0:1]
	global_load_dwordx4 v[124:127], v148, s[0:1] offset:64
	global_load_dwordx4 v[128:131], v148, s[0:1] offset:128
	global_load_dwordx4 v[132:135], v148, s[0:1] offset:192
	v_lshlrev_b32_e32 v146, 1, v146
	v_mov_b32_e32 v147, v97
	v_lshlrev_b64 v[44:45], 12, v[96:97]
	v_lshl_add_u64 v[44:45], s[64:65], 0, v[44:45]
	v_lshl_add_u64 v[44:45], v[44:45], 0, v[146:147]
	v_or_b32_e32 v52, 16, v96
	v_mov_b32_e32 v53, v97
	v_lshlrev_b64 v[46:47], 12, v[52:53]
	v_lshl_add_u64 v[46:47], s[64:65], 0, v[46:47]
	v_lshl_add_u64 v[46:47], v[46:47], 0, v[146:147]
	v_or_b32_e32 v52, 32, v96
	v_mov_b32_e32 v53, v97
	v_lshlrev_b64 v[48:49], 12, v[52:53]
	v_lshl_add_u64 v[48:49], s[64:65], 0, v[48:49]
	v_lshl_add_u64 v[48:49], v[48:49], 0, v[146:147]
	v_or_b32_e32 v52, 48, v96
	v_mov_b32_e32 v53, v97
	v_lshlrev_b64 v[50:51], 12, v[52:53]
	v_lshl_add_u64 v[50:51], s[64:65], 0, v[50:51]
	v_lshl_add_u64 v[50:51], v[50:51], 0, v[146:147]
	s_waitcnt vmcnt(0)
	v_pk_mul_f32 v[92:93], v[136:137], v[92:93] op_sel_hi:[0,1]
	v_pk_mul_f32 v[94:95], v[136:137], v[94:95] op_sel_hi:[0,1]
	v_pk_mul_f32 v[92:93], v[120:121], v[92:93]
	v_pk_mul_f32 v[94:95], v[94:95], v[122:123]
	v_cvt_pk_bf16_f32 v92, v92, v93
	v_cvt_pk_bf16_f32 v93, v94, v95
	global_store_dwordx2 v[44:45], v[92:93], off
	v_pk_mul_f32 v[88:89], v[136:137], v[88:89] op_sel_hi:[0,1]
	v_pk_mul_f32 v[90:91], v[136:137], v[90:91] op_sel_hi:[0,1]
	v_pk_mul_f32 v[88:89], v[124:125], v[88:89]
	v_pk_mul_f32 v[90:91], v[90:91], v[126:127]
	v_cvt_pk_bf16_f32 v88, v88, v89
	v_cvt_pk_bf16_f32 v89, v90, v91
	global_store_dwordx2 v[44:45], v[88:89], off offset:32
	v_pk_mul_f32 v[84:85], v[136:137], v[84:85] op_sel_hi:[0,1]
	v_pk_mul_f32 v[86:87], v[136:137], v[86:87] op_sel_hi:[0,1]
	v_pk_mul_f32 v[84:85], v[128:129], v[84:85]
	v_pk_mul_f32 v[86:87], v[86:87], v[130:131]
	v_cvt_pk_bf16_f32 v84, v84, v85
	v_cvt_pk_bf16_f32 v85, v86, v87
	global_store_dwordx2 v[44:45], v[84:85], off offset:64
	v_pk_mul_f32 v[80:81], v[136:137], v[80:81] op_sel_hi:[0,1]
	v_pk_mul_f32 v[82:83], v[136:137], v[82:83] op_sel_hi:[0,1]
	v_pk_mul_f32 v[80:81], v[132:133], v[80:81]
	v_pk_mul_f32 v[82:83], v[82:83], v[134:135]
	v_cvt_pk_bf16_f32 v80, v80, v81
	v_cvt_pk_bf16_f32 v81, v82, v83
	global_store_dwordx2 v[44:45], v[80:81], off offset:96
	v_pk_mul_f32 v[60:61], v[138:139], v[60:61] op_sel_hi:[0,1]
	v_pk_mul_f32 v[62:63], v[138:139], v[62:63] op_sel_hi:[0,1]
	v_pk_mul_f32 v[60:61], v[120:121], v[60:61]
	v_pk_mul_f32 v[62:63], v[62:63], v[122:123]
	v_cvt_pk_bf16_f32 v60, v60, v61
	v_cvt_pk_bf16_f32 v61, v62, v63
	global_store_dwordx2 v[46:47], v[60:61], off
	v_pk_mul_f32 v[40:41], v[138:139], v[40:41] op_sel_hi:[0,1]
	v_pk_mul_f32 v[42:43], v[138:139], v[42:43] op_sel_hi:[0,1]
	v_pk_mul_f32 v[40:41], v[124:125], v[40:41]
	v_pk_mul_f32 v[42:43], v[42:43], v[126:127]
	v_cvt_pk_bf16_f32 v40, v40, v41
	v_cvt_pk_bf16_f32 v41, v42, v43
	global_store_dwordx2 v[46:47], v[40:41], off offset:32
	v_pk_mul_f32 v[36:37], v[138:139], v[36:37] op_sel_hi:[0,1]
	v_pk_mul_f32 v[38:39], v[138:139], v[38:39] op_sel_hi:[0,1]
	v_pk_mul_f32 v[36:37], v[128:129], v[36:37]
	v_pk_mul_f32 v[38:39], v[38:39], v[130:131]
	v_cvt_pk_bf16_f32 v36, v36, v37
	v_cvt_pk_bf16_f32 v37, v38, v39
	global_store_dwordx2 v[46:47], v[36:37], off offset:64
	v_pk_mul_f32 v[28:29], v[138:139], v[28:29] op_sel_hi:[0,1]
	v_pk_mul_f32 v[30:31], v[138:139], v[30:31] op_sel_hi:[0,1]
	v_pk_mul_f32 v[28:29], v[132:133], v[28:29]
	v_pk_mul_f32 v[30:31], v[30:31], v[134:135]
	v_cvt_pk_bf16_f32 v28, v28, v29
	v_cvt_pk_bf16_f32 v29, v30, v31
	global_store_dwordx2 v[46:47], v[28:29], off offset:96
	v_pk_mul_f32 v[32:33], v[140:141], v[32:33] op_sel_hi:[0,1]
	v_pk_mul_f32 v[34:35], v[140:141], v[34:35] op_sel_hi:[0,1]
	v_pk_mul_f32 v[32:33], v[120:121], v[32:33]
	v_pk_mul_f32 v[34:35], v[34:35], v[122:123]
	v_cvt_pk_bf16_f32 v32, v32, v33
	v_cvt_pk_bf16_f32 v33, v34, v35
	global_store_dwordx2 v[48:49], v[32:33], off
	v_pk_mul_f32 v[24:25], v[140:141], v[24:25] op_sel_hi:[0,1]
	v_pk_mul_f32 v[26:27], v[140:141], v[26:27] op_sel_hi:[0,1]
	v_pk_mul_f32 v[24:25], v[124:125], v[24:25]
	v_pk_mul_f32 v[26:27], v[26:27], v[126:127]
	v_cvt_pk_bf16_f32 v24, v24, v25
	v_cvt_pk_bf16_f32 v25, v26, v27
	global_store_dwordx2 v[48:49], v[24:25], off offset:32
	v_pk_mul_f32 v[20:21], v[140:141], v[20:21] op_sel_hi:[0,1]
	v_pk_mul_f32 v[22:23], v[140:141], v[22:23] op_sel_hi:[0,1]
	v_pk_mul_f32 v[20:21], v[128:129], v[20:21]
	v_pk_mul_f32 v[22:23], v[22:23], v[130:131]
	v_cvt_pk_bf16_f32 v20, v20, v21
	v_cvt_pk_bf16_f32 v21, v22, v23
	global_store_dwordx2 v[48:49], v[20:21], off offset:64
	v_pk_mul_f32 v[16:17], v[140:141], v[16:17] op_sel_hi:[0,1]
	v_pk_mul_f32 v[18:19], v[140:141], v[18:19] op_sel_hi:[0,1]
	v_pk_mul_f32 v[16:17], v[132:133], v[16:17]
	v_pk_mul_f32 v[18:19], v[18:19], v[134:135]
	v_cvt_pk_bf16_f32 v16, v16, v17
	v_cvt_pk_bf16_f32 v17, v18, v19
	global_store_dwordx2 v[48:49], v[16:17], off offset:96
	v_pk_mul_f32 v[12:13], v[142:143], v[12:13] op_sel_hi:[0,1]
	v_pk_mul_f32 v[14:15], v[142:143], v[14:15] op_sel_hi:[0,1]
	v_pk_mul_f32 v[12:13], v[120:121], v[12:13]
	v_pk_mul_f32 v[14:15], v[14:15], v[122:123]
	v_cvt_pk_bf16_f32 v12, v12, v13
	v_cvt_pk_bf16_f32 v13, v14, v15
	global_store_dwordx2 v[50:51], v[12:13], off
	v_pk_mul_f32 v[8:9], v[142:143], v[8:9] op_sel_hi:[0,1]
	v_pk_mul_f32 v[10:11], v[142:143], v[10:11] op_sel_hi:[0,1]
	v_pk_mul_f32 v[8:9], v[124:125], v[8:9]
	v_pk_mul_f32 v[10:11], v[10:11], v[126:127]
	v_cvt_pk_bf16_f32 v8, v8, v9
	v_cvt_pk_bf16_f32 v9, v10, v11
	global_store_dwordx2 v[50:51], v[8:9], off offset:32
	v_pk_mul_f32 v[4:5], v[142:143], v[4:5] op_sel_hi:[0,1]
	v_pk_mul_f32 v[6:7], v[142:143], v[6:7] op_sel_hi:[0,1]
	v_pk_mul_f32 v[4:5], v[128:129], v[4:5]
	v_pk_mul_f32 v[6:7], v[6:7], v[130:131]
	v_cvt_pk_bf16_f32 v4, v4, v5
	v_cvt_pk_bf16_f32 v5, v6, v7
	global_store_dwordx2 v[50:51], v[4:5], off offset:64
	v_pk_mul_f32 v[0:1], v[142:143], v[0:1] op_sel_hi:[0,1]
	v_pk_mul_f32 v[2:3], v[142:143], v[2:3] op_sel_hi:[0,1]
	v_pk_mul_f32 v[0:1], v[132:133], v[0:1]
	v_pk_mul_f32 v[2:3], v[2:3], v[134:135]
	v_cvt_pk_bf16_f32 v0, v0, v1
	v_cvt_pk_bf16_f32 v1, v2, v3
	global_store_dwordx2 v[50:51], v[0:1], off offset:96
	s_add_i32 s8, s8, s3
	s_cmpk_lt_u32 s8, 0x200
	s_cbranch_scc1 .LBB0_889

.LBB0_977:
	v_lshrrev_b32_e32 v0, 6, v106
	v_lshl_add_u32 v104, s96, 2, v0
	s_mov_b32 s0, 0x8000
	v_cmp_gt_i32_e32 vcc, s0, v104
	s_and_saveexec_b64 s[0:1], vcc
	s_cbranch_execz .LBB0_992
	v_mov_b32_e32 v3, 0
	v_and_b32_e32 v7, 1, v106
	v_and_b32_e32 v4, 48, v106
	v_lshl_or_b32 v4, v7, 6, v4
	v_mov_b32_e32 v5, v3
	v_mov_b32_e32 v1, 0x110
	v_lshl_add_u64 v[4:5], s[56:57], 0, v[4:5]
	s_mov_b64 s[0:1], 0x800000
	v_lshl_add_u32 v128, v0, 11, v1
	v_and_b32_e32 v1, 15, v106
	v_and_b32_e32 v8, 63, v106
	v_bfe_u32 v6, v106, 4, 2
	v_lshlrev_b32_e32 v9, 1, v106
	v_lshl_add_u64 v[106:107], v[4:5], 0, s[0:1]
	v_mbcnt_lo_u32_b32 v5, -1, 0
	v_lshlrev_b32_e32 v4, 5, v1
	v_mbcnt_hi_u32_b32 v5, -1, v5
	v_lshlrev_b32_e32 v10, 5, v6
	v_and_b32_e32 v9, 28, v9
	v_lshl_or_b32 v4, v6, 3, v4
	v_and_b32_e32 v6, 64, v5
	v_lshl_add_u32 v11, v7, 7, v128
	v_add_u32_e32 v130, v128, v9
	v_cmp_eq_u32_e32 vcc, 0, v7
	v_add_u32_e32 v9, 64, v6
	v_lshlrev_b32_e32 v6, 3, v8
	v_mov_b32_e32 v7, v3
	s_add_u32 s38, s60, 0x10000
	v_lshl_add_u64 v[6:7], s[58:59], 0, v[6:7]
	s_addc_u32 s39, s61, 0
	v_lshl_add_u64 v[108:109], v[6:7], 0, s[0:1]
	v_readlane_b32 s0, v254, 0
	s_add_u32 s40, s62, 0x10000
	v_readlane_b32 s1, v254, 1
	s_addc_u32 s41, s63, 0
	s_lshl_b32 s33, s0, 2
	v_cmp_eq_u32_e64 s[0:1], 0, v1
	v_cmp_eq_u32_e64 s[2:3], 1, v1
	v_cmp_eq_u32_e64 s[4:5], 2, v1
	v_cmp_eq_u32_e64 s[6:7], 3, v1
	v_cmp_eq_u32_e64 s[8:9], 4, v1
	v_cmp_eq_u32_e64 s[10:11], 5, v1
	v_cmp_eq_u32_e64 s[12:13], 6, v1
	v_cmp_eq_u32_e64 s[14:15], 7, v1
	v_cmp_eq_u32_e64 s[16:17], 11, v1
	v_cmp_eq_u32_e64 s[18:19], 10, v1
	v_cmp_eq_u32_e64 s[20:21], 9, v1
	v_cmp_eq_u32_e64 s[22:23], 8, v1
	v_cmp_eq_u32_e64 s[24:25], 12, v1
	v_cmp_eq_u32_e64 s[26:27], 13, v1
	v_cmp_eq_u32_e64 s[28:29], 14, v1
	v_cmp_eq_u32_e64 s[30:31], 15, v1
	v_xor_b32_e32 v1, 32, v5
	v_cmp_lt_i32_e64 s[34:35], v1, v9
	v_readlane_b32 s44, v254, 24
	v_lshlrev_b32_e32 v6, 6, v8
	v_cndmask_b32_e64 v1, v5, v1, s[34:35]
	v_lshlrev_b32_e32 v132, 2, v1
	v_xor_b32_e32 v1, 16, v5
	v_cmp_lt_i32_e64 s[34:35], v1, v9
	v_mov_b32_e32 v7, v3
	v_readlane_b32 s45, v254, 25
	v_cndmask_b32_e64 v1, v5, v1, s[34:35]
	v_lshlrev_b32_e32 v133, 2, v1
	v_xor_b32_e32 v1, 8, v5
	v_cmp_lt_i32_e64 s[34:35], v1, v9
	v_lshlrev_b32_e32 v0, 2, v8
	v_lshlrev_b32_e32 v2, 4, v8
	v_cndmask_b32_e64 v1, v5, v1, s[34:35]
	v_lshlrev_b32_e32 v134, 2, v1
	v_xor_b32_e32 v1, 4, v5
	v_cmp_lt_i32_e64 s[34:35], v1, v9
	v_readlane_b32 s46, v254, 26
	v_readlane_b32 s47, v254, 27
	v_cndmask_b32_e64 v1, v5, v1, s[34:35]
	v_lshlrev_b32_e32 v135, 2, v1
	v_xor_b32_e32 v1, 2, v5
	v_cmp_lt_i32_e64 s[34:35], v1, v9
	v_readlane_b32 s48, v254, 28
	v_readlane_b32 s49, v254, 29
	v_cndmask_b32_e64 v1, v5, v1, s[34:35]
	v_lshlrev_b32_e32 v136, 2, v1
	v_xor_b32_e32 v1, 1, v5
	v_cmp_lt_i32_e64 s[34:35], v1, v9
	v_lshl_add_u64 v[8:9], s[44:45], 0, v[6:7]
	v_readlane_b32 s50, v254, 30
	v_cndmask_b32_e64 v1, v5, v1, s[34:35]
	s_mov_b64 s[34:35], 0x3000
	v_lshlrev_b32_e32 v137, 2, v1
	v_readlane_b32 s51, v254, 31
	v_readlane_b32 s52, v254, 32
	v_readlane_b32 s53, v254, 33
	v_readlane_b32 s54, v254, 34
	v_readlane_b32 s55, v254, 35
	v_readlane_b32 s56, v254, 36
	v_lshl_add_u64 v[110:111], v[8:9], 0, s[34:35]
	v_lshl_add_u64 v[8:9], s[46:47], 0, v[6:7]
	v_mov_b32_e32 v1, v3
	v_mov_b32_e32 v5, v3
	v_add_u32_e32 v129, v128, v0
	v_add_u32_e32 v131, v128, v4
	v_lshl_add_u64 v[112:113], v[8:9], 0, s[34:35]
	v_lshl_add_u64 v[114:115], s[90:91], 0, v[0:1]
	v_lshl_add_u64 v[116:117], s[94:95], 0, v[2:3]
	v_lshl_add_u64 v[118:119], s[82:83], 0, v[6:7]
	v_lshl_add_u64 v[120:121], s[92:93], 0, v[4:5]
	v_lshl_add_u64 v[122:123], s[48:49], 0, v[6:7]
	v_add_u32_e32 v138, 64, v128
	s_mov_b64 s[42:43], 0
	v_add_u32_e32 v139, v128, v2
	v_add_u32_e32 v140, v11, v10
	s_mov_b32 s45, 0x378e98ab
	s_mov_b32 s46, 0x3b7cd369
	s_mov_b32 s47, 0xbcc618b2
	s_mov_b32 s48, 0x3dda74e4
	s_mov_b32 s49, 0x3f228afd
	s_mov_b32 s50, 0x3e03c728
	s_mov_b32 s51, 0xbfb8aa3b
	s_mov_b32 s52, 0x42ce8ed0
	s_mov_b32 s53, 0xc2b17218
	v_mov_b32_e32 v141, 0x3ba10414
	s_brev_b32 s54, -2
	s_mov_b32 s44, 0x3fb504f3
	v_mov_b32_e32 v142, 0x3727c5ac
	s_mov_b32 s55, 0x800000
	s_movk_i32 s56, 0x7fff
	v_mov_b32_e32 v143, 0xb9c68948
	v_mov_b32_e32 v144, 0x7f800000
	v_mov_b32_e32 v145, 15
	v_readlane_b32 s57, v254, 37
	v_readlane_b32 s58, v254, 38
	v_readlane_b32 s59, v254, 39
	v_mov_b32_e32 v212, v104
	v_mov_b32_e32 v213, 0
	v_lshlrev_b64 v[214:215], 9, v[212:213]
	v_lshlrev_b64 v[216:217], 10, v[212:213]
	v_lshlrev_b64 v[218:219], 2, v[212:213]
	v_lshl_add_u64 v[214:215], v[114:115], 0, v[214:215]
	v_lshl_add_u64 v[216:217], v[116:117], 0, v[216:217]
	v_lshl_add_u64 v[220:221], s[68:69], 0, v[218:219]
	v_lshl_add_u64 v[218:219], s[70:71], 0, v[218:219]
	global_load_dword v230, v[214:215], off
	global_load_dword v231, v[214:215], off offset:256
	global_load_dwordx4 v[232:235], v[216:217], off
	global_load_dword v236, v[220:221], off
	global_load_dword v237, v[218:219], off
	s_waitcnt vmcnt(0)
	s_branch .LBB0_980
.LBB0_979:
	v_lshlrev_b64 v[32:33], 2, v[124:125]
	v_add_f32_e32 v16, v99, v105
	v_mul_f32_e32 v16, 0x40f00000, v16
	v_add_u32_e32 v104, s33, v104
	v_cmp_lt_i32_e64 s[36:37], s56, v104
	v_lshl_add_u64 v[32:33], v[122:123], 0, v[32:33]
	s_or_b64 s[42:43], s[36:37], s[42:43]
	v_pk_fma_f32 v[0:1], v[212:213], s[44:45], v[16:17] op_sel_hi:[1,0,0] neg_lo:[0,0,1] neg_hi:[0,0,1]
	s_nop 0
	v_pk_add_f32 v[34:35], v[90:91], v[0:1]
	v_pk_fma_f32 v[2:3], v[214:215], s[44:45], v[16:17] op_sel_hi:[1,0,0] neg_lo:[0,0,1] neg_hi:[0,0,1]
	v_add_f32_e32 v0, 0, v34
	v_pk_add_f32 v[36:37], v[88:89], v[2:3]
	v_add_f32_e32 v0, v0, v35
	v_pk_fma_f32 v[4:5], v[216:217], s[44:45], v[16:17] op_sel_hi:[1,0,0] neg_lo:[0,0,1] neg_hi:[0,0,1]
	v_add_f32_e32 v0, v0, v36
	v_pk_add_f32 v[38:39], v[84:85], v[4:5]
	v_add_f32_e32 v0, v0, v37
	v_pk_fma_f32 v[6:7], v[218:219], s[44:45], v[16:17] op_sel_hi:[1,0,0] neg_lo:[0,0,1] neg_hi:[0,0,1]
	v_add_f32_e32 v0, v0, v38
	v_pk_add_f32 v[40:41], v[80:81], v[6:7]
	v_add_f32_e32 v0, v0, v39
	v_pk_fma_f32 v[8:9], v[220:221], s[44:45], v[16:17] op_sel_hi:[1,0,0] neg_lo:[0,0,1] neg_hi:[0,0,1]
	v_add_f32_e32 v0, v0, v40
	v_pk_add_f32 v[42:43], v[76:77], v[8:9]
	v_add_f32_e32 v0, v0, v41
	v_pk_fma_f32 v[10:11], v[222:223], s[44:45], v[16:17] op_sel_hi:[1,0,0] neg_lo:[0,0,1] neg_hi:[0,0,1]
	v_add_f32_e32 v0, v0, v42
	v_pk_add_f32 v[44:45], v[68:69], v[10:11]
	v_add_f32_e32 v0, v0, v43
	v_pk_fma_f32 v[12:13], v[224:225], s[44:45], v[16:17] op_sel_hi:[1,0,0] neg_lo:[0,0,1] neg_hi:[0,0,1]
	v_add_f32_e32 v0, v0, v44
	v_pk_add_f32 v[46:47], v[62:63], v[12:13]
	v_add_f32_e32 v0, v0, v45
	v_pk_fma_f32 v[14:15], v[226:227], s[44:45], v[16:17] op_sel_hi:[1,0,0] neg_lo:[0,0,1] neg_hi:[0,0,1]
	v_add_f32_e32 v0, v0, v46
	v_pk_add_f32 v[48:49], v[60:61], v[14:15]
	v_add_f32_e32 v0, v0, v47
	v_add_f32_e32 v0, v0, v48
	v_add_f32_e32 v0, v0, v49
	ds_bpermute_b32 v1, v132, v0
	s_waitcnt lgkmcnt(0)
	v_add_f32_e32 v0, v0, v1
	ds_bpermute_b32 v1, v133, v0
	s_waitcnt lgkmcnt(0)
	v_add_f32_e32 v0, v0, v1
	ds_bpermute_b32 v1, v134, v0
	s_waitcnt lgkmcnt(0)
	v_add_f32_e32 v0, v0, v1
	ds_bpermute_b32 v1, v135, v0
	s_waitcnt lgkmcnt(0)
	v_add_f32_e32 v16, v0, v1
	ds_bpermute_b32 v17, v136, v16
	global_load_dwordx4 v[0:3], v[110:111], off offset:48
	global_load_dwordx4 v[4:7], v[110:111], off offset:32
	global_load_dwordx4 v[8:11], v[110:111], off offset:16
	global_load_dwordx4 v[12:15], v[110:111], off
	s_waitcnt lgkmcnt(0)
	v_add_f32_e32 v50, v16, v17
	global_load_dwordx4 v[16:19], v[112:113], off offset:48
	global_load_dwordx4 v[20:23], v[112:113], off offset:32
	global_load_dwordx4 v[24:27], v[112:113], off offset:16
	global_load_dwordx4 v[28:31], v[112:113], off
	ds_bpermute_b32 v51, v137, v50
	s_waitcnt lgkmcnt(0)
	v_add_f32_e32 v50, v50, v51
	v_mul_f32_e32 v50, 0x3a800000, v50
	v_pk_add_f32 v[34:35], v[34:35], v[50:51] op_sel_hi:[1,0] neg_lo:[0,1] neg_hi:[0,1]
	v_pk_add_f32 v[36:37], v[36:37], v[50:51] op_sel_hi:[1,0] neg_lo:[0,1] neg_hi:[0,1]
	v_pk_add_f32 v[38:39], v[38:39], v[50:51] op_sel_hi:[1,0] neg_lo:[0,1] neg_hi:[0,1]
	v_pk_add_f32 v[40:41], v[40:41], v[50:51] op_sel_hi:[1,0] neg_lo:[0,1] neg_hi:[0,1]
	v_pk_add_f32 v[42:43], v[42:43], v[50:51] op_sel_hi:[1,0] neg_lo:[0,1] neg_hi:[0,1]
	v_pk_add_f32 v[44:45], v[44:45], v[50:51] op_sel_hi:[1,0] neg_lo:[0,1] neg_hi:[0,1]
	v_pk_add_f32 v[46:47], v[46:47], v[50:51] op_sel_hi:[1,0] neg_lo:[0,1] neg_hi:[0,1]
	v_pk_add_f32 v[48:49], v[48:49], v[50:51] op_sel_hi:[1,0] neg_lo:[0,1] neg_hi:[0,1]
	v_pk_mul_f32 v[50:51], v[34:35], v[34:35]
	v_pk_mul_f32 v[52:53], v[36:37], v[36:37]
	v_add_f32_e32 v50, v50, v51
	v_add_f32_e32 v50, v52, v50
	v_pk_mul_f32 v[54:55], v[38:39], v[38:39]
	v_add_f32_e32 v50, v53, v50
	v_add_f32_e32 v50, v54, v50
	v_pk_mul_f32 v[56:57], v[40:41], v[40:41]
	v_add_f32_e32 v50, v55, v50
	v_add_f32_e32 v50, v56, v50
	v_pk_mul_f32 v[58:59], v[42:43], v[42:43]
	v_add_f32_e32 v50, v57, v50
	v_add_f32_e32 v50, v58, v50
	v_pk_mul_f32 v[60:61], v[44:45], v[44:45]
	v_add_f32_e32 v50, v59, v50
	v_add_f32_e32 v50, v60, v50
	v_pk_mul_f32 v[62:63], v[46:47], v[46:47]
	v_add_f32_e32 v50, v61, v50
	v_add_f32_e32 v50, v62, v50
	v_pk_mul_f32 v[64:65], v[48:49], v[48:49]
	v_add_f32_e32 v50, v63, v50
	v_add_f32_e32 v50, v64, v50
	v_add_f32_e32 v50, v65, v50
	ds_bpermute_b32 v51, v132, v50
	s_waitcnt lgkmcnt(0)
	v_add_f32_e32 v50, v50, v51
	ds_bpermute_b32 v51, v133, v50
	s_waitcnt lgkmcnt(0)
	v_add_f32_e32 v50, v50, v51
	ds_bpermute_b32 v51, v134, v50
	s_waitcnt lgkmcnt(0)
	v_add_f32_e32 v50, v50, v51
	ds_bpermute_b32 v51, v135, v50
	s_waitcnt lgkmcnt(0)
	v_add_f32_e32 v50, v50, v51
	ds_bpermute_b32 v51, v136, v50
	s_waitcnt lgkmcnt(0)
	v_add_f32_e32 v50, v50, v51
	ds_bpermute_b32 v51, v137, v50
	s_waitcnt lgkmcnt(0)
	v_add_f32_e32 v50, v50, v51
	v_fmamk_f32 v50, v50, 0x3a800000, v142
	v_mul_f32_e32 v51, 0x4b800000, v50
	v_cmp_gt_f32_e64 s[34:35], s55, v50
	s_nop 1
	v_cndmask_b32_e64 v50, v50, v51, s[34:35]
	v_rsq_f32_e32 v50, v50
	s_nop 0
	v_mul_f32_e32 v51, 0x45800000, v50
	v_cndmask_b32_e64 v50, v50, v51, s[34:35]
	v_pk_mul_f32 v[34:35], v[34:35], v[50:51] op_sel_hi:[1,0]
	v_pk_mul_f32 v[36:37], v[36:37], v[50:51] op_sel_hi:[1,0]
	v_pk_mul_f32 v[38:39], v[38:39], v[50:51] op_sel_hi:[1,0]
	v_pk_mul_f32 v[40:41], v[40:41], v[50:51] op_sel_hi:[1,0]
	v_pk_mul_f32 v[42:43], v[42:43], v[50:51] op_sel_hi:[1,0]
	v_pk_mul_f32 v[44:45], v[44:45], v[50:51] op_sel_hi:[1,0]
	v_pk_mul_f32 v[46:47], v[46:47], v[50:51] op_sel_hi:[1,0]
	v_pk_mul_f32 v[48:49], v[48:49], v[50:51] op_sel_hi:[1,0]
	s_waitcnt vmcnt(0)
	v_pk_fma_f32 v[12:13], v[12:13], v[34:35], v[28:29]
	v_pk_fma_f32 v[14:15], v[14:15], v[36:37], v[30:31]
	v_pk_fma_f32 v[8:9], v[8:9], v[38:39], v[24:25]
	v_pk_fma_f32 v[10:11], v[10:11], v[40:41], v[26:27]
	v_pk_fma_f32 v[4:5], v[4:5], v[42:43], v[20:21]
	v_pk_fma_f32 v[6:7], v[6:7], v[44:45], v[22:23]
	v_pk_fma_f32 v[0:1], v[46:47], v[0:1], v[16:17]
	v_pk_fma_f32 v[2:3], v[48:49], v[2:3], v[18:19]
	global_store_dwordx4 v[32:33], v[12:15], off
	global_store_dwordx4 v[32:33], v[8:11], off offset:16
	global_store_dwordx4 v[32:33], v[4:7], off offset:32
	global_store_dwordx4 v[32:33], v[0:3], off offset:48
	s_andn2_b64 exec, exec, s[42:43]
	s_cbranch_execz .LBB0_992
.LBB0_980:
	v_ashrrev_i32_e32 v105, 31, v104
	v_lshlrev_b64 v[124:125], 10, v[104:105]
	v_mov_b32_e32 v126, v236
	v_mov_b32_e32 v127, v237
	ds_write2st64_b32 v129, v230, v231 offset1:1
	ds_write_b128 v139, v[232:235] offset:1024
	ds_read2_b32 v[0:1], v130 offset1:8
	s_waitcnt lgkmcnt(0)
	v_ashrrev_i32_e32 v3, 31, v0
	v_mov_b32_e32 v2, v0
	v_lshlrev_b64 v[2:3], 9, v[2:3]
	v_lshl_add_u64 v[2:3], v[106:107], 0, v[2:3]
	global_load_dwordx4 v[84:87], v[2:3], off
	global_load_dwordx4 v[88:91], v[2:3], off offset:128
	global_load_dwordx4 v[92:95], v[2:3], off offset:256
	global_load_dwordx4 v[96:99], v[2:3], off offset:384
	v_ashrrev_i32_e32 v3, 31, v1
	v_mov_b32_e32 v2, v1
	v_lshlrev_b64 v[0:1], 9, v[2:3]
	v_lshl_add_u64 v[24:25], v[106:107], 0, v[0:1]
	global_load_dwordx4 v[100:103], v[24:25], off
	global_load_dwordx4 v[76:79], v[24:25], off offset:128
	ds_read2_b32 v[32:33], v130 offset0:16 offset1:24
	ds_read2_b32 v[80:81], v130 offset0:32 offset1:40
	ds_read_b128 v[4:7], v140 offset:1024
	ds_read_b128 v[0:3], v140 offset:1040
	global_load_dwordx4 v[146:149], v[24:25], off offset:256
	s_waitcnt lgkmcnt(3)
	v_ashrrev_i32_e32 v27, 31, v32
	v_mov_b32_e32 v26, v32
	v_lshlrev_b64 v[26:27], 9, v[26:27]
	ds_read_b128 v[12:15], v140 offset:1280
	ds_read_b128 v[8:11], v140 offset:1296
	ds_read_b128 v[20:23], v140 offset:1536
	ds_read_b128 v[16:19], v140 offset:1552
	v_lshl_add_u64 v[34:35], v[106:107], 0, v[26:27]
	global_load_dwordx4 v[72:75], v[24:25], off offset:384
	global_load_dwordx4 v[150:153], v[34:35], off
	v_ashrrev_i32_e32 v37, 31, v33
	v_mov_b32_e32 v36, v33
	s_waitcnt lgkmcnt(6)
	v_ashrrev_i32_e32 v33, 31, v80
	v_mov_b32_e32 v32, v80
	v_lshlrev_b64 v[36:37], 9, v[36:37]
	v_lshlrev_b64 v[32:33], 9, v[32:33]
	v_lshl_add_u64 v[36:37], v[106:107], 0, v[36:37]
	v_lshl_add_u64 v[32:33], v[106:107], 0, v[32:33]
	ds_read_b128 v[28:31], v140 offset:1792
	ds_read_b128 v[24:27], v140 offset:1808
	global_load_dwordx4 v[154:157], v[34:35], off offset:128
	global_load_dwordx4 v[68:71], v[34:35], off offset:256
	global_load_dwordx4 v[64:67], v[34:35], off offset:384
	global_load_dwordx4 v[60:63], v[36:37], off
	global_load_dwordx4 v[52:55], v[36:37], off offset:128
	global_load_dwordx4 v[56:59], v[36:37], off offset:256
	global_load_dwordx4 v[48:51], v[36:37], off offset:384
	global_load_dwordx4 v[44:47], v[32:33], off
	global_load_dwordx4 v[40:43], v[32:33], off offset:128
	s_nop 0
	global_load_dwordx4 v[36:39], v[32:33], off offset:256
	s_nop 0
	global_load_dwordx4 v[32:35], v[32:33], off offset:384
	v_ashrrev_i32_e32 v83, 31, v81
	s_waitcnt vmcnt(19)
	v_lshrrev_b32_e32 v80, 4, v84
	v_lshrrev_b32_e32 v82, 4, v85
	v_and_b32_e32 v158, 0xf0f0f0f, v84
	v_and_b32_e32 v160, 0xf0f0f0f, v85
	v_and_b32_e32 v159, 0xf0f0f0f, v80
	v_and_b32_e32 v161, 0xf0f0f0f, v82
	v_and_b32_e32 v84, 0xf0f0f0f, v86
	s_waitcnt vmcnt(15)
	v_lshrrev_b32_e32 v165, 4, v100
	v_and_b32_e32 v176, 0xf0f0f0f, v101
	v_lshrrev_b32_e32 v101, 4, v101
	v_and_b32_e32 v174, 0xf0f0f0f, v100
	v_and_b32_e32 v175, 0xf0f0f0f, v165
	v_and_b32_e32 v177, 0xf0f0f0f, v101
	v_and_b32_e32 v100, 0xf0f0f0f, v102
	v_lshrrev_b32_e32 v179, 4, v102
	v_and_b32_e32 v102, 0xf0f0f0f, v103
	v_lshrrev_b32_e32 v103, 4, v103
	v_and_b32_e32 v101, 0xf0f0f0f, v179
	v_and_b32_e32 v103, 0xf0f0f0f, v103
	s_waitcnt lgkmcnt(7)
	v_mfma_i32_16x16x64_i8 v[174:177], v[174:177], v[4:7], 0
	v_lshrrev_b32_e32 v85, 4, v86
	v_and_b32_e32 v86, 0xf0f0f0f, v87
	v_lshrrev_b32_e32 v87, 4, v87
	s_waitcnt vmcnt(14)
	v_lshrrev_b32_e32 v181, 4, v76
	v_and_b32_e32 v180, 0xf0f0f0f, v77
	v_lshrrev_b32_e32 v77, 4, v77
	v_and_b32_e32 v85, 0xf0f0f0f, v85
	v_and_b32_e32 v87, 0xf0f0f0f, v87
	v_and_b32_e32 v178, 0xf0f0f0f, v76
	v_mfma_i32_16x16x64_i8 v[158:161], v[158:161], v[4:7], 0
	v_and_b32_e32 v179, 0xf0f0f0f, v181
	v_and_b32_e32 v181, 0xf0f0f0f, v77
	v_and_b32_e32 v76, 0xf0f0f0f, v78
	s_waitcnt lgkmcnt(6)
	v_mfma_i32_16x16x64_i8 v[100:103], v[100:103], v[0:3], v[174:177]
	v_lshrrev_b32_e32 v183, 4, v78
	v_and_b32_e32 v78, 0xf0f0f0f, v79
	v_lshrrev_b32_e32 v79, 4, v79
	s_waitcnt vmcnt(10)
	v_lshrrev_b32_e32 v77, 4, v155
	v_mfma_i32_16x16x64_i8 v[84:87], v[84:87], v[0:3], v[158:161]
	v_and_b32_e32 v79, 0xf0f0f0f, v79
	v_lshrrev_b32_e32 v189, 4, v150
	v_lshrrev_b32_e32 v80, 4, v151
	v_and_b32_e32 v161, 0xf0f0f0f, v77
	v_and_b32_e32 v77, 0xf0f0f0f, v183
	s_waitcnt lgkmcnt(5)
	v_mfma_i32_16x16x64_i8 v[100:103], v[178:181], v[12:15], v[100:103]
	v_and_b32_e32 v188, 0xf0f0f0f, v150
	v_and_b32_e32 v190, 0xf0f0f0f, v151
	v_and_b32_e32 v189, 0xf0f0f0f, v189
	v_and_b32_e32 v191, 0xf0f0f0f, v80
	v_lshrrev_b32_e32 v163, 4, v88
	v_and_b32_e32 v164, 0xf0f0f0f, v89
	v_lshrrev_b32_e32 v89, 4, v89
	v_lshrrev_b32_e32 v185, 4, v146
	v_and_b32_e32 v184, 0xf0f0f0f, v147
	v_lshrrev_b32_e32 v147, 4, v147
	v_and_b32_e32 v162, 0xf0f0f0f, v88
	v_and_b32_e32 v182, 0xf0f0f0f, v146
	v_and_b32_e32 v163, 0xf0f0f0f, v163
	v_and_b32_e32 v165, 0xf0f0f0f, v89
	v_and_b32_e32 v183, 0xf0f0f0f, v185
	v_and_b32_e32 v185, 0xf0f0f0f, v147
	v_lshrrev_b32_e32 v82, 4, v152
	v_lshrrev_b32_e32 v80, 4, v153
	s_waitcnt lgkmcnt(4)
	v_mfma_i32_16x16x64_i8 v[76:79], v[76:79], v[8:11], v[100:103]
	v_and_b32_e32 v150, 0xf0f0f0f, v152
	v_and_b32_e32 v152, 0xf0f0f0f, v153
	v_and_b32_e32 v151, 0xf0f0f0f, v82
	v_and_b32_e32 v153, 0xf0f0f0f, v80
	v_and_b32_e32 v88, 0xf0f0f0f, v90
	v_lshrrev_b32_e32 v167, 4, v90
	v_and_b32_e32 v90, 0xf0f0f0f, v91
	v_lshrrev_b32_e32 v91, 4, v91
	v_and_b32_e32 v146, 0xf0f0f0f, v148
	v_lshrrev_b32_e32 v187, 4, v148
	v_and_b32_e32 v148, 0xf0f0f0f, v149
	v_lshrrev_b32_e32 v149, 4, v149
	v_mfma_i32_16x16x64_i8 v[188:191], v[188:191], v[4:7], 0
	v_and_b32_e32 v89, 0xf0f0f0f, v167
	v_and_b32_e32 v91, 0xf0f0f0f, v91
	v_and_b32_e32 v147, 0xf0f0f0f, v187
	v_and_b32_e32 v149, 0xf0f0f0f, v149
	v_mfma_i32_16x16x64_i8 v[84:87], v[162:165], v[12:15], v[84:87]
	v_lshrrev_b32_e32 v80, 4, v154
	v_lshrrev_b32_e32 v169, 4, v92
	v_and_b32_e32 v168, 0xf0f0f0f, v93
	s_waitcnt lgkmcnt(3)
	v_mfma_i32_16x16x64_i8 v[76:79], v[182:185], v[20:23], v[76:79]
	v_lshrrev_b32_e32 v93, 4, v93
	v_and_b32_e32 v159, 0xf0f0f0f, v80
	v_lshrrev_b32_e32 v80, 4, v72
	v_mfma_i32_16x16x64_i8 v[150:153], v[150:153], v[0:3], v[188:191]
	v_and_b32_e32 v166, 0xf0f0f0f, v92
	v_and_b32_e32 v186, 0xf0f0f0f, v72
	v_and_b32_e32 v167, 0xf0f0f0f, v169
	v_and_b32_e32 v188, 0xf0f0f0f, v73
	v_lshrrev_b32_e32 v73, 4, v73
	v_and_b32_e32 v169, 0xf0f0f0f, v93
	v_and_b32_e32 v187, 0xf0f0f0f, v80
	v_and_b32_e32 v189, 0xf0f0f0f, v73
	v_mfma_i32_16x16x64_i8 v[84:87], v[88:91], v[8:11], v[84:87]
	v_and_b32_e32 v92, 0xf0f0f0f, v94
	v_lshrrev_b32_e32 v171, 4, v94
	v_and_b32_e32 v94, 0xf0f0f0f, v95
	s_waitcnt lgkmcnt(2)
	v_mfma_i32_16x16x64_i8 v[76:79], v[146:149], v[16:19], v[76:79]
	v_lshrrev_b32_e32 v95, 4, v95
	v_and_b32_e32 v158, 0xf0f0f0f, v154
	v_and_b32_e32 v160, 0xf0f0f0f, v155
	v_and_b32_e32 v72, 0xf0f0f0f, v74
	v_lshrrev_b32_e32 v82, 4, v74
	v_and_b32_e32 v74, 0xf0f0f0f, v75
	v_lshrrev_b32_e32 v75, 4, v75
	v_and_b32_e32 v93, 0xf0f0f0f, v171
	v_and_b32_e32 v95, 0xf0f0f0f, v95
	v_and_b32_e32 v73, 0xf0f0f0f, v82
	v_and_b32_e32 v75, 0xf0f0f0f, v75
	v_mfma_i32_16x16x64_i8 v[84:87], v[166:169], v[20:23], v[84:87]
	v_lshrrev_b32_e32 v80, 4, v156
	v_lshrrev_b32_e32 v82, 4, v157
	v_and_b32_e32 v88, 0xf0f0f0f, v156
	s_waitcnt lgkmcnt(1)
	v_mfma_i32_16x16x64_i8 v[76:79], v[186:189], v[28:31], v[76:79]
	v_and_b32_e32 v90, 0xf0f0f0f, v157
	v_and_b32_e32 v89, 0xf0f0f0f, v80
	v_and_b32_e32 v91, 0xf0f0f0f, v82
	v_mfma_i32_16x16x64_i8 v[150:153], v[158:161], v[12:15], v[150:153]
	v_mov_b32_e32 v82, v81
	v_lshrrev_b32_e32 v173, 4, v96
	v_and_b32_e32 v172, 0xf0f0f0f, v97
	v_mfma_i32_16x16x64_i8 v[84:87], v[92:95], v[16:19], v[84:87]
	v_lshrrev_b32_e32 v97, 4, v97
	v_and_b32_e32 v170, 0xf0f0f0f, v96
	v_and_b32_e32 v171, 0xf0f0f0f, v173
	s_waitcnt lgkmcnt(0)
	v_mfma_i32_16x16x64_i8 v[92:95], v[72:75], v[24:27], v[76:79]
	v_lshlrev_b64 v[72:73], 9, v[82:83]
	v_lshl_add_u64 v[80:81], v[106:107], 0, v[72:73]
	v_and_b32_e32 v173, 0xf0f0f0f, v97
	s_waitcnt vmcnt(9)
	v_and_b32_e32 v76, 0xf0f0f0f, v68
	v_lshrrev_b32_e32 v68, 4, v68
	v_and_b32_e32 v77, 0xf0f0f0f, v68
	v_lshrrev_b32_e32 v68, 4, v69
	v_and_b32_e32 v78, 0xf0f0f0f, v69
	v_and_b32_e32 v79, 0xf0f0f0f, v68
	v_mfma_i32_16x16x64_i8 v[72:75], v[88:91], v[8:11], v[150:153]
	v_and_b32_e32 v68, 0xf0f0f0f, v70
	v_lshrrev_b32_e32 v69, 4, v70
	v_and_b32_e32 v70, 0xf0f0f0f, v71
	v_lshrrev_b32_e32 v71, 4, v71
	v_and_b32_e32 v69, 0xf0f0f0f, v69
	v_and_b32_e32 v71, 0xf0f0f0f, v71
	v_mfma_i32_16x16x64_i8 v[72:75], v[76:79], v[20:23], v[72:75]
	v_and_b32_e32 v96, 0xf0f0f0f, v98
	v_lshrrev_b32_e32 v192, 4, v98
	v_and_b32_e32 v98, 0xf0f0f0f, v99
	v_mfma_i32_16x16x64_i8 v[68:71], v[68:71], v[16:19], v[72:75]
	v_lshrrev_b32_e32 v99, 4, v99
	v_and_b32_e32 v97, 0xf0f0f0f, v192
	v_and_b32_e32 v99, 0xf0f0f0f, v99
	s_waitcnt vmcnt(8)
	v_and_b32_e32 v72, 0xf0f0f0f, v64
	v_lshrrev_b32_e32 v64, 4, v64
	v_and_b32_e32 v73, 0xf0f0f0f, v64
	v_lshrrev_b32_e32 v64, 4, v65
	v_and_b32_e32 v74, 0xf0f0f0f, v65
	v_and_b32_e32 v75, 0xf0f0f0f, v64
	v_and_b32_e32 v64, 0xf0f0f0f, v66
	v_lshrrev_b32_e32 v65, 4, v66
	v_and_b32_e32 v66, 0xf0f0f0f, v67
	v_lshrrev_b32_e32 v67, 4, v67
	v_and_b32_e32 v65, 0xf0f0f0f, v65
	v_and_b32_e32 v67, 0xf0f0f0f, v67
	v_mfma_i32_16x16x64_i8 v[84:87], v[170:173], v[28:31], v[84:87]
	s_waitcnt vmcnt(6)
	v_and_b32_e32 v146, 0xf0f0f0f, v54
	v_and_b32_e32 v148, 0xf0f0f0f, v55
	v_cndmask_b32_e32 v92, v93, v92, vcc
	v_mfma_i32_16x16x64_i8 v[72:75], v[72:75], v[28:31], v[68:71]
	v_mfma_i32_16x16x64_i8 v[100:103], v[96:99], v[24:27], v[84:87]
	global_load_dwordx4 v[88:91], v[80:81], off
	s_nop 1
	global_load_dwordx4 v[84:87], v[80:81], off offset:128
	ds_read2_b32 v[150:151], v130 offset0:48 offset1:56
	global_load_dwordx4 v[76:79], v[80:81], off offset:256
	global_load_dwordx4 v[68:71], v[80:81], off offset:384
	v_mfma_i32_16x16x64_i8 v[96:99], v[64:67], v[24:27], v[72:75]
	v_and_b32_e32 v64, 0xf0f0f0f, v60
	v_lshrrev_b32_e32 v60, 4, v60
	v_and_b32_e32 v65, 0xf0f0f0f, v60
	v_lshrrev_b32_e32 v60, 4, v61
	v_and_b32_e32 v66, 0xf0f0f0f, v61
	v_and_b32_e32 v67, 0xf0f0f0f, v60
	v_and_b32_e32 v60, 0xf0f0f0f, v62
	v_lshrrev_b32_e32 v61, 4, v62
	v_and_b32_e32 v62, 0xf0f0f0f, v63
	v_lshrrev_b32_e32 v63, 4, v63
	v_and_b32_e32 v61, 0xf0f0f0f, v61
	v_and_b32_e32 v63, 0xf0f0f0f, v63
	v_mfma_i32_16x16x64_i8 v[64:67], v[64:67], v[4:7], 0
	s_waitcnt lgkmcnt(0)
	v_ashrrev_i32_e32 v81, 31, v150
	v_mov_b32_e32 v80, v150
	v_lshlrev_b64 v[72:73], 9, v[80:81]
	v_mfma_i32_16x16x64_i8 v[60:63], v[60:63], v[0:3], v[64:67]
	v_lshl_add_u64 v[152:153], v[106:107], 0, v[72:73]
	v_cndmask_b32_e32 v100, v101, v100, vcc
	s_nop 0
	v_and_b32_e32 v64, 0xf0f0f0f, v52
	v_lshrrev_b32_e32 v52, 4, v52
	v_and_b32_e32 v65, 0xf0f0f0f, v52
	v_lshrrev_b32_e32 v52, 4, v53
	v_and_b32_e32 v66, 0xf0f0f0f, v53
	v_and_b32_e32 v67, 0xf0f0f0f, v52
	v_lshrrev_b32_e32 v52, 4, v54
	v_and_b32_e32 v147, 0xf0f0f0f, v52
	v_lshrrev_b32_e32 v52, 4, v55
	v_and_b32_e32 v149, 0xf0f0f0f, v52
	v_mfma_i32_16x16x64_i8 v[64:67], v[64:67], v[12:15], v[60:63]
	global_load_dwordx4 v[80:83], v[152:153], off
	global_load_dwordx4 v[72:75], v[152:153], off offset:128
	s_nop 0
	global_load_dwordx4 v[60:63], v[152:153], off offset:256
	global_load_dwordx4 v[52:55], v[152:153], off offset:384
	v_mfma_i32_16x16x64_i8 v[64:67], v[146:149], v[8:11], v[64:67]
	s_waitcnt vmcnt(13)
	v_and_b32_e32 v146, 0xf0f0f0f, v56
	v_lshrrev_b32_e32 v56, 4, v56
	v_and_b32_e32 v147, 0xf0f0f0f, v56
	v_lshrrev_b32_e32 v56, 4, v57
	v_and_b32_e32 v148, 0xf0f0f0f, v57
	v_and_b32_e32 v149, 0xf0f0f0f, v56
	v_and_b32_e32 v56, 0xf0f0f0f, v58
	v_lshrrev_b32_e32 v57, 4, v58
	v_and_b32_e32 v58, 0xf0f0f0f, v59
	v_lshrrev_b32_e32 v59, 4, v59
	v_and_b32_e32 v57, 0xf0f0f0f, v57
	v_and_b32_e32 v59, 0xf0f0f0f, v59
	v_mfma_i32_16x16x64_i8 v[64:67], v[146:149], v[20:23], v[64:67]
	v_ashrrev_i32_e32 v147, 31, v151
	v_mov_b32_e32 v146, v151
	v_lshlrev_b64 v[150:151], 9, v[146:147]
	v_mfma_i32_16x16x64_i8 v[56:59], v[56:59], v[16:19], v[64:67]
	s_waitcnt vmcnt(12)
	v_and_b32_e32 v146, 0xf0f0f0f, v50
	v_and_b32_e32 v148, 0xf0f0f0f, v51
	v_lshl_add_u64 v[150:151], v[106:107], 0, v[150:151]
	v_and_b32_e32 v64, 0xf0f0f0f, v48
	v_lshrrev_b32_e32 v48, 4, v48
	v_and_b32_e32 v65, 0xf0f0f0f, v48
	v_lshrrev_b32_e32 v48, 4, v49
	v_and_b32_e32 v66, 0xf0f0f0f, v49
	v_and_b32_e32 v67, 0xf0f0f0f, v48
	v_lshrrev_b32_e32 v48, 4, v50
	v_and_b32_e32 v147, 0xf0f0f0f, v48
	v_lshrrev_b32_e32 v48, 4, v51
	v_and_b32_e32 v149, 0xf0f0f0f, v48
	v_mfma_i32_16x16x64_i8 v[64:67], v[64:67], v[28:31], v[56:59]
	s_nop 2
	global_load_dwordx4 v[56:59], v[150:151], off
	global_load_dwordx4 v[48:51], v[150:151], off offset:128
	v_mfma_i32_16x16x64_i8 v[152:155], v[146:149], v[24:27], v[64:67]
	s_waitcnt vmcnt(13)
	v_and_b32_e32 v146, 0xf0f0f0f, v46
	v_and_b32_e32 v148, 0xf0f0f0f, v47
	v_and_b32_e32 v64, 0xf0f0f0f, v44
	v_lshrrev_b32_e32 v44, 4, v44
	v_and_b32_e32 v65, 0xf0f0f0f, v44
	v_lshrrev_b32_e32 v44, 4, v45
	v_and_b32_e32 v66, 0xf0f0f0f, v45
	v_and_b32_e32 v67, 0xf0f0f0f, v44
	v_lshrrev_b32_e32 v44, 4, v46
	v_and_b32_e32 v147, 0xf0f0f0f, v44
	v_lshrrev_b32_e32 v44, 4, v47
	v_and_b32_e32 v149, 0xf0f0f0f, v44
	v_mfma_i32_16x16x64_i8 v[156:159], v[64:67], v[4:7], 0
	global_load_dwordx4 v[64:67], v[150:151], off offset:256
	global_load_dwordx4 v[44:47], v[150:151], off offset:384
	v_mfma_i32_16x16x64_i8 v[146:149], v[146:149], v[0:3], v[156:159]
	s_waitcnt vmcnt(14)
	s_nop 3
	v_and_b32_e32 v156, 0xf0f0f0f, v40
	v_lshrrev_b32_e32 v40, 4, v40
	v_and_b32_e32 v157, 0xf0f0f0f, v40
	v_lshrrev_b32_e32 v40, 4, v41
	v_and_b32_e32 v158, 0xf0f0f0f, v41
	v_and_b32_e32 v159, 0xf0f0f0f, v40
	v_and_b32_e32 v40, 0xf0f0f0f, v42
	v_lshrrev_b32_e32 v41, 4, v42
	v_and_b32_e32 v42, 0xf0f0f0f, v43
	v_lshrrev_b32_e32 v43, 4, v43
	v_and_b32_e32 v41, 0xf0f0f0f, v41
	v_and_b32_e32 v43, 0xf0f0f0f, v43
	v_mfma_i32_16x16x64_i8 v[148:151], v[156:159], v[12:15], v[146:149]
	v_add_u32_dpp v156, v100, v100 quad_perm:[1,0,3,2] row_mask:0xf bank_mask:0xf bound_ctrl:1
	s_waitcnt vmcnt(13)
	v_and_b32_e32 v100, 0xf0f0f0f, v36
	v_lshrrev_b32_e32 v36, 4, v36
	v_and_b32_e32 v101, 0xf0f0f0f, v36
	v_lshrrev_b32_e32 v36, 4, v37
	v_cndmask_b32_e32 v146, v103, v102, vcc
	v_and_b32_e32 v102, 0xf0f0f0f, v37
	v_and_b32_e32 v103, 0xf0f0f0f, v36
	v_mfma_i32_16x16x64_i8 v[40:43], v[40:43], v[8:11], v[148:151]
	v_and_b32_e32 v36, 0xf0f0f0f, v38
	v_lshrrev_b32_e32 v37, 4, v38
	v_and_b32_e32 v38, 0xf0f0f0f, v39
	v_lshrrev_b32_e32 v39, 4, v39
	v_and_b32_e32 v37, 0xf0f0f0f, v37
	v_and_b32_e32 v39, 0xf0f0f0f, v39
	v_mfma_i32_16x16x64_i8 v[40:43], v[100:103], v[20:23], v[40:43]
	v_cndmask_b32_e64 v100, 0, v156, s[0:1]
	v_cndmask_b32_e32 v148, v95, v94, vcc
	v_cndmask_b32_e32 v150, v99, v98, vcc
	v_mfma_i32_16x16x64_i8 v[36:39], v[36:39], v[16:19], v[40:43]
	v_mov_b32_dpp v147, v146 quad_perm:[1,0,3,2] row_mask:0xf bank_mask:0xf bound_ctrl:1
	v_mov_b32_dpp v149, v148 quad_perm:[1,0,3,2] row_mask:0xf bank_mask:0xf bound_ctrl:1
	v_mov_b32_dpp v151, v150 quad_perm:[1,0,3,2] row_mask:0xf bank_mask:0xf bound_ctrl:1
	s_waitcnt vmcnt(12)
	v_and_b32_e32 v40, 0xf0f0f0f, v32
	v_lshrrev_b32_e32 v32, 4, v32
	v_and_b32_e32 v41, 0xf0f0f0f, v32
	v_lshrrev_b32_e32 v32, 4, v33
	v_and_b32_e32 v42, 0xf0f0f0f, v33
	v_and_b32_e32 v43, 0xf0f0f0f, v32
	v_and_b32_e32 v32, 0xf0f0f0f, v34
	v_lshrrev_b32_e32 v33, 4, v34
	v_and_b32_e32 v34, 0xf0f0f0f, v35
	v_lshrrev_b32_e32 v35, 4, v35
	v_and_b32_e32 v33, 0xf0f0f0f, v33
	v_and_b32_e32 v35, 0xf0f0f0f, v35
	v_mfma_i32_16x16x64_i8 v[36:39], v[40:43], v[28:31], v[36:39]
	v_add_u32_dpp v40, v92, v92 quad_perm:[1,0,3,2] row_mask:0xf bank_mask:0xf bound_ctrl:1
	s_waitcnt vmcnt(11)
	v_lshrrev_b32_e32 v41, 4, v90
	v_lshrrev_b32_e32 v43, 4, v91
	v_mfma_i32_16x16x64_i8 v[32:35], v[32:35], v[24:27], v[36:39]
	v_cndmask_b32_e64 v92, v100, v40, s[2:3]
	v_and_b32_e32 v40, 0xf0f0f0f, v90
	v_and_b32_e32 v41, 0xf0f0f0f, v41
	v_lshrrev_b32_e32 v37, 4, v88
	v_lshrrev_b32_e32 v39, 4, v89
	v_and_b32_e32 v36, 0xf0f0f0f, v88
	v_and_b32_e32 v37, 0xf0f0f0f, v37
	v_and_b32_e32 v38, 0xf0f0f0f, v89
	v_and_b32_e32 v39, 0xf0f0f0f, v39
	v_and_b32_e32 v42, 0xf0f0f0f, v91
	v_and_b32_e32 v43, 0xf0f0f0f, v43
	v_mfma_i32_16x16x64_i8 v[36:39], v[36:39], v[4:7], 0
	v_cndmask_b32_e32 v88, v97, v96, vcc
	v_cndmask_b32_e32 v89, v153, v152, vcc
	v_cndmask_b32_e32 v152, v155, v154, vcc
	v_mfma_i32_16x16x64_i8 v[36:39], v[40:43], v[0:3], v[36:39]
	s_waitcnt vmcnt(10)
	v_lshrrev_b32_e32 v41, 4, v84
	v_lshrrev_b32_e32 v43, 4, v85
	v_and_b32_e32 v40, 0xf0f0f0f, v84
	v_and_b32_e32 v41, 0xf0f0f0f, v41
	v_and_b32_e32 v42, 0xf0f0f0f, v85
	v_and_b32_e32 v43, 0xf0f0f0f, v43
	v_and_b32_e32 v84, 0xf0f0f0f, v86
	v_lshrrev_b32_e32 v85, 4, v86
	v_and_b32_e32 v86, 0xf0f0f0f, v87
	v_lshrrev_b32_e32 v87, 4, v87
	v_and_b32_e32 v85, 0xf0f0f0f, v85
	v_and_b32_e32 v87, 0xf0f0f0f, v87
	v_mfma_i32_16x16x64_i8 v[36:39], v[40:43], v[12:15], v[36:39]
	v_add_u32_dpp v40, v88, v88 quad_perm:[1,0,3,2] row_mask:0xf bank_mask:0xf bound_ctrl:1
	s_waitcnt vmcnt(9)
	v_lshrrev_b32_e32 v41, 4, v76
	v_lshrrev_b32_e32 v43, 4, v77
	v_cndmask_b32_e64 v88, v92, v40, s[4:5]
	v_and_b32_e32 v40, 0xf0f0f0f, v76
	v_and_b32_e32 v41, 0xf0f0f0f, v41
	v_and_b32_e32 v42, 0xf0f0f0f, v77
	v_and_b32_e32 v43, 0xf0f0f0f, v43
	v_mfma_i32_16x16x64_i8 v[36:39], v[84:87], v[8:11], v[36:39]
	v_and_b32_e32 v76, 0xf0f0f0f, v78
	v_lshrrev_b32_e32 v77, 4, v78
	v_and_b32_e32 v78, 0xf0f0f0f, v79
	v_lshrrev_b32_e32 v79, 4, v79
	v_and_b32_e32 v77, 0xf0f0f0f, v77
	v_and_b32_e32 v79, 0xf0f0f0f, v79
	v_mfma_i32_16x16x64_i8 v[36:39], v[40:43], v[20:23], v[36:39]
	ds_read2_b32 v[84:85], v130 offset0:64 offset1:72
	s_waitcnt vmcnt(8)
	v_lshrrev_b32_e32 v41, 4, v68
	v_lshrrev_b32_e32 v43, 4, v69
	v_and_b32_e32 v40, 0xf0f0f0f, v68
	v_and_b32_e32 v41, 0xf0f0f0f, v41
	v_and_b32_e32 v42, 0xf0f0f0f, v69
	v_and_b32_e32 v43, 0xf0f0f0f, v43
	v_mfma_i32_16x16x64_i8 v[36:39], v[76:79], v[16:19], v[36:39]
	v_and_b32_e32 v68, 0xf0f0f0f, v70
	v_lshrrev_b32_e32 v69, 4, v70
	v_and_b32_e32 v70, 0xf0f0f0f, v71
	v_lshrrev_b32_e32 v71, 4, v71
	s_waitcnt lgkmcnt(0)
	v_ashrrev_i32_e32 v77, 31, v84
	v_mov_b32_e32 v76, v84
	v_and_b32_e32 v69, 0xf0f0f0f, v69
	v_and_b32_e32 v71, 0xf0f0f0f, v71
	v_lshlrev_b64 v[76:77], 9, v[76:77]
	v_mfma_i32_16x16x64_i8 v[36:39], v[40:43], v[28:31], v[36:39]
	v_add_u32_dpp v40, v89, v89 quad_perm:[1,0,3,2] row_mask:0xf bank_mask:0xf bound_ctrl:1
	s_waitcnt vmcnt(7)
	v_lshrrev_b32_e32 v41, 4, v80
	v_lshrrev_b32_e32 v43, 4, v81
	v_lshl_add_u64 v[76:77], v[106:107], 0, v[76:77]
	v_cndmask_b32_e64 v166, v88, v40, s[6:7]
	v_and_b32_e32 v40, 0xf0f0f0f, v80
	v_and_b32_e32 v41, 0xf0f0f0f, v41
	v_and_b32_e32 v42, 0xf0f0f0f, v81
	v_and_b32_e32 v43, 0xf0f0f0f, v43
	global_load_dwordx4 v[92:95], v[76:77], off
	global_load_dwordx4 v[154:157], v[76:77], off offset:128
	global_load_dwordx4 v[100:103], v[76:77], off offset:256
	global_load_dwordx4 v[88:91], v[76:77], off offset:384
	v_mfma_i32_16x16x64_i8 v[36:39], v[68:71], v[24:27], v[36:39]
	v_lshrrev_b32_e32 v69, 4, v82
	v_lshrrev_b32_e32 v71, 4, v83
	v_and_b32_e32 v68, 0xf0f0f0f, v82
	v_and_b32_e32 v69, 0xf0f0f0f, v69
	v_and_b32_e32 v70, 0xf0f0f0f, v83
	v_and_b32_e32 v71, 0xf0f0f0f, v71
	v_mfma_i32_16x16x64_i8 v[40:43], v[40:43], v[4:7], 0
	s_nop 0
	v_cndmask_b32_e32 v36, v37, v36, vcc
	v_mov_b32_dpp v153, v152 quad_perm:[1,0,3,2] row_mask:0xf bank_mask:0xf bound_ctrl:1
	s_waitcnt vmcnt(1)
	v_and_b32_e32 v164, 0xf0f0f0f, v103
	v_mfma_i32_16x16x64_i8 v[40:43], v[68:71], v[0:3], v[40:43]
	v_lshrrev_b32_e32 v69, 4, v72
	v_lshrrev_b32_e32 v71, 4, v73
	v_and_b32_e32 v68, 0xf0f0f0f, v72
	v_and_b32_e32 v69, 0xf0f0f0f, v69
	v_and_b32_e32 v70, 0xf0f0f0f, v73
	v_and_b32_e32 v71, 0xf0f0f0f, v71
	v_and_b32_e32 v72, 0xf0f0f0f, v74
	v_lshrrev_b32_e32 v73, 4, v74
	v_and_b32_e32 v74, 0xf0f0f0f, v75
	v_lshrrev_b32_e32 v75, 4, v75
	v_and_b32_e32 v73, 0xf0f0f0f, v73
	v_and_b32_e32 v75, 0xf0f0f0f, v75
	v_mfma_i32_16x16x64_i8 v[40:43], v[68:71], v[12:15], v[40:43]
	v_and_b32_e32 v68, 0xf0f0f0f, v60
	v_lshrrev_b32_e32 v60, 4, v60
	v_and_b32_e32 v69, 0xf0f0f0f, v60
	v_lshrrev_b32_e32 v60, 4, v61
	v_and_b32_e32 v70, 0xf0f0f0f, v61
	v_and_b32_e32 v71, 0xf0f0f0f, v60
	v_mfma_i32_16x16x64_i8 v[40:43], v[72:75], v[8:11], v[40:43]
	v_and_b32_e32 v60, 0xf0f0f0f, v62
	v_lshrrev_b32_e32 v61, 4, v62
	v_and_b32_e32 v62, 0xf0f0f0f, v63
	v_lshrrev_b32_e32 v63, 4, v63
	v_and_b32_e32 v61, 0xf0f0f0f, v61
	v_and_b32_e32 v63, 0xf0f0f0f, v63
	v_mfma_i32_16x16x64_i8 v[40:43], v[68:71], v[20:23], v[40:43]
	v_ashrrev_i32_e32 v69, 31, v85
	v_mov_b32_e32 v68, v85
	v_lshlrev_b64 v[68:69], 9, v[68:69]
	v_mfma_i32_16x16x64_i8 v[40:43], v[60:63], v[16:19], v[40:43]
	v_and_b32_e32 v60, 0xf0f0f0f, v52
	v_lshrrev_b32_e32 v52, 4, v52
	v_and_b32_e32 v61, 0xf0f0f0f, v52
	v_lshrrev_b32_e32 v52, 4, v53
	v_and_b32_e32 v62, 0xf0f0f0f, v53
	v_and_b32_e32 v63, 0xf0f0f0f, v52
	v_and_b32_e32 v52, 0xf0f0f0f, v54
	v_lshrrev_b32_e32 v53, 4, v54
	v_and_b32_e32 v54, 0xf0f0f0f, v55
	v_lshrrev_b32_e32 v55, 4, v55
	v_and_b32_e32 v53, 0xf0f0f0f, v53
	v_and_b32_e32 v55, 0xf0f0f0f, v55
	v_mfma_i32_16x16x64_i8 v[40:43], v[60:63], v[28:31], v[40:43]
	v_lshl_add_u64 v[60:61], v[106:107], 0, v[68:69]
	global_load_dwordx4 v[96:99], v[60:61], off
	global_load_dwordx4 v[76:79], v[60:61], off offset:128
	global_load_dwordx4 v[84:87], v[60:61], off offset:256
	global_load_dwordx4 v[68:71], v[60:61], off offset:384
	v_mfma_i32_16x16x64_i8 v[72:75], v[52:55], v[24:27], v[40:43]
	v_lshrrev_b32_e32 v53, 4, v58
	v_lshrrev_b32_e32 v55, 4, v59
	v_and_b32_e32 v52, 0xf0f0f0f, v58
	v_lshrrev_b32_e32 v41, 4, v56
	v_lshrrev_b32_e32 v43, 4, v57
	v_and_b32_e32 v40, 0xf0f0f0f, v56
	v_and_b32_e32 v41, 0xf0f0f0f, v41
	v_and_b32_e32 v42, 0xf0f0f0f, v57
	v_and_b32_e32 v43, 0xf0f0f0f, v43
	v_and_b32_e32 v53, 0xf0f0f0f, v53
	v_and_b32_e32 v54, 0xf0f0f0f, v59
	v_and_b32_e32 v55, 0xf0f0f0f, v55
	v_mfma_i32_16x16x64_i8 v[40:43], v[40:43], v[4:7], 0
	ds_read2_b32 v[158:159], v130 offset0:80 offset1:88
	s_waitcnt vmcnt(3)
	v_lshrrev_b32_e32 v37, 4, v96
	v_mfma_i32_16x16x64_i8 v[40:43], v[52:55], v[0:3], v[40:43]
	v_and_b32_e32 v52, 0xf0f0f0f, v48
	v_lshrrev_b32_e32 v48, 4, v48
	v_and_b32_e32 v53, 0xf0f0f0f, v48
	v_lshrrev_b32_e32 v48, 4, v49
	v_and_b32_e32 v54, 0xf0f0f0f, v49
	v_and_b32_e32 v55, 0xf0f0f0f, v48
	v_and_b32_e32 v48, 0xf0f0f0f, v50
	v_lshrrev_b32_e32 v49, 4, v50
	v_and_b32_e32 v50, 0xf0f0f0f, v51
	v_lshrrev_b32_e32 v51, 4, v51
	v_and_b32_e32 v49, 0xf0f0f0f, v49
	v_and_b32_e32 v51, 0xf0f0f0f, v51
	v_mfma_i32_16x16x64_i8 v[40:43], v[52:55], v[12:15], v[40:43]
	s_waitcnt lgkmcnt(0)
	v_ashrrev_i32_e32 v53, 31, v158
	v_mov_b32_e32 v52, v158
	v_lshlrev_b64 v[56:57], 9, v[52:53]
	v_mfma_i32_16x16x64_i8 v[40:43], v[48:51], v[8:11], v[40:43]
	v_lshrrev_b32_e32 v49, 4, v64
	v_lshrrev_b32_e32 v51, 4, v65
	v_and_b32_e32 v48, 0xf0f0f0f, v64
	v_and_b32_e32 v49, 0xf0f0f0f, v49
	v_and_b32_e32 v50, 0xf0f0f0f, v65
	v_and_b32_e32 v51, 0xf0f0f0f, v51
	v_lshrrev_b32_e32 v53, 4, v66
	v_lshrrev_b32_e32 v55, 4, v67
	v_and_b32_e32 v52, 0xf0f0f0f, v66
	v_and_b32_e32 v53, 0xf0f0f0f, v53
	v_and_b32_e32 v54, 0xf0f0f0f, v67
	v_and_b32_e32 v55, 0xf0f0f0f, v55
	v_mfma_i32_16x16x64_i8 v[40:43], v[48:51], v[20:23], v[40:43]
	v_and_b32_e32 v48, 0xf0f0f0f, v44
	v_lshrrev_b32_e32 v44, 4, v44
	v_and_b32_e32 v49, 0xf0f0f0f, v44
	v_lshrrev_b32_e32 v44, 4, v45
	v_and_b32_e32 v50, 0xf0f0f0f, v45
	v_and_b32_e32 v51, 0xf0f0f0f, v44
	v_mfma_i32_16x16x64_i8 v[40:43], v[52:55], v[16:19], v[40:43]
	v_lshrrev_b32_e32 v44, 4, v46
	v_and_b32_e32 v53, 0xf0f0f0f, v44
	v_lshrrev_b32_e32 v44, 4, v47
	v_and_b32_e32 v52, 0xf0f0f0f, v46
	v_and_b32_e32 v54, 0xf0f0f0f, v47
	v_and_b32_e32 v55, 0xf0f0f0f, v44
	v_mfma_i32_16x16x64_i8 v[40:43], v[48:51], v[28:31], v[40:43]
	v_lshl_add_u64 v[64:65], v[106:107], 0, v[56:57]
	global_load_dwordx4 v[80:83], v[64:65], off
	global_load_dwordx4 v[60:63], v[64:65], off offset:128
	global_load_dwordx4 v[56:59], v[64:65], off offset:256
	global_load_dwordx4 v[44:47], v[64:65], off offset:384
	v_mfma_i32_16x16x64_i8 v[48:51], v[52:55], v[24:27], v[40:43]
	v_lshrrev_b32_e32 v53, 4, v94
	v_lshrrev_b32_e32 v55, 4, v95
	v_and_b32_e32 v52, 0xf0f0f0f, v94
	v_lshrrev_b32_e32 v41, 4, v92
	v_lshrrev_b32_e32 v43, 4, v93
	v_and_b32_e32 v40, 0xf0f0f0f, v92
	v_and_b32_e32 v41, 0xf0f0f0f, v41
	v_and_b32_e32 v42, 0xf0f0f0f, v93
	v_and_b32_e32 v43, 0xf0f0f0f, v43
	v_and_b32_e32 v53, 0xf0f0f0f, v53
	v_and_b32_e32 v54, 0xf0f0f0f, v95
	v_and_b32_e32 v55, 0xf0f0f0f, v55
	v_mfma_i32_16x16x64_i8 v[40:43], v[40:43], v[4:7], 0
	v_ashrrev_i32_e32 v65, 31, v159
	v_mov_b32_e32 v64, v159
	v_lshlrev_b64 v[64:65], 9, v[64:65]
	v_mfma_i32_16x16x64_i8 v[40:43], v[52:55], v[0:3], v[40:43]
	v_lshrrev_b32_e32 v53, 4, v154
	v_lshrrev_b32_e32 v55, 4, v155
	v_and_b32_e32 v52, 0xf0f0f0f, v154
	v_and_b32_e32 v53, 0xf0f0f0f, v53
	v_and_b32_e32 v54, 0xf0f0f0f, v155
	v_and_b32_e32 v55, 0xf0f0f0f, v55
	v_lshl_add_u64 v[162:163], v[106:107], 0, v[64:65]
	v_lshrrev_b32_e32 v64, 4, v156
	v_and_b32_e32 v155, 0xf0f0f0f, v64
	v_lshrrev_b32_e32 v64, 4, v157
	v_and_b32_e32 v154, 0xf0f0f0f, v156
	v_and_b32_e32 v156, 0xf0f0f0f, v157
	v_and_b32_e32 v157, 0xf0f0f0f, v64
	v_mfma_i32_16x16x64_i8 v[158:161], v[52:55], v[12:15], v[40:43]
	global_load_dwordx4 v[92:95], v[162:163], off
	global_load_dwordx4 v[64:67], v[162:163], off offset:128
	global_load_dwordx4 v[52:55], v[162:163], off offset:256
	global_load_dwordx4 v[40:43], v[162:163], off offset:384
	v_and_b32_e32 v162, 0xf0f0f0f, v102
	v_mfma_i32_16x16x64_i8 v[154:157], v[154:157], v[8:11], v[158:161]
	s_nop 2
	v_and_b32_e32 v158, 0xf0f0f0f, v100
	v_lshrrev_b32_e32 v100, 4, v100
	v_and_b32_e32 v159, 0xf0f0f0f, v100
	v_lshrrev_b32_e32 v100, 4, v101
	v_and_b32_e32 v160, 0xf0f0f0f, v101
	v_and_b32_e32 v161, 0xf0f0f0f, v100
	v_lshrrev_b32_e32 v100, 4, v102
	v_and_b32_e32 v163, 0xf0f0f0f, v100
	v_lshrrev_b32_e32 v100, 4, v103
	v_and_b32_e32 v165, 0xf0f0f0f, v100
	v_mfma_i32_16x16x64_i8 v[154:157], v[158:161], v[20:23], v[154:157]
	v_cndmask_b32_e32 v102, v33, v32, vcc
	v_cndmask_b32_e32 v100, v35, v34, vcc
	v_mfma_i32_16x16x64_i8 v[32:35], v[162:165], v[16:19], v[154:157]
	v_add_u32_dpp v102, v102, v102 quad_perm:[1,0,3,2] row_mask:0xf bank_mask:0xf bound_ctrl:1
	v_cndmask_b32_e64 v102, v166, v102, s[8:9]
	v_mov_b32_dpp v101, v100 quad_perm:[1,0,3,2] row_mask:0xf bank_mask:0xf bound_ctrl:1
	s_nop 1
	v_and_b32_e32 v154, 0xf0f0f0f, v88
	v_lshrrev_b32_e32 v88, 4, v88
	v_and_b32_e32 v155, 0xf0f0f0f, v88
	v_lshrrev_b32_e32 v88, 4, v89
	v_and_b32_e32 v156, 0xf0f0f0f, v89
	v_and_b32_e32 v157, 0xf0f0f0f, v88
	v_and_b32_e32 v88, 0xf0f0f0f, v90
	v_lshrrev_b32_e32 v89, 4, v90
	v_and_b32_e32 v90, 0xf0f0f0f, v91
	v_lshrrev_b32_e32 v91, 4, v91
	v_and_b32_e32 v89, 0xf0f0f0f, v89
	v_and_b32_e32 v91, 0xf0f0f0f, v91
	v_mfma_i32_16x16x64_i8 v[32:35], v[154:157], v[28:31], v[32:35]
	s_nop 0
	v_mfma_i32_16x16x64_i8 v[32:35], v[88:91], v[24:27], v[32:35]
	v_and_b32_e32 v89, 0xf0f0f0f, v37
	v_lshrrev_b32_e32 v37, 4, v97
	v_and_b32_e32 v88, 0xf0f0f0f, v96
	v_and_b32_e32 v90, 0xf0f0f0f, v97
	v_and_b32_e32 v91, 0xf0f0f0f, v37
	v_lshrrev_b32_e32 v37, 4, v98
	v_and_b32_e32 v97, 0xf0f0f0f, v37
	v_lshrrev_b32_e32 v37, 4, v99
	v_and_b32_e32 v96, 0xf0f0f0f, v98
	v_and_b32_e32 v98, 0xf0f0f0f, v99
	v_and_b32_e32 v99, 0xf0f0f0f, v37
	v_mfma_i32_16x16x64_i8 v[154:157], v[88:91], v[4:7], 0
	v_cndmask_b32_e32 v88, v39, v38, vcc
	v_add_u32_dpp v90, v36, v36 quad_perm:[1,0,3,2] row_mask:0xf bank_mask:0xf bound_ctrl:1
	v_cndmask_b32_e32 v91, v73, v72, vcc
	v_mfma_i32_16x16x64_i8 v[36:39], v[96:99], v[0:3], v[154:157]
	s_waitcnt vmcnt(10)
	v_and_b32_e32 v96, 0xf0f0f0f, v76
	v_lshrrev_b32_e32 v76, 4, v76
	v_and_b32_e32 v97, 0xf0f0f0f, v76
	v_lshrrev_b32_e32 v76, 4, v77
	v_and_b32_e32 v98, 0xf0f0f0f, v77
	v_and_b32_e32 v99, 0xf0f0f0f, v76
	v_and_b32_e32 v76, 0xf0f0f0f, v78
	v_lshrrev_b32_e32 v77, 4, v78
	v_and_b32_e32 v78, 0xf0f0f0f, v79
	v_lshrrev_b32_e32 v79, 4, v79
	v_and_b32_e32 v77, 0xf0f0f0f, v77
	v_and_b32_e32 v79, 0xf0f0f0f, v79
	v_mfma_i32_16x16x64_i8 v[36:39], v[96:99], v[12:15], v[36:39]
	s_waitcnt vmcnt(9)
	v_lshrrev_b32_e32 v73, 4, v84
	v_cndmask_b32_e32 v72, v75, v74, vcc
	v_and_b32_e32 v75, 0xf0f0f0f, v73
	v_lshrrev_b32_e32 v73, 4, v85
	v_mfma_i32_16x16x64_i8 v[36:39], v[76:79], v[8:11], v[36:39]
	v_and_b32_e32 v74, 0xf0f0f0f, v84
	v_and_b32_e32 v76, 0xf0f0f0f, v85
	v_and_b32_e32 v77, 0xf0f0f0f, v73
	v_lshrrev_b32_e32 v73, 4, v86
	v_and_b32_e32 v85, 0xf0f0f0f, v73
	v_lshrrev_b32_e32 v73, 4, v87
	v_and_b32_e32 v84, 0xf0f0f0f, v86
	v_and_b32_e32 v86, 0xf0f0f0f, v87
	v_and_b32_e32 v87, 0xf0f0f0f, v73
	v_cndmask_b32_e64 v90, v102, v90, s[10:11]
	v_mfma_i32_16x16x64_i8 v[36:39], v[74:77], v[20:23], v[36:39]
	v_add_u32_dpp v74, v91, v91 quad_perm:[1,0,3,2] row_mask:0xf bank_mask:0xf bound_ctrl:1
	v_cndmask_b32_e64 v78, v90, v74, s[12:13]
	s_waitcnt vmcnt(8)
	v_and_b32_e32 v74, 0xf0f0f0f, v68
	v_lshrrev_b32_e32 v68, 4, v68
	v_and_b32_e32 v75, 0xf0f0f0f, v68
	v_lshrrev_b32_e32 v68, 4, v69
	v_and_b32_e32 v76, 0xf0f0f0f, v69
	v_and_b32_e32 v77, 0xf0f0f0f, v68
	v_mfma_i32_16x16x64_i8 v[36:39], v[84:87], v[16:19], v[36:39]
	v_lshrrev_b32_e32 v68, 4, v70
	v_and_b32_e32 v85, 0xf0f0f0f, v68
	v_lshrrev_b32_e32 v68, 4, v71
	v_and_b32_e32 v84, 0xf0f0f0f, v70
	v_and_b32_e32 v86, 0xf0f0f0f, v71
	v_and_b32_e32 v87, 0xf0f0f0f, v68
	v_mfma_i32_16x16x64_i8 v[36:39], v[74:77], v[28:31], v[36:39]
	v_cndmask_b32_e32 v70, v49, v48, vcc
	v_cndmask_b32_e32 v68, v51, v50, vcc
	s_waitcnt vmcnt(7)
	v_lshrrev_b32_e32 v71, 4, v82
	v_mfma_i32_16x16x64_i8 v[48:51], v[84:87], v[24:27], v[36:39]
	v_and_b32_e32 v75, 0xf0f0f0f, v71
	v_lshrrev_b32_e32 v71, 4, v83
	v_and_b32_e32 v74, 0xf0f0f0f, v82
	v_lshrrev_b32_e32 v37, 4, v80
	v_lshrrev_b32_e32 v39, 4, v81
	v_and_b32_e32 v36, 0xf0f0f0f, v80
	v_and_b32_e32 v37, 0xf0f0f0f, v37
	v_and_b32_e32 v38, 0xf0f0f0f, v81
	v_and_b32_e32 v39, 0xf0f0f0f, v39
	v_and_b32_e32 v76, 0xf0f0f0f, v83
	v_and_b32_e32 v77, 0xf0f0f0f, v71
	v_mfma_i32_16x16x64_i8 v[36:39], v[36:39], v[4:7], 0
	v_add_u32_dpp v70, v70, v70 quad_perm:[1,0,3,2] row_mask:0xf bank_mask:0xf bound_ctrl:1
	v_cndmask_b32_e64 v98, v78, v70, s[14:15]
	ds_read2_b32 v[70:71], v130 offset0:96 offset1:104
	v_mfma_i32_16x16x64_i8 v[36:39], v[74:77], v[0:3], v[36:39]
	s_waitcnt vmcnt(6)
	v_and_b32_e32 v74, 0xf0f0f0f, v60
	v_lshrrev_b32_e32 v60, 4, v60
	v_and_b32_e32 v75, 0xf0f0f0f, v60
	v_lshrrev_b32_e32 v60, 4, v61
	v_and_b32_e32 v76, 0xf0f0f0f, v61
	v_and_b32_e32 v77, 0xf0f0f0f, v60
	v_and_b32_e32 v60, 0xf0f0f0f, v62
	v_lshrrev_b32_e32 v61, 4, v62
	v_and_b32_e32 v62, 0xf0f0f0f, v63
	v_lshrrev_b32_e32 v63, 4, v63
	v_and_b32_e32 v61, 0xf0f0f0f, v61
	v_and_b32_e32 v63, 0xf0f0f0f, v63
	v_mfma_i32_16x16x64_i8 v[36:39], v[74:77], v[12:15], v[36:39]
	s_waitcnt lgkmcnt(0)
	v_ashrrev_i32_e32 v75, 31, v70
	v_mov_b32_e32 v74, v70
	v_lshlrev_b64 v[74:75], 9, v[74:75]
	v_mfma_i32_16x16x64_i8 v[36:39], v[60:63], v[8:11], v[36:39]
	s_waitcnt vmcnt(5)
	v_and_b32_e32 v60, 0xf0f0f0f, v56
	v_lshrrev_b32_e32 v56, 4, v56
	v_and_b32_e32 v61, 0xf0f0f0f, v56
	v_lshrrev_b32_e32 v56, 4, v57
	v_and_b32_e32 v62, 0xf0f0f0f, v57
	v_and_b32_e32 v63, 0xf0f0f0f, v56
	v_lshl_add_u64 v[82:83], v[106:107], 0, v[74:75]
	v_and_b32_e32 v56, 0xf0f0f0f, v58
	v_mfma_i32_16x16x64_i8 v[36:39], v[60:63], v[20:23], v[36:39]
	global_load_dwordx4 v[60:63], v[82:83], off
	global_load_dwordx4 v[74:77], v[82:83], off offset:128
	global_load_dwordx4 v[78:81], v[82:83], off offset:256
	s_nop 0
	global_load_dwordx4 v[82:85], v[82:83], off offset:384
	v_lshrrev_b32_e32 v57, 4, v58
	v_and_b32_e32 v58, 0xf0f0f0f, v59
	v_lshrrev_b32_e32 v59, 4, v59
	v_and_b32_e32 v57, 0xf0f0f0f, v57
	v_and_b32_e32 v59, 0xf0f0f0f, v59
	v_ashrrev_i32_e32 v87, 31, v71
	v_mov_b32_e32 v86, v71
	v_mfma_i32_16x16x64_i8 v[36:39], v[56:59], v[16:19], v[36:39]
	s_waitcnt vmcnt(8)
	v_and_b32_e32 v56, 0xf0f0f0f, v44
	v_lshrrev_b32_e32 v44, 4, v44
	v_and_b32_e32 v57, 0xf0f0f0f, v44
	v_lshrrev_b32_e32 v44, 4, v45
	v_and_b32_e32 v58, 0xf0f0f0f, v45
	v_and_b32_e32 v59, 0xf0f0f0f, v44
	v_and_b32_e32 v44, 0xf0f0f0f, v46
	v_lshrrev_b32_e32 v45, 4, v46
	v_and_b32_e32 v46, 0xf0f0f0f, v47
	v_lshrrev_b32_e32 v47, 4, v47
	v_and_b32_e32 v45, 0xf0f0f0f, v45
	v_and_b32_e32 v47, 0xf0f0f0f, v47
	v_mfma_i32_16x16x64_i8 v[36:39], v[56:59], v[28:31], v[36:39]
	v_lshlrev_b64 v[70:71], 9, v[86:87]
	v_lshl_add_u64 v[70:71], v[106:107], 0, v[70:71]
	v_mov_b32_dpp v89, v88 quad_perm:[1,0,3,2] row_mask:0xf bank_mask:0xf bound_ctrl:1
	v_mfma_i32_16x16x64_i8 v[56:59], v[44:47], v[24:27], v[36:39]
	s_waitcnt vmcnt(7)
	v_and_b32_e32 v44, 0xf0f0f0f, v94
	v_lshrrev_b32_e32 v45, 4, v94
	v_and_b32_e32 v46, 0xf0f0f0f, v95
	v_and_b32_e32 v36, 0xf0f0f0f, v92
	v_lshrrev_b32_e32 v37, 4, v92
	v_and_b32_e32 v38, 0xf0f0f0f, v93
	v_lshrrev_b32_e32 v39, 4, v93
	v_lshrrev_b32_e32 v47, 4, v95
	global_load_dwordx4 v[90:93], v[70:71], off
	global_load_dwordx4 v[94:97], v[70:71], off offset:128
	v_and_b32_e32 v37, 0xf0f0f0f, v37
	v_and_b32_e32 v39, 0xf0f0f0f, v39
	v_and_b32_e32 v45, 0xf0f0f0f, v45
	v_and_b32_e32 v47, 0xf0f0f0f, v47
	v_mfma_i32_16x16x64_i8 v[36:39], v[36:39], v[4:7], 0
	ds_read2_b32 v[86:87], v130 offset0:112 offset1:120
	global_load_dwordx4 v[154:157], v[70:71], off offset:256
	global_load_dwordx4 v[158:161], v[70:71], off offset:384
	v_mov_b32_dpp v73, v72 quad_perm:[1,0,3,2] row_mask:0xf bank_mask:0xf bound_ctrl:1
	v_mfma_i32_16x16x64_i8 v[36:39], v[44:47], v[0:3], v[36:39]
	s_waitcnt vmcnt(10)
	v_lshrrev_b32_e32 v45, 4, v64
	v_lshrrev_b32_e32 v47, 4, v65
	v_and_b32_e32 v44, 0xf0f0f0f, v64
	v_and_b32_e32 v45, 0xf0f0f0f, v45
	v_and_b32_e32 v46, 0xf0f0f0f, v65
	v_and_b32_e32 v47, 0xf0f0f0f, v47
	v_and_b32_e32 v64, 0xf0f0f0f, v66
	v_lshrrev_b32_e32 v65, 4, v66
	v_and_b32_e32 v66, 0xf0f0f0f, v67
	v_lshrrev_b32_e32 v67, 4, v67
	v_and_b32_e32 v65, 0xf0f0f0f, v65
	v_and_b32_e32 v67, 0xf0f0f0f, v67
	v_mfma_i32_16x16x64_i8 v[36:39], v[44:47], v[12:15], v[36:39]
	s_waitcnt vmcnt(9)
	v_lshrrev_b32_e32 v45, 4, v52
	v_lshrrev_b32_e32 v47, 4, v53
	v_and_b32_e32 v44, 0xf0f0f0f, v52
	v_and_b32_e32 v45, 0xf0f0f0f, v45
	v_and_b32_e32 v46, 0xf0f0f0f, v53
	v_and_b32_e32 v47, 0xf0f0f0f, v47
	v_mfma_i32_16x16x64_i8 v[36:39], v[64:67], v[8:11], v[36:39]
	v_and_b32_e32 v52, 0xf0f0f0f, v54
	v_lshrrev_b32_e32 v53, 4, v54
	v_and_b32_e32 v54, 0xf0f0f0f, v55
	v_lshrrev_b32_e32 v55, 4, v55
	v_and_b32_e32 v53, 0xf0f0f0f, v53
	v_and_b32_e32 v55, 0xf0f0f0f, v55
	v_mfma_i32_16x16x64_i8 v[36:39], v[44:47], v[20:23], v[36:39]
	s_waitcnt vmcnt(8)
	v_and_b32_e32 v44, 0xf0f0f0f, v40
	v_lshrrev_b32_e32 v40, 4, v40
	v_and_b32_e32 v45, 0xf0f0f0f, v40
	v_lshrrev_b32_e32 v40, 4, v41
	v_and_b32_e32 v46, 0xf0f0f0f, v41
	v_and_b32_e32 v47, 0xf0f0f0f, v40
	v_mfma_i32_16x16x64_i8 v[36:39], v[52:55], v[16:19], v[36:39]
	v_and_b32_e32 v40, 0xf0f0f0f, v42
	v_lshrrev_b32_e32 v41, 4, v42
	v_and_b32_e32 v42, 0xf0f0f0f, v43
	v_lshrrev_b32_e32 v43, 4, v43
	v_and_b32_e32 v41, 0xf0f0f0f, v41
	v_and_b32_e32 v43, 0xf0f0f0f, v43
	v_mfma_i32_16x16x64_i8 v[36:39], v[44:47], v[28:31], v[36:39]
	s_waitcnt lgkmcnt(0)
	v_ashrrev_i32_e32 v65, 31, v86
	v_mov_b32_e32 v64, v86
	v_lshlrev_b64 v[44:45], 9, v[64:65]
	v_lshl_add_u64 v[44:45], v[106:107], 0, v[44:45]
	v_mfma_i32_16x16x64_i8 v[162:165], v[40:43], v[24:27], v[36:39]
	s_waitcnt vmcnt(7)
	v_and_b32_e32 v40, 0xf0f0f0f, v62
	v_lshrrev_b32_e32 v41, 4, v62
	v_and_b32_e32 v42, 0xf0f0f0f, v63
	v_and_b32_e32 v36, 0xf0f0f0f, v60
	v_lshrrev_b32_e32 v37, 4, v60
	v_and_b32_e32 v38, 0xf0f0f0f, v61
	v_lshrrev_b32_e32 v39, 4, v61
	v_lshrrev_b32_e32 v43, 4, v63
	global_load_dwordx4 v[166:169], v[44:45], off
	global_load_dwordx4 v[170:173], v[44:45], off offset:128
	global_load_dwordx4 v[174:177], v[44:45], off offset:256
	global_load_dwordx4 v[60:63], v[44:45], off offset:384
	v_and_b32_e32 v37, 0xf0f0f0f, v37
	v_and_b32_e32 v39, 0xf0f0f0f, v39
	v_and_b32_e32 v41, 0xf0f0f0f, v41
	v_and_b32_e32 v43, 0xf0f0f0f, v43
	v_mfma_i32_16x16x64_i8 v[36:39], v[36:39], v[4:7], 0
	s_waitcnt vmcnt(10)
	v_lshrrev_b32_e32 v45, 4, v76
	v_lshrrev_b32_e32 v47, 4, v77
	v_and_b32_e32 v44, 0xf0f0f0f, v76
	v_mfma_i32_16x16x64_i8 v[36:39], v[40:43], v[0:3], v[36:39]
	v_lshrrev_b32_e32 v41, 4, v74
	v_lshrrev_b32_e32 v43, 4, v75
	v_and_b32_e32 v40, 0xf0f0f0f, v74
	v_and_b32_e32 v41, 0xf0f0f0f, v41
	v_and_b32_e32 v42, 0xf0f0f0f, v75
	v_and_b32_e32 v43, 0xf0f0f0f, v43
	v_and_b32_e32 v45, 0xf0f0f0f, v45
	v_and_b32_e32 v46, 0xf0f0f0f, v77
	v_and_b32_e32 v47, 0xf0f0f0f, v47
	v_mfma_i32_16x16x64_i8 v[36:39], v[40:43], v[12:15], v[36:39]
	v_ashrrev_i32_e32 v41, 31, v87
	v_mov_b32_e32 v40, v87
	v_lshlrev_b64 v[52:53], 9, v[40:41]
	s_waitcnt vmcnt(9)
	v_lshrrev_b32_e32 v41, 4, v78
	v_lshrrev_b32_e32 v43, 4, v79
	v_and_b32_e32 v40, 0xf0f0f0f, v78
	v_and_b32_e32 v41, 0xf0f0f0f, v41
	v_and_b32_e32 v42, 0xf0f0f0f, v79
	v_and_b32_e32 v43, 0xf0f0f0f, v43
	v_mfma_i32_16x16x64_i8 v[36:39], v[44:47], v[8:11], v[36:39]
	v_lshrrev_b32_e32 v45, 4, v80
	v_lshrrev_b32_e32 v47, 4, v81
	v_and_b32_e32 v44, 0xf0f0f0f, v80
	v_and_b32_e32 v45, 0xf0f0f0f, v45
	v_and_b32_e32 v46, 0xf0f0f0f, v81
	v_and_b32_e32 v47, 0xf0f0f0f, v47
	v_mfma_i32_16x16x64_i8 v[36:39], v[40:43], v[20:23], v[36:39]
	v_lshl_add_u64 v[70:71], v[106:107], 0, v[52:53]
	global_load_dwordx4 v[52:55], v[70:71], off
	global_load_dwordx4 v[40:43], v[70:71], off offset:128
	s_waitcnt vmcnt(10)
	v_lshrrev_b32_e32 v65, 4, v84
	v_mfma_i32_16x16x64_i8 v[36:39], v[44:47], v[16:19], v[36:39]
	v_lshrrev_b32_e32 v45, 4, v82
	v_lshrrev_b32_e32 v47, 4, v83
	v_and_b32_e32 v44, 0xf0f0f0f, v82
	v_and_b32_e32 v45, 0xf0f0f0f, v45
	v_and_b32_e32 v46, 0xf0f0f0f, v83
	v_and_b32_e32 v47, 0xf0f0f0f, v47
	v_lshrrev_b32_e32 v67, 4, v85
	v_and_b32_e32 v64, 0xf0f0f0f, v84
	v_and_b32_e32 v65, 0xf0f0f0f, v65
	v_and_b32_e32 v66, 0xf0f0f0f, v85
	v_and_b32_e32 v67, 0xf0f0f0f, v67
	v_mfma_i32_16x16x64_i8 v[74:77], v[44:47], v[28:31], v[36:39]
	global_load_dwordx4 v[44:47], v[70:71], off offset:256
	s_nop 1
	global_load_dwordx4 v[36:39], v[70:71], off offset:384
	v_cndmask_b32_e32 v70, v33, v32, vcc
	s_waitcnt vmcnt(11)
	v_lshrrev_b32_e32 v32, 4, v90
	v_mfma_i32_16x16x64_i8 v[74:77], v[64:67], v[24:27], v[74:77]
	v_and_b32_e32 v65, 0xf0f0f0f, v32
	v_lshrrev_b32_e32 v32, 4, v91
	v_and_b32_e32 v64, 0xf0f0f0f, v90
	v_and_b32_e32 v66, 0xf0f0f0f, v91
	v_and_b32_e32 v67, 0xf0f0f0f, v32
	v_lshrrev_b32_e32 v32, 4, v92
	v_and_b32_e32 v79, 0xf0f0f0f, v32
	v_lshrrev_b32_e32 v32, 4, v93
	v_and_b32_e32 v78, 0xf0f0f0f, v92
	v_and_b32_e32 v80, 0xf0f0f0f, v93
	v_and_b32_e32 v81, 0xf0f0f0f, v32
	v_mfma_i32_16x16x64_i8 v[82:85], v[64:67], v[4:7], 0
	s_waitcnt vmcnt(10)
	v_lshrrev_b32_e32 v67, 4, v94
	v_cndmask_b32_e32 v64, v35, v34, vcc
	v_cndmask_b32_e32 v86, v57, v56, vcc
	v_mfma_i32_16x16x64_i8 v[32:35], v[78:81], v[0:3], v[82:85]
	v_and_b32_e32 v79, 0xf0f0f0f, v67
	v_lshrrev_b32_e32 v67, 4, v95
	v_and_b32_e32 v78, 0xf0f0f0f, v94
	v_and_b32_e32 v80, 0xf0f0f0f, v95
	v_and_b32_e32 v81, 0xf0f0f0f, v67
	v_lshrrev_b32_e32 v67, 4, v96
	v_and_b32_e32 v83, 0xf0f0f0f, v67
	v_lshrrev_b32_e32 v67, 4, v97
	v_and_b32_e32 v82, 0xf0f0f0f, v96
	v_and_b32_e32 v84, 0xf0f0f0f, v97
	v_and_b32_e32 v85, 0xf0f0f0f, v67
	v_mfma_i32_16x16x64_i8 v[32:35], v[78:81], v[12:15], v[32:35]
	v_cndmask_b32_e32 v67, v49, v48, vcc
	s_waitcnt vmcnt(9)
	v_lshrrev_b32_e32 v49, 4, v154
	v_and_b32_e32 v79, 0xf0f0f0f, v49
	v_lshrrev_b32_e32 v49, 4, v155
	v_and_b32_e32 v78, 0xf0f0f0f, v154
	v_and_b32_e32 v80, 0xf0f0f0f, v155
	v_and_b32_e32 v81, 0xf0f0f0f, v49
	v_mfma_i32_16x16x64_i8 v[32:35], v[82:85], v[8:11], v[32:35]
	v_lshrrev_b32_e32 v49, 4, v156
	v_and_b32_e32 v83, 0xf0f0f0f, v49
	v_lshrrev_b32_e32 v49, 4, v157
	v_and_b32_e32 v82, 0xf0f0f0f, v156
	v_and_b32_e32 v84, 0xf0f0f0f, v157
	v_and_b32_e32 v85, 0xf0f0f0f, v49
	v_mfma_i32_16x16x64_i8 v[32:35], v[78:81], v[20:23], v[32:35]
	v_cndmask_b32_e32 v48, v51, v50, vcc
	s_waitcnt vmcnt(8)
	v_lshrrev_b32_e32 v51, 4, v158
	v_and_b32_e32 v57, 0xf0f0f0f, v51
	v_lshrrev_b32_e32 v51, 4, v159
	v_cndmask_b32_e32 v50, v59, v58, vcc
	v_and_b32_e32 v56, 0xf0f0f0f, v158
	v_and_b32_e32 v58, 0xf0f0f0f, v159
	v_and_b32_e32 v59, 0xf0f0f0f, v51
	v_mfma_i32_16x16x64_i8 v[32:35], v[82:85], v[16:19], v[32:35]
	v_lshrrev_b32_e32 v51, 4, v160
	v_and_b32_e32 v79, 0xf0f0f0f, v51
	v_lshrrev_b32_e32 v51, 4, v161
	v_and_b32_e32 v78, 0xf0f0f0f, v160
	v_and_b32_e32 v80, 0xf0f0f0f, v161
	v_and_b32_e32 v81, 0xf0f0f0f, v51
	v_mfma_i32_16x16x64_i8 v[32:35], v[56:59], v[28:31], v[32:35]
	s_waitcnt vmcnt(7)
	v_lshrrev_b32_e32 v56, 4, v168
	v_and_b32_e32 v83, 0xf0f0f0f, v56
	v_lshrrev_b32_e32 v56, 4, v169
	v_mfma_i32_16x16x64_i8 v[78:81], v[78:81], v[24:27], v[32:35]
	v_and_b32_e32 v82, 0xf0f0f0f, v168
	v_and_b32_e32 v84, 0xf0f0f0f, v169
	v_and_b32_e32 v85, 0xf0f0f0f, v56
	v_lshrrev_b32_e32 v33, 4, v166
	v_lshrrev_b32_e32 v35, 4, v167
	v_and_b32_e32 v32, 0xf0f0f0f, v166
	v_and_b32_e32 v33, 0xf0f0f0f, v33
	v_and_b32_e32 v34, 0xf0f0f0f, v167
	v_and_b32_e32 v35, 0xf0f0f0f, v35
	v_cndmask_b32_e32 v59, v163, v162, vcc
	s_waitcnt vmcnt(6)
	v_and_b32_e32 v90, 0xf0f0f0f, v172
	v_mfma_i32_16x16x64_i8 v[32:35], v[32:35], v[4:7], 0
	v_add_u32_dpp v87, v59, v59 quad_perm:[1,0,3,2] row_mask:0xf bank_mask:0xf bound_ctrl:1
	v_lshrrev_b32_e32 v59, 4, v170
	v_and_b32_e32 v92, 0xf0f0f0f, v173
	v_mfma_i32_16x16x64_i8 v[32:35], v[82:85], v[0:3], v[32:35]
	v_and_b32_e32 v83, 0xf0f0f0f, v59
	v_lshrrev_b32_e32 v59, 4, v171
	v_and_b32_e32 v82, 0xf0f0f0f, v170
	v_and_b32_e32 v84, 0xf0f0f0f, v171
	v_and_b32_e32 v85, 0xf0f0f0f, v59
	v_lshrrev_b32_e32 v59, 4, v172
	v_and_b32_e32 v91, 0xf0f0f0f, v59
	v_lshrrev_b32_e32 v59, 4, v173
	v_and_b32_e32 v93, 0xf0f0f0f, v59
	v_mov_b32_dpp v71, v67 quad_perm:[1,0,3,2] row_mask:0xf bank_mask:0xf bound_ctrl:1
	v_mfma_i32_16x16x64_i8 v[32:35], v[82:85], v[12:15], v[32:35]
	v_add_u32_e32 v59, v67, v71
	s_waitcnt vmcnt(5)
	v_lshrrev_b32_e32 v67, 4, v174
	v_and_b32_e32 v83, 0xf0f0f0f, v67
	v_lshrrev_b32_e32 v67, 4, v175
	v_and_b32_e32 v82, 0xf0f0f0f, v174
	v_and_b32_e32 v84, 0xf0f0f0f, v175
	v_and_b32_e32 v85, 0xf0f0f0f, v67
	v_mfma_i32_16x16x64_i8 v[32:35], v[90:93], v[8:11], v[32:35]
	v_lshrrev_b32_e32 v67, 4, v176
	v_mov_b32_dpp v66, v70 quad_perm:[1,0,3,2] row_mask:0xf bank_mask:0xf bound_ctrl:1
	v_and_b32_e32 v91, 0xf0f0f0f, v67
	v_lshrrev_b32_e32 v67, 4, v177
	v_add_u32_e32 v66, v70, v66
	v_and_b32_e32 v90, 0xf0f0f0f, v176
	v_and_b32_e32 v92, 0xf0f0f0f, v177
	v_and_b32_e32 v93, 0xf0f0f0f, v67
	v_mov_b32_dpp v58, v86 quad_perm:[1,0,3,2] row_mask:0xf bank_mask:0xf bound_ctrl:1
	v_mfma_i32_16x16x64_i8 v[32:35], v[82:85], v[20:23], v[32:35]
	v_cndmask_b32_e64 v66, v98, v66, s[22:23]
	v_add_u32_e32 v58, v86, v58
	v_cndmask_b32_e64 v59, v66, v59, s[20:21]
	v_cndmask_b32_e64 v66, v59, v58, s[18:19]
	s_waitcnt vmcnt(4)
	v_and_b32_e32 v58, 0xf0f0f0f, v60
	v_lshrrev_b32_e32 v59, 4, v60
	v_and_b32_e32 v60, 0xf0f0f0f, v61
	v_lshrrev_b32_e32 v61, 4, v61
	v_and_b32_e32 v59, 0xf0f0f0f, v59
	v_and_b32_e32 v61, 0xf0f0f0f, v61
	v_mfma_i32_16x16x64_i8 v[32:35], v[90:93], v[16:19], v[32:35]
	v_and_b32_e32 v82, 0xf0f0f0f, v62
	v_lshrrev_b32_e32 v62, 4, v62
	v_and_b32_e32 v83, 0xf0f0f0f, v62
	v_lshrrev_b32_e32 v62, 4, v63
	v_and_b32_e32 v84, 0xf0f0f0f, v63
	v_and_b32_e32 v85, 0xf0f0f0f, v62
	v_mfma_i32_16x16x64_i8 v[32:35], v[58:61], v[28:31], v[32:35]
	v_cndmask_b32_e64 v59, v66, v87, s[16:17]
	ds_read_b64 v[66:67], v131
	v_cndmask_b32_e32 v70, v75, v74, vcc
	v_mfma_i32_16x16x64_i8 v[60:63], v[82:85], v[24:27], v[32:35]
	s_waitcnt vmcnt(3)
	v_and_b32_e32 v74, 0xf0f0f0f, v52
	v_cndmask_b32_e32 v58, v77, v76, vcc
	v_and_b32_e32 v76, 0xf0f0f0f, v53
	v_lshrrev_b32_e32 v32, 4, v52
	v_and_b32_e32 v75, 0xf0f0f0f, v32
	s_waitcnt lgkmcnt(0)
	v_ashrrev_i32_e32 v33, 31, v66
	v_mov_b32_e32 v32, v66
	v_lshl_add_u64 v[34:35], v[32:33], 2, s[38:39]
	global_load_dword v71, v[34:35], off
	v_ashrrev_i32_e32 v35, 31, v67
	v_mov_b32_e32 v34, v67
	v_lshl_add_u64 v[66:67], v[34:35], 2, s[38:39]
	global_load_dword v52, v[66:67], off
	v_lshrrev_b32_e32 v53, 4, v53
	v_and_b32_e32 v77, 0xf0f0f0f, v53
	v_lshrrev_b32_e32 v53, 4, v54
	v_and_b32_e32 v83, 0xf0f0f0f, v53
	v_lshrrev_b32_e32 v53, 4, v55
	v_and_b32_e32 v82, 0xf0f0f0f, v54
	v_and_b32_e32 v84, 0xf0f0f0f, v55
	v_and_b32_e32 v85, 0xf0f0f0f, v53
	v_mfma_i32_16x16x64_i8 v[74:77], v[74:77], v[4:7], 0
	v_add_u32_dpp v5, v70, v70 quad_perm:[1,0,3,2] row_mask:0xf bank_mask:0xf bound_ctrl:1
	v_cndmask_b32_e64 v53, v59, v5, s[24:25]
	s_waitcnt vmcnt(4)
	v_lshrrev_b32_e32 v5, 4, v40
	v_mfma_i32_16x16x64_i8 v[0:3], v[82:85], v[0:3], v[74:77]
	v_cndmask_b32_e32 v56, v165, v164, vcc
	v_mov_b32_dpp v69, v68 quad_perm:[1,0,3,2] row_mask:0xf bank_mask:0xf bound_ctrl:1
	v_mov_b32_dpp v65, v64 quad_perm:[1,0,3,2] row_mask:0xf bank_mask:0xf bound_ctrl:1
	v_and_b32_e32 v75, 0xf0f0f0f, v5
	v_lshrrev_b32_e32 v5, 4, v41
	v_and_b32_e32 v74, 0xf0f0f0f, v40
	v_and_b32_e32 v76, 0xf0f0f0f, v41
	v_and_b32_e32 v77, 0xf0f0f0f, v5
	v_lshrrev_b32_e32 v5, 4, v42
	v_and_b32_e32 v41, 0xf0f0f0f, v5
	v_lshrrev_b32_e32 v5, 4, v43
	v_and_b32_e32 v40, 0xf0f0f0f, v42
	v_and_b32_e32 v42, 0xf0f0f0f, v43
	v_and_b32_e32 v43, 0xf0f0f0f, v5
	v_mfma_i32_16x16x64_i8 v[12:15], v[74:77], v[12:15], v[0:3]
	v_mov_b32_dpp v49, v48 quad_perm:[1,0,3,2] row_mask:0xf bank_mask:0xf bound_ctrl:1
	v_mov_b32_dpp v51, v50 quad_perm:[1,0,3,2] row_mask:0xf bank_mask:0xf bound_ctrl:1
	v_mov_b32_dpp v57, v56 quad_perm:[1,0,3,2] row_mask:0xf bank_mask:0xf bound_ctrl:1
	s_waitcnt vmcnt(3)
	v_lshrrev_b32_e32 v1, 4, v44
	v_mfma_i32_16x16x64_i8 v[6:9], v[40:43], v[8:11], v[12:15]
	v_and_b32_e32 v11, 0xf0f0f0f, v1
	v_lshrrev_b32_e32 v1, 4, v45
	v_and_b32_e32 v10, 0xf0f0f0f, v44
	v_and_b32_e32 v12, 0xf0f0f0f, v45
	v_and_b32_e32 v13, 0xf0f0f0f, v1
	v_lshrrev_b32_e32 v1, 4, v46
	v_and_b32_e32 v41, 0xf0f0f0f, v1
	v_lshrrev_b32_e32 v1, 4, v47
	v_and_b32_e32 v40, 0xf0f0f0f, v46
	v_and_b32_e32 v42, 0xf0f0f0f, v47
	v_and_b32_e32 v43, 0xf0f0f0f, v1
	v_mfma_i32_16x16x64_i8 v[6:9], v[10:13], v[20:23], v[6:9]
	s_waitcnt vmcnt(2)
	v_lshrrev_b32_e32 v2, 4, v36
	v_and_b32_e32 v11, 0xf0f0f0f, v2
	v_lshrrev_b32_e32 v2, 4, v37
	v_and_b32_e32 v10, 0xf0f0f0f, v36
	v_and_b32_e32 v12, 0xf0f0f0f, v37
	v_and_b32_e32 v13, 0xf0f0f0f, v2
	v_mfma_i32_16x16x64_i8 v[6:9], v[40:43], v[16:19], v[6:9]
	v_lshrrev_b32_e32 v2, 4, v38
	v_and_b32_e32 v15, 0xf0f0f0f, v2
	v_lshrrev_b32_e32 v2, 4, v39
	v_and_b32_e32 v14, 0xf0f0f0f, v38
	v_and_b32_e32 v16, 0xf0f0f0f, v39
	v_and_b32_e32 v17, 0xf0f0f0f, v2
	v_mfma_i32_16x16x64_i8 v[8:11], v[10:13], v[28:31], v[6:9]
	v_cndmask_b32_e32 v0, v79, v78, vcc
	v_cndmask_b32_e32 v1, v61, v60, vcc
	v_cndmask_b32_e32 v3, v81, v80, vcc
	v_mfma_i32_16x16x64_i8 v[8:11], v[14:17], v[24:27], v[8:11]
	v_add_u32_dpp v0, v0, v0 quad_perm:[1,0,3,2] row_mask:0xf bank_mask:0xf bound_ctrl:1
	v_cndmask_b32_e64 v0, v53, v0, s[26:27]
	v_add_u32_dpp v1, v1, v1 quad_perm:[1,0,3,2] row_mask:0xf bank_mask:0xf bound_ctrl:1
	v_cndmask_b32_e64 v0, v0, v1, s[28:29]
	v_cndmask_b32_e32 v6, v63, v62, vcc
	s_nop 2
	v_cndmask_b32_e32 v1, v9, v8, vcc
	v_cndmask_b32_e32 v7, v11, v10, vcc
	v_mov_b32_dpp v4, v58 quad_perm:[1,0,3,2] row_mask:0xf bank_mask:0xf bound_ctrl:1
	v_add_u32_dpp v1, v1, v1 quad_perm:[1,0,3,2] row_mask:0xf bank_mask:0xf bound_ctrl:1
	v_cndmask_b32_e64 v0, v0, v1, s[30:31]
	v_cvt_f32_i32_e32 v0, v0
	v_mov_b32_dpp v5, v3 quad_perm:[1,0,3,2] row_mask:0xf bank_mask:0xf bound_ctrl:1
	v_mov_b32_dpp v8, v6 quad_perm:[1,0,3,2] row_mask:0xf bank_mask:0xf bound_ctrl:1
	v_mov_b32_dpp v9, v7 quad_perm:[1,0,3,2] row_mask:0xf bank_mask:0xf bound_ctrl:1
	v_fmac_f32_e32 v0, 0xc0f00000, v127
	s_waitcnt vmcnt(1)
	v_mul_f32_e32 v0, v71, v0
	v_mul_f32_e32 v0, v126, v0
	v_mul_f32_e32 v1, 0x3f3504f3, v0
	v_cmp_nlt_f32_e64 s[34:35], |v1|, 1.0
	s_and_saveexec_b64 s[36:37], s[34:35]
	s_xor_b64 s[36:37], exec, s[36:37]
	s_cbranch_execz .LBB0_982
	v_fma_f32 v2, |v1|, s45, v143
	v_fma_f32 v2, |v1|, v2, s46
	v_fma_f32 v2, |v1|, v2, s47
	v_fma_f32 v2, |v1|, v2, s48
	v_fma_f32 v2, |v1|, v2, s49
	v_fma_f32 v2, |v1|, v2, s50
	v_fma_f32 v2, |v1|, v2, |v1|
	v_mul_f32_e32 v10, 0xbfb8aa3b, v2
	v_fma_f32 v11, v2, s51, -v10
	v_rndne_f32_e32 v12, v10
	v_fmac_f32_e32 v11, 0xb2a5705f, v2
	v_sub_f32_e32 v10, v10, v12
	v_add_f32_e32 v10, v10, v11
	v_cvt_i32_f32_e32 v11, v12
	v_exp_f32_e32 v10, v10
	v_cmp_nlt_f32_e64 s[34:35], s52, v2
	v_ldexp_f32 v10, v10, v11
	s_nop 0
	v_cndmask_b32_e64 v10, 0, v10, s[34:35]
	v_cmp_ngt_f32_e64 s[34:35], s53, v2
	s_nop 1
	v_cndmask_b32_e64 v2, v144, v10, s[34:35]
	v_sub_f32_e32 v2, 1.0, v2

.LBB0_986:
	s_andn2_saveexec_b64 s[34:35], s[36:37]
	v_mul_f32_e32 v5, v4, v4
	v_fmamk_f32 v6, v5, 0xba1345e1, v141
	v_fmaak_f32 v6, v5, v6, 0xbcdac9b8
	v_fmaak_f32 v6, v5, v6, 0x3de703be
	v_fmaak_f32 v6, v5, v6, 0xbec09330
	v_fmaak_f32 v5, v5, v6, 0x3e0375d0
	v_fma_f32 v5, |v4|, v5, |v4|
	s_or_b64 exec, exec, s[34:35]
	v_lshlrev_b64 v[6:7], 7, v[104:105]
	v_lshl_add_u64 v[6:7], v[6:7], 2, v[120:121]
	v_lshl_add_u64 v[8:9], v[32:33], 2, s[40:41]
	v_lshl_add_u64 v[10:11], v[34:35], 2, s[40:41]
	global_load_dwordx2 v[6:7], v[6:7], off
	s_nop 0
	global_load_dword v8, v[8:9], off
	s_nop 0
	global_load_dword v9, v[10:11], off
	v_bfi_b32 v1, s54, v2, v1
	v_mul_f32_e32 v2, 0.5, v3
	v_bfi_b32 v3, s54, v5, v4
	v_mul_f32_e32 v0, 0.5, v0
	v_add_f32_e32 v1, 1.0, v1
	v_add_f32_e32 v3, 1.0, v3
	v_mul_f32_e32 v0, v0, v1
	v_mul_f32_e32 v1, v2, v3
	v_mov_b32_e32 v90, 0
	s_mov_b32 s34, 0
	v_mov_b32_e32 v91, v90
	v_mov_b32_e32 v88, v90
	v_mov_b32_e32 v89, v90
	v_mov_b32_e32 v84, v90
	v_mov_b32_e32 v85, v90
	v_mov_b32_e32 v80, v90
	v_mov_b32_e32 v81, v90
	v_mov_b32_e32 v76, v90
	v_mov_b32_e32 v77, v90
	v_mov_b32_e32 v68, v90
	v_mov_b32_e32 v69, v90
	v_mov_b32_e32 v62, v90
	v_mov_b32_e32 v63, v90
	v_mov_b32_e32 v60, v90
	v_mov_b32_e32 v61, v90
	s_waitcnt vmcnt(2)
	v_pk_mul_f32 v[0:1], v[0:1], v[6:7]
	s_waitcnt vmcnt(0)
	v_pk_mul_f32 v[22:23], v[0:1], v[8:9]
	ds_write_b64 v131, v[22:23] offset:512
	v_lshl_add_u64 v[228:229], v[124:125], 2, v[118:119]
	global_load_dwordx4 v[212:215], v[228:229], off
	global_load_dwordx4 v[216:219], v[228:229], off offset:16
	global_load_dwordx4 v[220:223], v[228:229], off offset:32
	global_load_dwordx4 v[224:227], v[228:229], off offset:48
	v_add_u32_e32 v32, s33, v104
	v_min_u32_e32 v32, 0x7fff, v32
	v_mov_b32_e32 v33, 0
	v_lshlrev_b64 v[34:35], 9, v[32:33]
	v_lshlrev_b64 v[36:37], 10, v[32:33]
	v_lshlrev_b64 v[38:39], 2, v[32:33]
	v_lshl_add_u64 v[34:35], v[114:115], 0, v[34:35]
	v_lshl_add_u64 v[36:37], v[116:117], 0, v[36:37]
	v_lshl_add_u64 v[40:41], s[68:69], 0, v[38:39]
	v_lshl_add_u64 v[38:39], s[70:71], 0, v[38:39]
	global_load_dword v230, v[34:35], off
	global_load_dword v231, v[34:35], off offset:256
	global_load_dwordx4 v[232:235], v[36:37], off
	global_load_dword v236, v[40:41], off
	global_load_dword v237, v[38:39], off
	s_mov_b32 s34, 0x0f0f0f0f
	s_mov_b32 s35, 0xf0f0f0f0
	v_readfirstlane_b32 s36, v108
	v_readfirstlane_b32 s37, v109
	v_mul_f32_e32 v210, 0x3d800000, v22
	v_mul_f32_e32 v211, 0x3d800000, v23
	v_subrev_u32_e32 v98, s36, v108
	ds_write_b64 v131, v[210:211] offset:1536
	ds_read_b128 v[70:73], v128 offset:0
	ds_read_b128 v[92:95], v128 offset:16
	ds_read_b128 v[48:51], v128 offset:32
	ds_read_b128 v[52:55], v128 offset:48
	s_waitcnt lgkmcnt(2)
	v_lshl_add_u32 v70, v70, 9, v98
	v_lshl_add_u32 v71, v71, 9, v98
	v_lshl_add_u32 v72, v72, 9, v98
	v_lshl_add_u32 v73, v73, 9, v98
	v_lshl_add_u32 v92, v92, 9, v98
	v_lshl_add_u32 v93, v93, 9, v98
	v_lshl_add_u32 v94, v94, 9, v98
	v_lshl_add_u32 v95, v95, 9, v98
	global_load_dwordx2 v[146:147], v70, s[36:37]
	global_load_dwordx2 v[148:149], v71, s[36:37]
	global_load_dwordx2 v[150:151], v72, s[36:37]
	global_load_dwordx2 v[152:153], v73, s[36:37]
	global_load_dwordx2 v[154:155], v92, s[36:37]
	global_load_dwordx2 v[156:157], v93, s[36:37]
	global_load_dwordx2 v[158:159], v94, s[36:37]
	global_load_dwordx2 v[160:161], v95, s[36:37]
	ds_read_b128 v[70:73], v128 offset:64
	ds_read_b128 v[92:95], v128 offset:80
	s_waitcnt lgkmcnt(2)
	v_lshl_add_u32 v48, v48, 9, v98
	v_lshl_add_u32 v49, v49, 9, v98
	v_lshl_add_u32 v50, v50, 9, v98
	v_lshl_add_u32 v51, v51, 9, v98
	v_lshl_add_u32 v52, v52, 9, v98
	v_lshl_add_u32 v53, v53, 9, v98
	v_lshl_add_u32 v54, v54, 9, v98
	v_lshl_add_u32 v55, v55, 9, v98
	global_load_dwordx2 v[162:163], v48, s[36:37]
	global_load_dwordx2 v[164:165], v49, s[36:37]
	global_load_dwordx2 v[166:167], v50, s[36:37]
	global_load_dwordx2 v[168:169], v51, s[36:37]
	global_load_dwordx2 v[170:171], v52, s[36:37]
	global_load_dwordx2 v[172:173], v53, s[36:37]
	global_load_dwordx2 v[174:175], v54, s[36:37]
	global_load_dwordx2 v[176:177], v55, s[36:37]
	ds_read_b128 v[48:51], v128 offset:96
	ds_read_b128 v[52:55], v128 offset:112
	s_waitcnt lgkmcnt(2)
	v_lshl_add_u32 v70, v70, 9, v98
	v_lshl_add_u32 v71, v71, 9, v98
	v_lshl_add_u32 v72, v72, 9, v98
	v_lshl_add_u32 v73, v73, 9, v98
	v_lshl_add_u32 v92, v92, 9, v98
	v_lshl_add_u32 v93, v93, 9, v98
	v_lshl_add_u32 v94, v94, 9, v98
	v_lshl_add_u32 v95, v95, 9, v98
	global_load_dwordx2 v[178:179], v70, s[36:37]
	global_load_dwordx2 v[180:181], v71, s[36:37]
	global_load_dwordx2 v[182:183], v72, s[36:37]
	global_load_dwordx2 v[184:185], v73, s[36:37]
	global_load_dwordx2 v[186:187], v92, s[36:37]
	global_load_dwordx2 v[188:189], v93, s[36:37]
	global_load_dwordx2 v[190:191], v94, s[36:37]
	global_load_dwordx2 v[192:193], v95, s[36:37]
	ds_read_b128 v[70:73], v128 offset:128
	ds_read_b128 v[92:95], v128 offset:144
	s_waitcnt lgkmcnt(2)
	v_lshl_add_u32 v48, v48, 9, v98
	v_lshl_add_u32 v49, v49, 9, v98
	v_lshl_add_u32 v50, v50, 9, v98
	v_lshl_add_u32 v51, v51, 9, v98
	v_lshl_add_u32 v52, v52, 9, v98
	v_lshl_add_u32 v53, v53, 9, v98
	v_lshl_add_u32 v54, v54, 9, v98
	v_lshl_add_u32 v55, v55, 9, v98
	global_load_dwordx2 v[194:195], v48, s[36:37]
	global_load_dwordx2 v[196:197], v49, s[36:37]
	global_load_dwordx2 v[198:199], v50, s[36:37]
	global_load_dwordx2 v[200:201], v51, s[36:37]
	global_load_dwordx2 v[202:203], v52, s[36:37]
	global_load_dwordx2 v[204:205], v53, s[36:37]
	global_load_dwordx2 v[206:207], v54, s[36:37]
	global_load_dwordx2 v[208:209], v55, s[36:37]
	s_waitcnt lgkmcnt(0)
	v_lshl_add_u32 v70, v70, 9, v98
	v_lshl_add_u32 v71, v71, 9, v98
	v_lshl_add_u32 v72, v72, 9, v98
	v_lshl_add_u32 v73, v73, 9, v98
	v_lshl_add_u32 v92, v92, 9, v98
	v_lshl_add_u32 v93, v93, 9, v98
	v_lshl_add_u32 v94, v94, 9, v98
	v_lshl_add_u32 v95, v95, 9, v98
	global_load_dwordx2 v[0:1], v70, s[36:37]
	global_load_dwordx2 v[2:3], v71, s[36:37]
	global_load_dwordx2 v[4:5], v72, s[36:37]
	global_load_dwordx2 v[6:7], v73, s[36:37]
	global_load_dwordx2 v[8:9], v92, s[36:37]
	global_load_dwordx2 v[10:11], v93, s[36:37]
	global_load_dwordx2 v[12:13], v94, s[36:37]
	global_load_dwordx2 v[14:15], v95, s[36:37]
	v_add_f32_e32 v210, v22, v23
	ds_bpermute_b32 v211, v132, v210
	s_waitcnt lgkmcnt(0)
	v_add_f32_e32 v210, v210, v211
	ds_bpermute_b32 v211, v133, v210
	s_waitcnt lgkmcnt(0)
	v_add_f32_e32 v210, v210, v211
	ds_bpermute_b32 v211, v134, v210
	s_waitcnt lgkmcnt(0)
	v_add_f32_e32 v210, v210, v211
	ds_bpermute_b32 v211, v135, v210
	s_waitcnt lgkmcnt(0)
	v_add_f32_e32 v210, v210, v211
	ds_bpermute_b32 v211, v136, v210
	s_waitcnt lgkmcnt(0)
	v_add_f32_e32 v99, v210, v211
	ds_bpermute_b32 v105, v137, v99
	ds_read_b128 v[70:73], v128 offset:160
	ds_read_b128 v[92:95], v128 offset:176
	ds_read_b128 v[32:35], v128 offset:512
	ds_read_b128 v[36:39], v128 offset:528
	ds_read_b128 v[40:43], v128 offset:1536
	ds_read_b128 v[44:47], v128 offset:1552
	s_waitcnt lgkmcnt(0)
	v_lshl_add_u32 v70, v70, 9, v98
	v_lshl_add_u32 v71, v71, 9, v98
	v_lshl_add_u32 v72, v72, 9, v98
	v_lshl_add_u32 v73, v73, 9, v98
	v_lshl_add_u32 v92, v92, 9, v98
	v_lshl_add_u32 v93, v93, 9, v98
	v_lshl_add_u32 v94, v94, 9, v98
	v_lshl_add_u32 v95, v95, 9, v98
	global_load_dwordx2 v[16:17], v70, s[36:37]
	global_load_dwordx2 v[18:19], v71, s[36:37]
	global_load_dwordx2 v[20:21], v72, s[36:37]
	global_load_dwordx2 v[22:23], v73, s[36:37]
	global_load_dwordx2 v[24:25], v92, s[36:37]
	global_load_dwordx2 v[26:27], v93, s[36:37]
	global_load_dwordx2 v[28:29], v94, s[36:37]
	global_load_dwordx2 v[30:31], v95, s[36:37]
	ds_read_b128 v[70:73], v128 offset:192
	ds_read_b128 v[92:95], v128 offset:208
	ds_read_b128 v[48:51], v128 offset:544
	ds_read_b128 v[52:55], v128 offset:560
	ds_read_b128 v[56:59], v128 offset:1568
	ds_read_b128 v[64:67], v128 offset:1584
	s_waitcnt vmcnt(40)
	v_and_b32_e32 v74, s34, v146
	v_and_b32_e32 v75, s35, v146
	v_and_b32_e32 v78, s34, v147
	v_and_b32_e32 v79, s35, v147
	v_cvt_f32_ubyte0_e32 v96, v74
	v_cvt_f32_ubyte1_e32 v97, v74
	v_cvt_f32_ubyte2_e32 v100, v74
	v_cvt_f32_ubyte3_e32 v101, v74
	v_pk_fma_f32 v[90:91], v[32:33], v[96:97], v[90:91] op_sel_hi:[0,1,1]
	v_cvt_f32_ubyte0_e32 v102, v75
	v_cvt_f32_ubyte1_e32 v103, v75
	v_pk_fma_f32 v[88:89], v[32:33], v[100:101], v[88:89] op_sel_hi:[0,1,1]
	v_cvt_f32_ubyte2_e32 v126, v75
	v_cvt_f32_ubyte3_e32 v127, v75
	v_pk_fma_f32 v[84:85], v[40:41], v[102:103], v[84:85] op_sel_hi:[0,1,1]
	v_cvt_f32_ubyte0_e32 v96, v78
	v_cvt_f32_ubyte1_e32 v97, v78
	v_pk_fma_f32 v[80:81], v[40:41], v[126:127], v[80:81] op_sel_hi:[0,1,1]
	v_and_b32_e32 v82, s34, v148
	v_and_b32_e32 v83, s35, v148
	v_and_b32_e32 v86, s34, v149
	v_and_b32_e32 v87, s35, v149
	v_cvt_f32_ubyte2_e32 v100, v78
	v_cvt_f32_ubyte3_e32 v101, v78
	v_pk_fma_f32 v[76:77], v[32:33], v[96:97], v[76:77] op_sel_hi:[0,1,1]
	v_cvt_f32_ubyte0_e32 v102, v79
	v_cvt_f32_ubyte1_e32 v103, v79
	v_pk_fma_f32 v[68:69], v[32:33], v[100:101], v[68:69] op_sel_hi:[0,1,1]
	v_cvt_f32_ubyte2_e32 v126, v79
	v_cvt_f32_ubyte3_e32 v127, v79
	v_pk_fma_f32 v[62:63], v[40:41], v[102:103], v[62:63] op_sel_hi:[0,1,1]
	v_cvt_f32_ubyte0_e32 v96, v82
	v_cvt_f32_ubyte1_e32 v97, v82
	v_pk_fma_f32 v[60:61], v[40:41], v[126:127], v[60:61] op_sel_hi:[0,1,1]
	v_cvt_f32_ubyte2_e32 v100, v82
	v_cvt_f32_ubyte3_e32 v101, v82
	v_pk_fma_f32 v[90:91], v[32:33], v[96:97], v[90:91] op_sel:[1,0,0]
	v_cvt_f32_ubyte0_e32 v102, v83
	v_cvt_f32_ubyte1_e32 v103, v83
	v_pk_fma_f32 v[88:89], v[32:33], v[100:101], v[88:89] op_sel:[1,0,0]
	v_cvt_f32_ubyte2_e32 v126, v83
	v_cvt_f32_ubyte3_e32 v127, v83
	v_pk_fma_f32 v[84:85], v[40:41], v[102:103], v[84:85] op_sel:[1,0,0]
	v_cvt_f32_ubyte0_e32 v96, v86
	v_cvt_f32_ubyte1_e32 v97, v86
	v_pk_fma_f32 v[80:81], v[40:41], v[126:127], v[80:81] op_sel:[1,0,0]
	v_and_b32_e32 v74, s34, v150
	v_and_b32_e32 v75, s35, v150
	v_and_b32_e32 v78, s34, v151
	v_and_b32_e32 v79, s35, v151
	v_cvt_f32_ubyte2_e32 v100, v86
	v_cvt_f32_ubyte3_e32 v101, v86
	v_pk_fma_f32 v[76:77], v[32:33], v[96:97], v[76:77] op_sel:[1,0,0]
	v_cvt_f32_ubyte0_e32 v102, v87
	v_cvt_f32_ubyte1_e32 v103, v87
	v_pk_fma_f32 v[68:69], v[32:33], v[100:101], v[68:69] op_sel:[1,0,0]
	v_cvt_f32_ubyte2_e32 v126, v87
	v_cvt_f32_ubyte3_e32 v127, v87
	v_pk_fma_f32 v[62:63], v[40:41], v[102:103], v[62:63] op_sel:[1,0,0]
	v_cvt_f32_ubyte0_e32 v96, v74
	v_cvt_f32_ubyte1_e32 v97, v74
	v_pk_fma_f32 v[60:61], v[40:41], v[126:127], v[60:61] op_sel:[1,0,0]
	v_cvt_f32_ubyte2_e32 v100, v74
	v_cvt_f32_ubyte3_e32 v101, v74
	v_pk_fma_f32 v[90:91], v[34:35], v[96:97], v[90:91] op_sel_hi:[0,1,1]
	v_cvt_f32_ubyte0_e32 v102, v75
	v_cvt_f32_ubyte1_e32 v103, v75
	v_pk_fma_f32 v[88:89], v[34:35], v[100:101], v[88:89] op_sel_hi:[0,1,1]
	v_cvt_f32_ubyte2_e32 v126, v75
	v_cvt_f32_ubyte3_e32 v127, v75
	v_pk_fma_f32 v[84:85], v[42:43], v[102:103], v[84:85] op_sel_hi:[0,1,1]
	v_cvt_f32_ubyte0_e32 v96, v78
	v_cvt_f32_ubyte1_e32 v97, v78
	v_pk_fma_f32 v[80:81], v[42:43], v[126:127], v[80:81] op_sel_hi:[0,1,1]
	v_and_b32_e32 v82, s34, v152
	v_and_b32_e32 v83, s35, v152
	v_and_b32_e32 v86, s34, v153
	v_and_b32_e32 v87, s35, v153
	v_cvt_f32_ubyte2_e32 v100, v78
	v_cvt_f32_ubyte3_e32 v101, v78
	v_pk_fma_f32 v[76:77], v[34:35], v[96:97], v[76:77] op_sel_hi:[0,1,1]
	v_cvt_f32_ubyte0_e32 v102, v79
	v_cvt_f32_ubyte1_e32 v103, v79
	v_pk_fma_f32 v[68:69], v[34:35], v[100:101], v[68:69] op_sel_hi:[0,1,1]
	v_cvt_f32_ubyte2_e32 v126, v79
	v_cvt_f32_ubyte3_e32 v127, v79
	v_pk_fma_f32 v[62:63], v[42:43], v[102:103], v[62:63] op_sel_hi:[0,1,1]
	v_cvt_f32_ubyte0_e32 v96, v82
	v_cvt_f32_ubyte1_e32 v97, v82
	v_pk_fma_f32 v[60:61], v[42:43], v[126:127], v[60:61] op_sel_hi:[0,1,1]
	v_cvt_f32_ubyte2_e32 v100, v82
	v_cvt_f32_ubyte3_e32 v101, v82
	v_pk_fma_f32 v[90:91], v[34:35], v[96:97], v[90:91] op_sel:[1,0,0]
	v_cvt_f32_ubyte0_e32 v102, v83
	v_cvt_f32_ubyte1_e32 v103, v83
	v_pk_fma_f32 v[88:89], v[34:35], v[100:101], v[88:89] op_sel:[1,0,0]
	v_cvt_f32_ubyte2_e32 v126, v83
	v_cvt_f32_ubyte3_e32 v127, v83
	v_pk_fma_f32 v[84:85], v[42:43], v[102:103], v[84:85] op_sel:[1,0,0]
	v_cvt_f32_ubyte0_e32 v96, v86
	v_cvt_f32_ubyte1_e32 v97, v86
	v_pk_fma_f32 v[80:81], v[42:43], v[126:127], v[80:81] op_sel:[1,0,0]
	v_and_b32_e32 v74, s34, v154
	v_and_b32_e32 v75, s35, v154
	v_and_b32_e32 v78, s34, v155
	v_and_b32_e32 v79, s35, v155
	v_cvt_f32_ubyte2_e32 v100, v86
	v_cvt_f32_ubyte3_e32 v101, v86
	v_pk_fma_f32 v[76:77], v[34:35], v[96:97], v[76:77] op_sel:[1,0,0]
	v_cvt_f32_ubyte0_e32 v102, v87
	v_cvt_f32_ubyte1_e32 v103, v87
	v_pk_fma_f32 v[68:69], v[34:35], v[100:101], v[68:69] op_sel:[1,0,0]
	v_cvt_f32_ubyte2_e32 v126, v87
	v_cvt_f32_ubyte3_e32 v127, v87
	v_pk_fma_f32 v[62:63], v[42:43], v[102:103], v[62:63] op_sel:[1,0,0]
	v_cvt_f32_ubyte0_e32 v96, v74
	v_cvt_f32_ubyte1_e32 v97, v74
	v_pk_fma_f32 v[60:61], v[42:43], v[126:127], v[60:61] op_sel:[1,0,0]
	v_cvt_f32_ubyte2_e32 v100, v74
	v_cvt_f32_ubyte3_e32 v101, v74
	v_pk_fma_f32 v[90:91], v[36:37], v[96:97], v[90:91] op_sel_hi:[0,1,1]
	v_cvt_f32_ubyte0_e32 v102, v75
	v_cvt_f32_ubyte1_e32 v103, v75
	v_pk_fma_f32 v[88:89], v[36:37], v[100:101], v[88:89] op_sel_hi:[0,1,1]
	v_cvt_f32_ubyte2_e32 v126, v75
	v_cvt_f32_ubyte3_e32 v127, v75
	v_pk_fma_f32 v[84:85], v[44:45], v[102:103], v[84:85] op_sel_hi:[0,1,1]
	v_cvt_f32_ubyte0_e32 v96, v78
	v_cvt_f32_ubyte1_e32 v97, v78
	v_pk_fma_f32 v[80:81], v[44:45], v[126:127], v[80:81] op_sel_hi:[0,1,1]
	v_and_b32_e32 v82, s34, v156
	v_and_b32_e32 v83, s35, v156
	v_and_b32_e32 v86, s34, v157
	v_and_b32_e32 v87, s35, v157
	v_cvt_f32_ubyte2_e32 v100, v78
	v_cvt_f32_ubyte3_e32 v101, v78
	v_pk_fma_f32 v[76:77], v[36:37], v[96:97], v[76:77] op_sel_hi:[0,1,1]
	v_cvt_f32_ubyte0_e32 v102, v79
	v_cvt_f32_ubyte1_e32 v103, v79
	v_pk_fma_f32 v[68:69], v[36:37], v[100:101], v[68:69] op_sel_hi:[0,1,1]
	v_cvt_f32_ubyte2_e32 v126, v79
	v_cvt_f32_ubyte3_e32 v127, v79
	v_pk_fma_f32 v[62:63], v[44:45], v[102:103], v[62:63] op_sel_hi:[0,1,1]
	v_cvt_f32_ubyte0_e32 v96, v82
	v_cvt_f32_ubyte1_e32 v97, v82
	v_pk_fma_f32 v[60:61], v[44:45], v[126:127], v[60:61] op_sel_hi:[0,1,1]
	v_cvt_f32_ubyte2_e32 v100, v82
	v_cvt_f32_ubyte3_e32 v101, v82
	v_pk_fma_f32 v[90:91], v[36:37], v[96:97], v[90:91] op_sel:[1,0,0]
	v_cvt_f32_ubyte0_e32 v102, v83
	v_cvt_f32_ubyte1_e32 v103, v83
	v_pk_fma_f32 v[88:89], v[36:37], v[100:101], v[88:89] op_sel:[1,0,0]
	v_cvt_f32_ubyte2_e32 v126, v83
	v_cvt_f32_ubyte3_e32 v127, v83
	v_pk_fma_f32 v[84:85], v[44:45], v[102:103], v[84:85] op_sel:[1,0,0]
	v_cvt_f32_ubyte0_e32 v96, v86
	v_cvt_f32_ubyte1_e32 v97, v86
	v_pk_fma_f32 v[80:81], v[44:45], v[126:127], v[80:81] op_sel:[1,0,0]
	v_and_b32_e32 v74, s34, v158
	v_and_b32_e32 v75, s35, v158
	v_and_b32_e32 v78, s34, v159
	v_and_b32_e32 v79, s35, v159
	v_cvt_f32_ubyte2_e32 v100, v86
	v_cvt_f32_ubyte3_e32 v101, v86
	v_pk_fma_f32 v[76:77], v[36:37], v[96:97], v[76:77] op_sel:[1,0,0]
	v_cvt_f32_ubyte0_e32 v102, v87
	v_cvt_f32_ubyte1_e32 v103, v87
	v_pk_fma_f32 v[68:69], v[36:37], v[100:101], v[68:69] op_sel:[1,0,0]
	v_cvt_f32_ubyte2_e32 v126, v87
	v_cvt_f32_ubyte3_e32 v127, v87
	v_pk_fma_f32 v[62:63], v[44:45], v[102:103], v[62:63] op_sel:[1,0,0]
	v_cvt_f32_ubyte0_e32 v96, v74
	v_cvt_f32_ubyte1_e32 v97, v74
	v_pk_fma_f32 v[60:61], v[44:45], v[126:127], v[60:61] op_sel:[1,0,0]
	v_cvt_f32_ubyte2_e32 v100, v74
	v_cvt_f32_ubyte3_e32 v101, v74
	v_pk_fma_f32 v[90:91], v[38:39], v[96:97], v[90:91] op_sel_hi:[0,1,1]
	v_cvt_f32_ubyte0_e32 v102, v75
	v_cvt_f32_ubyte1_e32 v103, v75
	v_pk_fma_f32 v[88:89], v[38:39], v[100:101], v[88:89] op_sel_hi:[0,1,1]
	v_cvt_f32_ubyte2_e32 v126, v75
	v_cvt_f32_ubyte3_e32 v127, v75
	v_pk_fma_f32 v[84:85], v[46:47], v[102:103], v[84:85] op_sel_hi:[0,1,1]
	v_cvt_f32_ubyte0_e32 v96, v78
	v_cvt_f32_ubyte1_e32 v97, v78
	v_pk_fma_f32 v[80:81], v[46:47], v[126:127], v[80:81] op_sel_hi:[0,1,1]
	v_and_b32_e32 v82, s34, v160
	v_and_b32_e32 v83, s35, v160
	v_and_b32_e32 v86, s34, v161
	v_and_b32_e32 v87, s35, v161
	v_cvt_f32_ubyte2_e32 v100, v78
	v_cvt_f32_ubyte3_e32 v101, v78
	v_pk_fma_f32 v[76:77], v[38:39], v[96:97], v[76:77] op_sel_hi:[0,1,1]
	v_cvt_f32_ubyte0_e32 v102, v79
	v_cvt_f32_ubyte1_e32 v103, v79
	v_pk_fma_f32 v[68:69], v[38:39], v[100:101], v[68:69] op_sel_hi:[0,1,1]
	v_cvt_f32_ubyte2_e32 v126, v79
	v_cvt_f32_ubyte3_e32 v127, v79
	v_pk_fma_f32 v[62:63], v[46:47], v[102:103], v[62:63] op_sel_hi:[0,1,1]
	v_cvt_f32_ubyte0_e32 v96, v82
	v_cvt_f32_ubyte1_e32 v97, v82
	v_pk_fma_f32 v[60:61], v[46:47], v[126:127], v[60:61] op_sel_hi:[0,1,1]
	v_cvt_f32_ubyte2_e32 v100, v82
	v_cvt_f32_ubyte3_e32 v101, v82
	v_pk_fma_f32 v[90:91], v[38:39], v[96:97], v[90:91] op_sel:[1,0,0]
	v_cvt_f32_ubyte0_e32 v102, v83
	v_cvt_f32_ubyte1_e32 v103, v83
	v_pk_fma_f32 v[88:89], v[38:39], v[100:101], v[88:89] op_sel:[1,0,0]
	v_cvt_f32_ubyte2_e32 v126, v83
	v_cvt_f32_ubyte3_e32 v127, v83
	v_pk_fma_f32 v[84:85], v[46:47], v[102:103], v[84:85] op_sel:[1,0,0]
	v_cvt_f32_ubyte0_e32 v96, v86
	v_cvt_f32_ubyte1_e32 v97, v86
	v_pk_fma_f32 v[80:81], v[46:47], v[126:127], v[80:81] op_sel:[1,0,0]
	v_cvt_f32_ubyte2_e32 v100, v86
	v_cvt_f32_ubyte3_e32 v101, v86
	v_pk_fma_f32 v[76:77], v[38:39], v[96:97], v[76:77] op_sel:[1,0,0]
	v_cvt_f32_ubyte0_e32 v102, v87
	v_cvt_f32_ubyte1_e32 v103, v87
	v_pk_fma_f32 v[68:69], v[38:39], v[100:101], v[68:69] op_sel:[1,0,0]
	v_cvt_f32_ubyte2_e32 v126, v87
	v_cvt_f32_ubyte3_e32 v127, v87
	v_pk_fma_f32 v[62:63], v[46:47], v[102:103], v[62:63] op_sel:[1,0,0]
	v_pk_fma_f32 v[60:61], v[46:47], v[126:127], v[60:61] op_sel:[1,0,0]
	s_waitcnt lgkmcnt(0)
	v_lshl_add_u32 v70, v70, 9, v98
	v_lshl_add_u32 v71, v71, 9, v98
	v_lshl_add_u32 v72, v72, 9, v98
	v_lshl_add_u32 v73, v73, 9, v98
	v_lshl_add_u32 v92, v92, 9, v98
	v_lshl_add_u32 v93, v93, 9, v98
	v_lshl_add_u32 v94, v94, 9, v98
	v_lshl_add_u32 v95, v95, 9, v98
	global_load_dwordx2 v[146:147], v70, s[36:37]
	global_load_dwordx2 v[148:149], v71, s[36:37]
	global_load_dwordx2 v[150:151], v72, s[36:37]
	global_load_dwordx2 v[152:153], v73, s[36:37]
	global_load_dwordx2 v[154:155], v92, s[36:37]
	global_load_dwordx2 v[156:157], v93, s[36:37]
	global_load_dwordx2 v[158:159], v94, s[36:37]
	global_load_dwordx2 v[160:161], v95, s[36:37]
	ds_read_b128 v[70:73], v128 offset:224
	ds_read_b128 v[92:95], v128 offset:240
	ds_read_b128 v[32:35], v128 offset:576
	ds_read_b128 v[36:39], v128 offset:592
	ds_read_b128 v[40:43], v128 offset:1600
	ds_read_b128 v[44:47], v128 offset:1616
	s_waitcnt vmcnt(40)
	v_and_b32_e32 v74, s34, v162
	v_and_b32_e32 v75, s35, v162
	v_and_b32_e32 v78, s34, v163
	v_and_b32_e32 v79, s35, v163
	v_cvt_f32_ubyte0_e32 v96, v74
	v_cvt_f32_ubyte1_e32 v97, v74
	v_cvt_f32_ubyte2_e32 v100, v74
	v_cvt_f32_ubyte3_e32 v101, v74
	v_pk_fma_f32 v[90:91], v[48:49], v[96:97], v[90:91] op_sel_hi:[0,1,1]
	v_cvt_f32_ubyte0_e32 v102, v75
	v_cvt_f32_ubyte1_e32 v103, v75
	v_pk_fma_f32 v[88:89], v[48:49], v[100:101], v[88:89] op_sel_hi:[0,1,1]
	v_cvt_f32_ubyte2_e32 v126, v75
	v_cvt_f32_ubyte3_e32 v127, v75
	v_pk_fma_f32 v[84:85], v[56:57], v[102:103], v[84:85] op_sel_hi:[0,1,1]
	v_cvt_f32_ubyte0_e32 v96, v78
	v_cvt_f32_ubyte1_e32 v97, v78
	v_pk_fma_f32 v[80:81], v[56:57], v[126:127], v[80:81] op_sel_hi:[0,1,1]
	v_and_b32_e32 v82, s34, v164
	v_and_b32_e32 v83, s35, v164
	v_and_b32_e32 v86, s34, v165
	v_and_b32_e32 v87, s35, v165
	v_cvt_f32_ubyte2_e32 v100, v78
	v_cvt_f32_ubyte3_e32 v101, v78
	v_pk_fma_f32 v[76:77], v[48:49], v[96:97], v[76:77] op_sel_hi:[0,1,1]
	v_cvt_f32_ubyte0_e32 v102, v79
	v_cvt_f32_ubyte1_e32 v103, v79
	v_pk_fma_f32 v[68:69], v[48:49], v[100:101], v[68:69] op_sel_hi:[0,1,1]
	v_cvt_f32_ubyte2_e32 v126, v79
	v_cvt_f32_ubyte3_e32 v127, v79
	v_pk_fma_f32 v[62:63], v[56:57], v[102:103], v[62:63] op_sel_hi:[0,1,1]
	v_cvt_f32_ubyte0_e32 v96, v82
	v_cvt_f32_ubyte1_e32 v97, v82
	v_pk_fma_f32 v[60:61], v[56:57], v[126:127], v[60:61] op_sel_hi:[0,1,1]
	v_cvt_f32_ubyte2_e32 v100, v82
	v_cvt_f32_ubyte3_e32 v101, v82
	v_pk_fma_f32 v[90:91], v[48:49], v[96:97], v[90:91] op_sel:[1,0,0]
	v_cvt_f32_ubyte0_e32 v102, v83
	v_cvt_f32_ubyte1_e32 v103, v83
	v_pk_fma_f32 v[88:89], v[48:49], v[100:101], v[88:89] op_sel:[1,0,0]
	v_cvt_f32_ubyte2_e32 v126, v83
	v_cvt_f32_ubyte3_e32 v127, v83
	v_pk_fma_f32 v[84:85], v[56:57], v[102:103], v[84:85] op_sel:[1,0,0]
	v_cvt_f32_ubyte0_e32 v96, v86
	v_cvt_f32_ubyte1_e32 v97, v86
	v_pk_fma_f32 v[80:81], v[56:57], v[126:127], v[80:81] op_sel:[1,0,0]
	v_and_b32_e32 v74, s34, v166
	v_and_b32_e32 v75, s35, v166
	v_and_b32_e32 v78, s34, v167
	v_and_b32_e32 v79, s35, v167
	v_cvt_f32_ubyte2_e32 v100, v86
	v_cvt_f32_ubyte3_e32 v101, v86
	v_pk_fma_f32 v[76:77], v[48:49], v[96:97], v[76:77] op_sel:[1,0,0]
	v_cvt_f32_ubyte0_e32 v102, v87
	v_cvt_f32_ubyte1_e32 v103, v87
	v_pk_fma_f32 v[68:69], v[48:49], v[100:101], v[68:69] op_sel:[1,0,0]
	v_cvt_f32_ubyte2_e32 v126, v87
	v_cvt_f32_ubyte3_e32 v127, v87
	v_pk_fma_f32 v[62:63], v[56:57], v[102:103], v[62:63] op_sel:[1,0,0]
	v_cvt_f32_ubyte0_e32 v96, v74
	v_cvt_f32_ubyte1_e32 v97, v74
	v_pk_fma_f32 v[60:61], v[56:57], v[126:127], v[60:61] op_sel:[1,0,0]
	v_cvt_f32_ubyte2_e32 v100, v74
	v_cvt_f32_ubyte3_e32 v101, v74
	v_pk_fma_f32 v[90:91], v[50:51], v[96:97], v[90:91] op_sel_hi:[0,1,1]
	v_cvt_f32_ubyte0_e32 v102, v75
	v_cvt_f32_ubyte1_e32 v103, v75
	v_pk_fma_f32 v[88:89], v[50:51], v[100:101], v[88:89] op_sel_hi:[0,1,1]
	v_cvt_f32_ubyte2_e32 v126, v75
	v_cvt_f32_ubyte3_e32 v127, v75
	v_pk_fma_f32 v[84:85], v[58:59], v[102:103], v[84:85] op_sel_hi:[0,1,1]
	v_cvt_f32_ubyte0_e32 v96, v78
	v_cvt_f32_ubyte1_e32 v97, v78
	v_pk_fma_f32 v[80:81], v[58:59], v[126:127], v[80:81] op_sel_hi:[0,1,1]
	v_and_b32_e32 v82, s34, v168
	v_and_b32_e32 v83, s35, v168
	v_and_b32_e32 v86, s34, v169
	v_and_b32_e32 v87, s35, v169
	v_cvt_f32_ubyte2_e32 v100, v78
	v_cvt_f32_ubyte3_e32 v101, v78
	v_pk_fma_f32 v[76:77], v[50:51], v[96:97], v[76:77] op_sel_hi:[0,1,1]
	v_cvt_f32_ubyte0_e32 v102, v79
	v_cvt_f32_ubyte1_e32 v103, v79
	v_pk_fma_f32 v[68:69], v[50:51], v[100:101], v[68:69] op_sel_hi:[0,1,1]
	v_cvt_f32_ubyte2_e32 v126, v79
	v_cvt_f32_ubyte3_e32 v127, v79
	v_pk_fma_f32 v[62:63], v[58:59], v[102:103], v[62:63] op_sel_hi:[0,1,1]
	v_cvt_f32_ubyte0_e32 v96, v82
	v_cvt_f32_ubyte1_e32 v97, v82
	v_pk_fma_f32 v[60:61], v[58:59], v[126:127], v[60:61] op_sel_hi:[0,1,1]
	v_cvt_f32_ubyte2_e32 v100, v82
	v_cvt_f32_ubyte3_e32 v101, v82
	v_pk_fma_f32 v[90:91], v[50:51], v[96:97], v[90:91] op_sel:[1,0,0]
	v_cvt_f32_ubyte0_e32 v102, v83
	v_cvt_f32_ubyte1_e32 v103, v83
	v_pk_fma_f32 v[88:89], v[50:51], v[100:101], v[88:89] op_sel:[1,0,0]
	v_cvt_f32_ubyte2_e32 v126, v83
	v_cvt_f32_ubyte3_e32 v127, v83
	v_pk_fma_f32 v[84:85], v[58:59], v[102:103], v[84:85] op_sel:[1,0,0]
	v_cvt_f32_ubyte0_e32 v96, v86
	v_cvt_f32_ubyte1_e32 v97, v86
	v_pk_fma_f32 v[80:81], v[58:59], v[126:127], v[80:81] op_sel:[1,0,0]
	v_and_b32_e32 v74, s34, v170
	v_and_b32_e32 v75, s35, v170
	v_and_b32_e32 v78, s34, v171
	v_and_b32_e32 v79, s35, v171
	v_cvt_f32_ubyte2_e32 v100, v86
	v_cvt_f32_ubyte3_e32 v101, v86
	v_pk_fma_f32 v[76:77], v[50:51], v[96:97], v[76:77] op_sel:[1,0,0]
	v_cvt_f32_ubyte0_e32 v102, v87
	v_cvt_f32_ubyte1_e32 v103, v87
	v_pk_fma_f32 v[68:69], v[50:51], v[100:101], v[68:69] op_sel:[1,0,0]
	v_cvt_f32_ubyte2_e32 v126, v87
	v_cvt_f32_ubyte3_e32 v127, v87
	v_pk_fma_f32 v[62:63], v[58:59], v[102:103], v[62:63] op_sel:[1,0,0]
	v_cvt_f32_ubyte0_e32 v96, v74
	v_cvt_f32_ubyte1_e32 v97, v74
	v_pk_fma_f32 v[60:61], v[58:59], v[126:127], v[60:61] op_sel:[1,0,0]
	v_cvt_f32_ubyte2_e32 v100, v74
	v_cvt_f32_ubyte3_e32 v101, v74
	v_pk_fma_f32 v[90:91], v[52:53], v[96:97], v[90:91] op_sel_hi:[0,1,1]
	v_cvt_f32_ubyte0_e32 v102, v75
	v_cvt_f32_ubyte1_e32 v103, v75
	v_pk_fma_f32 v[88:89], v[52:53], v[100:101], v[88:89] op_sel_hi:[0,1,1]
	v_cvt_f32_ubyte2_e32 v126, v75
	v_cvt_f32_ubyte3_e32 v127, v75
	v_pk_fma_f32 v[84:85], v[64:65], v[102:103], v[84:85] op_sel_hi:[0,1,1]
	v_cvt_f32_ubyte0_e32 v96, v78
	v_cvt_f32_ubyte1_e32 v97, v78
	v_pk_fma_f32 v[80:81], v[64:65], v[126:127], v[80:81] op_sel_hi:[0,1,1]
	v_and_b32_e32 v82, s34, v172
	v_and_b32_e32 v83, s35, v172
	v_and_b32_e32 v86, s34, v173
	v_and_b32_e32 v87, s35, v173
	v_cvt_f32_ubyte2_e32 v100, v78
	v_cvt_f32_ubyte3_e32 v101, v78
	v_pk_fma_f32 v[76:77], v[52:53], v[96:97], v[76:77] op_sel_hi:[0,1,1]
	v_cvt_f32_ubyte0_e32 v102, v79
	v_cvt_f32_ubyte1_e32 v103, v79
	v_pk_fma_f32 v[68:69], v[52:53], v[100:101], v[68:69] op_sel_hi:[0,1,1]
	v_cvt_f32_ubyte2_e32 v126, v79
	v_cvt_f32_ubyte3_e32 v127, v79
	v_pk_fma_f32 v[62:63], v[64:65], v[102:103], v[62:63] op_sel_hi:[0,1,1]
	v_cvt_f32_ubyte0_e32 v96, v82
	v_cvt_f32_ubyte1_e32 v97, v82
	v_pk_fma_f32 v[60:61], v[64:65], v[126:127], v[60:61] op_sel_hi:[0,1,1]
	v_cvt_f32_ubyte2_e32 v100, v82
	v_cvt_f32_ubyte3_e32 v101, v82
	v_pk_fma_f32 v[90:91], v[52:53], v[96:97], v[90:91] op_sel:[1,0,0]
	v_cvt_f32_ubyte0_e32 v102, v83
	v_cvt_f32_ubyte1_e32 v103, v83
	v_pk_fma_f32 v[88:89], v[52:53], v[100:101], v[88:89] op_sel:[1,0,0]
	v_cvt_f32_ubyte2_e32 v126, v83
	v_cvt_f32_ubyte3_e32 v127, v83
	v_pk_fma_f32 v[84:85], v[64:65], v[102:103], v[84:85] op_sel:[1,0,0]
	v_cvt_f32_ubyte0_e32 v96, v86
	v_cvt_f32_ubyte1_e32 v97, v86
	v_pk_fma_f32 v[80:81], v[64:65], v[126:127], v[80:81] op_sel:[1,0,0]
	v_and_b32_e32 v74, s34, v174
	v_and_b32_e32 v75, s35, v174
	v_and_b32_e32 v78, s34, v175
	v_and_b32_e32 v79, s35, v175
	v_cvt_f32_ubyte2_e32 v100, v86
	v_cvt_f32_ubyte3_e32 v101, v86
	v_pk_fma_f32 v[76:77], v[52:53], v[96:97], v[76:77] op_sel:[1,0,0]
	v_cvt_f32_ubyte0_e32 v102, v87
	v_cvt_f32_ubyte1_e32 v103, v87
	v_pk_fma_f32 v[68:69], v[52:53], v[100:101], v[68:69] op_sel:[1,0,0]
	v_cvt_f32_ubyte2_e32 v126, v87
	v_cvt_f32_ubyte3_e32 v127, v87
	v_pk_fma_f32 v[62:63], v[64:65], v[102:103], v[62:63] op_sel:[1,0,0]
	v_cvt_f32_ubyte0_e32 v96, v74
	v_cvt_f32_ubyte1_e32 v97, v74
	v_pk_fma_f32 v[60:61], v[64:65], v[126:127], v[60:61] op_sel:[1,0,0]
	v_cvt_f32_ubyte2_e32 v100, v74
	v_cvt_f32_ubyte3_e32 v101, v74
	v_pk_fma_f32 v[90:91], v[54:55], v[96:97], v[90:91] op_sel_hi:[0,1,1]
	v_cvt_f32_ubyte0_e32 v102, v75
	v_cvt_f32_ubyte1_e32 v103, v75
	v_pk_fma_f32 v[88:89], v[54:55], v[100:101], v[88:89] op_sel_hi:[0,1,1]
	v_cvt_f32_ubyte2_e32 v126, v75
	v_cvt_f32_ubyte3_e32 v127, v75
	v_pk_fma_f32 v[84:85], v[66:67], v[102:103], v[84:85] op_sel_hi:[0,1,1]
	v_cvt_f32_ubyte0_e32 v96, v78
	v_cvt_f32_ubyte1_e32 v97, v78
	v_pk_fma_f32 v[80:81], v[66:67], v[126:127], v[80:81] op_sel_hi:[0,1,1]
	v_and_b32_e32 v82, s34, v176
	v_and_b32_e32 v83, s35, v176
	v_and_b32_e32 v86, s34, v177
	v_and_b32_e32 v87, s35, v177
	v_cvt_f32_ubyte2_e32 v100, v78
	v_cvt_f32_ubyte3_e32 v101, v78
	v_pk_fma_f32 v[76:77], v[54:55], v[96:97], v[76:77] op_sel_hi:[0,1,1]
	v_cvt_f32_ubyte0_e32 v102, v79
	v_cvt_f32_ubyte1_e32 v103, v79
	v_pk_fma_f32 v[68:69], v[54:55], v[100:101], v[68:69] op_sel_hi:[0,1,1]
	v_cvt_f32_ubyte2_e32 v126, v79
	v_cvt_f32_ubyte3_e32 v127, v79
	v_pk_fma_f32 v[62:63], v[66:67], v[102:103], v[62:63] op_sel_hi:[0,1,1]
	v_cvt_f32_ubyte0_e32 v96, v82
	v_cvt_f32_ubyte1_e32 v97, v82
	v_pk_fma_f32 v[60:61], v[66:67], v[126:127], v[60:61] op_sel_hi:[0,1,1]
	v_cvt_f32_ubyte2_e32 v100, v82
	v_cvt_f32_ubyte3_e32 v101, v82
	v_pk_fma_f32 v[90:91], v[54:55], v[96:97], v[90:91] op_sel:[1,0,0]
	v_cvt_f32_ubyte0_e32 v102, v83
	v_cvt_f32_ubyte1_e32 v103, v83
	v_pk_fma_f32 v[88:89], v[54:55], v[100:101], v[88:89] op_sel:[1,0,0]
	v_cvt_f32_ubyte2_e32 v126, v83
	v_cvt_f32_ubyte3_e32 v127, v83
	v_pk_fma_f32 v[84:85], v[66:67], v[102:103], v[84:85] op_sel:[1,0,0]
	v_cvt_f32_ubyte0_e32 v96, v86
	v_cvt_f32_ubyte1_e32 v97, v86
	v_pk_fma_f32 v[80:81], v[66:67], v[126:127], v[80:81] op_sel:[1,0,0]
	v_cvt_f32_ubyte2_e32 v100, v86
	v_cvt_f32_ubyte3_e32 v101, v86
	v_pk_fma_f32 v[76:77], v[54:55], v[96:97], v[76:77] op_sel:[1,0,0]
	v_cvt_f32_ubyte0_e32 v102, v87
	v_cvt_f32_ubyte1_e32 v103, v87
	v_pk_fma_f32 v[68:69], v[54:55], v[100:101], v[68:69] op_sel:[1,0,0]
	v_cvt_f32_ubyte2_e32 v126, v87
	v_cvt_f32_ubyte3_e32 v127, v87
	v_pk_fma_f32 v[62:63], v[66:67], v[102:103], v[62:63] op_sel:[1,0,0]
	v_pk_fma_f32 v[60:61], v[66:67], v[126:127], v[60:61] op_sel:[1,0,0]
	s_waitcnt lgkmcnt(0)
	v_lshl_add_u32 v70, v70, 9, v98
	v_lshl_add_u32 v71, v71, 9, v98
	v_lshl_add_u32 v72, v72, 9, v98
	v_lshl_add_u32 v73, v73, 9, v98
	v_lshl_add_u32 v92, v92, 9, v98
	v_lshl_add_u32 v93, v93, 9, v98
	v_lshl_add_u32 v94, v94, 9, v98
	v_lshl_add_u32 v95, v95, 9, v98
	global_load_dwordx2 v[162:163], v70, s[36:37]
	global_load_dwordx2 v[164:165], v71, s[36:37]
	global_load_dwordx2 v[166:167], v72, s[36:37]
	global_load_dwordx2 v[168:169], v73, s[36:37]
	global_load_dwordx2 v[170:171], v92, s[36:37]
	global_load_dwordx2 v[172:173], v93, s[36:37]
	global_load_dwordx2 v[174:175], v94, s[36:37]
	global_load_dwordx2 v[176:177], v95, s[36:37]
	ds_read_b128 v[70:73], v128 offset:256
	ds_read_b128 v[92:95], v128 offset:272
	ds_read_b128 v[48:51], v128 offset:608
	ds_read_b128 v[52:55], v128 offset:624
	ds_read_b128 v[56:59], v128 offset:1632
	ds_read_b128 v[64:67], v128 offset:1648
	s_waitcnt vmcnt(40)
	v_and_b32_e32 v74, s34, v178
	v_and_b32_e32 v75, s35, v178
	v_and_b32_e32 v78, s34, v179
	v_and_b32_e32 v79, s35, v179
	v_cvt_f32_ubyte0_e32 v96, v74
	v_cvt_f32_ubyte1_e32 v97, v74
	v_cvt_f32_ubyte2_e32 v100, v74
	v_cvt_f32_ubyte3_e32 v101, v74
	v_pk_fma_f32 v[90:91], v[32:33], v[96:97], v[90:91] op_sel_hi:[0,1,1]
	v_cvt_f32_ubyte0_e32 v102, v75
	v_cvt_f32_ubyte1_e32 v103, v75
	v_pk_fma_f32 v[88:89], v[32:33], v[100:101], v[88:89] op_sel_hi:[0,1,1]
	v_cvt_f32_ubyte2_e32 v126, v75
	v_cvt_f32_ubyte3_e32 v127, v75
	v_pk_fma_f32 v[84:85], v[40:41], v[102:103], v[84:85] op_sel_hi:[0,1,1]
	v_cvt_f32_ubyte0_e32 v96, v78
	v_cvt_f32_ubyte1_e32 v97, v78
	v_pk_fma_f32 v[80:81], v[40:41], v[126:127], v[80:81] op_sel_hi:[0,1,1]
	v_and_b32_e32 v82, s34, v180
	v_and_b32_e32 v83, s35, v180
	v_and_b32_e32 v86, s34, v181
	v_and_b32_e32 v87, s35, v181
	v_cvt_f32_ubyte2_e32 v100, v78
	v_cvt_f32_ubyte3_e32 v101, v78
	v_pk_fma_f32 v[76:77], v[32:33], v[96:97], v[76:77] op_sel_hi:[0,1,1]
	v_cvt_f32_ubyte0_e32 v102, v79
	v_cvt_f32_ubyte1_e32 v103, v79
	v_pk_fma_f32 v[68:69], v[32:33], v[100:101], v[68:69] op_sel_hi:[0,1,1]
	v_cvt_f32_ubyte2_e32 v126, v79
	v_cvt_f32_ubyte3_e32 v127, v79
	v_pk_fma_f32 v[62:63], v[40:41], v[102:103], v[62:63] op_sel_hi:[0,1,1]
	v_cvt_f32_ubyte0_e32 v96, v82
	v_cvt_f32_ubyte1_e32 v97, v82
	v_pk_fma_f32 v[60:61], v[40:41], v[126:127], v[60:61] op_sel_hi:[0,1,1]
	v_cvt_f32_ubyte2_e32 v100, v82
	v_cvt_f32_ubyte3_e32 v101, v82
	v_pk_fma_f32 v[90:91], v[32:33], v[96:97], v[90:91] op_sel:[1,0,0]
	v_cvt_f32_ubyte0_e32 v102, v83
	v_cvt_f32_ubyte1_e32 v103, v83
	v_pk_fma_f32 v[88:89], v[32:33], v[100:101], v[88:89] op_sel:[1,0,0]
	v_cvt_f32_ubyte2_e32 v126, v83
	v_cvt_f32_ubyte3_e32 v127, v83
	v_pk_fma_f32 v[84:85], v[40:41], v[102:103], v[84:85] op_sel:[1,0,0]
	v_cvt_f32_ubyte0_e32 v96, v86
	v_cvt_f32_ubyte1_e32 v97, v86
	v_pk_fma_f32 v[80:81], v[40:41], v[126:127], v[80:81] op_sel:[1,0,0]
	v_and_b32_e32 v74, s34, v182
	v_and_b32_e32 v75, s35, v182
	v_and_b32_e32 v78, s34, v183
	v_and_b32_e32 v79, s35, v183
	v_cvt_f32_ubyte2_e32 v100, v86
	v_cvt_f32_ubyte3_e32 v101, v86
	v_pk_fma_f32 v[76:77], v[32:33], v[96:97], v[76:77] op_sel:[1,0,0]
	v_cvt_f32_ubyte0_e32 v102, v87
	v_cvt_f32_ubyte1_e32 v103, v87
	v_pk_fma_f32 v[68:69], v[32:33], v[100:101], v[68:69] op_sel:[1,0,0]
	v_cvt_f32_ubyte2_e32 v126, v87
	v_cvt_f32_ubyte3_e32 v127, v87
	v_pk_fma_f32 v[62:63], v[40:41], v[102:103], v[62:63] op_sel:[1,0,0]
	v_cvt_f32_ubyte0_e32 v96, v74
	v_cvt_f32_ubyte1_e32 v97, v74
	v_pk_fma_f32 v[60:61], v[40:41], v[126:127], v[60:61] op_sel:[1,0,0]
	v_cvt_f32_ubyte2_e32 v100, v74
	v_cvt_f32_ubyte3_e32 v101, v74
	v_pk_fma_f32 v[90:91], v[34:35], v[96:97], v[90:91] op_sel_hi:[0,1,1]
	v_cvt_f32_ubyte0_e32 v102, v75
	v_cvt_f32_ubyte1_e32 v103, v75
	v_pk_fma_f32 v[88:89], v[34:35], v[100:101], v[88:89] op_sel_hi:[0,1,1]
	v_cvt_f32_ubyte2_e32 v126, v75
	v_cvt_f32_ubyte3_e32 v127, v75
	v_pk_fma_f32 v[84:85], v[42:43], v[102:103], v[84:85] op_sel_hi:[0,1,1]
	v_cvt_f32_ubyte0_e32 v96, v78
	v_cvt_f32_ubyte1_e32 v97, v78
	v_pk_fma_f32 v[80:81], v[42:43], v[126:127], v[80:81] op_sel_hi:[0,1,1]
	v_and_b32_e32 v82, s34, v184
	v_and_b32_e32 v83, s35, v184
	v_and_b32_e32 v86, s34, v185
	v_and_b32_e32 v87, s35, v185
	v_cvt_f32_ubyte2_e32 v100, v78
	v_cvt_f32_ubyte3_e32 v101, v78
	v_pk_fma_f32 v[76:77], v[34:35], v[96:97], v[76:77] op_sel_hi:[0,1,1]
	v_cvt_f32_ubyte0_e32 v102, v79
	v_cvt_f32_ubyte1_e32 v103, v79
	v_pk_fma_f32 v[68:69], v[34:35], v[100:101], v[68:69] op_sel_hi:[0,1,1]
	v_cvt_f32_ubyte2_e32 v126, v79
	v_cvt_f32_ubyte3_e32 v127, v79
	v_pk_fma_f32 v[62:63], v[42:43], v[102:103], v[62:63] op_sel_hi:[0,1,1]
	v_cvt_f32_ubyte0_e32 v96, v82
	v_cvt_f32_ubyte1_e32 v97, v82
	v_pk_fma_f32 v[60:61], v[42:43], v[126:127], v[60:61] op_sel_hi:[0,1,1]
	v_cvt_f32_ubyte2_e32 v100, v82
	v_cvt_f32_ubyte3_e32 v101, v82
	v_pk_fma_f32 v[90:91], v[34:35], v[96:97], v[90:91] op_sel:[1,0,0]
	v_cvt_f32_ubyte0_e32 v102, v83
	v_cvt_f32_ubyte1_e32 v103, v83
	v_pk_fma_f32 v[88:89], v[34:35], v[100:101], v[88:89] op_sel:[1,0,0]
	v_cvt_f32_ubyte2_e32 v126, v83
	v_cvt_f32_ubyte3_e32 v127, v83
	v_pk_fma_f32 v[84:85], v[42:43], v[102:103], v[84:85] op_sel:[1,0,0]
	v_cvt_f32_ubyte0_e32 v96, v86
	v_cvt_f32_ubyte1_e32 v97, v86
	v_pk_fma_f32 v[80:81], v[42:43], v[126:127], v[80:81] op_sel:[1,0,0]
	v_and_b32_e32 v74, s34, v186
	v_and_b32_e32 v75, s35, v186
	v_and_b32_e32 v78, s34, v187
	v_and_b32_e32 v79, s35, v187
	v_cvt_f32_ubyte2_e32 v100, v86
	v_cvt_f32_ubyte3_e32 v101, v86
	v_pk_fma_f32 v[76:77], v[34:35], v[96:97], v[76:77] op_sel:[1,0,0]
	v_cvt_f32_ubyte0_e32 v102, v87
	v_cvt_f32_ubyte1_e32 v103, v87
	v_pk_fma_f32 v[68:69], v[34:35], v[100:101], v[68:69] op_sel:[1,0,0]
	v_cvt_f32_ubyte2_e32 v126, v87
	v_cvt_f32_ubyte3_e32 v127, v87
	v_pk_fma_f32 v[62:63], v[42:43], v[102:103], v[62:63] op_sel:[1,0,0]
	v_cvt_f32_ubyte0_e32 v96, v74
	v_cvt_f32_ubyte1_e32 v97, v74
	v_pk_fma_f32 v[60:61], v[42:43], v[126:127], v[60:61] op_sel:[1,0,0]
	v_cvt_f32_ubyte2_e32 v100, v74
	v_cvt_f32_ubyte3_e32 v101, v74
	v_pk_fma_f32 v[90:91], v[36:37], v[96:97], v[90:91] op_sel_hi:[0,1,1]
	v_cvt_f32_ubyte0_e32 v102, v75
	v_cvt_f32_ubyte1_e32 v103, v75
	v_pk_fma_f32 v[88:89], v[36:37], v[100:101], v[88:89] op_sel_hi:[0,1,1]
	v_cvt_f32_ubyte2_e32 v126, v75
	v_cvt_f32_ubyte3_e32 v127, v75
	v_pk_fma_f32 v[84:85], v[44:45], v[102:103], v[84:85] op_sel_hi:[0,1,1]
	v_cvt_f32_ubyte0_e32 v96, v78
	v_cvt_f32_ubyte1_e32 v97, v78
	v_pk_fma_f32 v[80:81], v[44:45], v[126:127], v[80:81] op_sel_hi:[0,1,1]
	v_and_b32_e32 v82, s34, v188
	v_and_b32_e32 v83, s35, v188
	v_and_b32_e32 v86, s34, v189
	v_and_b32_e32 v87, s35, v189
	v_cvt_f32_ubyte2_e32 v100, v78
	v_cvt_f32_ubyte3_e32 v101, v78
	v_pk_fma_f32 v[76:77], v[36:37], v[96:97], v[76:77] op_sel_hi:[0,1,1]
	v_cvt_f32_ubyte0_e32 v102, v79
	v_cvt_f32_ubyte1_e32 v103, v79
	v_pk_fma_f32 v[68:69], v[36:37], v[100:101], v[68:69] op_sel_hi:[0,1,1]
	v_cvt_f32_ubyte2_e32 v126, v79
	v_cvt_f32_ubyte3_e32 v127, v79
	v_pk_fma_f32 v[62:63], v[44:45], v[102:103], v[62:63] op_sel_hi:[0,1,1]
	v_cvt_f32_ubyte0_e32 v96, v82
	v_cvt_f32_ubyte1_e32 v97, v82
	v_pk_fma_f32 v[60:61], v[44:45], v[126:127], v[60:61] op_sel_hi:[0,1,1]
	v_cvt_f32_ubyte2_e32 v100, v82
	v_cvt_f32_ubyte3_e32 v101, v82
	v_pk_fma_f32 v[90:91], v[36:37], v[96:97], v[90:91] op_sel:[1,0,0]
	v_cvt_f32_ubyte0_e32 v102, v83
	v_cvt_f32_ubyte1_e32 v103, v83
	v_pk_fma_f32 v[88:89], v[36:37], v[100:101], v[88:89] op_sel:[1,0,0]
	v_cvt_f32_ubyte2_e32 v126, v83
	v_cvt_f32_ubyte3_e32 v127, v83
	v_pk_fma_f32 v[84:85], v[44:45], v[102:103], v[84:85] op_sel:[1,0,0]
	v_cvt_f32_ubyte0_e32 v96, v86
	v_cvt_f32_ubyte1_e32 v97, v86
	v_pk_fma_f32 v[80:81], v[44:45], v[126:127], v[80:81] op_sel:[1,0,0]
	v_and_b32_e32 v74, s34, v190
	v_and_b32_e32 v75, s35, v190
	v_and_b32_e32 v78, s34, v191
	v_and_b32_e32 v79, s35, v191
	v_cvt_f32_ubyte2_e32 v100, v86
	v_cvt_f32_ubyte3_e32 v101, v86
	v_pk_fma_f32 v[76:77], v[36:37], v[96:97], v[76:77] op_sel:[1,0,0]
	v_cvt_f32_ubyte0_e32 v102, v87
	v_cvt_f32_ubyte1_e32 v103, v87
	v_pk_fma_f32 v[68:69], v[36:37], v[100:101], v[68:69] op_sel:[1,0,0]
	v_cvt_f32_ubyte2_e32 v126, v87
	v_cvt_f32_ubyte3_e32 v127, v87
	v_pk_fma_f32 v[62:63], v[44:45], v[102:103], v[62:63] op_sel:[1,0,0]
	v_cvt_f32_ubyte0_e32 v96, v74
	v_cvt_f32_ubyte1_e32 v97, v74
	v_pk_fma_f32 v[60:61], v[44:45], v[126:127], v[60:61] op_sel:[1,0,0]
	v_cvt_f32_ubyte2_e32 v100, v74
	v_cvt_f32_ubyte3_e32 v101, v74
	v_pk_fma_f32 v[90:91], v[38:39], v[96:97], v[90:91] op_sel_hi:[0,1,1]
	v_cvt_f32_ubyte0_e32 v102, v75
	v_cvt_f32_ubyte1_e32 v103, v75
	v_pk_fma_f32 v[88:89], v[38:39], v[100:101], v[88:89] op_sel_hi:[0,1,1]
	v_cvt_f32_ubyte2_e32 v126, v75
	v_cvt_f32_ubyte3_e32 v127, v75
	v_pk_fma_f32 v[84:85], v[46:47], v[102:103], v[84:85] op_sel_hi:[0,1,1]
	v_cvt_f32_ubyte0_e32 v96, v78
	v_cvt_f32_ubyte1_e32 v97, v78
	v_pk_fma_f32 v[80:81], v[46:47], v[126:127], v[80:81] op_sel_hi:[0,1,1]
	v_and_b32_e32 v82, s34, v192
	v_and_b32_e32 v83, s35, v192
	v_and_b32_e32 v86, s34, v193
	v_and_b32_e32 v87, s35, v193
	v_cvt_f32_ubyte2_e32 v100, v78
	v_cvt_f32_ubyte3_e32 v101, v78
	v_pk_fma_f32 v[76:77], v[38:39], v[96:97], v[76:77] op_sel_hi:[0,1,1]
	v_cvt_f32_ubyte0_e32 v102, v79
	v_cvt_f32_ubyte1_e32 v103, v79
	v_pk_fma_f32 v[68:69], v[38:39], v[100:101], v[68:69] op_sel_hi:[0,1,1]
	v_cvt_f32_ubyte2_e32 v126, v79
	v_cvt_f32_ubyte3_e32 v127, v79
	v_pk_fma_f32 v[62:63], v[46:47], v[102:103], v[62:63] op_sel_hi:[0,1,1]
	v_cvt_f32_ubyte0_e32 v96, v82
	v_cvt_f32_ubyte1_e32 v97, v82
	v_pk_fma_f32 v[60:61], v[46:47], v[126:127], v[60:61] op_sel_hi:[0,1,1]
	v_cvt_f32_ubyte2_e32 v100, v82
	v_cvt_f32_ubyte3_e32 v101, v82
	v_pk_fma_f32 v[90:91], v[38:39], v[96:97], v[90:91] op_sel:[1,0,0]
	v_cvt_f32_ubyte0_e32 v102, v83
	v_cvt_f32_ubyte1_e32 v103, v83
	v_pk_fma_f32 v[88:89], v[38:39], v[100:101], v[88:89] op_sel:[1,0,0]
	v_cvt_f32_ubyte2_e32 v126, v83
	v_cvt_f32_ubyte3_e32 v127, v83
	v_pk_fma_f32 v[84:85], v[46:47], v[102:103], v[84:85] op_sel:[1,0,0]
	v_cvt_f32_ubyte0_e32 v96, v86
	v_cvt_f32_ubyte1_e32 v97, v86
	v_pk_fma_f32 v[80:81], v[46:47], v[126:127], v[80:81] op_sel:[1,0,0]
	v_cvt_f32_ubyte2_e32 v100, v86
	v_cvt_f32_ubyte3_e32 v101, v86
	v_pk_fma_f32 v[76:77], v[38:39], v[96:97], v[76:77] op_sel:[1,0,0]
	v_cvt_f32_ubyte0_e32 v102, v87
	v_cvt_f32_ubyte1_e32 v103, v87
	v_pk_fma_f32 v[68:69], v[38:39], v[100:101], v[68:69] op_sel:[1,0,0]
	v_cvt_f32_ubyte2_e32 v126, v87
	v_cvt_f32_ubyte3_e32 v127, v87
	v_pk_fma_f32 v[62:63], v[46:47], v[102:103], v[62:63] op_sel:[1,0,0]
	v_pk_fma_f32 v[60:61], v[46:47], v[126:127], v[60:61] op_sel:[1,0,0]
	s_waitcnt lgkmcnt(0)
	v_lshl_add_u32 v70, v70, 9, v98
	v_lshl_add_u32 v71, v71, 9, v98
	v_lshl_add_u32 v72, v72, 9, v98
	v_lshl_add_u32 v73, v73, 9, v98
	v_lshl_add_u32 v92, v92, 9, v98
	v_lshl_add_u32 v93, v93, 9, v98
	v_lshl_add_u32 v94, v94, 9, v98
	v_lshl_add_u32 v95, v95, 9, v98
	global_load_dwordx2 v[178:179], v70, s[36:37]
	global_load_dwordx2 v[180:181], v71, s[36:37]
	global_load_dwordx2 v[182:183], v72, s[36:37]
	global_load_dwordx2 v[184:185], v73, s[36:37]
	global_load_dwordx2 v[186:187], v92, s[36:37]
	global_load_dwordx2 v[188:189], v93, s[36:37]
	global_load_dwordx2 v[190:191], v94, s[36:37]
	global_load_dwordx2 v[192:193], v95, s[36:37]
	ds_read_b128 v[70:73], v128 offset:288
	ds_read_b128 v[92:95], v128 offset:304
	ds_read_b128 v[32:35], v128 offset:640
	ds_read_b128 v[36:39], v128 offset:656
	ds_read_b128 v[40:43], v128 offset:1664
	ds_read_b128 v[44:47], v128 offset:1680
	s_waitcnt vmcnt(40)
	v_and_b32_e32 v74, s34, v194
	v_and_b32_e32 v75, s35, v194
	v_and_b32_e32 v78, s34, v195
	v_and_b32_e32 v79, s35, v195
	v_cvt_f32_ubyte0_e32 v96, v74
	v_cvt_f32_ubyte1_e32 v97, v74
	v_cvt_f32_ubyte2_e32 v100, v74
	v_cvt_f32_ubyte3_e32 v101, v74
	v_pk_fma_f32 v[90:91], v[48:49], v[96:97], v[90:91] op_sel_hi:[0,1,1]
	v_cvt_f32_ubyte0_e32 v102, v75
	v_cvt_f32_ubyte1_e32 v103, v75
	v_pk_fma_f32 v[88:89], v[48:49], v[100:101], v[88:89] op_sel_hi:[0,1,1]
	v_cvt_f32_ubyte2_e32 v126, v75
	v_cvt_f32_ubyte3_e32 v127, v75
	v_pk_fma_f32 v[84:85], v[56:57], v[102:103], v[84:85] op_sel_hi:[0,1,1]
	v_cvt_f32_ubyte0_e32 v96, v78
	v_cvt_f32_ubyte1_e32 v97, v78
	v_pk_fma_f32 v[80:81], v[56:57], v[126:127], v[80:81] op_sel_hi:[0,1,1]
	v_and_b32_e32 v82, s34, v196
	v_and_b32_e32 v83, s35, v196
	v_and_b32_e32 v86, s34, v197
	v_and_b32_e32 v87, s35, v197
	v_cvt_f32_ubyte2_e32 v100, v78
	v_cvt_f32_ubyte3_e32 v101, v78
	v_pk_fma_f32 v[76:77], v[48:49], v[96:97], v[76:77] op_sel_hi:[0,1,1]
	v_cvt_f32_ubyte0_e32 v102, v79
	v_cvt_f32_ubyte1_e32 v103, v79
	v_pk_fma_f32 v[68:69], v[48:49], v[100:101], v[68:69] op_sel_hi:[0,1,1]
	v_cvt_f32_ubyte2_e32 v126, v79
	v_cvt_f32_ubyte3_e32 v127, v79
	v_pk_fma_f32 v[62:63], v[56:57], v[102:103], v[62:63] op_sel_hi:[0,1,1]
	v_cvt_f32_ubyte0_e32 v96, v82
	v_cvt_f32_ubyte1_e32 v97, v82
	v_pk_fma_f32 v[60:61], v[56:57], v[126:127], v[60:61] op_sel_hi:[0,1,1]
	v_cvt_f32_ubyte2_e32 v100, v82
	v_cvt_f32_ubyte3_e32 v101, v82
	v_pk_fma_f32 v[90:91], v[48:49], v[96:97], v[90:91] op_sel:[1,0,0]
	v_cvt_f32_ubyte0_e32 v102, v83
	v_cvt_f32_ubyte1_e32 v103, v83
	v_pk_fma_f32 v[88:89], v[48:49], v[100:101], v[88:89] op_sel:[1,0,0]
	v_cvt_f32_ubyte2_e32 v126, v83
	v_cvt_f32_ubyte3_e32 v127, v83
	v_pk_fma_f32 v[84:85], v[56:57], v[102:103], v[84:85] op_sel:[1,0,0]
	v_cvt_f32_ubyte0_e32 v96, v86
	v_cvt_f32_ubyte1_e32 v97, v86
	v_pk_fma_f32 v[80:81], v[56:57], v[126:127], v[80:81] op_sel:[1,0,0]
	v_and_b32_e32 v74, s34, v198
	v_and_b32_e32 v75, s35, v198
	v_and_b32_e32 v78, s34, v199
	v_and_b32_e32 v79, s35, v199
	v_cvt_f32_ubyte2_e32 v100, v86
	v_cvt_f32_ubyte3_e32 v101, v86
	v_pk_fma_f32 v[76:77], v[48:49], v[96:97], v[76:77] op_sel:[1,0,0]
	v_cvt_f32_ubyte0_e32 v102, v87
	v_cvt_f32_ubyte1_e32 v103, v87
	v_pk_fma_f32 v[68:69], v[48:49], v[100:101], v[68:69] op_sel:[1,0,0]
	v_cvt_f32_ubyte2_e32 v126, v87
	v_cvt_f32_ubyte3_e32 v127, v87
	v_pk_fma_f32 v[62:63], v[56:57], v[102:103], v[62:63] op_sel:[1,0,0]
	v_cvt_f32_ubyte0_e32 v96, v74
	v_cvt_f32_ubyte1_e32 v97, v74
	v_pk_fma_f32 v[60:61], v[56:57], v[126:127], v[60:61] op_sel:[1,0,0]
	v_cvt_f32_ubyte2_e32 v100, v74
	v_cvt_f32_ubyte3_e32 v101, v74
	v_pk_fma_f32 v[90:91], v[50:51], v[96:97], v[90:91] op_sel_hi:[0,1,1]
	v_cvt_f32_ubyte0_e32 v102, v75
	v_cvt_f32_ubyte1_e32 v103, v75
	v_pk_fma_f32 v[88:89], v[50:51], v[100:101], v[88:89] op_sel_hi:[0,1,1]
	v_cvt_f32_ubyte2_e32 v126, v75
	v_cvt_f32_ubyte3_e32 v127, v75
	v_pk_fma_f32 v[84:85], v[58:59], v[102:103], v[84:85] op_sel_hi:[0,1,1]
	v_cvt_f32_ubyte0_e32 v96, v78
	v_cvt_f32_ubyte1_e32 v97, v78
	v_pk_fma_f32 v[80:81], v[58:59], v[126:127], v[80:81] op_sel_hi:[0,1,1]
	v_and_b32_e32 v82, s34, v200
	v_and_b32_e32 v83, s35, v200
	v_and_b32_e32 v86, s34, v201
	v_and_b32_e32 v87, s35, v201
	v_cvt_f32_ubyte2_e32 v100, v78
	v_cvt_f32_ubyte3_e32 v101, v78
	v_pk_fma_f32 v[76:77], v[50:51], v[96:97], v[76:77] op_sel_hi:[0,1,1]
	v_cvt_f32_ubyte0_e32 v102, v79
	v_cvt_f32_ubyte1_e32 v103, v79
	v_pk_fma_f32 v[68:69], v[50:51], v[100:101], v[68:69] op_sel_hi:[0,1,1]
	v_cvt_f32_ubyte2_e32 v126, v79
	v_cvt_f32_ubyte3_e32 v127, v79
	v_pk_fma_f32 v[62:63], v[58:59], v[102:103], v[62:63] op_sel_hi:[0,1,1]
	v_cvt_f32_ubyte0_e32 v96, v82
	v_cvt_f32_ubyte1_e32 v97, v82
	v_pk_fma_f32 v[60:61], v[58:59], v[126:127], v[60:61] op_sel_hi:[0,1,1]
	v_cvt_f32_ubyte2_e32 v100, v82
	v_cvt_f32_ubyte3_e32 v101, v82
	v_pk_fma_f32 v[90:91], v[50:51], v[96:97], v[90:91] op_sel:[1,0,0]
	v_cvt_f32_ubyte0_e32 v102, v83
	v_cvt_f32_ubyte1_e32 v103, v83
	v_pk_fma_f32 v[88:89], v[50:51], v[100:101], v[88:89] op_sel:[1,0,0]
	v_cvt_f32_ubyte2_e32 v126, v83
	v_cvt_f32_ubyte3_e32 v127, v83
	v_pk_fma_f32 v[84:85], v[58:59], v[102:103], v[84:85] op_sel:[1,0,0]
	v_cvt_f32_ubyte0_e32 v96, v86
	v_cvt_f32_ubyte1_e32 v97, v86
	v_pk_fma_f32 v[80:81], v[58:59], v[126:127], v[80:81] op_sel:[1,0,0]
	v_and_b32_e32 v74, s34, v202
	v_and_b32_e32 v75, s35, v202
	v_and_b32_e32 v78, s34, v203
	v_and_b32_e32 v79, s35, v203
	v_cvt_f32_ubyte2_e32 v100, v86
	v_cvt_f32_ubyte3_e32 v101, v86
	v_pk_fma_f32 v[76:77], v[50:51], v[96:97], v[76:77] op_sel:[1,0,0]
	v_cvt_f32_ubyte0_e32 v102, v87
	v_cvt_f32_ubyte1_e32 v103, v87
	v_pk_fma_f32 v[68:69], v[50:51], v[100:101], v[68:69] op_sel:[1,0,0]
	v_cvt_f32_ubyte2_e32 v126, v87
	v_cvt_f32_ubyte3_e32 v127, v87
	v_pk_fma_f32 v[62:63], v[58:59], v[102:103], v[62:63] op_sel:[1,0,0]
	v_cvt_f32_ubyte0_e32 v96, v74
	v_cvt_f32_ubyte1_e32 v97, v74
	v_pk_fma_f32 v[60:61], v[58:59], v[126:127], v[60:61] op_sel:[1,0,0]
	v_cvt_f32_ubyte2_e32 v100, v74
	v_cvt_f32_ubyte3_e32 v101, v74
	v_pk_fma_f32 v[90:91], v[52:53], v[96:97], v[90:91] op_sel_hi:[0,1,1]
	v_cvt_f32_ubyte0_e32 v102, v75
	v_cvt_f32_ubyte1_e32 v103, v75
	v_pk_fma_f32 v[88:89], v[52:53], v[100:101], v[88:89] op_sel_hi:[0,1,1]
	v_cvt_f32_ubyte2_e32 v126, v75
	v_cvt_f32_ubyte3_e32 v127, v75
	v_pk_fma_f32 v[84:85], v[64:65], v[102:103], v[84:85] op_sel_hi:[0,1,1]
	v_cvt_f32_ubyte0_e32 v96, v78
	v_cvt_f32_ubyte1_e32 v97, v78
	v_pk_fma_f32 v[80:81], v[64:65], v[126:127], v[80:81] op_sel_hi:[0,1,1]
	v_and_b32_e32 v82, s34, v204
	v_and_b32_e32 v83, s35, v204
	v_and_b32_e32 v86, s34, v205
	v_and_b32_e32 v87, s35, v205
	v_cvt_f32_ubyte2_e32 v100, v78
	v_cvt_f32_ubyte3_e32 v101, v78
	v_pk_fma_f32 v[76:77], v[52:53], v[96:97], v[76:77] op_sel_hi:[0,1,1]
	v_cvt_f32_ubyte0_e32 v102, v79
	v_cvt_f32_ubyte1_e32 v103, v79
	v_pk_fma_f32 v[68:69], v[52:53], v[100:101], v[68:69] op_sel_hi:[0,1,1]
	v_cvt_f32_ubyte2_e32 v126, v79
	v_cvt_f32_ubyte3_e32 v127, v79
	v_pk_fma_f32 v[62:63], v[64:65], v[102:103], v[62:63] op_sel_hi:[0,1,1]
	v_cvt_f32_ubyte0_e32 v96, v82
	v_cvt_f32_ubyte1_e32 v97, v82
	v_pk_fma_f32 v[60:61], v[64:65], v[126:127], v[60:61] op_sel_hi:[0,1,1]
	v_cvt_f32_ubyte2_e32 v100, v82
	v_cvt_f32_ubyte3_e32 v101, v82
	v_pk_fma_f32 v[90:91], v[52:53], v[96:97], v[90:91] op_sel:[1,0,0]
	v_cvt_f32_ubyte0_e32 v102, v83
	v_cvt_f32_ubyte1_e32 v103, v83
	v_pk_fma_f32 v[88:89], v[52:53], v[100:101], v[88:89] op_sel:[1,0,0]
	v_cvt_f32_ubyte2_e32 v126, v83
	v_cvt_f32_ubyte3_e32 v127, v83
	v_pk_fma_f32 v[84:85], v[64:65], v[102:103], v[84:85] op_sel:[1,0,0]
	v_cvt_f32_ubyte0_e32 v96, v86
	v_cvt_f32_ubyte1_e32 v97, v86
	v_pk_fma_f32 v[80:81], v[64:65], v[126:127], v[80:81] op_sel:[1,0,0]
	v_and_b32_e32 v74, s34, v206
	v_and_b32_e32 v75, s35, v206
	v_and_b32_e32 v78, s34, v207
	v_and_b32_e32 v79, s35, v207
	v_cvt_f32_ubyte2_e32 v100, v86
	v_cvt_f32_ubyte3_e32 v101, v86
	v_pk_fma_f32 v[76:77], v[52:53], v[96:97], v[76:77] op_sel:[1,0,0]
	v_cvt_f32_ubyte0_e32 v102, v87
	v_cvt_f32_ubyte1_e32 v103, v87
	v_pk_fma_f32 v[68:69], v[52:53], v[100:101], v[68:69] op_sel:[1,0,0]
	v_cvt_f32_ubyte2_e32 v126, v87
	v_cvt_f32_ubyte3_e32 v127, v87
	v_pk_fma_f32 v[62:63], v[64:65], v[102:103], v[62:63] op_sel:[1,0,0]
	v_cvt_f32_ubyte0_e32 v96, v74
	v_cvt_f32_ubyte1_e32 v97, v74
	v_pk_fma_f32 v[60:61], v[64:65], v[126:127], v[60:61] op_sel:[1,0,0]
	v_cvt_f32_ubyte2_e32 v100, v74
	v_cvt_f32_ubyte3_e32 v101, v74
	v_pk_fma_f32 v[90:91], v[54:55], v[96:97], v[90:91] op_sel_hi:[0,1,1]
	v_cvt_f32_ubyte0_e32 v102, v75
	v_cvt_f32_ubyte1_e32 v103, v75
	v_pk_fma_f32 v[88:89], v[54:55], v[100:101], v[88:89] op_sel_hi:[0,1,1]
	v_cvt_f32_ubyte2_e32 v126, v75
	v_cvt_f32_ubyte3_e32 v127, v75
	v_pk_fma_f32 v[84:85], v[66:67], v[102:103], v[84:85] op_sel_hi:[0,1,1]
	v_cvt_f32_ubyte0_e32 v96, v78
	v_cvt_f32_ubyte1_e32 v97, v78
	v_pk_fma_f32 v[80:81], v[66:67], v[126:127], v[80:81] op_sel_hi:[0,1,1]
	v_and_b32_e32 v82, s34, v208
	v_and_b32_e32 v83, s35, v208
	v_and_b32_e32 v86, s34, v209
	v_and_b32_e32 v87, s35, v209
	v_cvt_f32_ubyte2_e32 v100, v78
	v_cvt_f32_ubyte3_e32 v101, v78
	v_pk_fma_f32 v[76:77], v[54:55], v[96:97], v[76:77] op_sel_hi:[0,1,1]
	v_cvt_f32_ubyte0_e32 v102, v79
	v_cvt_f32_ubyte1_e32 v103, v79
	v_pk_fma_f32 v[68:69], v[54:55], v[100:101], v[68:69] op_sel_hi:[0,1,1]
	v_cvt_f32_ubyte2_e32 v126, v79
	v_cvt_f32_ubyte3_e32 v127, v79
	v_pk_fma_f32 v[62:63], v[66:67], v[102:103], v[62:63] op_sel_hi:[0,1,1]
	v_cvt_f32_ubyte0_e32 v96, v82
	v_cvt_f32_ubyte1_e32 v97, v82
	v_pk_fma_f32 v[60:61], v[66:67], v[126:127], v[60:61] op_sel_hi:[0,1,1]
	v_cvt_f32_ubyte2_e32 v100, v82
	v_cvt_f32_ubyte3_e32 v101, v82
	v_pk_fma_f32 v[90:91], v[54:55], v[96:97], v[90:91] op_sel:[1,0,0]
	v_cvt_f32_ubyte0_e32 v102, v83
	v_cvt_f32_ubyte1_e32 v103, v83
	v_pk_fma_f32 v[88:89], v[54:55], v[100:101], v[88:89] op_sel:[1,0,0]
	v_cvt_f32_ubyte2_e32 v126, v83
	v_cvt_f32_ubyte3_e32 v127, v83
	v_pk_fma_f32 v[84:85], v[66:67], v[102:103], v[84:85] op_sel:[1,0,0]
	v_cvt_f32_ubyte0_e32 v96, v86
	v_cvt_f32_ubyte1_e32 v97, v86
	v_pk_fma_f32 v[80:81], v[66:67], v[126:127], v[80:81] op_sel:[1,0,0]
	v_cvt_f32_ubyte2_e32 v100, v86
	v_cvt_f32_ubyte3_e32 v101, v86
	v_pk_fma_f32 v[76:77], v[54:55], v[96:97], v[76:77] op_sel:[1,0,0]
	v_cvt_f32_ubyte0_e32 v102, v87
	v_cvt_f32_ubyte1_e32 v103, v87
	v_pk_fma_f32 v[68:69], v[54:55], v[100:101], v[68:69] op_sel:[1,0,0]
	v_cvt_f32_ubyte2_e32 v126, v87
	v_cvt_f32_ubyte3_e32 v127, v87
	v_pk_fma_f32 v[62:63], v[66:67], v[102:103], v[62:63] op_sel:[1,0,0]
	v_pk_fma_f32 v[60:61], v[66:67], v[126:127], v[60:61] op_sel:[1,0,0]
	s_waitcnt lgkmcnt(0)
	v_lshl_add_u32 v70, v70, 9, v98
	v_lshl_add_u32 v71, v71, 9, v98
	v_lshl_add_u32 v72, v72, 9, v98
	v_lshl_add_u32 v73, v73, 9, v98
	v_lshl_add_u32 v92, v92, 9, v98
	v_lshl_add_u32 v93, v93, 9, v98
	v_lshl_add_u32 v94, v94, 9, v98
	v_lshl_add_u32 v95, v95, 9, v98
	global_load_dwordx2 v[194:195], v70, s[36:37]
	global_load_dwordx2 v[196:197], v71, s[36:37]
	global_load_dwordx2 v[198:199], v72, s[36:37]
	global_load_dwordx2 v[200:201], v73, s[36:37]
	global_load_dwordx2 v[202:203], v92, s[36:37]
	global_load_dwordx2 v[204:205], v93, s[36:37]
	global_load_dwordx2 v[206:207], v94, s[36:37]
	global_load_dwordx2 v[208:209], v95, s[36:37]
	ds_read_b128 v[70:73], v128 offset:320
	ds_read_b128 v[92:95], v128 offset:336
	ds_read_b128 v[48:51], v128 offset:672
	ds_read_b128 v[52:55], v128 offset:688
	ds_read_b128 v[56:59], v128 offset:1696
	ds_read_b128 v[64:67], v128 offset:1712
	s_waitcnt vmcnt(40)
	v_and_b32_e32 v74, s34, v0
	v_and_b32_e32 v75, s35, v0
	v_and_b32_e32 v78, s34, v1
	v_and_b32_e32 v79, s35, v1
	v_cvt_f32_ubyte0_e32 v96, v74
	v_cvt_f32_ubyte1_e32 v97, v74
	v_cvt_f32_ubyte2_e32 v100, v74
	v_cvt_f32_ubyte3_e32 v101, v74
	v_pk_fma_f32 v[90:91], v[32:33], v[96:97], v[90:91] op_sel_hi:[0,1,1]
	v_cvt_f32_ubyte0_e32 v102, v75
	v_cvt_f32_ubyte1_e32 v103, v75
	v_pk_fma_f32 v[88:89], v[32:33], v[100:101], v[88:89] op_sel_hi:[0,1,1]
	v_cvt_f32_ubyte2_e32 v126, v75
	v_cvt_f32_ubyte3_e32 v127, v75
	v_pk_fma_f32 v[84:85], v[40:41], v[102:103], v[84:85] op_sel_hi:[0,1,1]
	v_cvt_f32_ubyte0_e32 v96, v78
	v_cvt_f32_ubyte1_e32 v97, v78
	v_pk_fma_f32 v[80:81], v[40:41], v[126:127], v[80:81] op_sel_hi:[0,1,1]
	v_and_b32_e32 v82, s34, v2
	v_and_b32_e32 v83, s35, v2
	v_and_b32_e32 v86, s34, v3
	v_and_b32_e32 v87, s35, v3
	v_cvt_f32_ubyte2_e32 v100, v78
	v_cvt_f32_ubyte3_e32 v101, v78
	v_pk_fma_f32 v[76:77], v[32:33], v[96:97], v[76:77] op_sel_hi:[0,1,1]
	v_cvt_f32_ubyte0_e32 v102, v79
	v_cvt_f32_ubyte1_e32 v103, v79
	v_pk_fma_f32 v[68:69], v[32:33], v[100:101], v[68:69] op_sel_hi:[0,1,1]
	v_cvt_f32_ubyte2_e32 v126, v79
	v_cvt_f32_ubyte3_e32 v127, v79
	v_pk_fma_f32 v[62:63], v[40:41], v[102:103], v[62:63] op_sel_hi:[0,1,1]
	v_cvt_f32_ubyte0_e32 v96, v82
	v_cvt_f32_ubyte1_e32 v97, v82
	v_pk_fma_f32 v[60:61], v[40:41], v[126:127], v[60:61] op_sel_hi:[0,1,1]
	v_cvt_f32_ubyte2_e32 v100, v82
	v_cvt_f32_ubyte3_e32 v101, v82
	v_pk_fma_f32 v[90:91], v[32:33], v[96:97], v[90:91] op_sel:[1,0,0]
	v_cvt_f32_ubyte0_e32 v102, v83
	v_cvt_f32_ubyte1_e32 v103, v83
	v_pk_fma_f32 v[88:89], v[32:33], v[100:101], v[88:89] op_sel:[1,0,0]
	v_cvt_f32_ubyte2_e32 v126, v83
	v_cvt_f32_ubyte3_e32 v127, v83
	v_pk_fma_f32 v[84:85], v[40:41], v[102:103], v[84:85] op_sel:[1,0,0]
	v_cvt_f32_ubyte0_e32 v96, v86
	v_cvt_f32_ubyte1_e32 v97, v86
	v_pk_fma_f32 v[80:81], v[40:41], v[126:127], v[80:81] op_sel:[1,0,0]
	v_and_b32_e32 v74, s34, v4
	v_and_b32_e32 v75, s35, v4
	v_and_b32_e32 v78, s34, v5
	v_and_b32_e32 v79, s35, v5
	v_cvt_f32_ubyte2_e32 v100, v86
	v_cvt_f32_ubyte3_e32 v101, v86
	v_pk_fma_f32 v[76:77], v[32:33], v[96:97], v[76:77] op_sel:[1,0,0]
	v_cvt_f32_ubyte0_e32 v102, v87
	v_cvt_f32_ubyte1_e32 v103, v87
	v_pk_fma_f32 v[68:69], v[32:33], v[100:101], v[68:69] op_sel:[1,0,0]
	v_cvt_f32_ubyte2_e32 v126, v87
	v_cvt_f32_ubyte3_e32 v127, v87
	v_pk_fma_f32 v[62:63], v[40:41], v[102:103], v[62:63] op_sel:[1,0,0]
	v_cvt_f32_ubyte0_e32 v96, v74
	v_cvt_f32_ubyte1_e32 v97, v74
	v_pk_fma_f32 v[60:61], v[40:41], v[126:127], v[60:61] op_sel:[1,0,0]
	v_cvt_f32_ubyte2_e32 v100, v74
	v_cvt_f32_ubyte3_e32 v101, v74
	v_pk_fma_f32 v[90:91], v[34:35], v[96:97], v[90:91] op_sel_hi:[0,1,1]
	v_cvt_f32_ubyte0_e32 v102, v75
	v_cvt_f32_ubyte1_e32 v103, v75
	v_pk_fma_f32 v[88:89], v[34:35], v[100:101], v[88:89] op_sel_hi:[0,1,1]
	v_cvt_f32_ubyte2_e32 v126, v75
	v_cvt_f32_ubyte3_e32 v127, v75
	v_pk_fma_f32 v[84:85], v[42:43], v[102:103], v[84:85] op_sel_hi:[0,1,1]
	v_cvt_f32_ubyte0_e32 v96, v78
	v_cvt_f32_ubyte1_e32 v97, v78
	v_pk_fma_f32 v[80:81], v[42:43], v[126:127], v[80:81] op_sel_hi:[0,1,1]
	v_and_b32_e32 v82, s34, v6
	v_and_b32_e32 v83, s35, v6
	v_and_b32_e32 v86, s34, v7
	v_and_b32_e32 v87, s35, v7
	v_cvt_f32_ubyte2_e32 v100, v78
	v_cvt_f32_ubyte3_e32 v101, v78
	v_pk_fma_f32 v[76:77], v[34:35], v[96:97], v[76:77] op_sel_hi:[0,1,1]
	v_cvt_f32_ubyte0_e32 v102, v79
	v_cvt_f32_ubyte1_e32 v103, v79
	v_pk_fma_f32 v[68:69], v[34:35], v[100:101], v[68:69] op_sel_hi:[0,1,1]
	v_cvt_f32_ubyte2_e32 v126, v79
	v_cvt_f32_ubyte3_e32 v127, v79
	v_pk_fma_f32 v[62:63], v[42:43], v[102:103], v[62:63] op_sel_hi:[0,1,1]
	v_cvt_f32_ubyte0_e32 v96, v82
	v_cvt_f32_ubyte1_e32 v97, v82
	v_pk_fma_f32 v[60:61], v[42:43], v[126:127], v[60:61] op_sel_hi:[0,1,1]
	v_cvt_f32_ubyte2_e32 v100, v82
	v_cvt_f32_ubyte3_e32 v101, v82
	v_pk_fma_f32 v[90:91], v[34:35], v[96:97], v[90:91] op_sel:[1,0,0]
	v_cvt_f32_ubyte0_e32 v102, v83
	v_cvt_f32_ubyte1_e32 v103, v83
	v_pk_fma_f32 v[88:89], v[34:35], v[100:101], v[88:89] op_sel:[1,0,0]
	v_cvt_f32_ubyte2_e32 v126, v83
	v_cvt_f32_ubyte3_e32 v127, v83
	v_pk_fma_f32 v[84:85], v[42:43], v[102:103], v[84:85] op_sel:[1,0,0]
	v_cvt_f32_ubyte0_e32 v96, v86
	v_cvt_f32_ubyte1_e32 v97, v86
	v_pk_fma_f32 v[80:81], v[42:43], v[126:127], v[80:81] op_sel:[1,0,0]
	v_and_b32_e32 v74, s34, v8
	v_and_b32_e32 v75, s35, v8
	v_and_b32_e32 v78, s34, v9
	v_and_b32_e32 v79, s35, v9
	v_cvt_f32_ubyte2_e32 v100, v86
	v_cvt_f32_ubyte3_e32 v101, v86
	v_pk_fma_f32 v[76:77], v[34:35], v[96:97], v[76:77] op_sel:[1,0,0]
	v_cvt_f32_ubyte0_e32 v102, v87
	v_cvt_f32_ubyte1_e32 v103, v87
	v_pk_fma_f32 v[68:69], v[34:35], v[100:101], v[68:69] op_sel:[1,0,0]
	v_cvt_f32_ubyte2_e32 v126, v87
	v_cvt_f32_ubyte3_e32 v127, v87
	v_pk_fma_f32 v[62:63], v[42:43], v[102:103], v[62:63] op_sel:[1,0,0]
	v_cvt_f32_ubyte0_e32 v96, v74
	v_cvt_f32_ubyte1_e32 v97, v74
	v_pk_fma_f32 v[60:61], v[42:43], v[126:127], v[60:61] op_sel:[1,0,0]
	v_cvt_f32_ubyte2_e32 v100, v74
	v_cvt_f32_ubyte3_e32 v101, v74
	v_pk_fma_f32 v[90:91], v[36:37], v[96:97], v[90:91] op_sel_hi:[0,1,1]
	v_cvt_f32_ubyte0_e32 v102, v75
	v_cvt_f32_ubyte1_e32 v103, v75
	v_pk_fma_f32 v[88:89], v[36:37], v[100:101], v[88:89] op_sel_hi:[0,1,1]
	v_cvt_f32_ubyte2_e32 v126, v75
	v_cvt_f32_ubyte3_e32 v127, v75
	v_pk_fma_f32 v[84:85], v[44:45], v[102:103], v[84:85] op_sel_hi:[0,1,1]
	v_cvt_f32_ubyte0_e32 v96, v78
	v_cvt_f32_ubyte1_e32 v97, v78
	v_pk_fma_f32 v[80:81], v[44:45], v[126:127], v[80:81] op_sel_hi:[0,1,1]
	v_and_b32_e32 v82, s34, v10
	v_and_b32_e32 v83, s35, v10
	v_and_b32_e32 v86, s34, v11
	v_and_b32_e32 v87, s35, v11
	v_cvt_f32_ubyte2_e32 v100, v78
	v_cvt_f32_ubyte3_e32 v101, v78
	v_pk_fma_f32 v[76:77], v[36:37], v[96:97], v[76:77] op_sel_hi:[0,1,1]
	v_cvt_f32_ubyte0_e32 v102, v79
	v_cvt_f32_ubyte1_e32 v103, v79
	v_pk_fma_f32 v[68:69], v[36:37], v[100:101], v[68:69] op_sel_hi:[0,1,1]
	v_cvt_f32_ubyte2_e32 v126, v79
	v_cvt_f32_ubyte3_e32 v127, v79
	v_pk_fma_f32 v[62:63], v[44:45], v[102:103], v[62:63] op_sel_hi:[0,1,1]
	v_cvt_f32_ubyte0_e32 v96, v82
	v_cvt_f32_ubyte1_e32 v97, v82
	v_pk_fma_f32 v[60:61], v[44:45], v[126:127], v[60:61] op_sel_hi:[0,1,1]
	v_cvt_f32_ubyte2_e32 v100, v82
	v_cvt_f32_ubyte3_e32 v101, v82
	v_pk_fma_f32 v[90:91], v[36:37], v[96:97], v[90:91] op_sel:[1,0,0]
	v_cvt_f32_ubyte0_e32 v102, v83
	v_cvt_f32_ubyte1_e32 v103, v83
	v_pk_fma_f32 v[88:89], v[36:37], v[100:101], v[88:89] op_sel:[1,0,0]
	v_cvt_f32_ubyte2_e32 v126, v83
	v_cvt_f32_ubyte3_e32 v127, v83
	v_pk_fma_f32 v[84:85], v[44:45], v[102:103], v[84:85] op_sel:[1,0,0]
	v_cvt_f32_ubyte0_e32 v96, v86
	v_cvt_f32_ubyte1_e32 v97, v86
	v_pk_fma_f32 v[80:81], v[44:45], v[126:127], v[80:81] op_sel:[1,0,0]
	v_and_b32_e32 v74, s34, v12
	v_and_b32_e32 v75, s35, v12
	v_and_b32_e32 v78, s34, v13
	v_and_b32_e32 v79, s35, v13
	v_cvt_f32_ubyte2_e32 v100, v86
	v_cvt_f32_ubyte3_e32 v101, v86
	v_pk_fma_f32 v[76:77], v[36:37], v[96:97], v[76:77] op_sel:[1,0,0]
	v_cvt_f32_ubyte0_e32 v102, v87
	v_cvt_f32_ubyte1_e32 v103, v87
	v_pk_fma_f32 v[68:69], v[36:37], v[100:101], v[68:69] op_sel:[1,0,0]
	v_cvt_f32_ubyte2_e32 v126, v87
	v_cvt_f32_ubyte3_e32 v127, v87
	v_pk_fma_f32 v[62:63], v[44:45], v[102:103], v[62:63] op_sel:[1,0,0]
	v_cvt_f32_ubyte0_e32 v96, v74
	v_cvt_f32_ubyte1_e32 v97, v74
	v_pk_fma_f32 v[60:61], v[44:45], v[126:127], v[60:61] op_sel:[1,0,0]
	v_cvt_f32_ubyte2_e32 v100, v74
	v_cvt_f32_ubyte3_e32 v101, v74
	v_pk_fma_f32 v[90:91], v[38:39], v[96:97], v[90:91] op_sel_hi:[0,1,1]
	v_cvt_f32_ubyte0_e32 v102, v75
	v_cvt_f32_ubyte1_e32 v103, v75
	v_pk_fma_f32 v[88:89], v[38:39], v[100:101], v[88:89] op_sel_hi:[0,1,1]
	v_cvt_f32_ubyte2_e32 v126, v75
	v_cvt_f32_ubyte3_e32 v127, v75
	v_pk_fma_f32 v[84:85], v[46:47], v[102:103], v[84:85] op_sel_hi:[0,1,1]
	v_cvt_f32_ubyte0_e32 v96, v78
	v_cvt_f32_ubyte1_e32 v97, v78
	v_pk_fma_f32 v[80:81], v[46:47], v[126:127], v[80:81] op_sel_hi:[0,1,1]
	v_and_b32_e32 v82, s34, v14
	v_and_b32_e32 v83, s35, v14
	v_and_b32_e32 v86, s34, v15
	v_and_b32_e32 v87, s35, v15
	v_cvt_f32_ubyte2_e32 v100, v78
	v_cvt_f32_ubyte3_e32 v101, v78
	v_pk_fma_f32 v[76:77], v[38:39], v[96:97], v[76:77] op_sel_hi:[0,1,1]
	v_cvt_f32_ubyte0_e32 v102, v79
	v_cvt_f32_ubyte1_e32 v103, v79
	v_pk_fma_f32 v[68:69], v[38:39], v[100:101], v[68:69] op_sel_hi:[0,1,1]
	v_cvt_f32_ubyte2_e32 v126, v79
	v_cvt_f32_ubyte3_e32 v127, v79
	v_pk_fma_f32 v[62:63], v[46:47], v[102:103], v[62:63] op_sel_hi:[0,1,1]
	v_cvt_f32_ubyte0_e32 v96, v82
	v_cvt_f32_ubyte1_e32 v97, v82
	v_pk_fma_f32 v[60:61], v[46:47], v[126:127], v[60:61] op_sel_hi:[0,1,1]
	v_cvt_f32_ubyte2_e32 v100, v82
	v_cvt_f32_ubyte3_e32 v101, v82
	v_pk_fma_f32 v[90:91], v[38:39], v[96:97], v[90:91] op_sel:[1,0,0]
	v_cvt_f32_ubyte0_e32 v102, v83
	v_cvt_f32_ubyte1_e32 v103, v83
	v_pk_fma_f32 v[88:89], v[38:39], v[100:101], v[88:89] op_sel:[1,0,0]
	v_cvt_f32_ubyte2_e32 v126, v83
	v_cvt_f32_ubyte3_e32 v127, v83
	v_pk_fma_f32 v[84:85], v[46:47], v[102:103], v[84:85] op_sel:[1,0,0]
	v_cvt_f32_ubyte0_e32 v96, v86
	v_cvt_f32_ubyte1_e32 v97, v86
	v_pk_fma_f32 v[80:81], v[46:47], v[126:127], v[80:81] op_sel:[1,0,0]
	v_cvt_f32_ubyte2_e32 v100, v86
	v_cvt_f32_ubyte3_e32 v101, v86
	v_pk_fma_f32 v[76:77], v[38:39], v[96:97], v[76:77] op_sel:[1,0,0]
	v_cvt_f32_ubyte0_e32 v102, v87
	v_cvt_f32_ubyte1_e32 v103, v87
	v_pk_fma_f32 v[68:69], v[38:39], v[100:101], v[68:69] op_sel:[1,0,0]
	v_cvt_f32_ubyte2_e32 v126, v87
	v_cvt_f32_ubyte3_e32 v127, v87
	v_pk_fma_f32 v[62:63], v[46:47], v[102:103], v[62:63] op_sel:[1,0,0]
	v_pk_fma_f32 v[60:61], v[46:47], v[126:127], v[60:61] op_sel:[1,0,0]
	s_waitcnt lgkmcnt(0)
	v_lshl_add_u32 v70, v70, 9, v98
	v_lshl_add_u32 v71, v71, 9, v98
	v_lshl_add_u32 v72, v72, 9, v98
	v_lshl_add_u32 v73, v73, 9, v98
	v_lshl_add_u32 v92, v92, 9, v98
	v_lshl_add_u32 v93, v93, 9, v98
	v_lshl_add_u32 v94, v94, 9, v98
	v_lshl_add_u32 v95, v95, 9, v98
	global_load_dwordx2 v[0:1], v70, s[36:37]
	global_load_dwordx2 v[2:3], v71, s[36:37]
	global_load_dwordx2 v[4:5], v72, s[36:37]
	global_load_dwordx2 v[6:7], v73, s[36:37]
	global_load_dwordx2 v[8:9], v92, s[36:37]
	global_load_dwordx2 v[10:11], v93, s[36:37]
	global_load_dwordx2 v[12:13], v94, s[36:37]
	global_load_dwordx2 v[14:15], v95, s[36:37]
	ds_read_b128 v[70:73], v128 offset:352
	ds_read_b128 v[92:95], v128 offset:368
	ds_read_b128 v[32:35], v128 offset:704
	ds_read_b128 v[36:39], v128 offset:720
	ds_read_b128 v[40:43], v128 offset:1728
	ds_read_b128 v[44:47], v128 offset:1744
	s_waitcnt vmcnt(40)
	v_and_b32_e32 v74, s34, v16
	v_and_b32_e32 v75, s35, v16
	v_and_b32_e32 v78, s34, v17
	v_and_b32_e32 v79, s35, v17
	v_cvt_f32_ubyte0_e32 v96, v74
	v_cvt_f32_ubyte1_e32 v97, v74
	v_cvt_f32_ubyte2_e32 v100, v74
	v_cvt_f32_ubyte3_e32 v101, v74
	v_pk_fma_f32 v[90:91], v[48:49], v[96:97], v[90:91] op_sel_hi:[0,1,1]
	v_cvt_f32_ubyte0_e32 v102, v75
	v_cvt_f32_ubyte1_e32 v103, v75
	v_pk_fma_f32 v[88:89], v[48:49], v[100:101], v[88:89] op_sel_hi:[0,1,1]
	v_cvt_f32_ubyte2_e32 v126, v75
	v_cvt_f32_ubyte3_e32 v127, v75
	v_pk_fma_f32 v[84:85], v[56:57], v[102:103], v[84:85] op_sel_hi:[0,1,1]
	v_cvt_f32_ubyte0_e32 v96, v78
	v_cvt_f32_ubyte1_e32 v97, v78
	v_pk_fma_f32 v[80:81], v[56:57], v[126:127], v[80:81] op_sel_hi:[0,1,1]
	v_and_b32_e32 v82, s34, v18
	v_and_b32_e32 v83, s35, v18
	v_and_b32_e32 v86, s34, v19
	v_and_b32_e32 v87, s35, v19
	v_cvt_f32_ubyte2_e32 v100, v78
	v_cvt_f32_ubyte3_e32 v101, v78
	v_pk_fma_f32 v[76:77], v[48:49], v[96:97], v[76:77] op_sel_hi:[0,1,1]
	v_cvt_f32_ubyte0_e32 v102, v79
	v_cvt_f32_ubyte1_e32 v103, v79
	v_pk_fma_f32 v[68:69], v[48:49], v[100:101], v[68:69] op_sel_hi:[0,1,1]
	v_cvt_f32_ubyte2_e32 v126, v79
	v_cvt_f32_ubyte3_e32 v127, v79
	v_pk_fma_f32 v[62:63], v[56:57], v[102:103], v[62:63] op_sel_hi:[0,1,1]
	v_cvt_f32_ubyte0_e32 v96, v82
	v_cvt_f32_ubyte1_e32 v97, v82
	v_pk_fma_f32 v[60:61], v[56:57], v[126:127], v[60:61] op_sel_hi:[0,1,1]
	v_cvt_f32_ubyte2_e32 v100, v82
	v_cvt_f32_ubyte3_e32 v101, v82
	v_pk_fma_f32 v[90:91], v[48:49], v[96:97], v[90:91] op_sel:[1,0,0]
	v_cvt_f32_ubyte0_e32 v102, v83
	v_cvt_f32_ubyte1_e32 v103, v83
	v_pk_fma_f32 v[88:89], v[48:49], v[100:101], v[88:89] op_sel:[1,0,0]
	v_cvt_f32_ubyte2_e32 v126, v83
	v_cvt_f32_ubyte3_e32 v127, v83
	v_pk_fma_f32 v[84:85], v[56:57], v[102:103], v[84:85] op_sel:[1,0,0]
	v_cvt_f32_ubyte0_e32 v96, v86
	v_cvt_f32_ubyte1_e32 v97, v86
	v_pk_fma_f32 v[80:81], v[56:57], v[126:127], v[80:81] op_sel:[1,0,0]
	v_and_b32_e32 v74, s34, v20
	v_and_b32_e32 v75, s35, v20
	v_and_b32_e32 v78, s34, v21
	v_and_b32_e32 v79, s35, v21
	v_cvt_f32_ubyte2_e32 v100, v86
	v_cvt_f32_ubyte3_e32 v101, v86
	v_pk_fma_f32 v[76:77], v[48:49], v[96:97], v[76:77] op_sel:[1,0,0]
	v_cvt_f32_ubyte0_e32 v102, v87
	v_cvt_f32_ubyte1_e32 v103, v87
	v_pk_fma_f32 v[68:69], v[48:49], v[100:101], v[68:69] op_sel:[1,0,0]
	v_cvt_f32_ubyte2_e32 v126, v87
	v_cvt_f32_ubyte3_e32 v127, v87
	v_pk_fma_f32 v[62:63], v[56:57], v[102:103], v[62:63] op_sel:[1,0,0]
	v_cvt_f32_ubyte0_e32 v96, v74
	v_cvt_f32_ubyte1_e32 v97, v74
	v_pk_fma_f32 v[60:61], v[56:57], v[126:127], v[60:61] op_sel:[1,0,0]
	v_cvt_f32_ubyte2_e32 v100, v74
	v_cvt_f32_ubyte3_e32 v101, v74
	v_pk_fma_f32 v[90:91], v[50:51], v[96:97], v[90:91] op_sel_hi:[0,1,1]
	v_cvt_f32_ubyte0_e32 v102, v75
	v_cvt_f32_ubyte1_e32 v103, v75
	v_pk_fma_f32 v[88:89], v[50:51], v[100:101], v[88:89] op_sel_hi:[0,1,1]
	v_cvt_f32_ubyte2_e32 v126, v75
	v_cvt_f32_ubyte3_e32 v127, v75
	v_pk_fma_f32 v[84:85], v[58:59], v[102:103], v[84:85] op_sel_hi:[0,1,1]
	v_cvt_f32_ubyte0_e32 v96, v78
	v_cvt_f32_ubyte1_e32 v97, v78
	v_pk_fma_f32 v[80:81], v[58:59], v[126:127], v[80:81] op_sel_hi:[0,1,1]
	v_and_b32_e32 v82, s34, v22
	v_and_b32_e32 v83, s35, v22
	v_and_b32_e32 v86, s34, v23
	v_and_b32_e32 v87, s35, v23
	v_cvt_f32_ubyte2_e32 v100, v78
	v_cvt_f32_ubyte3_e32 v101, v78
	v_pk_fma_f32 v[76:77], v[50:51], v[96:97], v[76:77] op_sel_hi:[0,1,1]
	v_cvt_f32_ubyte0_e32 v102, v79
	v_cvt_f32_ubyte1_e32 v103, v79
	v_pk_fma_f32 v[68:69], v[50:51], v[100:101], v[68:69] op_sel_hi:[0,1,1]
	v_cvt_f32_ubyte2_e32 v126, v79
	v_cvt_f32_ubyte3_e32 v127, v79
	v_pk_fma_f32 v[62:63], v[58:59], v[102:103], v[62:63] op_sel_hi:[0,1,1]
	v_cvt_f32_ubyte0_e32 v96, v82
	v_cvt_f32_ubyte1_e32 v97, v82
	v_pk_fma_f32 v[60:61], v[58:59], v[126:127], v[60:61] op_sel_hi:[0,1,1]
	v_cvt_f32_ubyte2_e32 v100, v82
	v_cvt_f32_ubyte3_e32 v101, v82
	v_pk_fma_f32 v[90:91], v[50:51], v[96:97], v[90:91] op_sel:[1,0,0]
	v_cvt_f32_ubyte0_e32 v102, v83
	v_cvt_f32_ubyte1_e32 v103, v83
	v_pk_fma_f32 v[88:89], v[50:51], v[100:101], v[88:89] op_sel:[1,0,0]
	v_cvt_f32_ubyte2_e32 v126, v83
	v_cvt_f32_ubyte3_e32 v127, v83
	v_pk_fma_f32 v[84:85], v[58:59], v[102:103], v[84:85] op_sel:[1,0,0]
	v_cvt_f32_ubyte0_e32 v96, v86
	v_cvt_f32_ubyte1_e32 v97, v86
	v_pk_fma_f32 v[80:81], v[58:59], v[126:127], v[80:81] op_sel:[1,0,0]
	v_and_b32_e32 v74, s34, v24
	v_and_b32_e32 v75, s35, v24
	v_and_b32_e32 v78, s34, v25
	v_and_b32_e32 v79, s35, v25
	v_cvt_f32_ubyte2_e32 v100, v86
	v_cvt_f32_ubyte3_e32 v101, v86
	v_pk_fma_f32 v[76:77], v[50:51], v[96:97], v[76:77] op_sel:[1,0,0]
	v_cvt_f32_ubyte0_e32 v102, v87
	v_cvt_f32_ubyte1_e32 v103, v87
	v_pk_fma_f32 v[68:69], v[50:51], v[100:101], v[68:69] op_sel:[1,0,0]
	v_cvt_f32_ubyte2_e32 v126, v87
	v_cvt_f32_ubyte3_e32 v127, v87
	v_pk_fma_f32 v[62:63], v[58:59], v[102:103], v[62:63] op_sel:[1,0,0]
	v_cvt_f32_ubyte0_e32 v96, v74
	v_cvt_f32_ubyte1_e32 v97, v74
	v_pk_fma_f32 v[60:61], v[58:59], v[126:127], v[60:61] op_sel:[1,0,0]
	v_cvt_f32_ubyte2_e32 v100, v74
	v_cvt_f32_ubyte3_e32 v101, v74
	v_pk_fma_f32 v[90:91], v[52:53], v[96:97], v[90:91] op_sel_hi:[0,1,1]
	v_cvt_f32_ubyte0_e32 v102, v75
	v_cvt_f32_ubyte1_e32 v103, v75
	v_pk_fma_f32 v[88:89], v[52:53], v[100:101], v[88:89] op_sel_hi:[0,1,1]
	v_cvt_f32_ubyte2_e32 v126, v75
	v_cvt_f32_ubyte3_e32 v127, v75
	v_pk_fma_f32 v[84:85], v[64:65], v[102:103], v[84:85] op_sel_hi:[0,1,1]
	v_cvt_f32_ubyte0_e32 v96, v78
	v_cvt_f32_ubyte1_e32 v97, v78
	v_pk_fma_f32 v[80:81], v[64:65], v[126:127], v[80:81] op_sel_hi:[0,1,1]
	v_and_b32_e32 v82, s34, v26
	v_and_b32_e32 v83, s35, v26
	v_and_b32_e32 v86, s34, v27
	v_and_b32_e32 v87, s35, v27
	v_cvt_f32_ubyte2_e32 v100, v78
	v_cvt_f32_ubyte3_e32 v101, v78
	v_pk_fma_f32 v[76:77], v[52:53], v[96:97], v[76:77] op_sel_hi:[0,1,1]
	v_cvt_f32_ubyte0_e32 v102, v79
	v_cvt_f32_ubyte1_e32 v103, v79
	v_pk_fma_f32 v[68:69], v[52:53], v[100:101], v[68:69] op_sel_hi:[0,1,1]
	v_cvt_f32_ubyte2_e32 v126, v79
	v_cvt_f32_ubyte3_e32 v127, v79
	v_pk_fma_f32 v[62:63], v[64:65], v[102:103], v[62:63] op_sel_hi:[0,1,1]
	v_cvt_f32_ubyte0_e32 v96, v82
	v_cvt_f32_ubyte1_e32 v97, v82
	v_pk_fma_f32 v[60:61], v[64:65], v[126:127], v[60:61] op_sel_hi:[0,1,1]
	v_cvt_f32_ubyte2_e32 v100, v82
	v_cvt_f32_ubyte3_e32 v101, v82
	v_pk_fma_f32 v[90:91], v[52:53], v[96:97], v[90:91] op_sel:[1,0,0]
	v_cvt_f32_ubyte0_e32 v102, v83
	v_cvt_f32_ubyte1_e32 v103, v83
	v_pk_fma_f32 v[88:89], v[52:53], v[100:101], v[88:89] op_sel:[1,0,0]
	v_cvt_f32_ubyte2_e32 v126, v83
	v_cvt_f32_ubyte3_e32 v127, v83
	v_pk_fma_f32 v[84:85], v[64:65], v[102:103], v[84:85] op_sel:[1,0,0]
	v_cvt_f32_ubyte0_e32 v96, v86
	v_cvt_f32_ubyte1_e32 v97, v86
	v_pk_fma_f32 v[80:81], v[64:65], v[126:127], v[80:81] op_sel:[1,0,0]
	v_and_b32_e32 v74, s34, v28
	v_and_b32_e32 v75, s35, v28
	v_and_b32_e32 v78, s34, v29
	v_and_b32_e32 v79, s35, v29
	v_cvt_f32_ubyte2_e32 v100, v86
	v_cvt_f32_ubyte3_e32 v101, v86
	v_pk_fma_f32 v[76:77], v[52:53], v[96:97], v[76:77] op_sel:[1,0,0]
	v_cvt_f32_ubyte0_e32 v102, v87
	v_cvt_f32_ubyte1_e32 v103, v87
	v_pk_fma_f32 v[68:69], v[52:53], v[100:101], v[68:69] op_sel:[1,0,0]
	v_cvt_f32_ubyte2_e32 v126, v87
	v_cvt_f32_ubyte3_e32 v127, v87
	v_pk_fma_f32 v[62:63], v[64:65], v[102:103], v[62:63] op_sel:[1,0,0]
	v_cvt_f32_ubyte0_e32 v96, v74
	v_cvt_f32_ubyte1_e32 v97, v74
	v_pk_fma_f32 v[60:61], v[64:65], v[126:127], v[60:61] op_sel:[1,0,0]
	v_cvt_f32_ubyte2_e32 v100, v74
	v_cvt_f32_ubyte3_e32 v101, v74
	v_pk_fma_f32 v[90:91], v[54:55], v[96:97], v[90:91] op_sel_hi:[0,1,1]
	v_cvt_f32_ubyte0_e32 v102, v75
	v_cvt_f32_ubyte1_e32 v103, v75
	v_pk_fma_f32 v[88:89], v[54:55], v[100:101], v[88:89] op_sel_hi:[0,1,1]
	v_cvt_f32_ubyte2_e32 v126, v75
	v_cvt_f32_ubyte3_e32 v127, v75
	v_pk_fma_f32 v[84:85], v[66:67], v[102:103], v[84:85] op_sel_hi:[0,1,1]
	v_cvt_f32_ubyte0_e32 v96, v78
	v_cvt_f32_ubyte1_e32 v97, v78
	v_pk_fma_f32 v[80:81], v[66:67], v[126:127], v[80:81] op_sel_hi:[0,1,1]
	v_and_b32_e32 v82, s34, v30
	v_and_b32_e32 v83, s35, v30
	v_and_b32_e32 v86, s34, v31
	v_and_b32_e32 v87, s35, v31
	v_cvt_f32_ubyte2_e32 v100, v78
	v_cvt_f32_ubyte3_e32 v101, v78
	v_pk_fma_f32 v[76:77], v[54:55], v[96:97], v[76:77] op_sel_hi:[0,1,1]
	v_cvt_f32_ubyte0_e32 v102, v79
	v_cvt_f32_ubyte1_e32 v103, v79
	v_pk_fma_f32 v[68:69], v[54:55], v[100:101], v[68:69] op_sel_hi:[0,1,1]
	v_cvt_f32_ubyte2_e32 v126, v79
	v_cvt_f32_ubyte3_e32 v127, v79
	v_pk_fma_f32 v[62:63], v[66:67], v[102:103], v[62:63] op_sel_hi:[0,1,1]
	v_cvt_f32_ubyte0_e32 v96, v82
	v_cvt_f32_ubyte1_e32 v97, v82
	v_pk_fma_f32 v[60:61], v[66:67], v[126:127], v[60:61] op_sel_hi:[0,1,1]
	v_cvt_f32_ubyte2_e32 v100, v82
	v_cvt_f32_ubyte3_e32 v101, v82
	v_pk_fma_f32 v[90:91], v[54:55], v[96:97], v[90:91] op_sel:[1,0,0]
	v_cvt_f32_ubyte0_e32 v102, v83
	v_cvt_f32_ubyte1_e32 v103, v83
	v_pk_fma_f32 v[88:89], v[54:55], v[100:101], v[88:89] op_sel:[1,0,0]
	v_cvt_f32_ubyte2_e32 v126, v83
	v_cvt_f32_ubyte3_e32 v127, v83
	v_pk_fma_f32 v[84:85], v[66:67], v[102:103], v[84:85] op_sel:[1,0,0]
	v_cvt_f32_ubyte0_e32 v96, v86
	v_cvt_f32_ubyte1_e32 v97, v86
	v_pk_fma_f32 v[80:81], v[66:67], v[126:127], v[80:81] op_sel:[1,0,0]
	v_cvt_f32_ubyte2_e32 v100, v86
	v_cvt_f32_ubyte3_e32 v101, v86
	v_pk_fma_f32 v[76:77], v[54:55], v[96:97], v[76:77] op_sel:[1,0,0]
	v_cvt_f32_ubyte0_e32 v102, v87
	v_cvt_f32_ubyte1_e32 v103, v87
	v_pk_fma_f32 v[68:69], v[54:55], v[100:101], v[68:69] op_sel:[1,0,0]
	v_cvt_f32_ubyte2_e32 v126, v87
	v_cvt_f32_ubyte3_e32 v127, v87
	v_pk_fma_f32 v[62:63], v[66:67], v[102:103], v[62:63] op_sel:[1,0,0]
	v_pk_fma_f32 v[60:61], v[66:67], v[126:127], v[60:61] op_sel:[1,0,0]
	s_waitcnt lgkmcnt(0)
	v_lshl_add_u32 v70, v70, 9, v98
	v_lshl_add_u32 v71, v71, 9, v98
	v_lshl_add_u32 v72, v72, 9, v98
	v_lshl_add_u32 v73, v73, 9, v98
	v_lshl_add_u32 v92, v92, 9, v98
	v_lshl_add_u32 v93, v93, 9, v98
	v_lshl_add_u32 v94, v94, 9, v98
	v_lshl_add_u32 v95, v95, 9, v98
	global_load_dwordx2 v[16:17], v70, s[36:37]
	global_load_dwordx2 v[18:19], v71, s[36:37]
	global_load_dwordx2 v[20:21], v72, s[36:37]
	global_load_dwordx2 v[22:23], v73, s[36:37]
	global_load_dwordx2 v[24:25], v92, s[36:37]
	global_load_dwordx2 v[26:27], v93, s[36:37]
	global_load_dwordx2 v[28:29], v94, s[36:37]
	global_load_dwordx2 v[30:31], v95, s[36:37]
	ds_read_b128 v[70:73], v128 offset:384
	ds_read_b128 v[92:95], v128 offset:400
	ds_read_b128 v[48:51], v128 offset:736
	ds_read_b128 v[52:55], v128 offset:752
	ds_read_b128 v[56:59], v128 offset:1760
	ds_read_b128 v[64:67], v128 offset:1776
	s_waitcnt vmcnt(40)
	v_and_b32_e32 v74, s34, v146
	v_and_b32_e32 v75, s35, v146
	v_and_b32_e32 v78, s34, v147
	v_and_b32_e32 v79, s35, v147
	v_cvt_f32_ubyte0_e32 v96, v74
	v_cvt_f32_ubyte1_e32 v97, v74
	v_cvt_f32_ubyte2_e32 v100, v74
	v_cvt_f32_ubyte3_e32 v101, v74
	v_pk_fma_f32 v[90:91], v[32:33], v[96:97], v[90:91] op_sel_hi:[0,1,1]
	v_cvt_f32_ubyte0_e32 v102, v75
	v_cvt_f32_ubyte1_e32 v103, v75
	v_pk_fma_f32 v[88:89], v[32:33], v[100:101], v[88:89] op_sel_hi:[0,1,1]
	v_cvt_f32_ubyte2_e32 v126, v75
	v_cvt_f32_ubyte3_e32 v127, v75
	v_pk_fma_f32 v[84:85], v[40:41], v[102:103], v[84:85] op_sel_hi:[0,1,1]
	v_cvt_f32_ubyte0_e32 v96, v78
	v_cvt_f32_ubyte1_e32 v97, v78
	v_pk_fma_f32 v[80:81], v[40:41], v[126:127], v[80:81] op_sel_hi:[0,1,1]
	v_and_b32_e32 v82, s34, v148
	v_and_b32_e32 v83, s35, v148
	v_and_b32_e32 v86, s34, v149
	v_and_b32_e32 v87, s35, v149
	v_cvt_f32_ubyte2_e32 v100, v78
	v_cvt_f32_ubyte3_e32 v101, v78
	v_pk_fma_f32 v[76:77], v[32:33], v[96:97], v[76:77] op_sel_hi:[0,1,1]
	v_cvt_f32_ubyte0_e32 v102, v79
	v_cvt_f32_ubyte1_e32 v103, v79
	v_pk_fma_f32 v[68:69], v[32:33], v[100:101], v[68:69] op_sel_hi:[0,1,1]
	v_cvt_f32_ubyte2_e32 v126, v79
	v_cvt_f32_ubyte3_e32 v127, v79
	v_pk_fma_f32 v[62:63], v[40:41], v[102:103], v[62:63] op_sel_hi:[0,1,1]
	v_cvt_f32_ubyte0_e32 v96, v82
	v_cvt_f32_ubyte1_e32 v97, v82
	v_pk_fma_f32 v[60:61], v[40:41], v[126:127], v[60:61] op_sel_hi:[0,1,1]
	v_cvt_f32_ubyte2_e32 v100, v82
	v_cvt_f32_ubyte3_e32 v101, v82
	v_pk_fma_f32 v[90:91], v[32:33], v[96:97], v[90:91] op_sel:[1,0,0]
	v_cvt_f32_ubyte0_e32 v102, v83
	v_cvt_f32_ubyte1_e32 v103, v83
	v_pk_fma_f32 v[88:89], v[32:33], v[100:101], v[88:89] op_sel:[1,0,0]
	v_cvt_f32_ubyte2_e32 v126, v83
	v_cvt_f32_ubyte3_e32 v127, v83
	v_pk_fma_f32 v[84:85], v[40:41], v[102:103], v[84:85] op_sel:[1,0,0]
	v_cvt_f32_ubyte0_e32 v96, v86
	v_cvt_f32_ubyte1_e32 v97, v86
	v_pk_fma_f32 v[80:81], v[40:41], v[126:127], v[80:81] op_sel:[1,0,0]
	v_and_b32_e32 v74, s34, v150
	v_and_b32_e32 v75, s35, v150
	v_and_b32_e32 v78, s34, v151
	v_and_b32_e32 v79, s35, v151
	v_cvt_f32_ubyte2_e32 v100, v86
	v_cvt_f32_ubyte3_e32 v101, v86
	v_pk_fma_f32 v[76:77], v[32:33], v[96:97], v[76:77] op_sel:[1,0,0]
	v_cvt_f32_ubyte0_e32 v102, v87
	v_cvt_f32_ubyte1_e32 v103, v87
	v_pk_fma_f32 v[68:69], v[32:33], v[100:101], v[68:69] op_sel:[1,0,0]
	v_cvt_f32_ubyte2_e32 v126, v87
	v_cvt_f32_ubyte3_e32 v127, v87
	v_pk_fma_f32 v[62:63], v[40:41], v[102:103], v[62:63] op_sel:[1,0,0]
	v_cvt_f32_ubyte0_e32 v96, v74
	v_cvt_f32_ubyte1_e32 v97, v74
	v_pk_fma_f32 v[60:61], v[40:41], v[126:127], v[60:61] op_sel:[1,0,0]
	v_cvt_f32_ubyte2_e32 v100, v74
	v_cvt_f32_ubyte3_e32 v101, v74
	v_pk_fma_f32 v[90:91], v[34:35], v[96:97], v[90:91] op_sel_hi:[0,1,1]
	v_cvt_f32_ubyte0_e32 v102, v75
	v_cvt_f32_ubyte1_e32 v103, v75
	v_pk_fma_f32 v[88:89], v[34:35], v[100:101], v[88:89] op_sel_hi:[0,1,1]
	v_cvt_f32_ubyte2_e32 v126, v75
	v_cvt_f32_ubyte3_e32 v127, v75
	v_pk_fma_f32 v[84:85], v[42:43], v[102:103], v[84:85] op_sel_hi:[0,1,1]
	v_cvt_f32_ubyte0_e32 v96, v78
	v_cvt_f32_ubyte1_e32 v97, v78
	v_pk_fma_f32 v[80:81], v[42:43], v[126:127], v[80:81] op_sel_hi:[0,1,1]
	v_and_b32_e32 v82, s34, v152
	v_and_b32_e32 v83, s35, v152
	v_and_b32_e32 v86, s34, v153
	v_and_b32_e32 v87, s35, v153
	v_cvt_f32_ubyte2_e32 v100, v78
	v_cvt_f32_ubyte3_e32 v101, v78
	v_pk_fma_f32 v[76:77], v[34:35], v[96:97], v[76:77] op_sel_hi:[0,1,1]
	v_cvt_f32_ubyte0_e32 v102, v79
	v_cvt_f32_ubyte1_e32 v103, v79
	v_pk_fma_f32 v[68:69], v[34:35], v[100:101], v[68:69] op_sel_hi:[0,1,1]
	v_cvt_f32_ubyte2_e32 v126, v79
	v_cvt_f32_ubyte3_e32 v127, v79
	v_pk_fma_f32 v[62:63], v[42:43], v[102:103], v[62:63] op_sel_hi:[0,1,1]
	v_cvt_f32_ubyte0_e32 v96, v82
	v_cvt_f32_ubyte1_e32 v97, v82
	v_pk_fma_f32 v[60:61], v[42:43], v[126:127], v[60:61] op_sel_hi:[0,1,1]
	v_cvt_f32_ubyte2_e32 v100, v82
	v_cvt_f32_ubyte3_e32 v101, v82
	v_pk_fma_f32 v[90:91], v[34:35], v[96:97], v[90:91] op_sel:[1,0,0]
	v_cvt_f32_ubyte0_e32 v102, v83
	v_cvt_f32_ubyte1_e32 v103, v83
	v_pk_fma_f32 v[88:89], v[34:35], v[100:101], v[88:89] op_sel:[1,0,0]
	v_cvt_f32_ubyte2_e32 v126, v83
	v_cvt_f32_ubyte3_e32 v127, v83
	v_pk_fma_f32 v[84:85], v[42:43], v[102:103], v[84:85] op_sel:[1,0,0]
	v_cvt_f32_ubyte0_e32 v96, v86
	v_cvt_f32_ubyte1_e32 v97, v86
	v_pk_fma_f32 v[80:81], v[42:43], v[126:127], v[80:81] op_sel:[1,0,0]
	v_and_b32_e32 v74, s34, v154
	v_and_b32_e32 v75, s35, v154
	v_and_b32_e32 v78, s34, v155
	v_and_b32_e32 v79, s35, v155
	v_cvt_f32_ubyte2_e32 v100, v86
	v_cvt_f32_ubyte3_e32 v101, v86
	v_pk_fma_f32 v[76:77], v[34:35], v[96:97], v[76:77] op_sel:[1,0,0]
	v_cvt_f32_ubyte0_e32 v102, v87
	v_cvt_f32_ubyte1_e32 v103, v87
	v_pk_fma_f32 v[68:69], v[34:35], v[100:101], v[68:69] op_sel:[1,0,0]
	v_cvt_f32_ubyte2_e32 v126, v87
	v_cvt_f32_ubyte3_e32 v127, v87
	v_pk_fma_f32 v[62:63], v[42:43], v[102:103], v[62:63] op_sel:[1,0,0]
	v_cvt_f32_ubyte0_e32 v96, v74
	v_cvt_f32_ubyte1_e32 v97, v74
	v_pk_fma_f32 v[60:61], v[42:43], v[126:127], v[60:61] op_sel:[1,0,0]
	v_cvt_f32_ubyte2_e32 v100, v74
	v_cvt_f32_ubyte3_e32 v101, v74
	v_pk_fma_f32 v[90:91], v[36:37], v[96:97], v[90:91] op_sel_hi:[0,1,1]
	v_cvt_f32_ubyte0_e32 v102, v75
	v_cvt_f32_ubyte1_e32 v103, v75
	v_pk_fma_f32 v[88:89], v[36:37], v[100:101], v[88:89] op_sel_hi:[0,1,1]
	v_cvt_f32_ubyte2_e32 v126, v75
	v_cvt_f32_ubyte3_e32 v127, v75
	v_pk_fma_f32 v[84:85], v[44:45], v[102:103], v[84:85] op_sel_hi:[0,1,1]
	v_cvt_f32_ubyte0_e32 v96, v78
	v_cvt_f32_ubyte1_e32 v97, v78
	v_pk_fma_f32 v[80:81], v[44:45], v[126:127], v[80:81] op_sel_hi:[0,1,1]
	v_and_b32_e32 v82, s34, v156
	v_and_b32_e32 v83, s35, v156
	v_and_b32_e32 v86, s34, v157
	v_and_b32_e32 v87, s35, v157
	v_cvt_f32_ubyte2_e32 v100, v78
	v_cvt_f32_ubyte3_e32 v101, v78
	v_pk_fma_f32 v[76:77], v[36:37], v[96:97], v[76:77] op_sel_hi:[0,1,1]
	v_cvt_f32_ubyte0_e32 v102, v79
	v_cvt_f32_ubyte1_e32 v103, v79
	v_pk_fma_f32 v[68:69], v[36:37], v[100:101], v[68:69] op_sel_hi:[0,1,1]
	v_cvt_f32_ubyte2_e32 v126, v79
	v_cvt_f32_ubyte3_e32 v127, v79
	v_pk_fma_f32 v[62:63], v[44:45], v[102:103], v[62:63] op_sel_hi:[0,1,1]
	v_cvt_f32_ubyte0_e32 v96, v82
	v_cvt_f32_ubyte1_e32 v97, v82
	v_pk_fma_f32 v[60:61], v[44:45], v[126:127], v[60:61] op_sel_hi:[0,1,1]
	v_cvt_f32_ubyte2_e32 v100, v82
	v_cvt_f32_ubyte3_e32 v101, v82
	v_pk_fma_f32 v[90:91], v[36:37], v[96:97], v[90:91] op_sel:[1,0,0]
	v_cvt_f32_ubyte0_e32 v102, v83
	v_cvt_f32_ubyte1_e32 v103, v83
	v_pk_fma_f32 v[88:89], v[36:37], v[100:101], v[88:89] op_sel:[1,0,0]
	v_cvt_f32_ubyte2_e32 v126, v83
	v_cvt_f32_ubyte3_e32 v127, v83
	v_pk_fma_f32 v[84:85], v[44:45], v[102:103], v[84:85] op_sel:[1,0,0]
	v_cvt_f32_ubyte0_e32 v96, v86
	v_cvt_f32_ubyte1_e32 v97, v86
	v_pk_fma_f32 v[80:81], v[44:45], v[126:127], v[80:81] op_sel:[1,0,0]
	v_and_b32_e32 v74, s34, v158
	v_and_b32_e32 v75, s35, v158
	v_and_b32_e32 v78, s34, v159
	v_and_b32_e32 v79, s35, v159
	v_cvt_f32_ubyte2_e32 v100, v86
	v_cvt_f32_ubyte3_e32 v101, v86
	v_pk_fma_f32 v[76:77], v[36:37], v[96:97], v[76:77] op_sel:[1,0,0]
	v_cvt_f32_ubyte0_e32 v102, v87
	v_cvt_f32_ubyte1_e32 v103, v87
	v_pk_fma_f32 v[68:69], v[36:37], v[100:101], v[68:69] op_sel:[1,0,0]
	v_cvt_f32_ubyte2_e32 v126, v87
	v_cvt_f32_ubyte3_e32 v127, v87
	v_pk_fma_f32 v[62:63], v[44:45], v[102:103], v[62:63] op_sel:[1,0,0]
	v_cvt_f32_ubyte0_e32 v96, v74
	v_cvt_f32_ubyte1_e32 v97, v74
	v_pk_fma_f32 v[60:61], v[44:45], v[126:127], v[60:61] op_sel:[1,0,0]
	v_cvt_f32_ubyte2_e32 v100, v74
	v_cvt_f32_ubyte3_e32 v101, v74
	v_pk_fma_f32 v[90:91], v[38:39], v[96:97], v[90:91] op_sel_hi:[0,1,1]
	v_cvt_f32_ubyte0_e32 v102, v75
	v_cvt_f32_ubyte1_e32 v103, v75
	v_pk_fma_f32 v[88:89], v[38:39], v[100:101], v[88:89] op_sel_hi:[0,1,1]
	v_cvt_f32_ubyte2_e32 v126, v75
	v_cvt_f32_ubyte3_e32 v127, v75
	v_pk_fma_f32 v[84:85], v[46:47], v[102:103], v[84:85] op_sel_hi:[0,1,1]
	v_cvt_f32_ubyte0_e32 v96, v78
	v_cvt_f32_ubyte1_e32 v97, v78
	v_pk_fma_f32 v[80:81], v[46:47], v[126:127], v[80:81] op_sel_hi:[0,1,1]
	v_and_b32_e32 v82, s34, v160
	v_and_b32_e32 v83, s35, v160
	v_and_b32_e32 v86, s34, v161
	v_and_b32_e32 v87, s35, v161
	v_cvt_f32_ubyte2_e32 v100, v78
	v_cvt_f32_ubyte3_e32 v101, v78
	v_pk_fma_f32 v[76:77], v[38:39], v[96:97], v[76:77] op_sel_hi:[0,1,1]
	v_cvt_f32_ubyte0_e32 v102, v79
	v_cvt_f32_ubyte1_e32 v103, v79
	v_pk_fma_f32 v[68:69], v[38:39], v[100:101], v[68:69] op_sel_hi:[0,1,1]
	v_cvt_f32_ubyte2_e32 v126, v79
	v_cvt_f32_ubyte3_e32 v127, v79
	v_pk_fma_f32 v[62:63], v[46:47], v[102:103], v[62:63] op_sel_hi:[0,1,1]
	v_cvt_f32_ubyte0_e32 v96, v82
	v_cvt_f32_ubyte1_e32 v97, v82
	v_pk_fma_f32 v[60:61], v[46:47], v[126:127], v[60:61] op_sel_hi:[0,1,1]
	v_cvt_f32_ubyte2_e32 v100, v82
	v_cvt_f32_ubyte3_e32 v101, v82
	v_pk_fma_f32 v[90:91], v[38:39], v[96:97], v[90:91] op_sel:[1,0,0]
	v_cvt_f32_ubyte0_e32 v102, v83
	v_cvt_f32_ubyte1_e32 v103, v83
	v_pk_fma_f32 v[88:89], v[38:39], v[100:101], v[88:89] op_sel:[1,0,0]
	v_cvt_f32_ubyte2_e32 v126, v83
	v_cvt_f32_ubyte3_e32 v127, v83
	v_pk_fma_f32 v[84:85], v[46:47], v[102:103], v[84:85] op_sel:[1,0,0]
	v_cvt_f32_ubyte0_e32 v96, v86
	v_cvt_f32_ubyte1_e32 v97, v86
	v_pk_fma_f32 v[80:81], v[46:47], v[126:127], v[80:81] op_sel:[1,0,0]
	v_cvt_f32_ubyte2_e32 v100, v86
	v_cvt_f32_ubyte3_e32 v101, v86
	v_pk_fma_f32 v[76:77], v[38:39], v[96:97], v[76:77] op_sel:[1,0,0]
	v_cvt_f32_ubyte0_e32 v102, v87
	v_cvt_f32_ubyte1_e32 v103, v87
	v_pk_fma_f32 v[68:69], v[38:39], v[100:101], v[68:69] op_sel:[1,0,0]
	v_cvt_f32_ubyte2_e32 v126, v87
	v_cvt_f32_ubyte3_e32 v127, v87
	v_pk_fma_f32 v[62:63], v[46:47], v[102:103], v[62:63] op_sel:[1,0,0]
	v_pk_fma_f32 v[60:61], v[46:47], v[126:127], v[60:61] op_sel:[1,0,0]
	s_waitcnt lgkmcnt(0)
	v_lshl_add_u32 v70, v70, 9, v98
	v_lshl_add_u32 v71, v71, 9, v98
	v_lshl_add_u32 v72, v72, 9, v98
	v_lshl_add_u32 v73, v73, 9, v98
	v_lshl_add_u32 v92, v92, 9, v98
	v_lshl_add_u32 v93, v93, 9, v98
	v_lshl_add_u32 v94, v94, 9, v98
	v_lshl_add_u32 v95, v95, 9, v98
	global_load_dwordx2 v[146:147], v70, s[36:37]
	global_load_dwordx2 v[148:149], v71, s[36:37]
	global_load_dwordx2 v[150:151], v72, s[36:37]
	global_load_dwordx2 v[152:153], v73, s[36:37]
	global_load_dwordx2 v[154:155], v92, s[36:37]
	global_load_dwordx2 v[156:157], v93, s[36:37]
	global_load_dwordx2 v[158:159], v94, s[36:37]
	global_load_dwordx2 v[160:161], v95, s[36:37]
	ds_read_b128 v[70:73], v128 offset:416
	ds_read_b128 v[92:95], v128 offset:432
	ds_read_b128 v[32:35], v128 offset:768
	ds_read_b128 v[36:39], v128 offset:784
	ds_read_b128 v[40:43], v128 offset:1792
	ds_read_b128 v[44:47], v128 offset:1808
	s_waitcnt vmcnt(40)
	v_and_b32_e32 v74, s34, v162
	v_and_b32_e32 v75, s35, v162
	v_and_b32_e32 v78, s34, v163
	v_and_b32_e32 v79, s35, v163
	v_cvt_f32_ubyte0_e32 v96, v74
	v_cvt_f32_ubyte1_e32 v97, v74
	v_cvt_f32_ubyte2_e32 v100, v74
	v_cvt_f32_ubyte3_e32 v101, v74
	v_pk_fma_f32 v[90:91], v[48:49], v[96:97], v[90:91] op_sel_hi:[0,1,1]
	v_cvt_f32_ubyte0_e32 v102, v75
	v_cvt_f32_ubyte1_e32 v103, v75
	v_pk_fma_f32 v[88:89], v[48:49], v[100:101], v[88:89] op_sel_hi:[0,1,1]
	v_cvt_f32_ubyte2_e32 v126, v75
	v_cvt_f32_ubyte3_e32 v127, v75
	v_pk_fma_f32 v[84:85], v[56:57], v[102:103], v[84:85] op_sel_hi:[0,1,1]
	v_cvt_f32_ubyte0_e32 v96, v78
	v_cvt_f32_ubyte1_e32 v97, v78
	v_pk_fma_f32 v[80:81], v[56:57], v[126:127], v[80:81] op_sel_hi:[0,1,1]
	v_and_b32_e32 v82, s34, v164
	v_and_b32_e32 v83, s35, v164
	v_and_b32_e32 v86, s34, v165
	v_and_b32_e32 v87, s35, v165
	v_cvt_f32_ubyte2_e32 v100, v78
	v_cvt_f32_ubyte3_e32 v101, v78
	v_pk_fma_f32 v[76:77], v[48:49], v[96:97], v[76:77] op_sel_hi:[0,1,1]
	v_cvt_f32_ubyte0_e32 v102, v79
	v_cvt_f32_ubyte1_e32 v103, v79
	v_pk_fma_f32 v[68:69], v[48:49], v[100:101], v[68:69] op_sel_hi:[0,1,1]
	v_cvt_f32_ubyte2_e32 v126, v79
	v_cvt_f32_ubyte3_e32 v127, v79
	v_pk_fma_f32 v[62:63], v[56:57], v[102:103], v[62:63] op_sel_hi:[0,1,1]
	v_cvt_f32_ubyte0_e32 v96, v82
	v_cvt_f32_ubyte1_e32 v97, v82
	v_pk_fma_f32 v[60:61], v[56:57], v[126:127], v[60:61] op_sel_hi:[0,1,1]
	v_cvt_f32_ubyte2_e32 v100, v82
	v_cvt_f32_ubyte3_e32 v101, v82
	v_pk_fma_f32 v[90:91], v[48:49], v[96:97], v[90:91] op_sel:[1,0,0]
	v_cvt_f32_ubyte0_e32 v102, v83
	v_cvt_f32_ubyte1_e32 v103, v83
	v_pk_fma_f32 v[88:89], v[48:49], v[100:101], v[88:89] op_sel:[1,0,0]
	v_cvt_f32_ubyte2_e32 v126, v83
	v_cvt_f32_ubyte3_e32 v127, v83
	v_pk_fma_f32 v[84:85], v[56:57], v[102:103], v[84:85] op_sel:[1,0,0]
	v_cvt_f32_ubyte0_e32 v96, v86
	v_cvt_f32_ubyte1_e32 v97, v86
	v_pk_fma_f32 v[80:81], v[56:57], v[126:127], v[80:81] op_sel:[1,0,0]
	v_and_b32_e32 v74, s34, v166
	v_and_b32_e32 v75, s35, v166
	v_and_b32_e32 v78, s34, v167
	v_and_b32_e32 v79, s35, v167
	v_cvt_f32_ubyte2_e32 v100, v86
	v_cvt_f32_ubyte3_e32 v101, v86
	v_pk_fma_f32 v[76:77], v[48:49], v[96:97], v[76:77] op_sel:[1,0,0]
	v_cvt_f32_ubyte0_e32 v102, v87
	v_cvt_f32_ubyte1_e32 v103, v87
	v_pk_fma_f32 v[68:69], v[48:49], v[100:101], v[68:69] op_sel:[1,0,0]
	v_cvt_f32_ubyte2_e32 v126, v87
	v_cvt_f32_ubyte3_e32 v127, v87
	v_pk_fma_f32 v[62:63], v[56:57], v[102:103], v[62:63] op_sel:[1,0,0]
	v_cvt_f32_ubyte0_e32 v96, v74
	v_cvt_f32_ubyte1_e32 v97, v74
	v_pk_fma_f32 v[60:61], v[56:57], v[126:127], v[60:61] op_sel:[1,0,0]
	v_cvt_f32_ubyte2_e32 v100, v74
	v_cvt_f32_ubyte3_e32 v101, v74
	v_pk_fma_f32 v[90:91], v[50:51], v[96:97], v[90:91] op_sel_hi:[0,1,1]
	v_cvt_f32_ubyte0_e32 v102, v75
	v_cvt_f32_ubyte1_e32 v103, v75
	v_pk_fma_f32 v[88:89], v[50:51], v[100:101], v[88:89] op_sel_hi:[0,1,1]
	v_cvt_f32_ubyte2_e32 v126, v75
	v_cvt_f32_ubyte3_e32 v127, v75
	v_pk_fma_f32 v[84:85], v[58:59], v[102:103], v[84:85] op_sel_hi:[0,1,1]
	v_cvt_f32_ubyte0_e32 v96, v78
	v_cvt_f32_ubyte1_e32 v97, v78
	v_pk_fma_f32 v[80:81], v[58:59], v[126:127], v[80:81] op_sel_hi:[0,1,1]
	v_and_b32_e32 v82, s34, v168
	v_and_b32_e32 v83, s35, v168
	v_and_b32_e32 v86, s34, v169
	v_and_b32_e32 v87, s35, v169
	v_cvt_f32_ubyte2_e32 v100, v78
	v_cvt_f32_ubyte3_e32 v101, v78
	v_pk_fma_f32 v[76:77], v[50:51], v[96:97], v[76:77] op_sel_hi:[0,1,1]
	v_cvt_f32_ubyte0_e32 v102, v79
	v_cvt_f32_ubyte1_e32 v103, v79
	v_pk_fma_f32 v[68:69], v[50:51], v[100:101], v[68:69] op_sel_hi:[0,1,1]
	v_cvt_f32_ubyte2_e32 v126, v79
	v_cvt_f32_ubyte3_e32 v127, v79
	v_pk_fma_f32 v[62:63], v[58:59], v[102:103], v[62:63] op_sel_hi:[0,1,1]
	v_cvt_f32_ubyte0_e32 v96, v82
	v_cvt_f32_ubyte1_e32 v97, v82
	v_pk_fma_f32 v[60:61], v[58:59], v[126:127], v[60:61] op_sel_hi:[0,1,1]
	v_cvt_f32_ubyte2_e32 v100, v82
	v_cvt_f32_ubyte3_e32 v101, v82
	v_pk_fma_f32 v[90:91], v[50:51], v[96:97], v[90:91] op_sel:[1,0,0]
	v_cvt_f32_ubyte0_e32 v102, v83
	v_cvt_f32_ubyte1_e32 v103, v83
	v_pk_fma_f32 v[88:89], v[50:51], v[100:101], v[88:89] op_sel:[1,0,0]
	v_cvt_f32_ubyte2_e32 v126, v83
	v_cvt_f32_ubyte3_e32 v127, v83
	v_pk_fma_f32 v[84:85], v[58:59], v[102:103], v[84:85] op_sel:[1,0,0]
	v_cvt_f32_ubyte0_e32 v96, v86
	v_cvt_f32_ubyte1_e32 v97, v86
	v_pk_fma_f32 v[80:81], v[58:59], v[126:127], v[80:81] op_sel:[1,0,0]
	v_and_b32_e32 v74, s34, v170
	v_and_b32_e32 v75, s35, v170
	v_and_b32_e32 v78, s34, v171
	v_and_b32_e32 v79, s35, v171
	v_cvt_f32_ubyte2_e32 v100, v86
	v_cvt_f32_ubyte3_e32 v101, v86
	v_pk_fma_f32 v[76:77], v[50:51], v[96:97], v[76:77] op_sel:[1,0,0]
	v_cvt_f32_ubyte0_e32 v102, v87
	v_cvt_f32_ubyte1_e32 v103, v87
	v_pk_fma_f32 v[68:69], v[50:51], v[100:101], v[68:69] op_sel:[1,0,0]
	v_cvt_f32_ubyte2_e32 v126, v87
	v_cvt_f32_ubyte3_e32 v127, v87
	v_pk_fma_f32 v[62:63], v[58:59], v[102:103], v[62:63] op_sel:[1,0,0]
	v_cvt_f32_ubyte0_e32 v96, v74
	v_cvt_f32_ubyte1_e32 v97, v74
	v_pk_fma_f32 v[60:61], v[58:59], v[126:127], v[60:61] op_sel:[1,0,0]
	v_cvt_f32_ubyte2_e32 v100, v74
	v_cvt_f32_ubyte3_e32 v101, v74
	v_pk_fma_f32 v[90:91], v[52:53], v[96:97], v[90:91] op_sel_hi:[0,1,1]
	v_cvt_f32_ubyte0_e32 v102, v75
	v_cvt_f32_ubyte1_e32 v103, v75
	v_pk_fma_f32 v[88:89], v[52:53], v[100:101], v[88:89] op_sel_hi:[0,1,1]
	v_cvt_f32_ubyte2_e32 v126, v75
	v_cvt_f32_ubyte3_e32 v127, v75
	v_pk_fma_f32 v[84:85], v[64:65], v[102:103], v[84:85] op_sel_hi:[0,1,1]
	v_cvt_f32_ubyte0_e32 v96, v78
	v_cvt_f32_ubyte1_e32 v97, v78
	v_pk_fma_f32 v[80:81], v[64:65], v[126:127], v[80:81] op_sel_hi:[0,1,1]
	v_and_b32_e32 v82, s34, v172
	v_and_b32_e32 v83, s35, v172
	v_and_b32_e32 v86, s34, v173
	v_and_b32_e32 v87, s35, v173
	v_cvt_f32_ubyte2_e32 v100, v78
	v_cvt_f32_ubyte3_e32 v101, v78
	v_pk_fma_f32 v[76:77], v[52:53], v[96:97], v[76:77] op_sel_hi:[0,1,1]
	v_cvt_f32_ubyte0_e32 v102, v79
	v_cvt_f32_ubyte1_e32 v103, v79
	v_pk_fma_f32 v[68:69], v[52:53], v[100:101], v[68:69] op_sel_hi:[0,1,1]
	v_cvt_f32_ubyte2_e32 v126, v79
	v_cvt_f32_ubyte3_e32 v127, v79
	v_pk_fma_f32 v[62:63], v[64:65], v[102:103], v[62:63] op_sel_hi:[0,1,1]
	v_cvt_f32_ubyte0_e32 v96, v82
	v_cvt_f32_ubyte1_e32 v97, v82
	v_pk_fma_f32 v[60:61], v[64:65], v[126:127], v[60:61] op_sel_hi:[0,1,1]
	v_cvt_f32_ubyte2_e32 v100, v82
	v_cvt_f32_ubyte3_e32 v101, v82
	v_pk_fma_f32 v[90:91], v[52:53], v[96:97], v[90:91] op_sel:[1,0,0]
	v_cvt_f32_ubyte0_e32 v102, v83
	v_cvt_f32_ubyte1_e32 v103, v83
	v_pk_fma_f32 v[88:89], v[52:53], v[100:101], v[88:89] op_sel:[1,0,0]
	v_cvt_f32_ubyte2_e32 v126, v83
	v_cvt_f32_ubyte3_e32 v127, v83
	v_pk_fma_f32 v[84:85], v[64:65], v[102:103], v[84:85] op_sel:[1,0,0]
	v_cvt_f32_ubyte0_e32 v96, v86
	v_cvt_f32_ubyte1_e32 v97, v86
	v_pk_fma_f32 v[80:81], v[64:65], v[126:127], v[80:81] op_sel:[1,0,0]
	v_and_b32_e32 v74, s34, v174
	v_and_b32_e32 v75, s35, v174
	v_and_b32_e32 v78, s34, v175
	v_and_b32_e32 v79, s35, v175
	v_cvt_f32_ubyte2_e32 v100, v86
	v_cvt_f32_ubyte3_e32 v101, v86
	v_pk_fma_f32 v[76:77], v[52:53], v[96:97], v[76:77] op_sel:[1,0,0]
	v_cvt_f32_ubyte0_e32 v102, v87
	v_cvt_f32_ubyte1_e32 v103, v87
	v_pk_fma_f32 v[68:69], v[52:53], v[100:101], v[68:69] op_sel:[1,0,0]
	v_cvt_f32_ubyte2_e32 v126, v87
	v_cvt_f32_ubyte3_e32 v127, v87
	v_pk_fma_f32 v[62:63], v[64:65], v[102:103], v[62:63] op_sel:[1,0,0]
	v_cvt_f32_ubyte0_e32 v96, v74
	v_cvt_f32_ubyte1_e32 v97, v74
	v_pk_fma_f32 v[60:61], v[64:65], v[126:127], v[60:61] op_sel:[1,0,0]
	v_cvt_f32_ubyte2_e32 v100, v74
	v_cvt_f32_ubyte3_e32 v101, v74
	v_pk_fma_f32 v[90:91], v[54:55], v[96:97], v[90:91] op_sel_hi:[0,1,1]
	v_cvt_f32_ubyte0_e32 v102, v75
	v_cvt_f32_ubyte1_e32 v103, v75
	v_pk_fma_f32 v[88:89], v[54:55], v[100:101], v[88:89] op_sel_hi:[0,1,1]
	v_cvt_f32_ubyte2_e32 v126, v75
	v_cvt_f32_ubyte3_e32 v127, v75
	v_pk_fma_f32 v[84:85], v[66:67], v[102:103], v[84:85] op_sel_hi:[0,1,1]
	v_cvt_f32_ubyte0_e32 v96, v78
	v_cvt_f32_ubyte1_e32 v97, v78
	v_pk_fma_f32 v[80:81], v[66:67], v[126:127], v[80:81] op_sel_hi:[0,1,1]
	v_and_b32_e32 v82, s34, v176
	v_and_b32_e32 v83, s35, v176
	v_and_b32_e32 v86, s34, v177
	v_and_b32_e32 v87, s35, v177
	v_cvt_f32_ubyte2_e32 v100, v78
	v_cvt_f32_ubyte3_e32 v101, v78
	v_pk_fma_f32 v[76:77], v[54:55], v[96:97], v[76:77] op_sel_hi:[0,1,1]
	v_cvt_f32_ubyte0_e32 v102, v79
	v_cvt_f32_ubyte1_e32 v103, v79
	v_pk_fma_f32 v[68:69], v[54:55], v[100:101], v[68:69] op_sel_hi:[0,1,1]
	v_cvt_f32_ubyte2_e32 v126, v79
	v_cvt_f32_ubyte3_e32 v127, v79
	v_pk_fma_f32 v[62:63], v[66:67], v[102:103], v[62:63] op_sel_hi:[0,1,1]
	v_cvt_f32_ubyte0_e32 v96, v82
	v_cvt_f32_ubyte1_e32 v97, v82
	v_pk_fma_f32 v[60:61], v[66:67], v[126:127], v[60:61] op_sel_hi:[0,1,1]
	v_cvt_f32_ubyte2_e32 v100, v82
	v_cvt_f32_ubyte3_e32 v101, v82
	v_pk_fma_f32 v[90:91], v[54:55], v[96:97], v[90:91] op_sel:[1,0,0]
	v_cvt_f32_ubyte0_e32 v102, v83
	v_cvt_f32_ubyte1_e32 v103, v83
	v_pk_fma_f32 v[88:89], v[54:55], v[100:101], v[88:89] op_sel:[1,0,0]
	v_cvt_f32_ubyte2_e32 v126, v83
	v_cvt_f32_ubyte3_e32 v127, v83
	v_pk_fma_f32 v[84:85], v[66:67], v[102:103], v[84:85] op_sel:[1,0,0]
	v_cvt_f32_ubyte0_e32 v96, v86
	v_cvt_f32_ubyte1_e32 v97, v86
	v_pk_fma_f32 v[80:81], v[66:67], v[126:127], v[80:81] op_sel:[1,0,0]
	v_cvt_f32_ubyte2_e32 v100, v86
	v_cvt_f32_ubyte3_e32 v101, v86
	v_pk_fma_f32 v[76:77], v[54:55], v[96:97], v[76:77] op_sel:[1,0,0]
	v_cvt_f32_ubyte0_e32 v102, v87
	v_cvt_f32_ubyte1_e32 v103, v87
	v_pk_fma_f32 v[68:69], v[54:55], v[100:101], v[68:69] op_sel:[1,0,0]
	v_cvt_f32_ubyte2_e32 v126, v87
	v_cvt_f32_ubyte3_e32 v127, v87
	v_pk_fma_f32 v[62:63], v[66:67], v[102:103], v[62:63] op_sel:[1,0,0]
	v_pk_fma_f32 v[60:61], v[66:67], v[126:127], v[60:61] op_sel:[1,0,0]
	s_waitcnt lgkmcnt(0)
	v_lshl_add_u32 v70, v70, 9, v98
	v_lshl_add_u32 v71, v71, 9, v98
	v_lshl_add_u32 v72, v72, 9, v98
	v_lshl_add_u32 v73, v73, 9, v98
	v_lshl_add_u32 v92, v92, 9, v98
	v_lshl_add_u32 v93, v93, 9, v98
	v_lshl_add_u32 v94, v94, 9, v98
	v_lshl_add_u32 v95, v95, 9, v98
	global_load_dwordx2 v[162:163], v70, s[36:37]
	global_load_dwordx2 v[164:165], v71, s[36:37]
	global_load_dwordx2 v[166:167], v72, s[36:37]
	global_load_dwordx2 v[168:169], v73, s[36:37]
	global_load_dwordx2 v[170:171], v92, s[36:37]
	global_load_dwordx2 v[172:173], v93, s[36:37]
	global_load_dwordx2 v[174:175], v94, s[36:37]
	global_load_dwordx2 v[176:177], v95, s[36:37]
	ds_read_b128 v[70:73], v128 offset:448
	ds_read_b128 v[92:95], v128 offset:464
	ds_read_b128 v[48:51], v128 offset:800
	ds_read_b128 v[52:55], v128 offset:816
	ds_read_b128 v[56:59], v128 offset:1824
	ds_read_b128 v[64:67], v128 offset:1840
	s_waitcnt vmcnt(40)
	v_and_b32_e32 v74, s34, v178
	v_and_b32_e32 v75, s35, v178
	v_and_b32_e32 v78, s34, v179
	v_and_b32_e32 v79, s35, v179
	v_cvt_f32_ubyte0_e32 v96, v74
	v_cvt_f32_ubyte1_e32 v97, v74
	v_cvt_f32_ubyte2_e32 v100, v74
	v_cvt_f32_ubyte3_e32 v101, v74
	v_pk_fma_f32 v[90:91], v[32:33], v[96:97], v[90:91] op_sel_hi:[0,1,1]
	v_cvt_f32_ubyte0_e32 v102, v75
	v_cvt_f32_ubyte1_e32 v103, v75
	v_pk_fma_f32 v[88:89], v[32:33], v[100:101], v[88:89] op_sel_hi:[0,1,1]
	v_cvt_f32_ubyte2_e32 v126, v75
	v_cvt_f32_ubyte3_e32 v127, v75
	v_pk_fma_f32 v[84:85], v[40:41], v[102:103], v[84:85] op_sel_hi:[0,1,1]
	v_cvt_f32_ubyte0_e32 v96, v78
	v_cvt_f32_ubyte1_e32 v97, v78
	v_pk_fma_f32 v[80:81], v[40:41], v[126:127], v[80:81] op_sel_hi:[0,1,1]
	v_and_b32_e32 v82, s34, v180
	v_and_b32_e32 v83, s35, v180
	v_and_b32_e32 v86, s34, v181
	v_and_b32_e32 v87, s35, v181
	v_cvt_f32_ubyte2_e32 v100, v78
	v_cvt_f32_ubyte3_e32 v101, v78
	v_pk_fma_f32 v[76:77], v[32:33], v[96:97], v[76:77] op_sel_hi:[0,1,1]
	v_cvt_f32_ubyte0_e32 v102, v79
	v_cvt_f32_ubyte1_e32 v103, v79
	v_pk_fma_f32 v[68:69], v[32:33], v[100:101], v[68:69] op_sel_hi:[0,1,1]
	v_cvt_f32_ubyte2_e32 v126, v79
	v_cvt_f32_ubyte3_e32 v127, v79
	v_pk_fma_f32 v[62:63], v[40:41], v[102:103], v[62:63] op_sel_hi:[0,1,1]
	v_cvt_f32_ubyte0_e32 v96, v82
	v_cvt_f32_ubyte1_e32 v97, v82
	v_pk_fma_f32 v[60:61], v[40:41], v[126:127], v[60:61] op_sel_hi:[0,1,1]
	v_cvt_f32_ubyte2_e32 v100, v82
	v_cvt_f32_ubyte3_e32 v101, v82
	v_pk_fma_f32 v[90:91], v[32:33], v[96:97], v[90:91] op_sel:[1,0,0]
	v_cvt_f32_ubyte0_e32 v102, v83
	v_cvt_f32_ubyte1_e32 v103, v83
	v_pk_fma_f32 v[88:89], v[32:33], v[100:101], v[88:89] op_sel:[1,0,0]
	v_cvt_f32_ubyte2_e32 v126, v83
	v_cvt_f32_ubyte3_e32 v127, v83
	v_pk_fma_f32 v[84:85], v[40:41], v[102:103], v[84:85] op_sel:[1,0,0]
	v_cvt_f32_ubyte0_e32 v96, v86
	v_cvt_f32_ubyte1_e32 v97, v86
	v_pk_fma_f32 v[80:81], v[40:41], v[126:127], v[80:81] op_sel:[1,0,0]
	v_and_b32_e32 v74, s34, v182
	v_and_b32_e32 v75, s35, v182
	v_and_b32_e32 v78, s34, v183
	v_and_b32_e32 v79, s35, v183
	v_cvt_f32_ubyte2_e32 v100, v86
	v_cvt_f32_ubyte3_e32 v101, v86
	v_pk_fma_f32 v[76:77], v[32:33], v[96:97], v[76:77] op_sel:[1,0,0]
	v_cvt_f32_ubyte0_e32 v102, v87
	v_cvt_f32_ubyte1_e32 v103, v87
	v_pk_fma_f32 v[68:69], v[32:33], v[100:101], v[68:69] op_sel:[1,0,0]
	v_cvt_f32_ubyte2_e32 v126, v87
	v_cvt_f32_ubyte3_e32 v127, v87
	v_pk_fma_f32 v[62:63], v[40:41], v[102:103], v[62:63] op_sel:[1,0,0]
	v_cvt_f32_ubyte0_e32 v96, v74
	v_cvt_f32_ubyte1_e32 v97, v74
	v_pk_fma_f32 v[60:61], v[40:41], v[126:127], v[60:61] op_sel:[1,0,0]
	v_cvt_f32_ubyte2_e32 v100, v74
	v_cvt_f32_ubyte3_e32 v101, v74
	v_pk_fma_f32 v[90:91], v[34:35], v[96:97], v[90:91] op_sel_hi:[0,1,1]
	v_cvt_f32_ubyte0_e32 v102, v75
	v_cvt_f32_ubyte1_e32 v103, v75
	v_pk_fma_f32 v[88:89], v[34:35], v[100:101], v[88:89] op_sel_hi:[0,1,1]
	v_cvt_f32_ubyte2_e32 v126, v75
	v_cvt_f32_ubyte3_e32 v127, v75
	v_pk_fma_f32 v[84:85], v[42:43], v[102:103], v[84:85] op_sel_hi:[0,1,1]
	v_cvt_f32_ubyte0_e32 v96, v78
	v_cvt_f32_ubyte1_e32 v97, v78
	v_pk_fma_f32 v[80:81], v[42:43], v[126:127], v[80:81] op_sel_hi:[0,1,1]
	v_and_b32_e32 v82, s34, v184
	v_and_b32_e32 v83, s35, v184
	v_and_b32_e32 v86, s34, v185
	v_and_b32_e32 v87, s35, v185
	v_cvt_f32_ubyte2_e32 v100, v78
	v_cvt_f32_ubyte3_e32 v101, v78
	v_pk_fma_f32 v[76:77], v[34:35], v[96:97], v[76:77] op_sel_hi:[0,1,1]
	v_cvt_f32_ubyte0_e32 v102, v79
	v_cvt_f32_ubyte1_e32 v103, v79
	v_pk_fma_f32 v[68:69], v[34:35], v[100:101], v[68:69] op_sel_hi:[0,1,1]
	v_cvt_f32_ubyte2_e32 v126, v79
	v_cvt_f32_ubyte3_e32 v127, v79
	v_pk_fma_f32 v[62:63], v[42:43], v[102:103], v[62:63] op_sel_hi:[0,1,1]
	v_cvt_f32_ubyte0_e32 v96, v82
	v_cvt_f32_ubyte1_e32 v97, v82
	v_pk_fma_f32 v[60:61], v[42:43], v[126:127], v[60:61] op_sel_hi:[0,1,1]
	v_cvt_f32_ubyte2_e32 v100, v82
	v_cvt_f32_ubyte3_e32 v101, v82
	v_pk_fma_f32 v[90:91], v[34:35], v[96:97], v[90:91] op_sel:[1,0,0]
	v_cvt_f32_ubyte0_e32 v102, v83
	v_cvt_f32_ubyte1_e32 v103, v83
	v_pk_fma_f32 v[88:89], v[34:35], v[100:101], v[88:89] op_sel:[1,0,0]
	v_cvt_f32_ubyte2_e32 v126, v83
	v_cvt_f32_ubyte3_e32 v127, v83
	v_pk_fma_f32 v[84:85], v[42:43], v[102:103], v[84:85] op_sel:[1,0,0]
	v_cvt_f32_ubyte0_e32 v96, v86
	v_cvt_f32_ubyte1_e32 v97, v86
	v_pk_fma_f32 v[80:81], v[42:43], v[126:127], v[80:81] op_sel:[1,0,0]
	v_and_b32_e32 v74, s34, v186
	v_and_b32_e32 v75, s35, v186
	v_and_b32_e32 v78, s34, v187
	v_and_b32_e32 v79, s35, v187
	v_cvt_f32_ubyte2_e32 v100, v86
	v_cvt_f32_ubyte3_e32 v101, v86
	v_pk_fma_f32 v[76:77], v[34:35], v[96:97], v[76:77] op_sel:[1,0,0]
	v_cvt_f32_ubyte0_e32 v102, v87
	v_cvt_f32_ubyte1_e32 v103, v87
	v_pk_fma_f32 v[68:69], v[34:35], v[100:101], v[68:69] op_sel:[1,0,0]
	v_cvt_f32_ubyte2_e32 v126, v87
	v_cvt_f32_ubyte3_e32 v127, v87
	v_pk_fma_f32 v[62:63], v[42:43], v[102:103], v[62:63] op_sel:[1,0,0]
	v_cvt_f32_ubyte0_e32 v96, v74
	v_cvt_f32_ubyte1_e32 v97, v74
	v_pk_fma_f32 v[60:61], v[42:43], v[126:127], v[60:61] op_sel:[1,0,0]
	v_cvt_f32_ubyte2_e32 v100, v74
	v_cvt_f32_ubyte3_e32 v101, v74
	v_pk_fma_f32 v[90:91], v[36:37], v[96:97], v[90:91] op_sel_hi:[0,1,1]
	v_cvt_f32_ubyte0_e32 v102, v75
	v_cvt_f32_ubyte1_e32 v103, v75
	v_pk_fma_f32 v[88:89], v[36:37], v[100:101], v[88:89] op_sel_hi:[0,1,1]
	v_cvt_f32_ubyte2_e32 v126, v75
	v_cvt_f32_ubyte3_e32 v127, v75
	v_pk_fma_f32 v[84:85], v[44:45], v[102:103], v[84:85] op_sel_hi:[0,1,1]
	v_cvt_f32_ubyte0_e32 v96, v78
	v_cvt_f32_ubyte1_e32 v97, v78
	v_pk_fma_f32 v[80:81], v[44:45], v[126:127], v[80:81] op_sel_hi:[0,1,1]
	v_and_b32_e32 v82, s34, v188
	v_and_b32_e32 v83, s35, v188
	v_and_b32_e32 v86, s34, v189
	v_and_b32_e32 v87, s35, v189
	v_cvt_f32_ubyte2_e32 v100, v78
	v_cvt_f32_ubyte3_e32 v101, v78
	v_pk_fma_f32 v[76:77], v[36:37], v[96:97], v[76:77] op_sel_hi:[0,1,1]
	v_cvt_f32_ubyte0_e32 v102, v79
	v_cvt_f32_ubyte1_e32 v103, v79
	v_pk_fma_f32 v[68:69], v[36:37], v[100:101], v[68:69] op_sel_hi:[0,1,1]
	v_cvt_f32_ubyte2_e32 v126, v79
	v_cvt_f32_ubyte3_e32 v127, v79
	v_pk_fma_f32 v[62:63], v[44:45], v[102:103], v[62:63] op_sel_hi:[0,1,1]
	v_cvt_f32_ubyte0_e32 v96, v82
	v_cvt_f32_ubyte1_e32 v97, v82
	v_pk_fma_f32 v[60:61], v[44:45], v[126:127], v[60:61] op_sel_hi:[0,1,1]
	v_cvt_f32_ubyte2_e32 v100, v82
	v_cvt_f32_ubyte3_e32 v101, v82
	v_pk_fma_f32 v[90:91], v[36:37], v[96:97], v[90:91] op_sel:[1,0,0]
	v_cvt_f32_ubyte0_e32 v102, v83
	v_cvt_f32_ubyte1_e32 v103, v83
	v_pk_fma_f32 v[88:89], v[36:37], v[100:101], v[88:89] op_sel:[1,0,0]
	v_cvt_f32_ubyte2_e32 v126, v83
	v_cvt_f32_ubyte3_e32 v127, v83
	v_pk_fma_f32 v[84:85], v[44:45], v[102:103], v[84:85] op_sel:[1,0,0]
	v_cvt_f32_ubyte0_e32 v96, v86
	v_cvt_f32_ubyte1_e32 v97, v86
	v_pk_fma_f32 v[80:81], v[44:45], v[126:127], v[80:81] op_sel:[1,0,0]
	v_and_b32_e32 v74, s34, v190
	v_and_b32_e32 v75, s35, v190
	v_and_b32_e32 v78, s34, v191
	v_and_b32_e32 v79, s35, v191
	v_cvt_f32_ubyte2_e32 v100, v86
	v_cvt_f32_ubyte3_e32 v101, v86
	v_pk_fma_f32 v[76:77], v[36:37], v[96:97], v[76:77] op_sel:[1,0,0]
	v_cvt_f32_ubyte0_e32 v102, v87
	v_cvt_f32_ubyte1_e32 v103, v87
	v_pk_fma_f32 v[68:69], v[36:37], v[100:101], v[68:69] op_sel:[1,0,0]
	v_cvt_f32_ubyte2_e32 v126, v87
	v_cvt_f32_ubyte3_e32 v127, v87
	v_pk_fma_f32 v[62:63], v[44:45], v[102:103], v[62:63] op_sel:[1,0,0]
	v_cvt_f32_ubyte0_e32 v96, v74
	v_cvt_f32_ubyte1_e32 v97, v74
	v_pk_fma_f32 v[60:61], v[44:45], v[126:127], v[60:61] op_sel:[1,0,0]
	v_cvt_f32_ubyte2_e32 v100, v74
	v_cvt_f32_ubyte3_e32 v101, v74
	v_pk_fma_f32 v[90:91], v[38:39], v[96:97], v[90:91] op_sel_hi:[0,1,1]
	v_cvt_f32_ubyte0_e32 v102, v75
	v_cvt_f32_ubyte1_e32 v103, v75
	v_pk_fma_f32 v[88:89], v[38:39], v[100:101], v[88:89] op_sel_hi:[0,1,1]
	v_cvt_f32_ubyte2_e32 v126, v75
	v_cvt_f32_ubyte3_e32 v127, v75
	v_pk_fma_f32 v[84:85], v[46:47], v[102:103], v[84:85] op_sel_hi:[0,1,1]
	v_cvt_f32_ubyte0_e32 v96, v78
	v_cvt_f32_ubyte1_e32 v97, v78
	v_pk_fma_f32 v[80:81], v[46:47], v[126:127], v[80:81] op_sel_hi:[0,1,1]
	v_and_b32_e32 v82, s34, v192
	v_and_b32_e32 v83, s35, v192
	v_and_b32_e32 v86, s34, v193
	v_and_b32_e32 v87, s35, v193
	v_cvt_f32_ubyte2_e32 v100, v78
	v_cvt_f32_ubyte3_e32 v101, v78
	v_pk_fma_f32 v[76:77], v[38:39], v[96:97], v[76:77] op_sel_hi:[0,1,1]
	v_cvt_f32_ubyte0_e32 v102, v79
	v_cvt_f32_ubyte1_e32 v103, v79
	v_pk_fma_f32 v[68:69], v[38:39], v[100:101], v[68:69] op_sel_hi:[0,1,1]
	v_cvt_f32_ubyte2_e32 v126, v79
	v_cvt_f32_ubyte3_e32 v127, v79
	v_pk_fma_f32 v[62:63], v[46:47], v[102:103], v[62:63] op_sel_hi:[0,1,1]
	v_cvt_f32_ubyte0_e32 v96, v82
	v_cvt_f32_ubyte1_e32 v97, v82
	v_pk_fma_f32 v[60:61], v[46:47], v[126:127], v[60:61] op_sel_hi:[0,1,1]
	v_cvt_f32_ubyte2_e32 v100, v82
	v_cvt_f32_ubyte3_e32 v101, v82
	v_pk_fma_f32 v[90:91], v[38:39], v[96:97], v[90:91] op_sel:[1,0,0]
	v_cvt_f32_ubyte0_e32 v102, v83
	v_cvt_f32_ubyte1_e32 v103, v83
	v_pk_fma_f32 v[88:89], v[38:39], v[100:101], v[88:89] op_sel:[1,0,0]
	v_cvt_f32_ubyte2_e32 v126, v83
	v_cvt_f32_ubyte3_e32 v127, v83
	v_pk_fma_f32 v[84:85], v[46:47], v[102:103], v[84:85] op_sel:[1,0,0]
	v_cvt_f32_ubyte0_e32 v96, v86
	v_cvt_f32_ubyte1_e32 v97, v86
	v_pk_fma_f32 v[80:81], v[46:47], v[126:127], v[80:81] op_sel:[1,0,0]
	v_cvt_f32_ubyte2_e32 v100, v86
	v_cvt_f32_ubyte3_e32 v101, v86
	v_pk_fma_f32 v[76:77], v[38:39], v[96:97], v[76:77] op_sel:[1,0,0]
	v_cvt_f32_ubyte0_e32 v102, v87
	v_cvt_f32_ubyte1_e32 v103, v87
	v_pk_fma_f32 v[68:69], v[38:39], v[100:101], v[68:69] op_sel:[1,0,0]
	v_cvt_f32_ubyte2_e32 v126, v87
	v_cvt_f32_ubyte3_e32 v127, v87
	v_pk_fma_f32 v[62:63], v[46:47], v[102:103], v[62:63] op_sel:[1,0,0]
	v_pk_fma_f32 v[60:61], v[46:47], v[126:127], v[60:61] op_sel:[1,0,0]
	s_waitcnt lgkmcnt(0)
	v_lshl_add_u32 v70, v70, 9, v98
	v_lshl_add_u32 v71, v71, 9, v98
	v_lshl_add_u32 v72, v72, 9, v98
	v_lshl_add_u32 v73, v73, 9, v98
	v_lshl_add_u32 v92, v92, 9, v98
	v_lshl_add_u32 v93, v93, 9, v98
	v_lshl_add_u32 v94, v94, 9, v98
	v_lshl_add_u32 v95, v95, 9, v98
	global_load_dwordx2 v[178:179], v70, s[36:37]
	global_load_dwordx2 v[180:181], v71, s[36:37]
	global_load_dwordx2 v[182:183], v72, s[36:37]
	global_load_dwordx2 v[184:185], v73, s[36:37]
	global_load_dwordx2 v[186:187], v92, s[36:37]
	global_load_dwordx2 v[188:189], v93, s[36:37]
	global_load_dwordx2 v[190:191], v94, s[36:37]
	global_load_dwordx2 v[192:193], v95, s[36:37]
	ds_read_b128 v[70:73], v128 offset:480
	ds_read_b128 v[92:95], v128 offset:496
	ds_read_b128 v[32:35], v128 offset:832
	ds_read_b128 v[36:39], v128 offset:848
	ds_read_b128 v[40:43], v128 offset:1856
	ds_read_b128 v[44:47], v128 offset:1872
	s_waitcnt vmcnt(40)
	v_and_b32_e32 v74, s34, v194
	v_and_b32_e32 v75, s35, v194
	v_and_b32_e32 v78, s34, v195
	v_and_b32_e32 v79, s35, v195
	v_cvt_f32_ubyte0_e32 v96, v74
	v_cvt_f32_ubyte1_e32 v97, v74
	v_cvt_f32_ubyte2_e32 v100, v74
	v_cvt_f32_ubyte3_e32 v101, v74
	v_pk_fma_f32 v[90:91], v[48:49], v[96:97], v[90:91] op_sel_hi:[0,1,1]
	v_cvt_f32_ubyte0_e32 v102, v75
	v_cvt_f32_ubyte1_e32 v103, v75
	v_pk_fma_f32 v[88:89], v[48:49], v[100:101], v[88:89] op_sel_hi:[0,1,1]
	v_cvt_f32_ubyte2_e32 v126, v75
	v_cvt_f32_ubyte3_e32 v127, v75
	v_pk_fma_f32 v[84:85], v[56:57], v[102:103], v[84:85] op_sel_hi:[0,1,1]
	v_cvt_f32_ubyte0_e32 v96, v78
	v_cvt_f32_ubyte1_e32 v97, v78
	v_pk_fma_f32 v[80:81], v[56:57], v[126:127], v[80:81] op_sel_hi:[0,1,1]
	v_and_b32_e32 v82, s34, v196
	v_and_b32_e32 v83, s35, v196
	v_and_b32_e32 v86, s34, v197
	v_and_b32_e32 v87, s35, v197
	v_cvt_f32_ubyte2_e32 v100, v78
	v_cvt_f32_ubyte3_e32 v101, v78
	v_pk_fma_f32 v[76:77], v[48:49], v[96:97], v[76:77] op_sel_hi:[0,1,1]
	v_cvt_f32_ubyte0_e32 v102, v79
	v_cvt_f32_ubyte1_e32 v103, v79
	v_pk_fma_f32 v[68:69], v[48:49], v[100:101], v[68:69] op_sel_hi:[0,1,1]
	v_cvt_f32_ubyte2_e32 v126, v79
	v_cvt_f32_ubyte3_e32 v127, v79
	v_pk_fma_f32 v[62:63], v[56:57], v[102:103], v[62:63] op_sel_hi:[0,1,1]
	v_cvt_f32_ubyte0_e32 v96, v82
	v_cvt_f32_ubyte1_e32 v97, v82
	v_pk_fma_f32 v[60:61], v[56:57], v[126:127], v[60:61] op_sel_hi:[0,1,1]
	v_cvt_f32_ubyte2_e32 v100, v82
	v_cvt_f32_ubyte3_e32 v101, v82
	v_pk_fma_f32 v[90:91], v[48:49], v[96:97], v[90:91] op_sel:[1,0,0]
	v_cvt_f32_ubyte0_e32 v102, v83
	v_cvt_f32_ubyte1_e32 v103, v83
	v_pk_fma_f32 v[88:89], v[48:49], v[100:101], v[88:89] op_sel:[1,0,0]
	v_cvt_f32_ubyte2_e32 v126, v83
	v_cvt_f32_ubyte3_e32 v127, v83
	v_pk_fma_f32 v[84:85], v[56:57], v[102:103], v[84:85] op_sel:[1,0,0]
	v_cvt_f32_ubyte0_e32 v96, v86
	v_cvt_f32_ubyte1_e32 v97, v86
	v_pk_fma_f32 v[80:81], v[56:57], v[126:127], v[80:81] op_sel:[1,0,0]
	v_and_b32_e32 v74, s34, v198
	v_and_b32_e32 v75, s35, v198
	v_and_b32_e32 v78, s34, v199
	v_and_b32_e32 v79, s35, v199
	v_cvt_f32_ubyte2_e32 v100, v86
	v_cvt_f32_ubyte3_e32 v101, v86
	v_pk_fma_f32 v[76:77], v[48:49], v[96:97], v[76:77] op_sel:[1,0,0]
	v_cvt_f32_ubyte0_e32 v102, v87
	v_cvt_f32_ubyte1_e32 v103, v87
	v_pk_fma_f32 v[68:69], v[48:49], v[100:101], v[68:69] op_sel:[1,0,0]
	v_cvt_f32_ubyte2_e32 v126, v87
	v_cvt_f32_ubyte3_e32 v127, v87
	v_pk_fma_f32 v[62:63], v[56:57], v[102:103], v[62:63] op_sel:[1,0,0]
	v_cvt_f32_ubyte0_e32 v96, v74
	v_cvt_f32_ubyte1_e32 v97, v74
	v_pk_fma_f32 v[60:61], v[56:57], v[126:127], v[60:61] op_sel:[1,0,0]
	v_cvt_f32_ubyte2_e32 v100, v74
	v_cvt_f32_ubyte3_e32 v101, v74
	v_pk_fma_f32 v[90:91], v[50:51], v[96:97], v[90:91] op_sel_hi:[0,1,1]
	v_cvt_f32_ubyte0_e32 v102, v75
	v_cvt_f32_ubyte1_e32 v103, v75
	v_pk_fma_f32 v[88:89], v[50:51], v[100:101], v[88:89] op_sel_hi:[0,1,1]
	v_cvt_f32_ubyte2_e32 v126, v75
	v_cvt_f32_ubyte3_e32 v127, v75
	v_pk_fma_f32 v[84:85], v[58:59], v[102:103], v[84:85] op_sel_hi:[0,1,1]
	v_cvt_f32_ubyte0_e32 v96, v78
	v_cvt_f32_ubyte1_e32 v97, v78
	v_pk_fma_f32 v[80:81], v[58:59], v[126:127], v[80:81] op_sel_hi:[0,1,1]
	v_and_b32_e32 v82, s34, v200
	v_and_b32_e32 v83, s35, v200
	v_and_b32_e32 v86, s34, v201
	v_and_b32_e32 v87, s35, v201
	v_cvt_f32_ubyte2_e32 v100, v78
	v_cvt_f32_ubyte3_e32 v101, v78
	v_pk_fma_f32 v[76:77], v[50:51], v[96:97], v[76:77] op_sel_hi:[0,1,1]
	v_cvt_f32_ubyte0_e32 v102, v79
	v_cvt_f32_ubyte1_e32 v103, v79
	v_pk_fma_f32 v[68:69], v[50:51], v[100:101], v[68:69] op_sel_hi:[0,1,1]
	v_cvt_f32_ubyte2_e32 v126, v79
	v_cvt_f32_ubyte3_e32 v127, v79
	v_pk_fma_f32 v[62:63], v[58:59], v[102:103], v[62:63] op_sel_hi:[0,1,1]
	v_cvt_f32_ubyte0_e32 v96, v82
	v_cvt_f32_ubyte1_e32 v97, v82
	v_pk_fma_f32 v[60:61], v[58:59], v[126:127], v[60:61] op_sel_hi:[0,1,1]
	v_cvt_f32_ubyte2_e32 v100, v82
	v_cvt_f32_ubyte3_e32 v101, v82
	v_pk_fma_f32 v[90:91], v[50:51], v[96:97], v[90:91] op_sel:[1,0,0]
	v_cvt_f32_ubyte0_e32 v102, v83
	v_cvt_f32_ubyte1_e32 v103, v83
	v_pk_fma_f32 v[88:89], v[50:51], v[100:101], v[88:89] op_sel:[1,0,0]
	v_cvt_f32_ubyte2_e32 v126, v83
	v_cvt_f32_ubyte3_e32 v127, v83
	v_pk_fma_f32 v[84:85], v[58:59], v[102:103], v[84:85] op_sel:[1,0,0]
	v_cvt_f32_ubyte0_e32 v96, v86
	v_cvt_f32_ubyte1_e32 v97, v86
	v_pk_fma_f32 v[80:81], v[58:59], v[126:127], v[80:81] op_sel:[1,0,0]
	v_and_b32_e32 v74, s34, v202
	v_and_b32_e32 v75, s35, v202
	v_and_b32_e32 v78, s34, v203
	v_and_b32_e32 v79, s35, v203
	v_cvt_f32_ubyte2_e32 v100, v86
	v_cvt_f32_ubyte3_e32 v101, v86
	v_pk_fma_f32 v[76:77], v[50:51], v[96:97], v[76:77] op_sel:[1,0,0]
	v_cvt_f32_ubyte0_e32 v102, v87
	v_cvt_f32_ubyte1_e32 v103, v87
	v_pk_fma_f32 v[68:69], v[50:51], v[100:101], v[68:69] op_sel:[1,0,0]
	v_cvt_f32_ubyte2_e32 v126, v87
	v_cvt_f32_ubyte3_e32 v127, v87
	v_pk_fma_f32 v[62:63], v[58:59], v[102:103], v[62:63] op_sel:[1,0,0]
	v_cvt_f32_ubyte0_e32 v96, v74
	v_cvt_f32_ubyte1_e32 v97, v74
	v_pk_fma_f32 v[60:61], v[58:59], v[126:127], v[60:61] op_sel:[1,0,0]
	v_cvt_f32_ubyte2_e32 v100, v74
	v_cvt_f32_ubyte3_e32 v101, v74
	v_pk_fma_f32 v[90:91], v[52:53], v[96:97], v[90:91] op_sel_hi:[0,1,1]
	v_cvt_f32_ubyte0_e32 v102, v75
	v_cvt_f32_ubyte1_e32 v103, v75
	v_pk_fma_f32 v[88:89], v[52:53], v[100:101], v[88:89] op_sel_hi:[0,1,1]
	v_cvt_f32_ubyte2_e32 v126, v75
	v_cvt_f32_ubyte3_e32 v127, v75
	v_pk_fma_f32 v[84:85], v[64:65], v[102:103], v[84:85] op_sel_hi:[0,1,1]
	v_cvt_f32_ubyte0_e32 v96, v78
	v_cvt_f32_ubyte1_e32 v97, v78
	v_pk_fma_f32 v[80:81], v[64:65], v[126:127], v[80:81] op_sel_hi:[0,1,1]
	v_and_b32_e32 v82, s34, v204
	v_and_b32_e32 v83, s35, v204
	v_and_b32_e32 v86, s34, v205
	v_and_b32_e32 v87, s35, v205
	v_cvt_f32_ubyte2_e32 v100, v78
	v_cvt_f32_ubyte3_e32 v101, v78
	v_pk_fma_f32 v[76:77], v[52:53], v[96:97], v[76:77] op_sel_hi:[0,1,1]
	v_cvt_f32_ubyte0_e32 v102, v79
	v_cvt_f32_ubyte1_e32 v103, v79
	v_pk_fma_f32 v[68:69], v[52:53], v[100:101], v[68:69] op_sel_hi:[0,1,1]
	v_cvt_f32_ubyte2_e32 v126, v79
	v_cvt_f32_ubyte3_e32 v127, v79
	v_pk_fma_f32 v[62:63], v[64:65], v[102:103], v[62:63] op_sel_hi:[0,1,1]
	v_cvt_f32_ubyte0_e32 v96, v82
	v_cvt_f32_ubyte1_e32 v97, v82
	v_pk_fma_f32 v[60:61], v[64:65], v[126:127], v[60:61] op_sel_hi:[0,1,1]
	v_cvt_f32_ubyte2_e32 v100, v82
	v_cvt_f32_ubyte3_e32 v101, v82
	v_pk_fma_f32 v[90:91], v[52:53], v[96:97], v[90:91] op_sel:[1,0,0]
	v_cvt_f32_ubyte0_e32 v102, v83
	v_cvt_f32_ubyte1_e32 v103, v83
	v_pk_fma_f32 v[88:89], v[52:53], v[100:101], v[88:89] op_sel:[1,0,0]
	v_cvt_f32_ubyte2_e32 v126, v83
	v_cvt_f32_ubyte3_e32 v127, v83
	v_pk_fma_f32 v[84:85], v[64:65], v[102:103], v[84:85] op_sel:[1,0,0]
	v_cvt_f32_ubyte0_e32 v96, v86
	v_cvt_f32_ubyte1_e32 v97, v86
	v_pk_fma_f32 v[80:81], v[64:65], v[126:127], v[80:81] op_sel:[1,0,0]
	v_and_b32_e32 v74, s34, v206
	v_and_b32_e32 v75, s35, v206
	v_and_b32_e32 v78, s34, v207
	v_and_b32_e32 v79, s35, v207
	v_cvt_f32_ubyte2_e32 v100, v86
	v_cvt_f32_ubyte3_e32 v101, v86
	v_pk_fma_f32 v[76:77], v[52:53], v[96:97], v[76:77] op_sel:[1,0,0]
	v_cvt_f32_ubyte0_e32 v102, v87
	v_cvt_f32_ubyte1_e32 v103, v87
	v_pk_fma_f32 v[68:69], v[52:53], v[100:101], v[68:69] op_sel:[1,0,0]
	v_cvt_f32_ubyte2_e32 v126, v87
	v_cvt_f32_ubyte3_e32 v127, v87
	v_pk_fma_f32 v[62:63], v[64:65], v[102:103], v[62:63] op_sel:[1,0,0]
	v_cvt_f32_ubyte0_e32 v96, v74
	v_cvt_f32_ubyte1_e32 v97, v74
	v_pk_fma_f32 v[60:61], v[64:65], v[126:127], v[60:61] op_sel:[1,0,0]
	v_cvt_f32_ubyte2_e32 v100, v74
	v_cvt_f32_ubyte3_e32 v101, v74
	v_pk_fma_f32 v[90:91], v[54:55], v[96:97], v[90:91] op_sel_hi:[0,1,1]
	v_cvt_f32_ubyte0_e32 v102, v75
	v_cvt_f32_ubyte1_e32 v103, v75
	v_pk_fma_f32 v[88:89], v[54:55], v[100:101], v[88:89] op_sel_hi:[0,1,1]
	v_cvt_f32_ubyte2_e32 v126, v75
	v_cvt_f32_ubyte3_e32 v127, v75
	v_pk_fma_f32 v[84:85], v[66:67], v[102:103], v[84:85] op_sel_hi:[0,1,1]
	v_cvt_f32_ubyte0_e32 v96, v78
	v_cvt_f32_ubyte1_e32 v97, v78
	v_pk_fma_f32 v[80:81], v[66:67], v[126:127], v[80:81] op_sel_hi:[0,1,1]
	v_and_b32_e32 v82, s34, v208
	v_and_b32_e32 v83, s35, v208
	v_and_b32_e32 v86, s34, v209
	v_and_b32_e32 v87, s35, v209
	v_cvt_f32_ubyte2_e32 v100, v78
	v_cvt_f32_ubyte3_e32 v101, v78
	v_pk_fma_f32 v[76:77], v[54:55], v[96:97], v[76:77] op_sel_hi:[0,1,1]
	v_cvt_f32_ubyte0_e32 v102, v79
	v_cvt_f32_ubyte1_e32 v103, v79
	v_pk_fma_f32 v[68:69], v[54:55], v[100:101], v[68:69] op_sel_hi:[0,1,1]
	v_cvt_f32_ubyte2_e32 v126, v79
	v_cvt_f32_ubyte3_e32 v127, v79
	v_pk_fma_f32 v[62:63], v[66:67], v[102:103], v[62:63] op_sel_hi:[0,1,1]
	v_cvt_f32_ubyte0_e32 v96, v82
	v_cvt_f32_ubyte1_e32 v97, v82
	v_pk_fma_f32 v[60:61], v[66:67], v[126:127], v[60:61] op_sel_hi:[0,1,1]
	v_cvt_f32_ubyte2_e32 v100, v82
	v_cvt_f32_ubyte3_e32 v101, v82
	v_pk_fma_f32 v[90:91], v[54:55], v[96:97], v[90:91] op_sel:[1,0,0]
	v_cvt_f32_ubyte0_e32 v102, v83
	v_cvt_f32_ubyte1_e32 v103, v83
	v_pk_fma_f32 v[88:89], v[54:55], v[100:101], v[88:89] op_sel:[1,0,0]
	v_cvt_f32_ubyte2_e32 v126, v83
	v_cvt_f32_ubyte3_e32 v127, v83
	v_pk_fma_f32 v[84:85], v[66:67], v[102:103], v[84:85] op_sel:[1,0,0]
	v_cvt_f32_ubyte0_e32 v96, v86
	v_cvt_f32_ubyte1_e32 v97, v86
	v_pk_fma_f32 v[80:81], v[66:67], v[126:127], v[80:81] op_sel:[1,0,0]
	v_cvt_f32_ubyte2_e32 v100, v86
	v_cvt_f32_ubyte3_e32 v101, v86
	v_pk_fma_f32 v[76:77], v[54:55], v[96:97], v[76:77] op_sel:[1,0,0]
	v_cvt_f32_ubyte0_e32 v102, v87
	v_cvt_f32_ubyte1_e32 v103, v87
	v_pk_fma_f32 v[68:69], v[54:55], v[100:101], v[68:69] op_sel:[1,0,0]
	v_cvt_f32_ubyte2_e32 v126, v87
	v_cvt_f32_ubyte3_e32 v127, v87
	v_pk_fma_f32 v[62:63], v[66:67], v[102:103], v[62:63] op_sel:[1,0,0]
	v_pk_fma_f32 v[60:61], v[66:67], v[126:127], v[60:61] op_sel:[1,0,0]
	s_waitcnt lgkmcnt(0)
	v_lshl_add_u32 v70, v70, 9, v98
	v_lshl_add_u32 v71, v71, 9, v98
	v_lshl_add_u32 v72, v72, 9, v98
	v_lshl_add_u32 v73, v73, 9, v98
	v_lshl_add_u32 v92, v92, 9, v98
	v_lshl_add_u32 v93, v93, 9, v98
	v_lshl_add_u32 v94, v94, 9, v98
	v_lshl_add_u32 v95, v95, 9, v98
	global_load_dwordx2 v[194:195], v70, s[36:37]
	global_load_dwordx2 v[196:197], v71, s[36:37]
	global_load_dwordx2 v[198:199], v72, s[36:37]
	global_load_dwordx2 v[200:201], v73, s[36:37]
	global_load_dwordx2 v[202:203], v92, s[36:37]
	global_load_dwordx2 v[204:205], v93, s[36:37]
	global_load_dwordx2 v[206:207], v94, s[36:37]
	global_load_dwordx2 v[208:209], v95, s[36:37]
	ds_read_b128 v[48:51], v128 offset:864
	ds_read_b128 v[52:55], v128 offset:880
	ds_read_b128 v[56:59], v128 offset:1888
	ds_read_b128 v[64:67], v128 offset:1904
	s_waitcnt vmcnt(40)
	v_and_b32_e32 v74, s34, v0
	v_and_b32_e32 v75, s35, v0
	v_and_b32_e32 v78, s34, v1
	v_and_b32_e32 v79, s35, v1
	v_cvt_f32_ubyte0_e32 v96, v74
	v_cvt_f32_ubyte1_e32 v97, v74
	v_cvt_f32_ubyte2_e32 v100, v74
	v_cvt_f32_ubyte3_e32 v101, v74
	v_pk_fma_f32 v[90:91], v[32:33], v[96:97], v[90:91] op_sel_hi:[0,1,1]
	v_cvt_f32_ubyte0_e32 v102, v75
	v_cvt_f32_ubyte1_e32 v103, v75
	v_pk_fma_f32 v[88:89], v[32:33], v[100:101], v[88:89] op_sel_hi:[0,1,1]
	v_cvt_f32_ubyte2_e32 v126, v75
	v_cvt_f32_ubyte3_e32 v127, v75
	v_pk_fma_f32 v[84:85], v[40:41], v[102:103], v[84:85] op_sel_hi:[0,1,1]
	v_cvt_f32_ubyte0_e32 v96, v78
	v_cvt_f32_ubyte1_e32 v97, v78
	v_pk_fma_f32 v[80:81], v[40:41], v[126:127], v[80:81] op_sel_hi:[0,1,1]
	v_and_b32_e32 v82, s34, v2
	v_and_b32_e32 v83, s35, v2
	v_and_b32_e32 v86, s34, v3
	v_and_b32_e32 v87, s35, v3
	v_cvt_f32_ubyte2_e32 v100, v78
	v_cvt_f32_ubyte3_e32 v101, v78
	v_pk_fma_f32 v[76:77], v[32:33], v[96:97], v[76:77] op_sel_hi:[0,1,1]
	v_cvt_f32_ubyte0_e32 v102, v79
	v_cvt_f32_ubyte1_e32 v103, v79
	v_pk_fma_f32 v[68:69], v[32:33], v[100:101], v[68:69] op_sel_hi:[0,1,1]
	v_cvt_f32_ubyte2_e32 v126, v79
	v_cvt_f32_ubyte3_e32 v127, v79
	v_pk_fma_f32 v[62:63], v[40:41], v[102:103], v[62:63] op_sel_hi:[0,1,1]
	v_cvt_f32_ubyte0_e32 v96, v82
	v_cvt_f32_ubyte1_e32 v97, v82
	v_pk_fma_f32 v[60:61], v[40:41], v[126:127], v[60:61] op_sel_hi:[0,1,1]
	v_cvt_f32_ubyte2_e32 v100, v82
	v_cvt_f32_ubyte3_e32 v101, v82
	v_pk_fma_f32 v[90:91], v[32:33], v[96:97], v[90:91] op_sel:[1,0,0]
	v_cvt_f32_ubyte0_e32 v102, v83
	v_cvt_f32_ubyte1_e32 v103, v83
	v_pk_fma_f32 v[88:89], v[32:33], v[100:101], v[88:89] op_sel:[1,0,0]
	v_cvt_f32_ubyte2_e32 v126, v83
	v_cvt_f32_ubyte3_e32 v127, v83
	v_pk_fma_f32 v[84:85], v[40:41], v[102:103], v[84:85] op_sel:[1,0,0]
	v_cvt_f32_ubyte0_e32 v96, v86
	v_cvt_f32_ubyte1_e32 v97, v86
	v_pk_fma_f32 v[80:81], v[40:41], v[126:127], v[80:81] op_sel:[1,0,0]
	v_and_b32_e32 v74, s34, v4
	v_and_b32_e32 v75, s35, v4
	v_and_b32_e32 v78, s34, v5
	v_and_b32_e32 v79, s35, v5
	v_cvt_f32_ubyte2_e32 v100, v86
	v_cvt_f32_ubyte3_e32 v101, v86
	v_pk_fma_f32 v[76:77], v[32:33], v[96:97], v[76:77] op_sel:[1,0,0]
	v_cvt_f32_ubyte0_e32 v102, v87
	v_cvt_f32_ubyte1_e32 v103, v87
	v_pk_fma_f32 v[68:69], v[32:33], v[100:101], v[68:69] op_sel:[1,0,0]
	v_cvt_f32_ubyte2_e32 v126, v87
	v_cvt_f32_ubyte3_e32 v127, v87
	v_pk_fma_f32 v[62:63], v[40:41], v[102:103], v[62:63] op_sel:[1,0,0]
	v_cvt_f32_ubyte0_e32 v96, v74
	v_cvt_f32_ubyte1_e32 v97, v74
	v_pk_fma_f32 v[60:61], v[40:41], v[126:127], v[60:61] op_sel:[1,0,0]
	v_cvt_f32_ubyte2_e32 v100, v74
	v_cvt_f32_ubyte3_e32 v101, v74
	v_pk_fma_f32 v[90:91], v[34:35], v[96:97], v[90:91] op_sel_hi:[0,1,1]
	v_cvt_f32_ubyte0_e32 v102, v75
	v_cvt_f32_ubyte1_e32 v103, v75
	v_pk_fma_f32 v[88:89], v[34:35], v[100:101], v[88:89] op_sel_hi:[0,1,1]
	v_cvt_f32_ubyte2_e32 v126, v75
	v_cvt_f32_ubyte3_e32 v127, v75
	v_pk_fma_f32 v[84:85], v[42:43], v[102:103], v[84:85] op_sel_hi:[0,1,1]
	v_cvt_f32_ubyte0_e32 v96, v78
	v_cvt_f32_ubyte1_e32 v97, v78
	v_pk_fma_f32 v[80:81], v[42:43], v[126:127], v[80:81] op_sel_hi:[0,1,1]
	v_and_b32_e32 v82, s34, v6
	v_and_b32_e32 v83, s35, v6
	v_and_b32_e32 v86, s34, v7
	v_and_b32_e32 v87, s35, v7
	v_cvt_f32_ubyte2_e32 v100, v78
	v_cvt_f32_ubyte3_e32 v101, v78
	v_pk_fma_f32 v[76:77], v[34:35], v[96:97], v[76:77] op_sel_hi:[0,1,1]
	v_cvt_f32_ubyte0_e32 v102, v79
	v_cvt_f32_ubyte1_e32 v103, v79
	v_pk_fma_f32 v[68:69], v[34:35], v[100:101], v[68:69] op_sel_hi:[0,1,1]
	v_cvt_f32_ubyte2_e32 v126, v79
	v_cvt_f32_ubyte3_e32 v127, v79
	v_pk_fma_f32 v[62:63], v[42:43], v[102:103], v[62:63] op_sel_hi:[0,1,1]
	v_cvt_f32_ubyte0_e32 v96, v82
	v_cvt_f32_ubyte1_e32 v97, v82
	v_pk_fma_f32 v[60:61], v[42:43], v[126:127], v[60:61] op_sel_hi:[0,1,1]
	v_cvt_f32_ubyte2_e32 v100, v82
	v_cvt_f32_ubyte3_e32 v101, v82
	v_pk_fma_f32 v[90:91], v[34:35], v[96:97], v[90:91] op_sel:[1,0,0]
	v_cvt_f32_ubyte0_e32 v102, v83
	v_cvt_f32_ubyte1_e32 v103, v83
	v_pk_fma_f32 v[88:89], v[34:35], v[100:101], v[88:89] op_sel:[1,0,0]
	v_cvt_f32_ubyte2_e32 v126, v83
	v_cvt_f32_ubyte3_e32 v127, v83
	v_pk_fma_f32 v[84:85], v[42:43], v[102:103], v[84:85] op_sel:[1,0,0]
	v_cvt_f32_ubyte0_e32 v96, v86
	v_cvt_f32_ubyte1_e32 v97, v86
	v_pk_fma_f32 v[80:81], v[42:43], v[126:127], v[80:81] op_sel:[1,0,0]
	v_and_b32_e32 v74, s34, v8
	v_and_b32_e32 v75, s35, v8
	v_and_b32_e32 v78, s34, v9
	v_and_b32_e32 v79, s35, v9
	v_cvt_f32_ubyte2_e32 v100, v86
	v_cvt_f32_ubyte3_e32 v101, v86
	v_pk_fma_f32 v[76:77], v[34:35], v[96:97], v[76:77] op_sel:[1,0,0]
	v_cvt_f32_ubyte0_e32 v102, v87
	v_cvt_f32_ubyte1_e32 v103, v87
	v_pk_fma_f32 v[68:69], v[34:35], v[100:101], v[68:69] op_sel:[1,0,0]
	v_cvt_f32_ubyte2_e32 v126, v87
	v_cvt_f32_ubyte3_e32 v127, v87
	v_pk_fma_f32 v[62:63], v[42:43], v[102:103], v[62:63] op_sel:[1,0,0]
	v_cvt_f32_ubyte0_e32 v96, v74
	v_cvt_f32_ubyte1_e32 v97, v74
	v_pk_fma_f32 v[60:61], v[42:43], v[126:127], v[60:61] op_sel:[1,0,0]
	v_cvt_f32_ubyte2_e32 v100, v74
	v_cvt_f32_ubyte3_e32 v101, v74
	v_pk_fma_f32 v[90:91], v[36:37], v[96:97], v[90:91] op_sel_hi:[0,1,1]
	v_cvt_f32_ubyte0_e32 v102, v75
	v_cvt_f32_ubyte1_e32 v103, v75
	v_pk_fma_f32 v[88:89], v[36:37], v[100:101], v[88:89] op_sel_hi:[0,1,1]
	v_cvt_f32_ubyte2_e32 v126, v75
	v_cvt_f32_ubyte3_e32 v127, v75
	v_pk_fma_f32 v[84:85], v[44:45], v[102:103], v[84:85] op_sel_hi:[0,1,1]
	v_cvt_f32_ubyte0_e32 v96, v78
	v_cvt_f32_ubyte1_e32 v97, v78
	v_pk_fma_f32 v[80:81], v[44:45], v[126:127], v[80:81] op_sel_hi:[0,1,1]
	v_and_b32_e32 v82, s34, v10
	v_and_b32_e32 v83, s35, v10
	v_and_b32_e32 v86, s34, v11
	v_and_b32_e32 v87, s35, v11
	v_cvt_f32_ubyte2_e32 v100, v78
	v_cvt_f32_ubyte3_e32 v101, v78
	v_pk_fma_f32 v[76:77], v[36:37], v[96:97], v[76:77] op_sel_hi:[0,1,1]
	v_cvt_f32_ubyte0_e32 v102, v79
	v_cvt_f32_ubyte1_e32 v103, v79
	v_pk_fma_f32 v[68:69], v[36:37], v[100:101], v[68:69] op_sel_hi:[0,1,1]
	v_cvt_f32_ubyte2_e32 v126, v79
	v_cvt_f32_ubyte3_e32 v127, v79
	v_pk_fma_f32 v[62:63], v[44:45], v[102:103], v[62:63] op_sel_hi:[0,1,1]
	v_cvt_f32_ubyte0_e32 v96, v82
	v_cvt_f32_ubyte1_e32 v97, v82
	v_pk_fma_f32 v[60:61], v[44:45], v[126:127], v[60:61] op_sel_hi:[0,1,1]
	v_cvt_f32_ubyte2_e32 v100, v82
	v_cvt_f32_ubyte3_e32 v101, v82
	v_pk_fma_f32 v[90:91], v[36:37], v[96:97], v[90:91] op_sel:[1,0,0]
	v_cvt_f32_ubyte0_e32 v102, v83
	v_cvt_f32_ubyte1_e32 v103, v83
	v_pk_fma_f32 v[88:89], v[36:37], v[100:101], v[88:89] op_sel:[1,0,0]
	v_cvt_f32_ubyte2_e32 v126, v83
	v_cvt_f32_ubyte3_e32 v127, v83
	v_pk_fma_f32 v[84:85], v[44:45], v[102:103], v[84:85] op_sel:[1,0,0]
	v_cvt_f32_ubyte0_e32 v96, v86
	v_cvt_f32_ubyte1_e32 v97, v86
	v_pk_fma_f32 v[80:81], v[44:45], v[126:127], v[80:81] op_sel:[1,0,0]
	v_and_b32_e32 v74, s34, v12
	v_and_b32_e32 v75, s35, v12
	v_and_b32_e32 v78, s34, v13
	v_and_b32_e32 v79, s35, v13
	v_cvt_f32_ubyte2_e32 v100, v86
	v_cvt_f32_ubyte3_e32 v101, v86
	v_pk_fma_f32 v[76:77], v[36:37], v[96:97], v[76:77] op_sel:[1,0,0]
	v_cvt_f32_ubyte0_e32 v102, v87
	v_cvt_f32_ubyte1_e32 v103, v87
	v_pk_fma_f32 v[68:69], v[36:37], v[100:101], v[68:69] op_sel:[1,0,0]
	v_cvt_f32_ubyte2_e32 v126, v87
	v_cvt_f32_ubyte3_e32 v127, v87
	v_pk_fma_f32 v[62:63], v[44:45], v[102:103], v[62:63] op_sel:[1,0,0]
	v_cvt_f32_ubyte0_e32 v96, v74
	v_cvt_f32_ubyte1_e32 v97, v74
	v_pk_fma_f32 v[60:61], v[44:45], v[126:127], v[60:61] op_sel:[1,0,0]
	v_cvt_f32_ubyte2_e32 v100, v74
	v_cvt_f32_ubyte3_e32 v101, v74
	v_pk_fma_f32 v[90:91], v[38:39], v[96:97], v[90:91] op_sel_hi:[0,1,1]
	v_cvt_f32_ubyte0_e32 v102, v75
	v_cvt_f32_ubyte1_e32 v103, v75
	v_pk_fma_f32 v[88:89], v[38:39], v[100:101], v[88:89] op_sel_hi:[0,1,1]
	v_cvt_f32_ubyte2_e32 v126, v75
	v_cvt_f32_ubyte3_e32 v127, v75
	v_pk_fma_f32 v[84:85], v[46:47], v[102:103], v[84:85] op_sel_hi:[0,1,1]
	v_cvt_f32_ubyte0_e32 v96, v78
	v_cvt_f32_ubyte1_e32 v97, v78
	v_pk_fma_f32 v[80:81], v[46:47], v[126:127], v[80:81] op_sel_hi:[0,1,1]
	v_and_b32_e32 v82, s34, v14
	v_and_b32_e32 v83, s35, v14
	v_and_b32_e32 v86, s34, v15
	v_and_b32_e32 v87, s35, v15
	v_cvt_f32_ubyte2_e32 v100, v78
	v_cvt_f32_ubyte3_e32 v101, v78
	v_pk_fma_f32 v[76:77], v[38:39], v[96:97], v[76:77] op_sel_hi:[0,1,1]
	v_cvt_f32_ubyte0_e32 v102, v79
	v_cvt_f32_ubyte1_e32 v103, v79
	v_pk_fma_f32 v[68:69], v[38:39], v[100:101], v[68:69] op_sel_hi:[0,1,1]
	v_cvt_f32_ubyte2_e32 v126, v79
	v_cvt_f32_ubyte3_e32 v127, v79
	v_pk_fma_f32 v[62:63], v[46:47], v[102:103], v[62:63] op_sel_hi:[0,1,1]
	v_cvt_f32_ubyte0_e32 v96, v82
	v_cvt_f32_ubyte1_e32 v97, v82
	v_pk_fma_f32 v[60:61], v[46:47], v[126:127], v[60:61] op_sel_hi:[0,1,1]
	v_cvt_f32_ubyte2_e32 v100, v82
	v_cvt_f32_ubyte3_e32 v101, v82
	v_pk_fma_f32 v[90:91], v[38:39], v[96:97], v[90:91] op_sel:[1,0,0]
	v_cvt_f32_ubyte0_e32 v102, v83
	v_cvt_f32_ubyte1_e32 v103, v83
	v_pk_fma_f32 v[88:89], v[38:39], v[100:101], v[88:89] op_sel:[1,0,0]
	v_cvt_f32_ubyte2_e32 v126, v83
	v_cvt_f32_ubyte3_e32 v127, v83
	v_pk_fma_f32 v[84:85], v[46:47], v[102:103], v[84:85] op_sel:[1,0,0]
	v_cvt_f32_ubyte0_e32 v96, v86
	v_cvt_f32_ubyte1_e32 v97, v86
	v_pk_fma_f32 v[80:81], v[46:47], v[126:127], v[80:81] op_sel:[1,0,0]
	v_cvt_f32_ubyte2_e32 v100, v86
	v_cvt_f32_ubyte3_e32 v101, v86
	v_pk_fma_f32 v[76:77], v[38:39], v[96:97], v[76:77] op_sel:[1,0,0]
	v_cvt_f32_ubyte0_e32 v102, v87
	v_cvt_f32_ubyte1_e32 v103, v87
	v_pk_fma_f32 v[68:69], v[38:39], v[100:101], v[68:69] op_sel:[1,0,0]
	v_cvt_f32_ubyte2_e32 v126, v87
	v_cvt_f32_ubyte3_e32 v127, v87
	v_pk_fma_f32 v[62:63], v[46:47], v[102:103], v[62:63] op_sel:[1,0,0]
	v_pk_fma_f32 v[60:61], v[46:47], v[126:127], v[60:61] op_sel:[1,0,0]
	s_waitcnt lgkmcnt(0)
	ds_read_b128 v[32:35], v128 offset:896
	ds_read_b128 v[36:39], v128 offset:912
	ds_read_b128 v[40:43], v128 offset:1920
	ds_read_b128 v[44:47], v128 offset:1936
	s_waitcnt vmcnt(32)
	v_and_b32_e32 v74, s34, v16
	v_and_b32_e32 v75, s35, v16
	v_and_b32_e32 v78, s34, v17
	v_and_b32_e32 v79, s35, v17
	v_cvt_f32_ubyte0_e32 v96, v74
	v_cvt_f32_ubyte1_e32 v97, v74
	v_cvt_f32_ubyte2_e32 v100, v74
	v_cvt_f32_ubyte3_e32 v101, v74
	v_pk_fma_f32 v[90:91], v[48:49], v[96:97], v[90:91] op_sel_hi:[0,1,1]
	v_cvt_f32_ubyte0_e32 v102, v75
	v_cvt_f32_ubyte1_e32 v103, v75
	v_pk_fma_f32 v[88:89], v[48:49], v[100:101], v[88:89] op_sel_hi:[0,1,1]
	v_cvt_f32_ubyte2_e32 v126, v75
	v_cvt_f32_ubyte3_e32 v127, v75
	v_pk_fma_f32 v[84:85], v[56:57], v[102:103], v[84:85] op_sel_hi:[0,1,1]
	v_cvt_f32_ubyte0_e32 v96, v78
	v_cvt_f32_ubyte1_e32 v97, v78
	v_pk_fma_f32 v[80:81], v[56:57], v[126:127], v[80:81] op_sel_hi:[0,1,1]
	v_and_b32_e32 v82, s34, v18
	v_and_b32_e32 v83, s35, v18
	v_and_b32_e32 v86, s34, v19
	v_and_b32_e32 v87, s35, v19
	v_cvt_f32_ubyte2_e32 v100, v78
	v_cvt_f32_ubyte3_e32 v101, v78
	v_pk_fma_f32 v[76:77], v[48:49], v[96:97], v[76:77] op_sel_hi:[0,1,1]
	v_cvt_f32_ubyte0_e32 v102, v79
	v_cvt_f32_ubyte1_e32 v103, v79
	v_pk_fma_f32 v[68:69], v[48:49], v[100:101], v[68:69] op_sel_hi:[0,1,1]
	v_cvt_f32_ubyte2_e32 v126, v79
	v_cvt_f32_ubyte3_e32 v127, v79
	v_pk_fma_f32 v[62:63], v[56:57], v[102:103], v[62:63] op_sel_hi:[0,1,1]
	v_cvt_f32_ubyte0_e32 v96, v82
	v_cvt_f32_ubyte1_e32 v97, v82
	v_pk_fma_f32 v[60:61], v[56:57], v[126:127], v[60:61] op_sel_hi:[0,1,1]
	v_cvt_f32_ubyte2_e32 v100, v82
	v_cvt_f32_ubyte3_e32 v101, v82
	v_pk_fma_f32 v[90:91], v[48:49], v[96:97], v[90:91] op_sel:[1,0,0]
	v_cvt_f32_ubyte0_e32 v102, v83
	v_cvt_f32_ubyte1_e32 v103, v83
	v_pk_fma_f32 v[88:89], v[48:49], v[100:101], v[88:89] op_sel:[1,0,0]
	v_cvt_f32_ubyte2_e32 v126, v83
	v_cvt_f32_ubyte3_e32 v127, v83
	v_pk_fma_f32 v[84:85], v[56:57], v[102:103], v[84:85] op_sel:[1,0,0]
	v_cvt_f32_ubyte0_e32 v96, v86
	v_cvt_f32_ubyte1_e32 v97, v86
	v_pk_fma_f32 v[80:81], v[56:57], v[126:127], v[80:81] op_sel:[1,0,0]
	v_and_b32_e32 v74, s34, v20
	v_and_b32_e32 v75, s35, v20
	v_and_b32_e32 v78, s34, v21
	v_and_b32_e32 v79, s35, v21
	v_cvt_f32_ubyte2_e32 v100, v86
	v_cvt_f32_ubyte3_e32 v101, v86
	v_pk_fma_f32 v[76:77], v[48:49], v[96:97], v[76:77] op_sel:[1,0,0]
	v_cvt_f32_ubyte0_e32 v102, v87
	v_cvt_f32_ubyte1_e32 v103, v87
	v_pk_fma_f32 v[68:69], v[48:49], v[100:101], v[68:69] op_sel:[1,0,0]
	v_cvt_f32_ubyte2_e32 v126, v87
	v_cvt_f32_ubyte3_e32 v127, v87
	v_pk_fma_f32 v[62:63], v[56:57], v[102:103], v[62:63] op_sel:[1,0,0]
	v_cvt_f32_ubyte0_e32 v96, v74
	v_cvt_f32_ubyte1_e32 v97, v74
	v_pk_fma_f32 v[60:61], v[56:57], v[126:127], v[60:61] op_sel:[1,0,0]
	v_cvt_f32_ubyte2_e32 v100, v74
	v_cvt_f32_ubyte3_e32 v101, v74
	v_pk_fma_f32 v[90:91], v[50:51], v[96:97], v[90:91] op_sel_hi:[0,1,1]
	v_cvt_f32_ubyte0_e32 v102, v75
	v_cvt_f32_ubyte1_e32 v103, v75
	v_pk_fma_f32 v[88:89], v[50:51], v[100:101], v[88:89] op_sel_hi:[0,1,1]
	v_cvt_f32_ubyte2_e32 v126, v75
	v_cvt_f32_ubyte3_e32 v127, v75
	v_pk_fma_f32 v[84:85], v[58:59], v[102:103], v[84:85] op_sel_hi:[0,1,1]
	v_cvt_f32_ubyte0_e32 v96, v78
	v_cvt_f32_ubyte1_e32 v97, v78
	v_pk_fma_f32 v[80:81], v[58:59], v[126:127], v[80:81] op_sel_hi:[0,1,1]
	v_and_b32_e32 v82, s34, v22
	v_and_b32_e32 v83, s35, v22
	v_and_b32_e32 v86, s34, v23
	v_and_b32_e32 v87, s35, v23
	v_cvt_f32_ubyte2_e32 v100, v78
	v_cvt_f32_ubyte3_e32 v101, v78
	v_pk_fma_f32 v[76:77], v[50:51], v[96:97], v[76:77] op_sel_hi:[0,1,1]
	v_cvt_f32_ubyte0_e32 v102, v79
	v_cvt_f32_ubyte1_e32 v103, v79
	v_pk_fma_f32 v[68:69], v[50:51], v[100:101], v[68:69] op_sel_hi:[0,1,1]
	v_cvt_f32_ubyte2_e32 v126, v79
	v_cvt_f32_ubyte3_e32 v127, v79
	v_pk_fma_f32 v[62:63], v[58:59], v[102:103], v[62:63] op_sel_hi:[0,1,1]
	v_cvt_f32_ubyte0_e32 v96, v82
	v_cvt_f32_ubyte1_e32 v97, v82
	v_pk_fma_f32 v[60:61], v[58:59], v[126:127], v[60:61] op_sel_hi:[0,1,1]
	v_cvt_f32_ubyte2_e32 v100, v82
	v_cvt_f32_ubyte3_e32 v101, v82
	v_pk_fma_f32 v[90:91], v[50:51], v[96:97], v[90:91] op_sel:[1,0,0]
	v_cvt_f32_ubyte0_e32 v102, v83
	v_cvt_f32_ubyte1_e32 v103, v83
	v_pk_fma_f32 v[88:89], v[50:51], v[100:101], v[88:89] op_sel:[1,0,0]
	v_cvt_f32_ubyte2_e32 v126, v83
	v_cvt_f32_ubyte3_e32 v127, v83
	v_pk_fma_f32 v[84:85], v[58:59], v[102:103], v[84:85] op_sel:[1,0,0]
	v_cvt_f32_ubyte0_e32 v96, v86
	v_cvt_f32_ubyte1_e32 v97, v86
	v_pk_fma_f32 v[80:81], v[58:59], v[126:127], v[80:81] op_sel:[1,0,0]
	v_and_b32_e32 v74, s34, v24
	v_and_b32_e32 v75, s35, v24
	v_and_b32_e32 v78, s34, v25
	v_and_b32_e32 v79, s35, v25
	v_cvt_f32_ubyte2_e32 v100, v86
	v_cvt_f32_ubyte3_e32 v101, v86
	v_pk_fma_f32 v[76:77], v[50:51], v[96:97], v[76:77] op_sel:[1,0,0]
	v_cvt_f32_ubyte0_e32 v102, v87
	v_cvt_f32_ubyte1_e32 v103, v87
	v_pk_fma_f32 v[68:69], v[50:51], v[100:101], v[68:69] op_sel:[1,0,0]
	v_cvt_f32_ubyte2_e32 v126, v87
	v_cvt_f32_ubyte3_e32 v127, v87
	v_pk_fma_f32 v[62:63], v[58:59], v[102:103], v[62:63] op_sel:[1,0,0]
	v_cvt_f32_ubyte0_e32 v96, v74
	v_cvt_f32_ubyte1_e32 v97, v74
	v_pk_fma_f32 v[60:61], v[58:59], v[126:127], v[60:61] op_sel:[1,0,0]
	v_cvt_f32_ubyte2_e32 v100, v74
	v_cvt_f32_ubyte3_e32 v101, v74
	v_pk_fma_f32 v[90:91], v[52:53], v[96:97], v[90:91] op_sel_hi:[0,1,1]
	v_cvt_f32_ubyte0_e32 v102, v75
	v_cvt_f32_ubyte1_e32 v103, v75
	v_pk_fma_f32 v[88:89], v[52:53], v[100:101], v[88:89] op_sel_hi:[0,1,1]
	v_cvt_f32_ubyte2_e32 v126, v75
	v_cvt_f32_ubyte3_e32 v127, v75
	v_pk_fma_f32 v[84:85], v[64:65], v[102:103], v[84:85] op_sel_hi:[0,1,1]
	v_cvt_f32_ubyte0_e32 v96, v78
	v_cvt_f32_ubyte1_e32 v97, v78
	v_pk_fma_f32 v[80:81], v[64:65], v[126:127], v[80:81] op_sel_hi:[0,1,1]
	v_and_b32_e32 v82, s34, v26
	v_and_b32_e32 v83, s35, v26
	v_and_b32_e32 v86, s34, v27
	v_and_b32_e32 v87, s35, v27
	v_cvt_f32_ubyte2_e32 v100, v78
	v_cvt_f32_ubyte3_e32 v101, v78
	v_pk_fma_f32 v[76:77], v[52:53], v[96:97], v[76:77] op_sel_hi:[0,1,1]
	v_cvt_f32_ubyte0_e32 v102, v79
	v_cvt_f32_ubyte1_e32 v103, v79
	v_pk_fma_f32 v[68:69], v[52:53], v[100:101], v[68:69] op_sel_hi:[0,1,1]
	v_cvt_f32_ubyte2_e32 v126, v79
	v_cvt_f32_ubyte3_e32 v127, v79
	v_pk_fma_f32 v[62:63], v[64:65], v[102:103], v[62:63] op_sel_hi:[0,1,1]
	v_cvt_f32_ubyte0_e32 v96, v82
	v_cvt_f32_ubyte1_e32 v97, v82
	v_pk_fma_f32 v[60:61], v[64:65], v[126:127], v[60:61] op_sel_hi:[0,1,1]
	v_cvt_f32_ubyte2_e32 v100, v82
	v_cvt_f32_ubyte3_e32 v101, v82
	v_pk_fma_f32 v[90:91], v[52:53], v[96:97], v[90:91] op_sel:[1,0,0]
	v_cvt_f32_ubyte0_e32 v102, v83
	v_cvt_f32_ubyte1_e32 v103, v83
	v_pk_fma_f32 v[88:89], v[52:53], v[100:101], v[88:89] op_sel:[1,0,0]
	v_cvt_f32_ubyte2_e32 v126, v83
	v_cvt_f32_ubyte3_e32 v127, v83
	v_pk_fma_f32 v[84:85], v[64:65], v[102:103], v[84:85] op_sel:[1,0,0]
	v_cvt_f32_ubyte0_e32 v96, v86
	v_cvt_f32_ubyte1_e32 v97, v86
	v_pk_fma_f32 v[80:81], v[64:65], v[126:127], v[80:81] op_sel:[1,0,0]
	v_and_b32_e32 v74, s34, v28
	v_and_b32_e32 v75, s35, v28
	v_and_b32_e32 v78, s34, v29
	v_and_b32_e32 v79, s35, v29
	v_cvt_f32_ubyte2_e32 v100, v86
	v_cvt_f32_ubyte3_e32 v101, v86
	v_pk_fma_f32 v[76:77], v[52:53], v[96:97], v[76:77] op_sel:[1,0,0]
	v_cvt_f32_ubyte0_e32 v102, v87
	v_cvt_f32_ubyte1_e32 v103, v87
	v_pk_fma_f32 v[68:69], v[52:53], v[100:101], v[68:69] op_sel:[1,0,0]
	v_cvt_f32_ubyte2_e32 v126, v87
	v_cvt_f32_ubyte3_e32 v127, v87
	v_pk_fma_f32 v[62:63], v[64:65], v[102:103], v[62:63] op_sel:[1,0,0]
	v_cvt_f32_ubyte0_e32 v96, v74
	v_cvt_f32_ubyte1_e32 v97, v74
	v_pk_fma_f32 v[60:61], v[64:65], v[126:127], v[60:61] op_sel:[1,0,0]
	v_cvt_f32_ubyte2_e32 v100, v74
	v_cvt_f32_ubyte3_e32 v101, v74
	v_pk_fma_f32 v[90:91], v[54:55], v[96:97], v[90:91] op_sel_hi:[0,1,1]
	v_cvt_f32_ubyte0_e32 v102, v75
	v_cvt_f32_ubyte1_e32 v103, v75
	v_pk_fma_f32 v[88:89], v[54:55], v[100:101], v[88:89] op_sel_hi:[0,1,1]
	v_cvt_f32_ubyte2_e32 v126, v75
	v_cvt_f32_ubyte3_e32 v127, v75
	v_pk_fma_f32 v[84:85], v[66:67], v[102:103], v[84:85] op_sel_hi:[0,1,1]
	v_cvt_f32_ubyte0_e32 v96, v78
	v_cvt_f32_ubyte1_e32 v97, v78
	v_pk_fma_f32 v[80:81], v[66:67], v[126:127], v[80:81] op_sel_hi:[0,1,1]
	v_and_b32_e32 v82, s34, v30
	v_and_b32_e32 v83, s35, v30
	v_and_b32_e32 v86, s34, v31
	v_and_b32_e32 v87, s35, v31
	v_cvt_f32_ubyte2_e32 v100, v78
	v_cvt_f32_ubyte3_e32 v101, v78
	v_pk_fma_f32 v[76:77], v[54:55], v[96:97], v[76:77] op_sel_hi:[0,1,1]
	v_cvt_f32_ubyte0_e32 v102, v79
	v_cvt_f32_ubyte1_e32 v103, v79
	v_pk_fma_f32 v[68:69], v[54:55], v[100:101], v[68:69] op_sel_hi:[0,1,1]
	v_cvt_f32_ubyte2_e32 v126, v79
	v_cvt_f32_ubyte3_e32 v127, v79
	v_pk_fma_f32 v[62:63], v[66:67], v[102:103], v[62:63] op_sel_hi:[0,1,1]
	v_cvt_f32_ubyte0_e32 v96, v82
	v_cvt_f32_ubyte1_e32 v97, v82
	v_pk_fma_f32 v[60:61], v[66:67], v[126:127], v[60:61] op_sel_hi:[0,1,1]
	v_cvt_f32_ubyte2_e32 v100, v82
	v_cvt_f32_ubyte3_e32 v101, v82
	v_pk_fma_f32 v[90:91], v[54:55], v[96:97], v[90:91] op_sel:[1,0,0]
	v_cvt_f32_ubyte0_e32 v102, v83
	v_cvt_f32_ubyte1_e32 v103, v83
	v_pk_fma_f32 v[88:89], v[54:55], v[100:101], v[88:89] op_sel:[1,0,0]
	v_cvt_f32_ubyte2_e32 v126, v83
	v_cvt_f32_ubyte3_e32 v127, v83
	v_pk_fma_f32 v[84:85], v[66:67], v[102:103], v[84:85] op_sel:[1,0,0]
	v_cvt_f32_ubyte0_e32 v96, v86
	v_cvt_f32_ubyte1_e32 v97, v86
	v_pk_fma_f32 v[80:81], v[66:67], v[126:127], v[80:81] op_sel:[1,0,0]
	v_cvt_f32_ubyte2_e32 v100, v86
	v_cvt_f32_ubyte3_e32 v101, v86
	v_pk_fma_f32 v[76:77], v[54:55], v[96:97], v[76:77] op_sel:[1,0,0]
	v_cvt_f32_ubyte0_e32 v102, v87
	v_cvt_f32_ubyte1_e32 v103, v87
	v_pk_fma_f32 v[68:69], v[54:55], v[100:101], v[68:69] op_sel:[1,0,0]
	v_cvt_f32_ubyte2_e32 v126, v87
	v_cvt_f32_ubyte3_e32 v127, v87
	v_pk_fma_f32 v[62:63], v[66:67], v[102:103], v[62:63] op_sel:[1,0,0]
	v_pk_fma_f32 v[60:61], v[66:67], v[126:127], v[60:61] op_sel:[1,0,0]
	s_waitcnt lgkmcnt(0)
	ds_read_b128 v[48:51], v128 offset:928
	ds_read_b128 v[52:55], v128 offset:944
	ds_read_b128 v[56:59], v128 offset:1952
	ds_read_b128 v[64:67], v128 offset:1968
	s_waitcnt vmcnt(24)
	v_and_b32_e32 v74, s34, v146
	v_and_b32_e32 v75, s35, v146
	v_and_b32_e32 v78, s34, v147
	v_and_b32_e32 v79, s35, v147
	v_cvt_f32_ubyte0_e32 v96, v74
	v_cvt_f32_ubyte1_e32 v97, v74
	v_cvt_f32_ubyte2_e32 v100, v74
	v_cvt_f32_ubyte3_e32 v101, v74
	v_pk_fma_f32 v[90:91], v[32:33], v[96:97], v[90:91] op_sel_hi:[0,1,1]
	v_cvt_f32_ubyte0_e32 v102, v75
	v_cvt_f32_ubyte1_e32 v103, v75
	v_pk_fma_f32 v[88:89], v[32:33], v[100:101], v[88:89] op_sel_hi:[0,1,1]
	v_cvt_f32_ubyte2_e32 v126, v75
	v_cvt_f32_ubyte3_e32 v127, v75
	v_pk_fma_f32 v[84:85], v[40:41], v[102:103], v[84:85] op_sel_hi:[0,1,1]
	v_cvt_f32_ubyte0_e32 v96, v78
	v_cvt_f32_ubyte1_e32 v97, v78
	v_pk_fma_f32 v[80:81], v[40:41], v[126:127], v[80:81] op_sel_hi:[0,1,1]
	v_and_b32_e32 v82, s34, v148
	v_and_b32_e32 v83, s35, v148
	v_and_b32_e32 v86, s34, v149
	v_and_b32_e32 v87, s35, v149
	v_cvt_f32_ubyte2_e32 v100, v78
	v_cvt_f32_ubyte3_e32 v101, v78
	v_pk_fma_f32 v[76:77], v[32:33], v[96:97], v[76:77] op_sel_hi:[0,1,1]
	v_cvt_f32_ubyte0_e32 v102, v79
	v_cvt_f32_ubyte1_e32 v103, v79
	v_pk_fma_f32 v[68:69], v[32:33], v[100:101], v[68:69] op_sel_hi:[0,1,1]
	v_cvt_f32_ubyte2_e32 v126, v79
	v_cvt_f32_ubyte3_e32 v127, v79
	v_pk_fma_f32 v[62:63], v[40:41], v[102:103], v[62:63] op_sel_hi:[0,1,1]
	v_cvt_f32_ubyte0_e32 v96, v82
	v_cvt_f32_ubyte1_e32 v97, v82
	v_pk_fma_f32 v[60:61], v[40:41], v[126:127], v[60:61] op_sel_hi:[0,1,1]
	v_cvt_f32_ubyte2_e32 v100, v82
	v_cvt_f32_ubyte3_e32 v101, v82
	v_pk_fma_f32 v[90:91], v[32:33], v[96:97], v[90:91] op_sel:[1,0,0]
	v_cvt_f32_ubyte0_e32 v102, v83
	v_cvt_f32_ubyte1_e32 v103, v83
	v_pk_fma_f32 v[88:89], v[32:33], v[100:101], v[88:89] op_sel:[1,0,0]
	v_cvt_f32_ubyte2_e32 v126, v83
	v_cvt_f32_ubyte3_e32 v127, v83
	v_pk_fma_f32 v[84:85], v[40:41], v[102:103], v[84:85] op_sel:[1,0,0]
	v_cvt_f32_ubyte0_e32 v96, v86
	v_cvt_f32_ubyte1_e32 v97, v86
	v_pk_fma_f32 v[80:81], v[40:41], v[126:127], v[80:81] op_sel:[1,0,0]
	v_and_b32_e32 v74, s34, v150
	v_and_b32_e32 v75, s35, v150
	v_and_b32_e32 v78, s34, v151
	v_and_b32_e32 v79, s35, v151
	v_cvt_f32_ubyte2_e32 v100, v86
	v_cvt_f32_ubyte3_e32 v101, v86
	v_pk_fma_f32 v[76:77], v[32:33], v[96:97], v[76:77] op_sel:[1,0,0]
	v_cvt_f32_ubyte0_e32 v102, v87
	v_cvt_f32_ubyte1_e32 v103, v87
	v_pk_fma_f32 v[68:69], v[32:33], v[100:101], v[68:69] op_sel:[1,0,0]
	v_cvt_f32_ubyte2_e32 v126, v87
	v_cvt_f32_ubyte3_e32 v127, v87
	v_pk_fma_f32 v[62:63], v[40:41], v[102:103], v[62:63] op_sel:[1,0,0]
	v_cvt_f32_ubyte0_e32 v96, v74
	v_cvt_f32_ubyte1_e32 v97, v74
	v_pk_fma_f32 v[60:61], v[40:41], v[126:127], v[60:61] op_sel:[1,0,0]
	v_cvt_f32_ubyte2_e32 v100, v74
	v_cvt_f32_ubyte3_e32 v101, v74
	v_pk_fma_f32 v[90:91], v[34:35], v[96:97], v[90:91] op_sel_hi:[0,1,1]
	v_cvt_f32_ubyte0_e32 v102, v75
	v_cvt_f32_ubyte1_e32 v103, v75
	v_pk_fma_f32 v[88:89], v[34:35], v[100:101], v[88:89] op_sel_hi:[0,1,1]
	v_cvt_f32_ubyte2_e32 v126, v75
	v_cvt_f32_ubyte3_e32 v127, v75
	v_pk_fma_f32 v[84:85], v[42:43], v[102:103], v[84:85] op_sel_hi:[0,1,1]
	v_cvt_f32_ubyte0_e32 v96, v78
	v_cvt_f32_ubyte1_e32 v97, v78
	v_pk_fma_f32 v[80:81], v[42:43], v[126:127], v[80:81] op_sel_hi:[0,1,1]
	v_and_b32_e32 v82, s34, v152
	v_and_b32_e32 v83, s35, v152
	v_and_b32_e32 v86, s34, v153
	v_and_b32_e32 v87, s35, v153
	v_cvt_f32_ubyte2_e32 v100, v78
	v_cvt_f32_ubyte3_e32 v101, v78
	v_pk_fma_f32 v[76:77], v[34:35], v[96:97], v[76:77] op_sel_hi:[0,1,1]
	v_cvt_f32_ubyte0_e32 v102, v79
	v_cvt_f32_ubyte1_e32 v103, v79
	v_pk_fma_f32 v[68:69], v[34:35], v[100:101], v[68:69] op_sel_hi:[0,1,1]
	v_cvt_f32_ubyte2_e32 v126, v79
	v_cvt_f32_ubyte3_e32 v127, v79
	v_pk_fma_f32 v[62:63], v[42:43], v[102:103], v[62:63] op_sel_hi:[0,1,1]
	v_cvt_f32_ubyte0_e32 v96, v82
	v_cvt_f32_ubyte1_e32 v97, v82
	v_pk_fma_f32 v[60:61], v[42:43], v[126:127], v[60:61] op_sel_hi:[0,1,1]
	v_cvt_f32_ubyte2_e32 v100, v82
	v_cvt_f32_ubyte3_e32 v101, v82
	v_pk_fma_f32 v[90:91], v[34:35], v[96:97], v[90:91] op_sel:[1,0,0]
	v_cvt_f32_ubyte0_e32 v102, v83
	v_cvt_f32_ubyte1_e32 v103, v83
	v_pk_fma_f32 v[88:89], v[34:35], v[100:101], v[88:89] op_sel:[1,0,0]
	v_cvt_f32_ubyte2_e32 v126, v83
	v_cvt_f32_ubyte3_e32 v127, v83
	v_pk_fma_f32 v[84:85], v[42:43], v[102:103], v[84:85] op_sel:[1,0,0]
	v_cvt_f32_ubyte0_e32 v96, v86
	v_cvt_f32_ubyte1_e32 v97, v86
	v_pk_fma_f32 v[80:81], v[42:43], v[126:127], v[80:81] op_sel:[1,0,0]
	v_and_b32_e32 v74, s34, v154
	v_and_b32_e32 v75, s35, v154
	v_and_b32_e32 v78, s34, v155
	v_and_b32_e32 v79, s35, v155
	v_cvt_f32_ubyte2_e32 v100, v86
	v_cvt_f32_ubyte3_e32 v101, v86
	v_pk_fma_f32 v[76:77], v[34:35], v[96:97], v[76:77] op_sel:[1,0,0]
	v_cvt_f32_ubyte0_e32 v102, v87
	v_cvt_f32_ubyte1_e32 v103, v87
	v_pk_fma_f32 v[68:69], v[34:35], v[100:101], v[68:69] op_sel:[1,0,0]
	v_cvt_f32_ubyte2_e32 v126, v87
	v_cvt_f32_ubyte3_e32 v127, v87
	v_pk_fma_f32 v[62:63], v[42:43], v[102:103], v[62:63] op_sel:[1,0,0]
	v_cvt_f32_ubyte0_e32 v96, v74
	v_cvt_f32_ubyte1_e32 v97, v74
	v_pk_fma_f32 v[60:61], v[42:43], v[126:127], v[60:61] op_sel:[1,0,0]
	v_cvt_f32_ubyte2_e32 v100, v74
	v_cvt_f32_ubyte3_e32 v101, v74
	v_pk_fma_f32 v[90:91], v[36:37], v[96:97], v[90:91] op_sel_hi:[0,1,1]
	v_cvt_f32_ubyte0_e32 v102, v75
	v_cvt_f32_ubyte1_e32 v103, v75
	v_pk_fma_f32 v[88:89], v[36:37], v[100:101], v[88:89] op_sel_hi:[0,1,1]
	v_cvt_f32_ubyte2_e32 v126, v75
	v_cvt_f32_ubyte3_e32 v127, v75
	v_pk_fma_f32 v[84:85], v[44:45], v[102:103], v[84:85] op_sel_hi:[0,1,1]
	v_cvt_f32_ubyte0_e32 v96, v78
	v_cvt_f32_ubyte1_e32 v97, v78
	v_pk_fma_f32 v[80:81], v[44:45], v[126:127], v[80:81] op_sel_hi:[0,1,1]
	v_and_b32_e32 v82, s34, v156
	v_and_b32_e32 v83, s35, v156
	v_and_b32_e32 v86, s34, v157
	v_and_b32_e32 v87, s35, v157
	v_cvt_f32_ubyte2_e32 v100, v78
	v_cvt_f32_ubyte3_e32 v101, v78
	v_pk_fma_f32 v[76:77], v[36:37], v[96:97], v[76:77] op_sel_hi:[0,1,1]
	v_cvt_f32_ubyte0_e32 v102, v79
	v_cvt_f32_ubyte1_e32 v103, v79
	v_pk_fma_f32 v[68:69], v[36:37], v[100:101], v[68:69] op_sel_hi:[0,1,1]
	v_cvt_f32_ubyte2_e32 v126, v79
	v_cvt_f32_ubyte3_e32 v127, v79
	v_pk_fma_f32 v[62:63], v[44:45], v[102:103], v[62:63] op_sel_hi:[0,1,1]
	v_cvt_f32_ubyte0_e32 v96, v82
	v_cvt_f32_ubyte1_e32 v97, v82
	v_pk_fma_f32 v[60:61], v[44:45], v[126:127], v[60:61] op_sel_hi:[0,1,1]
	v_cvt_f32_ubyte2_e32 v100, v82
	v_cvt_f32_ubyte3_e32 v101, v82
	v_pk_fma_f32 v[90:91], v[36:37], v[96:97], v[90:91] op_sel:[1,0,0]
	v_cvt_f32_ubyte0_e32 v102, v83
	v_cvt_f32_ubyte1_e32 v103, v83
	v_pk_fma_f32 v[88:89], v[36:37], v[100:101], v[88:89] op_sel:[1,0,0]
	v_cvt_f32_ubyte2_e32 v126, v83
	v_cvt_f32_ubyte3_e32 v127, v83
	v_pk_fma_f32 v[84:85], v[44:45], v[102:103], v[84:85] op_sel:[1,0,0]
	v_cvt_f32_ubyte0_e32 v96, v86
	v_cvt_f32_ubyte1_e32 v97, v86
	v_pk_fma_f32 v[80:81], v[44:45], v[126:127], v[80:81] op_sel:[1,0,0]
	v_and_b32_e32 v74, s34, v158
	v_and_b32_e32 v75, s35, v158
	v_and_b32_e32 v78, s34, v159
	v_and_b32_e32 v79, s35, v159
	v_cvt_f32_ubyte2_e32 v100, v86
	v_cvt_f32_ubyte3_e32 v101, v86
	v_pk_fma_f32 v[76:77], v[36:37], v[96:97], v[76:77] op_sel:[1,0,0]
	v_cvt_f32_ubyte0_e32 v102, v87
	v_cvt_f32_ubyte1_e32 v103, v87
	v_pk_fma_f32 v[68:69], v[36:37], v[100:101], v[68:69] op_sel:[1,0,0]
	v_cvt_f32_ubyte2_e32 v126, v87
	v_cvt_f32_ubyte3_e32 v127, v87
	v_pk_fma_f32 v[62:63], v[44:45], v[102:103], v[62:63] op_sel:[1,0,0]
	v_cvt_f32_ubyte0_e32 v96, v74
	v_cvt_f32_ubyte1_e32 v97, v74
	v_pk_fma_f32 v[60:61], v[44:45], v[126:127], v[60:61] op_sel:[1,0,0]
	v_cvt_f32_ubyte2_e32 v100, v74
	v_cvt_f32_ubyte3_e32 v101, v74
	v_pk_fma_f32 v[90:91], v[38:39], v[96:97], v[90:91] op_sel_hi:[0,1,1]
	v_cvt_f32_ubyte0_e32 v102, v75
	v_cvt_f32_ubyte1_e32 v103, v75
	v_pk_fma_f32 v[88:89], v[38:39], v[100:101], v[88:89] op_sel_hi:[0,1,1]
	v_cvt_f32_ubyte2_e32 v126, v75
	v_cvt_f32_ubyte3_e32 v127, v75
	v_pk_fma_f32 v[84:85], v[46:47], v[102:103], v[84:85] op_sel_hi:[0,1,1]
	v_cvt_f32_ubyte0_e32 v96, v78
	v_cvt_f32_ubyte1_e32 v97, v78
	v_pk_fma_f32 v[80:81], v[46:47], v[126:127], v[80:81] op_sel_hi:[0,1,1]
	v_and_b32_e32 v82, s34, v160
	v_and_b32_e32 v83, s35, v160
	v_and_b32_e32 v86, s34, v161
	v_and_b32_e32 v87, s35, v161
	v_cvt_f32_ubyte2_e32 v100, v78
	v_cvt_f32_ubyte3_e32 v101, v78
	v_pk_fma_f32 v[76:77], v[38:39], v[96:97], v[76:77] op_sel_hi:[0,1,1]
	v_cvt_f32_ubyte0_e32 v102, v79
	v_cvt_f32_ubyte1_e32 v103, v79
	v_pk_fma_f32 v[68:69], v[38:39], v[100:101], v[68:69] op_sel_hi:[0,1,1]
	v_cvt_f32_ubyte2_e32 v126, v79
	v_cvt_f32_ubyte3_e32 v127, v79
	v_pk_fma_f32 v[62:63], v[46:47], v[102:103], v[62:63] op_sel_hi:[0,1,1]
	v_cvt_f32_ubyte0_e32 v96, v82
	v_cvt_f32_ubyte1_e32 v97, v82
	v_pk_fma_f32 v[60:61], v[46:47], v[126:127], v[60:61] op_sel_hi:[0,1,1]
	v_cvt_f32_ubyte2_e32 v100, v82
	v_cvt_f32_ubyte3_e32 v101, v82
	v_pk_fma_f32 v[90:91], v[38:39], v[96:97], v[90:91] op_sel:[1,0,0]
	v_cvt_f32_ubyte0_e32 v102, v83
	v_cvt_f32_ubyte1_e32 v103, v83
	v_pk_fma_f32 v[88:89], v[38:39], v[100:101], v[88:89] op_sel:[1,0,0]
	v_cvt_f32_ubyte2_e32 v126, v83
	v_cvt_f32_ubyte3_e32 v127, v83
	v_pk_fma_f32 v[84:85], v[46:47], v[102:103], v[84:85] op_sel:[1,0,0]
	v_cvt_f32_ubyte0_e32 v96, v86
	v_cvt_f32_ubyte1_e32 v97, v86
	v_pk_fma_f32 v[80:81], v[46:47], v[126:127], v[80:81] op_sel:[1,0,0]
	v_cvt_f32_ubyte2_e32 v100, v86
	v_cvt_f32_ubyte3_e32 v101, v86
	v_pk_fma_f32 v[76:77], v[38:39], v[96:97], v[76:77] op_sel:[1,0,0]
	v_cvt_f32_ubyte0_e32 v102, v87
	v_cvt_f32_ubyte1_e32 v103, v87
	v_pk_fma_f32 v[68:69], v[38:39], v[100:101], v[68:69] op_sel:[1,0,0]
	v_cvt_f32_ubyte2_e32 v126, v87
	v_cvt_f32_ubyte3_e32 v127, v87
	v_pk_fma_f32 v[62:63], v[46:47], v[102:103], v[62:63] op_sel:[1,0,0]
	v_pk_fma_f32 v[60:61], v[46:47], v[126:127], v[60:61] op_sel:[1,0,0]
	s_waitcnt lgkmcnt(0)
	ds_read_b128 v[32:35], v128 offset:960
	ds_read_b128 v[36:39], v128 offset:976
	ds_read_b128 v[40:43], v128 offset:1984
	ds_read_b128 v[44:47], v128 offset:2000
	s_waitcnt vmcnt(16)
	v_and_b32_e32 v74, s34, v162
	v_and_b32_e32 v75, s35, v162
	v_and_b32_e32 v78, s34, v163
	v_and_b32_e32 v79, s35, v163
	v_cvt_f32_ubyte0_e32 v96, v74
	v_cvt_f32_ubyte1_e32 v97, v74
	v_cvt_f32_ubyte2_e32 v100, v74
	v_cvt_f32_ubyte3_e32 v101, v74
	v_pk_fma_f32 v[90:91], v[48:49], v[96:97], v[90:91] op_sel_hi:[0,1,1]
	v_cvt_f32_ubyte0_e32 v102, v75
	v_cvt_f32_ubyte1_e32 v103, v75
	v_pk_fma_f32 v[88:89], v[48:49], v[100:101], v[88:89] op_sel_hi:[0,1,1]
	v_cvt_f32_ubyte2_e32 v126, v75
	v_cvt_f32_ubyte3_e32 v127, v75
	v_pk_fma_f32 v[84:85], v[56:57], v[102:103], v[84:85] op_sel_hi:[0,1,1]
	v_cvt_f32_ubyte0_e32 v96, v78
	v_cvt_f32_ubyte1_e32 v97, v78
	v_pk_fma_f32 v[80:81], v[56:57], v[126:127], v[80:81] op_sel_hi:[0,1,1]
	v_and_b32_e32 v82, s34, v164
	v_and_b32_e32 v83, s35, v164
	v_and_b32_e32 v86, s34, v165
	v_and_b32_e32 v87, s35, v165
	v_cvt_f32_ubyte2_e32 v100, v78
	v_cvt_f32_ubyte3_e32 v101, v78
	v_pk_fma_f32 v[76:77], v[48:49], v[96:97], v[76:77] op_sel_hi:[0,1,1]
	v_cvt_f32_ubyte0_e32 v102, v79
	v_cvt_f32_ubyte1_e32 v103, v79
	v_pk_fma_f32 v[68:69], v[48:49], v[100:101], v[68:69] op_sel_hi:[0,1,1]
	v_cvt_f32_ubyte2_e32 v126, v79
	v_cvt_f32_ubyte3_e32 v127, v79
	v_pk_fma_f32 v[62:63], v[56:57], v[102:103], v[62:63] op_sel_hi:[0,1,1]
	v_cvt_f32_ubyte0_e32 v96, v82
	v_cvt_f32_ubyte1_e32 v97, v82
	v_pk_fma_f32 v[60:61], v[56:57], v[126:127], v[60:61] op_sel_hi:[0,1,1]
	v_cvt_f32_ubyte2_e32 v100, v82
	v_cvt_f32_ubyte3_e32 v101, v82
	v_pk_fma_f32 v[90:91], v[48:49], v[96:97], v[90:91] op_sel:[1,0,0]
	v_cvt_f32_ubyte0_e32 v102, v83
	v_cvt_f32_ubyte1_e32 v103, v83
	v_pk_fma_f32 v[88:89], v[48:49], v[100:101], v[88:89] op_sel:[1,0,0]
	v_cvt_f32_ubyte2_e32 v126, v83
	v_cvt_f32_ubyte3_e32 v127, v83
	v_pk_fma_f32 v[84:85], v[56:57], v[102:103], v[84:85] op_sel:[1,0,0]
	v_cvt_f32_ubyte0_e32 v96, v86
	v_cvt_f32_ubyte1_e32 v97, v86
	v_pk_fma_f32 v[80:81], v[56:57], v[126:127], v[80:81] op_sel:[1,0,0]
	v_and_b32_e32 v74, s34, v166
	v_and_b32_e32 v75, s35, v166
	v_and_b32_e32 v78, s34, v167
	v_and_b32_e32 v79, s35, v167
	v_cvt_f32_ubyte2_e32 v100, v86
	v_cvt_f32_ubyte3_e32 v101, v86
	v_pk_fma_f32 v[76:77], v[48:49], v[96:97], v[76:77] op_sel:[1,0,0]
	v_cvt_f32_ubyte0_e32 v102, v87
	v_cvt_f32_ubyte1_e32 v103, v87
	v_pk_fma_f32 v[68:69], v[48:49], v[100:101], v[68:69] op_sel:[1,0,0]
	v_cvt_f32_ubyte2_e32 v126, v87
	v_cvt_f32_ubyte3_e32 v127, v87
	v_pk_fma_f32 v[62:63], v[56:57], v[102:103], v[62:63] op_sel:[1,0,0]
	v_cvt_f32_ubyte0_e32 v96, v74
	v_cvt_f32_ubyte1_e32 v97, v74
	v_pk_fma_f32 v[60:61], v[56:57], v[126:127], v[60:61] op_sel:[1,0,0]
	v_cvt_f32_ubyte2_e32 v100, v74
	v_cvt_f32_ubyte3_e32 v101, v74
	v_pk_fma_f32 v[90:91], v[50:51], v[96:97], v[90:91] op_sel_hi:[0,1,1]
	v_cvt_f32_ubyte0_e32 v102, v75
	v_cvt_f32_ubyte1_e32 v103, v75
	v_pk_fma_f32 v[88:89], v[50:51], v[100:101], v[88:89] op_sel_hi:[0,1,1]
	v_cvt_f32_ubyte2_e32 v126, v75
	v_cvt_f32_ubyte3_e32 v127, v75
	v_pk_fma_f32 v[84:85], v[58:59], v[102:103], v[84:85] op_sel_hi:[0,1,1]
	v_cvt_f32_ubyte0_e32 v96, v78
	v_cvt_f32_ubyte1_e32 v97, v78
	v_pk_fma_f32 v[80:81], v[58:59], v[126:127], v[80:81] op_sel_hi:[0,1,1]
	v_and_b32_e32 v82, s34, v168
	v_and_b32_e32 v83, s35, v168
	v_and_b32_e32 v86, s34, v169
	v_and_b32_e32 v87, s35, v169
	v_cvt_f32_ubyte2_e32 v100, v78
	v_cvt_f32_ubyte3_e32 v101, v78
	v_pk_fma_f32 v[76:77], v[50:51], v[96:97], v[76:77] op_sel_hi:[0,1,1]
	v_cvt_f32_ubyte0_e32 v102, v79
	v_cvt_f32_ubyte1_e32 v103, v79
	v_pk_fma_f32 v[68:69], v[50:51], v[100:101], v[68:69] op_sel_hi:[0,1,1]
	v_cvt_f32_ubyte2_e32 v126, v79
	v_cvt_f32_ubyte3_e32 v127, v79
	v_pk_fma_f32 v[62:63], v[58:59], v[102:103], v[62:63] op_sel_hi:[0,1,1]
	v_cvt_f32_ubyte0_e32 v96, v82
	v_cvt_f32_ubyte1_e32 v97, v82
	v_pk_fma_f32 v[60:61], v[58:59], v[126:127], v[60:61] op_sel_hi:[0,1,1]
	v_cvt_f32_ubyte2_e32 v100, v82
	v_cvt_f32_ubyte3_e32 v101, v82
	v_pk_fma_f32 v[90:91], v[50:51], v[96:97], v[90:91] op_sel:[1,0,0]
	v_cvt_f32_ubyte0_e32 v102, v83
	v_cvt_f32_ubyte1_e32 v103, v83
	v_pk_fma_f32 v[88:89], v[50:51], v[100:101], v[88:89] op_sel:[1,0,0]
	v_cvt_f32_ubyte2_e32 v126, v83
	v_cvt_f32_ubyte3_e32 v127, v83
	v_pk_fma_f32 v[84:85], v[58:59], v[102:103], v[84:85] op_sel:[1,0,0]
	v_cvt_f32_ubyte0_e32 v96, v86
	v_cvt_f32_ubyte1_e32 v97, v86
	v_pk_fma_f32 v[80:81], v[58:59], v[126:127], v[80:81] op_sel:[1,0,0]
	v_and_b32_e32 v74, s34, v170
	v_and_b32_e32 v75, s35, v170
	v_and_b32_e32 v78, s34, v171
	v_and_b32_e32 v79, s35, v171
	v_cvt_f32_ubyte2_e32 v100, v86
	v_cvt_f32_ubyte3_e32 v101, v86
	v_pk_fma_f32 v[76:77], v[50:51], v[96:97], v[76:77] op_sel:[1,0,0]
	v_cvt_f32_ubyte0_e32 v102, v87
	v_cvt_f32_ubyte1_e32 v103, v87
	v_pk_fma_f32 v[68:69], v[50:51], v[100:101], v[68:69] op_sel:[1,0,0]
	v_cvt_f32_ubyte2_e32 v126, v87
	v_cvt_f32_ubyte3_e32 v127, v87
	v_pk_fma_f32 v[62:63], v[58:59], v[102:103], v[62:63] op_sel:[1,0,0]
	v_cvt_f32_ubyte0_e32 v96, v74
	v_cvt_f32_ubyte1_e32 v97, v74
	v_pk_fma_f32 v[60:61], v[58:59], v[126:127], v[60:61] op_sel:[1,0,0]
	v_cvt_f32_ubyte2_e32 v100, v74
	v_cvt_f32_ubyte3_e32 v101, v74
	v_pk_fma_f32 v[90:91], v[52:53], v[96:97], v[90:91] op_sel_hi:[0,1,1]
	v_cvt_f32_ubyte0_e32 v102, v75
	v_cvt_f32_ubyte1_e32 v103, v75
	v_pk_fma_f32 v[88:89], v[52:53], v[100:101], v[88:89] op_sel_hi:[0,1,1]
	v_cvt_f32_ubyte2_e32 v126, v75
	v_cvt_f32_ubyte3_e32 v127, v75
	v_pk_fma_f32 v[84:85], v[64:65], v[102:103], v[84:85] op_sel_hi:[0,1,1]
	v_cvt_f32_ubyte0_e32 v96, v78
	v_cvt_f32_ubyte1_e32 v97, v78
	v_pk_fma_f32 v[80:81], v[64:65], v[126:127], v[80:81] op_sel_hi:[0,1,1]
	v_and_b32_e32 v82, s34, v172
	v_and_b32_e32 v83, s35, v172
	v_and_b32_e32 v86, s34, v173
	v_and_b32_e32 v87, s35, v173
	v_cvt_f32_ubyte2_e32 v100, v78
	v_cvt_f32_ubyte3_e32 v101, v78
	v_pk_fma_f32 v[76:77], v[52:53], v[96:97], v[76:77] op_sel_hi:[0,1,1]
	v_cvt_f32_ubyte0_e32 v102, v79
	v_cvt_f32_ubyte1_e32 v103, v79
	v_pk_fma_f32 v[68:69], v[52:53], v[100:101], v[68:69] op_sel_hi:[0,1,1]
	v_cvt_f32_ubyte2_e32 v126, v79
	v_cvt_f32_ubyte3_e32 v127, v79
	v_pk_fma_f32 v[62:63], v[64:65], v[102:103], v[62:63] op_sel_hi:[0,1,1]
	v_cvt_f32_ubyte0_e32 v96, v82
	v_cvt_f32_ubyte1_e32 v97, v82
	v_pk_fma_f32 v[60:61], v[64:65], v[126:127], v[60:61] op_sel_hi:[0,1,1]
	v_cvt_f32_ubyte2_e32 v100, v82
	v_cvt_f32_ubyte3_e32 v101, v82
	v_pk_fma_f32 v[90:91], v[52:53], v[96:97], v[90:91] op_sel:[1,0,0]
	v_cvt_f32_ubyte0_e32 v102, v83
	v_cvt_f32_ubyte1_e32 v103, v83
	v_pk_fma_f32 v[88:89], v[52:53], v[100:101], v[88:89] op_sel:[1,0,0]
	v_cvt_f32_ubyte2_e32 v126, v83
	v_cvt_f32_ubyte3_e32 v127, v83
	v_pk_fma_f32 v[84:85], v[64:65], v[102:103], v[84:85] op_sel:[1,0,0]
	v_cvt_f32_ubyte0_e32 v96, v86
	v_cvt_f32_ubyte1_e32 v97, v86
	v_pk_fma_f32 v[80:81], v[64:65], v[126:127], v[80:81] op_sel:[1,0,0]
	v_and_b32_e32 v74, s34, v174
	v_and_b32_e32 v75, s35, v174
	v_and_b32_e32 v78, s34, v175
	v_and_b32_e32 v79, s35, v175
	v_cvt_f32_ubyte2_e32 v100, v86
	v_cvt_f32_ubyte3_e32 v101, v86
	v_pk_fma_f32 v[76:77], v[52:53], v[96:97], v[76:77] op_sel:[1,0,0]
	v_cvt_f32_ubyte0_e32 v102, v87
	v_cvt_f32_ubyte1_e32 v103, v87
	v_pk_fma_f32 v[68:69], v[52:53], v[100:101], v[68:69] op_sel:[1,0,0]
	v_cvt_f32_ubyte2_e32 v126, v87
	v_cvt_f32_ubyte3_e32 v127, v87
	v_pk_fma_f32 v[62:63], v[64:65], v[102:103], v[62:63] op_sel:[1,0,0]
	v_cvt_f32_ubyte0_e32 v96, v74
	v_cvt_f32_ubyte1_e32 v97, v74
	v_pk_fma_f32 v[60:61], v[64:65], v[126:127], v[60:61] op_sel:[1,0,0]
	v_cvt_f32_ubyte2_e32 v100, v74
	v_cvt_f32_ubyte3_e32 v101, v74
	v_pk_fma_f32 v[90:91], v[54:55], v[96:97], v[90:91] op_sel_hi:[0,1,1]
	v_cvt_f32_ubyte0_e32 v102, v75
	v_cvt_f32_ubyte1_e32 v103, v75
	v_pk_fma_f32 v[88:89], v[54:55], v[100:101], v[88:89] op_sel_hi:[0,1,1]
	v_cvt_f32_ubyte2_e32 v126, v75
	v_cvt_f32_ubyte3_e32 v127, v75
	v_pk_fma_f32 v[84:85], v[66:67], v[102:103], v[84:85] op_sel_hi:[0,1,1]
	v_cvt_f32_ubyte0_e32 v96, v78
	v_cvt_f32_ubyte1_e32 v97, v78
	v_pk_fma_f32 v[80:81], v[66:67], v[126:127], v[80:81] op_sel_hi:[0,1,1]
	v_and_b32_e32 v82, s34, v176
	v_and_b32_e32 v83, s35, v176
	v_and_b32_e32 v86, s34, v177
	v_and_b32_e32 v87, s35, v177
	v_cvt_f32_ubyte2_e32 v100, v78
	v_cvt_f32_ubyte3_e32 v101, v78
	v_pk_fma_f32 v[76:77], v[54:55], v[96:97], v[76:77] op_sel_hi:[0,1,1]
	v_cvt_f32_ubyte0_e32 v102, v79
	v_cvt_f32_ubyte1_e32 v103, v79
	v_pk_fma_f32 v[68:69], v[54:55], v[100:101], v[68:69] op_sel_hi:[0,1,1]
	v_cvt_f32_ubyte2_e32 v126, v79
	v_cvt_f32_ubyte3_e32 v127, v79
	v_pk_fma_f32 v[62:63], v[66:67], v[102:103], v[62:63] op_sel_hi:[0,1,1]
	v_cvt_f32_ubyte0_e32 v96, v82
	v_cvt_f32_ubyte1_e32 v97, v82
	v_pk_fma_f32 v[60:61], v[66:67], v[126:127], v[60:61] op_sel_hi:[0,1,1]
	v_cvt_f32_ubyte2_e32 v100, v82
	v_cvt_f32_ubyte3_e32 v101, v82
	v_pk_fma_f32 v[90:91], v[54:55], v[96:97], v[90:91] op_sel:[1,0,0]
	v_cvt_f32_ubyte0_e32 v102, v83
	v_cvt_f32_ubyte1_e32 v103, v83
	v_pk_fma_f32 v[88:89], v[54:55], v[100:101], v[88:89] op_sel:[1,0,0]
	v_cvt_f32_ubyte2_e32 v126, v83
	v_cvt_f32_ubyte3_e32 v127, v83
	v_pk_fma_f32 v[84:85], v[66:67], v[102:103], v[84:85] op_sel:[1,0,0]
	v_cvt_f32_ubyte0_e32 v96, v86
	v_cvt_f32_ubyte1_e32 v97, v86
	v_pk_fma_f32 v[80:81], v[66:67], v[126:127], v[80:81] op_sel:[1,0,0]
	v_cvt_f32_ubyte2_e32 v100, v86
	v_cvt_f32_ubyte3_e32 v101, v86
	v_pk_fma_f32 v[76:77], v[54:55], v[96:97], v[76:77] op_sel:[1,0,0]
	v_cvt_f32_ubyte0_e32 v102, v87
	v_cvt_f32_ubyte1_e32 v103, v87
	v_pk_fma_f32 v[68:69], v[54:55], v[100:101], v[68:69] op_sel:[1,0,0]
	v_cvt_f32_ubyte2_e32 v126, v87
	v_cvt_f32_ubyte3_e32 v127, v87
	v_pk_fma_f32 v[62:63], v[66:67], v[102:103], v[62:63] op_sel:[1,0,0]
	v_pk_fma_f32 v[60:61], v[66:67], v[126:127], v[60:61] op_sel:[1,0,0]
	s_waitcnt lgkmcnt(0)
	ds_read_b128 v[48:51], v128 offset:992
	ds_read_b128 v[52:55], v128 offset:1008
	ds_read_b128 v[56:59], v128 offset:2016
	ds_read_b128 v[64:67], v128 offset:2032
	s_waitcnt vmcnt(8)
	v_and_b32_e32 v74, s34, v178
	v_and_b32_e32 v75, s35, v178
	v_and_b32_e32 v78, s34, v179
	v_and_b32_e32 v79, s35, v179
	v_cvt_f32_ubyte0_e32 v96, v74
	v_cvt_f32_ubyte1_e32 v97, v74
	v_cvt_f32_ubyte2_e32 v100, v74
	v_cvt_f32_ubyte3_e32 v101, v74
	v_pk_fma_f32 v[90:91], v[32:33], v[96:97], v[90:91] op_sel_hi:[0,1,1]
	v_cvt_f32_ubyte0_e32 v102, v75
	v_cvt_f32_ubyte1_e32 v103, v75
	v_pk_fma_f32 v[88:89], v[32:33], v[100:101], v[88:89] op_sel_hi:[0,1,1]
	v_cvt_f32_ubyte2_e32 v126, v75
	v_cvt_f32_ubyte3_e32 v127, v75
	v_pk_fma_f32 v[84:85], v[40:41], v[102:103], v[84:85] op_sel_hi:[0,1,1]
	v_cvt_f32_ubyte0_e32 v96, v78
	v_cvt_f32_ubyte1_e32 v97, v78
	v_pk_fma_f32 v[80:81], v[40:41], v[126:127], v[80:81] op_sel_hi:[0,1,1]
	v_and_b32_e32 v82, s34, v180
	v_and_b32_e32 v83, s35, v180
	v_and_b32_e32 v86, s34, v181
	v_and_b32_e32 v87, s35, v181
	v_cvt_f32_ubyte2_e32 v100, v78
	v_cvt_f32_ubyte3_e32 v101, v78
	v_pk_fma_f32 v[76:77], v[32:33], v[96:97], v[76:77] op_sel_hi:[0,1,1]
	v_cvt_f32_ubyte0_e32 v102, v79
	v_cvt_f32_ubyte1_e32 v103, v79
	v_pk_fma_f32 v[68:69], v[32:33], v[100:101], v[68:69] op_sel_hi:[0,1,1]
	v_cvt_f32_ubyte2_e32 v126, v79
	v_cvt_f32_ubyte3_e32 v127, v79
	v_pk_fma_f32 v[62:63], v[40:41], v[102:103], v[62:63] op_sel_hi:[0,1,1]
	v_cvt_f32_ubyte0_e32 v96, v82
	v_cvt_f32_ubyte1_e32 v97, v82
	v_pk_fma_f32 v[60:61], v[40:41], v[126:127], v[60:61] op_sel_hi:[0,1,1]
	v_cvt_f32_ubyte2_e32 v100, v82
	v_cvt_f32_ubyte3_e32 v101, v82
	v_pk_fma_f32 v[90:91], v[32:33], v[96:97], v[90:91] op_sel:[1,0,0]
	v_cvt_f32_ubyte0_e32 v102, v83
	v_cvt_f32_ubyte1_e32 v103, v83
	v_pk_fma_f32 v[88:89], v[32:33], v[100:101], v[88:89] op_sel:[1,0,0]
	v_cvt_f32_ubyte2_e32 v126, v83
	v_cvt_f32_ubyte3_e32 v127, v83
	v_pk_fma_f32 v[84:85], v[40:41], v[102:103], v[84:85] op_sel:[1,0,0]
	v_cvt_f32_ubyte0_e32 v96, v86
	v_cvt_f32_ubyte1_e32 v97, v86
	v_pk_fma_f32 v[80:81], v[40:41], v[126:127], v[80:81] op_sel:[1,0,0]
	v_and_b32_e32 v74, s34, v182
	v_and_b32_e32 v75, s35, v182
	v_and_b32_e32 v78, s34, v183
	v_and_b32_e32 v79, s35, v183
	v_cvt_f32_ubyte2_e32 v100, v86
	v_cvt_f32_ubyte3_e32 v101, v86
	v_pk_fma_f32 v[76:77], v[32:33], v[96:97], v[76:77] op_sel:[1,0,0]
	v_cvt_f32_ubyte0_e32 v102, v87
	v_cvt_f32_ubyte1_e32 v103, v87
	v_pk_fma_f32 v[68:69], v[32:33], v[100:101], v[68:69] op_sel:[1,0,0]
	v_cvt_f32_ubyte2_e32 v126, v87
	v_cvt_f32_ubyte3_e32 v127, v87
	v_pk_fma_f32 v[62:63], v[40:41], v[102:103], v[62:63] op_sel:[1,0,0]
	v_cvt_f32_ubyte0_e32 v96, v74
	v_cvt_f32_ubyte1_e32 v97, v74
	v_pk_fma_f32 v[60:61], v[40:41], v[126:127], v[60:61] op_sel:[1,0,0]
	v_cvt_f32_ubyte2_e32 v100, v74
	v_cvt_f32_ubyte3_e32 v101, v74
	v_pk_fma_f32 v[90:91], v[34:35], v[96:97], v[90:91] op_sel_hi:[0,1,1]
	v_cvt_f32_ubyte0_e32 v102, v75
	v_cvt_f32_ubyte1_e32 v103, v75
	v_pk_fma_f32 v[88:89], v[34:35], v[100:101], v[88:89] op_sel_hi:[0,1,1]
	v_cvt_f32_ubyte2_e32 v126, v75
	v_cvt_f32_ubyte3_e32 v127, v75
	v_pk_fma_f32 v[84:85], v[42:43], v[102:103], v[84:85] op_sel_hi:[0,1,1]
	v_cvt_f32_ubyte0_e32 v96, v78
	v_cvt_f32_ubyte1_e32 v97, v78
	v_pk_fma_f32 v[80:81], v[42:43], v[126:127], v[80:81] op_sel_hi:[0,1,1]
	v_and_b32_e32 v82, s34, v184
	v_and_b32_e32 v83, s35, v184
	v_and_b32_e32 v86, s34, v185
	v_and_b32_e32 v87, s35, v185
	v_cvt_f32_ubyte2_e32 v100, v78
	v_cvt_f32_ubyte3_e32 v101, v78
	v_pk_fma_f32 v[76:77], v[34:35], v[96:97], v[76:77] op_sel_hi:[0,1,1]
	v_cvt_f32_ubyte0_e32 v102, v79
	v_cvt_f32_ubyte1_e32 v103, v79
	v_pk_fma_f32 v[68:69], v[34:35], v[100:101], v[68:69] op_sel_hi:[0,1,1]
	v_cvt_f32_ubyte2_e32 v126, v79
	v_cvt_f32_ubyte3_e32 v127, v79
	v_pk_fma_f32 v[62:63], v[42:43], v[102:103], v[62:63] op_sel_hi:[0,1,1]
	v_cvt_f32_ubyte0_e32 v96, v82
	v_cvt_f32_ubyte1_e32 v97, v82
	v_pk_fma_f32 v[60:61], v[42:43], v[126:127], v[60:61] op_sel_hi:[0,1,1]
	v_cvt_f32_ubyte2_e32 v100, v82
	v_cvt_f32_ubyte3_e32 v101, v82
	v_pk_fma_f32 v[90:91], v[34:35], v[96:97], v[90:91] op_sel:[1,0,0]
	v_cvt_f32_ubyte0_e32 v102, v83
	v_cvt_f32_ubyte1_e32 v103, v83
	v_pk_fma_f32 v[88:89], v[34:35], v[100:101], v[88:89] op_sel:[1,0,0]
	v_cvt_f32_ubyte2_e32 v126, v83
	v_cvt_f32_ubyte3_e32 v127, v83
	v_pk_fma_f32 v[84:85], v[42:43], v[102:103], v[84:85] op_sel:[1,0,0]
	v_cvt_f32_ubyte0_e32 v96, v86
	v_cvt_f32_ubyte1_e32 v97, v86
	v_pk_fma_f32 v[80:81], v[42:43], v[126:127], v[80:81] op_sel:[1,0,0]
	v_and_b32_e32 v74, s34, v186
	v_and_b32_e32 v75, s35, v186
	v_and_b32_e32 v78, s34, v187
	v_and_b32_e32 v79, s35, v187
	v_cvt_f32_ubyte2_e32 v100, v86
	v_cvt_f32_ubyte3_e32 v101, v86
	v_pk_fma_f32 v[76:77], v[34:35], v[96:97], v[76:77] op_sel:[1,0,0]
	v_cvt_f32_ubyte0_e32 v102, v87
	v_cvt_f32_ubyte1_e32 v103, v87
	v_pk_fma_f32 v[68:69], v[34:35], v[100:101], v[68:69] op_sel:[1,0,0]
	v_cvt_f32_ubyte2_e32 v126, v87
	v_cvt_f32_ubyte3_e32 v127, v87
	v_pk_fma_f32 v[62:63], v[42:43], v[102:103], v[62:63] op_sel:[1,0,0]
	v_cvt_f32_ubyte0_e32 v96, v74
	v_cvt_f32_ubyte1_e32 v97, v74
	v_pk_fma_f32 v[60:61], v[42:43], v[126:127], v[60:61] op_sel:[1,0,0]
	v_cvt_f32_ubyte2_e32 v100, v74
	v_cvt_f32_ubyte3_e32 v101, v74
	v_pk_fma_f32 v[90:91], v[36:37], v[96:97], v[90:91] op_sel_hi:[0,1,1]
	v_cvt_f32_ubyte0_e32 v102, v75
	v_cvt_f32_ubyte1_e32 v103, v75
	v_pk_fma_f32 v[88:89], v[36:37], v[100:101], v[88:89] op_sel_hi:[0,1,1]
	v_cvt_f32_ubyte2_e32 v126, v75
	v_cvt_f32_ubyte3_e32 v127, v75
	v_pk_fma_f32 v[84:85], v[44:45], v[102:103], v[84:85] op_sel_hi:[0,1,1]
	v_cvt_f32_ubyte0_e32 v96, v78
	v_cvt_f32_ubyte1_e32 v97, v78
	v_pk_fma_f32 v[80:81], v[44:45], v[126:127], v[80:81] op_sel_hi:[0,1,1]
	v_and_b32_e32 v82, s34, v188
	v_and_b32_e32 v83, s35, v188
	v_and_b32_e32 v86, s34, v189
	v_and_b32_e32 v87, s35, v189
	v_cvt_f32_ubyte2_e32 v100, v78
	v_cvt_f32_ubyte3_e32 v101, v78
	v_pk_fma_f32 v[76:77], v[36:37], v[96:97], v[76:77] op_sel_hi:[0,1,1]
	v_cvt_f32_ubyte0_e32 v102, v79
	v_cvt_f32_ubyte1_e32 v103, v79
	v_pk_fma_f32 v[68:69], v[36:37], v[100:101], v[68:69] op_sel_hi:[0,1,1]
	v_cvt_f32_ubyte2_e32 v126, v79
	v_cvt_f32_ubyte3_e32 v127, v79
	v_pk_fma_f32 v[62:63], v[44:45], v[102:103], v[62:63] op_sel_hi:[0,1,1]
	v_cvt_f32_ubyte0_e32 v96, v82
	v_cvt_f32_ubyte1_e32 v97, v82
	v_pk_fma_f32 v[60:61], v[44:45], v[126:127], v[60:61] op_sel_hi:[0,1,1]
	v_cvt_f32_ubyte2_e32 v100, v82
	v_cvt_f32_ubyte3_e32 v101, v82
	v_pk_fma_f32 v[90:91], v[36:37], v[96:97], v[90:91] op_sel:[1,0,0]
	v_cvt_f32_ubyte0_e32 v102, v83
	v_cvt_f32_ubyte1_e32 v103, v83
	v_pk_fma_f32 v[88:89], v[36:37], v[100:101], v[88:89] op_sel:[1,0,0]
	v_cvt_f32_ubyte2_e32 v126, v83
	v_cvt_f32_ubyte3_e32 v127, v83
	v_pk_fma_f32 v[84:85], v[44:45], v[102:103], v[84:85] op_sel:[1,0,0]
	v_cvt_f32_ubyte0_e32 v96, v86
	v_cvt_f32_ubyte1_e32 v97, v86
	v_pk_fma_f32 v[80:81], v[44:45], v[126:127], v[80:81] op_sel:[1,0,0]
	v_and_b32_e32 v74, s34, v190
	v_and_b32_e32 v75, s35, v190
	v_and_b32_e32 v78, s34, v191
	v_and_b32_e32 v79, s35, v191
	v_cvt_f32_ubyte2_e32 v100, v86
	v_cvt_f32_ubyte3_e32 v101, v86
	v_pk_fma_f32 v[76:77], v[36:37], v[96:97], v[76:77] op_sel:[1,0,0]
	v_cvt_f32_ubyte0_e32 v102, v87
	v_cvt_f32_ubyte1_e32 v103, v87
	v_pk_fma_f32 v[68:69], v[36:37], v[100:101], v[68:69] op_sel:[1,0,0]
	v_cvt_f32_ubyte2_e32 v126, v87
	v_cvt_f32_ubyte3_e32 v127, v87
	v_pk_fma_f32 v[62:63], v[44:45], v[102:103], v[62:63] op_sel:[1,0,0]
	v_cvt_f32_ubyte0_e32 v96, v74
	v_cvt_f32_ubyte1_e32 v97, v74
	v_pk_fma_f32 v[60:61], v[44:45], v[126:127], v[60:61] op_sel:[1,0,0]
	v_cvt_f32_ubyte2_e32 v100, v74
	v_cvt_f32_ubyte3_e32 v101, v74
	v_pk_fma_f32 v[90:91], v[38:39], v[96:97], v[90:91] op_sel_hi:[0,1,1]
	v_cvt_f32_ubyte0_e32 v102, v75
	v_cvt_f32_ubyte1_e32 v103, v75
	v_pk_fma_f32 v[88:89], v[38:39], v[100:101], v[88:89] op_sel_hi:[0,1,1]
	v_cvt_f32_ubyte2_e32 v126, v75
	v_cvt_f32_ubyte3_e32 v127, v75
	v_pk_fma_f32 v[84:85], v[46:47], v[102:103], v[84:85] op_sel_hi:[0,1,1]
	v_cvt_f32_ubyte0_e32 v96, v78
	v_cvt_f32_ubyte1_e32 v97, v78
	v_pk_fma_f32 v[80:81], v[46:47], v[126:127], v[80:81] op_sel_hi:[0,1,1]
	v_and_b32_e32 v82, s34, v192
	v_and_b32_e32 v83, s35, v192
	v_and_b32_e32 v86, s34, v193
	v_and_b32_e32 v87, s35, v193
	v_cvt_f32_ubyte2_e32 v100, v78
	v_cvt_f32_ubyte3_e32 v101, v78
	v_pk_fma_f32 v[76:77], v[38:39], v[96:97], v[76:77] op_sel_hi:[0,1,1]
	v_cvt_f32_ubyte0_e32 v102, v79
	v_cvt_f32_ubyte1_e32 v103, v79
	v_pk_fma_f32 v[68:69], v[38:39], v[100:101], v[68:69] op_sel_hi:[0,1,1]
	v_cvt_f32_ubyte2_e32 v126, v79
	v_cvt_f32_ubyte3_e32 v127, v79
	v_pk_fma_f32 v[62:63], v[46:47], v[102:103], v[62:63] op_sel_hi:[0,1,1]
	v_cvt_f32_ubyte0_e32 v96, v82
	v_cvt_f32_ubyte1_e32 v97, v82
	v_pk_fma_f32 v[60:61], v[46:47], v[126:127], v[60:61] op_sel_hi:[0,1,1]
	v_cvt_f32_ubyte2_e32 v100, v82
	v_cvt_f32_ubyte3_e32 v101, v82
	v_pk_fma_f32 v[90:91], v[38:39], v[96:97], v[90:91] op_sel:[1,0,0]
	v_cvt_f32_ubyte0_e32 v102, v83
	v_cvt_f32_ubyte1_e32 v103, v83
	v_pk_fma_f32 v[88:89], v[38:39], v[100:101], v[88:89] op_sel:[1,0,0]
	v_cvt_f32_ubyte2_e32 v126, v83
	v_cvt_f32_ubyte3_e32 v127, v83
	v_pk_fma_f32 v[84:85], v[46:47], v[102:103], v[84:85] op_sel:[1,0,0]
	v_cvt_f32_ubyte0_e32 v96, v86
	v_cvt_f32_ubyte1_e32 v97, v86
	v_pk_fma_f32 v[80:81], v[46:47], v[126:127], v[80:81] op_sel:[1,0,0]
	v_cvt_f32_ubyte2_e32 v100, v86
	v_cvt_f32_ubyte3_e32 v101, v86
	v_pk_fma_f32 v[76:77], v[38:39], v[96:97], v[76:77] op_sel:[1,0,0]
	v_cvt_f32_ubyte0_e32 v102, v87
	v_cvt_f32_ubyte1_e32 v103, v87
	v_pk_fma_f32 v[68:69], v[38:39], v[100:101], v[68:69] op_sel:[1,0,0]
	v_cvt_f32_ubyte2_e32 v126, v87
	v_cvt_f32_ubyte3_e32 v127, v87
	v_pk_fma_f32 v[62:63], v[46:47], v[102:103], v[62:63] op_sel:[1,0,0]
	v_pk_fma_f32 v[60:61], v[46:47], v[126:127], v[60:61] op_sel:[1,0,0]
	s_waitcnt lgkmcnt(0)
	s_waitcnt vmcnt(0)
	v_and_b32_e32 v74, s34, v194
	v_and_b32_e32 v75, s35, v194
	v_and_b32_e32 v78, s34, v195
	v_and_b32_e32 v79, s35, v195
	v_cvt_f32_ubyte0_e32 v96, v74
	v_cvt_f32_ubyte1_e32 v97, v74
	v_cvt_f32_ubyte2_e32 v100, v74
	v_cvt_f32_ubyte3_e32 v101, v74
	v_pk_fma_f32 v[90:91], v[48:49], v[96:97], v[90:91] op_sel_hi:[0,1,1]
	v_cvt_f32_ubyte0_e32 v102, v75
	v_cvt_f32_ubyte1_e32 v103, v75
	v_pk_fma_f32 v[88:89], v[48:49], v[100:101], v[88:89] op_sel_hi:[0,1,1]
	v_cvt_f32_ubyte2_e32 v126, v75
	v_cvt_f32_ubyte3_e32 v127, v75
	v_pk_fma_f32 v[84:85], v[56:57], v[102:103], v[84:85] op_sel_hi:[0,1,1]
	v_cvt_f32_ubyte0_e32 v96, v78
	v_cvt_f32_ubyte1_e32 v97, v78
	v_pk_fma_f32 v[80:81], v[56:57], v[126:127], v[80:81] op_sel_hi:[0,1,1]
	v_and_b32_e32 v82, s34, v196
	v_and_b32_e32 v83, s35, v196
	v_and_b32_e32 v86, s34, v197
	v_and_b32_e32 v87, s35, v197
	v_cvt_f32_ubyte2_e32 v100, v78
	v_cvt_f32_ubyte3_e32 v101, v78
	v_pk_fma_f32 v[76:77], v[48:49], v[96:97], v[76:77] op_sel_hi:[0,1,1]
	v_cvt_f32_ubyte0_e32 v102, v79
	v_cvt_f32_ubyte1_e32 v103, v79
	v_pk_fma_f32 v[68:69], v[48:49], v[100:101], v[68:69] op_sel_hi:[0,1,1]
	v_cvt_f32_ubyte2_e32 v126, v79
	v_cvt_f32_ubyte3_e32 v127, v79
	v_pk_fma_f32 v[62:63], v[56:57], v[102:103], v[62:63] op_sel_hi:[0,1,1]
	v_cvt_f32_ubyte0_e32 v96, v82
	v_cvt_f32_ubyte1_e32 v97, v82
	v_pk_fma_f32 v[60:61], v[56:57], v[126:127], v[60:61] op_sel_hi:[0,1,1]
	v_cvt_f32_ubyte2_e32 v100, v82
	v_cvt_f32_ubyte3_e32 v101, v82
	v_pk_fma_f32 v[90:91], v[48:49], v[96:97], v[90:91] op_sel:[1,0,0]
	v_cvt_f32_ubyte0_e32 v102, v83
	v_cvt_f32_ubyte1_e32 v103, v83
	v_pk_fma_f32 v[88:89], v[48:49], v[100:101], v[88:89] op_sel:[1,0,0]
	v_cvt_f32_ubyte2_e32 v126, v83
	v_cvt_f32_ubyte3_e32 v127, v83
	v_pk_fma_f32 v[84:85], v[56:57], v[102:103], v[84:85] op_sel:[1,0,0]
	v_cvt_f32_ubyte0_e32 v96, v86
	v_cvt_f32_ubyte1_e32 v97, v86
	v_pk_fma_f32 v[80:81], v[56:57], v[126:127], v[80:81] op_sel:[1,0,0]
	v_and_b32_e32 v74, s34, v198
	v_and_b32_e32 v75, s35, v198
	v_and_b32_e32 v78, s34, v199
	v_and_b32_e32 v79, s35, v199
	v_cvt_f32_ubyte2_e32 v100, v86
	v_cvt_f32_ubyte3_e32 v101, v86
	v_pk_fma_f32 v[76:77], v[48:49], v[96:97], v[76:77] op_sel:[1,0,0]
	v_cvt_f32_ubyte0_e32 v102, v87
	v_cvt_f32_ubyte1_e32 v103, v87
	v_pk_fma_f32 v[68:69], v[48:49], v[100:101], v[68:69] op_sel:[1,0,0]
	v_cvt_f32_ubyte2_e32 v126, v87
	v_cvt_f32_ubyte3_e32 v127, v87
	v_pk_fma_f32 v[62:63], v[56:57], v[102:103], v[62:63] op_sel:[1,0,0]
	v_cvt_f32_ubyte0_e32 v96, v74
	v_cvt_f32_ubyte1_e32 v97, v74
	v_pk_fma_f32 v[60:61], v[56:57], v[126:127], v[60:61] op_sel:[1,0,0]
	v_cvt_f32_ubyte2_e32 v100, v74
	v_cvt_f32_ubyte3_e32 v101, v74
	v_pk_fma_f32 v[90:91], v[50:51], v[96:97], v[90:91] op_sel_hi:[0,1,1]
	v_cvt_f32_ubyte0_e32 v102, v75
	v_cvt_f32_ubyte1_e32 v103, v75
	v_pk_fma_f32 v[88:89], v[50:51], v[100:101], v[88:89] op_sel_hi:[0,1,1]
	v_cvt_f32_ubyte2_e32 v126, v75
	v_cvt_f32_ubyte3_e32 v127, v75
	v_pk_fma_f32 v[84:85], v[58:59], v[102:103], v[84:85] op_sel_hi:[0,1,1]
	v_cvt_f32_ubyte0_e32 v96, v78
	v_cvt_f32_ubyte1_e32 v97, v78
	v_pk_fma_f32 v[80:81], v[58:59], v[126:127], v[80:81] op_sel_hi:[0,1,1]
	v_and_b32_e32 v82, s34, v200
	v_and_b32_e32 v83, s35, v200
	v_and_b32_e32 v86, s34, v201
	v_and_b32_e32 v87, s35, v201
	v_cvt_f32_ubyte2_e32 v100, v78
	v_cvt_f32_ubyte3_e32 v101, v78
	v_pk_fma_f32 v[76:77], v[50:51], v[96:97], v[76:77] op_sel_hi:[0,1,1]
	v_cvt_f32_ubyte0_e32 v102, v79
	v_cvt_f32_ubyte1_e32 v103, v79
	v_pk_fma_f32 v[68:69], v[50:51], v[100:101], v[68:69] op_sel_hi:[0,1,1]
	v_cvt_f32_ubyte2_e32 v126, v79
	v_cvt_f32_ubyte3_e32 v127, v79
	v_pk_fma_f32 v[62:63], v[58:59], v[102:103], v[62:63] op_sel_hi:[0,1,1]
	v_cvt_f32_ubyte0_e32 v96, v82
	v_cvt_f32_ubyte1_e32 v97, v82
	v_pk_fma_f32 v[60:61], v[58:59], v[126:127], v[60:61] op_sel_hi:[0,1,1]
	v_cvt_f32_ubyte2_e32 v100, v82
	v_cvt_f32_ubyte3_e32 v101, v82
	v_pk_fma_f32 v[90:91], v[50:51], v[96:97], v[90:91] op_sel:[1,0,0]
	v_cvt_f32_ubyte0_e32 v102, v83
	v_cvt_f32_ubyte1_e32 v103, v83
	v_pk_fma_f32 v[88:89], v[50:51], v[100:101], v[88:89] op_sel:[1,0,0]
	v_cvt_f32_ubyte2_e32 v126, v83
	v_cvt_f32_ubyte3_e32 v127, v83
	v_pk_fma_f32 v[84:85], v[58:59], v[102:103], v[84:85] op_sel:[1,0,0]
	v_cvt_f32_ubyte0_e32 v96, v86
	v_cvt_f32_ubyte1_e32 v97, v86
	v_pk_fma_f32 v[80:81], v[58:59], v[126:127], v[80:81] op_sel:[1,0,0]
	v_and_b32_e32 v74, s34, v202
	v_and_b32_e32 v75, s35, v202
	v_and_b32_e32 v78, s34, v203
	v_and_b32_e32 v79, s35, v203
	v_cvt_f32_ubyte2_e32 v100, v86
	v_cvt_f32_ubyte3_e32 v101, v86
	v_pk_fma_f32 v[76:77], v[50:51], v[96:97], v[76:77] op_sel:[1,0,0]
	v_cvt_f32_ubyte0_e32 v102, v87
	v_cvt_f32_ubyte1_e32 v103, v87
	v_pk_fma_f32 v[68:69], v[50:51], v[100:101], v[68:69] op_sel:[1,0,0]
	v_cvt_f32_ubyte2_e32 v126, v87
	v_cvt_f32_ubyte3_e32 v127, v87
	v_pk_fma_f32 v[62:63], v[58:59], v[102:103], v[62:63] op_sel:[1,0,0]
	v_cvt_f32_ubyte0_e32 v96, v74
	v_cvt_f32_ubyte1_e32 v97, v74
	v_pk_fma_f32 v[60:61], v[58:59], v[126:127], v[60:61] op_sel:[1,0,0]
	v_cvt_f32_ubyte2_e32 v100, v74
	v_cvt_f32_ubyte3_e32 v101, v74
	v_pk_fma_f32 v[90:91], v[52:53], v[96:97], v[90:91] op_sel_hi:[0,1,1]
	v_cvt_f32_ubyte0_e32 v102, v75
	v_cvt_f32_ubyte1_e32 v103, v75
	v_pk_fma_f32 v[88:89], v[52:53], v[100:101], v[88:89] op_sel_hi:[0,1,1]
	v_cvt_f32_ubyte2_e32 v126, v75
	v_cvt_f32_ubyte3_e32 v127, v75
	v_pk_fma_f32 v[84:85], v[64:65], v[102:103], v[84:85] op_sel_hi:[0,1,1]
	v_cvt_f32_ubyte0_e32 v96, v78
	v_cvt_f32_ubyte1_e32 v97, v78
	v_pk_fma_f32 v[80:81], v[64:65], v[126:127], v[80:81] op_sel_hi:[0,1,1]
	v_and_b32_e32 v82, s34, v204
	v_and_b32_e32 v83, s35, v204
	v_and_b32_e32 v86, s34, v205
	v_and_b32_e32 v87, s35, v205
	v_cvt_f32_ubyte2_e32 v100, v78
	v_cvt_f32_ubyte3_e32 v101, v78
	v_pk_fma_f32 v[76:77], v[52:53], v[96:97], v[76:77] op_sel_hi:[0,1,1]
	v_cvt_f32_ubyte0_e32 v102, v79
	v_cvt_f32_ubyte1_e32 v103, v79
	v_pk_fma_f32 v[68:69], v[52:53], v[100:101], v[68:69] op_sel_hi:[0,1,1]
	v_cvt_f32_ubyte2_e32 v126, v79
	v_cvt_f32_ubyte3_e32 v127, v79
	v_pk_fma_f32 v[62:63], v[64:65], v[102:103], v[62:63] op_sel_hi:[0,1,1]
	v_cvt_f32_ubyte0_e32 v96, v82
	v_cvt_f32_ubyte1_e32 v97, v82
	v_pk_fma_f32 v[60:61], v[64:65], v[126:127], v[60:61] op_sel_hi:[0,1,1]
	v_cvt_f32_ubyte2_e32 v100, v82
	v_cvt_f32_ubyte3_e32 v101, v82
	v_pk_fma_f32 v[90:91], v[52:53], v[96:97], v[90:91] op_sel:[1,0,0]
	v_cvt_f32_ubyte0_e32 v102, v83
	v_cvt_f32_ubyte1_e32 v103, v83
	v_pk_fma_f32 v[88:89], v[52:53], v[100:101], v[88:89] op_sel:[1,0,0]
	v_cvt_f32_ubyte2_e32 v126, v83
	v_cvt_f32_ubyte3_e32 v127, v83
	v_pk_fma_f32 v[84:85], v[64:65], v[102:103], v[84:85] op_sel:[1,0,0]
	v_cvt_f32_ubyte0_e32 v96, v86
	v_cvt_f32_ubyte1_e32 v97, v86
	v_pk_fma_f32 v[80:81], v[64:65], v[126:127], v[80:81] op_sel:[1,0,0]
	v_and_b32_e32 v74, s34, v206
	v_and_b32_e32 v75, s35, v206
	v_and_b32_e32 v78, s34, v207
	v_and_b32_e32 v79, s35, v207
	v_cvt_f32_ubyte2_e32 v100, v86
	v_cvt_f32_ubyte3_e32 v101, v86
	v_pk_fma_f32 v[76:77], v[52:53], v[96:97], v[76:77] op_sel:[1,0,0]
	v_cvt_f32_ubyte0_e32 v102, v87
	v_cvt_f32_ubyte1_e32 v103, v87
	v_pk_fma_f32 v[68:69], v[52:53], v[100:101], v[68:69] op_sel:[1,0,0]
	v_cvt_f32_ubyte2_e32 v126, v87
	v_cvt_f32_ubyte3_e32 v127, v87
	v_pk_fma_f32 v[62:63], v[64:65], v[102:103], v[62:63] op_sel:[1,0,0]
	v_cvt_f32_ubyte0_e32 v96, v74
	v_cvt_f32_ubyte1_e32 v97, v74
	v_pk_fma_f32 v[60:61], v[64:65], v[126:127], v[60:61] op_sel:[1,0,0]
	v_cvt_f32_ubyte2_e32 v100, v74
	v_cvt_f32_ubyte3_e32 v101, v74
	v_pk_fma_f32 v[90:91], v[54:55], v[96:97], v[90:91] op_sel_hi:[0,1,1]
	v_cvt_f32_ubyte0_e32 v102, v75
	v_cvt_f32_ubyte1_e32 v103, v75
	v_pk_fma_f32 v[88:89], v[54:55], v[100:101], v[88:89] op_sel_hi:[0,1,1]
	v_cvt_f32_ubyte2_e32 v126, v75
	v_cvt_f32_ubyte3_e32 v127, v75
	v_pk_fma_f32 v[84:85], v[66:67], v[102:103], v[84:85] op_sel_hi:[0,1,1]
	v_cvt_f32_ubyte0_e32 v96, v78
	v_cvt_f32_ubyte1_e32 v97, v78
	v_pk_fma_f32 v[80:81], v[66:67], v[126:127], v[80:81] op_sel_hi:[0,1,1]
	v_and_b32_e32 v82, s34, v208
	v_and_b32_e32 v83, s35, v208
	v_and_b32_e32 v86, s34, v209
	v_and_b32_e32 v87, s35, v209
	v_cvt_f32_ubyte2_e32 v100, v78
	v_cvt_f32_ubyte3_e32 v101, v78
	v_pk_fma_f32 v[76:77], v[54:55], v[96:97], v[76:77] op_sel_hi:[0,1,1]
	v_cvt_f32_ubyte0_e32 v102, v79
	v_cvt_f32_ubyte1_e32 v103, v79
	v_pk_fma_f32 v[68:69], v[54:55], v[100:101], v[68:69] op_sel_hi:[0,1,1]
	v_cvt_f32_ubyte2_e32 v126, v79
	v_cvt_f32_ubyte3_e32 v127, v79
	v_pk_fma_f32 v[62:63], v[66:67], v[102:103], v[62:63] op_sel_hi:[0,1,1]
	v_cvt_f32_ubyte0_e32 v96, v82
	v_cvt_f32_ubyte1_e32 v97, v82
	v_pk_fma_f32 v[60:61], v[66:67], v[126:127], v[60:61] op_sel_hi:[0,1,1]
	v_cvt_f32_ubyte2_e32 v100, v82
	v_cvt_f32_ubyte3_e32 v101, v82
	v_pk_fma_f32 v[90:91], v[54:55], v[96:97], v[90:91] op_sel:[1,0,0]
	v_cvt_f32_ubyte0_e32 v102, v83
	v_cvt_f32_ubyte1_e32 v103, v83
	v_pk_fma_f32 v[88:89], v[54:55], v[100:101], v[88:89] op_sel:[1,0,0]
	v_cvt_f32_ubyte2_e32 v126, v83
	v_cvt_f32_ubyte3_e32 v127, v83
	v_pk_fma_f32 v[84:85], v[66:67], v[102:103], v[84:85] op_sel:[1,0,0]
	v_cvt_f32_ubyte0_e32 v96, v86
	v_cvt_f32_ubyte1_e32 v97, v86
	v_pk_fma_f32 v[80:81], v[66:67], v[126:127], v[80:81] op_sel:[1,0,0]
	v_cvt_f32_ubyte2_e32 v100, v86
	v_cvt_f32_ubyte3_e32 v101, v86
	v_pk_fma_f32 v[76:77], v[54:55], v[96:97], v[76:77] op_sel:[1,0,0]
	v_cvt_f32_ubyte0_e32 v102, v87
	v_cvt_f32_ubyte1_e32 v103, v87
	v_pk_fma_f32 v[68:69], v[54:55], v[100:101], v[68:69] op_sel:[1,0,0]
	v_cvt_f32_ubyte2_e32 v126, v87
	v_cvt_f32_ubyte3_e32 v127, v87
	v_pk_fma_f32 v[62:63], v[66:67], v[102:103], v[62:63] op_sel:[1,0,0]
	v_pk_fma_f32 v[60:61], v[66:67], v[126:127], v[60:61] op_sel:[1,0,0]
	s_waitcnt lgkmcnt(0)
	s_branch .LBB0_979
